# K-loop periods rescheduled in all GEMM instances: ds_read/ds_write/global_load interleaved between MFMAs (2x2 blocked MFMA order), waits regenerated
# speedup vs baseline: 1.0139x; 1.0139x over previous
; DI int BIDX() { int b = blockIdx.x; asm volatile("" : "+s"(b)); return b; }
; DI int tile_groups(int MT, int NT) { return (MT >> 6) * ((NT + 7) >> 3) * 512; }
; DI void load_rstd(float (&rs)[4], const float* ssq, int row0, int lr) {
; #pragma unroll
;   for (int mt = 0; mt < 4; ++mt) {
;     const float4* q = (const float4*)(ssq + (size_t)(row0 + mt * 16 + lr) * 16);
;     const float4 a = q[0], b = q[1], c = q[2], d = q[3];
;     const float s = ((a.x + a.y) + (a.z + a.w)) + ((b.x + b.y) + (b.z + b.w)) + ((c.x + c.y) + (c.z + c.w)) + ((d.x + d.y) + (d.z + d.w));
;     rs[mt] = rsqrtf(s * (1.0f / 1024.0f) + EPS);
;   }
; }
; DI void phase_proj(const Params& P, int l, char* smem) {
;     ...
;   for (int vb = BIDX(); vb < tile_groups(128, 63); vb += gridDim.x) {
;     int tm, tn; if (!tile_of(vb, 128, 63, tm, tn)) continue;
;     const int m0 = tm * 128, n0 = tn * 128;
;     f32x4 acc[4][4]; zero_acc(acc);
;     const int row0 = m0 + wm * 64, col0 = n0 + wn * 64;
;     float rs[4]; load_rstd(rs, ssq, row0, lr);
;     if (n0 >= PW) {
.LBB0_637:
	s_ashr_i32 s1, s28, 9
	s_lshr_b32 s2, s1, 29
	s_add_i32 s2, s1, s2
	s_lshl_b32 s2, s2, 3
	s_and_b32 s4, s2, 0xffffffc0
	s_and_b32 s2, s26, 56
	s_bfe_u32 s5, s28, 0x30003
	s_or_b32 s2, s2, s5
	s_lshl_b32 s1, s1, 3
	s_or_b32 s2, s2, s4
	s_sub_i32 s1, s1, s4
	s_bfe_u32 s4, s28, 0x30006
	s_or_b32 s1, s1, s4
	s_cmpk_lt_i32 s2, 0x80
	s_cselect_b64 s[4:5], -1, 0
	s_cmp_lt_i32 s1, 63
	s_cselect_b64 s[16:17], -1, 0
	s_and_b64 s[4:5], s[4:5], s[16:17]
	s_andn2_b64 vcc, exec, s[4:5]
	s_cbranch_vccnz .LBB0_636
	s_lshl_b32 s18, s2, 7
	v_add_u32_e32 v99, s18, v101
	s_waitcnt vmcnt(0)
	v_or_b32_e32 v70, v99, v97
	v_ashrrev_i32_e32 v71, 31, v70
	v_readlane_b32 s20, v253, 13
	v_lshlrev_b64 v[0:1], 6, v[70:71]
	v_readlane_b32 s21, v253, 14
	v_or_b32_e32 v68, 16, v70
	v_ashrrev_i32_e32 v69, 31, v68
	v_lshl_add_u64 v[12:13], s[20:21], 0, v[0:1]
	global_load_dwordx4 v[0:3], v[12:13], off offset:48
	global_load_dwordx4 v[4:7], v[12:13], off offset:32
	global_load_dwordx4 v[8:11], v[12:13], off offset:16
	s_nop 0
	global_load_dwordx4 v[12:15], v[12:13], off
	s_mov_b32 s2, 0x358637bd
	s_mov_b32 s22, 0x3a800000
	v_or_b32_e32 v66, 32, v70
	v_ashrrev_i32_e32 v67, 31, v66
	v_or_b32_e32 v64, 48, v70
	v_ashrrev_i32_e32 v65, 31, v64
	s_ashr_i32 s19, s18, 31
	s_lshl_b32 s16, s1, 7
	v_or_b32_e32 v94, s16, v85
	s_waitcnt vmcnt(1)
	v_mov_b32_e32 v18, v9
	s_waitcnt vmcnt(0)
	v_mov_b32_e32 v16, v13
	v_mov_b32_e32 v17, v14
	v_mov_b32_e32 v19, v10
	v_mov_b32_e32 v13, v15
	v_mov_b32_e32 v9, v11
	v_pk_add_f32 v[12:13], v[16:17], v[12:13]
	v_pk_add_f32 v[8:9], v[18:19], v[8:9]
	v_pk_add_f32 v[10:11], v[12:13], v[12:13] op_sel:[0,1] op_sel_hi:[1,0]
	v_pk_add_f32 v[8:9], v[8:9], v[8:9] op_sel:[0,1] op_sel_hi:[1,0]
	v_mov_b32_e32 v11, v0
	v_mov_b32_e32 v9, v1
	v_pk_add_f32 v[0:1], v[10:11], v[8:9]
	v_mov_b32_e32 v8, v5
	v_pk_add_f32 v[4:5], v[4:5], v[8:9]
	s_nop 0
	v_mov_b32_e32 v5, v2
	v_mov_b32_e32 v2, v7
	v_pk_add_f32 v[6:7], v[6:7], v[2:3]
	s_nop 0
	v_mov_b32_e32 v7, v3
	v_pk_add_f32 v[2:3], v[4:5], v[6:7]
	s_nop 0
	v_pk_add_f32 v[16:17], v[0:1], v[2:3]
	v_lshlrev_b64 v[0:1], 6, v[68:69]
	v_lshl_add_u64 v[12:13], s[20:21], 0, v[0:1]
	global_load_dwordx4 v[0:3], v[12:13], off offset:48
	global_load_dwordx4 v[4:7], v[12:13], off offset:32
	global_load_dwordx4 v[8:11], v[12:13], off offset:16
	s_nop 0
	global_load_dwordx4 v[12:15], v[12:13], off
	s_waitcnt vmcnt(1)
	v_mov_b32_e32 v20, v9
	s_waitcnt vmcnt(0)
	v_mov_b32_e32 v18, v13
	v_mov_b32_e32 v19, v14
	v_mov_b32_e32 v21, v10
	v_mov_b32_e32 v13, v15
	v_mov_b32_e32 v9, v11
	v_pk_add_f32 v[12:13], v[18:19], v[12:13]
	v_pk_add_f32 v[8:9], v[20:21], v[8:9]
	v_pk_add_f32 v[10:11], v[12:13], v[12:13] op_sel:[0,1] op_sel_hi:[1,0]
	v_pk_add_f32 v[8:9], v[8:9], v[8:9] op_sel:[0,1] op_sel_hi:[1,0]
	v_mov_b32_e32 v11, v0
	v_mov_b32_e32 v9, v1
	v_pk_add_f32 v[0:1], v[10:11], v[8:9]
	v_mov_b32_e32 v8, v5
	v_pk_add_f32 v[4:5], v[4:5], v[8:9]
	s_nop 0
	v_mov_b32_e32 v5, v2
	v_mov_b32_e32 v2, v7
	v_pk_add_f32 v[6:7], v[6:7], v[2:3]
	s_nop 0
	v_mov_b32_e32 v7, v3
	v_pk_add_f32 v[2:3], v[4:5], v[6:7]
	s_nop 0
	v_pk_add_f32 v[0:1], v[0:1], v[2:3]
	v_mov_b32_e32 v3, v16
	v_mov_b32_e32 v2, v0
	v_mov_b32_e32 v16, v1
	v_pk_add_f32 v[0:1], v[2:3], v[16:17]
	v_mov_b64_e32 v[16:17], s[2:3]
	v_pk_fma_f32 v[0:1], v[0:1], s[22:23], v[16:17] op_sel_hi:[1,0,0]
	s_mov_b32 s2, 0x800000
	v_mul_f32_e32 v2, 0x4b800000, v1
	v_cmp_gt_f32_e64 s[4:5], s2, v1
	v_cmp_gt_f32_e32 vcc, s2, v0
	s_nop 0
	v_cndmask_b32_e64 v1, v1, v2, s[4:5]
	v_rsq_f32_e32 v1, v1
	s_nop 0
	v_mul_f32_e32 v2, 0x45800000, v1
	v_cndmask_b32_e64 v98, v1, v2, s[4:5]
	v_mul_f32_e32 v1, 0x4b800000, v0
	v_cndmask_b32_e32 v0, v0, v1, vcc
	v_rsq_f32_e32 v0, v0
	s_nop 0
	v_mul_f32_e32 v1, 0x45800000, v0
	v_cndmask_b32_e32 v96, v0, v1, vcc
	v_lshlrev_b64 v[0:1], 6, v[66:67]
	v_lshl_add_u64 v[12:13], s[20:21], 0, v[0:1]
	global_load_dwordx4 v[0:3], v[12:13], off offset:48
	global_load_dwordx4 v[4:7], v[12:13], off offset:32
	global_load_dwordx4 v[8:11], v[12:13], off offset:16
	s_nop 0
	global_load_dwordx4 v[12:15], v[12:13], off
	s_waitcnt vmcnt(1)
	v_mov_b32_e32 v20, v9
	s_waitcnt vmcnt(0)
	v_mov_b32_e32 v18, v13
	v_mov_b32_e32 v19, v14
	v_mov_b32_e32 v21, v10
	v_mov_b32_e32 v13, v15
	v_mov_b32_e32 v9, v11
	v_pk_add_f32 v[12:13], v[18:19], v[12:13]
	v_pk_add_f32 v[8:9], v[20:21], v[8:9]
	v_pk_add_f32 v[10:11], v[12:13], v[12:13] op_sel:[0,1] op_sel_hi:[1,0]
	v_pk_add_f32 v[8:9], v[8:9], v[8:9] op_sel:[0,1] op_sel_hi:[1,0]
	v_mov_b32_e32 v11, v0
	v_mov_b32_e32 v9, v1
	v_pk_add_f32 v[0:1], v[10:11], v[8:9]
	v_mov_b32_e32 v8, v5
	v_pk_add_f32 v[4:5], v[4:5], v[8:9]
	s_nop 0
	v_mov_b32_e32 v5, v2
	v_mov_b32_e32 v2, v7
	v_pk_add_f32 v[6:7], v[6:7], v[2:3]
	s_nop 0
	v_mov_b32_e32 v7, v3
	v_pk_add_f32 v[2:3], v[4:5], v[6:7]
	s_nop 0
	v_pk_add_f32 v[18:19], v[0:1], v[2:3]
	v_lshlrev_b64 v[0:1], 6, v[64:65]
	v_lshl_add_u64 v[12:13], s[20:21], 0, v[0:1]
	global_load_dwordx4 v[0:3], v[12:13], off offset:48
	global_load_dwordx4 v[4:7], v[12:13], off offset:32
	global_load_dwordx4 v[8:11], v[12:13], off offset:16
	s_nop 0
	global_load_dwordx4 v[12:15], v[12:13], off
	s_waitcnt vmcnt(1)
	v_mov_b32_e32 v22, v9
	s_waitcnt vmcnt(0)
	v_mov_b32_e32 v20, v13
	v_mov_b32_e32 v21, v14
	v_mov_b32_e32 v23, v10
	v_mov_b32_e32 v13, v15
	v_mov_b32_e32 v9, v11
	v_pk_add_f32 v[12:13], v[20:21], v[12:13]
	v_pk_add_f32 v[8:9], v[22:23], v[8:9]
	v_pk_add_f32 v[10:11], v[12:13], v[12:13] op_sel:[0,1] op_sel_hi:[1,0]
	v_pk_add_f32 v[8:9], v[8:9], v[8:9] op_sel:[0,1] op_sel_hi:[1,0]
	v_mov_b32_e32 v11, v0
	v_mov_b32_e32 v9, v1
	v_pk_add_f32 v[0:1], v[10:11], v[8:9]
	v_mov_b32_e32 v8, v5
	v_pk_add_f32 v[4:5], v[4:5], v[8:9]
	s_nop 0
	v_mov_b32_e32 v5, v2
	v_mov_b32_e32 v2, v7
	v_pk_add_f32 v[6:7], v[6:7], v[2:3]
	s_nop 0
	v_mov_b32_e32 v7, v3
	v_pk_add_f32 v[2:3], v[4:5], v[6:7]
	s_nop 0
	v_pk_add_f32 v[0:1], v[0:1], v[2:3]
	v_mov_b32_e32 v3, v18
	v_mov_b32_e32 v2, v0
	v_mov_b32_e32 v18, v1
	v_pk_add_f32 v[0:1], v[2:3], v[18:19]
	s_nop 0
	v_pk_fma_f32 v[0:1], v[0:1], s[22:23], v[16:17] op_sel_hi:[1,0,0]
	s_nop 0
	v_mul_f32_e32 v2, 0x4b800000, v1
	v_cmp_gt_f32_e64 s[4:5], s2, v1
	v_cmp_gt_f32_e32 vcc, s2, v0
	s_nop 0
	v_cndmask_b32_e64 v1, v1, v2, s[4:5]
	v_rsq_f32_e32 v1, v1
	s_nop 0
	v_mul_f32_e32 v2, 0x45800000, v1
	v_cndmask_b32_e64 v102, v1, v2, s[4:5]
	v_mul_f32_e32 v1, 0x4b800000, v0
	v_cndmask_b32_e32 v0, v0, v1, vcc
	v_rsq_f32_e32 v0, v0
	s_lshl_b64 s[4:5], s[18:19], 11
	v_readlane_b32 s18, v253, 11
	v_readlane_b32 s19, v253, 12
	s_add_u32 s18, s18, s4
	v_mul_f32_e32 v1, 0x45800000, v0
	s_addc_u32 s19, s19, s5
	v_cndmask_b32_e32 v100, v0, v1, vcc
	s_cmp_lt_i32 s1, 51
	s_mov_b64 s[4:5], -1
	s_cbranch_scc0 .LBB0_691
; DI int TIDX() { int t = threadIdx.x; asm volatile("" : "+v"(t)); return t; }
; #define GL_LOAD(s_, kt_) if (VAR != 1) { a##s_##0 = GL_A(0, kt_); a##s_##1 = GL_A(1, kt_); a##s_##2 = GL_A(2, kt_); a##s_##3 = GL_A(3, kt_); b##s_##0 = GL_B(0, kt_); b##s_##1 = GL_B(1, kt_); b##s_##2 = GL_B(2, kt_); b##s_##3 = GL_B(3, kt_); }
; #define LDS_STORE(s_, buf_) if (VAR != 2) { LDS_ST1(sA, 0, buf_, a##s_##0) LDS_ST1(sA, 1, buf_, a##s_##1) LDS_ST1(sA, 2, buf_, a##s_##2) LDS_ST1(sA, 3, buf_, a##s_##3) LDS_ST1(sB, 0, buf_, b##s_##0) LDS_ST1(sB, 1, buf_, b##s_##1) LDS_ST1(sB, 2, buf_, b##s_##2) LDS_ST1(sB, 3, buf_, b##s_##3) }
;   const int tid = TIDX(), lane = tid & 63, wid = tid >> 6, wm = wid >> 1, wn = wid & 1, lr = lane & 15, g = lane >> 4;
;   char* sA = smem; char* sB = smem + 2 * LTILE;
;   uint4 a00 = {}, a01 = {}, a02 = {}, a03 = {}, b00 = {}, b01 = {}, b02 = {}, b03 = {}, a10 = {}, a11 = {}, a12 = {}, a13 = {}, b10 = {}, b11 = {}, b12 = {}, b13 = {};
;   constexpr int nk = NK;
;   const int sw0 = (g ^ ((lr >> 1) & 7)) << 4, sw1 = sw0 ^ 64;
;   const int r0 = tid >> 3, kc = tid & 7, kcs = kc ^ ((r0 >> 1) & 7);
;     ...
;   GL_LOAD(0, 0)
;   GL_LOAD(1, 1)
;   LDS_STORE(0, 0)
;   if (VAR != 4) __syncthreads();
; #pragma unroll
;   for (int kt = 0; kt < nk; kt += 2) {
;     if (kt + 2 < nk) { GL_LOAD(0, kt + 2) }
;     MMA_TILE(0)
;     LDS_STORE(1, 1)
	v_mov_b32_e32 v56, v148
	s_ashr_i32 s17, s16, 31
	s_lshl_b64 s[4:5], s[16:17], 11
	v_ashrrev_i32_e32 v16, 3, v56
	v_readlane_b32 s1, v252, 19
	v_ashrrev_i32_e32 v17, 31, v16
	s_add_u32 s4, s1, s4
	v_readlane_b32 s1, v252, 20
	v_lshlrev_b64 v[8:9], 11, v[16:17]
	v_lshlrev_b32_e32 v17, 4, v56
	v_add_u32_e32 v18, 32, v16
	s_addc_u32 s5, s1, s5
	v_lshl_add_u64 v[0:1], s[18:19], 0, v[8:9]
	v_and_b32_e32 v150, 0x70, v17
	v_ashrrev_i32_e32 v19, 31, v18
	v_add_u32_e32 v20, 64, v16
	v_lshl_add_u64 v[0:1], v[0:1], 0, v[150:151]
	v_lshlrev_b64 v[10:11], 11, v[18:19]
	v_ashrrev_i32_e32 v21, 31, v20
	v_add_u32_e32 v54, 0x60, v16
	v_lshl_add_u64 v[8:9], s[4:5], 0, v[8:9]
	global_load_dwordx4 v[22:25], v[0:1], off
	v_lshl_add_u64 v[2:3], s[18:19], 0, v[10:11]
	v_lshlrev_b64 v[12:13], 11, v[20:21]
	v_ashrrev_i32_e32 v55, 31, v54
	v_lshl_add_u64 v[8:9], v[8:9], 0, v[150:151]
	v_lshl_add_u64 v[2:3], v[2:3], 0, v[150:151]
	v_lshl_add_u64 v[4:5], s[18:19], 0, v[12:13]
	v_lshlrev_b64 v[14:15], 11, v[54:55]
	global_load_dwordx4 v[38:41], v[8:9], off
	global_load_dwordx4 v[26:29], v[2:3], off
	v_lshl_add_u64 v[4:5], v[4:5], 0, v[150:151]
	v_lshl_add_u64 v[6:7], s[18:19], 0, v[14:15]
	global_load_dwordx4 v[30:33], v[4:5], off
	v_lshl_add_u64 v[6:7], v[6:7], 0, v[150:151]
	v_lshl_add_u64 v[10:11], s[4:5], 0, v[10:11]
	global_load_dwordx4 v[34:37], v[6:7], off
	v_lshl_add_u64 v[10:11], v[10:11], 0, v[150:151]
	v_lshl_add_u64 v[12:13], s[4:5], 0, v[12:13]
	global_load_dwordx4 v[42:45], v[10:11], off
	v_lshl_add_u64 v[12:13], v[12:13], 0, v[150:151]
	v_lshl_add_u64 v[14:15], s[4:5], 0, v[14:15]
	global_load_dwordx4 v[46:49], v[12:13], off
	v_lshl_add_u64 v[14:15], v[14:15], 0, v[150:151]
	global_load_dwordx4 v[50:53], v[14:15], off
	v_lshlrev_b32_e32 v21, 3, v56
	v_and_b32_e32 v62, 48, v56
	s_movk_i32 s1, 0x70
	v_and_b32_e32 v19, 15, v56
	v_lshrrev_b32_e32 v55, 1, v56
	v_lshlrev_b32_e32 v57, 7, v56
	v_and_b32_e32 v63, 0x70, v21
	v_bitop3_b32 v95, v21, v62, s1 bitop3:0x6c
	v_bitop3_b32 v21, v17, s1, v56 bitop3:0x48
	v_and_or_b32 v103, v55, s29, v19
	v_and_b32_e32 v150, 0x2780, v57
	v_lshl_or_b32 v19, v20, 7, v21
	v_lshl_or_b32 v20, v54, 7, v21
	global_load_dwordx4 v[54:57], v[0:1], off offset:128
	global_load_dwordx4 v[58:61], v[8:9], off offset:128
	global_load_dwordx4 v[72:75], v[2:3], off offset:128
	global_load_dwordx4 v[76:79], v[4:5], off offset:128
	global_load_dwordx4 v[80:83], v[6:7], off offset:128
	global_load_dwordx4 v[104:107], v[10:11], off offset:128
	global_load_dwordx4 v[108:111], v[12:13], off offset:128
	global_load_dwordx4 v[112:115], v[14:15], off offset:128
	v_lshl_or_b32 v17, v16, 7, v21
	v_or_b32_e32 v16, v150, v95
	v_lshlrev_b32_e32 v103, 7, v103
	v_lshl_or_b32 v18, v18, 7, v21
	v_bitop3_b32 v21, v103, v63, v62 bitop3:0xf6
	s_movk_i32 s1, 0x1ff
	v_cmp_lt_i32_e32 vcc, s1, v94
	s_mov_b64 s[22:23], -1
	s_mov_b64 s[20:21], 0
	s_waitcnt vmcnt(15)
	ds_write_b128 v17, v[22:25]
	s_waitcnt vmcnt(14)
	ds_write_b128 v17, v[38:41] offset:32768
	s_waitcnt vmcnt(13)
	ds_write_b128 v18, v[26:29]
	s_waitcnt vmcnt(12)
	ds_write_b128 v19, v[30:33]
	s_waitcnt vmcnt(11)
	ds_write_b128 v20, v[34:37]
	s_waitcnt vmcnt(10)
	ds_write_b128 v18, v[42:45] offset:32768
	s_waitcnt vmcnt(9)
	ds_write_b128 v19, v[46:49] offset:32768
	s_waitcnt vmcnt(8)
	ds_write_b128 v20, v[50:53] offset:32768
	s_waitcnt lgkmcnt(0)
	s_barrier
	ds_read_b128 v[22:25], v16 offset:32768
	ds_read_b128 v[30:33], v21
	s_waitcnt lgkmcnt(0)
	v_mfma_f32_16x16x32_f16 v[38:41], v[22:25], v[30:33], 0
	ds_read_b128 v[26:29], v16 offset:34816
	s_waitcnt lgkmcnt(0)
	v_mfma_f32_16x16x32_f16 v[46:49], v[26:29], v[30:33], 0
	ds_read_b128 v[34:37], v21 offset:2048
	ds_read_b128 v[42:45], v16 offset:36864
	s_waitcnt lgkmcnt(0)
	v_mfma_f32_16x16x32_f16 v[116:119], v[42:45], v[30:33], 0
	ds_read_b128 v[50:53], v16 offset:38912
	s_waitcnt lgkmcnt(0)
	v_mfma_f32_16x16x32_f16 v[120:123], v[50:53], v[30:33], 0
	ds_read_b128 v[30:33], v21 offset:4096
	v_mfma_f32_16x16x32_f16 v[124:127], v[22:25], v[34:37], 0
	ds_read_b128 v[136:139], v21 offset:6144
	s_waitcnt lgkmcnt(0)
	v_mfma_f32_16x16x32_f16 v[162:165], v[22:25], v[136:139], 0
	v_mfma_f32_16x16x32_f16 v[128:131], v[26:29], v[34:37], 0
	v_mfma_f32_16x16x32_f16 v[132:135], v[42:45], v[34:37], 0
	v_mfma_f32_16x16x32_f16 v[34:37], v[50:53], v[34:37], 0
	v_mfma_f32_16x16x32_f16 v[140:143], v[22:25], v[30:33], 0
	v_xor_b32_e32 v22, 64, v95
	v_or_b32_e32 v22, v150, v22
	v_mfma_f32_16x16x32_f16 v[144:147], v[26:29], v[30:33], 0
	v_mfma_f32_16x16x32_f16 v[154:157], v[42:45], v[30:33], 0
	v_mfma_f32_16x16x32_f16 v[158:161], v[50:53], v[30:33], 0
	v_bitop3_b32 v32, v103, v95, 64 bitop3:0xf6
	ds_read_b128 v[166:169], v32
	ds_read_b128 v[192:195], v22 offset:36864
	s_waitcnt lgkmcnt(0)
	v_mfma_f32_16x16x32_f16 v[116:119], v[192:195], v[166:169], v[116:119]
	ds_read_b128 v[188:191], v32 offset:2048
	ds_read_b128 v[196:199], v22 offset:38912
	s_waitcnt lgkmcnt(0)
	v_mfma_f32_16x16x32_f16 v[120:123], v[196:199], v[166:169], v[120:123]
	s_waitcnt vmcnt(7)
	ds_write_b128 v17, v[54:57] offset:16384
	s_waitcnt vmcnt(5)
	ds_write_b128 v18, v[72:75] offset:16384
	v_mfma_f32_16x16x32_f16 v[132:135], v[192:195], v[188:191], v[132:135]
	s_waitcnt vmcnt(4)
	ds_write_b128 v19, v[76:79] offset:16384
	s_waitcnt vmcnt(3)
	ds_write_b128 v20, v[80:83] offset:16384
	v_mfma_f32_16x16x32_f16 v[34:37], v[196:199], v[188:191], v[34:37]
	ds_write_b128 v17, v[58:61] offset:49152
	s_waitcnt vmcnt(2)
	ds_write_b128 v18, v[104:107] offset:49152
	s_waitcnt vmcnt(1)
	ds_write_b128 v19, v[108:111] offset:49152
	s_waitcnt vmcnt(0)
; #define GL_LOAD(s_, kt_) if (VAR != 1) { a##s_##0 = GL_A(0, kt_); a##s_##1 = GL_A(1, kt_); a##s_##2 = GL_A(2, kt_); a##s_##3 = GL_A(3, kt_); b##s_##0 = GL_B(0, kt_); b##s_##1 = GL_B(1, kt_); b##s_##2 = GL_B(2, kt_); b##s_##3 = GL_B(3, kt_); }
; #define LDS_STORE(s_, buf_) if (VAR != 2) { LDS_ST1(sA, 0, buf_, a##s_##0) LDS_ST1(sA, 1, buf_, a##s_##1) LDS_ST1(sA, 2, buf_, a##s_##2) LDS_ST1(sA, 3, buf_, a##s_##3) LDS_ST1(sB, 0, buf_, b##s_##0) LDS_ST1(sB, 1, buf_, b##s_##1) LDS_ST1(sB, 2, buf_, b##s_##2) LDS_ST1(sB, 3, buf_, b##s_##3) }
;     ...
;   for (int kt = 0; kt < nk; kt += 2) {
;     if (kt + 2 < nk) { GL_LOAD(0, kt + 2) }
;     MMA_TILE(0)
;     LDS_STORE(1, 1)
;     if (VAR != 4) __syncthreads();
;     if (kt + 3 < nk) { GL_LOAD(1, kt + 3) }
;     MMA_TILE(1)
;     if (kt + 2 < nk) { LDS_STORE(0, 0) }
;     if (VAR != 4) __syncthreads();
	ds_write_b128 v20, v[112:115] offset:49152
	v_mfma_f32_16x16x32_f16 v[24:27], v[26:29], v[136:139], 0
	v_mfma_f32_16x16x32_f16 v[28:31], v[42:45], v[136:139], 0
	ds_read_b128 v[42:45], v22 offset:32768
	v_mfma_f32_16x16x32_f16 v[50:53], v[50:53], v[136:139], 0
	ds_read_b128 v[136:139], v22 offset:34816
	s_waitcnt lgkmcnt(1)
	v_mfma_f32_16x16x32_f16 v[38:41], v[42:45], v[166:169], v[38:41]
	v_mfma_f32_16x16x32_f16 v[124:127], v[42:45], v[188:191], v[124:127]
	s_waitcnt lgkmcnt(0)
	v_mfma_f32_16x16x32_f16 v[46:49], v[136:139], v[166:169], v[46:49]
	ds_read_b128 v[166:169], v32 offset:4096
	v_mfma_f32_16x16x32_f16 v[128:131], v[136:139], v[188:191], v[128:131]
	ds_read_b128 v[188:191], v32 offset:6144
	s_waitcnt lgkmcnt(1)
	v_mfma_f32_16x16x32_f16 v[140:143], v[42:45], v[166:169], v[140:143]
	s_waitcnt lgkmcnt(0)
	v_mfma_f32_16x16x32_f16 v[42:45], v[42:45], v[188:191], v[162:165]
	s_nop 2
	global_load_dwordx4 v[162:165], v[0:1], off offset:256
	v_mfma_f32_16x16x32_f16 v[144:147], v[136:139], v[166:169], v[144:147]
	v_mfma_f32_16x16x32_f16 v[24:27], v[136:139], v[188:191], v[24:27]
	v_mfma_f32_16x16x32_f16 v[154:157], v[192:195], v[166:169], v[154:157]
	v_mfma_f32_16x16x32_f16 v[158:161], v[196:199], v[166:169], v[158:161]
	global_load_dwordx4 v[166:169], v[2:3], off offset:256
	global_load_dwordx4 v[200:203], v[4:5], off offset:256
	global_load_dwordx4 v[204:207], v[6:7], off offset:256
	global_load_dwordx4 v[136:139], v[8:9], off offset:256
	global_load_dwordx4 v[208:211], v[10:11], off offset:256
	global_load_dwordx4 v[212:215], v[12:13], off offset:256
	global_load_dwordx4 v[220:223], v[14:15], off offset:256
	s_waitcnt lgkmcnt(0)
	s_barrier
	v_mfma_f32_16x16x32_f16 v[28:31], v[192:195], v[188:191], v[28:31]
	ds_read_b128 v[54:57], v16 offset:49152
	v_mfma_f32_16x16x32_f16 v[50:53], v[196:199], v[188:191], v[50:53]
	ds_read_b128 v[58:61], v16 offset:51200
	ds_read_b128 v[72:75], v21 offset:16384
	s_waitcnt lgkmcnt(0)
	v_mfma_f32_16x16x32_f16 v[38:41], v[54:57], v[72:75], v[38:41]
	ds_read_b128 v[76:79], v21 offset:18432
	s_waitcnt lgkmcnt(0)
	v_mfma_f32_16x16x32_f16 v[112:115], v[54:57], v[76:79], v[124:127]
	ds_read_b128 v[80:83], v16 offset:53248
	v_mfma_f32_16x16x32_f16 v[46:49], v[58:61], v[72:75], v[46:49]
	ds_read_b128 v[104:107], v16 offset:55296
	s_waitcnt lgkmcnt(1)
	v_mfma_f32_16x16x32_f16 v[108:111], v[80:83], v[72:75], v[116:119]
	v_mfma_f32_16x16x32_f16 v[116:119], v[58:61], v[76:79], v[128:131]
	ds_read_b128 v[124:127], v21 offset:22528
	s_waitcnt lgkmcnt(1)
	v_mfma_f32_16x16x32_f16 v[72:75], v[104:107], v[72:75], v[120:123]
	v_mfma_f32_16x16x32_f16 v[120:123], v[80:83], v[76:79], v[132:135]
	v_mfma_f32_16x16x32_f16 v[34:37], v[104:107], v[76:79], v[34:37]
	ds_read_b128 v[76:79], v21 offset:20480
	s_waitcnt lgkmcnt(0)
	v_mfma_f32_16x16x32_f16 v[128:131], v[54:57], v[76:79], v[140:143]
	v_mfma_f32_16x16x32_f16 v[42:45], v[54:57], v[124:127], v[42:45]
	ds_read_b128 v[54:57], v22 offset:49152
	v_mfma_f32_16x16x32_f16 v[132:135], v[58:61], v[76:79], v[144:147]
	s_nop 2
	ds_read_b128 v[144:147], v22 offset:55296
	v_mfma_f32_16x16x32_f16 v[24:27], v[58:61], v[124:127], v[24:27]
	ds_read_b128 v[58:61], v22 offset:51200
	s_waitcnt vmcnt(7)
	ds_write_b128 v17, v[162:165]
	v_mfma_f32_16x16x32_f16 v[140:143], v[80:83], v[76:79], v[154:157]
	s_waitcnt vmcnt(6)
	ds_write_b128 v18, v[166:169]
	v_mfma_f32_16x16x32_f16 v[28:31], v[80:83], v[124:127], v[28:31]
	ds_read_b128 v[80:83], v32 offset:16384
	v_mfma_f32_16x16x32_f16 v[76:79], v[104:107], v[76:79], v[158:161]
	s_waitcnt vmcnt(5)
	ds_write_b128 v19, v[200:203]
	v_mfma_f32_16x16x32_f16 v[50:53], v[104:107], v[124:127], v[50:53]
	ds_read_b128 v[104:107], v32 offset:18432
	s_waitcnt lgkmcnt(2)
	v_mfma_f32_16x16x32_f16 v[38:41], v[54:57], v[80:83], v[38:41]
	ds_read_b128 v[124:127], v22 offset:53248
	v_mfma_f32_16x16x32_f16 v[46:49], v[58:61], v[80:83], v[46:49]
	s_waitcnt lgkmcnt(0)
	v_mfma_f32_16x16x32_f16 v[108:111], v[124:127], v[80:83], v[108:111]
	v_mfma_f32_16x16x32_f16 v[72:75], v[144:147], v[80:83], v[72:75]
	v_mfma_f32_16x16x32_f16 v[80:83], v[54:57], v[104:107], v[112:115]
	s_waitcnt vmcnt(4)
	ds_write_b128 v20, v[204:207]
	s_waitcnt vmcnt(3)
	ds_write_b128 v17, v[136:139] offset:32768
	s_waitcnt vmcnt(2)
	ds_write_b128 v18, v[208:211] offset:32768
	s_waitcnt vmcnt(1)
	ds_write_b128 v19, v[212:215] offset:32768
	v_mfma_f32_16x16x32_f16 v[112:115], v[58:61], v[104:107], v[116:119]
	s_waitcnt vmcnt(0)
	ds_write_b128 v20, v[220:223] offset:32768
	v_mfma_f32_16x16x32_f16 v[116:119], v[124:127], v[104:107], v[120:123]
	s_nop 2
	ds_read_b128 v[120:123], v32 offset:22528
	v_mfma_f32_16x16x32_f16 v[34:37], v[144:147], v[104:107], v[34:37]
	ds_read_b128 v[104:107], v32 offset:20480
	s_waitcnt lgkmcnt(0)
	v_mfma_f32_16x16x32_f16 v[128:131], v[54:57], v[104:107], v[128:131]
	v_mfma_f32_16x16x32_f16 v[42:45], v[54:57], v[120:123], v[42:45]
	global_load_dwordx4 v[54:57], v[0:1], off offset:384
	v_mfma_f32_16x16x32_f16 v[132:135], v[58:61], v[104:107], v[132:135]
	v_mfma_f32_16x16x32_f16 v[24:27], v[58:61], v[120:123], v[24:27]
	v_mfma_f32_16x16x32_f16 v[140:143], v[124:127], v[104:107], v[140:143]
	v_mfma_f32_16x16x32_f16 v[28:31], v[124:127], v[120:123], v[28:31]
	v_mfma_f32_16x16x32_f16 v[76:79], v[144:147], v[104:107], v[76:79]
	global_load_dwordx4 v[104:107], v[2:3], off offset:384
	global_load_dwordx4 v[154:157], v[4:5], off offset:384
	global_load_dwordx4 v[158:161], v[6:7], off offset:384
	global_load_dwordx4 v[58:61], v[8:9], off offset:384
	global_load_dwordx4 v[188:191], v[10:11], off offset:384
	global_load_dwordx4 v[192:195], v[12:13], off offset:384
	global_load_dwordx4 v[196:199], v[14:15], off offset:384
	s_waitcnt lgkmcnt(0)
	s_barrier
; #define GL_LOAD(s_, kt_) if (VAR != 1) { a##s_##0 = GL_A(0, kt_); a##s_##1 = GL_A(1, kt_); a##s_##2 = GL_A(2, kt_); a##s_##3 = GL_A(3, kt_); b##s_##0 = GL_B(0, kt_); b##s_##1 = GL_B(1, kt_); b##s_##2 = GL_B(2, kt_); b##s_##3 = GL_B(3, kt_); }
; #define LDS_STORE(s_, buf_) if (VAR != 2) { LDS_ST1(sA, 0, buf_, a##s_##0) LDS_ST1(sA, 1, buf_, a##s_##1) LDS_ST1(sA, 2, buf_, a##s_##2) LDS_ST1(sA, 3, buf_, a##s_##3) LDS_ST1(sB, 0, buf_, b##s_##0) LDS_ST1(sB, 1, buf_, b##s_##1) LDS_ST1(sB, 2, buf_, b##s_##2) LDS_ST1(sB, 3, buf_, b##s_##3) }
;     ...
;   for (int kt = 0; kt < nk; kt += 2) {
;     if (kt + 2 < nk) { GL_LOAD(0, kt + 2) }
;     MMA_TILE(0)
;     LDS_STORE(1, 1)
;     if (VAR != 4) __syncthreads();
;     if (kt + 3 < nk) { GL_LOAD(1, kt + 3) }
;     MMA_TILE(1)
;     if (kt + 2 < nk) { LDS_STORE(0, 0) }
;     if (VAR != 4) __syncthreads();
	v_mfma_f32_16x16x32_f16 v[50:53], v[144:147], v[120:123], v[50:53]
	ds_read_b128 v[124:127], v16 offset:32768
	ds_read_b128 v[136:139], v21
	s_waitcnt lgkmcnt(0)
	v_mfma_f32_16x16x32_f16 v[38:41], v[124:127], v[136:139], v[38:41]
	ds_read_b128 v[120:123], v16 offset:34816
	ds_read_b128 v[144:147], v21 offset:2048
	s_waitcnt lgkmcnt(0)
	v_mfma_f32_16x16x32_f16 v[80:83], v[124:127], v[144:147], v[80:83]
	ds_read_b128 v[162:165], v16 offset:36864
	v_mfma_f32_16x16x32_f16 v[46:49], v[120:123], v[136:139], v[46:49]
	ds_read_b128 v[166:169], v16 offset:38912
	v_mfma_f32_16x16x32_f16 v[112:115], v[120:123], v[144:147], v[112:115]
	s_waitcnt lgkmcnt(1)
	v_mfma_f32_16x16x32_f16 v[108:111], v[162:165], v[136:139], v[108:111]
	v_mfma_f32_16x16x32_f16 v[116:119], v[162:165], v[144:147], v[116:119]
	s_waitcnt lgkmcnt(0)
	v_mfma_f32_16x16x32_f16 v[72:75], v[166:169], v[136:139], v[72:75]
	ds_read_b128 v[136:139], v21 offset:4096
	v_mfma_f32_16x16x32_f16 v[34:37], v[166:169], v[144:147], v[34:37]
	ds_read_b128 v[144:147], v21 offset:6144
	s_waitcnt lgkmcnt(1)
	v_mfma_f32_16x16x32_f16 v[128:131], v[124:127], v[136:139], v[128:131]
	s_waitcnt lgkmcnt(0)
	v_mfma_f32_16x16x32_f16 v[42:45], v[124:127], v[144:147], v[42:45]
	ds_read_b128 v[124:127], v22 offset:34816
	v_mfma_f32_16x16x32_f16 v[132:135], v[120:123], v[136:139], v[132:135]
	v_mfma_f32_16x16x32_f16 v[24:27], v[120:123], v[144:147], v[24:27]
	ds_read_b128 v[120:123], v22 offset:32768
	v_mfma_f32_16x16x32_f16 v[140:143], v[162:165], v[136:139], v[140:143]
	s_waitcnt vmcnt(7)
	ds_write_b128 v17, v[54:57] offset:16384
	s_waitcnt vmcnt(6)
	ds_write_b128 v18, v[104:107] offset:16384
	v_mfma_f32_16x16x32_f16 v[28:31], v[162:165], v[144:147], v[28:31]
	ds_read_b128 v[162:165], v22 offset:36864
	s_waitcnt vmcnt(5)
	ds_write_b128 v19, v[154:157] offset:16384
	v_mfma_f32_16x16x32_f16 v[76:79], v[166:169], v[136:139], v[76:79]
	ds_read_b128 v[136:139], v32
	v_mfma_f32_16x16x32_f16 v[50:53], v[166:169], v[144:147], v[50:53]
	ds_read_b128 v[144:147], v32 offset:2048
	s_waitcnt lgkmcnt(1)
	v_mfma_f32_16x16x32_f16 v[38:41], v[120:123], v[136:139], v[38:41]
	ds_read_b128 v[166:169], v22 offset:38912
	s_waitcnt lgkmcnt(1)
	v_mfma_f32_16x16x32_f16 v[80:83], v[120:123], v[144:147], v[80:83]
	s_waitcnt vmcnt(4)
	ds_write_b128 v20, v[158:161] offset:16384
	v_mfma_f32_16x16x32_f16 v[46:49], v[124:127], v[136:139], v[46:49]
	s_waitcnt vmcnt(3)
	ds_write_b128 v17, v[58:61] offset:49152
	v_mfma_f32_16x16x32_f16 v[112:115], v[124:127], v[144:147], v[112:115]
	s_waitcnt vmcnt(2)
	ds_write_b128 v18, v[188:191] offset:49152
	v_mfma_f32_16x16x32_f16 v[108:111], v[162:165], v[136:139], v[108:111]
	s_waitcnt vmcnt(1)
	ds_write_b128 v19, v[192:195] offset:49152
	v_mfma_f32_16x16x32_f16 v[116:119], v[162:165], v[144:147], v[116:119]
	s_waitcnt vmcnt(0)
	ds_write_b128 v20, v[196:199] offset:49152
	s_waitcnt lgkmcnt(5)
	v_mfma_f32_16x16x32_f16 v[72:75], v[166:169], v[136:139], v[72:75]
	ds_read_b128 v[136:139], v32 offset:4096
	v_mfma_f32_16x16x32_f16 v[34:37], v[166:169], v[144:147], v[34:37]
	ds_read_b128 v[144:147], v32 offset:6144
	s_waitcnt lgkmcnt(1)
	v_mfma_f32_16x16x32_f16 v[128:131], v[120:123], v[136:139], v[128:131]
	s_waitcnt lgkmcnt(0)
	v_mfma_f32_16x16x32_f16 v[42:45], v[120:123], v[144:147], v[42:45]
	global_load_dwordx4 v[120:123], v[0:1], off offset:512
	v_mfma_f32_16x16x32_f16 v[132:135], v[124:127], v[136:139], v[132:135]
	v_mfma_f32_16x16x32_f16 v[24:27], v[124:127], v[144:147], v[24:27]
	v_mfma_f32_16x16x32_f16 v[140:143], v[162:165], v[136:139], v[140:143]
	v_mfma_f32_16x16x32_f16 v[28:31], v[162:165], v[144:147], v[28:31]
	v_mfma_f32_16x16x32_f16 v[76:79], v[166:169], v[136:139], v[76:79]
	global_load_dwordx4 v[136:139], v[2:3], off offset:512
	global_load_dwordx4 v[200:203], v[4:5], off offset:512
	global_load_dwordx4 v[204:207], v[6:7], off offset:512
	global_load_dwordx4 v[124:127], v[8:9], off offset:512
	global_load_dwordx4 v[208:211], v[10:11], off offset:512
	global_load_dwordx4 v[212:215], v[12:13], off offset:512
	global_load_dwordx4 v[220:223], v[14:15], off offset:512
	s_waitcnt lgkmcnt(0)
	s_barrier
	v_mfma_f32_16x16x32_f16 v[50:53], v[166:169], v[144:147], v[50:53]
	ds_read_b128 v[54:57], v16 offset:49152
	ds_read_b128 v[104:107], v21 offset:16384
	s_waitcnt lgkmcnt(0)
	v_mfma_f32_16x16x32_f16 v[38:41], v[54:57], v[104:107], v[38:41]
	ds_read_b128 v[58:61], v16 offset:51200
	ds_read_b128 v[144:147], v21 offset:18432
	s_waitcnt lgkmcnt(0)
	v_mfma_f32_16x16x32_f16 v[80:83], v[54:57], v[144:147], v[80:83]
	ds_read_b128 v[154:157], v16 offset:53248
	v_mfma_f32_16x16x32_f16 v[46:49], v[58:61], v[104:107], v[46:49]
	ds_read_b128 v[158:161], v16 offset:55296
	s_waitcnt lgkmcnt(1)
	v_mfma_f32_16x16x32_f16 v[108:111], v[154:157], v[104:107], v[108:111]
	s_waitcnt lgkmcnt(0)
	v_mfma_f32_16x16x32_f16 v[72:75], v[158:161], v[104:107], v[72:75]
	v_mfma_f32_16x16x32_f16 v[104:107], v[58:61], v[144:147], v[112:115]
	v_mfma_f32_16x16x32_f16 v[112:115], v[154:157], v[144:147], v[116:119]
	s_nop 2
	ds_read_b128 v[116:119], v21 offset:20480
	v_mfma_f32_16x16x32_f16 v[34:37], v[158:161], v[144:147], v[34:37]
	ds_read_b128 v[144:147], v21 offset:22528
	s_waitcnt lgkmcnt(1)
	v_mfma_f32_16x16x32_f16 v[128:131], v[54:57], v[116:119], v[128:131]
	s_waitcnt lgkmcnt(0)
	v_mfma_f32_16x16x32_f16 v[42:45], v[54:57], v[144:147], v[42:45]
	ds_read_b128 v[54:57], v22 offset:49152
	v_mfma_f32_16x16x32_f16 v[132:135], v[58:61], v[116:119], v[132:135]
	v_mfma_f32_16x16x32_f16 v[24:27], v[58:61], v[144:147], v[24:27]
	ds_read_b128 v[58:61], v22 offset:51200
	v_mfma_f32_16x16x32_f16 v[140:143], v[154:157], v[116:119], v[140:143]
	s_waitcnt vmcnt(7)
; #define GL_LOAD(s_, kt_) if (VAR != 1) { a##s_##0 = GL_A(0, kt_); a##s_##1 = GL_A(1, kt_); a##s_##2 = GL_A(2, kt_); a##s_##3 = GL_A(3, kt_); b##s_##0 = GL_B(0, kt_); b##s_##1 = GL_B(1, kt_); b##s_##2 = GL_B(2, kt_); b##s_##3 = GL_B(3, kt_); }
; #define LDS_STORE(s_, buf_) if (VAR != 2) { LDS_ST1(sA, 0, buf_, a##s_##0) LDS_ST1(sA, 1, buf_, a##s_##1) LDS_ST1(sA, 2, buf_, a##s_##2) LDS_ST1(sA, 3, buf_, a##s_##3) LDS_ST1(sB, 0, buf_, b##s_##0) LDS_ST1(sB, 1, buf_, b##s_##1) LDS_ST1(sB, 2, buf_, b##s_##2) LDS_ST1(sB, 3, buf_, b##s_##3) }
;     ...
;   for (int kt = 0; kt < nk; kt += 2) {
;     if (kt + 2 < nk) { GL_LOAD(0, kt + 2) }
;     MMA_TILE(0)
;     LDS_STORE(1, 1)
;     if (VAR != 4) __syncthreads();
;     if (kt + 3 < nk) { GL_LOAD(1, kt + 3) }
;     MMA_TILE(1)
;     if (kt + 2 < nk) { LDS_STORE(0, 0) }
;     if (VAR != 4) __syncthreads();
	ds_write_b128 v17, v[120:123]
	s_waitcnt vmcnt(6)
	ds_write_b128 v18, v[136:139]
	v_mfma_f32_16x16x32_f16 v[28:31], v[154:157], v[144:147], v[28:31]
	ds_read_b128 v[154:157], v22 offset:53248
	s_waitcnt vmcnt(5)
	ds_write_b128 v19, v[200:203]
	v_mfma_f32_16x16x32_f16 v[76:79], v[158:161], v[116:119], v[76:79]
	ds_read_b128 v[116:119], v32 offset:16384
	v_mfma_f32_16x16x32_f16 v[50:53], v[158:161], v[144:147], v[50:53]
	ds_read_b128 v[144:147], v32 offset:18432
	s_waitcnt lgkmcnt(1)
	v_mfma_f32_16x16x32_f16 v[38:41], v[54:57], v[116:119], v[38:41]
	ds_read_b128 v[158:161], v22 offset:55296
	s_waitcnt lgkmcnt(1)
	v_mfma_f32_16x16x32_f16 v[80:83], v[54:57], v[144:147], v[80:83]
	s_waitcnt vmcnt(4)
	ds_write_b128 v20, v[204:207]
	v_mfma_f32_16x16x32_f16 v[46:49], v[58:61], v[116:119], v[46:49]
	s_waitcnt vmcnt(3)
	ds_write_b128 v17, v[124:127] offset:32768
	v_mfma_f32_16x16x32_f16 v[104:107], v[58:61], v[144:147], v[104:107]
	s_waitcnt vmcnt(2)
	ds_write_b128 v18, v[208:211] offset:32768
	v_mfma_f32_16x16x32_f16 v[108:111], v[154:157], v[116:119], v[108:111]
	s_waitcnt vmcnt(1)
	ds_write_b128 v19, v[212:215] offset:32768
	v_mfma_f32_16x16x32_f16 v[112:115], v[154:157], v[144:147], v[112:115]
	s_waitcnt vmcnt(0)
	ds_write_b128 v20, v[220:223] offset:32768
	s_waitcnt lgkmcnt(5)
	v_mfma_f32_16x16x32_f16 v[72:75], v[158:161], v[116:119], v[72:75]
	ds_read_b128 v[116:119], v32 offset:20480
	v_mfma_f32_16x16x32_f16 v[34:37], v[158:161], v[144:147], v[34:37]
	ds_read_b128 v[144:147], v32 offset:22528
	s_waitcnt lgkmcnt(1)
	v_mfma_f32_16x16x32_f16 v[128:131], v[54:57], v[116:119], v[128:131]
	s_waitcnt lgkmcnt(0)
	v_mfma_f32_16x16x32_f16 v[42:45], v[54:57], v[144:147], v[42:45]
	global_load_dwordx4 v[54:57], v[0:1], off offset:640
	v_mfma_f32_16x16x32_f16 v[132:135], v[58:61], v[116:119], v[132:135]
	v_mfma_f32_16x16x32_f16 v[24:27], v[58:61], v[144:147], v[24:27]
	v_mfma_f32_16x16x32_f16 v[140:143], v[154:157], v[116:119], v[140:143]
	v_mfma_f32_16x16x32_f16 v[28:31], v[154:157], v[144:147], v[28:31]
	v_mfma_f32_16x16x32_f16 v[76:79], v[158:161], v[116:119], v[76:79]
	global_load_dwordx4 v[116:119], v[2:3], off offset:640
	global_load_dwordx4 v[162:165], v[4:5], off offset:640
	global_load_dwordx4 v[166:169], v[6:7], off offset:640
	global_load_dwordx4 v[58:61], v[8:9], off offset:640
	global_load_dwordx4 v[188:191], v[10:11], off offset:640
	global_load_dwordx4 v[192:195], v[12:13], off offset:640
	global_load_dwordx4 v[196:199], v[14:15], off offset:640
	s_waitcnt lgkmcnt(0)
	s_barrier
	v_mfma_f32_16x16x32_f16 v[50:53], v[158:161], v[144:147], v[50:53]
	ds_read_b128 v[120:123], v16 offset:32768
	ds_read_b128 v[136:139], v21
	s_waitcnt lgkmcnt(0)
	v_mfma_f32_16x16x32_f16 v[38:41], v[120:123], v[136:139], v[38:41]
	ds_read_b128 v[124:127], v16 offset:34816
	ds_read_b128 v[144:147], v21 offset:2048
	s_waitcnt lgkmcnt(0)
	v_mfma_f32_16x16x32_f16 v[80:83], v[120:123], v[144:147], v[80:83]
	ds_read_b128 v[154:157], v16 offset:36864
	v_mfma_f32_16x16x32_f16 v[46:49], v[124:127], v[136:139], v[46:49]
	ds_read_b128 v[158:161], v16 offset:38912
	v_mfma_f32_16x16x32_f16 v[104:107], v[124:127], v[144:147], v[104:107]
	s_waitcnt lgkmcnt(1)
	v_mfma_f32_16x16x32_f16 v[108:111], v[154:157], v[136:139], v[108:111]
	v_mfma_f32_16x16x32_f16 v[112:115], v[154:157], v[144:147], v[112:115]
	s_waitcnt lgkmcnt(0)
	v_mfma_f32_16x16x32_f16 v[72:75], v[158:161], v[136:139], v[72:75]
	ds_read_b128 v[136:139], v21 offset:4096
	v_mfma_f32_16x16x32_f16 v[34:37], v[158:161], v[144:147], v[34:37]
	ds_read_b128 v[144:147], v21 offset:6144
	s_waitcnt lgkmcnt(1)
	v_mfma_f32_16x16x32_f16 v[128:131], v[120:123], v[136:139], v[128:131]
	s_waitcnt lgkmcnt(0)
	v_mfma_f32_16x16x32_f16 v[42:45], v[120:123], v[144:147], v[42:45]
	ds_read_b128 v[120:123], v22 offset:32768
	v_mfma_f32_16x16x32_f16 v[132:135], v[124:127], v[136:139], v[132:135]
	v_mfma_f32_16x16x32_f16 v[24:27], v[124:127], v[144:147], v[24:27]
	ds_read_b128 v[124:127], v22 offset:34816
	v_mfma_f32_16x16x32_f16 v[140:143], v[154:157], v[136:139], v[140:143]
	s_waitcnt vmcnt(7)
	ds_write_b128 v17, v[54:57] offset:16384
	s_waitcnt vmcnt(6)
	ds_write_b128 v18, v[116:119] offset:16384
	v_mfma_f32_16x16x32_f16 v[28:31], v[154:157], v[144:147], v[28:31]
	ds_read_b128 v[154:157], v22 offset:36864
	s_waitcnt vmcnt(5)
	ds_write_b128 v19, v[162:165] offset:16384
	v_mfma_f32_16x16x32_f16 v[76:79], v[158:161], v[136:139], v[76:79]
	ds_read_b128 v[136:139], v32
	v_mfma_f32_16x16x32_f16 v[50:53], v[158:161], v[144:147], v[50:53]
	ds_read_b128 v[144:147], v32 offset:2048
	s_waitcnt lgkmcnt(1)
	v_mfma_f32_16x16x32_f16 v[38:41], v[120:123], v[136:139], v[38:41]
	ds_read_b128 v[158:161], v22 offset:38912
	s_waitcnt lgkmcnt(1)
	v_mfma_f32_16x16x32_f16 v[80:83], v[120:123], v[144:147], v[80:83]
	s_waitcnt vmcnt(4)
	ds_write_b128 v20, v[166:169] offset:16384
	v_mfma_f32_16x16x32_f16 v[46:49], v[124:127], v[136:139], v[46:49]
	s_waitcnt vmcnt(3)
	ds_write_b128 v17, v[58:61] offset:49152
	v_mfma_f32_16x16x32_f16 v[104:107], v[124:127], v[144:147], v[104:107]
	s_waitcnt vmcnt(2)
	ds_write_b128 v18, v[188:191] offset:49152
	v_mfma_f32_16x16x32_f16 v[108:111], v[154:157], v[136:139], v[108:111]
	s_waitcnt vmcnt(1)
	ds_write_b128 v19, v[192:195] offset:49152
	v_mfma_f32_16x16x32_f16 v[112:115], v[154:157], v[144:147], v[112:115]
	s_waitcnt vmcnt(0)
	ds_write_b128 v20, v[196:199] offset:49152
	s_waitcnt lgkmcnt(5)
	v_mfma_f32_16x16x32_f16 v[72:75], v[158:161], v[136:139], v[72:75]
	ds_read_b128 v[136:139], v32 offset:4096
	v_mfma_f32_16x16x32_f16 v[34:37], v[158:161], v[144:147], v[34:37]
	ds_read_b128 v[144:147], v32 offset:6144
	s_waitcnt lgkmcnt(1)
	v_mfma_f32_16x16x32_f16 v[128:131], v[120:123], v[136:139], v[128:131]
	s_waitcnt lgkmcnt(0)
	v_mfma_f32_16x16x32_f16 v[42:45], v[120:123], v[144:147], v[42:45]
	global_load_dwordx4 v[120:123], v[0:1], off offset:768
	v_mfma_f32_16x16x32_f16 v[132:135], v[124:127], v[136:139], v[132:135]
	v_mfma_f32_16x16x32_f16 v[24:27], v[124:127], v[144:147], v[24:27]
	v_mfma_f32_16x16x32_f16 v[140:143], v[154:157], v[136:139], v[140:143]
	v_mfma_f32_16x16x32_f16 v[28:31], v[154:157], v[144:147], v[28:31]
	v_mfma_f32_16x16x32_f16 v[76:79], v[158:161], v[136:139], v[76:79]
	global_load_dwordx4 v[136:139], v[2:3], off offset:768
	global_load_dwordx4 v[200:203], v[4:5], off offset:768
	global_load_dwordx4 v[204:207], v[6:7], off offset:768
	global_load_dwordx4 v[124:127], v[8:9], off offset:768
	global_load_dwordx4 v[208:211], v[10:11], off offset:768
	global_load_dwordx4 v[212:215], v[12:13], off offset:768
	global_load_dwordx4 v[220:223], v[14:15], off offset:768
	s_waitcnt lgkmcnt(0)
	s_barrier
; #define GL_LOAD(s_, kt_) if (VAR != 1) { a##s_##0 = GL_A(0, kt_); a##s_##1 = GL_A(1, kt_); a##s_##2 = GL_A(2, kt_); a##s_##3 = GL_A(3, kt_); b##s_##0 = GL_B(0, kt_); b##s_##1 = GL_B(1, kt_); b##s_##2 = GL_B(2, kt_); b##s_##3 = GL_B(3, kt_); }
; #define LDS_STORE(s_, buf_) if (VAR != 2) { LDS_ST1(sA, 0, buf_, a##s_##0) LDS_ST1(sA, 1, buf_, a##s_##1) LDS_ST1(sA, 2, buf_, a##s_##2) LDS_ST1(sA, 3, buf_, a##s_##3) LDS_ST1(sB, 0, buf_, b##s_##0) LDS_ST1(sB, 1, buf_, b##s_##1) LDS_ST1(sB, 2, buf_, b##s_##2) LDS_ST1(sB, 3, buf_, b##s_##3) }
;     ...
;   for (int kt = 0; kt < nk; kt += 2) {
;     if (kt + 2 < nk) { GL_LOAD(0, kt + 2) }
;     MMA_TILE(0)
;     LDS_STORE(1, 1)
;     if (VAR != 4) __syncthreads();
;     if (kt + 3 < nk) { GL_LOAD(1, kt + 3) }
;     MMA_TILE(1)
;     if (kt + 2 < nk) { LDS_STORE(0, 0) }
;     if (VAR != 4) __syncthreads();
	v_mfma_f32_16x16x32_f16 v[50:53], v[158:161], v[144:147], v[50:53]
	ds_read_b128 v[54:57], v16 offset:49152
	ds_read_b128 v[116:119], v21 offset:16384
	s_waitcnt lgkmcnt(0)
	v_mfma_f32_16x16x32_f16 v[38:41], v[54:57], v[116:119], v[38:41]
	ds_read_b128 v[58:61], v16 offset:51200
	ds_read_b128 v[144:147], v21 offset:18432
	s_waitcnt lgkmcnt(0)
	v_mfma_f32_16x16x32_f16 v[80:83], v[54:57], v[144:147], v[80:83]
	ds_read_b128 v[154:157], v16 offset:53248
	v_mfma_f32_16x16x32_f16 v[46:49], v[58:61], v[116:119], v[46:49]
	ds_read_b128 v[158:161], v16 offset:55296
	v_mfma_f32_16x16x32_f16 v[104:107], v[58:61], v[144:147], v[104:107]
	s_waitcnt lgkmcnt(1)
	v_mfma_f32_16x16x32_f16 v[108:111], v[154:157], v[116:119], v[108:111]
	v_mfma_f32_16x16x32_f16 v[112:115], v[154:157], v[144:147], v[112:115]
	s_waitcnt lgkmcnt(0)
	v_mfma_f32_16x16x32_f16 v[72:75], v[158:161], v[116:119], v[72:75]
	ds_read_b128 v[116:119], v21 offset:20480
	v_mfma_f32_16x16x32_f16 v[34:37], v[158:161], v[144:147], v[34:37]
	ds_read_b128 v[144:147], v21 offset:22528
	s_waitcnt lgkmcnt(1)
	v_mfma_f32_16x16x32_f16 v[128:131], v[54:57], v[116:119], v[128:131]
	s_waitcnt lgkmcnt(0)
	v_mfma_f32_16x16x32_f16 v[42:45], v[54:57], v[144:147], v[42:45]
	ds_read_b128 v[54:57], v22 offset:49152
	v_mfma_f32_16x16x32_f16 v[132:135], v[58:61], v[116:119], v[132:135]
	v_mfma_f32_16x16x32_f16 v[24:27], v[58:61], v[144:147], v[24:27]
	ds_read_b128 v[58:61], v22 offset:51200
	v_mfma_f32_16x16x32_f16 v[140:143], v[154:157], v[116:119], v[140:143]
	s_waitcnt vmcnt(7)
	ds_write_b128 v17, v[120:123]
	s_waitcnt vmcnt(6)
	ds_write_b128 v18, v[136:139]
	v_mfma_f32_16x16x32_f16 v[28:31], v[154:157], v[144:147], v[28:31]
	ds_read_b128 v[154:157], v22 offset:53248
	s_waitcnt vmcnt(5)
	ds_write_b128 v19, v[200:203]
	v_mfma_f32_16x16x32_f16 v[76:79], v[158:161], v[116:119], v[76:79]
	ds_read_b128 v[116:119], v32 offset:16384
	v_mfma_f32_16x16x32_f16 v[50:53], v[158:161], v[144:147], v[50:53]
	ds_read_b128 v[144:147], v32 offset:18432
	s_waitcnt lgkmcnt(1)
	v_mfma_f32_16x16x32_f16 v[38:41], v[54:57], v[116:119], v[38:41]
	ds_read_b128 v[158:161], v22 offset:55296
	s_waitcnt lgkmcnt(1)
	v_mfma_f32_16x16x32_f16 v[80:83], v[54:57], v[144:147], v[80:83]
	s_waitcnt vmcnt(4)
	ds_write_b128 v20, v[204:207]
	v_mfma_f32_16x16x32_f16 v[46:49], v[58:61], v[116:119], v[46:49]
	s_waitcnt vmcnt(3)
	ds_write_b128 v17, v[124:127] offset:32768
	v_mfma_f32_16x16x32_f16 v[104:107], v[58:61], v[144:147], v[104:107]
	s_waitcnt vmcnt(2)
	ds_write_b128 v18, v[208:211] offset:32768
	v_mfma_f32_16x16x32_f16 v[108:111], v[154:157], v[116:119], v[108:111]
	s_waitcnt vmcnt(1)
	ds_write_b128 v19, v[212:215] offset:32768
	v_mfma_f32_16x16x32_f16 v[112:115], v[154:157], v[144:147], v[112:115]
	s_waitcnt vmcnt(0)
	ds_write_b128 v20, v[220:223] offset:32768
	s_waitcnt lgkmcnt(5)
	v_mfma_f32_16x16x32_f16 v[72:75], v[158:161], v[116:119], v[72:75]
	ds_read_b128 v[116:119], v32 offset:20480
	v_mfma_f32_16x16x32_f16 v[34:37], v[158:161], v[144:147], v[34:37]
	ds_read_b128 v[144:147], v32 offset:22528
	s_waitcnt lgkmcnt(1)
	v_mfma_f32_16x16x32_f16 v[128:131], v[54:57], v[116:119], v[128:131]
	s_waitcnt lgkmcnt(0)
	v_mfma_f32_16x16x32_f16 v[42:45], v[54:57], v[144:147], v[42:45]
	global_load_dwordx4 v[54:57], v[0:1], off offset:896
	v_mfma_f32_16x16x32_f16 v[132:135], v[58:61], v[116:119], v[132:135]
	v_mfma_f32_16x16x32_f16 v[24:27], v[58:61], v[144:147], v[24:27]
	v_mfma_f32_16x16x32_f16 v[140:143], v[154:157], v[116:119], v[140:143]
	v_mfma_f32_16x16x32_f16 v[28:31], v[154:157], v[144:147], v[28:31]
	v_mfma_f32_16x16x32_f16 v[76:79], v[158:161], v[116:119], v[76:79]
	global_load_dwordx4 v[116:119], v[2:3], off offset:896
	global_load_dwordx4 v[162:165], v[4:5], off offset:896
	global_load_dwordx4 v[166:169], v[6:7], off offset:896
	global_load_dwordx4 v[58:61], v[8:9], off offset:896
	global_load_dwordx4 v[188:191], v[10:11], off offset:896
	global_load_dwordx4 v[192:195], v[12:13], off offset:896
	global_load_dwordx4 v[196:199], v[14:15], off offset:896
	s_waitcnt lgkmcnt(0)
	s_barrier
	v_mfma_f32_16x16x32_f16 v[50:53], v[158:161], v[144:147], v[50:53]
	ds_read_b128 v[120:123], v16 offset:32768
	ds_read_b128 v[136:139], v21
	s_waitcnt lgkmcnt(0)
	v_mfma_f32_16x16x32_f16 v[38:41], v[120:123], v[136:139], v[38:41]
	ds_read_b128 v[124:127], v16 offset:34816
	ds_read_b128 v[144:147], v21 offset:2048
	s_waitcnt lgkmcnt(0)
	v_mfma_f32_16x16x32_f16 v[80:83], v[120:123], v[144:147], v[80:83]
	ds_read_b128 v[154:157], v16 offset:36864
	v_mfma_f32_16x16x32_f16 v[46:49], v[124:127], v[136:139], v[46:49]
	ds_read_b128 v[158:161], v16 offset:38912
	v_mfma_f32_16x16x32_f16 v[104:107], v[124:127], v[144:147], v[104:107]
	s_waitcnt lgkmcnt(1)
	v_mfma_f32_16x16x32_f16 v[108:111], v[154:157], v[136:139], v[108:111]
	v_mfma_f32_16x16x32_f16 v[112:115], v[154:157], v[144:147], v[112:115]
	s_waitcnt lgkmcnt(0)
	v_mfma_f32_16x16x32_f16 v[72:75], v[158:161], v[136:139], v[72:75]
	ds_read_b128 v[136:139], v21 offset:4096
	v_mfma_f32_16x16x32_f16 v[34:37], v[158:161], v[144:147], v[34:37]
	ds_read_b128 v[144:147], v21 offset:6144
	s_waitcnt lgkmcnt(1)
	v_mfma_f32_16x16x32_f16 v[128:131], v[120:123], v[136:139], v[128:131]
	s_waitcnt lgkmcnt(0)
	v_mfma_f32_16x16x32_f16 v[42:45], v[120:123], v[144:147], v[42:45]
	ds_read_b128 v[120:123], v22 offset:32768
	v_mfma_f32_16x16x32_f16 v[132:135], v[124:127], v[136:139], v[132:135]
	v_mfma_f32_16x16x32_f16 v[24:27], v[124:127], v[144:147], v[24:27]
	ds_read_b128 v[124:127], v22 offset:34816
	v_mfma_f32_16x16x32_f16 v[140:143], v[154:157], v[136:139], v[140:143]
	s_waitcnt vmcnt(7)
	ds_write_b128 v17, v[54:57] offset:16384
	s_waitcnt vmcnt(6)
; #define GL_LOAD(s_, kt_) if (VAR != 1) { a##s_##0 = GL_A(0, kt_); a##s_##1 = GL_A(1, kt_); a##s_##2 = GL_A(2, kt_); a##s_##3 = GL_A(3, kt_); b##s_##0 = GL_B(0, kt_); b##s_##1 = GL_B(1, kt_); b##s_##2 = GL_B(2, kt_); b##s_##3 = GL_B(3, kt_); }
; #define LDS_STORE(s_, buf_) if (VAR != 2) { LDS_ST1(sA, 0, buf_, a##s_##0) LDS_ST1(sA, 1, buf_, a##s_##1) LDS_ST1(sA, 2, buf_, a##s_##2) LDS_ST1(sA, 3, buf_, a##s_##3) LDS_ST1(sB, 0, buf_, b##s_##0) LDS_ST1(sB, 1, buf_, b##s_##1) LDS_ST1(sB, 2, buf_, b##s_##2) LDS_ST1(sB, 3, buf_, b##s_##3) }
;     ...
;   for (int kt = 0; kt < nk; kt += 2) {
;     if (kt + 2 < nk) { GL_LOAD(0, kt + 2) }
;     MMA_TILE(0)
;     LDS_STORE(1, 1)
;     if (VAR != 4) __syncthreads();
;     if (kt + 3 < nk) { GL_LOAD(1, kt + 3) }
;     MMA_TILE(1)
;     if (kt + 2 < nk) { LDS_STORE(0, 0) }
;     if (VAR != 4) __syncthreads();
	ds_write_b128 v18, v[116:119] offset:16384
	v_mfma_f32_16x16x32_f16 v[28:31], v[154:157], v[144:147], v[28:31]
	ds_read_b128 v[154:157], v22 offset:36864
	s_waitcnt vmcnt(5)
	ds_write_b128 v19, v[162:165] offset:16384
	v_mfma_f32_16x16x32_f16 v[76:79], v[158:161], v[136:139], v[76:79]
	ds_read_b128 v[136:139], v32
	v_mfma_f32_16x16x32_f16 v[50:53], v[158:161], v[144:147], v[50:53]
	ds_read_b128 v[144:147], v32 offset:2048
	s_waitcnt lgkmcnt(1)
	v_mfma_f32_16x16x32_f16 v[38:41], v[120:123], v[136:139], v[38:41]
	ds_read_b128 v[158:161], v22 offset:38912
	s_waitcnt lgkmcnt(1)
	v_mfma_f32_16x16x32_f16 v[80:83], v[120:123], v[144:147], v[80:83]
	s_waitcnt vmcnt(4)
	ds_write_b128 v20, v[166:169] offset:16384
	v_mfma_f32_16x16x32_f16 v[46:49], v[124:127], v[136:139], v[46:49]
	s_waitcnt vmcnt(3)
	ds_write_b128 v17, v[58:61] offset:49152
	v_mfma_f32_16x16x32_f16 v[104:107], v[124:127], v[144:147], v[104:107]
	s_waitcnt vmcnt(2)
	ds_write_b128 v18, v[188:191] offset:49152
	v_mfma_f32_16x16x32_f16 v[108:111], v[154:157], v[136:139], v[108:111]
	s_waitcnt vmcnt(1)
	ds_write_b128 v19, v[192:195] offset:49152
	v_mfma_f32_16x16x32_f16 v[112:115], v[154:157], v[144:147], v[112:115]
	s_waitcnt vmcnt(0)
	ds_write_b128 v20, v[196:199] offset:49152
	s_waitcnt lgkmcnt(5)
	v_mfma_f32_16x16x32_f16 v[72:75], v[158:161], v[136:139], v[72:75]
	ds_read_b128 v[136:139], v32 offset:4096
	v_mfma_f32_16x16x32_f16 v[34:37], v[158:161], v[144:147], v[34:37]
	ds_read_b128 v[144:147], v32 offset:6144
	s_waitcnt lgkmcnt(1)
	v_mfma_f32_16x16x32_f16 v[128:131], v[120:123], v[136:139], v[128:131]
	s_waitcnt lgkmcnt(0)
	v_mfma_f32_16x16x32_f16 v[42:45], v[120:123], v[144:147], v[42:45]
	global_load_dwordx4 v[120:123], v[0:1], off offset:1024
	v_mfma_f32_16x16x32_f16 v[132:135], v[124:127], v[136:139], v[132:135]
	v_mfma_f32_16x16x32_f16 v[24:27], v[124:127], v[144:147], v[24:27]
	v_mfma_f32_16x16x32_f16 v[140:143], v[154:157], v[136:139], v[140:143]
	v_mfma_f32_16x16x32_f16 v[28:31], v[154:157], v[144:147], v[28:31]
	v_mfma_f32_16x16x32_f16 v[76:79], v[158:161], v[136:139], v[76:79]
	global_load_dwordx4 v[136:139], v[2:3], off offset:1024
	global_load_dwordx4 v[200:203], v[4:5], off offset:1024
	global_load_dwordx4 v[204:207], v[6:7], off offset:1024
	global_load_dwordx4 v[124:127], v[8:9], off offset:1024
	global_load_dwordx4 v[208:211], v[10:11], off offset:1024
	global_load_dwordx4 v[212:215], v[12:13], off offset:1024
	global_load_dwordx4 v[220:223], v[14:15], off offset:1024
	s_waitcnt lgkmcnt(0)
	s_barrier
	v_mfma_f32_16x16x32_f16 v[50:53], v[158:161], v[144:147], v[50:53]
	ds_read_b128 v[54:57], v16 offset:49152
	ds_read_b128 v[116:119], v21 offset:16384
	s_waitcnt lgkmcnt(0)
	v_mfma_f32_16x16x32_f16 v[38:41], v[54:57], v[116:119], v[38:41]
	ds_read_b128 v[58:61], v16 offset:51200
	ds_read_b128 v[144:147], v21 offset:18432
	s_waitcnt lgkmcnt(0)
	v_mfma_f32_16x16x32_f16 v[80:83], v[54:57], v[144:147], v[80:83]
	ds_read_b128 v[154:157], v16 offset:53248
	v_mfma_f32_16x16x32_f16 v[46:49], v[58:61], v[116:119], v[46:49]
	ds_read_b128 v[158:161], v16 offset:55296
	v_mfma_f32_16x16x32_f16 v[104:107], v[58:61], v[144:147], v[104:107]
	s_waitcnt lgkmcnt(1)
	v_mfma_f32_16x16x32_f16 v[108:111], v[154:157], v[116:119], v[108:111]
	v_mfma_f32_16x16x32_f16 v[112:115], v[154:157], v[144:147], v[112:115]
	s_waitcnt lgkmcnt(0)
	v_mfma_f32_16x16x32_f16 v[72:75], v[158:161], v[116:119], v[72:75]
	ds_read_b128 v[116:119], v21 offset:20480
	v_mfma_f32_16x16x32_f16 v[34:37], v[158:161], v[144:147], v[34:37]
	ds_read_b128 v[144:147], v21 offset:22528
	s_waitcnt lgkmcnt(1)
	v_mfma_f32_16x16x32_f16 v[128:131], v[54:57], v[116:119], v[128:131]
	s_waitcnt lgkmcnt(0)
	v_mfma_f32_16x16x32_f16 v[42:45], v[54:57], v[144:147], v[42:45]
	ds_read_b128 v[54:57], v22 offset:49152
	v_mfma_f32_16x16x32_f16 v[132:135], v[58:61], v[116:119], v[132:135]
	v_mfma_f32_16x16x32_f16 v[24:27], v[58:61], v[144:147], v[24:27]
	ds_read_b128 v[58:61], v22 offset:51200
	v_mfma_f32_16x16x32_f16 v[140:143], v[154:157], v[116:119], v[140:143]
	s_waitcnt vmcnt(7)
	ds_write_b128 v17, v[120:123]
	s_waitcnt vmcnt(6)
	ds_write_b128 v18, v[136:139]
	v_mfma_f32_16x16x32_f16 v[28:31], v[154:157], v[144:147], v[28:31]
	ds_read_b128 v[154:157], v22 offset:53248
	s_waitcnt vmcnt(5)
	ds_write_b128 v19, v[200:203]
	v_mfma_f32_16x16x32_f16 v[76:79], v[158:161], v[116:119], v[76:79]
	ds_read_b128 v[116:119], v32 offset:16384
	v_mfma_f32_16x16x32_f16 v[50:53], v[158:161], v[144:147], v[50:53]
	ds_read_b128 v[144:147], v32 offset:18432
	s_waitcnt lgkmcnt(1)
	v_mfma_f32_16x16x32_f16 v[38:41], v[54:57], v[116:119], v[38:41]
	ds_read_b128 v[158:161], v22 offset:55296
	s_waitcnt lgkmcnt(1)
	v_mfma_f32_16x16x32_f16 v[80:83], v[54:57], v[144:147], v[80:83]
	s_waitcnt vmcnt(4)
	ds_write_b128 v20, v[204:207]
	v_mfma_f32_16x16x32_f16 v[46:49], v[58:61], v[116:119], v[46:49]
	s_waitcnt vmcnt(3)
	ds_write_b128 v17, v[124:127] offset:32768
	v_mfma_f32_16x16x32_f16 v[104:107], v[58:61], v[144:147], v[104:107]
	s_waitcnt vmcnt(2)
	ds_write_b128 v18, v[208:211] offset:32768
	v_mfma_f32_16x16x32_f16 v[108:111], v[154:157], v[116:119], v[108:111]
	s_waitcnt vmcnt(1)
	ds_write_b128 v19, v[212:215] offset:32768
	v_mfma_f32_16x16x32_f16 v[112:115], v[154:157], v[144:147], v[112:115]
	s_waitcnt vmcnt(0)
	ds_write_b128 v20, v[220:223] offset:32768
	s_waitcnt lgkmcnt(5)
	v_mfma_f32_16x16x32_f16 v[72:75], v[158:161], v[116:119], v[72:75]
	ds_read_b128 v[116:119], v32 offset:20480
	v_mfma_f32_16x16x32_f16 v[34:37], v[158:161], v[144:147], v[34:37]
	ds_read_b128 v[144:147], v32 offset:22528
	s_waitcnt lgkmcnt(1)
	v_mfma_f32_16x16x32_f16 v[128:131], v[54:57], v[116:119], v[128:131]
	s_waitcnt lgkmcnt(0)
	v_mfma_f32_16x16x32_f16 v[42:45], v[54:57], v[144:147], v[42:45]
	global_load_dwordx4 v[54:57], v[0:1], off offset:1152
	v_mfma_f32_16x16x32_f16 v[132:135], v[58:61], v[116:119], v[132:135]
	v_mfma_f32_16x16x32_f16 v[24:27], v[58:61], v[144:147], v[24:27]
	v_mfma_f32_16x16x32_f16 v[140:143], v[154:157], v[116:119], v[140:143]
	v_mfma_f32_16x16x32_f16 v[28:31], v[154:157], v[144:147], v[28:31]
	v_mfma_f32_16x16x32_f16 v[76:79], v[158:161], v[116:119], v[76:79]
	global_load_dwordx4 v[116:119], v[2:3], off offset:1152
	global_load_dwordx4 v[162:165], v[4:5], off offset:1152
	global_load_dwordx4 v[166:169], v[6:7], off offset:1152
	global_load_dwordx4 v[58:61], v[8:9], off offset:1152
	global_load_dwordx4 v[188:191], v[10:11], off offset:1152
	global_load_dwordx4 v[192:195], v[12:13], off offset:1152
	global_load_dwordx4 v[196:199], v[14:15], off offset:1152
	s_waitcnt lgkmcnt(0)
	s_barrier
; #define GL_LOAD(s_, kt_) if (VAR != 1) { a##s_##0 = GL_A(0, kt_); a##s_##1 = GL_A(1, kt_); a##s_##2 = GL_A(2, kt_); a##s_##3 = GL_A(3, kt_); b##s_##0 = GL_B(0, kt_); b##s_##1 = GL_B(1, kt_); b##s_##2 = GL_B(2, kt_); b##s_##3 = GL_B(3, kt_); }
; #define LDS_STORE(s_, buf_) if (VAR != 2) { LDS_ST1(sA, 0, buf_, a##s_##0) LDS_ST1(sA, 1, buf_, a##s_##1) LDS_ST1(sA, 2, buf_, a##s_##2) LDS_ST1(sA, 3, buf_, a##s_##3) LDS_ST1(sB, 0, buf_, b##s_##0) LDS_ST1(sB, 1, buf_, b##s_##1) LDS_ST1(sB, 2, buf_, b##s_##2) LDS_ST1(sB, 3, buf_, b##s_##3) }
;     ...
;   for (int kt = 0; kt < nk; kt += 2) {
;     if (kt + 2 < nk) { GL_LOAD(0, kt + 2) }
;     MMA_TILE(0)
;     LDS_STORE(1, 1)
;     if (VAR != 4) __syncthreads();
;     if (kt + 3 < nk) { GL_LOAD(1, kt + 3) }
;     MMA_TILE(1)
;     if (kt + 2 < nk) { LDS_STORE(0, 0) }
;     if (VAR != 4) __syncthreads();
	v_mfma_f32_16x16x32_f16 v[50:53], v[158:161], v[144:147], v[50:53]
	ds_read_b128 v[120:123], v16 offset:32768
	ds_read_b128 v[136:139], v21
	s_waitcnt lgkmcnt(0)
	v_mfma_f32_16x16x32_f16 v[38:41], v[120:123], v[136:139], v[38:41]
	ds_read_b128 v[124:127], v16 offset:34816
	ds_read_b128 v[144:147], v21 offset:2048
	s_waitcnt lgkmcnt(0)
	v_mfma_f32_16x16x32_f16 v[80:83], v[120:123], v[144:147], v[80:83]
	ds_read_b128 v[154:157], v16 offset:36864
	v_mfma_f32_16x16x32_f16 v[46:49], v[124:127], v[136:139], v[46:49]
	ds_read_b128 v[158:161], v16 offset:38912
	v_mfma_f32_16x16x32_f16 v[104:107], v[124:127], v[144:147], v[104:107]
	s_waitcnt lgkmcnt(1)
	v_mfma_f32_16x16x32_f16 v[108:111], v[154:157], v[136:139], v[108:111]
	v_mfma_f32_16x16x32_f16 v[112:115], v[154:157], v[144:147], v[112:115]
	s_waitcnt lgkmcnt(0)
	v_mfma_f32_16x16x32_f16 v[72:75], v[158:161], v[136:139], v[72:75]
	ds_read_b128 v[136:139], v21 offset:4096
	v_mfma_f32_16x16x32_f16 v[34:37], v[158:161], v[144:147], v[34:37]
	ds_read_b128 v[144:147], v21 offset:6144
	s_waitcnt lgkmcnt(1)
	v_mfma_f32_16x16x32_f16 v[128:131], v[120:123], v[136:139], v[128:131]
	s_waitcnt lgkmcnt(0)
	v_mfma_f32_16x16x32_f16 v[42:45], v[120:123], v[144:147], v[42:45]
	ds_read_b128 v[120:123], v22 offset:32768
	v_mfma_f32_16x16x32_f16 v[132:135], v[124:127], v[136:139], v[132:135]
	v_mfma_f32_16x16x32_f16 v[24:27], v[124:127], v[144:147], v[24:27]
	ds_read_b128 v[124:127], v22 offset:34816
	v_mfma_f32_16x16x32_f16 v[140:143], v[154:157], v[136:139], v[140:143]
	s_waitcnt vmcnt(7)
	ds_write_b128 v17, v[54:57] offset:16384
	s_waitcnt vmcnt(6)
	ds_write_b128 v18, v[116:119] offset:16384
	v_mfma_f32_16x16x32_f16 v[28:31], v[154:157], v[144:147], v[28:31]
	ds_read_b128 v[154:157], v22 offset:36864
	s_waitcnt vmcnt(5)
	ds_write_b128 v19, v[162:165] offset:16384
	v_mfma_f32_16x16x32_f16 v[76:79], v[158:161], v[136:139], v[76:79]
	ds_read_b128 v[136:139], v32
	v_mfma_f32_16x16x32_f16 v[50:53], v[158:161], v[144:147], v[50:53]
	ds_read_b128 v[144:147], v32 offset:2048
	s_waitcnt lgkmcnt(1)
	v_mfma_f32_16x16x32_f16 v[38:41], v[120:123], v[136:139], v[38:41]
	ds_read_b128 v[158:161], v22 offset:38912
	s_waitcnt lgkmcnt(1)
	v_mfma_f32_16x16x32_f16 v[80:83], v[120:123], v[144:147], v[80:83]
	s_waitcnt vmcnt(4)
	ds_write_b128 v20, v[166:169] offset:16384
	v_mfma_f32_16x16x32_f16 v[46:49], v[124:127], v[136:139], v[46:49]
	s_waitcnt vmcnt(3)
	ds_write_b128 v17, v[58:61] offset:49152
	v_mfma_f32_16x16x32_f16 v[104:107], v[124:127], v[144:147], v[104:107]
	s_waitcnt vmcnt(2)
	ds_write_b128 v18, v[188:191] offset:49152
	v_mfma_f32_16x16x32_f16 v[108:111], v[154:157], v[136:139], v[108:111]
	s_waitcnt vmcnt(1)
	ds_write_b128 v19, v[192:195] offset:49152
	v_mfma_f32_16x16x32_f16 v[112:115], v[154:157], v[144:147], v[112:115]
	s_waitcnt vmcnt(0)
	ds_write_b128 v20, v[196:199] offset:49152
	s_waitcnt lgkmcnt(5)
	v_mfma_f32_16x16x32_f16 v[72:75], v[158:161], v[136:139], v[72:75]
	ds_read_b128 v[136:139], v32 offset:4096
	v_mfma_f32_16x16x32_f16 v[34:37], v[158:161], v[144:147], v[34:37]
	ds_read_b128 v[144:147], v32 offset:6144
	s_waitcnt lgkmcnt(1)
	v_mfma_f32_16x16x32_f16 v[128:131], v[120:123], v[136:139], v[128:131]
	s_waitcnt lgkmcnt(0)
	v_mfma_f32_16x16x32_f16 v[42:45], v[120:123], v[144:147], v[42:45]
	global_load_dwordx4 v[120:123], v[0:1], off offset:1280
	v_mfma_f32_16x16x32_f16 v[132:135], v[124:127], v[136:139], v[132:135]
	v_mfma_f32_16x16x32_f16 v[24:27], v[124:127], v[144:147], v[24:27]
	v_mfma_f32_16x16x32_f16 v[140:143], v[154:157], v[136:139], v[140:143]
	v_mfma_f32_16x16x32_f16 v[28:31], v[154:157], v[144:147], v[28:31]
	v_mfma_f32_16x16x32_f16 v[76:79], v[158:161], v[136:139], v[76:79]
	global_load_dwordx4 v[136:139], v[2:3], off offset:1280
	global_load_dwordx4 v[200:203], v[4:5], off offset:1280
	global_load_dwordx4 v[204:207], v[6:7], off offset:1280
	global_load_dwordx4 v[124:127], v[8:9], off offset:1280
	global_load_dwordx4 v[208:211], v[10:11], off offset:1280
	global_load_dwordx4 v[212:215], v[12:13], off offset:1280
	global_load_dwordx4 v[220:223], v[14:15], off offset:1280
	s_waitcnt lgkmcnt(0)
	s_barrier
	v_mfma_f32_16x16x32_f16 v[50:53], v[158:161], v[144:147], v[50:53]
	ds_read_b128 v[54:57], v16 offset:49152
	ds_read_b128 v[116:119], v21 offset:16384
	s_waitcnt lgkmcnt(0)
	v_mfma_f32_16x16x32_f16 v[38:41], v[54:57], v[116:119], v[38:41]
	ds_read_b128 v[58:61], v16 offset:51200
	ds_read_b128 v[144:147], v21 offset:18432
	s_waitcnt lgkmcnt(0)
	v_mfma_f32_16x16x32_f16 v[80:83], v[54:57], v[144:147], v[80:83]
	ds_read_b128 v[154:157], v16 offset:53248
	v_mfma_f32_16x16x32_f16 v[46:49], v[58:61], v[116:119], v[46:49]
	ds_read_b128 v[158:161], v16 offset:55296
	v_mfma_f32_16x16x32_f16 v[104:107], v[58:61], v[144:147], v[104:107]
	s_waitcnt lgkmcnt(1)
	v_mfma_f32_16x16x32_f16 v[108:111], v[154:157], v[116:119], v[108:111]
	v_mfma_f32_16x16x32_f16 v[112:115], v[154:157], v[144:147], v[112:115]
	s_waitcnt lgkmcnt(0)
	v_mfma_f32_16x16x32_f16 v[72:75], v[158:161], v[116:119], v[72:75]
	ds_read_b128 v[116:119], v21 offset:20480
	v_mfma_f32_16x16x32_f16 v[34:37], v[158:161], v[144:147], v[34:37]
	ds_read_b128 v[144:147], v21 offset:22528
	s_waitcnt lgkmcnt(1)
	v_mfma_f32_16x16x32_f16 v[128:131], v[54:57], v[116:119], v[128:131]
	s_waitcnt lgkmcnt(0)
	v_mfma_f32_16x16x32_f16 v[42:45], v[54:57], v[144:147], v[42:45]
	ds_read_b128 v[54:57], v22 offset:49152
	v_mfma_f32_16x16x32_f16 v[132:135], v[58:61], v[116:119], v[132:135]
	v_mfma_f32_16x16x32_f16 v[24:27], v[58:61], v[144:147], v[24:27]
	ds_read_b128 v[58:61], v22 offset:51200
	v_mfma_f32_16x16x32_f16 v[140:143], v[154:157], v[116:119], v[140:143]
	s_waitcnt vmcnt(7)
; #define GL_LOAD(s_, kt_) if (VAR != 1) { a##s_##0 = GL_A(0, kt_); a##s_##1 = GL_A(1, kt_); a##s_##2 = GL_A(2, kt_); a##s_##3 = GL_A(3, kt_); b##s_##0 = GL_B(0, kt_); b##s_##1 = GL_B(1, kt_); b##s_##2 = GL_B(2, kt_); b##s_##3 = GL_B(3, kt_); }
; #define LDS_STORE(s_, buf_) if (VAR != 2) { LDS_ST1(sA, 0, buf_, a##s_##0) LDS_ST1(sA, 1, buf_, a##s_##1) LDS_ST1(sA, 2, buf_, a##s_##2) LDS_ST1(sA, 3, buf_, a##s_##3) LDS_ST1(sB, 0, buf_, b##s_##0) LDS_ST1(sB, 1, buf_, b##s_##1) LDS_ST1(sB, 2, buf_, b##s_##2) LDS_ST1(sB, 3, buf_, b##s_##3) }
;     ...
;   for (int kt = 0; kt < nk; kt += 2) {
;     if (kt + 2 < nk) { GL_LOAD(0, kt + 2) }
;     MMA_TILE(0)
;     LDS_STORE(1, 1)
;     if (VAR != 4) __syncthreads();
;     if (kt + 3 < nk) { GL_LOAD(1, kt + 3) }
;     MMA_TILE(1)
;     if (kt + 2 < nk) { LDS_STORE(0, 0) }
;     if (VAR != 4) __syncthreads();
	ds_write_b128 v17, v[120:123]
	s_waitcnt vmcnt(6)
	ds_write_b128 v18, v[136:139]
	v_mfma_f32_16x16x32_f16 v[28:31], v[154:157], v[144:147], v[28:31]
	ds_read_b128 v[154:157], v22 offset:53248
	s_waitcnt vmcnt(5)
	ds_write_b128 v19, v[200:203]
	v_mfma_f32_16x16x32_f16 v[76:79], v[158:161], v[116:119], v[76:79]
	ds_read_b128 v[116:119], v32 offset:16384
	v_mfma_f32_16x16x32_f16 v[50:53], v[158:161], v[144:147], v[50:53]
	ds_read_b128 v[144:147], v32 offset:18432
	s_waitcnt lgkmcnt(1)
	v_mfma_f32_16x16x32_f16 v[38:41], v[54:57], v[116:119], v[38:41]
	ds_read_b128 v[158:161], v22 offset:55296
	s_waitcnt lgkmcnt(1)
	v_mfma_f32_16x16x32_f16 v[80:83], v[54:57], v[144:147], v[80:83]
	s_waitcnt vmcnt(4)
	ds_write_b128 v20, v[204:207]
	v_mfma_f32_16x16x32_f16 v[46:49], v[58:61], v[116:119], v[46:49]
	s_waitcnt vmcnt(3)
	ds_write_b128 v17, v[124:127] offset:32768
	v_mfma_f32_16x16x32_f16 v[104:107], v[58:61], v[144:147], v[104:107]
	s_waitcnt vmcnt(2)
	ds_write_b128 v18, v[208:211] offset:32768
	v_mfma_f32_16x16x32_f16 v[108:111], v[154:157], v[116:119], v[108:111]
	s_waitcnt vmcnt(1)
	ds_write_b128 v19, v[212:215] offset:32768
	v_mfma_f32_16x16x32_f16 v[112:115], v[154:157], v[144:147], v[112:115]
	s_waitcnt vmcnt(0)
	ds_write_b128 v20, v[220:223] offset:32768
	s_waitcnt lgkmcnt(5)
	v_mfma_f32_16x16x32_f16 v[72:75], v[158:161], v[116:119], v[72:75]
	ds_read_b128 v[116:119], v32 offset:20480
	v_mfma_f32_16x16x32_f16 v[34:37], v[158:161], v[144:147], v[34:37]
	ds_read_b128 v[144:147], v32 offset:22528
	s_waitcnt lgkmcnt(1)
	v_mfma_f32_16x16x32_f16 v[128:131], v[54:57], v[116:119], v[128:131]
	s_waitcnt lgkmcnt(0)
	v_mfma_f32_16x16x32_f16 v[42:45], v[54:57], v[144:147], v[42:45]
	global_load_dwordx4 v[54:57], v[0:1], off offset:1408
	v_mfma_f32_16x16x32_f16 v[132:135], v[58:61], v[116:119], v[132:135]
	v_mfma_f32_16x16x32_f16 v[24:27], v[58:61], v[144:147], v[24:27]
	v_mfma_f32_16x16x32_f16 v[140:143], v[154:157], v[116:119], v[140:143]
	v_mfma_f32_16x16x32_f16 v[28:31], v[154:157], v[144:147], v[28:31]
	v_mfma_f32_16x16x32_f16 v[76:79], v[158:161], v[116:119], v[76:79]
	global_load_dwordx4 v[116:119], v[2:3], off offset:1408
	global_load_dwordx4 v[162:165], v[4:5], off offset:1408
	global_load_dwordx4 v[166:169], v[6:7], off offset:1408
	global_load_dwordx4 v[58:61], v[8:9], off offset:1408
	global_load_dwordx4 v[188:191], v[10:11], off offset:1408
	global_load_dwordx4 v[192:195], v[12:13], off offset:1408
	global_load_dwordx4 v[196:199], v[14:15], off offset:1408
	s_waitcnt lgkmcnt(0)
	s_barrier
	v_mfma_f32_16x16x32_f16 v[50:53], v[158:161], v[144:147], v[50:53]
	ds_read_b128 v[120:123], v16 offset:32768
	ds_read_b128 v[136:139], v21
	s_waitcnt lgkmcnt(0)
	v_mfma_f32_16x16x32_f16 v[38:41], v[120:123], v[136:139], v[38:41]
	ds_read_b128 v[124:127], v16 offset:34816
	ds_read_b128 v[144:147], v21 offset:2048
	s_waitcnt lgkmcnt(0)
	v_mfma_f32_16x16x32_f16 v[80:83], v[120:123], v[144:147], v[80:83]
	ds_read_b128 v[154:157], v16 offset:36864
	v_mfma_f32_16x16x32_f16 v[46:49], v[124:127], v[136:139], v[46:49]
	ds_read_b128 v[158:161], v16 offset:38912
	v_mfma_f32_16x16x32_f16 v[104:107], v[124:127], v[144:147], v[104:107]
	s_waitcnt lgkmcnt(1)
	v_mfma_f32_16x16x32_f16 v[108:111], v[154:157], v[136:139], v[108:111]
	v_mfma_f32_16x16x32_f16 v[112:115], v[154:157], v[144:147], v[112:115]
	s_waitcnt lgkmcnt(0)
	v_mfma_f32_16x16x32_f16 v[72:75], v[158:161], v[136:139], v[72:75]
	ds_read_b128 v[136:139], v21 offset:4096
	v_mfma_f32_16x16x32_f16 v[34:37], v[158:161], v[144:147], v[34:37]
	ds_read_b128 v[144:147], v21 offset:6144
	s_waitcnt lgkmcnt(1)
	v_mfma_f32_16x16x32_f16 v[128:131], v[120:123], v[136:139], v[128:131]
	s_waitcnt lgkmcnt(0)
	v_mfma_f32_16x16x32_f16 v[42:45], v[120:123], v[144:147], v[42:45]
	ds_read_b128 v[120:123], v22 offset:32768
	v_mfma_f32_16x16x32_f16 v[132:135], v[124:127], v[136:139], v[132:135]
	v_mfma_f32_16x16x32_f16 v[24:27], v[124:127], v[144:147], v[24:27]
	ds_read_b128 v[124:127], v22 offset:34816
	v_mfma_f32_16x16x32_f16 v[140:143], v[154:157], v[136:139], v[140:143]
	s_waitcnt vmcnt(7)
	ds_write_b128 v17, v[54:57] offset:16384
	s_waitcnt vmcnt(6)
	ds_write_b128 v18, v[116:119] offset:16384
	v_mfma_f32_16x16x32_f16 v[28:31], v[154:157], v[144:147], v[28:31]
	ds_read_b128 v[154:157], v22 offset:36864
	s_waitcnt vmcnt(5)
	ds_write_b128 v19, v[162:165] offset:16384
	v_mfma_f32_16x16x32_f16 v[76:79], v[158:161], v[136:139], v[76:79]
	ds_read_b128 v[136:139], v32
	v_mfma_f32_16x16x32_f16 v[50:53], v[158:161], v[144:147], v[50:53]
	ds_read_b128 v[144:147], v32 offset:2048
	s_waitcnt lgkmcnt(1)
	v_mfma_f32_16x16x32_f16 v[38:41], v[120:123], v[136:139], v[38:41]
	ds_read_b128 v[158:161], v22 offset:38912
	s_waitcnt lgkmcnt(1)
	v_mfma_f32_16x16x32_f16 v[80:83], v[120:123], v[144:147], v[80:83]
	s_waitcnt vmcnt(4)
	ds_write_b128 v20, v[166:169] offset:16384
	v_mfma_f32_16x16x32_f16 v[46:49], v[124:127], v[136:139], v[46:49]
	s_waitcnt vmcnt(3)
	ds_write_b128 v17, v[58:61] offset:49152
	v_mfma_f32_16x16x32_f16 v[104:107], v[124:127], v[144:147], v[104:107]
	s_waitcnt vmcnt(2)
	ds_write_b128 v18, v[188:191] offset:49152
	v_mfma_f32_16x16x32_f16 v[108:111], v[154:157], v[136:139], v[108:111]
	s_waitcnt vmcnt(1)
	ds_write_b128 v19, v[192:195] offset:49152
	v_mfma_f32_16x16x32_f16 v[112:115], v[154:157], v[144:147], v[112:115]
	s_waitcnt vmcnt(0)
	ds_write_b128 v20, v[196:199] offset:49152
	s_waitcnt lgkmcnt(5)
	v_mfma_f32_16x16x32_f16 v[72:75], v[158:161], v[136:139], v[72:75]
	ds_read_b128 v[136:139], v32 offset:4096
	v_mfma_f32_16x16x32_f16 v[34:37], v[158:161], v[144:147], v[34:37]
	ds_read_b128 v[144:147], v32 offset:6144
	s_waitcnt lgkmcnt(1)
	v_mfma_f32_16x16x32_f16 v[128:131], v[120:123], v[136:139], v[128:131]
	s_waitcnt lgkmcnt(0)
	v_mfma_f32_16x16x32_f16 v[42:45], v[120:123], v[144:147], v[42:45]
	global_load_dwordx4 v[120:123], v[0:1], off offset:1536
	v_mfma_f32_16x16x32_f16 v[132:135], v[124:127], v[136:139], v[132:135]
	v_mfma_f32_16x16x32_f16 v[24:27], v[124:127], v[144:147], v[24:27]
	v_mfma_f32_16x16x32_f16 v[140:143], v[154:157], v[136:139], v[140:143]
	v_mfma_f32_16x16x32_f16 v[28:31], v[154:157], v[144:147], v[28:31]
	v_mfma_f32_16x16x32_f16 v[76:79], v[158:161], v[136:139], v[76:79]
	global_load_dwordx4 v[136:139], v[2:3], off offset:1536
	global_load_dwordx4 v[200:203], v[4:5], off offset:1536
	global_load_dwordx4 v[204:207], v[6:7], off offset:1536
	global_load_dwordx4 v[124:127], v[8:9], off offset:1536
	global_load_dwordx4 v[208:211], v[10:11], off offset:1536
	global_load_dwordx4 v[212:215], v[12:13], off offset:1536
	global_load_dwordx4 v[220:223], v[14:15], off offset:1536
	s_waitcnt lgkmcnt(0)
	s_barrier
; #define GL_LOAD(s_, kt_) if (VAR != 1) { a##s_##0 = GL_A(0, kt_); a##s_##1 = GL_A(1, kt_); a##s_##2 = GL_A(2, kt_); a##s_##3 = GL_A(3, kt_); b##s_##0 = GL_B(0, kt_); b##s_##1 = GL_B(1, kt_); b##s_##2 = GL_B(2, kt_); b##s_##3 = GL_B(3, kt_); }
; #define LDS_STORE(s_, buf_) if (VAR != 2) { LDS_ST1(sA, 0, buf_, a##s_##0) LDS_ST1(sA, 1, buf_, a##s_##1) LDS_ST1(sA, 2, buf_, a##s_##2) LDS_ST1(sA, 3, buf_, a##s_##3) LDS_ST1(sB, 0, buf_, b##s_##0) LDS_ST1(sB, 1, buf_, b##s_##1) LDS_ST1(sB, 2, buf_, b##s_##2) LDS_ST1(sB, 3, buf_, b##s_##3) }
;     ...
;   for (int kt = 0; kt < nk; kt += 2) {
;     if (kt + 2 < nk) { GL_LOAD(0, kt + 2) }
;     MMA_TILE(0)
;     LDS_STORE(1, 1)
;     if (VAR != 4) __syncthreads();
;     if (kt + 3 < nk) { GL_LOAD(1, kt + 3) }
;     MMA_TILE(1)
;     if (kt + 2 < nk) { LDS_STORE(0, 0) }
;     if (VAR != 4) __syncthreads();
	v_mfma_f32_16x16x32_f16 v[50:53], v[158:161], v[144:147], v[50:53]
	ds_read_b128 v[54:57], v16 offset:49152
	ds_read_b128 v[116:119], v21 offset:16384
	s_waitcnt lgkmcnt(0)
	v_mfma_f32_16x16x32_f16 v[38:41], v[54:57], v[116:119], v[38:41]
	ds_read_b128 v[58:61], v16 offset:51200
	ds_read_b128 v[144:147], v21 offset:18432
	s_waitcnt lgkmcnt(0)
	v_mfma_f32_16x16x32_f16 v[80:83], v[54:57], v[144:147], v[80:83]
	ds_read_b128 v[154:157], v16 offset:53248
	v_mfma_f32_16x16x32_f16 v[46:49], v[58:61], v[116:119], v[46:49]
	ds_read_b128 v[158:161], v16 offset:55296
	v_mfma_f32_16x16x32_f16 v[104:107], v[58:61], v[144:147], v[104:107]
	s_waitcnt lgkmcnt(1)
	v_mfma_f32_16x16x32_f16 v[108:111], v[154:157], v[116:119], v[108:111]
	v_mfma_f32_16x16x32_f16 v[112:115], v[154:157], v[144:147], v[112:115]
	s_waitcnt lgkmcnt(0)
	v_mfma_f32_16x16x32_f16 v[72:75], v[158:161], v[116:119], v[72:75]
	ds_read_b128 v[116:119], v21 offset:20480
	v_mfma_f32_16x16x32_f16 v[34:37], v[158:161], v[144:147], v[34:37]
	ds_read_b128 v[144:147], v21 offset:22528
	s_waitcnt lgkmcnt(1)
	v_mfma_f32_16x16x32_f16 v[128:131], v[54:57], v[116:119], v[128:131]
	s_waitcnt lgkmcnt(0)
	v_mfma_f32_16x16x32_f16 v[42:45], v[54:57], v[144:147], v[42:45]
	ds_read_b128 v[54:57], v22 offset:49152
	v_mfma_f32_16x16x32_f16 v[132:135], v[58:61], v[116:119], v[132:135]
	v_mfma_f32_16x16x32_f16 v[24:27], v[58:61], v[144:147], v[24:27]
	ds_read_b128 v[58:61], v22 offset:51200
	v_mfma_f32_16x16x32_f16 v[140:143], v[154:157], v[116:119], v[140:143]
	s_waitcnt vmcnt(7)
	ds_write_b128 v17, v[120:123]
	s_waitcnt vmcnt(6)
	ds_write_b128 v18, v[136:139]
	v_mfma_f32_16x16x32_f16 v[28:31], v[154:157], v[144:147], v[28:31]
	ds_read_b128 v[154:157], v22 offset:53248
	s_waitcnt vmcnt(5)
	ds_write_b128 v19, v[200:203]
	v_mfma_f32_16x16x32_f16 v[76:79], v[158:161], v[116:119], v[76:79]
	ds_read_b128 v[116:119], v32 offset:16384
	v_mfma_f32_16x16x32_f16 v[50:53], v[158:161], v[144:147], v[50:53]
	ds_read_b128 v[144:147], v32 offset:18432
	s_waitcnt lgkmcnt(1)
	v_mfma_f32_16x16x32_f16 v[38:41], v[54:57], v[116:119], v[38:41]
	ds_read_b128 v[158:161], v22 offset:55296
	s_waitcnt lgkmcnt(1)
	v_mfma_f32_16x16x32_f16 v[80:83], v[54:57], v[144:147], v[80:83]
	s_waitcnt vmcnt(4)
	ds_write_b128 v20, v[204:207]
	v_mfma_f32_16x16x32_f16 v[46:49], v[58:61], v[116:119], v[46:49]
	s_waitcnt vmcnt(3)
	ds_write_b128 v17, v[124:127] offset:32768
	v_mfma_f32_16x16x32_f16 v[104:107], v[58:61], v[144:147], v[104:107]
	s_waitcnt vmcnt(2)
	ds_write_b128 v18, v[208:211] offset:32768
	v_mfma_f32_16x16x32_f16 v[108:111], v[154:157], v[116:119], v[108:111]
	s_waitcnt vmcnt(1)
	ds_write_b128 v19, v[212:215] offset:32768
	v_mfma_f32_16x16x32_f16 v[112:115], v[154:157], v[144:147], v[112:115]
	s_waitcnt vmcnt(0)
	ds_write_b128 v20, v[220:223] offset:32768
	s_waitcnt lgkmcnt(5)
	v_mfma_f32_16x16x32_f16 v[72:75], v[158:161], v[116:119], v[72:75]
	ds_read_b128 v[116:119], v32 offset:20480
	v_mfma_f32_16x16x32_f16 v[34:37], v[158:161], v[144:147], v[34:37]
	ds_read_b128 v[144:147], v32 offset:22528
	s_waitcnt lgkmcnt(1)
	v_mfma_f32_16x16x32_f16 v[128:131], v[54:57], v[116:119], v[128:131]
	s_waitcnt lgkmcnt(0)
	v_mfma_f32_16x16x32_f16 v[42:45], v[54:57], v[144:147], v[42:45]
	global_load_dwordx4 v[54:57], v[0:1], off offset:1664
	v_mfma_f32_16x16x32_f16 v[132:135], v[58:61], v[116:119], v[132:135]
	v_mfma_f32_16x16x32_f16 v[24:27], v[58:61], v[144:147], v[24:27]
	v_mfma_f32_16x16x32_f16 v[140:143], v[154:157], v[116:119], v[140:143]
	v_mfma_f32_16x16x32_f16 v[28:31], v[154:157], v[144:147], v[28:31]
	v_mfma_f32_16x16x32_f16 v[76:79], v[158:161], v[116:119], v[76:79]
	global_load_dwordx4 v[116:119], v[2:3], off offset:1664
	global_load_dwordx4 v[162:165], v[4:5], off offset:1664
	global_load_dwordx4 v[166:169], v[6:7], off offset:1664
	global_load_dwordx4 v[58:61], v[8:9], off offset:1664
	global_load_dwordx4 v[188:191], v[10:11], off offset:1664
	global_load_dwordx4 v[192:195], v[12:13], off offset:1664
	global_load_dwordx4 v[196:199], v[14:15], off offset:1664
	s_waitcnt lgkmcnt(0)
	s_barrier
	v_mfma_f32_16x16x32_f16 v[50:53], v[158:161], v[144:147], v[50:53]
	ds_read_b128 v[120:123], v16 offset:32768
	ds_read_b128 v[136:139], v21
	s_waitcnt lgkmcnt(0)
	v_mfma_f32_16x16x32_f16 v[38:41], v[120:123], v[136:139], v[38:41]
	ds_read_b128 v[124:127], v16 offset:34816
	ds_read_b128 v[144:147], v21 offset:2048
	s_waitcnt lgkmcnt(0)
	v_mfma_f32_16x16x32_f16 v[80:83], v[120:123], v[144:147], v[80:83]
	ds_read_b128 v[154:157], v16 offset:36864
	v_mfma_f32_16x16x32_f16 v[46:49], v[124:127], v[136:139], v[46:49]
	ds_read_b128 v[158:161], v16 offset:38912
	v_mfma_f32_16x16x32_f16 v[104:107], v[124:127], v[144:147], v[104:107]
	s_waitcnt lgkmcnt(1)
	v_mfma_f32_16x16x32_f16 v[108:111], v[154:157], v[136:139], v[108:111]
	v_mfma_f32_16x16x32_f16 v[112:115], v[154:157], v[144:147], v[112:115]
	s_waitcnt lgkmcnt(0)
	v_mfma_f32_16x16x32_f16 v[72:75], v[158:161], v[136:139], v[72:75]
	ds_read_b128 v[136:139], v21 offset:4096
	v_mfma_f32_16x16x32_f16 v[34:37], v[158:161], v[144:147], v[34:37]
	ds_read_b128 v[144:147], v21 offset:6144
	s_waitcnt lgkmcnt(1)
	v_mfma_f32_16x16x32_f16 v[128:131], v[120:123], v[136:139], v[128:131]
	s_waitcnt lgkmcnt(0)
	v_mfma_f32_16x16x32_f16 v[42:45], v[120:123], v[144:147], v[42:45]
	ds_read_b128 v[120:123], v22 offset:32768
	v_mfma_f32_16x16x32_f16 v[132:135], v[124:127], v[136:139], v[132:135]
	v_mfma_f32_16x16x32_f16 v[24:27], v[124:127], v[144:147], v[24:27]
	ds_read_b128 v[124:127], v22 offset:34816
	v_mfma_f32_16x16x32_f16 v[140:143], v[154:157], v[136:139], v[140:143]
	s_waitcnt vmcnt(7)
	ds_write_b128 v17, v[54:57] offset:16384
	s_waitcnt vmcnt(6)
; #define GL_LOAD(s_, kt_) if (VAR != 1) { a##s_##0 = GL_A(0, kt_); a##s_##1 = GL_A(1, kt_); a##s_##2 = GL_A(2, kt_); a##s_##3 = GL_A(3, kt_); b##s_##0 = GL_B(0, kt_); b##s_##1 = GL_B(1, kt_); b##s_##2 = GL_B(2, kt_); b##s_##3 = GL_B(3, kt_); }
; #define LDS_STORE(s_, buf_) if (VAR != 2) { LDS_ST1(sA, 0, buf_, a##s_##0) LDS_ST1(sA, 1, buf_, a##s_##1) LDS_ST1(sA, 2, buf_, a##s_##2) LDS_ST1(sA, 3, buf_, a##s_##3) LDS_ST1(sB, 0, buf_, b##s_##0) LDS_ST1(sB, 1, buf_, b##s_##1) LDS_ST1(sB, 2, buf_, b##s_##2) LDS_ST1(sB, 3, buf_, b##s_##3) }
;     ...
;   for (int kt = 0; kt < nk; kt += 2) {
;     if (kt + 2 < nk) { GL_LOAD(0, kt + 2) }
;     MMA_TILE(0)
;     LDS_STORE(1, 1)
;     if (VAR != 4) __syncthreads();
;     if (kt + 3 < nk) { GL_LOAD(1, kt + 3) }
;     MMA_TILE(1)
;     if (kt + 2 < nk) { LDS_STORE(0, 0) }
;     if (VAR != 4) __syncthreads();
	ds_write_b128 v18, v[116:119] offset:16384
	v_mfma_f32_16x16x32_f16 v[28:31], v[154:157], v[144:147], v[28:31]
	ds_read_b128 v[154:157], v22 offset:36864
	s_waitcnt vmcnt(5)
	ds_write_b128 v19, v[162:165] offset:16384
	v_mfma_f32_16x16x32_f16 v[76:79], v[158:161], v[136:139], v[76:79]
	ds_read_b128 v[136:139], v32
	v_mfma_f32_16x16x32_f16 v[50:53], v[158:161], v[144:147], v[50:53]
	ds_read_b128 v[144:147], v32 offset:2048
	s_waitcnt lgkmcnt(1)
	v_mfma_f32_16x16x32_f16 v[38:41], v[120:123], v[136:139], v[38:41]
	ds_read_b128 v[158:161], v22 offset:38912
	s_waitcnt lgkmcnt(1)
	v_mfma_f32_16x16x32_f16 v[80:83], v[120:123], v[144:147], v[80:83]
	s_waitcnt vmcnt(4)
	ds_write_b128 v20, v[166:169] offset:16384
	v_mfma_f32_16x16x32_f16 v[46:49], v[124:127], v[136:139], v[46:49]
	s_waitcnt vmcnt(3)
	ds_write_b128 v17, v[58:61] offset:49152
	v_mfma_f32_16x16x32_f16 v[104:107], v[124:127], v[144:147], v[104:107]
	s_waitcnt vmcnt(2)
	ds_write_b128 v18, v[188:191] offset:49152
	v_mfma_f32_16x16x32_f16 v[108:111], v[154:157], v[136:139], v[108:111]
	s_waitcnt vmcnt(1)
	ds_write_b128 v19, v[192:195] offset:49152
	v_mfma_f32_16x16x32_f16 v[112:115], v[154:157], v[144:147], v[112:115]
	s_waitcnt vmcnt(0)
	ds_write_b128 v20, v[196:199] offset:49152
	s_waitcnt lgkmcnt(5)
	v_mfma_f32_16x16x32_f16 v[72:75], v[158:161], v[136:139], v[72:75]
	ds_read_b128 v[136:139], v32 offset:4096
	v_mfma_f32_16x16x32_f16 v[34:37], v[158:161], v[144:147], v[34:37]
	ds_read_b128 v[144:147], v32 offset:6144
	s_waitcnt lgkmcnt(1)
	v_mfma_f32_16x16x32_f16 v[128:131], v[120:123], v[136:139], v[128:131]
	s_waitcnt lgkmcnt(0)
	v_mfma_f32_16x16x32_f16 v[42:45], v[120:123], v[144:147], v[42:45]
	global_load_dwordx4 v[120:123], v[0:1], off offset:1792
	v_mfma_f32_16x16x32_f16 v[132:135], v[124:127], v[136:139], v[132:135]
	v_mfma_f32_16x16x32_f16 v[24:27], v[124:127], v[144:147], v[24:27]
	v_mfma_f32_16x16x32_f16 v[140:143], v[154:157], v[136:139], v[140:143]
	v_mfma_f32_16x16x32_f16 v[28:31], v[154:157], v[144:147], v[28:31]
	v_mfma_f32_16x16x32_f16 v[76:79], v[158:161], v[136:139], v[76:79]
	global_load_dwordx4 v[136:139], v[2:3], off offset:1792
	global_load_dwordx4 v[200:203], v[4:5], off offset:1792
	global_load_dwordx4 v[204:207], v[6:7], off offset:1792
	global_load_dwordx4 v[124:127], v[8:9], off offset:1792
	global_load_dwordx4 v[208:211], v[10:11], off offset:1792
	global_load_dwordx4 v[212:215], v[12:13], off offset:1792
	global_load_dwordx4 v[220:223], v[14:15], off offset:1792
	s_waitcnt lgkmcnt(0)
	s_barrier
	v_mfma_f32_16x16x32_f16 v[50:53], v[158:161], v[144:147], v[50:53]
	ds_read_b128 v[54:57], v16 offset:49152
	ds_read_b128 v[116:119], v21 offset:16384
	s_waitcnt lgkmcnt(0)
	v_mfma_f32_16x16x32_f16 v[38:41], v[54:57], v[116:119], v[38:41]
	ds_read_b128 v[58:61], v16 offset:51200
	ds_read_b128 v[144:147], v21 offset:18432
	s_waitcnt lgkmcnt(0)
	v_mfma_f32_16x16x32_f16 v[80:83], v[54:57], v[144:147], v[80:83]
	ds_read_b128 v[154:157], v16 offset:53248
	v_mfma_f32_16x16x32_f16 v[46:49], v[58:61], v[116:119], v[46:49]
	ds_read_b128 v[158:161], v16 offset:55296
	v_mfma_f32_16x16x32_f16 v[104:107], v[58:61], v[144:147], v[104:107]
	s_waitcnt lgkmcnt(1)
	v_mfma_f32_16x16x32_f16 v[108:111], v[154:157], v[116:119], v[108:111]
	v_mfma_f32_16x16x32_f16 v[112:115], v[154:157], v[144:147], v[112:115]
	s_waitcnt lgkmcnt(0)
	v_mfma_f32_16x16x32_f16 v[72:75], v[158:161], v[116:119], v[72:75]
	ds_read_b128 v[116:119], v21 offset:20480
	v_mfma_f32_16x16x32_f16 v[34:37], v[158:161], v[144:147], v[34:37]
	ds_read_b128 v[144:147], v21 offset:22528
	s_waitcnt lgkmcnt(1)
	v_mfma_f32_16x16x32_f16 v[128:131], v[54:57], v[116:119], v[128:131]
	s_waitcnt lgkmcnt(0)
	v_mfma_f32_16x16x32_f16 v[42:45], v[54:57], v[144:147], v[42:45]
	ds_read_b128 v[54:57], v22 offset:49152
	v_mfma_f32_16x16x32_f16 v[132:135], v[58:61], v[116:119], v[132:135]
	v_mfma_f32_16x16x32_f16 v[24:27], v[58:61], v[144:147], v[24:27]
	ds_read_b128 v[58:61], v22 offset:51200
	v_mfma_f32_16x16x32_f16 v[140:143], v[154:157], v[116:119], v[140:143]
	s_waitcnt vmcnt(7)
	ds_write_b128 v17, v[120:123]
	s_waitcnt vmcnt(6)
	ds_write_b128 v18, v[136:139]
	v_mfma_f32_16x16x32_f16 v[28:31], v[154:157], v[144:147], v[28:31]
	ds_read_b128 v[154:157], v22 offset:53248
	s_waitcnt vmcnt(5)
	ds_write_b128 v19, v[200:203]
	v_mfma_f32_16x16x32_f16 v[76:79], v[158:161], v[116:119], v[76:79]
	ds_read_b128 v[116:119], v32 offset:16384
	v_mfma_f32_16x16x32_f16 v[50:53], v[158:161], v[144:147], v[50:53]
	ds_read_b128 v[144:147], v32 offset:18432
	s_waitcnt lgkmcnt(1)
	v_mfma_f32_16x16x32_f16 v[38:41], v[54:57], v[116:119], v[38:41]
	ds_read_b128 v[158:161], v22 offset:55296
	s_waitcnt lgkmcnt(1)
	v_mfma_f32_16x16x32_f16 v[80:83], v[54:57], v[144:147], v[80:83]
	s_waitcnt vmcnt(4)
	ds_write_b128 v20, v[204:207]
	v_mfma_f32_16x16x32_f16 v[46:49], v[58:61], v[116:119], v[46:49]
	s_waitcnt vmcnt(3)
	ds_write_b128 v17, v[124:127] offset:32768
	v_mfma_f32_16x16x32_f16 v[104:107], v[58:61], v[144:147], v[104:107]
	s_waitcnt vmcnt(2)
	ds_write_b128 v18, v[208:211] offset:32768
	v_mfma_f32_16x16x32_f16 v[108:111], v[154:157], v[116:119], v[108:111]
	s_waitcnt vmcnt(1)
	ds_write_b128 v19, v[212:215] offset:32768
	v_mfma_f32_16x16x32_f16 v[112:115], v[154:157], v[144:147], v[112:115]
	s_waitcnt vmcnt(0)
	ds_write_b128 v20, v[220:223] offset:32768
	s_waitcnt lgkmcnt(5)
	v_mfma_f32_16x16x32_f16 v[72:75], v[158:161], v[116:119], v[72:75]
	ds_read_b128 v[116:119], v32 offset:20480
	v_mfma_f32_16x16x32_f16 v[34:37], v[158:161], v[144:147], v[34:37]
	ds_read_b128 v[144:147], v32 offset:22528
	s_waitcnt lgkmcnt(1)
	v_mfma_f32_16x16x32_f16 v[128:131], v[54:57], v[116:119], v[128:131]
	s_waitcnt lgkmcnt(0)
	v_mfma_f32_16x16x32_f16 v[42:45], v[54:57], v[144:147], v[42:45]
	global_load_dwordx4 v[54:57], v[0:1], off offset:1920
	global_load_dwordx4 v[0:3], v[2:3], off offset:1920
	v_mfma_f32_16x16x32_f16 v[132:135], v[58:61], v[116:119], v[132:135]
	v_mfma_f32_16x16x32_f16 v[24:27], v[58:61], v[144:147], v[24:27]
	v_mfma_f32_16x16x32_f16 v[140:143], v[154:157], v[116:119], v[140:143]
	v_mfma_f32_16x16x32_f16 v[28:31], v[154:157], v[144:147], v[28:31]
	v_mfma_f32_16x16x32_f16 v[76:79], v[158:161], v[116:119], v[76:79]
	global_load_dwordx4 v[116:119], v[4:5], off offset:1920
	global_load_dwordx4 v[4:7], v[6:7], off offset:1920
	global_load_dwordx4 v[58:61], v[8:9], off offset:1920
	global_load_dwordx4 v[8:11], v[10:11], off offset:1920
	global_load_dwordx4 v[162:165], v[12:13], off offset:1920
	global_load_dwordx4 v[12:15], v[14:15], off offset:1920
	s_waitcnt lgkmcnt(0)
	s_barrier
; #define GL_LOAD(s_, kt_) if (VAR != 1) { a##s_##0 = GL_A(0, kt_); a##s_##1 = GL_A(1, kt_); a##s_##2 = GL_A(2, kt_); a##s_##3 = GL_A(3, kt_); b##s_##0 = GL_B(0, kt_); b##s_##1 = GL_B(1, kt_); b##s_##2 = GL_B(2, kt_); b##s_##3 = GL_B(3, kt_); }
; #define LDS_STORE(s_, buf_) if (VAR != 2) { LDS_ST1(sA, 0, buf_, a##s_##0) LDS_ST1(sA, 1, buf_, a##s_##1) LDS_ST1(sA, 2, buf_, a##s_##2) LDS_ST1(sA, 3, buf_, a##s_##3) LDS_ST1(sB, 0, buf_, b##s_##0) LDS_ST1(sB, 1, buf_, b##s_##1) LDS_ST1(sB, 2, buf_, b##s_##2) LDS_ST1(sB, 3, buf_, b##s_##3) }
;     ...
;   for (int kt = 0; kt < nk; kt += 2) {
;     if (kt + 2 < nk) { GL_LOAD(0, kt + 2) }
;     MMA_TILE(0)
;     LDS_STORE(1, 1)
;     if (VAR != 4) __syncthreads();
;     if (kt + 3 < nk) { GL_LOAD(1, kt + 3) }
;     MMA_TILE(1)
;     if (kt + 2 < nk) { LDS_STORE(0, 0) }
;     if (VAR != 4) __syncthreads();
	ds_read_b128 v[120:123], v16 offset:32768
	v_mfma_f32_16x16x32_f16 v[50:53], v[158:161], v[144:147], v[50:53]
	ds_read_b128 v[124:127], v16 offset:34816
	ds_read_b128 v[136:139], v21
	ds_read_b128 v[144:147], v21 offset:2048
	ds_read_b128 v[154:157], v16 offset:36864
	ds_read_b128 v[158:161], v16 offset:38912
	s_waitcnt lgkmcnt(3)
	v_mfma_f32_16x16x32_f16 v[38:41], v[120:123], v[136:139], v[38:41]
	v_mfma_f32_16x16x32_f16 v[46:49], v[124:127], v[136:139], v[46:49]
	s_waitcnt lgkmcnt(1)
	v_mfma_f32_16x16x32_f16 v[108:111], v[154:157], v[136:139], v[108:111]
	s_waitcnt lgkmcnt(0)
	v_mfma_f32_16x16x32_f16 v[72:75], v[158:161], v[136:139], v[72:75]
	v_mfma_f32_16x16x32_f16 v[80:83], v[120:123], v[144:147], v[80:83]
	v_mfma_f32_16x16x32_f16 v[104:107], v[124:127], v[144:147], v[104:107]
	v_mfma_f32_16x16x32_f16 v[112:115], v[154:157], v[144:147], v[112:115]
	v_mfma_f32_16x16x32_f16 v[34:37], v[158:161], v[144:147], v[34:37]
	ds_read_b128 v[136:139], v21 offset:4096
	ds_read_b128 v[144:147], v21 offset:6144
	s_waitcnt lgkmcnt(1)
	v_mfma_f32_16x16x32_f16 v[128:131], v[120:123], v[136:139], v[128:131]
	v_mfma_f32_16x16x32_f16 v[132:135], v[124:127], v[136:139], v[132:135]
	v_mfma_f32_16x16x32_f16 v[140:143], v[154:157], v[136:139], v[140:143]
	v_mfma_f32_16x16x32_f16 v[76:79], v[158:161], v[136:139], v[76:79]
	s_waitcnt lgkmcnt(0)
	v_mfma_f32_16x16x32_f16 v[42:45], v[120:123], v[144:147], v[42:45]
	ds_read_b128 v[120:123], v22 offset:32768
	v_mfma_f32_16x16x32_f16 v[24:27], v[124:127], v[144:147], v[24:27]
	v_mfma_f32_16x16x32_f16 v[28:31], v[154:157], v[144:147], v[28:31]
	v_mfma_f32_16x16x32_f16 v[50:53], v[158:161], v[144:147], v[50:53]
	ds_read_b128 v[124:127], v22 offset:34816
	ds_read_b128 v[136:139], v32
	ds_read_b128 v[144:147], v32 offset:2048
	ds_read_b128 v[154:157], v22 offset:36864
	ds_read_b128 v[158:161], v22 offset:38912
	s_waitcnt lgkmcnt(3)
	v_mfma_f32_16x16x32_f16 v[38:41], v[120:123], v[136:139], v[38:41]
	v_mfma_f32_16x16x32_f16 v[46:49], v[124:127], v[136:139], v[46:49]
	s_waitcnt lgkmcnt(1)
	v_mfma_f32_16x16x32_f16 v[108:111], v[154:157], v[136:139], v[108:111]
	s_waitcnt lgkmcnt(0)
	v_mfma_f32_16x16x32_f16 v[72:75], v[158:161], v[136:139], v[72:75]
	v_mfma_f32_16x16x32_f16 v[80:83], v[120:123], v[144:147], v[80:83]
	v_mfma_f32_16x16x32_f16 v[104:107], v[124:127], v[144:147], v[104:107]
	v_mfma_f32_16x16x32_f16 v[112:115], v[154:157], v[144:147], v[112:115]
	v_mfma_f32_16x16x32_f16 v[34:37], v[158:161], v[144:147], v[34:37]
	ds_read_b128 v[136:139], v32 offset:4096
	ds_read_b128 v[144:147], v32 offset:6144
	s_waitcnt vmcnt(7)
	ds_write_b128 v17, v[54:57] offset:16384
	s_waitcnt vmcnt(6)
	ds_write_b128 v18, v[0:3] offset:16384
	s_waitcnt vmcnt(5)
	ds_write_b128 v19, v[116:119] offset:16384
	s_waitcnt vmcnt(4)
	ds_write_b128 v20, v[4:7] offset:16384
	s_waitcnt vmcnt(3)
	ds_write_b128 v17, v[58:61] offset:49152
	s_waitcnt vmcnt(2)
	ds_write_b128 v18, v[8:11] offset:49152
	s_waitcnt vmcnt(1)
	ds_write_b128 v19, v[162:165] offset:49152
	s_waitcnt vmcnt(0)
	ds_write_b128 v20, v[12:15] offset:49152
	s_waitcnt lgkmcnt(0)
	s_barrier
; #define LDS_STORE(s_, buf_) if (VAR != 2) { LDS_ST1(sA, 0, buf_, a##s_##0) LDS_ST1(sA, 1, buf_, a##s_##1) LDS_ST1(sA, 2, buf_, a##s_##2) LDS_ST1(sA, 3, buf_, a##s_##3) LDS_ST1(sB, 0, buf_, b##s_##0) LDS_ST1(sB, 1, buf_, b##s_##1) LDS_ST1(sB, 2, buf_, b##s_##2) LDS_ST1(sB, 3, buf_, b##s_##3) }
;     ...
;     MMA_TILE(1)
;     if (kt + 2 < nk) { LDS_STORE(0, 0) }
;     if (VAR != 4) __syncthreads();
; DI void phase_proj(const Params& P, int l, char* smem) {
;     ...
;       const float* gain = nullptr; bool rope = false; float sc = 1.f; bool sig = false;
;       constexpr float QS = 0.125f * 1.4426950408889634f;
;       if (col0 < C_AK) { gain = P.a_q_norm + l * 64; rope = true; sc = QS; }
;       else if (col0 < C_BQ) { gain = P.a_k_norm + l * 64; rope = true; }
;       else if (col0 < C_BK) { sc = QS; }
;       else if (col0 < C_CQ) { }
;       else if (col0 < C_CK) { gain = P.c_q_norm + l * 64; rope = true; sc = QS; }
;       else if (col0 < C_IQ) { gain = P.c_k_norm + l * 64; rope = true; }
;       else if (col0 < C_IK) { rope = true; sc = 0.125f; }
;       else if (col0 < C_IW) { gain = P.idx_k_norm + l * 64; rope = true; }
;       else if (col0 < C_GL) { sc = 0.5f; }
;       else { sig = true; }
	ds_read_b128 v[0:3], v16 offset:49152
	v_mfma_f32_16x16x32_f16 v[4:7], v[158:161], v[144:147], v[50:53]
	ds_read_b128 v[8:11], v16 offset:51200
	ds_read_b128 v[12:15], v21 offset:16384
	s_nop 0
	ds_read_b128 v[50:53], v21 offset:18432
	ds_read_b128 v[54:57], v16 offset:53248
	ds_read_b128 v[16:19], v16 offset:55296
	s_waitcnt lgkmcnt(3)
	v_mfma_f32_16x16x32_f16 v[38:41], v[0:3], v[12:15], v[38:41]
	v_mfma_f32_16x16x32_f16 v[46:49], v[8:11], v[12:15], v[46:49]
	s_waitcnt lgkmcnt(1)
	v_mfma_f32_16x16x32_f16 v[58:61], v[54:57], v[12:15], v[108:111]
	s_waitcnt lgkmcnt(0)
	v_mfma_f32_16x16x32_f16 v[12:15], v[16:19], v[12:15], v[72:75]
	v_mfma_f32_16x16x32_f16 v[72:75], v[0:3], v[50:53], v[80:83]
	v_mfma_f32_16x16x32_f16 v[80:83], v[8:11], v[50:53], v[104:107]
	v_mfma_f32_16x16x32_f16 v[104:107], v[54:57], v[50:53], v[112:115]
	v_mfma_f32_16x16x32_f16 v[34:37], v[16:19], v[50:53], v[34:37]
	ds_read_b128 v[50:53], v21 offset:20480
	ds_read_b128 v[108:111], v21 offset:22528
	v_mfma_f32_16x16x32_f16 v[128:131], v[120:123], v[136:139], v[128:131]
	v_mfma_f32_16x16x32_f16 v[132:135], v[124:127], v[136:139], v[132:135]
	v_mfma_f32_16x16x32_f16 v[140:143], v[154:157], v[136:139], v[140:143]
	v_mfma_f32_16x16x32_f16 v[42:45], v[120:123], v[144:147], v[42:45]
	v_mfma_f32_16x16x32_f16 v[24:27], v[124:127], v[144:147], v[24:27]
	v_mfma_f32_16x16x32_f16 v[28:31], v[154:157], v[144:147], v[28:31]
	v_mfma_f32_16x16x32_f16 v[76:79], v[158:161], v[136:139], v[76:79]
	s_waitcnt lgkmcnt(1)
	v_mfma_f32_16x16x32_f16 v[112:115], v[0:3], v[50:53], v[128:131]
	v_mfma_f32_16x16x32_f16 v[116:119], v[8:11], v[50:53], v[132:135]
	v_mfma_f32_16x16x32_f16 v[120:123], v[54:57], v[50:53], v[140:143]
	s_nop 1
	ds_read_b128 v[132:135], v22 offset:49152
	s_waitcnt lgkmcnt(1)
	v_mfma_f32_16x16x32_f16 v[0:3], v[0:3], v[108:111], v[42:45]
	v_mfma_f32_16x16x32_f16 v[124:127], v[8:11], v[108:111], v[24:27]
	v_mfma_f32_16x16x32_f16 v[128:131], v[54:57], v[108:111], v[28:31]
	v_mfma_f32_16x16x32_f16 v[108:111], v[16:19], v[108:111], v[4:7]
	ds_read_b128 v[136:139], v22 offset:51200
	s_nop 1
	ds_read_b128 v[4:7], v32 offset:16384
	ds_read_b128 v[8:11], v32 offset:18432
	ds_read_b128 v[140:143], v22 offset:53248
	ds_read_b128 v[144:147], v22 offset:55296
	v_mfma_f32_16x16x32_f16 v[76:79], v[16:19], v[50:53], v[76:79]
	s_waitcnt lgkmcnt(3)
	v_mfma_f32_16x16x32_f16 v[28:31], v[132:135], v[4:7], v[38:41]
	v_mfma_f32_16x16x32_f16 v[24:27], v[136:139], v[4:7], v[46:49]
	s_waitcnt lgkmcnt(1)
	v_mfma_f32_16x16x32_f16 v[60:63], v[140:143], v[4:7], v[58:61]
	s_waitcnt lgkmcnt(0)
	v_mfma_f32_16x16x32_f16 v[56:59], v[144:147], v[4:7], v[12:15]
	v_mfma_f32_16x16x32_f16 v[48:51], v[144:147], v[8:11], v[34:37]
	ds_read_b128 v[4:7], v32 offset:20480
	s_nop 1
	ds_read_b128 v[32:35], v32 offset:22528
	s_waitcnt lgkmcnt(0)
	s_barrier
	v_mfma_f32_16x16x32_f16 v[20:23], v[132:135], v[8:11], v[72:75]
	v_mfma_f32_16x16x32_f16 v[16:19], v[136:139], v[8:11], v[80:83]
	s_nop 1
	v_mov_b32_e32 v72, 0x3e38aa3b
	v_mfma_f32_16x16x32_f16 v[52:55], v[140:143], v[8:11], v[104:107]
	v_mfma_f32_16x16x32_f16 v[12:15], v[132:135], v[4:7], v[112:115]
	v_mfma_f32_16x16x32_f16 v[8:11], v[136:139], v[4:7], v[116:119]
	v_mfma_f32_16x16x32_f16 v[44:47], v[140:143], v[4:7], v[120:123]
	v_mfma_f32_16x16x32_f16 v[40:43], v[144:147], v[4:7], v[76:79]
	s_nop 1
	v_mov_b64_e32 v[122:123], s[14:15]
	v_mfma_f32_16x16x32_f16 v[4:7], v[132:135], v[32:35], v[0:3]
	v_mfma_f32_16x16x32_f16 v[0:3], v[136:139], v[32:35], v[124:127]
	v_mfma_f32_16x16x32_f16 v[36:39], v[140:143], v[32:35], v[128:131]
	v_mfma_f32_16x16x32_f16 v[32:35], v[144:147], v[32:35], v[108:111]
	s_and_saveexec_b64 s[4:5], vcc
	s_cbranch_execz .LBB0_654
	s_cmpk_lt_u32 s16, 0x400
	s_cbranch_scc1 .LBB0_649
	s_cmpk_lt_u32 s16, 0x600
	s_cbranch_scc1 .LBB0_650
	s_cmpk_lt_u32 s16, 0x800
	s_cbranch_scc1 .LBB0_651
	s_cmpk_lt_u32 s16, 0xa00
	s_cbranch_scc1 .LBB0_693
	s_cmpk_lt_u32 s16, 0xc00
	s_cbranch_scc1 .LBB0_694
	s_cmpk_lt_u32 s16, 0xd00
	s_cbranch_scc1 .LBB0_695
	s_movk_i32 s1, 0xd3f
	v_cmp_lt_u32_e32 vcc, s1, v94
	v_mov_b32_e32 v72, 1.0
	v_mov_b64_e32 v[122:123], s[6:7]
	s_and_saveexec_b64 s[24:25], vcc
	s_cmpk_gt_u32 s16, 0xd7f
	s_cselect_b64 s[20:21], -1, 0
	v_cndmask_b32_e64 v72, 0.5, 1.0, s[20:21]
	v_mov_b64_e32 v[122:123], 0
	s_xor_b64 s[22:23], exec, -1
	s_and_b64 s[20:21], s[20:21], exec
	s_or_b64 exec, exec, s[24:25]
	v_readlane_b32 s30, v252, 17
	v_readlane_b32 s31, v252, 18
	s_branch .LBB0_653

; DI int TIDX() { int t = threadIdx.x; asm volatile("" : "+v"(t)); return t; }
; #define GL_LOAD(s_, kt_) if (VAR != 1) { a##s_##0 = GL_A(0, kt_); a##s_##1 = GL_A(1, kt_); a##s_##2 = GL_A(2, kt_); a##s_##3 = GL_A(3, kt_); b##s_##0 = GL_B(0, kt_); b##s_##1 = GL_B(1, kt_); b##s_##2 = GL_B(2, kt_); b##s_##3 = GL_B(3, kt_); }
; #define LDS_STORE(s_, buf_) if (VAR != 2) { LDS_ST1(sA, 0, buf_, a##s_##0) LDS_ST1(sA, 1, buf_, a##s_##1) LDS_ST1(sA, 2, buf_, a##s_##2) LDS_ST1(sA, 3, buf_, a##s_##3) LDS_ST1(sB, 0, buf_, b##s_##0) LDS_ST1(sB, 1, buf_, b##s_##1) LDS_ST1(sB, 2, buf_, b##s_##2) LDS_ST1(sB, 3, buf_, b##s_##3) }
;   const int tid = TIDX(), lane = tid & 63, wid = tid >> 6, wm = wid >> 1, wn = wid & 1, lr = lane & 15, g = lane >> 4;
;   char* sA = smem; char* sB = smem + 2 * LTILE;
;   uint4 a00 = {}, a01 = {}, a02 = {}, a03 = {}, b00 = {}, b01 = {}, b02 = {}, b03 = {}, a10 = {}, a11 = {}, a12 = {}, a13 = {}, b10 = {}, b11 = {}, b12 = {}, b13 = {};
;   constexpr int nk = NK;
;   const int sw0 = (g ^ ((lr >> 1) & 7)) << 4, sw1 = sw0 ^ 64;
;   const int r0 = tid >> 3, kc = tid & 7, kcs = kc ^ ((r0 >> 1) & 7);
;     ...
;   GL_LOAD(0, 0)
;   GL_LOAD(1, 1)
;   LDS_STORE(0, 0)
;   if (VAR != 4) __syncthreads();
; #pragma unroll
;   for (int kt = 0; kt < nk; kt += 2) {
;     if (kt + 2 < nk) { GL_LOAD(0, kt + 2) }
;     MMA_TILE(0)
; DI void phase_proj(const Params& P, int l, char* smem) {
;     ...
;     if (n0 >= PW) {
;       gemm_kloop<false, false, 16>(acc, xb + (size_t)m0 * DM, DM, Wt + (size_t)n0 * DM, DM, smem);
;       const int cb = col0 - PW;
;       const int br = cb >> 9, c0 = cb & 511;
.LBB0_691:
	s_and_b64 vcc, exec, s[4:5]
	s_cbranch_vccz .LBB0_636
	v_mov_b32_e32 v18, v148
	s_mov_b32 s17, s27
	s_lshl_b64 s[4:5], s[16:17], 11
	v_ashrrev_i32_e32 v16, 3, v18
	v_readlane_b32 s1, v252, 19
	v_ashrrev_i32_e32 v17, 31, v16
	v_add_u32_e32 v54, 64, v16
	s_add_u32 s4, s1, s4
	v_readlane_b32 s1, v252, 20
	v_lshlrev_b64 v[6:7], 11, v[16:17]
	v_lshlrev_b32_e32 v17, 4, v18
	v_add_u32_e32 v20, 32, v16
	v_ashrrev_i32_e32 v55, 31, v54
	s_addc_u32 s5, s1, s5
	v_lshl_add_u64 v[0:1], s[18:19], 0, v[6:7]
	v_and_b32_e32 v150, 0x70, v17
	v_ashrrev_i32_e32 v21, 31, v20
	v_lshlrev_b64 v[12:13], 11, v[54:55]
	v_lshl_add_u64 v[0:1], v[0:1], 0, v[150:151]
	v_lshlrev_b64 v[10:11], 11, v[20:21]
	v_lshl_add_u64 v[4:5], s[18:19], 0, v[12:13]
	v_add_u32_e32 v56, 0x60, v16
	v_lshl_add_u64 v[6:7], s[4:5], 0, v[6:7]
	global_load_dwordx4 v[22:25], v[0:1], off
	v_lshl_add_u64 v[2:3], s[18:19], 0, v[10:11]
	v_lshl_add_u64 v[4:5], v[4:5], 0, v[150:151]
	v_ashrrev_i32_e32 v57, 31, v56
	v_lshl_add_u64 v[6:7], v[6:7], 0, v[150:151]
	v_lshl_add_u64 v[2:3], v[2:3], 0, v[150:151]
	global_load_dwordx4 v[30:33], v[4:5], off
	global_load_dwordx4 v[38:41], v[6:7], off
	v_lshlrev_b64 v[14:15], 11, v[56:57]
	global_load_dwordx4 v[26:29], v[2:3], off
	v_lshl_add_u64 v[8:9], s[18:19], 0, v[14:15]
	v_lshl_add_u64 v[8:9], v[8:9], 0, v[150:151]
	v_lshl_add_u64 v[10:11], s[4:5], 0, v[10:11]
	global_load_dwordx4 v[34:37], v[8:9], off
	v_lshl_add_u64 v[10:11], v[10:11], 0, v[150:151]
	v_lshl_add_u64 v[12:13], s[4:5], 0, v[12:13]
	global_load_dwordx4 v[42:45], v[10:11], off
	v_lshl_add_u64 v[12:13], v[12:13], 0, v[150:151]
	v_lshl_add_u64 v[14:15], s[4:5], 0, v[14:15]
	global_load_dwordx4 v[46:49], v[12:13], off
	v_lshl_add_u64 v[14:15], v[14:15], 0, v[150:151]
	global_load_dwordx4 v[50:53], v[14:15], off
	v_and_b32_e32 v19, 15, v18
	v_lshrrev_b32_e32 v55, 1, v18
	v_lshlrev_b32_e32 v21, 3, v18
	s_movk_i32 s1, 0x70
	v_and_or_b32 v55, v55, s29, v19
	v_and_b32_e32 v82, 48, v18
	v_and_b32_e32 v57, 0x70, v21
	v_bitop3_b32 v17, v17, s1, v18 bitop3:0x48
	v_lshlrev_b32_e32 v95, 7, v55
	v_lshlrev_b32_e32 v83, 7, v18
	v_lshl_or_b32 v18, v16, 7, v17
	v_lshl_or_b32 v19, v20, 7, v17
	v_lshl_or_b32 v20, v54, 7, v17
	v_lshl_or_b32 v17, v56, 7, v17
	v_bitop3_b32 v16, v95, v57, v82 bitop3:0xf6
	global_load_dwordx4 v[54:57], v[0:1], off offset:128
	global_load_dwordx4 v[58:61], v[6:7], off offset:128
	global_load_dwordx4 v[62:65], v[2:3], off offset:128
	global_load_dwordx4 v[66:69], v[4:5], off offset:128
	global_load_dwordx4 v[70:73], v[8:9], off offset:128
	global_load_dwordx4 v[74:77], v[10:11], off offset:128
	global_load_dwordx4 v[78:81], v[12:13], off offset:128
	global_load_dwordx4 v[104:107], v[14:15], off offset:128
	v_bitop3_b32 v21, v21, v82, s1 bitop3:0x6c
	v_add_u32_e32 v94, 0xffffe680, v94
	s_movk_i32 s1, 0x1c0
	v_and_or_b32 v103, v175, 64, v84
	s_mov_b64 s[4:5], 0x60
	s_waitcnt vmcnt(15)
	ds_write_b128 v18, v[22:25]
	s_waitcnt vmcnt(13)
	ds_write_b128 v18, v[38:41] offset:32768
	s_waitcnt vmcnt(12)
	ds_write_b128 v19, v[26:29]
	ds_write_b128 v20, v[30:33]
	s_waitcnt vmcnt(11)
	ds_write_b128 v17, v[34:37]
	s_waitcnt vmcnt(10)
	ds_write_b128 v19, v[42:45] offset:32768
	s_waitcnt vmcnt(9)
	ds_write_b128 v20, v[46:49] offset:32768
	s_waitcnt vmcnt(8)
	ds_write_b128 v17, v[50:53] offset:32768
	s_waitcnt lgkmcnt(0)
	s_barrier
	ds_read_b128 v[22:25], v16
	v_and_b32_e32 v26, 0x2780, v83
	v_or_b32_e32 v28, v26, v21
	ds_read_b128 v[30:33], v28 offset:32768
	s_waitcnt lgkmcnt(0)
	v_mfma_f32_16x16x32_f16 v[42:45], v[22:25], v[30:33], 0
	ds_read_b128 v[34:37], v16 offset:2048
	s_waitcnt lgkmcnt(0)
	v_mfma_f32_16x16x32_f16 v[116:119], v[34:37], v[30:33], 0
	ds_read_b128 v[38:41], v28 offset:34816
	ds_read_b128 v[128:131], v16 offset:4096
	s_waitcnt lgkmcnt(0)
	v_mfma_f32_16x16x32_f16 v[136:139], v[128:131], v[30:33], 0
	ds_read_b128 v[50:53], v28 offset:36864
	ds_read_b128 v[132:135], v16 offset:6144
	s_waitcnt lgkmcnt(0)
	v_mfma_f32_16x16x32_f16 v[154:157], v[132:135], v[30:33], 0
	ds_read_b128 v[108:111], v28 offset:38912
	v_mfma_f32_16x16x32_f16 v[46:49], v[22:25], v[38:41], 0
	v_bitop3_b32 v29, v95, v21, 64 bitop3:0xf6
	v_mfma_f32_16x16x32_f16 v[112:115], v[22:25], v[50:53], 0
	ds_read_b128 v[158:161], v29
	s_waitcnt lgkmcnt(1)
	v_mfma_f32_16x16x32_f16 v[22:25], v[22:25], v[108:111], 0
	ds_read_b128 v[162:165], v29 offset:2048
	v_mfma_f32_16x16x32_f16 v[120:123], v[34:37], v[38:41], 0
	v_xor_b32_e32 v21, 64, v21
	v_mfma_f32_16x16x32_f16 v[124:127], v[34:37], v[50:53], 0
	v_ashrrev_i32_e32 v95, 12, v99
	v_mfma_f32_16x16x32_f16 v[34:37], v[34:37], v[108:111], 0
	v_and_b32_e32 v99, 0xfc0, v99
	v_mfma_f32_16x16x32_f16 v[140:143], v[128:131], v[38:41], 0
	v_lshlrev_b32_e32 v150, 1, v99
	v_or_b32_e32 v32, v26, v21
	v_mfma_f32_16x16x32_f16 v[144:147], v[128:131], v[50:53], 0
	ds_read_b128 v[166:169], v32 offset:34816
	ds_read_b128 v[188:191], v32 offset:36864
	v_mfma_f32_16x16x32_f16 v[128:131], v[128:131], v[108:111], 0
	ds_read_b128 v[192:195], v32 offset:38912
	s_waitcnt vmcnt(7)
	ds_write_b128 v18, v[54:57] offset:16384
	v_mfma_f32_16x16x32_f16 v[38:41], v[132:135], v[38:41], 0
	s_waitcnt vmcnt(5)
	ds_write_b128 v19, v[62:65] offset:16384
	v_mfma_f32_16x16x32_f16 v[50:53], v[132:135], v[50:53], 0
	s_waitcnt vmcnt(4)
	ds_write_b128 v20, v[66:69] offset:16384
	v_mfma_f32_16x16x32_f16 v[108:111], v[132:135], v[108:111], 0
	ds_read_b128 v[132:135], v32 offset:32768
	s_waitcnt lgkmcnt(6)
	v_mfma_f32_16x16x32_f16 v[46:49], v[158:161], v[166:169], v[46:49]
	s_waitcnt vmcnt(3)
	ds_write_b128 v17, v[70:73] offset:16384
	s_waitcnt lgkmcnt(6)
; #define GL_LOAD(s_, kt_) if (VAR != 1) { a##s_##0 = GL_A(0, kt_); a##s_##1 = GL_A(1, kt_); a##s_##2 = GL_A(2, kt_); a##s_##3 = GL_A(3, kt_); b##s_##0 = GL_B(0, kt_); b##s_##1 = GL_B(1, kt_); b##s_##2 = GL_B(2, kt_); b##s_##3 = GL_B(3, kt_); }
; #define LDS_STORE(s_, buf_) if (VAR != 2) { LDS_ST1(sA, 0, buf_, a##s_##0) LDS_ST1(sA, 1, buf_, a##s_##1) LDS_ST1(sA, 2, buf_, a##s_##2) LDS_ST1(sA, 3, buf_, a##s_##3) LDS_ST1(sB, 0, buf_, b##s_##0) LDS_ST1(sB, 1, buf_, b##s_##1) LDS_ST1(sB, 2, buf_, b##s_##2) LDS_ST1(sB, 3, buf_, b##s_##3) }
;     ...
;   for (int kt = 0; kt < nk; kt += 2) {
;     if (kt + 2 < nk) { GL_LOAD(0, kt + 2) }
;     MMA_TILE(0)
;     LDS_STORE(1, 1)
;     if (VAR != 4) __syncthreads();
;     if (kt + 3 < nk) { GL_LOAD(1, kt + 3) }
;     MMA_TILE(1)
;     if (kt + 2 < nk) { LDS_STORE(0, 0) }
;     if (VAR != 4) __syncthreads();
	v_mfma_f32_16x16x32_f16 v[112:115], v[158:161], v[188:191], v[112:115]
	ds_write_b128 v18, v[58:61] offset:49152
	s_waitcnt lgkmcnt(6)
	v_mfma_f32_16x16x32_f16 v[22:25], v[158:161], v[192:195], v[22:25]
	s_waitcnt vmcnt(2)
	ds_write_b128 v19, v[74:77] offset:49152
	v_mfma_f32_16x16x32_f16 v[120:123], v[162:165], v[166:169], v[120:123]
	s_waitcnt vmcnt(1)
	ds_write_b128 v20, v[78:81] offset:49152
	v_mfma_f32_16x16x32_f16 v[124:127], v[162:165], v[188:191], v[124:127]
	s_waitcnt vmcnt(0)
	ds_write_b128 v17, v[104:107] offset:49152
	v_mfma_f32_16x16x32_f16 v[34:37], v[162:165], v[192:195], v[34:37]
	s_waitcnt lgkmcnt(5)
	v_mfma_f32_16x16x32_f16 v[42:45], v[158:161], v[132:135], v[42:45]
	ds_read_b128 v[158:161], v29 offset:4096
	v_mfma_f32_16x16x32_f16 v[116:119], v[162:165], v[132:135], v[116:119]
	ds_read_b128 v[162:165], v29 offset:6144
	s_waitcnt lgkmcnt(1)
	v_mfma_f32_16x16x32_f16 v[136:139], v[158:161], v[132:135], v[136:139]
	v_mfma_f32_16x16x32_f16 v[140:143], v[158:161], v[166:169], v[140:143]
	s_waitcnt lgkmcnt(0)
	v_mfma_f32_16x16x32_f16 v[132:135], v[162:165], v[132:135], v[154:157]
	s_nop 2
	global_load_dwordx4 v[154:157], v[0:1], off offset:256
	v_mfma_f32_16x16x32_f16 v[38:41], v[162:165], v[166:169], v[38:41]
	v_mfma_f32_16x16x32_f16 v[144:147], v[158:161], v[188:191], v[144:147]
	v_mfma_f32_16x16x32_f16 v[128:131], v[158:161], v[192:195], v[128:131]
	global_load_dwordx4 v[158:161], v[2:3], off offset:256
	global_load_dwordx4 v[196:199], v[4:5], off offset:256
	global_load_dwordx4 v[200:203], v[8:9], off offset:256
	global_load_dwordx4 v[166:169], v[6:7], off offset:256
	global_load_dwordx4 v[204:207], v[10:11], off offset:256
	global_load_dwordx4 v[208:211], v[12:13], off offset:256
	global_load_dwordx4 v[212:215], v[14:15], off offset:256
	s_waitcnt lgkmcnt(0)
	s_barrier
	v_mfma_f32_16x16x32_f16 v[58:61], v[162:165], v[192:195], v[108:111]
	ds_read_b128 v[54:57], v16 offset:16384
	v_mfma_f32_16x16x32_f16 v[50:53], v[162:165], v[188:191], v[50:53]
	ds_read_b128 v[62:65], v28 offset:49152
	s_waitcnt lgkmcnt(0)
	v_mfma_f32_16x16x32_f16 v[42:45], v[54:57], v[62:65], v[42:45]
	ds_read_b128 v[66:69], v16 offset:18432
	ds_read_b128 v[70:73], v28 offset:51200
	s_waitcnt lgkmcnt(0)
	v_mfma_f32_16x16x32_f16 v[46:49], v[54:57], v[70:73], v[46:49]
	ds_read_b128 v[74:77], v28 offset:53248
	s_waitcnt lgkmcnt(0)
	v_mfma_f32_16x16x32_f16 v[104:107], v[54:57], v[74:77], v[112:115]
	ds_read_b128 v[78:81], v28 offset:55296
	s_waitcnt lgkmcnt(0)
	v_mfma_f32_16x16x32_f16 v[22:25], v[54:57], v[78:81], v[22:25]
	v_mfma_f32_16x16x32_f16 v[54:57], v[66:69], v[62:65], v[116:119]
	s_nop 2
	ds_read_b128 v[116:119], v16 offset:22528
	v_mfma_f32_16x16x32_f16 v[108:111], v[66:69], v[70:73], v[120:123]
	v_mfma_f32_16x16x32_f16 v[112:115], v[66:69], v[74:77], v[124:127]
	v_mfma_f32_16x16x32_f16 v[34:37], v[66:69], v[78:81], v[34:37]
	ds_read_b128 v[66:69], v16 offset:20480
	s_waitcnt lgkmcnt(0)
	v_mfma_f32_16x16x32_f16 v[124:127], v[66:69], v[70:73], v[140:143]
	v_mfma_f32_16x16x32_f16 v[120:123], v[66:69], v[62:65], v[136:139]
	v_mfma_f32_16x16x32_f16 v[38:41], v[116:119], v[70:73], v[38:41]
	ds_read_b128 v[70:73], v29 offset:16384
	v_mfma_f32_16x16x32_f16 v[62:65], v[116:119], v[62:65], v[132:135]
	s_nop 2
	ds_read_b128 v[132:135], v32 offset:55296
	s_waitcnt vmcnt(7)
	ds_write_b128 v18, v[154:157]
	v_mfma_f32_16x16x32_f16 v[136:139], v[66:69], v[74:77], v[144:147]
	s_waitcnt vmcnt(6)
	ds_write_b128 v19, v[158:161]
	s_waitcnt vmcnt(5)
	ds_write_b128 v20, v[196:199]
	v_mfma_f32_16x16x32_f16 v[66:69], v[66:69], v[78:81], v[128:131]
	s_nop 2
	ds_read_b128 v[128:131], v32 offset:53248
	v_mfma_f32_16x16x32_f16 v[50:53], v[116:119], v[74:77], v[50:53]
	ds_read_b128 v[74:77], v32 offset:49152
	v_mfma_f32_16x16x32_f16 v[58:61], v[116:119], v[78:81], v[58:61]
	ds_read_b128 v[78:81], v29 offset:18432
	s_waitcnt lgkmcnt(1)
	v_mfma_f32_16x16x32_f16 v[42:45], v[70:73], v[74:77], v[42:45]
	ds_read_b128 v[116:119], v32 offset:51200
	s_waitcnt lgkmcnt(0)
	v_mfma_f32_16x16x32_f16 v[46:49], v[70:73], v[116:119], v[46:49]
	s_waitcnt vmcnt(4)
	ds_write_b128 v17, v[200:203]
	v_mfma_f32_16x16x32_f16 v[54:57], v[78:81], v[74:77], v[54:57]
	s_waitcnt vmcnt(3)
	ds_write_b128 v18, v[166:169] offset:32768
	v_mfma_f32_16x16x32_f16 v[104:107], v[70:73], v[128:131], v[104:107]
	v_mfma_f32_16x16x32_f16 v[22:25], v[70:73], v[132:135], v[22:25]
	v_mfma_f32_16x16x32_f16 v[70:73], v[78:81], v[116:119], v[108:111]
	s_waitcnt vmcnt(2)
	ds_write_b128 v19, v[204:207] offset:32768
	s_waitcnt vmcnt(1)
	ds_write_b128 v20, v[208:211] offset:32768
	s_waitcnt vmcnt(0)
	ds_write_b128 v17, v[212:215] offset:32768
	v_mfma_f32_16x16x32_f16 v[108:111], v[78:81], v[128:131], v[112:115]
	s_nop 2
	ds_read_b128 v[112:115], v29 offset:22528
	v_mfma_f32_16x16x32_f16 v[34:37], v[78:81], v[132:135], v[34:37]
	ds_read_b128 v[78:81], v29 offset:20480
	s_waitcnt lgkmcnt(0)
	v_mfma_f32_16x16x32_f16 v[120:123], v[78:81], v[74:77], v[120:123]
	v_mfma_f32_16x16x32_f16 v[124:127], v[78:81], v[116:119], v[124:127]
	v_mfma_f32_16x16x32_f16 v[62:65], v[112:115], v[74:77], v[62:65]
	global_load_dwordx4 v[74:77], v[0:1], off offset:384
	v_mfma_f32_16x16x32_f16 v[38:41], v[112:115], v[116:119], v[38:41]
	v_mfma_f32_16x16x32_f16 v[136:139], v[78:81], v[128:131], v[136:139]
	v_mfma_f32_16x16x32_f16 v[66:69], v[78:81], v[132:135], v[66:69]
	global_load_dwordx4 v[78:81], v[2:3], off offset:384
	global_load_dwordx4 v[140:143], v[4:5], off offset:384
	v_mfma_f32_16x16x32_f16 v[50:53], v[112:115], v[128:131], v[50:53]
	global_load_dwordx4 v[144:147], v[8:9], off offset:384
	global_load_dwordx4 v[116:119], v[6:7], off offset:384
	global_load_dwordx4 v[162:165], v[10:11], off offset:384
	global_load_dwordx4 v[188:191], v[12:13], off offset:384
	global_load_dwordx4 v[192:195], v[14:15], off offset:384
	s_waitcnt lgkmcnt(0)
	s_barrier
; #define GL_LOAD(s_, kt_) if (VAR != 1) { a##s_##0 = GL_A(0, kt_); a##s_##1 = GL_A(1, kt_); a##s_##2 = GL_A(2, kt_); a##s_##3 = GL_A(3, kt_); b##s_##0 = GL_B(0, kt_); b##s_##1 = GL_B(1, kt_); b##s_##2 = GL_B(2, kt_); b##s_##3 = GL_B(3, kt_); }
; #define LDS_STORE(s_, buf_) if (VAR != 2) { LDS_ST1(sA, 0, buf_, a##s_##0) LDS_ST1(sA, 1, buf_, a##s_##1) LDS_ST1(sA, 2, buf_, a##s_##2) LDS_ST1(sA, 3, buf_, a##s_##3) LDS_ST1(sB, 0, buf_, b##s_##0) LDS_ST1(sB, 1, buf_, b##s_##1) LDS_ST1(sB, 2, buf_, b##s_##2) LDS_ST1(sB, 3, buf_, b##s_##3) }
;     ...
;   GL_LOAD(0, 0)
;   GL_LOAD(1, 1)
;   LDS_STORE(0, 0)
;   if (VAR != 4) __syncthreads();
; #pragma unroll
;   for (int kt = 0; kt < nk; kt += 2) {
;     if (kt + 2 < nk) { GL_LOAD(0, kt + 2) }
;     MMA_TILE(0)
;     LDS_STORE(1, 1)
;     if (VAR != 4) __syncthreads();
;     if (kt + 3 < nk) { GL_LOAD(1, kt + 3) }
;     MMA_TILE(1)
;     if (kt + 2 < nk) { LDS_STORE(0, 0) }
;     if (VAR != 4) __syncthreads();
	v_mfma_f32_16x16x32_f16 v[58:61], v[112:115], v[132:135], v[58:61]
	ds_read_b128 v[128:131], v16
	ds_read_b128 v[112:115], v28 offset:32768
	s_waitcnt lgkmcnt(0)
	v_mfma_f32_16x16x32_f16 v[42:45], v[128:131], v[112:115], v[42:45]
	ds_read_b128 v[132:135], v16 offset:2048
	ds_read_b128 v[154:157], v28 offset:34816
	s_waitcnt lgkmcnt(0)
	v_mfma_f32_16x16x32_f16 v[46:49], v[128:131], v[154:157], v[46:49]
	ds_read_b128 v[158:161], v28 offset:36864
	v_mfma_f32_16x16x32_f16 v[54:57], v[132:135], v[112:115], v[54:57]
	ds_read_b128 v[166:169], v28 offset:38912
	v_mfma_f32_16x16x32_f16 v[70:73], v[132:135], v[154:157], v[70:73]
	s_waitcnt lgkmcnt(1)
	v_mfma_f32_16x16x32_f16 v[104:107], v[128:131], v[158:161], v[104:107]
	s_waitcnt lgkmcnt(0)
	v_mfma_f32_16x16x32_f16 v[22:25], v[128:131], v[166:169], v[22:25]
	ds_read_b128 v[128:131], v16 offset:4096
	v_mfma_f32_16x16x32_f16 v[108:111], v[132:135], v[158:161], v[108:111]
	v_mfma_f32_16x16x32_f16 v[34:37], v[132:135], v[166:169], v[34:37]
	ds_read_b128 v[132:135], v16 offset:6144
	s_waitcnt lgkmcnt(1)
	v_mfma_f32_16x16x32_f16 v[120:123], v[128:131], v[112:115], v[120:123]
	v_mfma_f32_16x16x32_f16 v[124:127], v[128:131], v[154:157], v[124:127]
	s_waitcnt lgkmcnt(0)
	v_mfma_f32_16x16x32_f16 v[62:65], v[132:135], v[112:115], v[62:65]
	ds_read_b128 v[112:115], v29
	v_mfma_f32_16x16x32_f16 v[38:41], v[132:135], v[154:157], v[38:41]
	ds_read_b128 v[154:157], v32 offset:34816
	s_waitcnt vmcnt(7)
	ds_write_b128 v18, v[74:77] offset:16384
	v_mfma_f32_16x16x32_f16 v[136:139], v[128:131], v[158:161], v[136:139]
	s_waitcnt vmcnt(6)
	ds_write_b128 v19, v[78:81] offset:16384
	s_waitcnt vmcnt(5)
	ds_write_b128 v20, v[140:143] offset:16384
	v_mfma_f32_16x16x32_f16 v[66:69], v[128:131], v[166:169], v[66:69]
	ds_read_b128 v[128:131], v32 offset:32768
	s_waitcnt vmcnt(4)
	ds_write_b128 v17, v[144:147] offset:16384
	v_mfma_f32_16x16x32_f16 v[50:53], v[132:135], v[158:161], v[50:53]
	ds_read_b128 v[158:161], v32 offset:36864
	v_mfma_f32_16x16x32_f16 v[58:61], v[132:135], v[166:169], v[58:61]
	ds_read_b128 v[132:135], v29 offset:2048
	s_waitcnt lgkmcnt(3)
	v_mfma_f32_16x16x32_f16 v[42:45], v[112:115], v[128:131], v[42:45]
	ds_read_b128 v[166:169], v32 offset:38912
	v_mfma_f32_16x16x32_f16 v[46:49], v[112:115], v[154:157], v[46:49]
	s_waitcnt vmcnt(3)
	ds_write_b128 v18, v[116:119] offset:49152
	s_waitcnt lgkmcnt(2)
	v_mfma_f32_16x16x32_f16 v[54:57], v[132:135], v[128:131], v[54:57]
	s_waitcnt vmcnt(2)
	ds_write_b128 v19, v[162:165] offset:49152
	v_mfma_f32_16x16x32_f16 v[70:73], v[132:135], v[154:157], v[70:73]
	s_waitcnt vmcnt(1)
	ds_write_b128 v20, v[188:191] offset:49152
	v_mfma_f32_16x16x32_f16 v[104:107], v[112:115], v[158:161], v[104:107]
	s_waitcnt vmcnt(0)
	ds_write_b128 v17, v[192:195] offset:49152
	s_waitcnt lgkmcnt(4)
	v_mfma_f32_16x16x32_f16 v[22:25], v[112:115], v[166:169], v[22:25]
	ds_read_b128 v[112:115], v29 offset:4096
	v_mfma_f32_16x16x32_f16 v[108:111], v[132:135], v[158:161], v[108:111]
	v_mfma_f32_16x16x32_f16 v[34:37], v[132:135], v[166:169], v[34:37]
	ds_read_b128 v[132:135], v29 offset:6144
	s_waitcnt lgkmcnt(1)
	v_mfma_f32_16x16x32_f16 v[120:123], v[112:115], v[128:131], v[120:123]
	v_mfma_f32_16x16x32_f16 v[124:127], v[112:115], v[154:157], v[124:127]
	s_waitcnt lgkmcnt(0)
	v_mfma_f32_16x16x32_f16 v[62:65], v[132:135], v[128:131], v[62:65]
	v_mfma_f32_16x16x32_f16 v[38:41], v[132:135], v[154:157], v[38:41]
	v_mfma_f32_16x16x32_f16 v[136:139], v[112:115], v[158:161], v[136:139]
	v_mfma_f32_16x16x32_f16 v[66:69], v[112:115], v[166:169], v[66:69]
	global_load_dwordx4 v[112:115], v[0:1], off offset:512
	global_load_dwordx4 v[128:131], v[2:3], off offset:512
	global_load_dwordx4 v[196:199], v[4:5], off offset:512
	global_load_dwordx4 v[200:203], v[8:9], off offset:512
	global_load_dwordx4 v[154:157], v[6:7], off offset:512
	global_load_dwordx4 v[204:207], v[10:11], off offset:512
	global_load_dwordx4 v[208:211], v[12:13], off offset:512
	global_load_dwordx4 v[212:215], v[14:15], off offset:512
	s_waitcnt lgkmcnt(0)
	s_barrier
	v_mfma_f32_16x16x32_f16 v[50:53], v[132:135], v[158:161], v[50:53]
	ds_read_b128 v[74:77], v16 offset:16384
	v_mfma_f32_16x16x32_f16 v[58:61], v[132:135], v[166:169], v[58:61]
	ds_read_b128 v[78:81], v28 offset:49152
	s_waitcnt lgkmcnt(0)
	v_mfma_f32_16x16x32_f16 v[42:45], v[74:77], v[78:81], v[42:45]
	ds_read_b128 v[116:119], v16 offset:18432
	ds_read_b128 v[132:135], v28 offset:51200
	s_waitcnt lgkmcnt(0)
	v_mfma_f32_16x16x32_f16 v[46:49], v[74:77], v[132:135], v[46:49]
	ds_read_b128 v[140:143], v28 offset:53248
	v_mfma_f32_16x16x32_f16 v[54:57], v[116:119], v[78:81], v[54:57]
	ds_read_b128 v[144:147], v28 offset:55296
	v_mfma_f32_16x16x32_f16 v[70:73], v[116:119], v[132:135], v[70:73]
	s_waitcnt lgkmcnt(1)
	v_mfma_f32_16x16x32_f16 v[104:107], v[74:77], v[140:143], v[104:107]
	s_waitcnt lgkmcnt(0)
	v_mfma_f32_16x16x32_f16 v[22:25], v[74:77], v[144:147], v[22:25]
	v_mfma_f32_16x16x32_f16 v[74:77], v[116:119], v[140:143], v[108:111]
	s_nop 2
	ds_read_b128 v[108:111], v16 offset:20480
	v_mfma_f32_16x16x32_f16 v[34:37], v[116:119], v[144:147], v[34:37]
	ds_read_b128 v[116:119], v16 offset:22528
	s_waitcnt lgkmcnt(1)
	v_mfma_f32_16x16x32_f16 v[120:123], v[108:111], v[78:81], v[120:123]
	v_mfma_f32_16x16x32_f16 v[124:127], v[108:111], v[132:135], v[124:127]
	s_waitcnt lgkmcnt(0)
	v_mfma_f32_16x16x32_f16 v[62:65], v[116:119], v[78:81], v[62:65]
	ds_read_b128 v[78:81], v29 offset:16384
	v_mfma_f32_16x16x32_f16 v[38:41], v[116:119], v[132:135], v[38:41]
	ds_read_b128 v[132:135], v32 offset:51200
	s_waitcnt vmcnt(7)
	ds_write_b128 v18, v[112:115]
	v_mfma_f32_16x16x32_f16 v[136:139], v[108:111], v[140:143], v[136:139]
	s_waitcnt vmcnt(6)
; #define GL_LOAD(s_, kt_) if (VAR != 1) { a##s_##0 = GL_A(0, kt_); a##s_##1 = GL_A(1, kt_); a##s_##2 = GL_A(2, kt_); a##s_##3 = GL_A(3, kt_); b##s_##0 = GL_B(0, kt_); b##s_##1 = GL_B(1, kt_); b##s_##2 = GL_B(2, kt_); b##s_##3 = GL_B(3, kt_); }
; #define LDS_STORE(s_, buf_) if (VAR != 2) { LDS_ST1(sA, 0, buf_, a##s_##0) LDS_ST1(sA, 1, buf_, a##s_##1) LDS_ST1(sA, 2, buf_, a##s_##2) LDS_ST1(sA, 3, buf_, a##s_##3) LDS_ST1(sB, 0, buf_, b##s_##0) LDS_ST1(sB, 1, buf_, b##s_##1) LDS_ST1(sB, 2, buf_, b##s_##2) LDS_ST1(sB, 3, buf_, b##s_##3) }
;     ...
;   GL_LOAD(0, 0)
;   GL_LOAD(1, 1)
;   LDS_STORE(0, 0)
;   if (VAR != 4) __syncthreads();
; #pragma unroll
;   for (int kt = 0; kt < nk; kt += 2) {
;     if (kt + 2 < nk) { GL_LOAD(0, kt + 2) }
;     MMA_TILE(0)
;     LDS_STORE(1, 1)
;     if (VAR != 4) __syncthreads();
;     if (kt + 3 < nk) { GL_LOAD(1, kt + 3) }
;     MMA_TILE(1)
;     if (kt + 2 < nk) { LDS_STORE(0, 0) }
;     if (VAR != 4) __syncthreads();
	ds_write_b128 v19, v[128:131]
	s_waitcnt vmcnt(5)
	ds_write_b128 v20, v[196:199]
	v_mfma_f32_16x16x32_f16 v[66:69], v[108:111], v[144:147], v[66:69]
	ds_read_b128 v[108:111], v32 offset:49152
	s_waitcnt vmcnt(4)
	ds_write_b128 v17, v[200:203]
	v_mfma_f32_16x16x32_f16 v[50:53], v[116:119], v[140:143], v[50:53]
	ds_read_b128 v[140:143], v32 offset:53248
	v_mfma_f32_16x16x32_f16 v[58:61], v[116:119], v[144:147], v[58:61]
	ds_read_b128 v[116:119], v29 offset:18432
	s_waitcnt lgkmcnt(3)
	v_mfma_f32_16x16x32_f16 v[42:45], v[78:81], v[108:111], v[42:45]
	ds_read_b128 v[144:147], v32 offset:55296
	v_mfma_f32_16x16x32_f16 v[46:49], v[78:81], v[132:135], v[46:49]
	s_waitcnt vmcnt(3)
	ds_write_b128 v18, v[154:157] offset:32768
	s_waitcnt lgkmcnt(2)
	v_mfma_f32_16x16x32_f16 v[54:57], v[116:119], v[108:111], v[54:57]
	s_waitcnt vmcnt(2)
	ds_write_b128 v19, v[204:207] offset:32768
	v_mfma_f32_16x16x32_f16 v[70:73], v[116:119], v[132:135], v[70:73]
	s_waitcnt vmcnt(1)
	ds_write_b128 v20, v[208:211] offset:32768
	v_mfma_f32_16x16x32_f16 v[104:107], v[78:81], v[140:143], v[104:107]
	s_waitcnt vmcnt(0)
	ds_write_b128 v17, v[212:215] offset:32768
	s_waitcnt lgkmcnt(4)
	v_mfma_f32_16x16x32_f16 v[22:25], v[78:81], v[144:147], v[22:25]
	ds_read_b128 v[78:81], v29 offset:20480
	v_mfma_f32_16x16x32_f16 v[74:77], v[116:119], v[140:143], v[74:77]
	v_mfma_f32_16x16x32_f16 v[34:37], v[116:119], v[144:147], v[34:37]
	ds_read_b128 v[116:119], v29 offset:22528
	s_waitcnt lgkmcnt(1)
	v_mfma_f32_16x16x32_f16 v[120:123], v[78:81], v[108:111], v[120:123]
	v_mfma_f32_16x16x32_f16 v[124:127], v[78:81], v[132:135], v[124:127]
	s_waitcnt lgkmcnt(0)
	v_mfma_f32_16x16x32_f16 v[62:65], v[116:119], v[108:111], v[62:65]
	v_mfma_f32_16x16x32_f16 v[38:41], v[116:119], v[132:135], v[38:41]
	v_mfma_f32_16x16x32_f16 v[136:139], v[78:81], v[140:143], v[136:139]
	v_mfma_f32_16x16x32_f16 v[66:69], v[78:81], v[144:147], v[66:69]
	global_load_dwordx4 v[78:81], v[0:1], off offset:640
	global_load_dwordx4 v[108:111], v[2:3], off offset:640
	global_load_dwordx4 v[158:161], v[4:5], off offset:640
	global_load_dwordx4 v[162:165], v[8:9], off offset:640
	global_load_dwordx4 v[132:135], v[6:7], off offset:640
	global_load_dwordx4 v[166:169], v[10:11], off offset:640
	global_load_dwordx4 v[188:191], v[12:13], off offset:640
	global_load_dwordx4 v[192:195], v[14:15], off offset:640
	s_waitcnt lgkmcnt(0)
	s_barrier
	v_mfma_f32_16x16x32_f16 v[50:53], v[116:119], v[140:143], v[50:53]
	ds_read_b128 v[112:115], v16
	v_mfma_f32_16x16x32_f16 v[58:61], v[116:119], v[144:147], v[58:61]
	ds_read_b128 v[116:119], v28 offset:32768
	s_waitcnt lgkmcnt(0)
	v_mfma_f32_16x16x32_f16 v[42:45], v[112:115], v[116:119], v[42:45]
	ds_read_b128 v[128:131], v16 offset:2048
	ds_read_b128 v[140:143], v28 offset:34816
	s_waitcnt lgkmcnt(0)
	v_mfma_f32_16x16x32_f16 v[46:49], v[112:115], v[140:143], v[46:49]
	ds_read_b128 v[144:147], v28 offset:36864
	v_mfma_f32_16x16x32_f16 v[54:57], v[128:131], v[116:119], v[54:57]
	ds_read_b128 v[154:157], v28 offset:38912
	v_mfma_f32_16x16x32_f16 v[70:73], v[128:131], v[140:143], v[70:73]
	s_waitcnt lgkmcnt(1)
	v_mfma_f32_16x16x32_f16 v[104:107], v[112:115], v[144:147], v[104:107]
	s_waitcnt lgkmcnt(0)
	v_mfma_f32_16x16x32_f16 v[22:25], v[112:115], v[154:157], v[22:25]
	ds_read_b128 v[112:115], v16 offset:4096
	v_mfma_f32_16x16x32_f16 v[74:77], v[128:131], v[144:147], v[74:77]
	v_mfma_f32_16x16x32_f16 v[34:37], v[128:131], v[154:157], v[34:37]
	ds_read_b128 v[128:131], v16 offset:6144
	s_waitcnt lgkmcnt(1)
	v_mfma_f32_16x16x32_f16 v[120:123], v[112:115], v[116:119], v[120:123]
	v_mfma_f32_16x16x32_f16 v[124:127], v[112:115], v[140:143], v[124:127]
	s_waitcnt lgkmcnt(0)
	v_mfma_f32_16x16x32_f16 v[62:65], v[128:131], v[116:119], v[62:65]
	ds_read_b128 v[116:119], v32 offset:32768
	v_mfma_f32_16x16x32_f16 v[38:41], v[128:131], v[140:143], v[38:41]
	ds_read_b128 v[140:143], v32 offset:34816
	s_waitcnt vmcnt(7)
	ds_write_b128 v18, v[78:81] offset:16384
	v_mfma_f32_16x16x32_f16 v[136:139], v[112:115], v[144:147], v[136:139]
	s_waitcnt vmcnt(6)
	ds_write_b128 v19, v[108:111] offset:16384
	s_waitcnt vmcnt(5)
	ds_write_b128 v20, v[158:161] offset:16384
	v_mfma_f32_16x16x32_f16 v[66:69], v[112:115], v[154:157], v[66:69]
	ds_read_b128 v[112:115], v29
	s_waitcnt vmcnt(4)
	ds_write_b128 v17, v[162:165] offset:16384
	v_mfma_f32_16x16x32_f16 v[50:53], v[128:131], v[144:147], v[50:53]
	ds_read_b128 v[144:147], v32 offset:36864
	v_mfma_f32_16x16x32_f16 v[58:61], v[128:131], v[154:157], v[58:61]
	ds_read_b128 v[128:131], v29 offset:2048
	s_waitcnt lgkmcnt(3)
	v_mfma_f32_16x16x32_f16 v[42:45], v[112:115], v[116:119], v[42:45]
	ds_read_b128 v[154:157], v32 offset:38912
	v_mfma_f32_16x16x32_f16 v[46:49], v[112:115], v[140:143], v[46:49]
	s_waitcnt vmcnt(3)
	ds_write_b128 v18, v[132:135] offset:49152
	s_waitcnt lgkmcnt(2)
	v_mfma_f32_16x16x32_f16 v[54:57], v[128:131], v[116:119], v[54:57]
	s_waitcnt vmcnt(2)
	ds_write_b128 v19, v[166:169] offset:49152
	v_mfma_f32_16x16x32_f16 v[70:73], v[128:131], v[140:143], v[70:73]
	s_waitcnt vmcnt(1)
	ds_write_b128 v20, v[188:191] offset:49152
	v_mfma_f32_16x16x32_f16 v[104:107], v[112:115], v[144:147], v[104:107]
	s_waitcnt vmcnt(0)
	ds_write_b128 v17, v[192:195] offset:49152
	s_waitcnt lgkmcnt(4)
	v_mfma_f32_16x16x32_f16 v[22:25], v[112:115], v[154:157], v[22:25]
	ds_read_b128 v[112:115], v29 offset:4096
	v_mfma_f32_16x16x32_f16 v[74:77], v[128:131], v[144:147], v[74:77]
	v_mfma_f32_16x16x32_f16 v[34:37], v[128:131], v[154:157], v[34:37]
	ds_read_b128 v[128:131], v29 offset:6144
	s_waitcnt lgkmcnt(1)
	v_mfma_f32_16x16x32_f16 v[120:123], v[112:115], v[116:119], v[120:123]
	v_mfma_f32_16x16x32_f16 v[124:127], v[112:115], v[140:143], v[124:127]
	s_waitcnt lgkmcnt(0)
	v_mfma_f32_16x16x32_f16 v[62:65], v[128:131], v[116:119], v[62:65]
	v_mfma_f32_16x16x32_f16 v[38:41], v[128:131], v[140:143], v[38:41]
	v_mfma_f32_16x16x32_f16 v[136:139], v[112:115], v[144:147], v[136:139]
	v_mfma_f32_16x16x32_f16 v[66:69], v[112:115], v[154:157], v[66:69]
	global_load_dwordx4 v[112:115], v[0:1], off offset:768
	global_load_dwordx4 v[116:119], v[2:3], off offset:768
	global_load_dwordx4 v[196:199], v[4:5], off offset:768
	global_load_dwordx4 v[200:203], v[8:9], off offset:768
	global_load_dwordx4 v[140:143], v[6:7], off offset:768
	global_load_dwordx4 v[204:207], v[10:11], off offset:768
	global_load_dwordx4 v[208:211], v[12:13], off offset:768
	global_load_dwordx4 v[212:215], v[14:15], off offset:768
	s_waitcnt lgkmcnt(0)
	s_barrier
; #define GL_LOAD(s_, kt_) if (VAR != 1) { a##s_##0 = GL_A(0, kt_); a##s_##1 = GL_A(1, kt_); a##s_##2 = GL_A(2, kt_); a##s_##3 = GL_A(3, kt_); b##s_##0 = GL_B(0, kt_); b##s_##1 = GL_B(1, kt_); b##s_##2 = GL_B(2, kt_); b##s_##3 = GL_B(3, kt_); }
; #define LDS_STORE(s_, buf_) if (VAR != 2) { LDS_ST1(sA, 0, buf_, a##s_##0) LDS_ST1(sA, 1, buf_, a##s_##1) LDS_ST1(sA, 2, buf_, a##s_##2) LDS_ST1(sA, 3, buf_, a##s_##3) LDS_ST1(sB, 0, buf_, b##s_##0) LDS_ST1(sB, 1, buf_, b##s_##1) LDS_ST1(sB, 2, buf_, b##s_##2) LDS_ST1(sB, 3, buf_, b##s_##3) }
;     ...
;   GL_LOAD(0, 0)
;   GL_LOAD(1, 1)
;   LDS_STORE(0, 0)
;   if (VAR != 4) __syncthreads();
; #pragma unroll
;   for (int kt = 0; kt < nk; kt += 2) {
;     if (kt + 2 < nk) { GL_LOAD(0, kt + 2) }
;     MMA_TILE(0)
;     LDS_STORE(1, 1)
;     if (VAR != 4) __syncthreads();
;     if (kt + 3 < nk) { GL_LOAD(1, kt + 3) }
;     MMA_TILE(1)
;     if (kt + 2 < nk) { LDS_STORE(0, 0) }
;     if (VAR != 4) __syncthreads();
	v_mfma_f32_16x16x32_f16 v[50:53], v[128:131], v[144:147], v[50:53]
	ds_read_b128 v[78:81], v16 offset:16384
	v_mfma_f32_16x16x32_f16 v[58:61], v[128:131], v[154:157], v[58:61]
	ds_read_b128 v[108:111], v28 offset:49152
	s_waitcnt lgkmcnt(0)
	v_mfma_f32_16x16x32_f16 v[42:45], v[78:81], v[108:111], v[42:45]
	ds_read_b128 v[128:131], v16 offset:18432
	ds_read_b128 v[132:135], v28 offset:51200
	s_waitcnt lgkmcnt(0)
	v_mfma_f32_16x16x32_f16 v[46:49], v[78:81], v[132:135], v[46:49]
	ds_read_b128 v[144:147], v28 offset:53248
	v_mfma_f32_16x16x32_f16 v[54:57], v[128:131], v[108:111], v[54:57]
	ds_read_b128 v[154:157], v28 offset:55296
	v_mfma_f32_16x16x32_f16 v[70:73], v[128:131], v[132:135], v[70:73]
	s_waitcnt lgkmcnt(1)
	v_mfma_f32_16x16x32_f16 v[104:107], v[78:81], v[144:147], v[104:107]
	s_waitcnt lgkmcnt(0)
	v_mfma_f32_16x16x32_f16 v[22:25], v[78:81], v[154:157], v[22:25]
	ds_read_b128 v[78:81], v16 offset:20480
	v_mfma_f32_16x16x32_f16 v[74:77], v[128:131], v[144:147], v[74:77]
	v_mfma_f32_16x16x32_f16 v[34:37], v[128:131], v[154:157], v[34:37]
	ds_read_b128 v[128:131], v16 offset:22528
	s_waitcnt lgkmcnt(1)
	v_mfma_f32_16x16x32_f16 v[120:123], v[78:81], v[108:111], v[120:123]
	v_mfma_f32_16x16x32_f16 v[124:127], v[78:81], v[132:135], v[124:127]
	s_waitcnt lgkmcnt(0)
	v_mfma_f32_16x16x32_f16 v[62:65], v[128:131], v[108:111], v[62:65]
	ds_read_b128 v[108:111], v32 offset:49152
	v_mfma_f32_16x16x32_f16 v[38:41], v[128:131], v[132:135], v[38:41]
	ds_read_b128 v[132:135], v32 offset:51200
	s_waitcnt vmcnt(7)
	ds_write_b128 v18, v[112:115]
	v_mfma_f32_16x16x32_f16 v[136:139], v[78:81], v[144:147], v[136:139]
	s_waitcnt vmcnt(6)
	ds_write_b128 v19, v[116:119]
	s_waitcnt vmcnt(5)
	ds_write_b128 v20, v[196:199]
	v_mfma_f32_16x16x32_f16 v[66:69], v[78:81], v[154:157], v[66:69]
	ds_read_b128 v[78:81], v29 offset:16384
	s_waitcnt vmcnt(4)
	ds_write_b128 v17, v[200:203]
	v_mfma_f32_16x16x32_f16 v[50:53], v[128:131], v[144:147], v[50:53]
	ds_read_b128 v[144:147], v32 offset:53248
	v_mfma_f32_16x16x32_f16 v[58:61], v[128:131], v[154:157], v[58:61]
	ds_read_b128 v[128:131], v29 offset:18432
	s_waitcnt lgkmcnt(3)
	v_mfma_f32_16x16x32_f16 v[42:45], v[78:81], v[108:111], v[42:45]
	ds_read_b128 v[154:157], v32 offset:55296
	v_mfma_f32_16x16x32_f16 v[46:49], v[78:81], v[132:135], v[46:49]
	s_waitcnt vmcnt(3)
	ds_write_b128 v18, v[140:143] offset:32768
	s_waitcnt lgkmcnt(2)
	v_mfma_f32_16x16x32_f16 v[54:57], v[128:131], v[108:111], v[54:57]
	s_waitcnt vmcnt(2)
	ds_write_b128 v19, v[204:207] offset:32768
	v_mfma_f32_16x16x32_f16 v[70:73], v[128:131], v[132:135], v[70:73]
	s_waitcnt vmcnt(1)
	ds_write_b128 v20, v[208:211] offset:32768
	v_mfma_f32_16x16x32_f16 v[104:107], v[78:81], v[144:147], v[104:107]
	s_waitcnt vmcnt(0)
	ds_write_b128 v17, v[212:215] offset:32768
	s_waitcnt lgkmcnt(4)
	v_mfma_f32_16x16x32_f16 v[22:25], v[78:81], v[154:157], v[22:25]
	ds_read_b128 v[78:81], v29 offset:20480
	v_mfma_f32_16x16x32_f16 v[74:77], v[128:131], v[144:147], v[74:77]
	v_mfma_f32_16x16x32_f16 v[34:37], v[128:131], v[154:157], v[34:37]
	ds_read_b128 v[128:131], v29 offset:22528
	s_waitcnt lgkmcnt(1)
	v_mfma_f32_16x16x32_f16 v[120:123], v[78:81], v[108:111], v[120:123]
	v_mfma_f32_16x16x32_f16 v[124:127], v[78:81], v[132:135], v[124:127]
	s_waitcnt lgkmcnt(0)
	v_mfma_f32_16x16x32_f16 v[62:65], v[128:131], v[108:111], v[62:65]
	v_mfma_f32_16x16x32_f16 v[38:41], v[128:131], v[132:135], v[38:41]
	v_mfma_f32_16x16x32_f16 v[136:139], v[78:81], v[144:147], v[136:139]
	v_mfma_f32_16x16x32_f16 v[66:69], v[78:81], v[154:157], v[66:69]
	global_load_dwordx4 v[78:81], v[0:1], off offset:896
	global_load_dwordx4 v[108:111], v[2:3], off offset:896
	global_load_dwordx4 v[158:161], v[4:5], off offset:896
	global_load_dwordx4 v[162:165], v[8:9], off offset:896
	global_load_dwordx4 v[132:135], v[6:7], off offset:896
	global_load_dwordx4 v[166:169], v[10:11], off offset:896
	global_load_dwordx4 v[188:191], v[12:13], off offset:896
	global_load_dwordx4 v[192:195], v[14:15], off offset:896
	s_waitcnt lgkmcnt(0)
	s_barrier
	v_mfma_f32_16x16x32_f16 v[50:53], v[128:131], v[144:147], v[50:53]
	ds_read_b128 v[112:115], v16
	v_mfma_f32_16x16x32_f16 v[58:61], v[128:131], v[154:157], v[58:61]
	ds_read_b128 v[116:119], v28 offset:32768
	s_waitcnt lgkmcnt(0)
	v_mfma_f32_16x16x32_f16 v[42:45], v[112:115], v[116:119], v[42:45]
	ds_read_b128 v[128:131], v16 offset:2048
	ds_read_b128 v[140:143], v28 offset:34816
	s_waitcnt lgkmcnt(0)
	v_mfma_f32_16x16x32_f16 v[46:49], v[112:115], v[140:143], v[46:49]
	ds_read_b128 v[144:147], v28 offset:36864
	v_mfma_f32_16x16x32_f16 v[54:57], v[128:131], v[116:119], v[54:57]
	ds_read_b128 v[154:157], v28 offset:38912
	v_mfma_f32_16x16x32_f16 v[70:73], v[128:131], v[140:143], v[70:73]
	s_waitcnt lgkmcnt(1)
	v_mfma_f32_16x16x32_f16 v[104:107], v[112:115], v[144:147], v[104:107]
	s_waitcnt lgkmcnt(0)
	v_mfma_f32_16x16x32_f16 v[22:25], v[112:115], v[154:157], v[22:25]
	ds_read_b128 v[112:115], v16 offset:4096
	v_mfma_f32_16x16x32_f16 v[74:77], v[128:131], v[144:147], v[74:77]
	v_mfma_f32_16x16x32_f16 v[34:37], v[128:131], v[154:157], v[34:37]
	ds_read_b128 v[128:131], v16 offset:6144
	s_waitcnt lgkmcnt(1)
	v_mfma_f32_16x16x32_f16 v[120:123], v[112:115], v[116:119], v[120:123]
	v_mfma_f32_16x16x32_f16 v[124:127], v[112:115], v[140:143], v[124:127]
	s_waitcnt lgkmcnt(0)
	v_mfma_f32_16x16x32_f16 v[62:65], v[128:131], v[116:119], v[62:65]
	ds_read_b128 v[116:119], v32 offset:32768
	v_mfma_f32_16x16x32_f16 v[38:41], v[128:131], v[140:143], v[38:41]
	ds_read_b128 v[140:143], v32 offset:34816
	s_waitcnt vmcnt(7)
; #define GL_LOAD(s_, kt_) if (VAR != 1) { a##s_##0 = GL_A(0, kt_); a##s_##1 = GL_A(1, kt_); a##s_##2 = GL_A(2, kt_); a##s_##3 = GL_A(3, kt_); b##s_##0 = GL_B(0, kt_); b##s_##1 = GL_B(1, kt_); b##s_##2 = GL_B(2, kt_); b##s_##3 = GL_B(3, kt_); }
; #define LDS_STORE(s_, buf_) if (VAR != 2) { LDS_ST1(sA, 0, buf_, a##s_##0) LDS_ST1(sA, 1, buf_, a##s_##1) LDS_ST1(sA, 2, buf_, a##s_##2) LDS_ST1(sA, 3, buf_, a##s_##3) LDS_ST1(sB, 0, buf_, b##s_##0) LDS_ST1(sB, 1, buf_, b##s_##1) LDS_ST1(sB, 2, buf_, b##s_##2) LDS_ST1(sB, 3, buf_, b##s_##3) }
;     ...
;   GL_LOAD(0, 0)
;   GL_LOAD(1, 1)
;   LDS_STORE(0, 0)
;   if (VAR != 4) __syncthreads();
; #pragma unroll
;   for (int kt = 0; kt < nk; kt += 2) {
;     if (kt + 2 < nk) { GL_LOAD(0, kt + 2) }
;     MMA_TILE(0)
;     LDS_STORE(1, 1)
;     if (VAR != 4) __syncthreads();
;     if (kt + 3 < nk) { GL_LOAD(1, kt + 3) }
;     MMA_TILE(1)
;     if (kt + 2 < nk) { LDS_STORE(0, 0) }
;     if (VAR != 4) __syncthreads();
	ds_write_b128 v18, v[78:81] offset:16384
	v_mfma_f32_16x16x32_f16 v[136:139], v[112:115], v[144:147], v[136:139]
	s_waitcnt vmcnt(6)
	ds_write_b128 v19, v[108:111] offset:16384
	s_waitcnt vmcnt(5)
	ds_write_b128 v20, v[158:161] offset:16384
	v_mfma_f32_16x16x32_f16 v[66:69], v[112:115], v[154:157], v[66:69]
	ds_read_b128 v[112:115], v29
	s_waitcnt vmcnt(4)
	ds_write_b128 v17, v[162:165] offset:16384
	v_mfma_f32_16x16x32_f16 v[50:53], v[128:131], v[144:147], v[50:53]
	ds_read_b128 v[144:147], v32 offset:36864
	v_mfma_f32_16x16x32_f16 v[58:61], v[128:131], v[154:157], v[58:61]
	ds_read_b128 v[128:131], v29 offset:2048
	s_waitcnt lgkmcnt(3)
	v_mfma_f32_16x16x32_f16 v[42:45], v[112:115], v[116:119], v[42:45]
	ds_read_b128 v[154:157], v32 offset:38912
	v_mfma_f32_16x16x32_f16 v[46:49], v[112:115], v[140:143], v[46:49]
	s_waitcnt vmcnt(3)
	ds_write_b128 v18, v[132:135] offset:49152
	s_waitcnt lgkmcnt(2)
	v_mfma_f32_16x16x32_f16 v[54:57], v[128:131], v[116:119], v[54:57]
	s_waitcnt vmcnt(2)
	ds_write_b128 v19, v[166:169] offset:49152
	v_mfma_f32_16x16x32_f16 v[70:73], v[128:131], v[140:143], v[70:73]
	s_waitcnt vmcnt(1)
	ds_write_b128 v20, v[188:191] offset:49152
	v_mfma_f32_16x16x32_f16 v[104:107], v[112:115], v[144:147], v[104:107]
	s_waitcnt vmcnt(0)
	ds_write_b128 v17, v[192:195] offset:49152
	s_waitcnt lgkmcnt(4)
	v_mfma_f32_16x16x32_f16 v[22:25], v[112:115], v[154:157], v[22:25]
	ds_read_b128 v[112:115], v29 offset:4096
	v_mfma_f32_16x16x32_f16 v[74:77], v[128:131], v[144:147], v[74:77]
	v_mfma_f32_16x16x32_f16 v[34:37], v[128:131], v[154:157], v[34:37]
	ds_read_b128 v[128:131], v29 offset:6144
	s_waitcnt lgkmcnt(1)
	v_mfma_f32_16x16x32_f16 v[120:123], v[112:115], v[116:119], v[120:123]
	v_mfma_f32_16x16x32_f16 v[124:127], v[112:115], v[140:143], v[124:127]
	s_waitcnt lgkmcnt(0)
	v_mfma_f32_16x16x32_f16 v[62:65], v[128:131], v[116:119], v[62:65]
	v_mfma_f32_16x16x32_f16 v[38:41], v[128:131], v[140:143], v[38:41]
	v_mfma_f32_16x16x32_f16 v[136:139], v[112:115], v[144:147], v[136:139]
	v_mfma_f32_16x16x32_f16 v[66:69], v[112:115], v[154:157], v[66:69]
	global_load_dwordx4 v[112:115], v[0:1], off offset:1024
	global_load_dwordx4 v[116:119], v[2:3], off offset:1024
	global_load_dwordx4 v[196:199], v[4:5], off offset:1024
	global_load_dwordx4 v[200:203], v[8:9], off offset:1024
	global_load_dwordx4 v[140:143], v[6:7], off offset:1024
	global_load_dwordx4 v[204:207], v[10:11], off offset:1024
	global_load_dwordx4 v[208:211], v[12:13], off offset:1024
	global_load_dwordx4 v[212:215], v[14:15], off offset:1024
	s_waitcnt lgkmcnt(0)
	s_barrier
	v_mfma_f32_16x16x32_f16 v[50:53], v[128:131], v[144:147], v[50:53]
	ds_read_b128 v[78:81], v16 offset:16384
	v_mfma_f32_16x16x32_f16 v[58:61], v[128:131], v[154:157], v[58:61]
	ds_read_b128 v[108:111], v28 offset:49152
	s_waitcnt lgkmcnt(0)
	v_mfma_f32_16x16x32_f16 v[42:45], v[78:81], v[108:111], v[42:45]
	ds_read_b128 v[128:131], v16 offset:18432
	ds_read_b128 v[132:135], v28 offset:51200
	s_waitcnt lgkmcnt(0)
	v_mfma_f32_16x16x32_f16 v[46:49], v[78:81], v[132:135], v[46:49]
	ds_read_b128 v[144:147], v28 offset:53248
	v_mfma_f32_16x16x32_f16 v[54:57], v[128:131], v[108:111], v[54:57]
	ds_read_b128 v[154:157], v28 offset:55296
	v_mfma_f32_16x16x32_f16 v[70:73], v[128:131], v[132:135], v[70:73]
	s_waitcnt lgkmcnt(1)
	v_mfma_f32_16x16x32_f16 v[104:107], v[78:81], v[144:147], v[104:107]
	s_waitcnt lgkmcnt(0)
	v_mfma_f32_16x16x32_f16 v[22:25], v[78:81], v[154:157], v[22:25]
	ds_read_b128 v[78:81], v16 offset:20480
	v_mfma_f32_16x16x32_f16 v[74:77], v[128:131], v[144:147], v[74:77]
	v_mfma_f32_16x16x32_f16 v[34:37], v[128:131], v[154:157], v[34:37]
	ds_read_b128 v[128:131], v16 offset:22528
	s_waitcnt lgkmcnt(1)
	v_mfma_f32_16x16x32_f16 v[120:123], v[78:81], v[108:111], v[120:123]
	v_mfma_f32_16x16x32_f16 v[124:127], v[78:81], v[132:135], v[124:127]
	s_waitcnt lgkmcnt(0)
	v_mfma_f32_16x16x32_f16 v[62:65], v[128:131], v[108:111], v[62:65]
	ds_read_b128 v[108:111], v32 offset:49152
	v_mfma_f32_16x16x32_f16 v[38:41], v[128:131], v[132:135], v[38:41]
	ds_read_b128 v[132:135], v32 offset:51200
	s_waitcnt vmcnt(7)
	ds_write_b128 v18, v[112:115]
	v_mfma_f32_16x16x32_f16 v[136:139], v[78:81], v[144:147], v[136:139]
	s_waitcnt vmcnt(6)
	ds_write_b128 v19, v[116:119]
	s_waitcnt vmcnt(5)
	ds_write_b128 v20, v[196:199]
	v_mfma_f32_16x16x32_f16 v[66:69], v[78:81], v[154:157], v[66:69]
	ds_read_b128 v[78:81], v29 offset:16384
	s_waitcnt vmcnt(4)
	ds_write_b128 v17, v[200:203]
	v_mfma_f32_16x16x32_f16 v[50:53], v[128:131], v[144:147], v[50:53]
	ds_read_b128 v[144:147], v32 offset:53248
	v_mfma_f32_16x16x32_f16 v[58:61], v[128:131], v[154:157], v[58:61]
	ds_read_b128 v[128:131], v29 offset:18432
	s_waitcnt lgkmcnt(3)
	v_mfma_f32_16x16x32_f16 v[42:45], v[78:81], v[108:111], v[42:45]
	ds_read_b128 v[154:157], v32 offset:55296
	v_mfma_f32_16x16x32_f16 v[46:49], v[78:81], v[132:135], v[46:49]
	s_waitcnt vmcnt(3)
	ds_write_b128 v18, v[140:143] offset:32768
	s_waitcnt lgkmcnt(2)
	v_mfma_f32_16x16x32_f16 v[54:57], v[128:131], v[108:111], v[54:57]
	s_waitcnt vmcnt(2)
	ds_write_b128 v19, v[204:207] offset:32768
	v_mfma_f32_16x16x32_f16 v[70:73], v[128:131], v[132:135], v[70:73]
	s_waitcnt vmcnt(1)
	ds_write_b128 v20, v[208:211] offset:32768
	v_mfma_f32_16x16x32_f16 v[104:107], v[78:81], v[144:147], v[104:107]
	s_waitcnt vmcnt(0)
	ds_write_b128 v17, v[212:215] offset:32768
	s_waitcnt lgkmcnt(4)
	v_mfma_f32_16x16x32_f16 v[22:25], v[78:81], v[154:157], v[22:25]
	ds_read_b128 v[78:81], v29 offset:20480
	v_mfma_f32_16x16x32_f16 v[74:77], v[128:131], v[144:147], v[74:77]
	v_mfma_f32_16x16x32_f16 v[34:37], v[128:131], v[154:157], v[34:37]
	ds_read_b128 v[128:131], v29 offset:22528
	s_waitcnt lgkmcnt(1)
	v_mfma_f32_16x16x32_f16 v[120:123], v[78:81], v[108:111], v[120:123]
	v_mfma_f32_16x16x32_f16 v[124:127], v[78:81], v[132:135], v[124:127]
	s_waitcnt lgkmcnt(0)
	v_mfma_f32_16x16x32_f16 v[62:65], v[128:131], v[108:111], v[62:65]
	v_mfma_f32_16x16x32_f16 v[38:41], v[128:131], v[132:135], v[38:41]
	v_mfma_f32_16x16x32_f16 v[136:139], v[78:81], v[144:147], v[136:139]
	v_mfma_f32_16x16x32_f16 v[66:69], v[78:81], v[154:157], v[66:69]
	global_load_dwordx4 v[78:81], v[0:1], off offset:1152
	global_load_dwordx4 v[108:111], v[2:3], off offset:1152
	global_load_dwordx4 v[158:161], v[4:5], off offset:1152
	global_load_dwordx4 v[162:165], v[8:9], off offset:1152
	global_load_dwordx4 v[132:135], v[6:7], off offset:1152
	global_load_dwordx4 v[166:169], v[10:11], off offset:1152
	global_load_dwordx4 v[188:191], v[12:13], off offset:1152
	global_load_dwordx4 v[192:195], v[14:15], off offset:1152
	s_waitcnt lgkmcnt(0)
	s_barrier
; #define GL_LOAD(s_, kt_) if (VAR != 1) { a##s_##0 = GL_A(0, kt_); a##s_##1 = GL_A(1, kt_); a##s_##2 = GL_A(2, kt_); a##s_##3 = GL_A(3, kt_); b##s_##0 = GL_B(0, kt_); b##s_##1 = GL_B(1, kt_); b##s_##2 = GL_B(2, kt_); b##s_##3 = GL_B(3, kt_); }
; #define LDS_STORE(s_, buf_) if (VAR != 2) { LDS_ST1(sA, 0, buf_, a##s_##0) LDS_ST1(sA, 1, buf_, a##s_##1) LDS_ST1(sA, 2, buf_, a##s_##2) LDS_ST1(sA, 3, buf_, a##s_##3) LDS_ST1(sB, 0, buf_, b##s_##0) LDS_ST1(sB, 1, buf_, b##s_##1) LDS_ST1(sB, 2, buf_, b##s_##2) LDS_ST1(sB, 3, buf_, b##s_##3) }
;     ...
;   GL_LOAD(0, 0)
;   GL_LOAD(1, 1)
;   LDS_STORE(0, 0)
;   if (VAR != 4) __syncthreads();
; #pragma unroll
;   for (int kt = 0; kt < nk; kt += 2) {
;     if (kt + 2 < nk) { GL_LOAD(0, kt + 2) }
;     MMA_TILE(0)
;     LDS_STORE(1, 1)
;     if (VAR != 4) __syncthreads();
;     if (kt + 3 < nk) { GL_LOAD(1, kt + 3) }
;     MMA_TILE(1)
;     if (kt + 2 < nk) { LDS_STORE(0, 0) }
;     if (VAR != 4) __syncthreads();
	v_mfma_f32_16x16x32_f16 v[50:53], v[128:131], v[144:147], v[50:53]
	ds_read_b128 v[112:115], v16
	v_mfma_f32_16x16x32_f16 v[58:61], v[128:131], v[154:157], v[58:61]
	ds_read_b128 v[116:119], v28 offset:32768
	s_waitcnt lgkmcnt(0)
	v_mfma_f32_16x16x32_f16 v[42:45], v[112:115], v[116:119], v[42:45]
	ds_read_b128 v[128:131], v16 offset:2048
	ds_read_b128 v[140:143], v28 offset:34816
	s_waitcnt lgkmcnt(0)
	v_mfma_f32_16x16x32_f16 v[46:49], v[112:115], v[140:143], v[46:49]
	ds_read_b128 v[144:147], v28 offset:36864
	v_mfma_f32_16x16x32_f16 v[54:57], v[128:131], v[116:119], v[54:57]
	ds_read_b128 v[154:157], v28 offset:38912
	v_mfma_f32_16x16x32_f16 v[70:73], v[128:131], v[140:143], v[70:73]
	s_waitcnt lgkmcnt(1)
	v_mfma_f32_16x16x32_f16 v[104:107], v[112:115], v[144:147], v[104:107]
	s_waitcnt lgkmcnt(0)
	v_mfma_f32_16x16x32_f16 v[22:25], v[112:115], v[154:157], v[22:25]
	ds_read_b128 v[112:115], v16 offset:4096
	v_mfma_f32_16x16x32_f16 v[74:77], v[128:131], v[144:147], v[74:77]
	v_mfma_f32_16x16x32_f16 v[34:37], v[128:131], v[154:157], v[34:37]
	ds_read_b128 v[128:131], v16 offset:6144
	s_waitcnt lgkmcnt(1)
	v_mfma_f32_16x16x32_f16 v[120:123], v[112:115], v[116:119], v[120:123]
	v_mfma_f32_16x16x32_f16 v[124:127], v[112:115], v[140:143], v[124:127]
	s_waitcnt lgkmcnt(0)
	v_mfma_f32_16x16x32_f16 v[62:65], v[128:131], v[116:119], v[62:65]
	ds_read_b128 v[116:119], v32 offset:32768
	v_mfma_f32_16x16x32_f16 v[38:41], v[128:131], v[140:143], v[38:41]
	ds_read_b128 v[140:143], v32 offset:34816
	s_waitcnt vmcnt(7)
	ds_write_b128 v18, v[78:81] offset:16384
	v_mfma_f32_16x16x32_f16 v[136:139], v[112:115], v[144:147], v[136:139]
	s_waitcnt vmcnt(6)
	ds_write_b128 v19, v[108:111] offset:16384
	s_waitcnt vmcnt(5)
	ds_write_b128 v20, v[158:161] offset:16384
	v_mfma_f32_16x16x32_f16 v[66:69], v[112:115], v[154:157], v[66:69]
	ds_read_b128 v[112:115], v29
	s_waitcnt vmcnt(4)
	ds_write_b128 v17, v[162:165] offset:16384
	v_mfma_f32_16x16x32_f16 v[50:53], v[128:131], v[144:147], v[50:53]
	ds_read_b128 v[144:147], v32 offset:36864
	v_mfma_f32_16x16x32_f16 v[58:61], v[128:131], v[154:157], v[58:61]
	ds_read_b128 v[128:131], v29 offset:2048
	s_waitcnt lgkmcnt(3)
	v_mfma_f32_16x16x32_f16 v[42:45], v[112:115], v[116:119], v[42:45]
	ds_read_b128 v[154:157], v32 offset:38912
	v_mfma_f32_16x16x32_f16 v[46:49], v[112:115], v[140:143], v[46:49]
	s_waitcnt vmcnt(3)
	ds_write_b128 v18, v[132:135] offset:49152
	s_waitcnt lgkmcnt(2)
	v_mfma_f32_16x16x32_f16 v[54:57], v[128:131], v[116:119], v[54:57]
	s_waitcnt vmcnt(2)
	ds_write_b128 v19, v[166:169] offset:49152
	v_mfma_f32_16x16x32_f16 v[70:73], v[128:131], v[140:143], v[70:73]
	s_waitcnt vmcnt(1)
	ds_write_b128 v20, v[188:191] offset:49152
	v_mfma_f32_16x16x32_f16 v[104:107], v[112:115], v[144:147], v[104:107]
	s_waitcnt vmcnt(0)
	ds_write_b128 v17, v[192:195] offset:49152
	s_waitcnt lgkmcnt(4)
	v_mfma_f32_16x16x32_f16 v[22:25], v[112:115], v[154:157], v[22:25]
	ds_read_b128 v[112:115], v29 offset:4096
	v_mfma_f32_16x16x32_f16 v[74:77], v[128:131], v[144:147], v[74:77]
	v_mfma_f32_16x16x32_f16 v[34:37], v[128:131], v[154:157], v[34:37]
	ds_read_b128 v[128:131], v29 offset:6144
	s_waitcnt lgkmcnt(1)
	v_mfma_f32_16x16x32_f16 v[120:123], v[112:115], v[116:119], v[120:123]
	v_mfma_f32_16x16x32_f16 v[124:127], v[112:115], v[140:143], v[124:127]
	s_waitcnt lgkmcnt(0)
	v_mfma_f32_16x16x32_f16 v[62:65], v[128:131], v[116:119], v[62:65]
	v_mfma_f32_16x16x32_f16 v[38:41], v[128:131], v[140:143], v[38:41]
	v_mfma_f32_16x16x32_f16 v[136:139], v[112:115], v[144:147], v[136:139]
	v_mfma_f32_16x16x32_f16 v[66:69], v[112:115], v[154:157], v[66:69]
	global_load_dwordx4 v[112:115], v[0:1], off offset:1280
	global_load_dwordx4 v[116:119], v[2:3], off offset:1280
	global_load_dwordx4 v[196:199], v[4:5], off offset:1280
	global_load_dwordx4 v[200:203], v[8:9], off offset:1280
	global_load_dwordx4 v[140:143], v[6:7], off offset:1280
	global_load_dwordx4 v[204:207], v[10:11], off offset:1280
	global_load_dwordx4 v[208:211], v[12:13], off offset:1280
	global_load_dwordx4 v[212:215], v[14:15], off offset:1280
	s_waitcnt lgkmcnt(0)
	s_barrier
	v_mfma_f32_16x16x32_f16 v[50:53], v[128:131], v[144:147], v[50:53]
	ds_read_b128 v[78:81], v16 offset:16384
	v_mfma_f32_16x16x32_f16 v[58:61], v[128:131], v[154:157], v[58:61]
	ds_read_b128 v[108:111], v28 offset:49152
	s_waitcnt lgkmcnt(0)
	v_mfma_f32_16x16x32_f16 v[42:45], v[78:81], v[108:111], v[42:45]
	ds_read_b128 v[128:131], v16 offset:18432
	ds_read_b128 v[132:135], v28 offset:51200
	s_waitcnt lgkmcnt(0)
	v_mfma_f32_16x16x32_f16 v[46:49], v[78:81], v[132:135], v[46:49]
	ds_read_b128 v[144:147], v28 offset:53248
	v_mfma_f32_16x16x32_f16 v[54:57], v[128:131], v[108:111], v[54:57]
	ds_read_b128 v[154:157], v28 offset:55296
	v_mfma_f32_16x16x32_f16 v[70:73], v[128:131], v[132:135], v[70:73]
	s_waitcnt lgkmcnt(1)
	v_mfma_f32_16x16x32_f16 v[104:107], v[78:81], v[144:147], v[104:107]
	s_waitcnt lgkmcnt(0)
	v_mfma_f32_16x16x32_f16 v[22:25], v[78:81], v[154:157], v[22:25]
	ds_read_b128 v[78:81], v16 offset:20480
	v_mfma_f32_16x16x32_f16 v[74:77], v[128:131], v[144:147], v[74:77]
	v_mfma_f32_16x16x32_f16 v[34:37], v[128:131], v[154:157], v[34:37]
	ds_read_b128 v[128:131], v16 offset:22528
	s_waitcnt lgkmcnt(1)
	v_mfma_f32_16x16x32_f16 v[120:123], v[78:81], v[108:111], v[120:123]
	v_mfma_f32_16x16x32_f16 v[124:127], v[78:81], v[132:135], v[124:127]
	s_waitcnt lgkmcnt(0)
	v_mfma_f32_16x16x32_f16 v[62:65], v[128:131], v[108:111], v[62:65]
	ds_read_b128 v[108:111], v32 offset:49152
	v_mfma_f32_16x16x32_f16 v[38:41], v[128:131], v[132:135], v[38:41]
	ds_read_b128 v[132:135], v32 offset:51200
	s_waitcnt vmcnt(7)
; #define GL_LOAD(s_, kt_) if (VAR != 1) { a##s_##0 = GL_A(0, kt_); a##s_##1 = GL_A(1, kt_); a##s_##2 = GL_A(2, kt_); a##s_##3 = GL_A(3, kt_); b##s_##0 = GL_B(0, kt_); b##s_##1 = GL_B(1, kt_); b##s_##2 = GL_B(2, kt_); b##s_##3 = GL_B(3, kt_); }
; #define LDS_STORE(s_, buf_) if (VAR != 2) { LDS_ST1(sA, 0, buf_, a##s_##0) LDS_ST1(sA, 1, buf_, a##s_##1) LDS_ST1(sA, 2, buf_, a##s_##2) LDS_ST1(sA, 3, buf_, a##s_##3) LDS_ST1(sB, 0, buf_, b##s_##0) LDS_ST1(sB, 1, buf_, b##s_##1) LDS_ST1(sB, 2, buf_, b##s_##2) LDS_ST1(sB, 3, buf_, b##s_##3) }
;     ...
;   GL_LOAD(0, 0)
;   GL_LOAD(1, 1)
;   LDS_STORE(0, 0)
;   if (VAR != 4) __syncthreads();
; #pragma unroll
;   for (int kt = 0; kt < nk; kt += 2) {
;     if (kt + 2 < nk) { GL_LOAD(0, kt + 2) }
;     MMA_TILE(0)
;     LDS_STORE(1, 1)
;     if (VAR != 4) __syncthreads();
;     if (kt + 3 < nk) { GL_LOAD(1, kt + 3) }
;     MMA_TILE(1)
;     if (kt + 2 < nk) { LDS_STORE(0, 0) }
;     if (VAR != 4) __syncthreads();
	ds_write_b128 v18, v[112:115]
	v_mfma_f32_16x16x32_f16 v[136:139], v[78:81], v[144:147], v[136:139]
	s_waitcnt vmcnt(6)
	ds_write_b128 v19, v[116:119]
	s_waitcnt vmcnt(5)
	ds_write_b128 v20, v[196:199]
	v_mfma_f32_16x16x32_f16 v[66:69], v[78:81], v[154:157], v[66:69]
	ds_read_b128 v[78:81], v29 offset:16384
	s_waitcnt vmcnt(4)
	ds_write_b128 v17, v[200:203]
	v_mfma_f32_16x16x32_f16 v[50:53], v[128:131], v[144:147], v[50:53]
	ds_read_b128 v[144:147], v32 offset:53248
	v_mfma_f32_16x16x32_f16 v[58:61], v[128:131], v[154:157], v[58:61]
	ds_read_b128 v[128:131], v29 offset:18432
	s_waitcnt lgkmcnt(3)
	v_mfma_f32_16x16x32_f16 v[42:45], v[78:81], v[108:111], v[42:45]
	ds_read_b128 v[154:157], v32 offset:55296
	v_mfma_f32_16x16x32_f16 v[46:49], v[78:81], v[132:135], v[46:49]
	s_waitcnt vmcnt(3)
	ds_write_b128 v18, v[140:143] offset:32768
	s_waitcnt lgkmcnt(2)
	v_mfma_f32_16x16x32_f16 v[54:57], v[128:131], v[108:111], v[54:57]
	s_waitcnt vmcnt(2)
	ds_write_b128 v19, v[204:207] offset:32768
	v_mfma_f32_16x16x32_f16 v[70:73], v[128:131], v[132:135], v[70:73]
	s_waitcnt vmcnt(1)
	ds_write_b128 v20, v[208:211] offset:32768
	v_mfma_f32_16x16x32_f16 v[104:107], v[78:81], v[144:147], v[104:107]
	s_waitcnt vmcnt(0)
	ds_write_b128 v17, v[212:215] offset:32768
	s_waitcnt lgkmcnt(4)
	v_mfma_f32_16x16x32_f16 v[22:25], v[78:81], v[154:157], v[22:25]
	ds_read_b128 v[78:81], v29 offset:20480
	v_mfma_f32_16x16x32_f16 v[74:77], v[128:131], v[144:147], v[74:77]
	v_mfma_f32_16x16x32_f16 v[34:37], v[128:131], v[154:157], v[34:37]
	ds_read_b128 v[128:131], v29 offset:22528
	s_waitcnt lgkmcnt(1)
	v_mfma_f32_16x16x32_f16 v[120:123], v[78:81], v[108:111], v[120:123]
	v_mfma_f32_16x16x32_f16 v[124:127], v[78:81], v[132:135], v[124:127]
	s_waitcnt lgkmcnt(0)
	v_mfma_f32_16x16x32_f16 v[62:65], v[128:131], v[108:111], v[62:65]
	v_mfma_f32_16x16x32_f16 v[38:41], v[128:131], v[132:135], v[38:41]
	v_mfma_f32_16x16x32_f16 v[136:139], v[78:81], v[144:147], v[136:139]
	v_mfma_f32_16x16x32_f16 v[66:69], v[78:81], v[154:157], v[66:69]
	global_load_dwordx4 v[78:81], v[0:1], off offset:1408
	global_load_dwordx4 v[108:111], v[2:3], off offset:1408
	global_load_dwordx4 v[158:161], v[4:5], off offset:1408
	global_load_dwordx4 v[162:165], v[8:9], off offset:1408
	global_load_dwordx4 v[132:135], v[6:7], off offset:1408
	global_load_dwordx4 v[166:169], v[10:11], off offset:1408
	global_load_dwordx4 v[188:191], v[12:13], off offset:1408
	global_load_dwordx4 v[192:195], v[14:15], off offset:1408
	s_waitcnt lgkmcnt(0)
	s_barrier
	v_mfma_f32_16x16x32_f16 v[50:53], v[128:131], v[144:147], v[50:53]
	ds_read_b128 v[112:115], v16
	v_mfma_f32_16x16x32_f16 v[58:61], v[128:131], v[154:157], v[58:61]
	ds_read_b128 v[116:119], v28 offset:32768
	s_waitcnt lgkmcnt(0)
	v_mfma_f32_16x16x32_f16 v[42:45], v[112:115], v[116:119], v[42:45]
	ds_read_b128 v[128:131], v16 offset:2048
	ds_read_b128 v[140:143], v28 offset:34816
	s_waitcnt lgkmcnt(0)
	v_mfma_f32_16x16x32_f16 v[46:49], v[112:115], v[140:143], v[46:49]
	ds_read_b128 v[144:147], v28 offset:36864
	v_mfma_f32_16x16x32_f16 v[54:57], v[128:131], v[116:119], v[54:57]
	ds_read_b128 v[154:157], v28 offset:38912
	v_mfma_f32_16x16x32_f16 v[70:73], v[128:131], v[140:143], v[70:73]
	s_waitcnt lgkmcnt(1)
	v_mfma_f32_16x16x32_f16 v[104:107], v[112:115], v[144:147], v[104:107]
	s_waitcnt lgkmcnt(0)
	v_mfma_f32_16x16x32_f16 v[22:25], v[112:115], v[154:157], v[22:25]
	ds_read_b128 v[112:115], v16 offset:4096
	v_mfma_f32_16x16x32_f16 v[74:77], v[128:131], v[144:147], v[74:77]
	v_mfma_f32_16x16x32_f16 v[34:37], v[128:131], v[154:157], v[34:37]
	ds_read_b128 v[128:131], v16 offset:6144
	s_waitcnt lgkmcnt(1)
	v_mfma_f32_16x16x32_f16 v[120:123], v[112:115], v[116:119], v[120:123]
	v_mfma_f32_16x16x32_f16 v[124:127], v[112:115], v[140:143], v[124:127]
	s_waitcnt lgkmcnt(0)
	v_mfma_f32_16x16x32_f16 v[62:65], v[128:131], v[116:119], v[62:65]
	ds_read_b128 v[116:119], v32 offset:32768
	v_mfma_f32_16x16x32_f16 v[38:41], v[128:131], v[140:143], v[38:41]
	ds_read_b128 v[140:143], v32 offset:34816
	s_waitcnt vmcnt(7)
	ds_write_b128 v18, v[78:81] offset:16384
	v_mfma_f32_16x16x32_f16 v[136:139], v[112:115], v[144:147], v[136:139]
	s_waitcnt vmcnt(6)
	ds_write_b128 v19, v[108:111] offset:16384
	s_waitcnt vmcnt(5)
	ds_write_b128 v20, v[158:161] offset:16384
	v_mfma_f32_16x16x32_f16 v[66:69], v[112:115], v[154:157], v[66:69]
	ds_read_b128 v[112:115], v29
	s_waitcnt vmcnt(4)
	ds_write_b128 v17, v[162:165] offset:16384
	v_mfma_f32_16x16x32_f16 v[50:53], v[128:131], v[144:147], v[50:53]
	ds_read_b128 v[144:147], v32 offset:36864
	v_mfma_f32_16x16x32_f16 v[58:61], v[128:131], v[154:157], v[58:61]
	ds_read_b128 v[128:131], v29 offset:2048
	s_waitcnt lgkmcnt(3)
	v_mfma_f32_16x16x32_f16 v[42:45], v[112:115], v[116:119], v[42:45]
	ds_read_b128 v[154:157], v32 offset:38912
	v_mfma_f32_16x16x32_f16 v[46:49], v[112:115], v[140:143], v[46:49]
	s_waitcnt vmcnt(3)
	ds_write_b128 v18, v[132:135] offset:49152
	s_waitcnt lgkmcnt(2)
	v_mfma_f32_16x16x32_f16 v[54:57], v[128:131], v[116:119], v[54:57]
	s_waitcnt vmcnt(2)
	ds_write_b128 v19, v[166:169] offset:49152
	v_mfma_f32_16x16x32_f16 v[70:73], v[128:131], v[140:143], v[70:73]
	s_waitcnt vmcnt(1)
	ds_write_b128 v20, v[188:191] offset:49152
	v_mfma_f32_16x16x32_f16 v[104:107], v[112:115], v[144:147], v[104:107]
	s_waitcnt vmcnt(0)
	ds_write_b128 v17, v[192:195] offset:49152
	s_waitcnt lgkmcnt(4)
	v_mfma_f32_16x16x32_f16 v[22:25], v[112:115], v[154:157], v[22:25]
	ds_read_b128 v[112:115], v29 offset:4096
	v_mfma_f32_16x16x32_f16 v[74:77], v[128:131], v[144:147], v[74:77]
	v_mfma_f32_16x16x32_f16 v[34:37], v[128:131], v[154:157], v[34:37]
	ds_read_b128 v[128:131], v29 offset:6144
	s_waitcnt lgkmcnt(1)
	v_mfma_f32_16x16x32_f16 v[120:123], v[112:115], v[116:119], v[120:123]
	v_mfma_f32_16x16x32_f16 v[124:127], v[112:115], v[140:143], v[124:127]
	s_waitcnt lgkmcnt(0)
	v_mfma_f32_16x16x32_f16 v[62:65], v[128:131], v[116:119], v[62:65]
	v_mfma_f32_16x16x32_f16 v[38:41], v[128:131], v[140:143], v[38:41]
	v_mfma_f32_16x16x32_f16 v[136:139], v[112:115], v[144:147], v[136:139]
	v_mfma_f32_16x16x32_f16 v[66:69], v[112:115], v[154:157], v[66:69]
	global_load_dwordx4 v[112:115], v[0:1], off offset:1536
	global_load_dwordx4 v[116:119], v[2:3], off offset:1536
	global_load_dwordx4 v[196:199], v[4:5], off offset:1536
	global_load_dwordx4 v[200:203], v[8:9], off offset:1536
	global_load_dwordx4 v[140:143], v[6:7], off offset:1536
	global_load_dwordx4 v[204:207], v[10:11], off offset:1536
	global_load_dwordx4 v[208:211], v[12:13], off offset:1536
	global_load_dwordx4 v[212:215], v[14:15], off offset:1536
	s_waitcnt lgkmcnt(0)
	s_barrier
; #define GL_LOAD(s_, kt_) if (VAR != 1) { a##s_##0 = GL_A(0, kt_); a##s_##1 = GL_A(1, kt_); a##s_##2 = GL_A(2, kt_); a##s_##3 = GL_A(3, kt_); b##s_##0 = GL_B(0, kt_); b##s_##1 = GL_B(1, kt_); b##s_##2 = GL_B(2, kt_); b##s_##3 = GL_B(3, kt_); }
; #define LDS_STORE(s_, buf_) if (VAR != 2) { LDS_ST1(sA, 0, buf_, a##s_##0) LDS_ST1(sA, 1, buf_, a##s_##1) LDS_ST1(sA, 2, buf_, a##s_##2) LDS_ST1(sA, 3, buf_, a##s_##3) LDS_ST1(sB, 0, buf_, b##s_##0) LDS_ST1(sB, 1, buf_, b##s_##1) LDS_ST1(sB, 2, buf_, b##s_##2) LDS_ST1(sB, 3, buf_, b##s_##3) }
;     ...
;   GL_LOAD(0, 0)
;   GL_LOAD(1, 1)
;   LDS_STORE(0, 0)
;   if (VAR != 4) __syncthreads();
; #pragma unroll
;   for (int kt = 0; kt < nk; kt += 2) {
;     if (kt + 2 < nk) { GL_LOAD(0, kt + 2) }
;     MMA_TILE(0)
;     LDS_STORE(1, 1)
;     if (VAR != 4) __syncthreads();
;     if (kt + 3 < nk) { GL_LOAD(1, kt + 3) }
;     MMA_TILE(1)
;     if (kt + 2 < nk) { LDS_STORE(0, 0) }
;     if (VAR != 4) __syncthreads();
	v_mfma_f32_16x16x32_f16 v[50:53], v[128:131], v[144:147], v[50:53]
	ds_read_b128 v[78:81], v16 offset:16384
	v_mfma_f32_16x16x32_f16 v[58:61], v[128:131], v[154:157], v[58:61]
	ds_read_b128 v[108:111], v28 offset:49152
	s_waitcnt lgkmcnt(0)
	v_mfma_f32_16x16x32_f16 v[42:45], v[78:81], v[108:111], v[42:45]
	ds_read_b128 v[128:131], v16 offset:18432
	ds_read_b128 v[132:135], v28 offset:51200
	s_waitcnt lgkmcnt(0)
	v_mfma_f32_16x16x32_f16 v[46:49], v[78:81], v[132:135], v[46:49]
	ds_read_b128 v[144:147], v28 offset:53248
	v_mfma_f32_16x16x32_f16 v[54:57], v[128:131], v[108:111], v[54:57]
	ds_read_b128 v[154:157], v28 offset:55296
	v_mfma_f32_16x16x32_f16 v[70:73], v[128:131], v[132:135], v[70:73]
	s_waitcnt lgkmcnt(1)
	v_mfma_f32_16x16x32_f16 v[104:107], v[78:81], v[144:147], v[104:107]
	s_waitcnt lgkmcnt(0)
	v_mfma_f32_16x16x32_f16 v[22:25], v[78:81], v[154:157], v[22:25]
	ds_read_b128 v[78:81], v16 offset:20480
	v_mfma_f32_16x16x32_f16 v[74:77], v[128:131], v[144:147], v[74:77]
	v_mfma_f32_16x16x32_f16 v[34:37], v[128:131], v[154:157], v[34:37]
	ds_read_b128 v[128:131], v16 offset:22528
	s_waitcnt lgkmcnt(1)
	v_mfma_f32_16x16x32_f16 v[120:123], v[78:81], v[108:111], v[120:123]
	v_mfma_f32_16x16x32_f16 v[124:127], v[78:81], v[132:135], v[124:127]
	s_waitcnt lgkmcnt(0)
	v_mfma_f32_16x16x32_f16 v[62:65], v[128:131], v[108:111], v[62:65]
	ds_read_b128 v[108:111], v32 offset:49152
	v_mfma_f32_16x16x32_f16 v[38:41], v[128:131], v[132:135], v[38:41]
	ds_read_b128 v[132:135], v32 offset:51200
	s_waitcnt vmcnt(7)
	ds_write_b128 v18, v[112:115]
	v_mfma_f32_16x16x32_f16 v[136:139], v[78:81], v[144:147], v[136:139]
	s_waitcnt vmcnt(6)
	ds_write_b128 v19, v[116:119]
	s_waitcnt vmcnt(5)
	ds_write_b128 v20, v[196:199]
	v_mfma_f32_16x16x32_f16 v[66:69], v[78:81], v[154:157], v[66:69]
	ds_read_b128 v[78:81], v29 offset:16384
	s_waitcnt vmcnt(4)
	ds_write_b128 v17, v[200:203]
	v_mfma_f32_16x16x32_f16 v[50:53], v[128:131], v[144:147], v[50:53]
	ds_read_b128 v[144:147], v32 offset:53248
	v_mfma_f32_16x16x32_f16 v[58:61], v[128:131], v[154:157], v[58:61]
	ds_read_b128 v[128:131], v29 offset:18432
	s_waitcnt lgkmcnt(3)
	v_mfma_f32_16x16x32_f16 v[42:45], v[78:81], v[108:111], v[42:45]
	ds_read_b128 v[154:157], v32 offset:55296
	v_mfma_f32_16x16x32_f16 v[46:49], v[78:81], v[132:135], v[46:49]
	s_waitcnt vmcnt(3)
	ds_write_b128 v18, v[140:143] offset:32768
	s_waitcnt lgkmcnt(2)
	v_mfma_f32_16x16x32_f16 v[54:57], v[128:131], v[108:111], v[54:57]
	s_waitcnt vmcnt(2)
	ds_write_b128 v19, v[204:207] offset:32768
	v_mfma_f32_16x16x32_f16 v[70:73], v[128:131], v[132:135], v[70:73]
	s_waitcnt vmcnt(1)
	ds_write_b128 v20, v[208:211] offset:32768
	v_mfma_f32_16x16x32_f16 v[104:107], v[78:81], v[144:147], v[104:107]
	s_waitcnt vmcnt(0)
	ds_write_b128 v17, v[212:215] offset:32768
	s_waitcnt lgkmcnt(4)
	v_mfma_f32_16x16x32_f16 v[22:25], v[78:81], v[154:157], v[22:25]
	ds_read_b128 v[78:81], v29 offset:20480
	v_mfma_f32_16x16x32_f16 v[74:77], v[128:131], v[144:147], v[74:77]
	v_mfma_f32_16x16x32_f16 v[34:37], v[128:131], v[154:157], v[34:37]
	ds_read_b128 v[128:131], v29 offset:22528
	s_waitcnt lgkmcnt(1)
	v_mfma_f32_16x16x32_f16 v[120:123], v[78:81], v[108:111], v[120:123]
	v_mfma_f32_16x16x32_f16 v[124:127], v[78:81], v[132:135], v[124:127]
	s_waitcnt lgkmcnt(0)
	v_mfma_f32_16x16x32_f16 v[62:65], v[128:131], v[108:111], v[62:65]
	v_mfma_f32_16x16x32_f16 v[38:41], v[128:131], v[132:135], v[38:41]
	v_mfma_f32_16x16x32_f16 v[136:139], v[78:81], v[144:147], v[136:139]
	v_mfma_f32_16x16x32_f16 v[66:69], v[78:81], v[154:157], v[66:69]
	global_load_dwordx4 v[78:81], v[0:1], off offset:1664
	global_load_dwordx4 v[108:111], v[2:3], off offset:1664
	global_load_dwordx4 v[158:161], v[4:5], off offset:1664
	global_load_dwordx4 v[162:165], v[8:9], off offset:1664
	global_load_dwordx4 v[132:135], v[6:7], off offset:1664
	global_load_dwordx4 v[166:169], v[10:11], off offset:1664
	global_load_dwordx4 v[188:191], v[12:13], off offset:1664
	global_load_dwordx4 v[192:195], v[14:15], off offset:1664
	s_waitcnt lgkmcnt(0)
	s_barrier
	v_mfma_f32_16x16x32_f16 v[50:53], v[128:131], v[144:147], v[50:53]
	ds_read_b128 v[112:115], v16
	v_mfma_f32_16x16x32_f16 v[58:61], v[128:131], v[154:157], v[58:61]
	ds_read_b128 v[116:119], v28 offset:32768
	s_waitcnt lgkmcnt(0)
	v_mfma_f32_16x16x32_f16 v[42:45], v[112:115], v[116:119], v[42:45]
	ds_read_b128 v[128:131], v16 offset:2048
	ds_read_b128 v[140:143], v28 offset:34816
	s_waitcnt lgkmcnt(0)
	v_mfma_f32_16x16x32_f16 v[46:49], v[112:115], v[140:143], v[46:49]
	ds_read_b128 v[144:147], v28 offset:36864
	v_mfma_f32_16x16x32_f16 v[54:57], v[128:131], v[116:119], v[54:57]
	ds_read_b128 v[154:157], v28 offset:38912
	v_mfma_f32_16x16x32_f16 v[70:73], v[128:131], v[140:143], v[70:73]
	s_waitcnt lgkmcnt(1)
	v_mfma_f32_16x16x32_f16 v[104:107], v[112:115], v[144:147], v[104:107]
	s_waitcnt lgkmcnt(0)
	v_mfma_f32_16x16x32_f16 v[22:25], v[112:115], v[154:157], v[22:25]
	ds_read_b128 v[112:115], v16 offset:4096
	v_mfma_f32_16x16x32_f16 v[74:77], v[128:131], v[144:147], v[74:77]
	v_mfma_f32_16x16x32_f16 v[34:37], v[128:131], v[154:157], v[34:37]
	ds_read_b128 v[128:131], v16 offset:6144
	s_waitcnt lgkmcnt(1)
	v_mfma_f32_16x16x32_f16 v[120:123], v[112:115], v[116:119], v[120:123]
	v_mfma_f32_16x16x32_f16 v[124:127], v[112:115], v[140:143], v[124:127]
	s_waitcnt lgkmcnt(0)
	v_mfma_f32_16x16x32_f16 v[62:65], v[128:131], v[116:119], v[62:65]
	ds_read_b128 v[116:119], v32 offset:32768
	v_mfma_f32_16x16x32_f16 v[38:41], v[128:131], v[140:143], v[38:41]
	ds_read_b128 v[140:143], v32 offset:34816
	s_waitcnt vmcnt(7)
; #define GL_LOAD(s_, kt_) if (VAR != 1) { a##s_##0 = GL_A(0, kt_); a##s_##1 = GL_A(1, kt_); a##s_##2 = GL_A(2, kt_); a##s_##3 = GL_A(3, kt_); b##s_##0 = GL_B(0, kt_); b##s_##1 = GL_B(1, kt_); b##s_##2 = GL_B(2, kt_); b##s_##3 = GL_B(3, kt_); }
; #define LDS_STORE(s_, buf_) if (VAR != 2) { LDS_ST1(sA, 0, buf_, a##s_##0) LDS_ST1(sA, 1, buf_, a##s_##1) LDS_ST1(sA, 2, buf_, a##s_##2) LDS_ST1(sA, 3, buf_, a##s_##3) LDS_ST1(sB, 0, buf_, b##s_##0) LDS_ST1(sB, 1, buf_, b##s_##1) LDS_ST1(sB, 2, buf_, b##s_##2) LDS_ST1(sB, 3, buf_, b##s_##3) }
;     ...
;   GL_LOAD(0, 0)
;   GL_LOAD(1, 1)
;   LDS_STORE(0, 0)
;   if (VAR != 4) __syncthreads();
; #pragma unroll
;   for (int kt = 0; kt < nk; kt += 2) {
;     if (kt + 2 < nk) { GL_LOAD(0, kt + 2) }
;     MMA_TILE(0)
;     LDS_STORE(1, 1)
;     if (VAR != 4) __syncthreads();
;     if (kt + 3 < nk) { GL_LOAD(1, kt + 3) }
;     MMA_TILE(1)
;     if (kt + 2 < nk) { LDS_STORE(0, 0) }
;     if (VAR != 4) __syncthreads();
	ds_write_b128 v18, v[78:81] offset:16384
	v_mfma_f32_16x16x32_f16 v[136:139], v[112:115], v[144:147], v[136:139]
	s_waitcnt vmcnt(6)
	ds_write_b128 v19, v[108:111] offset:16384
	s_waitcnt vmcnt(5)
	ds_write_b128 v20, v[158:161] offset:16384
	v_mfma_f32_16x16x32_f16 v[66:69], v[112:115], v[154:157], v[66:69]
	ds_read_b128 v[112:115], v29
	s_waitcnt vmcnt(4)
	ds_write_b128 v17, v[162:165] offset:16384
	v_mfma_f32_16x16x32_f16 v[50:53], v[128:131], v[144:147], v[50:53]
	ds_read_b128 v[144:147], v32 offset:36864
	v_mfma_f32_16x16x32_f16 v[58:61], v[128:131], v[154:157], v[58:61]
	ds_read_b128 v[128:131], v29 offset:2048
	s_waitcnt lgkmcnt(3)
	v_mfma_f32_16x16x32_f16 v[42:45], v[112:115], v[116:119], v[42:45]
	ds_read_b128 v[154:157], v32 offset:38912
	v_mfma_f32_16x16x32_f16 v[46:49], v[112:115], v[140:143], v[46:49]
	s_waitcnt vmcnt(3)
	ds_write_b128 v18, v[132:135] offset:49152
	s_waitcnt lgkmcnt(2)
	v_mfma_f32_16x16x32_f16 v[54:57], v[128:131], v[116:119], v[54:57]
	s_waitcnt vmcnt(2)
	ds_write_b128 v19, v[166:169] offset:49152
	v_mfma_f32_16x16x32_f16 v[70:73], v[128:131], v[140:143], v[70:73]
	s_waitcnt vmcnt(1)
	ds_write_b128 v20, v[188:191] offset:49152
	v_mfma_f32_16x16x32_f16 v[104:107], v[112:115], v[144:147], v[104:107]
	s_waitcnt vmcnt(0)
	ds_write_b128 v17, v[192:195] offset:49152
	s_waitcnt lgkmcnt(4)
	v_mfma_f32_16x16x32_f16 v[22:25], v[112:115], v[154:157], v[22:25]
	ds_read_b128 v[112:115], v29 offset:4096
	v_mfma_f32_16x16x32_f16 v[74:77], v[128:131], v[144:147], v[74:77]
	v_mfma_f32_16x16x32_f16 v[34:37], v[128:131], v[154:157], v[34:37]
	ds_read_b128 v[128:131], v29 offset:6144
	s_waitcnt lgkmcnt(1)
	v_mfma_f32_16x16x32_f16 v[120:123], v[112:115], v[116:119], v[120:123]
	v_mfma_f32_16x16x32_f16 v[124:127], v[112:115], v[140:143], v[124:127]
	s_waitcnt lgkmcnt(0)
	v_mfma_f32_16x16x32_f16 v[62:65], v[128:131], v[116:119], v[62:65]
	v_mfma_f32_16x16x32_f16 v[38:41], v[128:131], v[140:143], v[38:41]
	v_mfma_f32_16x16x32_f16 v[136:139], v[112:115], v[144:147], v[136:139]
	v_mfma_f32_16x16x32_f16 v[66:69], v[112:115], v[154:157], v[66:69]
	global_load_dwordx4 v[112:115], v[0:1], off offset:1792
	global_load_dwordx4 v[116:119], v[2:3], off offset:1792
	global_load_dwordx4 v[196:199], v[4:5], off offset:1792
	global_load_dwordx4 v[200:203], v[8:9], off offset:1792
	global_load_dwordx4 v[140:143], v[6:7], off offset:1792
	global_load_dwordx4 v[204:207], v[10:11], off offset:1792
	global_load_dwordx4 v[208:211], v[12:13], off offset:1792
	global_load_dwordx4 v[212:215], v[14:15], off offset:1792
	s_waitcnt lgkmcnt(0)
	s_barrier
	v_mfma_f32_16x16x32_f16 v[50:53], v[128:131], v[144:147], v[50:53]
	ds_read_b128 v[78:81], v16 offset:16384
	v_mfma_f32_16x16x32_f16 v[58:61], v[128:131], v[154:157], v[58:61]
	ds_read_b128 v[108:111], v28 offset:49152
	s_waitcnt lgkmcnt(0)
	v_mfma_f32_16x16x32_f16 v[42:45], v[78:81], v[108:111], v[42:45]
	ds_read_b128 v[128:131], v16 offset:18432
	ds_read_b128 v[132:135], v28 offset:51200
	s_waitcnt lgkmcnt(0)
	v_mfma_f32_16x16x32_f16 v[46:49], v[78:81], v[132:135], v[46:49]
	ds_read_b128 v[144:147], v28 offset:53248
	v_mfma_f32_16x16x32_f16 v[54:57], v[128:131], v[108:111], v[54:57]
	ds_read_b128 v[154:157], v28 offset:55296
	v_mfma_f32_16x16x32_f16 v[70:73], v[128:131], v[132:135], v[70:73]
	s_waitcnt lgkmcnt(1)
	v_mfma_f32_16x16x32_f16 v[104:107], v[78:81], v[144:147], v[104:107]
	s_waitcnt lgkmcnt(0)
	v_mfma_f32_16x16x32_f16 v[22:25], v[78:81], v[154:157], v[22:25]
	ds_read_b128 v[78:81], v16 offset:20480
	v_mfma_f32_16x16x32_f16 v[74:77], v[128:131], v[144:147], v[74:77]
	v_mfma_f32_16x16x32_f16 v[34:37], v[128:131], v[154:157], v[34:37]
	ds_read_b128 v[128:131], v16 offset:22528
	s_waitcnt lgkmcnt(1)
	v_mfma_f32_16x16x32_f16 v[120:123], v[78:81], v[108:111], v[120:123]
	v_mfma_f32_16x16x32_f16 v[124:127], v[78:81], v[132:135], v[124:127]
	s_waitcnt lgkmcnt(0)
	v_mfma_f32_16x16x32_f16 v[62:65], v[128:131], v[108:111], v[62:65]
	ds_read_b128 v[108:111], v32 offset:49152
	v_mfma_f32_16x16x32_f16 v[38:41], v[128:131], v[132:135], v[38:41]
	ds_read_b128 v[132:135], v32 offset:51200
	s_waitcnt vmcnt(7)
	ds_write_b128 v18, v[112:115]
	v_mfma_f32_16x16x32_f16 v[136:139], v[78:81], v[144:147], v[136:139]
	s_waitcnt vmcnt(6)
	ds_write_b128 v19, v[116:119]
	s_waitcnt vmcnt(5)
	ds_write_b128 v20, v[196:199]
	v_mfma_f32_16x16x32_f16 v[66:69], v[78:81], v[154:157], v[66:69]
	ds_read_b128 v[78:81], v29 offset:16384
	s_waitcnt vmcnt(4)
	ds_write_b128 v17, v[200:203]
	v_mfma_f32_16x16x32_f16 v[50:53], v[128:131], v[144:147], v[50:53]
	ds_read_b128 v[144:147], v32 offset:53248
	v_mfma_f32_16x16x32_f16 v[58:61], v[128:131], v[154:157], v[58:61]
	ds_read_b128 v[128:131], v29 offset:18432
	s_waitcnt lgkmcnt(3)
	v_mfma_f32_16x16x32_f16 v[42:45], v[78:81], v[108:111], v[42:45]
	ds_read_b128 v[154:157], v32 offset:55296
	v_mfma_f32_16x16x32_f16 v[46:49], v[78:81], v[132:135], v[46:49]
	s_waitcnt vmcnt(3)
	ds_write_b128 v18, v[140:143] offset:32768
	s_waitcnt lgkmcnt(2)
	v_mfma_f32_16x16x32_f16 v[54:57], v[128:131], v[108:111], v[54:57]
	s_waitcnt vmcnt(2)
	ds_write_b128 v19, v[204:207] offset:32768
	v_mfma_f32_16x16x32_f16 v[70:73], v[128:131], v[132:135], v[70:73]
	s_waitcnt vmcnt(1)
	ds_write_b128 v20, v[208:211] offset:32768
	v_mfma_f32_16x16x32_f16 v[104:107], v[78:81], v[144:147], v[104:107]
	s_waitcnt vmcnt(0)
	ds_write_b128 v17, v[212:215] offset:32768
	s_waitcnt lgkmcnt(4)
	v_mfma_f32_16x16x32_f16 v[22:25], v[78:81], v[154:157], v[22:25]
	ds_read_b128 v[78:81], v29 offset:20480
	v_mfma_f32_16x16x32_f16 v[74:77], v[128:131], v[144:147], v[74:77]
	v_mfma_f32_16x16x32_f16 v[34:37], v[128:131], v[154:157], v[34:37]
	ds_read_b128 v[128:131], v29 offset:22528
	s_waitcnt lgkmcnt(1)
	v_mfma_f32_16x16x32_f16 v[120:123], v[78:81], v[108:111], v[120:123]
	v_mfma_f32_16x16x32_f16 v[124:127], v[78:81], v[132:135], v[124:127]
	s_waitcnt lgkmcnt(0)
	v_mfma_f32_16x16x32_f16 v[62:65], v[128:131], v[108:111], v[62:65]
	v_mfma_f32_16x16x32_f16 v[38:41], v[128:131], v[132:135], v[38:41]
	v_mfma_f32_16x16x32_f16 v[136:139], v[78:81], v[144:147], v[136:139]
	v_mfma_f32_16x16x32_f16 v[66:69], v[78:81], v[154:157], v[66:69]
	global_load_dwordx4 v[80:83], v[0:1], off offset:1920
	global_load_dwordx4 v[108:111], v[2:3], off offset:1920
	global_load_dwordx4 v[158:161], v[4:5], off offset:1920
	global_load_dwordx4 v[162:165], v[8:9], off offset:1920
	global_load_dwordx4 v[132:135], v[6:7], off offset:1920
	global_load_dwordx4 v[166:169], v[10:11], off offset:1920
	global_load_dwordx4 v[188:191], v[12:13], off offset:1920
	global_load_dwordx4 v[12:15], v[14:15], off offset:1920
	s_waitcnt lgkmcnt(0)
	s_barrier
; DI unsigned pack2(float lo, float hi) { f2_t v = {lo, hi}; h2_t b = __builtin_convertvector(v, h2_t); return __builtin_bit_cast(unsigned, b); }
; #define GL_LOAD(s_, kt_) if (VAR != 1) { a##s_##0 = GL_A(0, kt_); a##s_##1 = GL_A(1, kt_); a##s_##2 = GL_A(2, kt_); a##s_##3 = GL_A(3, kt_); b##s_##0 = GL_B(0, kt_); b##s_##1 = GL_B(1, kt_); b##s_##2 = GL_B(2, kt_); b##s_##3 = GL_B(3, kt_); }
; #define LDS_STORE(s_, buf_) if (VAR != 2) { LDS_ST1(sA, 0, buf_, a##s_##0) LDS_ST1(sA, 1, buf_, a##s_##1) LDS_ST1(sA, 2, buf_, a##s_##2) LDS_ST1(sA, 3, buf_, a##s_##3) LDS_ST1(sB, 0, buf_, b##s_##0) LDS_ST1(sB, 1, buf_, b##s_##1) LDS_ST1(sB, 2, buf_, b##s_##2) LDS_ST1(sB, 3, buf_, b##s_##3) }
;     ...
;   GL_LOAD(0, 0)
;   GL_LOAD(1, 1)
;   LDS_STORE(0, 0)
;   if (VAR != 4) __syncthreads();
; #pragma unroll
;   for (int kt = 0; kt < nk; kt += 2) {
;     if (kt + 2 < nk) { GL_LOAD(0, kt + 2) }
;     MMA_TILE(0)
;     LDS_STORE(1, 1)
;     if (VAR != 4) __syncthreads();
;     if (kt + 3 < nk) { GL_LOAD(1, kt + 3) }
;     MMA_TILE(1)
;     if (kt + 2 < nk) { LDS_STORE(0, 0) }
;     if (VAR != 4) __syncthreads();
; DI void phase_proj(const Params& P, int l, char* smem) {
;     ...
; #pragma unroll
;       for (int mt = 0; mt < 4; ++mt) {
;         float r4[4];
; #pragma unroll
;         for (int j = 0; j < 4; ++j) r4[j] = __shfl(rs[mt], 4 * g + j);
; #pragma unroll
;         for (int nt = 0; nt < 4; ++nt) {
;           const int c = c0 + nt * 16 + lr;
;           bf16_t* dst = VT + ((size_t)(br * NB + b) * 512 + c) * SEQ + s0 + mt * 16 + 4 * g;
;           *(uint2*)dst = make_uint2(pack2(acc[mt][nt][0] * r4[0], acc[mt][nt][1] * r4[1]), pack2(acc[mt][nt][2] * r4[2], acc[mt][nt][3] * r4[3]));
;         }
;       }
	ds_read_b128 v[0:3], v16
	v_mfma_f32_16x16x32_f16 v[50:53], v[128:131], v[144:147], v[50:53]
	v_mfma_f32_16x16x32_f16 v[112:115], v[128:131], v[154:157], v[58:61]
	ds_read_b128 v[116:119], v28 offset:32768
	ds_read_b128 v[4:7], v16 offset:2048
	ds_read_b128 v[128:131], v28 offset:34816
	s_waitcnt lgkmcnt(2)
	v_mfma_f32_16x16x32_f16 v[140:143], v[0:3], v[116:119], v[42:45]
	s_waitcnt lgkmcnt(0)
	v_mfma_f32_16x16x32_f16 v[144:147], v[0:3], v[128:131], v[46:49]
	s_nop 0
	ds_read_b128 v[42:45], v28 offset:36864
	s_nop 0
	ds_read_b128 v[46:49], v28 offset:38912
	s_waitcnt lgkmcnt(0)
	v_mfma_f32_16x16x32_f16 v[154:157], v[0:3], v[46:49], v[22:25]
	v_mfma_f32_16x16x32_f16 v[204:207], v[4:7], v[46:49], v[34:37]
	s_nop 1
	ds_read_b128 v[22:25], v16 offset:4096
	ds_read_b128 v[34:37], v16 offset:6144
	ds_read_b128 v[208:211], v29
	ds_read_b128 v[212:215], v29 offset:2048
	v_mfma_f32_16x16x32_f16 v[104:107], v[0:3], v[42:45], v[104:107]
	v_mfma_f32_16x16x32_f16 v[192:195], v[4:7], v[116:119], v[54:57]
	v_mfma_f32_16x16x32_f16 v[200:203], v[4:7], v[42:45], v[74:77]
	s_nop 2
	ds_read_b128 v[76:79], v32 offset:32768
	ds_read_b128 v[56:59], v32 offset:34816
	ds_read_b128 v[220:223], v29 offset:4096
	ds_read_b128 v[0:3], v29 offset:6144
	v_mfma_f32_16x16x32_f16 v[196:199], v[4:7], v[128:131], v[70:73]
	ds_read_b128 v[8:11], v32 offset:36864
	ds_read_b128 v[4:7], v32 offset:38912
	s_waitcnt vmcnt(7)
	ds_write_b128 v18, v[80:83] offset:16384
	s_waitcnt lgkmcnt(10)
	v_mfma_f32_16x16x32_f16 v[120:123], v[22:25], v[116:119], v[120:123]
	s_waitcnt vmcnt(6)
	ds_write_b128 v19, v[108:111] offset:16384
	s_waitcnt vmcnt(5)
	ds_write_b128 v20, v[158:161] offset:16384
	s_waitcnt vmcnt(4)
	ds_write_b128 v17, v[162:165] offset:16384
	s_waitcnt vmcnt(3)
	ds_write_b128 v18, v[132:135] offset:49152
	s_waitcnt vmcnt(2)
	ds_write_b128 v19, v[166:169] offset:49152
	s_waitcnt vmcnt(1)
	ds_write_b128 v20, v[188:191] offset:49152
	v_mfma_f32_16x16x32_f16 v[136:139], v[22:25], v[42:45], v[136:139]
	s_waitcnt vmcnt(0)
	ds_write_b128 v17, v[12:15] offset:49152
	s_waitcnt lgkmcnt(0)
	s_barrier
	v_mfma_f32_16x16x32_f16 v[224:227], v[22:25], v[46:49], v[66:69]
	v_and_or_b32 v188, v94, s1, v97
	v_ashrrev_i32_e32 v94, 7, v94
	v_mfma_f32_16x16x32_f16 v[108:111], v[34:37], v[116:119], v[62:65]
	ds_read_b128 v[116:119], v16 offset:16384
	ds_read_b128 v[80:83], v16 offset:18432
	v_and_b32_e32 v94, -4, v94
	v_add_u32_e32 v94, v94, v95
	v_mfma_f32_16x16x32_f16 v[72:75], v[34:37], v[128:131], v[38:41]
	v_ashrrev_i32_e32 v95, 31, v94
	v_lshlrev_b64 v[170:171], 21, v[94:95]
	v_lshl_add_u64 v[94:95], v[92:93], 0, v[150:151]
	v_mfma_f32_16x16x32_f16 v[40:43], v[34:37], v[42:45], v[50:53]
	v_lshlrev_b32_e32 v150, 2, v103
	v_lshl_or_b32 v170, v188, 12, v170
	ds_bpermute_b32 v188, v150, v98
	v_mfma_f32_16x16x32_f16 v[44:47], v[34:37], v[46:49], v[112:115]
	ds_bpermute_b32 v189, v150, v98 offset:4
	ds_bpermute_b32 v190, v150, v98 offset:8
	v_mfma_f32_16x16x32_f16 v[112:115], v[208:211], v[76:79], v[140:143]
	v_mfma_f32_16x16x32_f16 v[124:127], v[22:25], v[128:131], v[124:127]
	ds_read_b128 v[36:39], v28 offset:49152
	ds_read_b128 v[24:27], v28 offset:51200
	ds_read_b128 v[64:67], v16 offset:20480
	ds_read_b128 v[12:15], v16 offset:22528
	ds_read_b128 v[20:23], v28 offset:53248
	ds_read_b128 v[16:19], v28 offset:55296
	ds_read_b128 v[128:131], v29 offset:16384
	ds_read_b128 v[132:135], v29 offset:18432
	ds_read_b128 v[60:63], v32 offset:49152
	ds_read_b128 v[52:55], v32 offset:51200
	ds_read_b128 v[68:71], v29 offset:20480
	ds_read_b128 v[28:31], v29 offset:22528
	s_waitcnt lgkmcnt(11)
	v_mfma_f32_16x16x32_f16 v[112:115], v[116:119], v[36:39], v[112:115]
	ds_read_b128 v[48:51], v32 offset:53248
	ds_read_b128 v[32:35], v32 offset:55296
	s_waitcnt lgkmcnt(0)
	s_barrier
	v_mfma_f32_16x16x32_f16 v[140:143], v[208:211], v[56:59], v[144:147]
	v_mfma_f32_16x16x32_f16 v[144:147], v[208:211], v[4:7], v[154:157]
	v_mfma_f32_16x16x32_f16 v[154:157], v[212:215], v[76:79], v[192:195]
	s_nop 2
	v_or_b32_e32 v194, 12, v150
	ds_bpermute_b32 v191, v194, v98
	v_mfma_f32_16x16x32_f16 v[112:115], v[128:131], v[60:63], v[112:115]
	v_lshl_add_u64 v[98:99], v[170:171], 1, v[94:95]
	v_mfma_f32_16x16x32_f16 v[104:107], v[208:211], v[8:11], v[104:107]
	v_mfma_f32_16x16x32_f16 v[104:107], v[116:119], v[20:23], v[104:107]
	s_nop 4
	v_mul_f32_e64 v112, v112, v188
	v_mul_f32_e64 v113, v113, v189
	s_waitcnt lgkmcnt(0)
	v_pk_mul_f32 v[114:115], v[114:115], v[190:191]
	v_cvt_pk_f16_f32 v112, v112, v113
	v_cvt_pk_f16_f32 v113, v114, v115
	global_store_dwordx2 v[98:99], v[112:113], off
	v_mfma_f32_16x16x32_f16 v[112:115], v[116:119], v[24:27], v[140:143]
	v_mfma_f32_16x16x32_f16 v[112:115], v[128:131], v[52:55], v[112:115]
	s_nop 1
	v_or_b32_e32 v140, 0x10000, v170
	v_mov_b32_e32 v141, v171
	v_lshlrev_b64 v[140:141], 1, v[140:141]
	v_mfma_f32_16x16x32_f16 v[104:107], v[128:131], v[48:51], v[104:107]
	v_lshl_add_u64 v[142:143], v[94:95], 0, v[140:141]
	s_nop 0
	v_pk_mul_f32 v[112:113], v[112:113], v[188:189]
	v_pk_mul_f32 v[114:115], v[114:115], v[190:191]
	v_cvt_pk_f16_f32 v112, v112, v113
	v_cvt_pk_f16_f32 v113, v114, v115
	global_store_dwordx2 v[142:143], v[112:113], off
	v_or_b32_e32 v112, 0x20000, v170
	v_mov_b32_e32 v113, v171
	v_lshlrev_b64 v[142:143], 1, v[112:113]
	v_pk_mul_f32 v[104:105], v[104:105], v[188:189]
	v_pk_mul_f32 v[106:107], v[106:107], v[190:191]
	v_lshl_add_u64 v[192:193], v[94:95], 0, v[142:143]
	v_cvt_pk_f16_f32 v104, v104, v105
	v_cvt_pk_f16_f32 v105, v106, v107
	global_store_dwordx2 v[192:193], v[104:105], off
	v_mfma_f32_16x16x32_f16 v[104:107], v[116:119], v[16:19], v[144:147]
	v_or_b32_e32 v170, 0x30000, v170
	v_lshlrev_b64 v[116:117], 1, v[170:171]
	v_lshl_add_u64 v[118:119], v[94:95], 0, v[116:117]
	v_mfma_f32_16x16x32_f16 v[104:107], v[128:131], v[32:35], v[104:107]
	ds_bpermute_b32 v128, v150, v96 offset:8
	ds_bpermute_b32 v129, v194, v96
	v_lshl_add_u64 v[130:131], v[94:95], 0, 32
	v_mfma_f32_16x16x32_f16 v[158:161], v[212:215], v[56:59], v[196:199]
	v_lshl_add_u64 v[144:145], v[130:131], 0, v[140:141]
	s_nop 2
	v_pk_mul_f32 v[104:105], v[104:105], v[188:189]
	v_pk_mul_f32 v[106:107], v[106:107], v[190:191]
	v_cvt_pk_f16_f32 v104, v104, v105
	v_cvt_pk_f16_f32 v105, v106, v107
	global_store_dwordx2 v[118:119], v[104:105], off
	v_mfma_f32_16x16x32_f16 v[104:107], v[80:83], v[36:39], v[154:157]
	ds_bpermute_b32 v118, v150, v96
	ds_bpermute_b32 v119, v150, v96 offset:4
	v_mfma_f32_16x16x32_f16 v[104:107], v[132:135], v[60:63], v[104:107]
	v_mfma_f32_16x16x32_f16 v[120:123], v[220:223], v[76:79], v[120:123]
	v_mfma_f32_16x16x32_f16 v[76:79], v[0:3], v[76:79], v[108:111]
	s_waitcnt lgkmcnt(0)
; DI unsigned pack2(float lo, float hi) { f2_t v = {lo, hi}; h2_t b = __builtin_convertvector(v, h2_t); return __builtin_bit_cast(unsigned, b); }
; DI void phase_proj(const Params& P, int l, char* smem) {
;     ...
; #pragma unroll
;       for (int mt = 0; mt < 4; ++mt) {
;         float r4[4];
; #pragma unroll
;         for (int j = 0; j < 4; ++j) r4[j] = __shfl(rs[mt], 4 * g + j);
; #pragma unroll
;         for (int nt = 0; nt < 4; ++nt) {
;           const int c = c0 + nt * 16 + lr;
;           bf16_t* dst = VT + ((size_t)(br * NB + b) * 512 + c) * SEQ + s0 + mt * 16 + 4 * g;
;           *(uint2*)dst = make_uint2(pack2(acc[mt][nt][0] * r4[0], acc[mt][nt][1] * r4[1]), pack2(acc[mt][nt][2] * r4[2], acc[mt][nt][3] * r4[3]));
;         }
;       }
	s_nop 4
	v_pk_mul_f32 v[104:105], v[104:105], v[118:119]
	v_pk_mul_f32 v[106:107], v[106:107], v[128:129]
	v_cvt_pk_f16_f32 v104, v104, v105
	v_mfma_f32_16x16x32_f16 v[108:111], v[80:83], v[24:27], v[158:161]
	v_cvt_pk_f16_f32 v105, v106, v107
	global_store_dwordx2 v[98:99], v[104:105], off offset:32
	v_mfma_f32_16x16x32_f16 v[162:165], v[212:215], v[8:11], v[200:203]
	v_mfma_f32_16x16x32_f16 v[166:169], v[212:215], v[4:7], v[204:207]
	v_mfma_f32_16x16x32_f16 v[104:107], v[132:135], v[52:55], v[108:111]
	v_mfma_f32_16x16x32_f16 v[108:111], v[80:83], v[20:23], v[162:165]
	v_mfma_f32_16x16x32_f16 v[80:83], v[80:83], v[16:19], v[166:169]
	s_nop 5
	v_mul_f32_e64 v104, v104, v118
	v_mul_f32_e64 v105, v105, v119
	v_pk_mul_f32 v[106:107], v[106:107], v[128:129]
	v_cvt_pk_f16_f32 v104, v104, v105
	v_cvt_pk_f16_f32 v105, v106, v107
	v_mfma_f32_16x16x32_f16 v[80:83], v[132:135], v[32:35], v[80:83]
	global_store_dwordx2 v[144:145], v[104:105], off
	v_mfma_f32_16x16x32_f16 v[104:107], v[132:135], v[48:51], v[108:111]
	v_mfma_f32_16x16x32_f16 v[124:127], v[220:223], v[56:59], v[124:127]
	s_nop 4
	v_mul_f32_e64 v80, v80, v118
	v_mul_f32_e64 v81, v81, v119
	v_pk_mul_f32 v[104:105], v[104:105], v[118:119]
	v_pk_mul_f32 v[106:107], v[106:107], v[128:129]
	v_mfma_f32_16x16x32_f16 v[56:59], v[0:3], v[56:59], v[72:75]
	v_cvt_pk_f16_f32 v80, v80, v81
	v_lshl_add_u64 v[108:109], v[130:131], 0, v[142:143]
	v_cvt_pk_f16_f32 v104, v104, v105
	v_pk_mul_f32 v[72:73], v[82:83], v[128:129]
	v_cvt_pk_f16_f32 v105, v106, v107
	v_cvt_pk_f16_f32 v81, v72, v73
	v_mfma_f32_16x16x32_f16 v[72:75], v[64:67], v[36:39], v[120:123]
	global_store_dwordx2 v[108:109], v[104:105], off
	v_lshl_add_u64 v[104:105], v[130:131], 0, v[116:117]
	global_store_dwordx2 v[104:105], v[80:81], off
	ds_bpermute_b32 v104, v150, v102
	ds_bpermute_b32 v105, v150, v102 offset:4
	ds_bpermute_b32 v106, v150, v102 offset:8
	v_mfma_f32_16x16x32_f16 v[72:75], v[68:71], v[60:63], v[72:75]
	ds_bpermute_b32 v107, v194, v102
	v_lshl_add_u64 v[102:103], v[94:95], 0, 64
	v_mfma_f32_16x16x32_f16 v[80:83], v[64:67], v[24:27], v[124:127]
	v_mfma_f32_16x16x32_f16 v[136:139], v[220:223], v[8:11], v[136:139]
	s_waitcnt lgkmcnt(2)
	s_nop 2
	v_pk_mul_f32 v[72:73], v[72:73], v[104:105]
	s_nop 0
	v_cvt_pk_f16_f32 v108, v72, v73
	v_mfma_f32_16x16x32_f16 v[112:115], v[220:223], v[4:7], v[224:227]
	s_waitcnt lgkmcnt(0)
	v_pk_mul_f32 v[72:73], v[74:75], v[106:107]
	s_nop 0
	v_cvt_pk_f16_f32 v109, v72, v73
	v_mfma_f32_16x16x32_f16 v[72:75], v[68:71], v[52:55], v[80:83]
	global_store_dwordx2 v[98:99], v[108:109], off offset:64
	v_lshl_add_u64 v[108:109], v[102:103], 0, v[140:141]
	v_mfma_f32_16x16x32_f16 v[80:83], v[64:67], v[20:23], v[136:139]
	v_mfma_f32_16x16x32_f16 v[64:67], v[64:67], v[16:19], v[112:115]
	s_nop 3
	v_mul_f32_e64 v72, v72, v104
	v_mul_f32_e64 v73, v73, v105
	v_cvt_pk_f16_f32 v110, v72, v73
	v_pk_mul_f32 v[72:73], v[74:75], v[106:107]
	v_mfma_f32_16x16x32_f16 v[64:67], v[68:71], v[32:35], v[64:67]
	v_cvt_pk_f16_f32 v111, v72, v73
	global_store_dwordx2 v[108:109], v[110:111], off
	v_mfma_f32_16x16x32_f16 v[72:75], v[68:71], v[48:51], v[80:83]
	v_lshl_add_u64 v[68:69], v[102:103], 0, v[116:117]
	s_nop 3
	v_pk_mul_f32 v[64:65], v[64:65], v[104:105]
	v_mfma_f32_16x16x32_f16 v[8:11], v[0:3], v[8:11], v[40:43]
	v_lshl_add_u64 v[80:81], v[102:103], 0, v[142:143]
	v_pk_mul_f32 v[72:73], v[72:73], v[104:105]
	v_pk_mul_f32 v[74:75], v[74:75], v[106:107]
	v_mfma_f32_16x16x32_f16 v[0:3], v[0:3], v[4:7], v[44:47]
	v_mul_f32_e64 v42, v66, v106
	v_mul_f32_e64 v43, v67, v107
	v_cvt_pk_f16_f32 v72, v72, v73
	v_cvt_pk_f16_f32 v73, v74, v75
	v_mfma_f32_16x16x32_f16 v[4:7], v[12:15], v[36:39], v[76:79]
	v_cvt_pk_f16_f32 v40, v64, v65
	v_cvt_pk_f16_f32 v41, v42, v43
	global_store_dwordx2 v[80:81], v[72:73], off
	global_store_dwordx2 v[68:69], v[40:41], off
	ds_bpermute_b32 v40, v150, v100
	ds_bpermute_b32 v41, v150, v100 offset:4
	ds_bpermute_b32 v36, v150, v100 offset:8
	ds_bpermute_b32 v37, v194, v100
	v_mfma_f32_16x16x32_f16 v[4:7], v[28:31], v[60:63], v[4:7]
	v_lshl_add_u64 v[38:39], v[94:95], 0, s[4:5]
	v_mfma_f32_16x16x32_f16 v[0:3], v[12:15], v[16:19], v[0:3]
	v_mfma_f32_16x16x32_f16 v[0:3], v[28:31], v[32:35], v[0:3]
	s_waitcnt lgkmcnt(2)
	s_nop 3
	v_pk_mul_f32 v[4:5], v[4:5], v[40:41]
	s_waitcnt lgkmcnt(0)
	v_pk_mul_f32 v[44:45], v[6:7], v[36:37]
	v_cvt_pk_f16_f32 v42, v4, v5
	v_mfma_f32_16x16x32_f16 v[4:7], v[12:15], v[24:27], v[56:59]
	v_cvt_pk_f16_f32 v43, v44, v45
	global_store_dwordx2 v[98:99], v[42:43], off offset:96
	v_lshl_add_u64 v[24:25], v[38:39], 0, v[140:141]
	v_mfma_f32_16x16x32_f16 v[4:7], v[28:31], v[52:55], v[4:7]
	v_mul_f32_e64 v0, v0, v40
	v_mul_f32_e64 v1, v1, v41
	v_pk_mul_f32 v[2:3], v[2:3], v[36:37]
	v_cvt_pk_f16_f32 v0, v0, v1
	v_cvt_pk_f16_f32 v1, v2, v3
	s_nop 2
	v_pk_mul_f32 v[4:5], v[4:5], v[40:41]
	v_pk_mul_f32 v[42:43], v[6:7], v[36:37]
	v_cvt_pk_f16_f32 v26, v4, v5
	v_mfma_f32_16x16x32_f16 v[4:7], v[12:15], v[20:23], v[8:11]
	v_cvt_pk_f16_f32 v27, v42, v43
	global_store_dwordx2 v[24:25], v[26:27], off
	v_mfma_f32_16x16x32_f16 v[4:7], v[28:31], v[48:51], v[4:7]
	v_lshl_add_u64 v[8:9], v[38:39], 0, v[142:143]
	s_nop 6
	v_pk_mul_f32 v[4:5], v[4:5], v[40:41]
	v_pk_mul_f32 v[6:7], v[6:7], v[36:37]
	v_cvt_pk_f16_f32 v4, v4, v5
	v_cvt_pk_f16_f32 v5, v6, v7
	global_store_dwordx2 v[8:9], v[4:5], off
	v_lshl_add_u64 v[4:5], v[38:39], 0, v[116:117]
	global_store_dwordx2 v[4:5], v[0:1], off
	s_branch .LBB0_636

; #define GL_LOAD(s_, kt_) if (VAR != 1) { a##s_##0 = GL_A(0, kt_); a##s_##1 = GL_A(1, kt_); a##s_##2 = GL_A(2, kt_); a##s_##3 = GL_A(3, kt_); b##s_##0 = GL_B(0, kt_); b##s_##1 = GL_B(1, kt_); b##s_##2 = GL_B(2, kt_); b##s_##3 = GL_B(3, kt_); }
; #define LDS_STORE(s_, buf_) if (VAR != 2) { LDS_ST1(sA, 0, buf_, a##s_##0) LDS_ST1(sA, 1, buf_, a##s_##1) LDS_ST1(sA, 2, buf_, a##s_##2) LDS_ST1(sA, 3, buf_, a##s_##3) LDS_ST1(sB, 0, buf_, b##s_##0) LDS_ST1(sB, 1, buf_, b##s_##1) LDS_ST1(sB, 2, buf_, b##s_##2) LDS_ST1(sB, 3, buf_, b##s_##3) }
;     ...
;   GL_LOAD(0, 0)
;   GL_LOAD(1, 1)
;   LDS_STORE(0, 0)
;   if (VAR != 4) __syncthreads();
; #pragma unroll
;   for (int kt = 0; kt < nk; kt += 2) {
;     if (kt + 2 < nk) { GL_LOAD(0, kt + 2) }
;     MMA_TILE(0)
;     LDS_STORE(1, 1)
;     if (VAR != 4) __syncthreads();
;     if (kt + 3 < nk) { GL_LOAD(1, kt + 3) }
;     MMA_TILE(1)
;     if (kt + 2 < nk) { LDS_STORE(0, 0) }
;     if (VAR != 4) __syncthreads();
; DI void phase_merge(const Params& P, int l, char* smem) {
;     ...
;     for (int br = 0; br < 3; ++br) {
;       f32x4 acc[4][4]; zero_acc(acc);
;       const int ycol = br == 0 ? C_AQ : (br == 1 ? C_BQ : C_CQ);
;       const bf16_t* Wb = W + (br == 0 ? WO_BRA : (br == 1 ? WO_BRB : WO_BRC));
;       gemm_kloop<false, true, 8>(acc, Pb + (size_t)m0 * PW + ycol, PW, Wb + (size_t)n0 * 512, 512, smem);
.LBB0_1161:
	s_cmp_lg_u32 s4, 0
	s_cselect_b64 s[6:7], -1, 0
	s_cmpk_eq_i32 s4, 0x800
	s_mov_b32 s8, 0x860000
	s_cselect_b32 s17, 0x400, s36
	s_cselect_b32 s20, s8, 0x8e0000
	s_cmp_eq_u32 s4, 0
	s_cselect_b64 s[8:9], -1, 0
	s_and_b64 s[18:19], s[8:9], exec
	s_cselect_b32 s17, 0, s17
	s_cselect_b32 s20, 0x7e0000, s20
	s_lshl_b32 s17, s17, 1
	s_add_u32 s18, s13, s17
	s_addc_u32 s19, s14, 0
	v_mov_b32_e32 v56, v148
	v_mov_b64_e32 v[6:7], s[18:19]
	v_ashrrev_i32_e32 v16, 3, v56
	v_lshlrev_b32_e32 v57, 4, v56
	v_mad_i64_i32 v[0:1], s[18:19], v16, s0, v[6:7]
	v_and_b32_e32 v150, 0x70, v57
	v_add_u32_e32 v18, 32, v16
	s_lshl_b32 s17, s20, 1
	v_lshl_add_u64 v[0:1], v[0:1], 0, v[150:151]
	v_mad_i64_i32 v[2:3], s[18:19], v18, s0, v[6:7]
	v_add_u32_e32 v52, 64, v16
	s_add_u32 s20, s15, s17
	v_ashrrev_i32_e32 v17, 31, v16
	global_load_dwordx4 v[20:23], v[0:1], off
	v_lshl_add_u64 v[2:3], v[2:3], 0, v[150:151]
	v_mad_i64_i32 v[4:5], s[18:19], v52, s0, v[6:7]
	v_add_u32_e32 v54, 0x60, v16
	s_addc_u32 s21, s16, 0
	v_ashrrev_i32_e32 v19, 31, v18
	global_load_dwordx4 v[24:27], v[2:3], off
	v_lshl_add_u64 v[4:5], v[4:5], 0, v[150:151]
	v_mad_i64_i32 v[6:7], s[18:19], v54, s0, v[6:7]
	v_lshlrev_b64 v[8:9], 10, v[16:17]
	v_ashrrev_i32_e32 v53, 31, v52
	global_load_dwordx4 v[28:31], v[4:5], off
	v_lshl_add_u64 v[6:7], v[6:7], 0, v[150:151]
	v_lshl_add_u64 v[8:9], s[20:21], 0, v[8:9]
	v_lshlrev_b64 v[10:11], 10, v[18:19]
	v_ashrrev_i32_e32 v55, 31, v54
	global_load_dwordx4 v[32:35], v[6:7], off
	v_lshl_add_u64 v[8:9], v[8:9], 0, v[150:151]
	v_lshl_add_u64 v[10:11], s[20:21], 0, v[10:11]
	v_lshlrev_b64 v[12:13], 10, v[52:53]
	global_load_dwordx4 v[36:39], v[8:9], off
	v_lshl_add_u64 v[10:11], v[10:11], 0, v[150:151]
	v_lshl_add_u64 v[12:13], s[20:21], 0, v[12:13]
	v_lshlrev_b64 v[14:15], 10, v[54:55]
	global_load_dwordx4 v[40:43], v[10:11], off
	v_lshl_add_u64 v[12:13], v[12:13], 0, v[150:151]
	v_lshl_add_u64 v[14:15], s[20:21], 0, v[14:15]
	global_load_dwordx4 v[44:47], v[12:13], off
	v_lshl_add_u64 v[14:15], v[14:15], 0, v[150:151]
	global_load_dwordx4 v[48:51], v[14:15], off
	v_lshlrev_b32_e32 v19, 3, v56
	v_and_b32_e32 v108, 48, v56
	v_and_b32_e32 v17, 15, v56
	v_lshrrev_b32_e32 v53, 1, v56
	v_lshlrev_b32_e32 v55, 7, v56
	v_and_b32_e32 v109, 0x70, v19
	v_bitop3_b32 v115, v19, v108, s23 bitop3:0x6c
	v_bitop3_b32 v19, v57, s23, v56 bitop3:0x48
	v_and_or_b32 v136, v53, s24, v17
	v_and_b32_e32 v150, 0x2780, v55
	v_lshl_or_b32 v16, v16, 7, v19
	v_lshl_or_b32 v17, v18, 7, v19
	v_lshl_or_b32 v18, v52, 7, v19
	v_lshl_or_b32 v19, v54, 7, v19
	global_load_dwordx4 v[52:55], v[0:1], off offset:128
	global_load_dwordx4 v[56:59], v[2:3], off offset:128
	global_load_dwordx4 v[104:107], v[4:5], off offset:128
	global_load_dwordx4 v[116:119], v[6:7], off offset:128
	global_load_dwordx4 v[120:123], v[8:9], off offset:128
	global_load_dwordx4 v[124:127], v[10:11], off offset:128
	global_load_dwordx4 v[128:131], v[12:13], off offset:128
	global_load_dwordx4 v[132:135], v[14:15], off offset:128
	s_and_b64 vcc, s[8:9], exec
	s_waitcnt vmcnt(15)
	ds_write_b128 v16, v[20:23]
	s_waitcnt vmcnt(14)
	ds_write_b128 v17, v[24:27]
	s_waitcnt vmcnt(13)
	ds_write_b128 v18, v[28:31]
	s_waitcnt vmcnt(12)
	ds_write_b128 v19, v[32:35]
	s_waitcnt vmcnt(11)
	ds_write_b128 v16, v[36:39] offset:32768
	s_waitcnt vmcnt(10)
	ds_write_b128 v17, v[40:43] offset:32768
	s_waitcnt vmcnt(9)
	ds_write_b128 v18, v[44:47] offset:32768
	s_waitcnt vmcnt(8)
	ds_write_b128 v19, v[48:51] offset:32768
	v_or_b32_e32 v20, v150, v115
	s_waitcnt lgkmcnt(0)
	s_barrier
	ds_read_b128 v[22:25], v20 offset:32768
	v_lshlrev_b32_e32 v50, 7, v136
	v_bitop3_b32 v21, v50, v109, v108 bitop3:0xf6
	ds_read_b128 v[30:33], v21
	s_waitcnt lgkmcnt(0)
	v_mfma_f32_16x16x32_f16 v[38:41], v[22:25], v[30:33], 0
	ds_read_b128 v[26:29], v20 offset:34816
	ds_read_b128 v[34:37], v21 offset:2048
	s_waitcnt lgkmcnt(0)
	v_mfma_f32_16x16x32_f16 v[144:147], v[22:25], v[34:37], 0
	ds_read_b128 v[42:45], v20 offset:36864
	ds_read_b128 v[162:165], v21 offset:4096
	s_waitcnt lgkmcnt(0)
	v_mfma_f32_16x16x32_f16 v[190:193], v[22:25], v[162:165], 0
	ds_read_b128 v[136:139], v20 offset:38912
	ds_read_b128 v[166:169], v21 offset:6144
	s_waitcnt lgkmcnt(0)
	v_mfma_f32_16x16x32_f16 v[202:205], v[22:25], v[166:169], 0
	v_lshl_add_u64 v[108:109], v[80:81], 0, s[4:5]
	v_mfma_f32_16x16x32_f16 v[46:49], v[26:29], v[30:33], 0
	v_xor_b32_e32 v22, 64, v115
	v_mfma_f32_16x16x32_f16 v[140:143], v[42:45], v[30:33], 0
	v_or_b32_e32 v23, v150, v22
	v_mfma_f32_16x16x32_f16 v[30:33], v[136:139], v[30:33], 0
	ds_read_b128 v[206:209], v23 offset:32768
	v_mfma_f32_16x16x32_f16 v[154:157], v[26:29], v[34:37], 0
	ds_read_b128 v[224:227], v23 offset:36864
	v_mfma_f32_16x16x32_f16 v[158:161], v[42:45], v[34:37], 0
	ds_read_b128 v[228:231], v23 offset:38912
	v_mfma_f32_16x16x32_f16 v[34:37], v[136:139], v[34:37], 0
	v_bitop3_b32 v22, v50, v115, 64 bitop3:0xf6
	v_mfma_f32_16x16x32_f16 v[194:197], v[26:29], v[162:165], 0
	ds_read_b128 v[210:213], v22
	v_mfma_f32_16x16x32_f16 v[198:201], v[42:45], v[162:165], 0
	ds_read_b128 v[220:223], v22 offset:2048
	v_mfma_f32_16x16x32_f16 v[162:165], v[136:139], v[162:165], 0
	s_waitcnt vmcnt(7)
	ds_write_b128 v16, v[52:55] offset:16384
	v_mfma_f32_16x16x32_f16 v[24:27], v[26:29], v[166:169], 0
	s_waitcnt vmcnt(6)
	ds_write_b128 v17, v[56:59] offset:16384
	v_mfma_f32_16x16x32_f16 v[42:45], v[42:45], v[166:169], 0
	s_waitcnt vmcnt(5)
	ds_write_b128 v18, v[104:107] offset:16384
	v_mfma_f32_16x16x32_f16 v[136:139], v[136:139], v[166:169], 0
	ds_read_b128 v[166:169], v23 offset:34816
	s_waitcnt lgkmcnt(5)
; #define GL_LOAD(s_, kt_) if (VAR != 1) { a##s_##0 = GL_A(0, kt_); a##s_##1 = GL_A(1, kt_); a##s_##2 = GL_A(2, kt_); a##s_##3 = GL_A(3, kt_); b##s_##0 = GL_B(0, kt_); b##s_##1 = GL_B(1, kt_); b##s_##2 = GL_B(2, kt_); b##s_##3 = GL_B(3, kt_); }
; #define LDS_STORE(s_, buf_) if (VAR != 2) { LDS_ST1(sA, 0, buf_, a##s_##0) LDS_ST1(sA, 1, buf_, a##s_##1) LDS_ST1(sA, 2, buf_, a##s_##2) LDS_ST1(sA, 3, buf_, a##s_##3) LDS_ST1(sB, 0, buf_, b##s_##0) LDS_ST1(sB, 1, buf_, b##s_##1) LDS_ST1(sB, 2, buf_, b##s_##2) LDS_ST1(sB, 3, buf_, b##s_##3) }
;     ...
;   GL_LOAD(0, 0)
;   GL_LOAD(1, 1)
;   LDS_STORE(0, 0)
;   if (VAR != 4) __syncthreads();
; #pragma unroll
;   for (int kt = 0; kt < nk; kt += 2) {
;     if (kt + 2 < nk) { GL_LOAD(0, kt + 2) }
;     MMA_TILE(0)
;     LDS_STORE(1, 1)
;     if (VAR != 4) __syncthreads();
;     if (kt + 3 < nk) { GL_LOAD(1, kt + 3) }
;     MMA_TILE(1)
;     if (kt + 2 < nk) { LDS_STORE(0, 0) }
;     if (VAR != 4) __syncthreads();
	v_mfma_f32_16x16x32_f16 v[38:41], v[206:209], v[210:213], v[38:41]
	s_waitcnt vmcnt(4)
	ds_write_b128 v19, v[116:119] offset:16384
	v_mfma_f32_16x16x32_f16 v[140:143], v[224:227], v[210:213], v[140:143]
	s_waitcnt vmcnt(3)
	ds_write_b128 v16, v[120:123] offset:49152
	v_mfma_f32_16x16x32_f16 v[28:31], v[228:231], v[210:213], v[30:33]
	s_waitcnt vmcnt(2)
	ds_write_b128 v17, v[124:127] offset:49152
	s_waitcnt lgkmcnt(7)
	v_mfma_f32_16x16x32_f16 v[144:147], v[206:209], v[220:223], v[144:147]
	s_waitcnt vmcnt(1)
	ds_write_b128 v18, v[128:131] offset:49152
	v_mfma_f32_16x16x32_f16 v[158:161], v[224:227], v[220:223], v[158:161]
	s_waitcnt vmcnt(0)
	ds_write_b128 v19, v[132:135] offset:49152
	v_mfma_f32_16x16x32_f16 v[32:35], v[228:231], v[220:223], v[34:37]
	s_waitcnt lgkmcnt(5)
	v_mfma_f32_16x16x32_f16 v[46:49], v[166:169], v[210:213], v[46:49]
	ds_read_b128 v[210:213], v22 offset:4096
	v_mfma_f32_16x16x32_f16 v[154:157], v[166:169], v[220:223], v[154:157]
	ds_read_b128 v[220:223], v22 offset:6144
	s_waitcnt lgkmcnt(1)
	v_mfma_f32_16x16x32_f16 v[190:193], v[206:209], v[210:213], v[190:193]
	s_waitcnt lgkmcnt(0)
	v_mfma_f32_16x16x32_f16 v[202:205], v[206:209], v[220:223], v[202:205]
	global_load_dwordx4 v[206:209], v[0:1], off offset:256
	v_mfma_f32_16x16x32_f16 v[194:197], v[166:169], v[210:213], v[194:197]
	v_mfma_f32_16x16x32_f16 v[24:27], v[166:169], v[220:223], v[24:27]
	v_mfma_f32_16x16x32_f16 v[198:201], v[224:227], v[210:213], v[198:201]
	v_mfma_f32_16x16x32_f16 v[162:165], v[228:231], v[210:213], v[162:165]
	global_load_dwordx4 v[210:213], v[2:3], off offset:256
	global_load_dwordx4 v[232:235], v[4:5], off offset:256
	global_load_dwordx4 v[236:239], v[6:7], off offset:256
	global_load_dwordx4 v[166:169], v[8:9], off offset:256
	global_load_dwordx4 v[240:243], v[10:11], off offset:256
	global_load_dwordx4 v[244:247], v[12:13], off offset:256
	global_load_dwordx4 v[248:251], v[14:15], off offset:256
	s_waitcnt lgkmcnt(0)
	s_barrier
	v_mfma_f32_16x16x32_f16 v[54:57], v[228:231], v[220:223], v[136:139]
	ds_read_b128 v[50:53], v20 offset:49152
	v_mfma_f32_16x16x32_f16 v[42:45], v[224:227], v[220:223], v[42:45]
	ds_read_b128 v[104:107], v20 offset:51200
	ds_read_b128 v[116:119], v21 offset:16384
	s_waitcnt lgkmcnt(0)
	v_mfma_f32_16x16x32_f16 v[36:39], v[50:53], v[116:119], v[38:41]
	ds_read_b128 v[120:123], v21 offset:18432
	v_mfma_f32_16x16x32_f16 v[46:49], v[104:107], v[116:119], v[46:49]
	ds_read_b128 v[124:127], v20 offset:53248
	s_waitcnt lgkmcnt(0)
	v_mfma_f32_16x16x32_f16 v[132:135], v[124:127], v[116:119], v[140:143]
	ds_read_b128 v[128:131], v20 offset:55296
	s_waitcnt lgkmcnt(0)
	v_mfma_f32_16x16x32_f16 v[28:31], v[128:131], v[116:119], v[28:31]
	v_mfma_f32_16x16x32_f16 v[116:119], v[50:53], v[120:123], v[144:147]
	s_nop 2
	ds_read_b128 v[144:147], v21 offset:22528
	v_mfma_f32_16x16x32_f16 v[136:139], v[104:107], v[120:123], v[154:157]
	v_mfma_f32_16x16x32_f16 v[140:143], v[124:127], v[120:123], v[158:161]
	v_mfma_f32_16x16x32_f16 v[32:35], v[128:131], v[120:123], v[32:35]
	ds_read_b128 v[120:123], v21 offset:20480
	s_waitcnt lgkmcnt(0)
	v_mfma_f32_16x16x32_f16 v[154:157], v[50:53], v[120:123], v[190:193]
	v_mfma_f32_16x16x32_f16 v[50:53], v[50:53], v[144:147], v[202:205]
	v_mfma_f32_16x16x32_f16 v[158:161], v[104:107], v[120:123], v[194:197]
	s_nop 2
	ds_read_b128 v[194:197], v23 offset:55296
	v_mfma_f32_16x16x32_f16 v[24:27], v[104:107], v[144:147], v[24:27]
	ds_read_b128 v[104:107], v23 offset:49152
	s_waitcnt vmcnt(7)
	ds_write_b128 v16, v[206:209]
	v_mfma_f32_16x16x32_f16 v[190:193], v[124:127], v[120:123], v[198:201]
	s_waitcnt vmcnt(6)
	ds_write_b128 v17, v[210:213]
	s_waitcnt vmcnt(5)
	ds_write_b128 v18, v[232:235]
	v_mfma_f32_16x16x32_f16 v[40:43], v[124:127], v[144:147], v[42:45]
	ds_read_b128 v[124:127], v23 offset:51200
	v_mfma_f32_16x16x32_f16 v[120:123], v[128:131], v[120:123], v[162:165]
	s_nop 2
	ds_read_b128 v[162:165], v23 offset:53248
	v_mfma_f32_16x16x32_f16 v[54:57], v[128:131], v[144:147], v[54:57]
	ds_read_b128 v[128:131], v22 offset:16384
	s_waitcnt lgkmcnt(0)
	v_mfma_f32_16x16x32_f16 v[36:39], v[104:107], v[128:131], v[36:39]
	ds_read_b128 v[144:147], v22 offset:18432
	s_waitcnt lgkmcnt(0)
	v_mfma_f32_16x16x32_f16 v[116:119], v[104:107], v[144:147], v[116:119]
	s_waitcnt vmcnt(4)
	ds_write_b128 v19, v[236:239]
	v_mfma_f32_16x16x32_f16 v[44:47], v[124:127], v[128:131], v[46:49]
	s_waitcnt vmcnt(3)
	ds_write_b128 v16, v[166:169] offset:32768
	v_mfma_f32_16x16x32_f16 v[132:135], v[162:165], v[128:131], v[132:135]
	v_mfma_f32_16x16x32_f16 v[28:31], v[194:197], v[128:131], v[28:31]
	v_mfma_f32_16x16x32_f16 v[128:131], v[124:127], v[144:147], v[136:139]
	s_waitcnt vmcnt(2)
	ds_write_b128 v17, v[240:243] offset:32768
	s_waitcnt vmcnt(1)
	ds_write_b128 v18, v[244:247] offset:32768
	s_waitcnt vmcnt(0)
	ds_write_b128 v19, v[248:251] offset:32768
	v_mfma_f32_16x16x32_f16 v[136:139], v[162:165], v[144:147], v[140:143]
	s_nop 2
	ds_read_b128 v[140:143], v22 offset:20480
	v_mfma_f32_16x16x32_f16 v[32:35], v[194:197], v[144:147], v[32:35]
	ds_read_b128 v[144:147], v22 offset:22528
	s_waitcnt lgkmcnt(1)
	v_mfma_f32_16x16x32_f16 v[154:157], v[104:107], v[140:143], v[154:157]
	s_waitcnt lgkmcnt(0)
	v_mfma_f32_16x16x32_f16 v[48:51], v[104:107], v[144:147], v[50:53]
	global_load_dwordx4 v[104:107], v[0:1], off offset:384
	v_mfma_f32_16x16x32_f16 v[158:161], v[124:127], v[140:143], v[158:161]
	v_mfma_f32_16x16x32_f16 v[24:27], v[124:127], v[144:147], v[24:27]
	v_mfma_f32_16x16x32_f16 v[190:193], v[162:165], v[140:143], v[190:193]
	v_mfma_f32_16x16x32_f16 v[40:43], v[162:165], v[144:147], v[40:43]
	v_mfma_f32_16x16x32_f16 v[120:123], v[194:197], v[140:143], v[120:123]
	global_load_dwordx4 v[140:143], v[2:3], off offset:384
	global_load_dwordx4 v[198:201], v[4:5], off offset:384
	global_load_dwordx4 v[202:205], v[6:7], off offset:384
	global_load_dwordx4 v[124:127], v[8:9], off offset:384
	global_load_dwordx4 v[220:223], v[10:11], off offset:384
	global_load_dwordx4 v[224:227], v[12:13], off offset:384
	global_load_dwordx4 v[228:231], v[14:15], off offset:384
	s_waitcnt lgkmcnt(0)
	s_barrier
; #define GL_LOAD(s_, kt_) if (VAR != 1) { a##s_##0 = GL_A(0, kt_); a##s_##1 = GL_A(1, kt_); a##s_##2 = GL_A(2, kt_); a##s_##3 = GL_A(3, kt_); b##s_##0 = GL_B(0, kt_); b##s_##1 = GL_B(1, kt_); b##s_##2 = GL_B(2, kt_); b##s_##3 = GL_B(3, kt_); }
; #define LDS_STORE(s_, buf_) if (VAR != 2) { LDS_ST1(sA, 0, buf_, a##s_##0) LDS_ST1(sA, 1, buf_, a##s_##1) LDS_ST1(sA, 2, buf_, a##s_##2) LDS_ST1(sA, 3, buf_, a##s_##3) LDS_ST1(sB, 0, buf_, b##s_##0) LDS_ST1(sB, 1, buf_, b##s_##1) LDS_ST1(sB, 2, buf_, b##s_##2) LDS_ST1(sB, 3, buf_, b##s_##3) }
;     ...
;   GL_LOAD(0, 0)
;   GL_LOAD(1, 1)
;   LDS_STORE(0, 0)
;   if (VAR != 4) __syncthreads();
; #pragma unroll
;   for (int kt = 0; kt < nk; kt += 2) {
;     if (kt + 2 < nk) { GL_LOAD(0, kt + 2) }
;     MMA_TILE(0)
;     LDS_STORE(1, 1)
;     if (VAR != 4) __syncthreads();
;     if (kt + 3 < nk) { GL_LOAD(1, kt + 3) }
;     MMA_TILE(1)
;     if (kt + 2 < nk) { LDS_STORE(0, 0) }
;     if (VAR != 4) __syncthreads();
	v_mfma_f32_16x16x32_f16 v[52:55], v[194:197], v[144:147], v[54:57]
	ds_read_b128 v[162:165], v20 offset:32768
	ds_read_b128 v[144:147], v21
	s_waitcnt lgkmcnt(0)
	v_mfma_f32_16x16x32_f16 v[36:39], v[162:165], v[144:147], v[36:39]
	ds_read_b128 v[56:59], v20 offset:34816
	ds_read_b128 v[166:169], v21 offset:2048
	s_waitcnt lgkmcnt(0)
	v_mfma_f32_16x16x32_f16 v[116:119], v[162:165], v[166:169], v[116:119]
	ds_read_b128 v[194:197], v20 offset:36864
	v_mfma_f32_16x16x32_f16 v[44:47], v[56:59], v[144:147], v[44:47]
	ds_read_b128 v[206:209], v20 offset:38912
	v_mfma_f32_16x16x32_f16 v[128:131], v[56:59], v[166:169], v[128:131]
	s_waitcnt lgkmcnt(1)
	v_mfma_f32_16x16x32_f16 v[132:135], v[194:197], v[144:147], v[132:135]
	v_mfma_f32_16x16x32_f16 v[136:139], v[194:197], v[166:169], v[136:139]
	s_waitcnt lgkmcnt(0)
	v_mfma_f32_16x16x32_f16 v[28:31], v[206:209], v[144:147], v[28:31]
	ds_read_b128 v[144:147], v21 offset:4096
	v_mfma_f32_16x16x32_f16 v[32:35], v[206:209], v[166:169], v[32:35]
	ds_read_b128 v[166:169], v21 offset:6144
	s_waitcnt lgkmcnt(1)
	v_mfma_f32_16x16x32_f16 v[154:157], v[162:165], v[144:147], v[154:157]
	s_waitcnt lgkmcnt(0)
	v_mfma_f32_16x16x32_f16 v[48:51], v[162:165], v[166:169], v[48:51]
	ds_read_b128 v[162:165], v22
	v_mfma_f32_16x16x32_f16 v[158:161], v[56:59], v[144:147], v[158:161]
	v_mfma_f32_16x16x32_f16 v[24:27], v[56:59], v[166:169], v[24:27]
	ds_read_b128 v[56:59], v23 offset:32768
	v_mfma_f32_16x16x32_f16 v[190:193], v[194:197], v[144:147], v[190:193]
	s_waitcnt vmcnt(7)
	ds_write_b128 v16, v[104:107] offset:16384
	s_waitcnt vmcnt(6)
	ds_write_b128 v17, v[140:143] offset:16384
	v_mfma_f32_16x16x32_f16 v[40:43], v[194:197], v[166:169], v[40:43]
	ds_read_b128 v[194:197], v23 offset:36864
	s_waitcnt vmcnt(5)
	ds_write_b128 v18, v[198:201] offset:16384
	v_mfma_f32_16x16x32_f16 v[120:123], v[206:209], v[144:147], v[120:123]
	ds_read_b128 v[144:147], v23 offset:34816
	v_mfma_f32_16x16x32_f16 v[52:55], v[206:209], v[166:169], v[52:55]
	ds_read_b128 v[166:169], v22 offset:2048
	s_waitcnt lgkmcnt(6)
	v_mfma_f32_16x16x32_f16 v[36:39], v[56:59], v[162:165], v[36:39]
	ds_read_b128 v[206:209], v23 offset:38912
	s_waitcnt lgkmcnt(1)
	v_mfma_f32_16x16x32_f16 v[116:119], v[56:59], v[166:169], v[116:119]
	s_waitcnt vmcnt(4)
	ds_write_b128 v19, v[202:205] offset:16384
	v_mfma_f32_16x16x32_f16 v[44:47], v[144:147], v[162:165], v[44:47]
	s_waitcnt vmcnt(3)
	ds_write_b128 v16, v[124:127] offset:49152
	v_mfma_f32_16x16x32_f16 v[128:131], v[144:147], v[166:169], v[128:131]
	s_waitcnt vmcnt(2)
	ds_write_b128 v17, v[220:223] offset:49152
	v_mfma_f32_16x16x32_f16 v[132:135], v[194:197], v[162:165], v[132:135]
	s_waitcnt vmcnt(1)
	ds_write_b128 v18, v[224:227] offset:49152
	v_mfma_f32_16x16x32_f16 v[136:139], v[194:197], v[166:169], v[136:139]
	s_waitcnt vmcnt(0)
	ds_write_b128 v19, v[228:231] offset:49152
	s_waitcnt lgkmcnt(5)
	v_mfma_f32_16x16x32_f16 v[28:31], v[206:209], v[162:165], v[28:31]
	ds_read_b128 v[162:165], v22 offset:4096
	v_mfma_f32_16x16x32_f16 v[32:35], v[206:209], v[166:169], v[32:35]
	ds_read_b128 v[166:169], v22 offset:6144
	s_waitcnt lgkmcnt(1)
	v_mfma_f32_16x16x32_f16 v[154:157], v[56:59], v[162:165], v[154:157]
	s_waitcnt lgkmcnt(0)
	v_mfma_f32_16x16x32_f16 v[48:51], v[56:59], v[166:169], v[48:51]
	global_load_dwordx4 v[56:59], v[0:1], off offset:512
	v_mfma_f32_16x16x32_f16 v[158:161], v[144:147], v[162:165], v[158:161]
	v_mfma_f32_16x16x32_f16 v[24:27], v[144:147], v[166:169], v[24:27]
	v_mfma_f32_16x16x32_f16 v[190:193], v[194:197], v[162:165], v[190:193]
	v_mfma_f32_16x16x32_f16 v[40:43], v[194:197], v[166:169], v[40:43]
	v_mfma_f32_16x16x32_f16 v[120:123], v[206:209], v[162:165], v[120:123]
	global_load_dwordx4 v[162:165], v[2:3], off offset:512
	global_load_dwordx4 v[210:213], v[4:5], off offset:512
	global_load_dwordx4 v[232:235], v[6:7], off offset:512
	global_load_dwordx4 v[144:147], v[8:9], off offset:512
	global_load_dwordx4 v[236:239], v[10:11], off offset:512
	global_load_dwordx4 v[240:243], v[12:13], off offset:512
	global_load_dwordx4 v[244:247], v[14:15], off offset:512
	s_waitcnt lgkmcnt(0)
	s_barrier
	v_mfma_f32_16x16x32_f16 v[52:55], v[206:209], v[166:169], v[52:55]
	ds_read_b128 v[104:107], v20 offset:49152
	ds_read_b128 v[140:143], v21 offset:16384
	s_waitcnt lgkmcnt(0)
	v_mfma_f32_16x16x32_f16 v[36:39], v[104:107], v[140:143], v[36:39]
	ds_read_b128 v[124:127], v20 offset:51200
	ds_read_b128 v[166:169], v21 offset:18432
	s_waitcnt lgkmcnt(0)
	v_mfma_f32_16x16x32_f16 v[116:119], v[104:107], v[166:169], v[116:119]
	ds_read_b128 v[194:197], v20 offset:53248
	v_mfma_f32_16x16x32_f16 v[44:47], v[124:127], v[140:143], v[44:47]
	ds_read_b128 v[198:201], v20 offset:55296
	v_mfma_f32_16x16x32_f16 v[128:131], v[124:127], v[166:169], v[128:131]
	s_waitcnt lgkmcnt(1)
	v_mfma_f32_16x16x32_f16 v[132:135], v[194:197], v[140:143], v[132:135]
	v_mfma_f32_16x16x32_f16 v[136:139], v[194:197], v[166:169], v[136:139]
	s_waitcnt lgkmcnt(0)
	v_mfma_f32_16x16x32_f16 v[28:31], v[198:201], v[140:143], v[28:31]
	ds_read_b128 v[140:143], v21 offset:20480
	v_mfma_f32_16x16x32_f16 v[32:35], v[198:201], v[166:169], v[32:35]
	ds_read_b128 v[166:169], v21 offset:22528
	s_waitcnt lgkmcnt(1)
	v_mfma_f32_16x16x32_f16 v[154:157], v[104:107], v[140:143], v[154:157]
	s_waitcnt lgkmcnt(0)
	v_mfma_f32_16x16x32_f16 v[48:51], v[104:107], v[166:169], v[48:51]
	ds_read_b128 v[104:107], v23 offset:49152
	v_mfma_f32_16x16x32_f16 v[158:161], v[124:127], v[140:143], v[158:161]
	v_mfma_f32_16x16x32_f16 v[24:27], v[124:127], v[166:169], v[24:27]
	ds_read_b128 v[124:127], v23 offset:51200
	v_mfma_f32_16x16x32_f16 v[190:193], v[194:197], v[140:143], v[190:193]
	s_waitcnt vmcnt(7)
; #define GL_LOAD(s_, kt_) if (VAR != 1) { a##s_##0 = GL_A(0, kt_); a##s_##1 = GL_A(1, kt_); a##s_##2 = GL_A(2, kt_); a##s_##3 = GL_A(3, kt_); b##s_##0 = GL_B(0, kt_); b##s_##1 = GL_B(1, kt_); b##s_##2 = GL_B(2, kt_); b##s_##3 = GL_B(3, kt_); }
; #define LDS_STORE(s_, buf_) if (VAR != 2) { LDS_ST1(sA, 0, buf_, a##s_##0) LDS_ST1(sA, 1, buf_, a##s_##1) LDS_ST1(sA, 2, buf_, a##s_##2) LDS_ST1(sA, 3, buf_, a##s_##3) LDS_ST1(sB, 0, buf_, b##s_##0) LDS_ST1(sB, 1, buf_, b##s_##1) LDS_ST1(sB, 2, buf_, b##s_##2) LDS_ST1(sB, 3, buf_, b##s_##3) }
;     ...
;   GL_LOAD(0, 0)
;   GL_LOAD(1, 1)
;   LDS_STORE(0, 0)
;   if (VAR != 4) __syncthreads();
; #pragma unroll
;   for (int kt = 0; kt < nk; kt += 2) {
;     if (kt + 2 < nk) { GL_LOAD(0, kt + 2) }
;     MMA_TILE(0)
;     LDS_STORE(1, 1)
;     if (VAR != 4) __syncthreads();
;     if (kt + 3 < nk) { GL_LOAD(1, kt + 3) }
;     MMA_TILE(1)
;     if (kt + 2 < nk) { LDS_STORE(0, 0) }
;     if (VAR != 4) __syncthreads();
	ds_write_b128 v16, v[56:59]
	s_waitcnt vmcnt(6)
	ds_write_b128 v17, v[162:165]
	v_mfma_f32_16x16x32_f16 v[40:43], v[194:197], v[166:169], v[40:43]
	ds_read_b128 v[194:197], v23 offset:53248
	s_waitcnt vmcnt(5)
	ds_write_b128 v18, v[210:213]
	v_mfma_f32_16x16x32_f16 v[120:123], v[198:201], v[140:143], v[120:123]
	ds_read_b128 v[140:143], v22 offset:16384
	v_mfma_f32_16x16x32_f16 v[52:55], v[198:201], v[166:169], v[52:55]
	ds_read_b128 v[166:169], v22 offset:18432
	s_waitcnt lgkmcnt(1)
	v_mfma_f32_16x16x32_f16 v[36:39], v[104:107], v[140:143], v[36:39]
	ds_read_b128 v[198:201], v23 offset:55296
	s_waitcnt lgkmcnt(1)
	v_mfma_f32_16x16x32_f16 v[116:119], v[104:107], v[166:169], v[116:119]
	s_waitcnt vmcnt(4)
	ds_write_b128 v19, v[232:235]
	v_mfma_f32_16x16x32_f16 v[44:47], v[124:127], v[140:143], v[44:47]
	s_waitcnt vmcnt(3)
	ds_write_b128 v16, v[144:147] offset:32768
	v_mfma_f32_16x16x32_f16 v[128:131], v[124:127], v[166:169], v[128:131]
	s_waitcnt vmcnt(2)
	ds_write_b128 v17, v[236:239] offset:32768
	v_mfma_f32_16x16x32_f16 v[132:135], v[194:197], v[140:143], v[132:135]
	s_waitcnt vmcnt(1)
	ds_write_b128 v18, v[240:243] offset:32768
	v_mfma_f32_16x16x32_f16 v[136:139], v[194:197], v[166:169], v[136:139]
	s_waitcnt vmcnt(0)
	ds_write_b128 v19, v[244:247] offset:32768
	s_waitcnt lgkmcnt(5)
	v_mfma_f32_16x16x32_f16 v[28:31], v[198:201], v[140:143], v[28:31]
	ds_read_b128 v[140:143], v22 offset:20480
	v_mfma_f32_16x16x32_f16 v[32:35], v[198:201], v[166:169], v[32:35]
	ds_read_b128 v[166:169], v22 offset:22528
	s_waitcnt lgkmcnt(1)
	v_mfma_f32_16x16x32_f16 v[154:157], v[104:107], v[140:143], v[154:157]
	s_waitcnt lgkmcnt(0)
	v_mfma_f32_16x16x32_f16 v[48:51], v[104:107], v[166:169], v[48:51]
	global_load_dwordx4 v[104:107], v[0:1], off offset:640
	v_mfma_f32_16x16x32_f16 v[158:161], v[124:127], v[140:143], v[158:161]
	v_mfma_f32_16x16x32_f16 v[24:27], v[124:127], v[166:169], v[24:27]
	v_mfma_f32_16x16x32_f16 v[190:193], v[194:197], v[140:143], v[190:193]
	v_mfma_f32_16x16x32_f16 v[40:43], v[194:197], v[166:169], v[40:43]
	v_mfma_f32_16x16x32_f16 v[120:123], v[198:201], v[140:143], v[120:123]
	global_load_dwordx4 v[140:143], v[2:3], off offset:640
	global_load_dwordx4 v[202:205], v[4:5], off offset:640
	global_load_dwordx4 v[206:209], v[6:7], off offset:640
	global_load_dwordx4 v[124:127], v[8:9], off offset:640
	global_load_dwordx4 v[220:223], v[10:11], off offset:640
	global_load_dwordx4 v[224:227], v[12:13], off offset:640
	global_load_dwordx4 v[228:231], v[14:15], off offset:640
	s_waitcnt lgkmcnt(0)
	s_barrier
	v_mfma_f32_16x16x32_f16 v[52:55], v[198:201], v[166:169], v[52:55]
	ds_read_b128 v[56:59], v20 offset:32768
	ds_read_b128 v[162:165], v21
	s_waitcnt lgkmcnt(0)
	v_mfma_f32_16x16x32_f16 v[36:39], v[56:59], v[162:165], v[36:39]
	ds_read_b128 v[144:147], v20 offset:34816
	ds_read_b128 v[166:169], v21 offset:2048
	s_waitcnt lgkmcnt(0)
	v_mfma_f32_16x16x32_f16 v[116:119], v[56:59], v[166:169], v[116:119]
	ds_read_b128 v[194:197], v20 offset:36864
	v_mfma_f32_16x16x32_f16 v[44:47], v[144:147], v[162:165], v[44:47]
	ds_read_b128 v[198:201], v20 offset:38912
	v_mfma_f32_16x16x32_f16 v[128:131], v[144:147], v[166:169], v[128:131]
	s_waitcnt lgkmcnt(1)
	v_mfma_f32_16x16x32_f16 v[132:135], v[194:197], v[162:165], v[132:135]
	v_mfma_f32_16x16x32_f16 v[136:139], v[194:197], v[166:169], v[136:139]
	s_waitcnt lgkmcnt(0)
	v_mfma_f32_16x16x32_f16 v[28:31], v[198:201], v[162:165], v[28:31]
	ds_read_b128 v[162:165], v21 offset:4096
	v_mfma_f32_16x16x32_f16 v[32:35], v[198:201], v[166:169], v[32:35]
	ds_read_b128 v[166:169], v21 offset:6144
	s_waitcnt lgkmcnt(1)
	v_mfma_f32_16x16x32_f16 v[154:157], v[56:59], v[162:165], v[154:157]
	s_waitcnt lgkmcnt(0)
	v_mfma_f32_16x16x32_f16 v[48:51], v[56:59], v[166:169], v[48:51]
	ds_read_b128 v[56:59], v23 offset:32768
	v_mfma_f32_16x16x32_f16 v[158:161], v[144:147], v[162:165], v[158:161]
	v_mfma_f32_16x16x32_f16 v[24:27], v[144:147], v[166:169], v[24:27]
	ds_read_b128 v[144:147], v23 offset:34816
	v_mfma_f32_16x16x32_f16 v[190:193], v[194:197], v[162:165], v[190:193]
	s_waitcnt vmcnt(7)
	ds_write_b128 v16, v[104:107] offset:16384
	s_waitcnt vmcnt(6)
	ds_write_b128 v17, v[140:143] offset:16384
	v_mfma_f32_16x16x32_f16 v[40:43], v[194:197], v[166:169], v[40:43]
	ds_read_b128 v[194:197], v23 offset:36864
	s_waitcnt vmcnt(5)
	ds_write_b128 v18, v[202:205] offset:16384
	v_mfma_f32_16x16x32_f16 v[120:123], v[198:201], v[162:165], v[120:123]
	ds_read_b128 v[162:165], v22
	v_mfma_f32_16x16x32_f16 v[52:55], v[198:201], v[166:169], v[52:55]
	ds_read_b128 v[166:169], v22 offset:2048
	s_waitcnt lgkmcnt(1)
	v_mfma_f32_16x16x32_f16 v[36:39], v[56:59], v[162:165], v[36:39]
	ds_read_b128 v[198:201], v23 offset:38912
	s_waitcnt lgkmcnt(1)
	v_mfma_f32_16x16x32_f16 v[116:119], v[56:59], v[166:169], v[116:119]
	s_waitcnt vmcnt(4)
	ds_write_b128 v19, v[206:209] offset:16384
	v_mfma_f32_16x16x32_f16 v[44:47], v[144:147], v[162:165], v[44:47]
	s_waitcnt vmcnt(3)
	ds_write_b128 v16, v[124:127] offset:49152
	v_mfma_f32_16x16x32_f16 v[128:131], v[144:147], v[166:169], v[128:131]
	s_waitcnt vmcnt(2)
	ds_write_b128 v17, v[220:223] offset:49152
	v_mfma_f32_16x16x32_f16 v[132:135], v[194:197], v[162:165], v[132:135]
	s_waitcnt vmcnt(1)
	ds_write_b128 v18, v[224:227] offset:49152
	v_mfma_f32_16x16x32_f16 v[136:139], v[194:197], v[166:169], v[136:139]
	s_waitcnt vmcnt(0)
	ds_write_b128 v19, v[228:231] offset:49152
	s_waitcnt lgkmcnt(5)
	v_mfma_f32_16x16x32_f16 v[28:31], v[198:201], v[162:165], v[28:31]
	ds_read_b128 v[162:165], v22 offset:4096
	v_mfma_f32_16x16x32_f16 v[32:35], v[198:201], v[166:169], v[32:35]
	ds_read_b128 v[166:169], v22 offset:6144
	s_waitcnt lgkmcnt(1)
	v_mfma_f32_16x16x32_f16 v[154:157], v[56:59], v[162:165], v[154:157]
	s_waitcnt lgkmcnt(0)
	v_mfma_f32_16x16x32_f16 v[48:51], v[56:59], v[166:169], v[48:51]
	global_load_dwordx4 v[56:59], v[0:1], off offset:768
	v_mfma_f32_16x16x32_f16 v[158:161], v[144:147], v[162:165], v[158:161]
	v_mfma_f32_16x16x32_f16 v[24:27], v[144:147], v[166:169], v[24:27]
	v_mfma_f32_16x16x32_f16 v[190:193], v[194:197], v[162:165], v[190:193]
	v_mfma_f32_16x16x32_f16 v[40:43], v[194:197], v[166:169], v[40:43]
	v_mfma_f32_16x16x32_f16 v[120:123], v[198:201], v[162:165], v[120:123]
	global_load_dwordx4 v[162:165], v[2:3], off offset:768
	global_load_dwordx4 v[210:213], v[4:5], off offset:768
	global_load_dwordx4 v[232:235], v[6:7], off offset:768
	global_load_dwordx4 v[144:147], v[8:9], off offset:768
	global_load_dwordx4 v[236:239], v[10:11], off offset:768
	global_load_dwordx4 v[240:243], v[12:13], off offset:768
	global_load_dwordx4 v[244:247], v[14:15], off offset:768
	s_waitcnt lgkmcnt(0)
	s_barrier
; #define GL_LOAD(s_, kt_) if (VAR != 1) { a##s_##0 = GL_A(0, kt_); a##s_##1 = GL_A(1, kt_); a##s_##2 = GL_A(2, kt_); a##s_##3 = GL_A(3, kt_); b##s_##0 = GL_B(0, kt_); b##s_##1 = GL_B(1, kt_); b##s_##2 = GL_B(2, kt_); b##s_##3 = GL_B(3, kt_); }
; #define LDS_STORE(s_, buf_) if (VAR != 2) { LDS_ST1(sA, 0, buf_, a##s_##0) LDS_ST1(sA, 1, buf_, a##s_##1) LDS_ST1(sA, 2, buf_, a##s_##2) LDS_ST1(sA, 3, buf_, a##s_##3) LDS_ST1(sB, 0, buf_, b##s_##0) LDS_ST1(sB, 1, buf_, b##s_##1) LDS_ST1(sB, 2, buf_, b##s_##2) LDS_ST1(sB, 3, buf_, b##s_##3) }
;     ...
;   GL_LOAD(0, 0)
;   GL_LOAD(1, 1)
;   LDS_STORE(0, 0)
;   if (VAR != 4) __syncthreads();
; #pragma unroll
;   for (int kt = 0; kt < nk; kt += 2) {
;     if (kt + 2 < nk) { GL_LOAD(0, kt + 2) }
;     MMA_TILE(0)
;     LDS_STORE(1, 1)
;     if (VAR != 4) __syncthreads();
;     if (kt + 3 < nk) { GL_LOAD(1, kt + 3) }
;     MMA_TILE(1)
;     if (kt + 2 < nk) { LDS_STORE(0, 0) }
;     if (VAR != 4) __syncthreads();
	v_mfma_f32_16x16x32_f16 v[52:55], v[198:201], v[166:169], v[52:55]
	ds_read_b128 v[104:107], v20 offset:49152
	ds_read_b128 v[140:143], v21 offset:16384
	s_waitcnt lgkmcnt(0)
	v_mfma_f32_16x16x32_f16 v[36:39], v[104:107], v[140:143], v[36:39]
	ds_read_b128 v[124:127], v20 offset:51200
	ds_read_b128 v[166:169], v21 offset:18432
	s_waitcnt lgkmcnt(0)
	v_mfma_f32_16x16x32_f16 v[116:119], v[104:107], v[166:169], v[116:119]
	ds_read_b128 v[194:197], v20 offset:53248
	v_mfma_f32_16x16x32_f16 v[44:47], v[124:127], v[140:143], v[44:47]
	ds_read_b128 v[198:201], v20 offset:55296
	v_mfma_f32_16x16x32_f16 v[128:131], v[124:127], v[166:169], v[128:131]
	s_waitcnt lgkmcnt(1)
	v_mfma_f32_16x16x32_f16 v[132:135], v[194:197], v[140:143], v[132:135]
	v_mfma_f32_16x16x32_f16 v[136:139], v[194:197], v[166:169], v[136:139]
	s_waitcnt lgkmcnt(0)
	v_mfma_f32_16x16x32_f16 v[28:31], v[198:201], v[140:143], v[28:31]
	ds_read_b128 v[140:143], v21 offset:20480
	v_mfma_f32_16x16x32_f16 v[32:35], v[198:201], v[166:169], v[32:35]
	ds_read_b128 v[166:169], v21 offset:22528
	s_waitcnt lgkmcnt(1)
	v_mfma_f32_16x16x32_f16 v[154:157], v[104:107], v[140:143], v[154:157]
	s_waitcnt lgkmcnt(0)
	v_mfma_f32_16x16x32_f16 v[48:51], v[104:107], v[166:169], v[48:51]
	ds_read_b128 v[104:107], v23 offset:49152
	v_mfma_f32_16x16x32_f16 v[158:161], v[124:127], v[140:143], v[158:161]
	v_mfma_f32_16x16x32_f16 v[24:27], v[124:127], v[166:169], v[24:27]
	ds_read_b128 v[124:127], v23 offset:51200
	v_mfma_f32_16x16x32_f16 v[190:193], v[194:197], v[140:143], v[190:193]
	s_waitcnt vmcnt(7)
	ds_write_b128 v16, v[56:59]
	s_waitcnt vmcnt(6)
	ds_write_b128 v17, v[162:165]
	v_mfma_f32_16x16x32_f16 v[40:43], v[194:197], v[166:169], v[40:43]
	ds_read_b128 v[194:197], v23 offset:53248
	s_waitcnt vmcnt(5)
	ds_write_b128 v18, v[210:213]
	v_mfma_f32_16x16x32_f16 v[120:123], v[198:201], v[140:143], v[120:123]
	ds_read_b128 v[140:143], v22 offset:16384
	v_mfma_f32_16x16x32_f16 v[52:55], v[198:201], v[166:169], v[52:55]
	ds_read_b128 v[166:169], v22 offset:18432
	s_waitcnt lgkmcnt(1)
	v_mfma_f32_16x16x32_f16 v[36:39], v[104:107], v[140:143], v[36:39]
	ds_read_b128 v[198:201], v23 offset:55296
	s_waitcnt lgkmcnt(1)
	v_mfma_f32_16x16x32_f16 v[116:119], v[104:107], v[166:169], v[116:119]
	s_waitcnt vmcnt(4)
	ds_write_b128 v19, v[232:235]
	v_mfma_f32_16x16x32_f16 v[44:47], v[124:127], v[140:143], v[44:47]
	s_waitcnt vmcnt(3)
	ds_write_b128 v16, v[144:147] offset:32768
	v_mfma_f32_16x16x32_f16 v[128:131], v[124:127], v[166:169], v[128:131]
	s_waitcnt vmcnt(2)
	ds_write_b128 v17, v[236:239] offset:32768
	v_mfma_f32_16x16x32_f16 v[132:135], v[194:197], v[140:143], v[132:135]
	s_waitcnt vmcnt(1)
	ds_write_b128 v18, v[240:243] offset:32768
	v_mfma_f32_16x16x32_f16 v[136:139], v[194:197], v[166:169], v[136:139]
	s_waitcnt vmcnt(0)
	ds_write_b128 v19, v[244:247] offset:32768
	s_waitcnt lgkmcnt(5)
	v_mfma_f32_16x16x32_f16 v[28:31], v[198:201], v[140:143], v[28:31]
	ds_read_b128 v[140:143], v22 offset:20480
	v_mfma_f32_16x16x32_f16 v[32:35], v[198:201], v[166:169], v[32:35]
	ds_read_b128 v[166:169], v22 offset:22528
	s_waitcnt lgkmcnt(1)
	v_mfma_f32_16x16x32_f16 v[154:157], v[104:107], v[140:143], v[154:157]
	s_waitcnt lgkmcnt(0)
	v_mfma_f32_16x16x32_f16 v[48:51], v[104:107], v[166:169], v[48:51]
	global_load_dwordx4 v[104:107], v[0:1], off offset:896
	global_load_dwordx4 v[0:3], v[2:3], off offset:896
	v_mfma_f32_16x16x32_f16 v[158:161], v[124:127], v[140:143], v[158:161]
	v_mfma_f32_16x16x32_f16 v[24:27], v[124:127], v[166:169], v[24:27]
	v_mfma_f32_16x16x32_f16 v[190:193], v[194:197], v[140:143], v[190:193]
	v_mfma_f32_16x16x32_f16 v[40:43], v[194:197], v[166:169], v[40:43]
	v_mfma_f32_16x16x32_f16 v[120:123], v[198:201], v[140:143], v[120:123]
	global_load_dwordx4 v[140:143], v[4:5], off offset:896
	global_load_dwordx4 v[4:7], v[6:7], off offset:896
	global_load_dwordx4 v[124:127], v[8:9], off offset:896
	global_load_dwordx4 v[8:11], v[10:11], off offset:896
	global_load_dwordx4 v[202:205], v[12:13], off offset:896
	global_load_dwordx4 v[12:15], v[14:15], off offset:896
	s_waitcnt lgkmcnt(0)
	s_barrier
	ds_read_b128 v[56:59], v20 offset:32768
	v_mfma_f32_16x16x32_f16 v[52:55], v[198:201], v[166:169], v[52:55]
	ds_read_b128 v[144:147], v20 offset:34816
	ds_read_b128 v[162:165], v21
	ds_read_b128 v[166:169], v21 offset:2048
	ds_read_b128 v[194:197], v20 offset:36864
	ds_read_b128 v[198:201], v20 offset:38912
	s_waitcnt lgkmcnt(3)
	v_mfma_f32_16x16x32_f16 v[36:39], v[56:59], v[162:165], v[36:39]
	v_mfma_f32_16x16x32_f16 v[44:47], v[144:147], v[162:165], v[44:47]
	s_waitcnt lgkmcnt(1)
	v_mfma_f32_16x16x32_f16 v[132:135], v[194:197], v[162:165], v[132:135]
	s_waitcnt lgkmcnt(0)
	v_mfma_f32_16x16x32_f16 v[28:31], v[198:201], v[162:165], v[28:31]
	v_mfma_f32_16x16x32_f16 v[116:119], v[56:59], v[166:169], v[116:119]
	v_mfma_f32_16x16x32_f16 v[128:131], v[144:147], v[166:169], v[128:131]
	v_mfma_f32_16x16x32_f16 v[136:139], v[194:197], v[166:169], v[136:139]
	v_mfma_f32_16x16x32_f16 v[32:35], v[198:201], v[166:169], v[32:35]
	ds_read_b128 v[162:165], v21 offset:4096
	ds_read_b128 v[166:169], v21 offset:6144
	s_waitcnt lgkmcnt(1)
	v_mfma_f32_16x16x32_f16 v[154:157], v[56:59], v[162:165], v[154:157]
	v_mfma_f32_16x16x32_f16 v[158:161], v[144:147], v[162:165], v[158:161]
	v_mfma_f32_16x16x32_f16 v[190:193], v[194:197], v[162:165], v[190:193]
	v_mfma_f32_16x16x32_f16 v[120:123], v[198:201], v[162:165], v[120:123]
	s_waitcnt lgkmcnt(0)
; DI unsigned pack2(float lo, float hi) { f2_t v = {lo, hi}; h2_t b = __builtin_convertvector(v, h2_t); return __builtin_bit_cast(unsigned, b); }
; DI float lo_f(unsigned u) { return (float)(__builtin_bit_cast(h2_t, u)[0]); }
; DI float hi_f(unsigned u) { return (float)(__builtin_bit_cast(h2_t, u)[1]); }
; #define GL_LOAD(s_, kt_) if (VAR != 1) { a##s_##0 = GL_A(0, kt_); a##s_##1 = GL_A(1, kt_); a##s_##2 = GL_A(2, kt_); a##s_##3 = GL_A(3, kt_); b##s_##0 = GL_B(0, kt_); b##s_##1 = GL_B(1, kt_); b##s_##2 = GL_B(2, kt_); b##s_##3 = GL_B(3, kt_); }
; #define LDS_STORE(s_, buf_) if (VAR != 2) { LDS_ST1(sA, 0, buf_, a##s_##0) LDS_ST1(sA, 1, buf_, a##s_##1) LDS_ST1(sA, 2, buf_, a##s_##2) LDS_ST1(sA, 3, buf_, a##s_##3) LDS_ST1(sB, 0, buf_, b##s_##0) LDS_ST1(sB, 1, buf_, b##s_##1) LDS_ST1(sB, 2, buf_, b##s_##2) LDS_ST1(sB, 3, buf_, b##s_##3) }
;     ...
;   GL_LOAD(0, 0)
;   GL_LOAD(1, 1)
;   LDS_STORE(0, 0)
;   if (VAR != 4) __syncthreads();
; #pragma unroll
;   for (int kt = 0; kt < nk; kt += 2) {
;     if (kt + 2 < nk) { GL_LOAD(0, kt + 2) }
;     MMA_TILE(0)
;     LDS_STORE(1, 1)
;     if (VAR != 4) __syncthreads();
;     if (kt + 3 < nk) { GL_LOAD(1, kt + 3) }
;     MMA_TILE(1)
;     if (kt + 2 < nk) { LDS_STORE(0, 0) }
;     if (VAR != 4) __syncthreads();
; DI void phase_merge(const Params& P, int l, char* smem) {
;     ...
;       for (int mt = 0; mt < 4; ++mt) {
;         const int row = row0 + mt * 16 + lr;
; #pragma unroll
;         for (int nt = 0; nt < 4; ++nt) {
;           const uint2 gu = *(const uint2*)(Pb + (size_t)row * PW + C_GL + br * 1024 + col0 + nt * 16 + 4 * g);
;           float t0 = lo_f(gu.x) * acc[mt][nt][0], t1 = hi_f(gu.x) * acc[mt][nt][1], t2 = lo_f(gu.y) * acc[mt][nt][2], t3 = hi_f(gu.y) * acc[mt][nt][3];
;           if (br > 0) { t0 += lo_f(tot[mt][nt][0]); t1 += hi_f(tot[mt][nt][0]); t2 += lo_f(tot[mt][nt][1]); t3 += hi_f(tot[mt][nt][1]); }
;           tot[mt][nt][0] = pack2(t0, t1); tot[mt][nt][1] = pack2(t2, t3);
;         }
	v_mfma_f32_16x16x32_f16 v[48:51], v[56:59], v[166:169], v[48:51]
	ds_read_b128 v[56:59], v23 offset:32768
	v_mfma_f32_16x16x32_f16 v[24:27], v[144:147], v[166:169], v[24:27]
	v_mfma_f32_16x16x32_f16 v[40:43], v[194:197], v[166:169], v[40:43]
	v_mfma_f32_16x16x32_f16 v[52:55], v[198:201], v[166:169], v[52:55]
	ds_read_b128 v[144:147], v23 offset:34816
	ds_read_b128 v[162:165], v22
	ds_read_b128 v[166:169], v22 offset:2048
	ds_read_b128 v[194:197], v23 offset:36864
	ds_read_b128 v[198:201], v23 offset:38912
	s_waitcnt lgkmcnt(3)
	v_mfma_f32_16x16x32_f16 v[36:39], v[56:59], v[162:165], v[36:39]
	v_mfma_f32_16x16x32_f16 v[44:47], v[144:147], v[162:165], v[44:47]
	s_waitcnt lgkmcnt(1)
	v_mfma_f32_16x16x32_f16 v[132:135], v[194:197], v[162:165], v[132:135]
	s_waitcnt lgkmcnt(0)
	v_mfma_f32_16x16x32_f16 v[28:31], v[198:201], v[162:165], v[28:31]
	v_mfma_f32_16x16x32_f16 v[116:119], v[56:59], v[166:169], v[116:119]
	v_mfma_f32_16x16x32_f16 v[128:131], v[144:147], v[166:169], v[128:131]
	v_mfma_f32_16x16x32_f16 v[136:139], v[194:197], v[166:169], v[136:139]
	v_mfma_f32_16x16x32_f16 v[32:35], v[198:201], v[166:169], v[32:35]
	ds_read_b128 v[162:165], v22 offset:4096
	ds_read_b128 v[166:169], v22 offset:6144
	s_waitcnt vmcnt(7)
	ds_write_b128 v16, v[104:107] offset:16384
	s_waitcnt vmcnt(6)
	ds_write_b128 v17, v[0:3] offset:16384
	s_waitcnt vmcnt(5)
	ds_write_b128 v18, v[140:143] offset:16384
	s_waitcnt vmcnt(4)
	ds_write_b128 v19, v[4:7] offset:16384
	s_waitcnt vmcnt(3)
	ds_write_b128 v16, v[124:127] offset:49152
	s_waitcnt vmcnt(2)
	ds_write_b128 v17, v[8:11] offset:49152
	s_waitcnt vmcnt(1)
	ds_write_b128 v18, v[202:205] offset:49152
	s_waitcnt vmcnt(0)
	ds_write_b128 v19, v[12:15] offset:49152
	s_waitcnt lgkmcnt(0)
	v_mfma_f32_16x16x32_f16 v[154:157], v[56:59], v[162:165], v[154:157]
	s_barrier
	ds_read_b128 v[0:3], v20 offset:49152
	v_mfma_f32_16x16x32_f16 v[48:51], v[56:59], v[166:169], v[48:51]
	ds_read_b128 v[8:11], v20 offset:51200
	ds_read_b128 v[12:15], v21 offset:16384
	ds_read_b128 v[16:19], v21 offset:18432
	ds_read_b128 v[56:59], v20 offset:55296
	v_mfma_f32_16x16x32_f16 v[4:7], v[198:201], v[166:169], v[52:55]
	s_nop 2
	ds_read_b128 v[52:55], v20 offset:53248
	s_waitcnt lgkmcnt(3)
	v_mfma_f32_16x16x32_f16 v[36:39], v[0:3], v[12:15], v[36:39]
	v_mfma_f32_16x16x32_f16 v[44:47], v[8:11], v[12:15], v[44:47]
	s_waitcnt lgkmcnt(0)
	v_mfma_f32_16x16x32_f16 v[104:107], v[52:55], v[12:15], v[132:135]
	v_mfma_f32_16x16x32_f16 v[12:15], v[56:59], v[12:15], v[28:31]
	v_mfma_f32_16x16x32_f16 v[28:31], v[0:3], v[16:19], v[116:119]
	v_mfma_f32_16x16x32_f16 v[116:119], v[8:11], v[16:19], v[128:131]
	v_mfma_f32_16x16x32_f16 v[124:127], v[52:55], v[16:19], v[136:139]
	v_mfma_f32_16x16x32_f16 v[16:19], v[56:59], v[16:19], v[32:35]
	s_nop 2
	ds_read_b128 v[32:35], v21 offset:20480
	ds_read_b128 v[128:131], v21 offset:22528
	v_mfma_f32_16x16x32_f16 v[158:161], v[144:147], v[162:165], v[158:161]
	v_mfma_f32_16x16x32_f16 v[190:193], v[194:197], v[162:165], v[190:193]
	v_mfma_f32_16x16x32_f16 v[120:123], v[198:201], v[162:165], v[120:123]
	v_mfma_f32_16x16x32_f16 v[24:27], v[144:147], v[166:169], v[24:27]
	v_mfma_f32_16x16x32_f16 v[40:43], v[194:197], v[166:169], v[40:43]
	s_waitcnt lgkmcnt(1)
	v_mfma_f32_16x16x32_f16 v[132:135], v[0:3], v[32:35], v[154:157]
	v_mfma_f32_16x16x32_f16 v[136:139], v[8:11], v[32:35], v[158:161]
	s_nop 1
	ds_read_b128 v[154:157], v23 offset:49152
	v_mfma_f32_16x16x32_f16 v[140:143], v[52:55], v[32:35], v[190:193]
	v_mfma_f32_16x16x32_f16 v[120:123], v[56:59], v[32:35], v[120:123]
	s_waitcnt lgkmcnt(1)
	v_mfma_f32_16x16x32_f16 v[0:3], v[0:3], v[128:131], v[48:51]
	v_mfma_f32_16x16x32_f16 v[8:11], v[8:11], v[128:131], v[24:27]
	v_mfma_f32_16x16x32_f16 v[144:147], v[52:55], v[128:131], v[40:43]
	v_mfma_f32_16x16x32_f16 v[128:131], v[56:59], v[128:131], v[4:7]
	s_nop 2
	ds_read_b128 v[4:7], v23 offset:51200
	ds_read_b128 v[24:27], v22 offset:16384
	ds_read_b128 v[32:35], v22 offset:18432
	ds_read_b128 v[162:165], v23 offset:53248
	ds_read_b128 v[166:169], v23 offset:55296
	s_waitcnt lgkmcnt(0)
	v_mfma_f32_16x16x32_f16 v[48:51], v[166:169], v[24:27], v[12:15]
	v_mfma_f32_16x16x32_f16 v[40:43], v[4:7], v[32:35], v[116:119]
	s_nop 1
	ds_read_b128 v[12:15], v22 offset:20480
	ds_read_b128 v[116:119], v22 offset:22528
	s_waitcnt lgkmcnt(0)
	s_barrier
	v_mfma_f32_16x16x32_f16 v[158:161], v[154:157], v[24:27], v[36:39]
	v_mfma_f32_16x16x32_f16 v[56:59], v[4:7], v[24:27], v[44:47]
	v_mfma_f32_16x16x32_f16 v[52:55], v[162:165], v[24:27], v[104:107]
	v_mfma_f32_16x16x32_f16 v[44:47], v[154:157], v[32:35], v[28:31]
	v_mfma_f32_16x16x32_f16 v[36:39], v[162:165], v[32:35], v[124:127]
	v_mfma_f32_16x16x32_f16 v[32:35], v[166:169], v[32:35], v[16:19]
	v_mfma_f32_16x16x32_f16 v[28:31], v[154:157], v[12:15], v[132:135]
	v_mfma_f32_16x16x32_f16 v[24:27], v[4:7], v[12:15], v[136:139]
	v_mfma_f32_16x16x32_f16 v[20:23], v[162:165], v[12:15], v[140:143]
	v_mfma_f32_16x16x32_f16 v[16:19], v[166:169], v[12:15], v[120:123]
	v_mfma_f32_16x16x32_f16 v[12:15], v[154:157], v[116:119], v[0:3]
	s_nop 2
	global_load_dwordx2 v[0:1], v[108:109], off offset:-64
	v_mfma_f32_16x16x32_f16 v[8:11], v[4:7], v[116:119], v[8:11]
	s_waitcnt vmcnt(0)
	v_cvt_f32_f16_e32 v2, v0
	v_cvt_f32_f16_sdwa v3, v0 dst_sel:DWORD dst_unused:UNUSED_PAD src0_sel:WORD_1
	v_cvt_f32_f16_e32 v0, v1
	v_cvt_f32_f16_sdwa v1, v1 dst_sel:DWORD dst_unused:UNUSED_PAD src0_sel:WORD_1
	v_mfma_f32_16x16x32_f16 v[4:7], v[162:165], v[116:119], v[144:147]
	v_mul_f32_e64 v104, v158, v2
	v_mul_f32_e64 v105, v159, v3
	v_pk_mul_f32 v[106:107], v[160:161], v[0:1]
	v_mfma_f32_16x16x32_f16 v[0:3], v[166:169], v[116:119], v[128:131]
	s_cbranch_vccnz .LBB0_1163
	v_cvt_f32_f16_sdwa v117, v102 dst_sel:DWORD dst_unused:UNUSED_PAD src0_sel:WORD_1
	v_cvt_f32_f16_e32 v116, v102
	v_pk_add_f32 v[104:105], v[104:105], v[116:117]
	v_cvt_f32_f16_sdwa v117, v103 dst_sel:DWORD dst_unused:UNUSED_PAD src0_sel:WORD_1
	v_cvt_f32_f16_e32 v116, v103
	v_pk_add_f32 v[106:107], v[106:107], v[116:117]

; DI int TIDX() { int t = threadIdx.x; asm volatile("" : "+v"(t)); return t; }
; DI int BIDX() { int b = blockIdx.x; asm volatile("" : "+s"(b)); return b; }
; #define GL_LOAD(s_, kt_) if (VAR != 1) { a##s_##0 = GL_A(0, kt_); a##s_##1 = GL_A(1, kt_); a##s_##2 = GL_A(2, kt_); a##s_##3 = GL_A(3, kt_); b##s_##0 = GL_B(0, kt_); b##s_##1 = GL_B(1, kt_); b##s_##2 = GL_B(2, kt_); b##s_##3 = GL_B(3, kt_); }
; #define LDS_STORE(s_, buf_) if (VAR != 2) { LDS_ST1(sA, 0, buf_, a##s_##0) LDS_ST1(sA, 1, buf_, a##s_##1) LDS_ST1(sA, 2, buf_, a##s_##2) LDS_ST1(sA, 3, buf_, a##s_##3) LDS_ST1(sB, 0, buf_, b##s_##0) LDS_ST1(sB, 1, buf_, b##s_##1) LDS_ST1(sB, 2, buf_, b##s_##2) LDS_ST1(sB, 3, buf_, b##s_##3) }
; DI int tile_groups(int MT, int NT) { return (MT >> 6) * ((NT + 7) >> 3) * 512; }
;   const int tid = TIDX(), lane = tid & 63, wid = tid >> 6, wm = wid >> 1, wn = wid & 1, lr = lane & 15, g = lane >> 4;
;   char* sA = smem; char* sB = smem + 2 * LTILE;
;   uint4 a00 = {}, a01 = {}, a02 = {}, a03 = {}, b00 = {}, b01 = {}, b02 = {}, b03 = {}, a10 = {}, a11 = {}, a12 = {}, a13 = {}, b10 = {}, b11 = {}, b12 = {}, b13 = {};
;   constexpr int nk = NK;
;   const int sw0 = (g ^ ((lr >> 1) & 7)) << 4, sw1 = sw0 ^ 64;
;   const int r0 = tid >> 3, kc = tid & 7, kcs = kc ^ ((r0 >> 1) & 7);
;     ...
;   GL_LOAD(0, 0)
;   GL_LOAD(1, 1)
;   LDS_STORE(0, 0)
;   if (VAR != 4) __syncthreads();
; #pragma unroll
;   for (int kt = 0; kt < nk; kt += 2) {
;     if (kt + 2 < nk) { GL_LOAD(0, kt + 2) }
;     MMA_TILE(0)
; DI void phase_resgemm(const Params& P, const bf16_t* A, int K, const bf16_t* Wt, float* ssq_out, const float* xsrc, char* smem) {
;     ...
;   for (int vb = BIDX(); vb < tile_groups(128, 8); vb += gridDim.x) {
;     int tm, tn; if (!tile_of(vb, 128, 8, tm, tn)) continue;
;     const int m0 = tm * 128, n0 = tn * 128;
;     f32x4 acc[4][4]; zero_acc(acc);
;     if (K == 1024) gemm_kloop<false, true, 16>(acc, A + (size_t)m0 * K, K, Wt + (size_t)n0 * K, K, smem);
;     else gemm_kloop<false, true, 64>(acc, A + (size_t)m0 * K, K, Wt + (size_t)n0 * K, K, smem);
.LBB0_1249:
	s_ashr_i32 s6, s1, 3
	s_andn2_b32 s6, s6, 63
	s_and_b32 s7, s10, 56
	s_or_b32 s6, s6, s7
	s_bfe_u32 s7, s1, 0x30003
	s_or_b32 s6, s6, s7
	s_cmpk_gt_i32 s6, 0x7f
	s_cbranch_scc1 .LBB0_1248
	s_lshl_b32 s6, s6, 7
	s_ashr_i32 s7, s6, 31
	v_mov_b32_e32 v20, v148
	s_and_b32 s11, s9, 0x380
	s_lshl_b64 s[12:13], s[6:7], 11
	v_readlane_b32 s14, v253, 19
	v_readlane_b32 s15, v253, 20
	v_ashrrev_i32_e32 v16, 3, v20
	s_add_u32 s12, s14, s12
	v_ashrrev_i32_e32 v17, 31, v16
	v_add_u32_e32 v18, 32, v16
	s_addc_u32 s13, s15, s13
	v_lshlrev_b64 v[8:9], 11, v[16:17]
	v_lshlrev_b32_e32 v17, 4, v20
	v_ashrrev_i32_e32 v19, 31, v18
	v_add_u32_e32 v54, 64, v16
	s_waitcnt lgkmcnt(0)
	v_lshl_add_u64 v[0:1], s[12:13], 0, v[8:9]
	v_and_b32_e32 v150, 0x70, v17
	v_lshlrev_b64 v[10:11], 11, v[18:19]
	v_ashrrev_i32_e32 v55, 31, v54
	v_add_u32_e32 v58, 0x60, v16
	s_lshl_b32 s7, s11, 11
	v_lshl_add_u64 v[0:1], v[0:1], 0, v[150:151]
	v_lshl_add_u64 v[2:3], s[12:13], 0, v[10:11]
	v_lshlrev_b64 v[12:13], 11, v[54:55]
	v_ashrrev_i32_e32 v59, 31, v58
	s_add_u32 s14, s2, s7
	global_load_dwordx4 v[22:25], v[0:1], off
	v_lshl_add_u64 v[2:3], v[2:3], 0, v[150:151]
	v_lshl_add_u64 v[4:5], s[12:13], 0, v[12:13]
	v_lshlrev_b64 v[14:15], 11, v[58:59]
	s_addc_u32 s15, s8, 0
	global_load_dwordx4 v[26:29], v[2:3], off
	v_lshl_add_u64 v[4:5], v[4:5], 0, v[150:151]
	v_lshl_add_u64 v[6:7], s[12:13], 0, v[14:15]
	global_load_dwordx4 v[30:33], v[4:5], off
	v_lshl_add_u64 v[6:7], v[6:7], 0, v[150:151]
	v_lshl_add_u64 v[8:9], s[14:15], 0, v[8:9]
	global_load_dwordx4 v[34:37], v[6:7], off
	v_lshl_add_u64 v[8:9], v[8:9], 0, v[150:151]
	v_lshl_add_u64 v[10:11], s[14:15], 0, v[10:11]
	global_load_dwordx4 v[38:41], v[8:9], off
	v_lshl_add_u64 v[10:11], v[10:11], 0, v[150:151]
	v_lshl_add_u64 v[12:13], s[14:15], 0, v[12:13]
	global_load_dwordx4 v[42:45], v[10:11], off
	v_lshl_add_u64 v[12:13], v[12:13], 0, v[150:151]
	v_lshl_add_u64 v[14:15], s[14:15], 0, v[14:15]
	global_load_dwordx4 v[46:49], v[12:13], off
	v_lshl_add_u64 v[14:15], v[14:15], 0, v[150:151]
	global_load_dwordx4 v[50:53], v[14:15], off
	v_lshlrev_b32_e32 v21, 3, v20
	v_and_b32_e32 v55, 48, v20
	v_and_b32_e32 v19, 15, v20
	v_lshrrev_b32_e32 v59, 1, v20
	s_waitcnt vmcnt(10)
	v_lshlrev_b32_e32 v60, 7, v20
	v_and_b32_e32 v90, 0x70, v21
	v_bitop3_b32 v134, v21, v55, s23 bitop3:0x6c
	v_bitop3_b32 v21, v17, s23, v20 bitop3:0x48
	v_and_or_b32 v91, v59, s24, v19
	v_and_b32_e32 v130, 0x2780, v60
	v_lshl_or_b32 v20, v18, 7, v21
	v_lshl_or_b32 v18, v58, 7, v21
	global_load_dwordx4 v[58:61], v[0:1], off offset:128
	global_load_dwordx4 v[62:65], v[2:3], off offset:128
	global_load_dwordx4 v[66:69], v[4:5], off offset:128
	global_load_dwordx4 v[70:73], v[6:7], off offset:128
	global_load_dwordx4 v[74:77], v[8:9], off offset:128
	global_load_dwordx4 v[78:81], v[10:11], off offset:128
	global_load_dwordx4 v[82:85], v[12:13], off offset:128
	global_load_dwordx4 v[86:89], v[14:15], off offset:128
	v_lshl_or_b32 v19, v16, 7, v21
	v_or_b32_e32 v16, v130, v134
	v_lshl_or_b32 v17, v54, 7, v21
	v_lshlrev_b32_e32 v54, 7, v91
	v_bitop3_b32 v21, v54, v90, v55 bitop3:0xf6
	v_readlane_b32 s12, v254, 55
	v_readlane_b32 s13, v254, 56
	v_readlane_b32 s14, v254, 57
	v_readlane_b32 s15, v254, 58
	s_waitcnt vmcnt(15)
	ds_write_b128 v19, v[22:25]
	s_waitcnt vmcnt(14)
	ds_write_b128 v20, v[26:29]
	s_waitcnt vmcnt(13)
	ds_write_b128 v17, v[30:33]
	s_waitcnt vmcnt(12)
	ds_write_b128 v18, v[34:37]
	s_waitcnt vmcnt(11)
	ds_write_b128 v19, v[38:41] offset:32768
	s_waitcnt vmcnt(10)
	ds_write_b128 v20, v[42:45] offset:32768
	s_waitcnt vmcnt(9)
	ds_write_b128 v17, v[46:49] offset:32768
	s_waitcnt vmcnt(8)
	ds_write_b128 v18, v[50:53] offset:32768
	s_waitcnt lgkmcnt(0)
	s_barrier
	ds_read_b128 v[22:25], v16 offset:32768
	ds_read_b128 v[30:33], v21
	s_waitcnt lgkmcnt(0)
	v_mfma_f32_16x16x32_f16 v[38:41], v[22:25], v[30:33], 0
	ds_read_b128 v[26:29], v16 offset:34816
	ds_read_b128 v[34:37], v21 offset:2048
	s_waitcnt lgkmcnt(0)
	v_mfma_f32_16x16x32_f16 v[94:97], v[22:25], v[34:37], 0
	ds_read_b128 v[42:45], v16 offset:36864
	ds_read_b128 v[106:109], v21 offset:4096
	s_waitcnt lgkmcnt(0)
	v_mfma_f32_16x16x32_f16 v[114:117], v[22:25], v[106:109], 0
	ds_read_b128 v[50:53], v16 offset:38912
	ds_read_b128 v[110:113], v21 offset:6144
	s_waitcnt lgkmcnt(0)
	v_mfma_f32_16x16x32_f16 v[126:129], v[22:25], v[110:113], 0
	v_xor_b32_e32 v22, 64, v134
	v_mfma_f32_16x16x32_f16 v[46:49], v[26:29], v[30:33], 0
	v_or_b32_e32 v22, v130, v22
	v_mfma_f32_16x16x32_f16 v[90:93], v[42:45], v[30:33], 0
	ds_read_b128 v[130:133], v22 offset:32768
	v_mfma_f32_16x16x32_f16 v[30:33], v[50:53], v[30:33], 0
	ds_read_b128 v[142:145], v22 offset:36864
	v_mfma_f32_16x16x32_f16 v[98:101], v[26:29], v[34:37], 0
	ds_read_b128 v[154:157], v22 offset:38912
	v_mfma_f32_16x16x32_f16 v[102:105], v[42:45], v[34:37], 0
	v_bitop3_b32 v23, v54, v134, 64 bitop3:0xf6
	v_mfma_f32_16x16x32_f16 v[34:37], v[50:53], v[34:37], 0
	ds_read_b128 v[134:137], v23
	v_mfma_f32_16x16x32_f16 v[118:121], v[26:29], v[106:109], 0
	ds_read_b128 v[138:141], v23 offset:2048
	v_mfma_f32_16x16x32_f16 v[122:125], v[42:45], v[106:109], 0
	v_mfma_f32_16x16x32_f16 v[106:109], v[50:53], v[106:109], 0
	s_waitcnt vmcnt(7)
	ds_write_b128 v19, v[58:61] offset:16384
	v_mfma_f32_16x16x32_f16 v[24:27], v[26:29], v[110:113], 0
	s_waitcnt vmcnt(6)
	ds_write_b128 v20, v[62:65] offset:16384
	v_mfma_f32_16x16x32_f16 v[42:45], v[42:45], v[110:113], 0
	s_waitcnt vmcnt(5)
	ds_write_b128 v17, v[66:69] offset:16384
	v_mfma_f32_16x16x32_f16 v[50:53], v[50:53], v[110:113], 0
	ds_read_b128 v[110:113], v22 offset:34816
	s_waitcnt lgkmcnt(5)
; #define GL_LOAD(s_, kt_) if (VAR != 1) { a##s_##0 = GL_A(0, kt_); a##s_##1 = GL_A(1, kt_); a##s_##2 = GL_A(2, kt_); a##s_##3 = GL_A(3, kt_); b##s_##0 = GL_B(0, kt_); b##s_##1 = GL_B(1, kt_); b##s_##2 = GL_B(2, kt_); b##s_##3 = GL_B(3, kt_); }
; #define LDS_STORE(s_, buf_) if (VAR != 2) { LDS_ST1(sA, 0, buf_, a##s_##0) LDS_ST1(sA, 1, buf_, a##s_##1) LDS_ST1(sA, 2, buf_, a##s_##2) LDS_ST1(sA, 3, buf_, a##s_##3) LDS_ST1(sB, 0, buf_, b##s_##0) LDS_ST1(sB, 1, buf_, b##s_##1) LDS_ST1(sB, 2, buf_, b##s_##2) LDS_ST1(sB, 3, buf_, b##s_##3) }
;     ...
;   for (int kt = 0; kt < nk; kt += 2) {
;     if (kt + 2 < nk) { GL_LOAD(0, kt + 2) }
;     MMA_TILE(0)
;     LDS_STORE(1, 1)
;     if (VAR != 4) __syncthreads();
;     if (kt + 3 < nk) { GL_LOAD(1, kt + 3) }
;     MMA_TILE(1)
;     if (kt + 2 < nk) { LDS_STORE(0, 0) }
;     if (VAR != 4) __syncthreads();
	v_mfma_f32_16x16x32_f16 v[38:41], v[130:133], v[134:137], v[38:41]
	s_waitcnt vmcnt(4)
	ds_write_b128 v18, v[70:73] offset:16384
	v_mfma_f32_16x16x32_f16 v[90:93], v[142:145], v[134:137], v[90:93]
	s_waitcnt vmcnt(3)
	ds_write_b128 v19, v[74:77] offset:49152
	v_mfma_f32_16x16x32_f16 v[28:31], v[154:157], v[134:137], v[30:33]
	s_waitcnt vmcnt(2)
	ds_write_b128 v20, v[78:81] offset:49152
	s_waitcnt lgkmcnt(7)
	v_mfma_f32_16x16x32_f16 v[94:97], v[130:133], v[138:141], v[94:97]
	s_waitcnt vmcnt(1)
	ds_write_b128 v17, v[82:85] offset:49152
	v_mfma_f32_16x16x32_f16 v[102:105], v[142:145], v[138:141], v[102:105]
	s_waitcnt vmcnt(0)
	ds_write_b128 v18, v[86:89] offset:49152
	v_mfma_f32_16x16x32_f16 v[32:35], v[154:157], v[138:141], v[34:37]
	s_waitcnt lgkmcnt(5)
	v_mfma_f32_16x16x32_f16 v[46:49], v[110:113], v[134:137], v[46:49]
	ds_read_b128 v[134:137], v23 offset:4096
	v_mfma_f32_16x16x32_f16 v[98:101], v[110:113], v[138:141], v[98:101]
	ds_read_b128 v[138:141], v23 offset:6144
	s_waitcnt lgkmcnt(1)
	v_mfma_f32_16x16x32_f16 v[114:117], v[130:133], v[134:137], v[114:117]
	s_waitcnt lgkmcnt(0)
	v_mfma_f32_16x16x32_f16 v[126:129], v[130:133], v[138:141], v[126:129]
	global_load_dwordx4 v[130:133], v[0:1], off offset:256
	v_mfma_f32_16x16x32_f16 v[118:121], v[110:113], v[134:137], v[118:121]
	v_mfma_f32_16x16x32_f16 v[24:27], v[110:113], v[138:141], v[24:27]
	v_mfma_f32_16x16x32_f16 v[122:125], v[142:145], v[134:137], v[122:125]
	v_mfma_f32_16x16x32_f16 v[106:109], v[154:157], v[134:137], v[106:109]
	global_load_dwordx4 v[134:137], v[2:3], off offset:256
	global_load_dwordx4 v[158:161], v[4:5], off offset:256
	global_load_dwordx4 v[162:165], v[6:7], off offset:256
	global_load_dwordx4 v[110:113], v[8:9], off offset:256
	global_load_dwordx4 v[166:169], v[10:11], off offset:256
	global_load_dwordx4 v[190:193], v[12:13], off offset:256
	global_load_dwordx4 v[194:197], v[14:15], off offset:256
	s_waitcnt lgkmcnt(0)
	s_barrier
	v_mfma_f32_16x16x32_f16 v[42:45], v[142:145], v[138:141], v[42:45]
	ds_read_b128 v[58:61], v16 offset:49152
	v_mfma_f32_16x16x32_f16 v[50:53], v[154:157], v[138:141], v[50:53]
	ds_read_b128 v[62:65], v16 offset:51200
	ds_read_b128 v[66:69], v21 offset:16384
	s_waitcnt lgkmcnt(0)
	v_mfma_f32_16x16x32_f16 v[36:39], v[58:61], v[66:69], v[38:41]
	ds_read_b128 v[70:73], v21 offset:18432
	v_mfma_f32_16x16x32_f16 v[46:49], v[62:65], v[66:69], v[46:49]
	ds_read_b128 v[74:77], v16 offset:53248
	s_waitcnt lgkmcnt(0)
	v_mfma_f32_16x16x32_f16 v[82:85], v[74:77], v[66:69], v[90:93]
	ds_read_b128 v[78:81], v16 offset:55296
	s_waitcnt lgkmcnt(0)
	v_mfma_f32_16x16x32_f16 v[28:31], v[78:81], v[66:69], v[28:31]
	v_mfma_f32_16x16x32_f16 v[66:69], v[58:61], v[70:73], v[94:97]
	s_nop 2
	ds_read_b128 v[94:97], v21 offset:22528
	v_mfma_f32_16x16x32_f16 v[86:89], v[62:65], v[70:73], v[98:101]
	v_mfma_f32_16x16x32_f16 v[90:93], v[74:77], v[70:73], v[102:105]
	v_mfma_f32_16x16x32_f16 v[32:35], v[78:81], v[70:73], v[32:35]
	ds_read_b128 v[70:73], v21 offset:20480
	s_waitcnt lgkmcnt(0)
	v_mfma_f32_16x16x32_f16 v[98:101], v[58:61], v[70:73], v[114:117]
	v_mfma_f32_16x16x32_f16 v[58:61], v[58:61], v[94:97], v[126:129]
	v_mfma_f32_16x16x32_f16 v[102:105], v[62:65], v[70:73], v[118:121]
	s_nop 2
	ds_read_b128 v[118:121], v22 offset:55296
	v_mfma_f32_16x16x32_f16 v[24:27], v[62:65], v[94:97], v[24:27]
	ds_read_b128 v[62:65], v22 offset:49152
	s_waitcnt vmcnt(7)
	ds_write_b128 v19, v[130:133]
	v_mfma_f32_16x16x32_f16 v[114:117], v[74:77], v[70:73], v[122:125]
	s_waitcnt vmcnt(6)
	ds_write_b128 v20, v[134:137]
	s_waitcnt vmcnt(5)
	ds_write_b128 v17, v[158:161]
	v_mfma_f32_16x16x32_f16 v[40:43], v[74:77], v[94:97], v[42:45]
	ds_read_b128 v[74:77], v22 offset:51200
	v_mfma_f32_16x16x32_f16 v[70:73], v[78:81], v[70:73], v[106:109]
	s_nop 2
	ds_read_b128 v[106:109], v22 offset:53248
	v_mfma_f32_16x16x32_f16 v[50:53], v[78:81], v[94:97], v[50:53]
	ds_read_b128 v[78:81], v23 offset:16384
	s_waitcnt lgkmcnt(0)
	v_mfma_f32_16x16x32_f16 v[36:39], v[62:65], v[78:81], v[36:39]
	ds_read_b128 v[94:97], v23 offset:18432
	s_waitcnt lgkmcnt(0)
	v_mfma_f32_16x16x32_f16 v[66:69], v[62:65], v[94:97], v[66:69]
	s_waitcnt vmcnt(4)
	ds_write_b128 v18, v[162:165]
	v_mfma_f32_16x16x32_f16 v[44:47], v[74:77], v[78:81], v[46:49]
	s_waitcnt vmcnt(3)
	ds_write_b128 v19, v[110:113] offset:32768
	v_mfma_f32_16x16x32_f16 v[82:85], v[106:109], v[78:81], v[82:85]
	v_mfma_f32_16x16x32_f16 v[28:31], v[118:121], v[78:81], v[28:31]
	v_mfma_f32_16x16x32_f16 v[78:81], v[74:77], v[94:97], v[86:89]
	s_waitcnt vmcnt(2)
	ds_write_b128 v20, v[166:169] offset:32768
	s_waitcnt vmcnt(1)
	ds_write_b128 v17, v[190:193] offset:32768
	s_waitcnt vmcnt(0)
	ds_write_b128 v18, v[194:197] offset:32768
	v_mfma_f32_16x16x32_f16 v[86:89], v[106:109], v[94:97], v[90:93]
	s_nop 2
	ds_read_b128 v[90:93], v23 offset:20480
	v_mfma_f32_16x16x32_f16 v[32:35], v[118:121], v[94:97], v[32:35]
	ds_read_b128 v[94:97], v23 offset:22528
	s_waitcnt lgkmcnt(1)
	v_mfma_f32_16x16x32_f16 v[98:101], v[62:65], v[90:93], v[98:101]
	s_waitcnt lgkmcnt(0)
	v_mfma_f32_16x16x32_f16 v[58:61], v[62:65], v[94:97], v[58:61]
	global_load_dwordx4 v[62:65], v[0:1], off offset:384
	v_mfma_f32_16x16x32_f16 v[102:105], v[74:77], v[90:93], v[102:105]
	v_mfma_f32_16x16x32_f16 v[24:27], v[74:77], v[94:97], v[24:27]
	v_mfma_f32_16x16x32_f16 v[114:117], v[106:109], v[90:93], v[114:117]
	v_mfma_f32_16x16x32_f16 v[40:43], v[106:109], v[94:97], v[40:43]
	v_mfma_f32_16x16x32_f16 v[70:73], v[118:121], v[90:93], v[70:73]
	global_load_dwordx4 v[90:93], v[2:3], off offset:384
	global_load_dwordx4 v[122:125], v[4:5], off offset:384
	global_load_dwordx4 v[126:129], v[6:7], off offset:384
	global_load_dwordx4 v[74:77], v[8:9], off offset:384
	global_load_dwordx4 v[138:141], v[10:11], off offset:384
	global_load_dwordx4 v[142:145], v[12:13], off offset:384
	global_load_dwordx4 v[154:157], v[14:15], off offset:384
	s_waitcnt lgkmcnt(0)
	s_barrier
; #define GL_LOAD(s_, kt_) if (VAR != 1) { a##s_##0 = GL_A(0, kt_); a##s_##1 = GL_A(1, kt_); a##s_##2 = GL_A(2, kt_); a##s_##3 = GL_A(3, kt_); b##s_##0 = GL_B(0, kt_); b##s_##1 = GL_B(1, kt_); b##s_##2 = GL_B(2, kt_); b##s_##3 = GL_B(3, kt_); }
; #define LDS_STORE(s_, buf_) if (VAR != 2) { LDS_ST1(sA, 0, buf_, a##s_##0) LDS_ST1(sA, 1, buf_, a##s_##1) LDS_ST1(sA, 2, buf_, a##s_##2) LDS_ST1(sA, 3, buf_, a##s_##3) LDS_ST1(sB, 0, buf_, b##s_##0) LDS_ST1(sB, 1, buf_, b##s_##1) LDS_ST1(sB, 2, buf_, b##s_##2) LDS_ST1(sB, 3, buf_, b##s_##3) }
;     ...
;   for (int kt = 0; kt < nk; kt += 2) {
;     if (kt + 2 < nk) { GL_LOAD(0, kt + 2) }
;     MMA_TILE(0)
;     LDS_STORE(1, 1)
;     if (VAR != 4) __syncthreads();
;     if (kt + 3 < nk) { GL_LOAD(1, kt + 3) }
;     MMA_TILE(1)
;     if (kt + 2 < nk) { LDS_STORE(0, 0) }
;     if (VAR != 4) __syncthreads();
	v_mfma_f32_16x16x32_f16 v[48:51], v[118:121], v[94:97], v[50:53]
	ds_read_b128 v[106:109], v16 offset:32768
	ds_read_b128 v[94:97], v21
	s_waitcnt lgkmcnt(0)
	v_mfma_f32_16x16x32_f16 v[36:39], v[106:109], v[94:97], v[36:39]
	ds_read_b128 v[52:55], v16 offset:34816
	ds_read_b128 v[110:113], v21 offset:2048
	s_waitcnt lgkmcnt(0)
	v_mfma_f32_16x16x32_f16 v[66:69], v[106:109], v[110:113], v[66:69]
	ds_read_b128 v[118:121], v16 offset:36864
	v_mfma_f32_16x16x32_f16 v[44:47], v[52:55], v[94:97], v[44:47]
	ds_read_b128 v[130:133], v16 offset:38912
	v_mfma_f32_16x16x32_f16 v[78:81], v[52:55], v[110:113], v[78:81]
	s_waitcnt lgkmcnt(1)
	v_mfma_f32_16x16x32_f16 v[82:85], v[118:121], v[94:97], v[82:85]
	v_mfma_f32_16x16x32_f16 v[86:89], v[118:121], v[110:113], v[86:89]
	s_waitcnt lgkmcnt(0)
	v_mfma_f32_16x16x32_f16 v[28:31], v[130:133], v[94:97], v[28:31]
	ds_read_b128 v[94:97], v21 offset:4096
	v_mfma_f32_16x16x32_f16 v[32:35], v[130:133], v[110:113], v[32:35]
	ds_read_b128 v[110:113], v21 offset:6144
	s_waitcnt lgkmcnt(1)
	v_mfma_f32_16x16x32_f16 v[98:101], v[106:109], v[94:97], v[98:101]
	s_waitcnt lgkmcnt(0)
	v_mfma_f32_16x16x32_f16 v[58:61], v[106:109], v[110:113], v[58:61]
	ds_read_b128 v[106:109], v23
	v_mfma_f32_16x16x32_f16 v[102:105], v[52:55], v[94:97], v[102:105]
	v_mfma_f32_16x16x32_f16 v[24:27], v[52:55], v[110:113], v[24:27]
	ds_read_b128 v[52:55], v22 offset:32768
	v_mfma_f32_16x16x32_f16 v[114:117], v[118:121], v[94:97], v[114:117]
	s_waitcnt vmcnt(7)
	ds_write_b128 v19, v[62:65] offset:16384
	s_waitcnt vmcnt(6)
	ds_write_b128 v20, v[90:93] offset:16384
	v_mfma_f32_16x16x32_f16 v[40:43], v[118:121], v[110:113], v[40:43]
	ds_read_b128 v[118:121], v22 offset:36864
	s_waitcnt vmcnt(5)
	ds_write_b128 v17, v[122:125] offset:16384
	v_mfma_f32_16x16x32_f16 v[70:73], v[130:133], v[94:97], v[70:73]
	ds_read_b128 v[94:97], v22 offset:34816
	v_mfma_f32_16x16x32_f16 v[48:51], v[130:133], v[110:113], v[48:51]
	ds_read_b128 v[110:113], v23 offset:2048
	s_waitcnt lgkmcnt(6)
	v_mfma_f32_16x16x32_f16 v[36:39], v[52:55], v[106:109], v[36:39]
	ds_read_b128 v[130:133], v22 offset:38912
	s_waitcnt lgkmcnt(1)
	v_mfma_f32_16x16x32_f16 v[66:69], v[52:55], v[110:113], v[66:69]
	s_waitcnt vmcnt(4)
	ds_write_b128 v18, v[126:129] offset:16384
	v_mfma_f32_16x16x32_f16 v[44:47], v[94:97], v[106:109], v[44:47]
	s_waitcnt vmcnt(3)
	ds_write_b128 v19, v[74:77] offset:49152
	v_mfma_f32_16x16x32_f16 v[78:81], v[94:97], v[110:113], v[78:81]
	s_waitcnt vmcnt(2)
	ds_write_b128 v20, v[138:141] offset:49152
	v_mfma_f32_16x16x32_f16 v[82:85], v[118:121], v[106:109], v[82:85]
	s_waitcnt vmcnt(1)
	ds_write_b128 v17, v[142:145] offset:49152
	v_mfma_f32_16x16x32_f16 v[86:89], v[118:121], v[110:113], v[86:89]
	s_waitcnt vmcnt(0)
	ds_write_b128 v18, v[154:157] offset:49152
	s_waitcnt lgkmcnt(5)
	v_mfma_f32_16x16x32_f16 v[28:31], v[130:133], v[106:109], v[28:31]
	ds_read_b128 v[106:109], v23 offset:4096
	v_mfma_f32_16x16x32_f16 v[32:35], v[130:133], v[110:113], v[32:35]
	ds_read_b128 v[110:113], v23 offset:6144
	s_waitcnt lgkmcnt(1)
	v_mfma_f32_16x16x32_f16 v[98:101], v[52:55], v[106:109], v[98:101]
	s_waitcnt lgkmcnt(0)
	v_mfma_f32_16x16x32_f16 v[52:55], v[52:55], v[110:113], v[58:61]
	s_nop 2
	global_load_dwordx4 v[58:61], v[0:1], off offset:512
	v_mfma_f32_16x16x32_f16 v[102:105], v[94:97], v[106:109], v[102:105]
	v_mfma_f32_16x16x32_f16 v[24:27], v[94:97], v[110:113], v[24:27]
	v_mfma_f32_16x16x32_f16 v[114:117], v[118:121], v[106:109], v[114:117]
	v_mfma_f32_16x16x32_f16 v[40:43], v[118:121], v[110:113], v[40:43]
	v_mfma_f32_16x16x32_f16 v[70:73], v[130:133], v[106:109], v[70:73]
	global_load_dwordx4 v[106:109], v[2:3], off offset:512
	global_load_dwordx4 v[134:137], v[4:5], off offset:512
	global_load_dwordx4 v[158:161], v[6:7], off offset:512
	global_load_dwordx4 v[94:97], v[8:9], off offset:512
	global_load_dwordx4 v[162:165], v[10:11], off offset:512
	global_load_dwordx4 v[166:169], v[12:13], off offset:512
	global_load_dwordx4 v[190:193], v[14:15], off offset:512
	s_waitcnt lgkmcnt(0)
	s_barrier
	v_mfma_f32_16x16x32_f16 v[48:51], v[130:133], v[110:113], v[48:51]
	ds_read_b128 v[62:65], v16 offset:49152
	ds_read_b128 v[90:93], v21 offset:16384
	s_waitcnt lgkmcnt(0)
	v_mfma_f32_16x16x32_f16 v[36:39], v[62:65], v[90:93], v[36:39]
	ds_read_b128 v[74:77], v16 offset:51200
	ds_read_b128 v[110:113], v21 offset:18432
	s_waitcnt lgkmcnt(0)
	v_mfma_f32_16x16x32_f16 v[66:69], v[62:65], v[110:113], v[66:69]
	ds_read_b128 v[118:121], v16 offset:53248
	v_mfma_f32_16x16x32_f16 v[44:47], v[74:77], v[90:93], v[44:47]
	ds_read_b128 v[122:125], v16 offset:55296
	v_mfma_f32_16x16x32_f16 v[78:81], v[74:77], v[110:113], v[78:81]
	s_waitcnt lgkmcnt(1)
	v_mfma_f32_16x16x32_f16 v[82:85], v[118:121], v[90:93], v[82:85]
	v_mfma_f32_16x16x32_f16 v[86:89], v[118:121], v[110:113], v[86:89]
	s_waitcnt lgkmcnt(0)
	v_mfma_f32_16x16x32_f16 v[28:31], v[122:125], v[90:93], v[28:31]
	ds_read_b128 v[90:93], v21 offset:20480
	v_mfma_f32_16x16x32_f16 v[32:35], v[122:125], v[110:113], v[32:35]
	ds_read_b128 v[110:113], v21 offset:22528
	s_waitcnt lgkmcnt(1)
	v_mfma_f32_16x16x32_f16 v[98:101], v[62:65], v[90:93], v[98:101]
	s_waitcnt lgkmcnt(0)
	v_mfma_f32_16x16x32_f16 v[52:55], v[62:65], v[110:113], v[52:55]
	ds_read_b128 v[62:65], v22 offset:49152
	v_mfma_f32_16x16x32_f16 v[102:105], v[74:77], v[90:93], v[102:105]
	v_mfma_f32_16x16x32_f16 v[24:27], v[74:77], v[110:113], v[24:27]
	ds_read_b128 v[74:77], v22 offset:51200
	v_mfma_f32_16x16x32_f16 v[114:117], v[118:121], v[90:93], v[114:117]
	s_waitcnt vmcnt(7)
	ds_write_b128 v19, v[58:61]
	s_waitcnt vmcnt(6)
; #define GL_LOAD(s_, kt_) if (VAR != 1) { a##s_##0 = GL_A(0, kt_); a##s_##1 = GL_A(1, kt_); a##s_##2 = GL_A(2, kt_); a##s_##3 = GL_A(3, kt_); b##s_##0 = GL_B(0, kt_); b##s_##1 = GL_B(1, kt_); b##s_##2 = GL_B(2, kt_); b##s_##3 = GL_B(3, kt_); }
; #define LDS_STORE(s_, buf_) if (VAR != 2) { LDS_ST1(sA, 0, buf_, a##s_##0) LDS_ST1(sA, 1, buf_, a##s_##1) LDS_ST1(sA, 2, buf_, a##s_##2) LDS_ST1(sA, 3, buf_, a##s_##3) LDS_ST1(sB, 0, buf_, b##s_##0) LDS_ST1(sB, 1, buf_, b##s_##1) LDS_ST1(sB, 2, buf_, b##s_##2) LDS_ST1(sB, 3, buf_, b##s_##3) }
;     ...
;   for (int kt = 0; kt < nk; kt += 2) {
;     if (kt + 2 < nk) { GL_LOAD(0, kt + 2) }
;     MMA_TILE(0)
;     LDS_STORE(1, 1)
;     if (VAR != 4) __syncthreads();
;     if (kt + 3 < nk) { GL_LOAD(1, kt + 3) }
;     MMA_TILE(1)
;     if (kt + 2 < nk) { LDS_STORE(0, 0) }
;     if (VAR != 4) __syncthreads();
	ds_write_b128 v20, v[106:109]
	v_mfma_f32_16x16x32_f16 v[40:43], v[118:121], v[110:113], v[40:43]
	ds_read_b128 v[118:121], v22 offset:53248
	s_waitcnt vmcnt(5)
	ds_write_b128 v17, v[134:137]
	v_mfma_f32_16x16x32_f16 v[70:73], v[122:125], v[90:93], v[70:73]
	ds_read_b128 v[90:93], v23 offset:16384
	v_mfma_f32_16x16x32_f16 v[48:51], v[122:125], v[110:113], v[48:51]
	ds_read_b128 v[110:113], v23 offset:18432
	s_waitcnt lgkmcnt(1)
	v_mfma_f32_16x16x32_f16 v[36:39], v[62:65], v[90:93], v[36:39]
	ds_read_b128 v[122:125], v22 offset:55296
	s_waitcnt lgkmcnt(1)
	v_mfma_f32_16x16x32_f16 v[66:69], v[62:65], v[110:113], v[66:69]
	s_waitcnt vmcnt(4)
	ds_write_b128 v18, v[158:161]
	v_mfma_f32_16x16x32_f16 v[44:47], v[74:77], v[90:93], v[44:47]
	s_waitcnt vmcnt(3)
	ds_write_b128 v19, v[94:97] offset:32768
	v_mfma_f32_16x16x32_f16 v[78:81], v[74:77], v[110:113], v[78:81]
	s_waitcnt vmcnt(2)
	ds_write_b128 v20, v[162:165] offset:32768
	v_mfma_f32_16x16x32_f16 v[82:85], v[118:121], v[90:93], v[82:85]
	s_waitcnt vmcnt(1)
	ds_write_b128 v17, v[166:169] offset:32768
	v_mfma_f32_16x16x32_f16 v[86:89], v[118:121], v[110:113], v[86:89]
	s_waitcnt vmcnt(0)
	ds_write_b128 v18, v[190:193] offset:32768
	s_waitcnt lgkmcnt(5)
	v_mfma_f32_16x16x32_f16 v[28:31], v[122:125], v[90:93], v[28:31]
	ds_read_b128 v[90:93], v23 offset:20480
	v_mfma_f32_16x16x32_f16 v[32:35], v[122:125], v[110:113], v[32:35]
	ds_read_b128 v[110:113], v23 offset:22528
	s_waitcnt lgkmcnt(1)
	v_mfma_f32_16x16x32_f16 v[98:101], v[62:65], v[90:93], v[98:101]
	s_waitcnt lgkmcnt(0)
	v_mfma_f32_16x16x32_f16 v[52:55], v[62:65], v[110:113], v[52:55]
	global_load_dwordx4 v[62:65], v[0:1], off offset:640
	v_mfma_f32_16x16x32_f16 v[102:105], v[74:77], v[90:93], v[102:105]
	v_mfma_f32_16x16x32_f16 v[24:27], v[74:77], v[110:113], v[24:27]
	v_mfma_f32_16x16x32_f16 v[114:117], v[118:121], v[90:93], v[114:117]
	v_mfma_f32_16x16x32_f16 v[40:43], v[118:121], v[110:113], v[40:43]
	v_mfma_f32_16x16x32_f16 v[70:73], v[122:125], v[90:93], v[70:73]
	global_load_dwordx4 v[90:93], v[2:3], off offset:640
	global_load_dwordx4 v[126:129], v[4:5], off offset:640
	global_load_dwordx4 v[130:133], v[6:7], off offset:640
	global_load_dwordx4 v[74:77], v[8:9], off offset:640
	global_load_dwordx4 v[138:141], v[10:11], off offset:640
	global_load_dwordx4 v[142:145], v[12:13], off offset:640
	global_load_dwordx4 v[154:157], v[14:15], off offset:640
	s_waitcnt lgkmcnt(0)
	s_barrier
	v_mfma_f32_16x16x32_f16 v[48:51], v[122:125], v[110:113], v[48:51]
	ds_read_b128 v[58:61], v16 offset:32768
	ds_read_b128 v[106:109], v21
	s_waitcnt lgkmcnt(0)
	v_mfma_f32_16x16x32_f16 v[36:39], v[58:61], v[106:109], v[36:39]
	ds_read_b128 v[94:97], v16 offset:34816
	ds_read_b128 v[110:113], v21 offset:2048
	s_waitcnt lgkmcnt(0)
	v_mfma_f32_16x16x32_f16 v[66:69], v[58:61], v[110:113], v[66:69]
	ds_read_b128 v[118:121], v16 offset:36864
	v_mfma_f32_16x16x32_f16 v[44:47], v[94:97], v[106:109], v[44:47]
	ds_read_b128 v[122:125], v16 offset:38912
	v_mfma_f32_16x16x32_f16 v[78:81], v[94:97], v[110:113], v[78:81]
	s_waitcnt lgkmcnt(1)
	v_mfma_f32_16x16x32_f16 v[82:85], v[118:121], v[106:109], v[82:85]
	v_mfma_f32_16x16x32_f16 v[86:89], v[118:121], v[110:113], v[86:89]
	s_waitcnt lgkmcnt(0)
	v_mfma_f32_16x16x32_f16 v[28:31], v[122:125], v[106:109], v[28:31]
	ds_read_b128 v[106:109], v21 offset:4096
	v_mfma_f32_16x16x32_f16 v[32:35], v[122:125], v[110:113], v[32:35]
	ds_read_b128 v[110:113], v21 offset:6144
	s_waitcnt lgkmcnt(1)
	v_mfma_f32_16x16x32_f16 v[98:101], v[58:61], v[106:109], v[98:101]
	s_waitcnt lgkmcnt(0)
	v_mfma_f32_16x16x32_f16 v[52:55], v[58:61], v[110:113], v[52:55]
	ds_read_b128 v[58:61], v22 offset:32768
	v_mfma_f32_16x16x32_f16 v[102:105], v[94:97], v[106:109], v[102:105]
	v_mfma_f32_16x16x32_f16 v[24:27], v[94:97], v[110:113], v[24:27]
	ds_read_b128 v[94:97], v22 offset:34816
	v_mfma_f32_16x16x32_f16 v[114:117], v[118:121], v[106:109], v[114:117]
	s_waitcnt vmcnt(7)
	ds_write_b128 v19, v[62:65] offset:16384
	s_waitcnt vmcnt(6)
	ds_write_b128 v20, v[90:93] offset:16384
	v_mfma_f32_16x16x32_f16 v[40:43], v[118:121], v[110:113], v[40:43]
	ds_read_b128 v[118:121], v22 offset:36864
	s_waitcnt vmcnt(5)
	ds_write_b128 v17, v[126:129] offset:16384
	v_mfma_f32_16x16x32_f16 v[70:73], v[122:125], v[106:109], v[70:73]
	ds_read_b128 v[106:109], v23
	v_mfma_f32_16x16x32_f16 v[48:51], v[122:125], v[110:113], v[48:51]
	ds_read_b128 v[110:113], v23 offset:2048
	s_waitcnt lgkmcnt(1)
	v_mfma_f32_16x16x32_f16 v[36:39], v[58:61], v[106:109], v[36:39]
	ds_read_b128 v[122:125], v22 offset:38912
	s_waitcnt lgkmcnt(1)
	v_mfma_f32_16x16x32_f16 v[66:69], v[58:61], v[110:113], v[66:69]
	s_waitcnt vmcnt(4)
	ds_write_b128 v18, v[130:133] offset:16384
	v_mfma_f32_16x16x32_f16 v[44:47], v[94:97], v[106:109], v[44:47]
	s_waitcnt vmcnt(3)
	ds_write_b128 v19, v[74:77] offset:49152
	v_mfma_f32_16x16x32_f16 v[78:81], v[94:97], v[110:113], v[78:81]
	s_waitcnt vmcnt(2)
	ds_write_b128 v20, v[138:141] offset:49152
	v_mfma_f32_16x16x32_f16 v[82:85], v[118:121], v[106:109], v[82:85]
	s_waitcnt vmcnt(1)
	ds_write_b128 v17, v[142:145] offset:49152
	v_mfma_f32_16x16x32_f16 v[86:89], v[118:121], v[110:113], v[86:89]
	s_waitcnt vmcnt(0)
	ds_write_b128 v18, v[154:157] offset:49152
	s_waitcnt lgkmcnt(5)
	v_mfma_f32_16x16x32_f16 v[28:31], v[122:125], v[106:109], v[28:31]
	ds_read_b128 v[106:109], v23 offset:4096
	v_mfma_f32_16x16x32_f16 v[32:35], v[122:125], v[110:113], v[32:35]
	ds_read_b128 v[110:113], v23 offset:6144
	s_waitcnt lgkmcnt(1)
	v_mfma_f32_16x16x32_f16 v[98:101], v[58:61], v[106:109], v[98:101]
	s_waitcnt lgkmcnt(0)
	v_mfma_f32_16x16x32_f16 v[52:55], v[58:61], v[110:113], v[52:55]
	global_load_dwordx4 v[58:61], v[0:1], off offset:768
	v_mfma_f32_16x16x32_f16 v[102:105], v[94:97], v[106:109], v[102:105]
	v_mfma_f32_16x16x32_f16 v[24:27], v[94:97], v[110:113], v[24:27]
	v_mfma_f32_16x16x32_f16 v[114:117], v[118:121], v[106:109], v[114:117]
	v_mfma_f32_16x16x32_f16 v[40:43], v[118:121], v[110:113], v[40:43]
	v_mfma_f32_16x16x32_f16 v[70:73], v[122:125], v[106:109], v[70:73]
	global_load_dwordx4 v[106:109], v[2:3], off offset:768
	global_load_dwordx4 v[134:137], v[4:5], off offset:768
	global_load_dwordx4 v[158:161], v[6:7], off offset:768
	global_load_dwordx4 v[94:97], v[8:9], off offset:768
	global_load_dwordx4 v[162:165], v[10:11], off offset:768
	global_load_dwordx4 v[166:169], v[12:13], off offset:768
	global_load_dwordx4 v[190:193], v[14:15], off offset:768
	s_waitcnt lgkmcnt(0)
	s_barrier
; #define GL_LOAD(s_, kt_) if (VAR != 1) { a##s_##0 = GL_A(0, kt_); a##s_##1 = GL_A(1, kt_); a##s_##2 = GL_A(2, kt_); a##s_##3 = GL_A(3, kt_); b##s_##0 = GL_B(0, kt_); b##s_##1 = GL_B(1, kt_); b##s_##2 = GL_B(2, kt_); b##s_##3 = GL_B(3, kt_); }
; #define LDS_STORE(s_, buf_) if (VAR != 2) { LDS_ST1(sA, 0, buf_, a##s_##0) LDS_ST1(sA, 1, buf_, a##s_##1) LDS_ST1(sA, 2, buf_, a##s_##2) LDS_ST1(sA, 3, buf_, a##s_##3) LDS_ST1(sB, 0, buf_, b##s_##0) LDS_ST1(sB, 1, buf_, b##s_##1) LDS_ST1(sB, 2, buf_, b##s_##2) LDS_ST1(sB, 3, buf_, b##s_##3) }
;     ...
;   for (int kt = 0; kt < nk; kt += 2) {
;     if (kt + 2 < nk) { GL_LOAD(0, kt + 2) }
;     MMA_TILE(0)
;     LDS_STORE(1, 1)
;     if (VAR != 4) __syncthreads();
;     if (kt + 3 < nk) { GL_LOAD(1, kt + 3) }
;     MMA_TILE(1)
;     if (kt + 2 < nk) { LDS_STORE(0, 0) }
;     if (VAR != 4) __syncthreads();
	v_mfma_f32_16x16x32_f16 v[48:51], v[122:125], v[110:113], v[48:51]
	ds_read_b128 v[62:65], v16 offset:49152
	ds_read_b128 v[90:93], v21 offset:16384
	s_waitcnt lgkmcnt(0)
	v_mfma_f32_16x16x32_f16 v[36:39], v[62:65], v[90:93], v[36:39]
	ds_read_b128 v[74:77], v16 offset:51200
	ds_read_b128 v[110:113], v21 offset:18432
	s_waitcnt lgkmcnt(0)
	v_mfma_f32_16x16x32_f16 v[66:69], v[62:65], v[110:113], v[66:69]
	ds_read_b128 v[118:121], v16 offset:53248
	v_mfma_f32_16x16x32_f16 v[44:47], v[74:77], v[90:93], v[44:47]
	ds_read_b128 v[122:125], v16 offset:55296
	v_mfma_f32_16x16x32_f16 v[78:81], v[74:77], v[110:113], v[78:81]
	s_waitcnt lgkmcnt(1)
	v_mfma_f32_16x16x32_f16 v[82:85], v[118:121], v[90:93], v[82:85]
	v_mfma_f32_16x16x32_f16 v[86:89], v[118:121], v[110:113], v[86:89]
	s_waitcnt lgkmcnt(0)
	v_mfma_f32_16x16x32_f16 v[28:31], v[122:125], v[90:93], v[28:31]
	ds_read_b128 v[90:93], v21 offset:20480
	v_mfma_f32_16x16x32_f16 v[32:35], v[122:125], v[110:113], v[32:35]
	ds_read_b128 v[110:113], v21 offset:22528
	s_waitcnt lgkmcnt(1)
	v_mfma_f32_16x16x32_f16 v[98:101], v[62:65], v[90:93], v[98:101]
	s_waitcnt lgkmcnt(0)
	v_mfma_f32_16x16x32_f16 v[52:55], v[62:65], v[110:113], v[52:55]
	ds_read_b128 v[62:65], v22 offset:49152
	v_mfma_f32_16x16x32_f16 v[102:105], v[74:77], v[90:93], v[102:105]
	v_mfma_f32_16x16x32_f16 v[24:27], v[74:77], v[110:113], v[24:27]
	ds_read_b128 v[74:77], v22 offset:51200
	v_mfma_f32_16x16x32_f16 v[114:117], v[118:121], v[90:93], v[114:117]
	s_waitcnt vmcnt(7)
	ds_write_b128 v19, v[58:61]
	s_waitcnt vmcnt(6)
	ds_write_b128 v20, v[106:109]
	v_mfma_f32_16x16x32_f16 v[40:43], v[118:121], v[110:113], v[40:43]
	ds_read_b128 v[118:121], v22 offset:53248
	s_waitcnt vmcnt(5)
	ds_write_b128 v17, v[134:137]
	v_mfma_f32_16x16x32_f16 v[70:73], v[122:125], v[90:93], v[70:73]
	ds_read_b128 v[90:93], v23 offset:16384
	v_mfma_f32_16x16x32_f16 v[48:51], v[122:125], v[110:113], v[48:51]
	ds_read_b128 v[110:113], v23 offset:18432
	s_waitcnt lgkmcnt(1)
	v_mfma_f32_16x16x32_f16 v[36:39], v[62:65], v[90:93], v[36:39]
	ds_read_b128 v[122:125], v22 offset:55296
	s_waitcnt lgkmcnt(1)
	v_mfma_f32_16x16x32_f16 v[66:69], v[62:65], v[110:113], v[66:69]
	s_waitcnt vmcnt(4)
	ds_write_b128 v18, v[158:161]
	v_mfma_f32_16x16x32_f16 v[44:47], v[74:77], v[90:93], v[44:47]
	s_waitcnt vmcnt(3)
	ds_write_b128 v19, v[94:97] offset:32768
	v_mfma_f32_16x16x32_f16 v[78:81], v[74:77], v[110:113], v[78:81]
	s_waitcnt vmcnt(2)
	ds_write_b128 v20, v[162:165] offset:32768
	v_mfma_f32_16x16x32_f16 v[82:85], v[118:121], v[90:93], v[82:85]
	s_waitcnt vmcnt(1)
	ds_write_b128 v17, v[166:169] offset:32768
	v_mfma_f32_16x16x32_f16 v[86:89], v[118:121], v[110:113], v[86:89]
	s_waitcnt vmcnt(0)
	ds_write_b128 v18, v[190:193] offset:32768
	s_waitcnt lgkmcnt(5)
	v_mfma_f32_16x16x32_f16 v[28:31], v[122:125], v[90:93], v[28:31]
	ds_read_b128 v[90:93], v23 offset:20480
	v_mfma_f32_16x16x32_f16 v[32:35], v[122:125], v[110:113], v[32:35]
	ds_read_b128 v[110:113], v23 offset:22528
	s_waitcnt lgkmcnt(1)
	v_mfma_f32_16x16x32_f16 v[98:101], v[62:65], v[90:93], v[98:101]
	s_waitcnt lgkmcnt(0)
	v_mfma_f32_16x16x32_f16 v[52:55], v[62:65], v[110:113], v[52:55]
	global_load_dwordx4 v[62:65], v[0:1], off offset:896
	v_mfma_f32_16x16x32_f16 v[102:105], v[74:77], v[90:93], v[102:105]
	v_mfma_f32_16x16x32_f16 v[24:27], v[74:77], v[110:113], v[24:27]
	v_mfma_f32_16x16x32_f16 v[114:117], v[118:121], v[90:93], v[114:117]
	v_mfma_f32_16x16x32_f16 v[40:43], v[118:121], v[110:113], v[40:43]
	v_mfma_f32_16x16x32_f16 v[70:73], v[122:125], v[90:93], v[70:73]
	global_load_dwordx4 v[90:93], v[2:3], off offset:896
	global_load_dwordx4 v[126:129], v[4:5], off offset:896
	global_load_dwordx4 v[130:133], v[6:7], off offset:896
	global_load_dwordx4 v[74:77], v[8:9], off offset:896
	global_load_dwordx4 v[138:141], v[10:11], off offset:896
	global_load_dwordx4 v[142:145], v[12:13], off offset:896
	global_load_dwordx4 v[154:157], v[14:15], off offset:896
	s_waitcnt lgkmcnt(0)
	s_barrier
	v_mfma_f32_16x16x32_f16 v[48:51], v[122:125], v[110:113], v[48:51]
	ds_read_b128 v[58:61], v16 offset:32768
	ds_read_b128 v[106:109], v21
	s_waitcnt lgkmcnt(0)
	v_mfma_f32_16x16x32_f16 v[36:39], v[58:61], v[106:109], v[36:39]
	ds_read_b128 v[94:97], v16 offset:34816
	ds_read_b128 v[110:113], v21 offset:2048
	s_waitcnt lgkmcnt(0)
	v_mfma_f32_16x16x32_f16 v[66:69], v[58:61], v[110:113], v[66:69]
	ds_read_b128 v[118:121], v16 offset:36864
	v_mfma_f32_16x16x32_f16 v[44:47], v[94:97], v[106:109], v[44:47]
	ds_read_b128 v[122:125], v16 offset:38912
	v_mfma_f32_16x16x32_f16 v[78:81], v[94:97], v[110:113], v[78:81]
	s_waitcnt lgkmcnt(1)
	v_mfma_f32_16x16x32_f16 v[82:85], v[118:121], v[106:109], v[82:85]
	v_mfma_f32_16x16x32_f16 v[86:89], v[118:121], v[110:113], v[86:89]
	s_waitcnt lgkmcnt(0)
	v_mfma_f32_16x16x32_f16 v[28:31], v[122:125], v[106:109], v[28:31]
	ds_read_b128 v[106:109], v21 offset:4096
	v_mfma_f32_16x16x32_f16 v[32:35], v[122:125], v[110:113], v[32:35]
	ds_read_b128 v[110:113], v21 offset:6144
	s_waitcnt lgkmcnt(1)
	v_mfma_f32_16x16x32_f16 v[98:101], v[58:61], v[106:109], v[98:101]
	s_waitcnt lgkmcnt(0)
	v_mfma_f32_16x16x32_f16 v[52:55], v[58:61], v[110:113], v[52:55]
	ds_read_b128 v[58:61], v22 offset:32768
	v_mfma_f32_16x16x32_f16 v[102:105], v[94:97], v[106:109], v[102:105]
	v_mfma_f32_16x16x32_f16 v[24:27], v[94:97], v[110:113], v[24:27]
	ds_read_b128 v[94:97], v22 offset:34816
	v_mfma_f32_16x16x32_f16 v[114:117], v[118:121], v[106:109], v[114:117]
	s_waitcnt vmcnt(7)
	ds_write_b128 v19, v[62:65] offset:16384
	s_waitcnt vmcnt(6)
	ds_write_b128 v20, v[90:93] offset:16384
	v_mfma_f32_16x16x32_f16 v[40:43], v[118:121], v[110:113], v[40:43]
	ds_read_b128 v[118:121], v22 offset:36864
	s_waitcnt vmcnt(5)
; #define GL_LOAD(s_, kt_) if (VAR != 1) { a##s_##0 = GL_A(0, kt_); a##s_##1 = GL_A(1, kt_); a##s_##2 = GL_A(2, kt_); a##s_##3 = GL_A(3, kt_); b##s_##0 = GL_B(0, kt_); b##s_##1 = GL_B(1, kt_); b##s_##2 = GL_B(2, kt_); b##s_##3 = GL_B(3, kt_); }
; #define LDS_STORE(s_, buf_) if (VAR != 2) { LDS_ST1(sA, 0, buf_, a##s_##0) LDS_ST1(sA, 1, buf_, a##s_##1) LDS_ST1(sA, 2, buf_, a##s_##2) LDS_ST1(sA, 3, buf_, a##s_##3) LDS_ST1(sB, 0, buf_, b##s_##0) LDS_ST1(sB, 1, buf_, b##s_##1) LDS_ST1(sB, 2, buf_, b##s_##2) LDS_ST1(sB, 3, buf_, b##s_##3) }
;     ...
;   for (int kt = 0; kt < nk; kt += 2) {
;     if (kt + 2 < nk) { GL_LOAD(0, kt + 2) }
;     MMA_TILE(0)
;     LDS_STORE(1, 1)
;     if (VAR != 4) __syncthreads();
;     if (kt + 3 < nk) { GL_LOAD(1, kt + 3) }
;     MMA_TILE(1)
;     if (kt + 2 < nk) { LDS_STORE(0, 0) }
;     if (VAR != 4) __syncthreads();
	ds_write_b128 v17, v[126:129] offset:16384
	v_mfma_f32_16x16x32_f16 v[70:73], v[122:125], v[106:109], v[70:73]
	ds_read_b128 v[106:109], v23
	v_mfma_f32_16x16x32_f16 v[48:51], v[122:125], v[110:113], v[48:51]
	ds_read_b128 v[110:113], v23 offset:2048
	s_waitcnt lgkmcnt(1)
	v_mfma_f32_16x16x32_f16 v[36:39], v[58:61], v[106:109], v[36:39]
	ds_read_b128 v[122:125], v22 offset:38912
	s_waitcnt lgkmcnt(1)
	v_mfma_f32_16x16x32_f16 v[66:69], v[58:61], v[110:113], v[66:69]
	s_waitcnt vmcnt(4)
	ds_write_b128 v18, v[130:133] offset:16384
	v_mfma_f32_16x16x32_f16 v[44:47], v[94:97], v[106:109], v[44:47]
	s_waitcnt vmcnt(3)
	ds_write_b128 v19, v[74:77] offset:49152
	v_mfma_f32_16x16x32_f16 v[78:81], v[94:97], v[110:113], v[78:81]
	s_waitcnt vmcnt(2)
	ds_write_b128 v20, v[138:141] offset:49152
	v_mfma_f32_16x16x32_f16 v[82:85], v[118:121], v[106:109], v[82:85]
	s_waitcnt vmcnt(1)
	ds_write_b128 v17, v[142:145] offset:49152
	v_mfma_f32_16x16x32_f16 v[86:89], v[118:121], v[110:113], v[86:89]
	s_waitcnt vmcnt(0)
	ds_write_b128 v18, v[154:157] offset:49152
	s_waitcnt lgkmcnt(5)
	v_mfma_f32_16x16x32_f16 v[28:31], v[122:125], v[106:109], v[28:31]
	ds_read_b128 v[106:109], v23 offset:4096
	v_mfma_f32_16x16x32_f16 v[32:35], v[122:125], v[110:113], v[32:35]
	ds_read_b128 v[110:113], v23 offset:6144
	s_waitcnt lgkmcnt(1)
	v_mfma_f32_16x16x32_f16 v[98:101], v[58:61], v[106:109], v[98:101]
	s_waitcnt lgkmcnt(0)
	v_mfma_f32_16x16x32_f16 v[52:55], v[58:61], v[110:113], v[52:55]
	global_load_dwordx4 v[58:61], v[0:1], off offset:1024
	v_mfma_f32_16x16x32_f16 v[102:105], v[94:97], v[106:109], v[102:105]
	v_mfma_f32_16x16x32_f16 v[24:27], v[94:97], v[110:113], v[24:27]
	v_mfma_f32_16x16x32_f16 v[114:117], v[118:121], v[106:109], v[114:117]
	v_mfma_f32_16x16x32_f16 v[40:43], v[118:121], v[110:113], v[40:43]
	v_mfma_f32_16x16x32_f16 v[70:73], v[122:125], v[106:109], v[70:73]
	global_load_dwordx4 v[106:109], v[2:3], off offset:1024
	global_load_dwordx4 v[134:137], v[4:5], off offset:1024
	global_load_dwordx4 v[158:161], v[6:7], off offset:1024
	global_load_dwordx4 v[94:97], v[8:9], off offset:1024
	global_load_dwordx4 v[162:165], v[10:11], off offset:1024
	global_load_dwordx4 v[166:169], v[12:13], off offset:1024
	global_load_dwordx4 v[190:193], v[14:15], off offset:1024
	s_waitcnt lgkmcnt(0)
	s_barrier
	v_mfma_f32_16x16x32_f16 v[48:51], v[122:125], v[110:113], v[48:51]
	ds_read_b128 v[62:65], v16 offset:49152
	ds_read_b128 v[90:93], v21 offset:16384
	s_waitcnt lgkmcnt(0)
	v_mfma_f32_16x16x32_f16 v[36:39], v[62:65], v[90:93], v[36:39]
	ds_read_b128 v[74:77], v16 offset:51200
	ds_read_b128 v[110:113], v21 offset:18432
	s_waitcnt lgkmcnt(0)
	v_mfma_f32_16x16x32_f16 v[66:69], v[62:65], v[110:113], v[66:69]
	ds_read_b128 v[118:121], v16 offset:53248
	v_mfma_f32_16x16x32_f16 v[44:47], v[74:77], v[90:93], v[44:47]
	ds_read_b128 v[122:125], v16 offset:55296
	v_mfma_f32_16x16x32_f16 v[78:81], v[74:77], v[110:113], v[78:81]
	s_waitcnt lgkmcnt(1)
	v_mfma_f32_16x16x32_f16 v[82:85], v[118:121], v[90:93], v[82:85]
	v_mfma_f32_16x16x32_f16 v[86:89], v[118:121], v[110:113], v[86:89]
	s_waitcnt lgkmcnt(0)
	v_mfma_f32_16x16x32_f16 v[28:31], v[122:125], v[90:93], v[28:31]
	ds_read_b128 v[90:93], v21 offset:20480
	v_mfma_f32_16x16x32_f16 v[32:35], v[122:125], v[110:113], v[32:35]
	ds_read_b128 v[110:113], v21 offset:22528
	s_waitcnt lgkmcnt(1)
	v_mfma_f32_16x16x32_f16 v[98:101], v[62:65], v[90:93], v[98:101]
	s_waitcnt lgkmcnt(0)
	v_mfma_f32_16x16x32_f16 v[52:55], v[62:65], v[110:113], v[52:55]
	ds_read_b128 v[62:65], v22 offset:49152
	v_mfma_f32_16x16x32_f16 v[102:105], v[74:77], v[90:93], v[102:105]
	v_mfma_f32_16x16x32_f16 v[24:27], v[74:77], v[110:113], v[24:27]
	ds_read_b128 v[74:77], v22 offset:51200
	v_mfma_f32_16x16x32_f16 v[114:117], v[118:121], v[90:93], v[114:117]
	s_waitcnt vmcnt(7)
	ds_write_b128 v19, v[58:61]
	s_waitcnt vmcnt(6)
	ds_write_b128 v20, v[106:109]
	v_mfma_f32_16x16x32_f16 v[40:43], v[118:121], v[110:113], v[40:43]
	ds_read_b128 v[118:121], v22 offset:53248
	s_waitcnt vmcnt(5)
	ds_write_b128 v17, v[134:137]
	v_mfma_f32_16x16x32_f16 v[70:73], v[122:125], v[90:93], v[70:73]
	ds_read_b128 v[90:93], v23 offset:16384
	v_mfma_f32_16x16x32_f16 v[48:51], v[122:125], v[110:113], v[48:51]
	ds_read_b128 v[110:113], v23 offset:18432
	s_waitcnt lgkmcnt(1)
	v_mfma_f32_16x16x32_f16 v[36:39], v[62:65], v[90:93], v[36:39]
	ds_read_b128 v[122:125], v22 offset:55296
	s_waitcnt lgkmcnt(1)
	v_mfma_f32_16x16x32_f16 v[66:69], v[62:65], v[110:113], v[66:69]
	s_waitcnt vmcnt(4)
	ds_write_b128 v18, v[158:161]
	v_mfma_f32_16x16x32_f16 v[44:47], v[74:77], v[90:93], v[44:47]
	s_waitcnt vmcnt(3)
	ds_write_b128 v19, v[94:97] offset:32768
	v_mfma_f32_16x16x32_f16 v[78:81], v[74:77], v[110:113], v[78:81]
	s_waitcnt vmcnt(2)
	ds_write_b128 v20, v[162:165] offset:32768
	v_mfma_f32_16x16x32_f16 v[82:85], v[118:121], v[90:93], v[82:85]
	s_waitcnt vmcnt(1)
	ds_write_b128 v17, v[166:169] offset:32768
	v_mfma_f32_16x16x32_f16 v[86:89], v[118:121], v[110:113], v[86:89]
	s_waitcnt vmcnt(0)
	ds_write_b128 v18, v[190:193] offset:32768
	s_waitcnt lgkmcnt(5)
	v_mfma_f32_16x16x32_f16 v[28:31], v[122:125], v[90:93], v[28:31]
	ds_read_b128 v[90:93], v23 offset:20480
	v_mfma_f32_16x16x32_f16 v[32:35], v[122:125], v[110:113], v[32:35]
	ds_read_b128 v[110:113], v23 offset:22528
	s_waitcnt lgkmcnt(1)
	v_mfma_f32_16x16x32_f16 v[98:101], v[62:65], v[90:93], v[98:101]
	s_waitcnt lgkmcnt(0)
	v_mfma_f32_16x16x32_f16 v[52:55], v[62:65], v[110:113], v[52:55]
	global_load_dwordx4 v[62:65], v[0:1], off offset:1152
	v_mfma_f32_16x16x32_f16 v[102:105], v[74:77], v[90:93], v[102:105]
	v_mfma_f32_16x16x32_f16 v[24:27], v[74:77], v[110:113], v[24:27]
	v_mfma_f32_16x16x32_f16 v[114:117], v[118:121], v[90:93], v[114:117]
	v_mfma_f32_16x16x32_f16 v[40:43], v[118:121], v[110:113], v[40:43]
	v_mfma_f32_16x16x32_f16 v[70:73], v[122:125], v[90:93], v[70:73]
	global_load_dwordx4 v[90:93], v[2:3], off offset:1152
	global_load_dwordx4 v[126:129], v[4:5], off offset:1152
	global_load_dwordx4 v[130:133], v[6:7], off offset:1152
	global_load_dwordx4 v[74:77], v[8:9], off offset:1152
	global_load_dwordx4 v[138:141], v[10:11], off offset:1152
	global_load_dwordx4 v[142:145], v[12:13], off offset:1152
	global_load_dwordx4 v[154:157], v[14:15], off offset:1152
	s_waitcnt lgkmcnt(0)
	s_barrier
; #define GL_LOAD(s_, kt_) if (VAR != 1) { a##s_##0 = GL_A(0, kt_); a##s_##1 = GL_A(1, kt_); a##s_##2 = GL_A(2, kt_); a##s_##3 = GL_A(3, kt_); b##s_##0 = GL_B(0, kt_); b##s_##1 = GL_B(1, kt_); b##s_##2 = GL_B(2, kt_); b##s_##3 = GL_B(3, kt_); }
; #define LDS_STORE(s_, buf_) if (VAR != 2) { LDS_ST1(sA, 0, buf_, a##s_##0) LDS_ST1(sA, 1, buf_, a##s_##1) LDS_ST1(sA, 2, buf_, a##s_##2) LDS_ST1(sA, 3, buf_, a##s_##3) LDS_ST1(sB, 0, buf_, b##s_##0) LDS_ST1(sB, 1, buf_, b##s_##1) LDS_ST1(sB, 2, buf_, b##s_##2) LDS_ST1(sB, 3, buf_, b##s_##3) }
;     ...
;   for (int kt = 0; kt < nk; kt += 2) {
;     if (kt + 2 < nk) { GL_LOAD(0, kt + 2) }
;     MMA_TILE(0)
;     LDS_STORE(1, 1)
;     if (VAR != 4) __syncthreads();
;     if (kt + 3 < nk) { GL_LOAD(1, kt + 3) }
;     MMA_TILE(1)
;     if (kt + 2 < nk) { LDS_STORE(0, 0) }
;     if (VAR != 4) __syncthreads();
	v_mfma_f32_16x16x32_f16 v[48:51], v[122:125], v[110:113], v[48:51]
	ds_read_b128 v[58:61], v16 offset:32768
	ds_read_b128 v[106:109], v21
	s_waitcnt lgkmcnt(0)
	v_mfma_f32_16x16x32_f16 v[36:39], v[58:61], v[106:109], v[36:39]
	ds_read_b128 v[94:97], v16 offset:34816
	ds_read_b128 v[110:113], v21 offset:2048
	s_waitcnt lgkmcnt(0)
	v_mfma_f32_16x16x32_f16 v[66:69], v[58:61], v[110:113], v[66:69]
	ds_read_b128 v[118:121], v16 offset:36864
	v_mfma_f32_16x16x32_f16 v[44:47], v[94:97], v[106:109], v[44:47]
	ds_read_b128 v[122:125], v16 offset:38912
	v_mfma_f32_16x16x32_f16 v[78:81], v[94:97], v[110:113], v[78:81]
	s_waitcnt lgkmcnt(1)
	v_mfma_f32_16x16x32_f16 v[82:85], v[118:121], v[106:109], v[82:85]
	v_mfma_f32_16x16x32_f16 v[86:89], v[118:121], v[110:113], v[86:89]
	s_waitcnt lgkmcnt(0)
	v_mfma_f32_16x16x32_f16 v[28:31], v[122:125], v[106:109], v[28:31]
	ds_read_b128 v[106:109], v21 offset:4096
	v_mfma_f32_16x16x32_f16 v[32:35], v[122:125], v[110:113], v[32:35]
	ds_read_b128 v[110:113], v21 offset:6144
	s_waitcnt lgkmcnt(1)
	v_mfma_f32_16x16x32_f16 v[98:101], v[58:61], v[106:109], v[98:101]
	s_waitcnt lgkmcnt(0)
	v_mfma_f32_16x16x32_f16 v[52:55], v[58:61], v[110:113], v[52:55]
	ds_read_b128 v[58:61], v22 offset:32768
	v_mfma_f32_16x16x32_f16 v[102:105], v[94:97], v[106:109], v[102:105]
	v_mfma_f32_16x16x32_f16 v[24:27], v[94:97], v[110:113], v[24:27]
	ds_read_b128 v[94:97], v22 offset:34816
	v_mfma_f32_16x16x32_f16 v[114:117], v[118:121], v[106:109], v[114:117]
	s_waitcnt vmcnt(7)
	ds_write_b128 v19, v[62:65] offset:16384
	s_waitcnt vmcnt(6)
	ds_write_b128 v20, v[90:93] offset:16384
	v_mfma_f32_16x16x32_f16 v[40:43], v[118:121], v[110:113], v[40:43]
	ds_read_b128 v[118:121], v22 offset:36864
	s_waitcnt vmcnt(5)
	ds_write_b128 v17, v[126:129] offset:16384
	v_mfma_f32_16x16x32_f16 v[70:73], v[122:125], v[106:109], v[70:73]
	ds_read_b128 v[106:109], v23
	v_mfma_f32_16x16x32_f16 v[48:51], v[122:125], v[110:113], v[48:51]
	ds_read_b128 v[110:113], v23 offset:2048
	s_waitcnt lgkmcnt(1)
	v_mfma_f32_16x16x32_f16 v[36:39], v[58:61], v[106:109], v[36:39]
	ds_read_b128 v[122:125], v22 offset:38912
	s_waitcnt lgkmcnt(1)
	v_mfma_f32_16x16x32_f16 v[66:69], v[58:61], v[110:113], v[66:69]
	s_waitcnt vmcnt(4)
	ds_write_b128 v18, v[130:133] offset:16384
	v_mfma_f32_16x16x32_f16 v[44:47], v[94:97], v[106:109], v[44:47]
	s_waitcnt vmcnt(3)
	ds_write_b128 v19, v[74:77] offset:49152
	v_mfma_f32_16x16x32_f16 v[78:81], v[94:97], v[110:113], v[78:81]
	s_waitcnt vmcnt(2)
	ds_write_b128 v20, v[138:141] offset:49152
	v_mfma_f32_16x16x32_f16 v[82:85], v[118:121], v[106:109], v[82:85]
	s_waitcnt vmcnt(1)
	ds_write_b128 v17, v[142:145] offset:49152
	v_mfma_f32_16x16x32_f16 v[86:89], v[118:121], v[110:113], v[86:89]
	s_waitcnt vmcnt(0)
	ds_write_b128 v18, v[154:157] offset:49152
	s_waitcnt lgkmcnt(5)
	v_mfma_f32_16x16x32_f16 v[28:31], v[122:125], v[106:109], v[28:31]
	ds_read_b128 v[106:109], v23 offset:4096
	v_mfma_f32_16x16x32_f16 v[32:35], v[122:125], v[110:113], v[32:35]
	ds_read_b128 v[110:113], v23 offset:6144
	s_waitcnt lgkmcnt(1)
	v_mfma_f32_16x16x32_f16 v[98:101], v[58:61], v[106:109], v[98:101]
	s_waitcnt lgkmcnt(0)
	v_mfma_f32_16x16x32_f16 v[52:55], v[58:61], v[110:113], v[52:55]
	global_load_dwordx4 v[58:61], v[0:1], off offset:1280
	v_mfma_f32_16x16x32_f16 v[102:105], v[94:97], v[106:109], v[102:105]
	v_mfma_f32_16x16x32_f16 v[24:27], v[94:97], v[110:113], v[24:27]
	v_mfma_f32_16x16x32_f16 v[114:117], v[118:121], v[106:109], v[114:117]
	v_mfma_f32_16x16x32_f16 v[40:43], v[118:121], v[110:113], v[40:43]
	v_mfma_f32_16x16x32_f16 v[70:73], v[122:125], v[106:109], v[70:73]
	global_load_dwordx4 v[106:109], v[2:3], off offset:1280
	global_load_dwordx4 v[134:137], v[4:5], off offset:1280
	global_load_dwordx4 v[158:161], v[6:7], off offset:1280
	global_load_dwordx4 v[94:97], v[8:9], off offset:1280
	global_load_dwordx4 v[162:165], v[10:11], off offset:1280
	global_load_dwordx4 v[166:169], v[12:13], off offset:1280
	global_load_dwordx4 v[190:193], v[14:15], off offset:1280
	s_waitcnt lgkmcnt(0)
	s_barrier
	v_mfma_f32_16x16x32_f16 v[48:51], v[122:125], v[110:113], v[48:51]
	ds_read_b128 v[62:65], v16 offset:49152
	ds_read_b128 v[90:93], v21 offset:16384
	s_waitcnt lgkmcnt(0)
	v_mfma_f32_16x16x32_f16 v[36:39], v[62:65], v[90:93], v[36:39]
	ds_read_b128 v[74:77], v16 offset:51200
	ds_read_b128 v[110:113], v21 offset:18432
	s_waitcnt lgkmcnt(0)
	v_mfma_f32_16x16x32_f16 v[66:69], v[62:65], v[110:113], v[66:69]
	ds_read_b128 v[118:121], v16 offset:53248
	v_mfma_f32_16x16x32_f16 v[44:47], v[74:77], v[90:93], v[44:47]
	ds_read_b128 v[122:125], v16 offset:55296
	v_mfma_f32_16x16x32_f16 v[78:81], v[74:77], v[110:113], v[78:81]
	s_waitcnt lgkmcnt(1)
	v_mfma_f32_16x16x32_f16 v[82:85], v[118:121], v[90:93], v[82:85]
	v_mfma_f32_16x16x32_f16 v[86:89], v[118:121], v[110:113], v[86:89]
	s_waitcnt lgkmcnt(0)
	v_mfma_f32_16x16x32_f16 v[28:31], v[122:125], v[90:93], v[28:31]
	ds_read_b128 v[90:93], v21 offset:20480
	v_mfma_f32_16x16x32_f16 v[32:35], v[122:125], v[110:113], v[32:35]
	ds_read_b128 v[110:113], v21 offset:22528
	s_waitcnt lgkmcnt(1)
	v_mfma_f32_16x16x32_f16 v[98:101], v[62:65], v[90:93], v[98:101]
	s_waitcnt lgkmcnt(0)
	v_mfma_f32_16x16x32_f16 v[52:55], v[62:65], v[110:113], v[52:55]
	ds_read_b128 v[62:65], v22 offset:49152
	v_mfma_f32_16x16x32_f16 v[102:105], v[74:77], v[90:93], v[102:105]
	v_mfma_f32_16x16x32_f16 v[24:27], v[74:77], v[110:113], v[24:27]
	ds_read_b128 v[74:77], v22 offset:51200
	v_mfma_f32_16x16x32_f16 v[114:117], v[118:121], v[90:93], v[114:117]
	s_waitcnt vmcnt(7)
	ds_write_b128 v19, v[58:61]
	s_waitcnt vmcnt(6)
; #define GL_LOAD(s_, kt_) if (VAR != 1) { a##s_##0 = GL_A(0, kt_); a##s_##1 = GL_A(1, kt_); a##s_##2 = GL_A(2, kt_); a##s_##3 = GL_A(3, kt_); b##s_##0 = GL_B(0, kt_); b##s_##1 = GL_B(1, kt_); b##s_##2 = GL_B(2, kt_); b##s_##3 = GL_B(3, kt_); }
; #define LDS_STORE(s_, buf_) if (VAR != 2) { LDS_ST1(sA, 0, buf_, a##s_##0) LDS_ST1(sA, 1, buf_, a##s_##1) LDS_ST1(sA, 2, buf_, a##s_##2) LDS_ST1(sA, 3, buf_, a##s_##3) LDS_ST1(sB, 0, buf_, b##s_##0) LDS_ST1(sB, 1, buf_, b##s_##1) LDS_ST1(sB, 2, buf_, b##s_##2) LDS_ST1(sB, 3, buf_, b##s_##3) }
;     ...
;   for (int kt = 0; kt < nk; kt += 2) {
;     if (kt + 2 < nk) { GL_LOAD(0, kt + 2) }
;     MMA_TILE(0)
;     LDS_STORE(1, 1)
;     if (VAR != 4) __syncthreads();
;     if (kt + 3 < nk) { GL_LOAD(1, kt + 3) }
;     MMA_TILE(1)
;     if (kt + 2 < nk) { LDS_STORE(0, 0) }
;     if (VAR != 4) __syncthreads();
	ds_write_b128 v20, v[106:109]
	v_mfma_f32_16x16x32_f16 v[40:43], v[118:121], v[110:113], v[40:43]
	ds_read_b128 v[118:121], v22 offset:53248
	s_waitcnt vmcnt(5)
	ds_write_b128 v17, v[134:137]
	v_mfma_f32_16x16x32_f16 v[70:73], v[122:125], v[90:93], v[70:73]
	ds_read_b128 v[90:93], v23 offset:16384
	v_mfma_f32_16x16x32_f16 v[48:51], v[122:125], v[110:113], v[48:51]
	ds_read_b128 v[110:113], v23 offset:18432
	s_waitcnt lgkmcnt(1)
	v_mfma_f32_16x16x32_f16 v[36:39], v[62:65], v[90:93], v[36:39]
	ds_read_b128 v[122:125], v22 offset:55296
	s_waitcnt lgkmcnt(1)
	v_mfma_f32_16x16x32_f16 v[66:69], v[62:65], v[110:113], v[66:69]
	s_waitcnt vmcnt(4)
	ds_write_b128 v18, v[158:161]
	v_mfma_f32_16x16x32_f16 v[44:47], v[74:77], v[90:93], v[44:47]
	s_waitcnt vmcnt(3)
	ds_write_b128 v19, v[94:97] offset:32768
	v_mfma_f32_16x16x32_f16 v[78:81], v[74:77], v[110:113], v[78:81]
	s_waitcnt vmcnt(2)
	ds_write_b128 v20, v[162:165] offset:32768
	v_mfma_f32_16x16x32_f16 v[82:85], v[118:121], v[90:93], v[82:85]
	s_waitcnt vmcnt(1)
	ds_write_b128 v17, v[166:169] offset:32768
	v_mfma_f32_16x16x32_f16 v[86:89], v[118:121], v[110:113], v[86:89]
	s_waitcnt vmcnt(0)
	ds_write_b128 v18, v[190:193] offset:32768
	s_waitcnt lgkmcnt(5)
	v_mfma_f32_16x16x32_f16 v[28:31], v[122:125], v[90:93], v[28:31]
	ds_read_b128 v[90:93], v23 offset:20480
	v_mfma_f32_16x16x32_f16 v[32:35], v[122:125], v[110:113], v[32:35]
	ds_read_b128 v[110:113], v23 offset:22528
	s_waitcnt lgkmcnt(1)
	v_mfma_f32_16x16x32_f16 v[98:101], v[62:65], v[90:93], v[98:101]
	s_waitcnt lgkmcnt(0)
	v_mfma_f32_16x16x32_f16 v[52:55], v[62:65], v[110:113], v[52:55]
	global_load_dwordx4 v[62:65], v[0:1], off offset:1408
	v_mfma_f32_16x16x32_f16 v[102:105], v[74:77], v[90:93], v[102:105]
	v_mfma_f32_16x16x32_f16 v[24:27], v[74:77], v[110:113], v[24:27]
	v_mfma_f32_16x16x32_f16 v[114:117], v[118:121], v[90:93], v[114:117]
	v_mfma_f32_16x16x32_f16 v[40:43], v[118:121], v[110:113], v[40:43]
	v_mfma_f32_16x16x32_f16 v[70:73], v[122:125], v[90:93], v[70:73]
	global_load_dwordx4 v[90:93], v[2:3], off offset:1408
	global_load_dwordx4 v[126:129], v[4:5], off offset:1408
	global_load_dwordx4 v[130:133], v[6:7], off offset:1408
	global_load_dwordx4 v[74:77], v[8:9], off offset:1408
	global_load_dwordx4 v[138:141], v[10:11], off offset:1408
	global_load_dwordx4 v[142:145], v[12:13], off offset:1408
	global_load_dwordx4 v[154:157], v[14:15], off offset:1408
	s_waitcnt lgkmcnt(0)
	s_barrier
	v_mfma_f32_16x16x32_f16 v[48:51], v[122:125], v[110:113], v[48:51]
	ds_read_b128 v[58:61], v16 offset:32768
	ds_read_b128 v[106:109], v21
	s_waitcnt lgkmcnt(0)
	v_mfma_f32_16x16x32_f16 v[36:39], v[58:61], v[106:109], v[36:39]
	ds_read_b128 v[94:97], v16 offset:34816
	ds_read_b128 v[110:113], v21 offset:2048
	s_waitcnt lgkmcnt(0)
	v_mfma_f32_16x16x32_f16 v[66:69], v[58:61], v[110:113], v[66:69]
	ds_read_b128 v[118:121], v16 offset:36864
	v_mfma_f32_16x16x32_f16 v[44:47], v[94:97], v[106:109], v[44:47]
	ds_read_b128 v[122:125], v16 offset:38912
	v_mfma_f32_16x16x32_f16 v[78:81], v[94:97], v[110:113], v[78:81]
	s_waitcnt lgkmcnt(1)
	v_mfma_f32_16x16x32_f16 v[82:85], v[118:121], v[106:109], v[82:85]
	v_mfma_f32_16x16x32_f16 v[86:89], v[118:121], v[110:113], v[86:89]
	s_waitcnt lgkmcnt(0)
	v_mfma_f32_16x16x32_f16 v[28:31], v[122:125], v[106:109], v[28:31]
	ds_read_b128 v[106:109], v21 offset:4096
	v_mfma_f32_16x16x32_f16 v[32:35], v[122:125], v[110:113], v[32:35]
	ds_read_b128 v[110:113], v21 offset:6144
	s_waitcnt lgkmcnt(1)
	v_mfma_f32_16x16x32_f16 v[98:101], v[58:61], v[106:109], v[98:101]
	s_waitcnt lgkmcnt(0)
	v_mfma_f32_16x16x32_f16 v[52:55], v[58:61], v[110:113], v[52:55]
	ds_read_b128 v[58:61], v22 offset:32768
	v_mfma_f32_16x16x32_f16 v[102:105], v[94:97], v[106:109], v[102:105]
	v_mfma_f32_16x16x32_f16 v[24:27], v[94:97], v[110:113], v[24:27]
	ds_read_b128 v[94:97], v22 offset:34816
	v_mfma_f32_16x16x32_f16 v[114:117], v[118:121], v[106:109], v[114:117]
	s_waitcnt vmcnt(7)
	ds_write_b128 v19, v[62:65] offset:16384
	s_waitcnt vmcnt(6)
	ds_write_b128 v20, v[90:93] offset:16384
	v_mfma_f32_16x16x32_f16 v[40:43], v[118:121], v[110:113], v[40:43]
	ds_read_b128 v[118:121], v22 offset:36864
	s_waitcnt vmcnt(5)
	ds_write_b128 v17, v[126:129] offset:16384
	v_mfma_f32_16x16x32_f16 v[70:73], v[122:125], v[106:109], v[70:73]
	ds_read_b128 v[106:109], v23
	v_mfma_f32_16x16x32_f16 v[48:51], v[122:125], v[110:113], v[48:51]
	ds_read_b128 v[110:113], v23 offset:2048
	s_waitcnt lgkmcnt(1)
	v_mfma_f32_16x16x32_f16 v[36:39], v[58:61], v[106:109], v[36:39]
	ds_read_b128 v[122:125], v22 offset:38912
	s_waitcnt lgkmcnt(1)
	v_mfma_f32_16x16x32_f16 v[66:69], v[58:61], v[110:113], v[66:69]
	s_waitcnt vmcnt(4)
	ds_write_b128 v18, v[130:133] offset:16384
	v_mfma_f32_16x16x32_f16 v[44:47], v[94:97], v[106:109], v[44:47]
	s_waitcnt vmcnt(3)
	ds_write_b128 v19, v[74:77] offset:49152
	v_mfma_f32_16x16x32_f16 v[78:81], v[94:97], v[110:113], v[78:81]
	s_waitcnt vmcnt(2)
	ds_write_b128 v20, v[138:141] offset:49152
	v_mfma_f32_16x16x32_f16 v[82:85], v[118:121], v[106:109], v[82:85]
	s_waitcnt vmcnt(1)
	ds_write_b128 v17, v[142:145] offset:49152
	v_mfma_f32_16x16x32_f16 v[86:89], v[118:121], v[110:113], v[86:89]
	s_waitcnt vmcnt(0)
	ds_write_b128 v18, v[154:157] offset:49152
	s_waitcnt lgkmcnt(5)
	v_mfma_f32_16x16x32_f16 v[28:31], v[122:125], v[106:109], v[28:31]
	ds_read_b128 v[106:109], v23 offset:4096
	v_mfma_f32_16x16x32_f16 v[32:35], v[122:125], v[110:113], v[32:35]
	ds_read_b128 v[110:113], v23 offset:6144
	s_waitcnt lgkmcnt(1)
	v_mfma_f32_16x16x32_f16 v[98:101], v[58:61], v[106:109], v[98:101]
	s_waitcnt lgkmcnt(0)
	v_mfma_f32_16x16x32_f16 v[52:55], v[58:61], v[110:113], v[52:55]
	global_load_dwordx4 v[58:61], v[0:1], off offset:1536
	v_mfma_f32_16x16x32_f16 v[102:105], v[94:97], v[106:109], v[102:105]
	v_mfma_f32_16x16x32_f16 v[24:27], v[94:97], v[110:113], v[24:27]
	v_mfma_f32_16x16x32_f16 v[114:117], v[118:121], v[106:109], v[114:117]
	v_mfma_f32_16x16x32_f16 v[40:43], v[118:121], v[110:113], v[40:43]
	v_mfma_f32_16x16x32_f16 v[70:73], v[122:125], v[106:109], v[70:73]
	global_load_dwordx4 v[106:109], v[2:3], off offset:1536
	global_load_dwordx4 v[134:137], v[4:5], off offset:1536
	global_load_dwordx4 v[158:161], v[6:7], off offset:1536
	global_load_dwordx4 v[94:97], v[8:9], off offset:1536
	global_load_dwordx4 v[162:165], v[10:11], off offset:1536
	global_load_dwordx4 v[166:169], v[12:13], off offset:1536
	global_load_dwordx4 v[190:193], v[14:15], off offset:1536
	s_waitcnt lgkmcnt(0)
	s_barrier
; #define GL_LOAD(s_, kt_) if (VAR != 1) { a##s_##0 = GL_A(0, kt_); a##s_##1 = GL_A(1, kt_); a##s_##2 = GL_A(2, kt_); a##s_##3 = GL_A(3, kt_); b##s_##0 = GL_B(0, kt_); b##s_##1 = GL_B(1, kt_); b##s_##2 = GL_B(2, kt_); b##s_##3 = GL_B(3, kt_); }
; #define LDS_STORE(s_, buf_) if (VAR != 2) { LDS_ST1(sA, 0, buf_, a##s_##0) LDS_ST1(sA, 1, buf_, a##s_##1) LDS_ST1(sA, 2, buf_, a##s_##2) LDS_ST1(sA, 3, buf_, a##s_##3) LDS_ST1(sB, 0, buf_, b##s_##0) LDS_ST1(sB, 1, buf_, b##s_##1) LDS_ST1(sB, 2, buf_, b##s_##2) LDS_ST1(sB, 3, buf_, b##s_##3) }
;     ...
;   for (int kt = 0; kt < nk; kt += 2) {
;     if (kt + 2 < nk) { GL_LOAD(0, kt + 2) }
;     MMA_TILE(0)
;     LDS_STORE(1, 1)
;     if (VAR != 4) __syncthreads();
;     if (kt + 3 < nk) { GL_LOAD(1, kt + 3) }
;     MMA_TILE(1)
;     if (kt + 2 < nk) { LDS_STORE(0, 0) }
;     if (VAR != 4) __syncthreads();
	v_mfma_f32_16x16x32_f16 v[48:51], v[122:125], v[110:113], v[48:51]
	ds_read_b128 v[62:65], v16 offset:49152
	ds_read_b128 v[90:93], v21 offset:16384
	s_waitcnt lgkmcnt(0)
	v_mfma_f32_16x16x32_f16 v[36:39], v[62:65], v[90:93], v[36:39]
	ds_read_b128 v[74:77], v16 offset:51200
	ds_read_b128 v[110:113], v21 offset:18432
	s_waitcnt lgkmcnt(0)
	v_mfma_f32_16x16x32_f16 v[66:69], v[62:65], v[110:113], v[66:69]
	ds_read_b128 v[118:121], v16 offset:53248
	v_mfma_f32_16x16x32_f16 v[44:47], v[74:77], v[90:93], v[44:47]
	ds_read_b128 v[122:125], v16 offset:55296
	v_mfma_f32_16x16x32_f16 v[78:81], v[74:77], v[110:113], v[78:81]
	s_waitcnt lgkmcnt(1)
	v_mfma_f32_16x16x32_f16 v[82:85], v[118:121], v[90:93], v[82:85]
	v_mfma_f32_16x16x32_f16 v[86:89], v[118:121], v[110:113], v[86:89]
	s_waitcnt lgkmcnt(0)
	v_mfma_f32_16x16x32_f16 v[28:31], v[122:125], v[90:93], v[28:31]
	ds_read_b128 v[90:93], v21 offset:20480
	v_mfma_f32_16x16x32_f16 v[32:35], v[122:125], v[110:113], v[32:35]
	ds_read_b128 v[110:113], v21 offset:22528
	s_waitcnt lgkmcnt(1)
	v_mfma_f32_16x16x32_f16 v[98:101], v[62:65], v[90:93], v[98:101]
	s_waitcnt lgkmcnt(0)
	v_mfma_f32_16x16x32_f16 v[52:55], v[62:65], v[110:113], v[52:55]
	ds_read_b128 v[62:65], v22 offset:49152
	v_mfma_f32_16x16x32_f16 v[102:105], v[74:77], v[90:93], v[102:105]
	v_mfma_f32_16x16x32_f16 v[24:27], v[74:77], v[110:113], v[24:27]
	ds_read_b128 v[74:77], v22 offset:51200
	v_mfma_f32_16x16x32_f16 v[114:117], v[118:121], v[90:93], v[114:117]
	s_waitcnt vmcnt(7)
	ds_write_b128 v19, v[58:61]
	s_waitcnt vmcnt(6)
	ds_write_b128 v20, v[106:109]
	v_mfma_f32_16x16x32_f16 v[40:43], v[118:121], v[110:113], v[40:43]
	ds_read_b128 v[118:121], v22 offset:53248
	s_waitcnt vmcnt(5)
	ds_write_b128 v17, v[134:137]
	v_mfma_f32_16x16x32_f16 v[70:73], v[122:125], v[90:93], v[70:73]
	ds_read_b128 v[90:93], v23 offset:16384
	v_mfma_f32_16x16x32_f16 v[48:51], v[122:125], v[110:113], v[48:51]
	ds_read_b128 v[110:113], v23 offset:18432
	s_waitcnt lgkmcnt(1)
	v_mfma_f32_16x16x32_f16 v[36:39], v[62:65], v[90:93], v[36:39]
	ds_read_b128 v[122:125], v22 offset:55296
	s_waitcnt lgkmcnt(1)
	v_mfma_f32_16x16x32_f16 v[66:69], v[62:65], v[110:113], v[66:69]
	s_waitcnt vmcnt(4)
	ds_write_b128 v18, v[158:161]
	v_mfma_f32_16x16x32_f16 v[44:47], v[74:77], v[90:93], v[44:47]
	s_waitcnt vmcnt(3)
	ds_write_b128 v19, v[94:97] offset:32768
	v_mfma_f32_16x16x32_f16 v[78:81], v[74:77], v[110:113], v[78:81]
	s_waitcnt vmcnt(2)
	ds_write_b128 v20, v[162:165] offset:32768
	v_mfma_f32_16x16x32_f16 v[82:85], v[118:121], v[90:93], v[82:85]
	s_waitcnt vmcnt(1)
	ds_write_b128 v17, v[166:169] offset:32768
	v_mfma_f32_16x16x32_f16 v[86:89], v[118:121], v[110:113], v[86:89]
	s_waitcnt vmcnt(0)
	ds_write_b128 v18, v[190:193] offset:32768
	s_waitcnt lgkmcnt(5)
	v_mfma_f32_16x16x32_f16 v[28:31], v[122:125], v[90:93], v[28:31]
	ds_read_b128 v[90:93], v23 offset:20480
	v_mfma_f32_16x16x32_f16 v[32:35], v[122:125], v[110:113], v[32:35]
	ds_read_b128 v[110:113], v23 offset:22528
	s_waitcnt lgkmcnt(1)
	v_mfma_f32_16x16x32_f16 v[98:101], v[62:65], v[90:93], v[98:101]
	s_waitcnt lgkmcnt(0)
	v_mfma_f32_16x16x32_f16 v[52:55], v[62:65], v[110:113], v[52:55]
	global_load_dwordx4 v[62:65], v[0:1], off offset:1664
	v_mfma_f32_16x16x32_f16 v[102:105], v[74:77], v[90:93], v[102:105]
	v_mfma_f32_16x16x32_f16 v[24:27], v[74:77], v[110:113], v[24:27]
	v_mfma_f32_16x16x32_f16 v[114:117], v[118:121], v[90:93], v[114:117]
	v_mfma_f32_16x16x32_f16 v[40:43], v[118:121], v[110:113], v[40:43]
	v_mfma_f32_16x16x32_f16 v[70:73], v[122:125], v[90:93], v[70:73]
	global_load_dwordx4 v[90:93], v[2:3], off offset:1664
	global_load_dwordx4 v[126:129], v[4:5], off offset:1664
	global_load_dwordx4 v[130:133], v[6:7], off offset:1664
	global_load_dwordx4 v[74:77], v[8:9], off offset:1664
	global_load_dwordx4 v[138:141], v[10:11], off offset:1664
	global_load_dwordx4 v[142:145], v[12:13], off offset:1664
	global_load_dwordx4 v[154:157], v[14:15], off offset:1664
	s_waitcnt lgkmcnt(0)
	s_barrier
	v_mfma_f32_16x16x32_f16 v[48:51], v[122:125], v[110:113], v[48:51]
	ds_read_b128 v[58:61], v16 offset:32768
	ds_read_b128 v[106:109], v21
	s_waitcnt lgkmcnt(0)
	v_mfma_f32_16x16x32_f16 v[36:39], v[58:61], v[106:109], v[36:39]
	ds_read_b128 v[94:97], v16 offset:34816
	ds_read_b128 v[110:113], v21 offset:2048
	s_waitcnt lgkmcnt(0)
	v_mfma_f32_16x16x32_f16 v[66:69], v[58:61], v[110:113], v[66:69]
	ds_read_b128 v[118:121], v16 offset:36864
	v_mfma_f32_16x16x32_f16 v[44:47], v[94:97], v[106:109], v[44:47]
	ds_read_b128 v[122:125], v16 offset:38912
	v_mfma_f32_16x16x32_f16 v[78:81], v[94:97], v[110:113], v[78:81]
	s_waitcnt lgkmcnt(1)
	v_mfma_f32_16x16x32_f16 v[82:85], v[118:121], v[106:109], v[82:85]
	v_mfma_f32_16x16x32_f16 v[86:89], v[118:121], v[110:113], v[86:89]
	s_waitcnt lgkmcnt(0)
	v_mfma_f32_16x16x32_f16 v[28:31], v[122:125], v[106:109], v[28:31]
	ds_read_b128 v[106:109], v21 offset:4096
	v_mfma_f32_16x16x32_f16 v[32:35], v[122:125], v[110:113], v[32:35]
	ds_read_b128 v[110:113], v21 offset:6144
	s_waitcnt lgkmcnt(1)
	v_mfma_f32_16x16x32_f16 v[98:101], v[58:61], v[106:109], v[98:101]
	s_waitcnt lgkmcnt(0)
	v_mfma_f32_16x16x32_f16 v[52:55], v[58:61], v[110:113], v[52:55]
	ds_read_b128 v[58:61], v22 offset:32768
	v_mfma_f32_16x16x32_f16 v[102:105], v[94:97], v[106:109], v[102:105]
	v_mfma_f32_16x16x32_f16 v[24:27], v[94:97], v[110:113], v[24:27]
	ds_read_b128 v[94:97], v22 offset:34816
	v_mfma_f32_16x16x32_f16 v[114:117], v[118:121], v[106:109], v[114:117]
	s_waitcnt vmcnt(7)
	ds_write_b128 v19, v[62:65] offset:16384
	s_waitcnt vmcnt(6)
; #define GL_LOAD(s_, kt_) if (VAR != 1) { a##s_##0 = GL_A(0, kt_); a##s_##1 = GL_A(1, kt_); a##s_##2 = GL_A(2, kt_); a##s_##3 = GL_A(3, kt_); b##s_##0 = GL_B(0, kt_); b##s_##1 = GL_B(1, kt_); b##s_##2 = GL_B(2, kt_); b##s_##3 = GL_B(3, kt_); }
; #define LDS_STORE(s_, buf_) if (VAR != 2) { LDS_ST1(sA, 0, buf_, a##s_##0) LDS_ST1(sA, 1, buf_, a##s_##1) LDS_ST1(sA, 2, buf_, a##s_##2) LDS_ST1(sA, 3, buf_, a##s_##3) LDS_ST1(sB, 0, buf_, b##s_##0) LDS_ST1(sB, 1, buf_, b##s_##1) LDS_ST1(sB, 2, buf_, b##s_##2) LDS_ST1(sB, 3, buf_, b##s_##3) }
;     ...
;   for (int kt = 0; kt < nk; kt += 2) {
;     if (kt + 2 < nk) { GL_LOAD(0, kt + 2) }
;     MMA_TILE(0)
;     LDS_STORE(1, 1)
;     if (VAR != 4) __syncthreads();
;     if (kt + 3 < nk) { GL_LOAD(1, kt + 3) }
;     MMA_TILE(1)
;     if (kt + 2 < nk) { LDS_STORE(0, 0) }
;     if (VAR != 4) __syncthreads();
	ds_write_b128 v20, v[90:93] offset:16384
	v_mfma_f32_16x16x32_f16 v[40:43], v[118:121], v[110:113], v[40:43]
	ds_read_b128 v[118:121], v22 offset:36864
	s_waitcnt vmcnt(5)
	ds_write_b128 v17, v[126:129] offset:16384
	v_mfma_f32_16x16x32_f16 v[70:73], v[122:125], v[106:109], v[70:73]
	ds_read_b128 v[106:109], v23
	v_mfma_f32_16x16x32_f16 v[48:51], v[122:125], v[110:113], v[48:51]
	ds_read_b128 v[110:113], v23 offset:2048
	s_waitcnt lgkmcnt(1)
	v_mfma_f32_16x16x32_f16 v[36:39], v[58:61], v[106:109], v[36:39]
	ds_read_b128 v[122:125], v22 offset:38912
	s_waitcnt lgkmcnt(1)
	v_mfma_f32_16x16x32_f16 v[66:69], v[58:61], v[110:113], v[66:69]
	s_waitcnt vmcnt(4)
	ds_write_b128 v18, v[130:133] offset:16384
	v_mfma_f32_16x16x32_f16 v[44:47], v[94:97], v[106:109], v[44:47]
	s_waitcnt vmcnt(3)
	ds_write_b128 v19, v[74:77] offset:49152
	v_mfma_f32_16x16x32_f16 v[78:81], v[94:97], v[110:113], v[78:81]
	s_waitcnt vmcnt(2)
	ds_write_b128 v20, v[138:141] offset:49152
	v_mfma_f32_16x16x32_f16 v[82:85], v[118:121], v[106:109], v[82:85]
	s_waitcnt vmcnt(1)
	ds_write_b128 v17, v[142:145] offset:49152
	v_mfma_f32_16x16x32_f16 v[86:89], v[118:121], v[110:113], v[86:89]
	s_waitcnt vmcnt(0)
	ds_write_b128 v18, v[154:157] offset:49152
	s_waitcnt lgkmcnt(5)
	v_mfma_f32_16x16x32_f16 v[28:31], v[122:125], v[106:109], v[28:31]
	ds_read_b128 v[106:109], v23 offset:4096
	v_mfma_f32_16x16x32_f16 v[32:35], v[122:125], v[110:113], v[32:35]
	ds_read_b128 v[110:113], v23 offset:6144
	s_waitcnt lgkmcnt(1)
	v_mfma_f32_16x16x32_f16 v[98:101], v[58:61], v[106:109], v[98:101]
	s_waitcnt lgkmcnt(0)
	v_mfma_f32_16x16x32_f16 v[52:55], v[58:61], v[110:113], v[52:55]
	global_load_dwordx4 v[58:61], v[0:1], off offset:1792
	v_mfma_f32_16x16x32_f16 v[102:105], v[94:97], v[106:109], v[102:105]
	v_mfma_f32_16x16x32_f16 v[24:27], v[94:97], v[110:113], v[24:27]
	v_mfma_f32_16x16x32_f16 v[114:117], v[118:121], v[106:109], v[114:117]
	v_mfma_f32_16x16x32_f16 v[40:43], v[118:121], v[110:113], v[40:43]
	v_mfma_f32_16x16x32_f16 v[70:73], v[122:125], v[106:109], v[70:73]
	global_load_dwordx4 v[106:109], v[2:3], off offset:1792
	global_load_dwordx4 v[134:137], v[4:5], off offset:1792
	global_load_dwordx4 v[158:161], v[6:7], off offset:1792
	global_load_dwordx4 v[94:97], v[8:9], off offset:1792
	global_load_dwordx4 v[162:165], v[10:11], off offset:1792
	global_load_dwordx4 v[166:169], v[12:13], off offset:1792
	global_load_dwordx4 v[190:193], v[14:15], off offset:1792
	s_waitcnt lgkmcnt(0)
	s_barrier
	v_mfma_f32_16x16x32_f16 v[48:51], v[122:125], v[110:113], v[48:51]
	ds_read_b128 v[62:65], v16 offset:49152
	ds_read_b128 v[90:93], v21 offset:16384
	s_waitcnt lgkmcnt(0)
	v_mfma_f32_16x16x32_f16 v[36:39], v[62:65], v[90:93], v[36:39]
	ds_read_b128 v[74:77], v16 offset:51200
	ds_read_b128 v[110:113], v21 offset:18432
	s_waitcnt lgkmcnt(0)
	v_mfma_f32_16x16x32_f16 v[66:69], v[62:65], v[110:113], v[66:69]
	ds_read_b128 v[118:121], v16 offset:53248
	v_mfma_f32_16x16x32_f16 v[44:47], v[74:77], v[90:93], v[44:47]
	ds_read_b128 v[122:125], v16 offset:55296
	v_mfma_f32_16x16x32_f16 v[78:81], v[74:77], v[110:113], v[78:81]
	v_or_b32_e32 v130, s11, v56
	s_waitcnt lgkmcnt(1)
	v_mfma_f32_16x16x32_f16 v[82:85], v[118:121], v[90:93], v[82:85]
	v_lshrrev_b32_e32 v150, 4, v130
	v_mfma_f32_16x16x32_f16 v[86:89], v[118:121], v[110:113], v[86:89]
	s_waitcnt lgkmcnt(0)
	v_mfma_f32_16x16x32_f16 v[28:31], v[122:125], v[90:93], v[28:31]
	ds_read_b128 v[90:93], v21 offset:20480
	v_mfma_f32_16x16x32_f16 v[32:35], v[122:125], v[110:113], v[32:35]
	ds_read_b128 v[110:113], v21 offset:22528
	s_waitcnt lgkmcnt(1)
	v_mfma_f32_16x16x32_f16 v[98:101], v[62:65], v[90:93], v[98:101]
	s_waitcnt lgkmcnt(0)
	v_mfma_f32_16x16x32_f16 v[52:55], v[62:65], v[110:113], v[52:55]
	ds_read_b128 v[62:65], v22 offset:49152
	v_mfma_f32_16x16x32_f16 v[102:105], v[74:77], v[90:93], v[102:105]
	v_mfma_f32_16x16x32_f16 v[24:27], v[74:77], v[110:113], v[24:27]
	ds_read_b128 v[74:77], v22 offset:51200
	v_mfma_f32_16x16x32_f16 v[114:117], v[118:121], v[90:93], v[114:117]
	s_waitcnt vmcnt(7)
	ds_write_b128 v19, v[58:61]
	s_waitcnt vmcnt(6)
	ds_write_b128 v20, v[106:109]
	v_mfma_f32_16x16x32_f16 v[40:43], v[118:121], v[110:113], v[40:43]
	ds_read_b128 v[118:121], v22 offset:53248
	s_waitcnt vmcnt(5)
	ds_write_b128 v17, v[134:137]
	v_mfma_f32_16x16x32_f16 v[70:73], v[122:125], v[90:93], v[70:73]
	ds_read_b128 v[90:93], v23 offset:16384
	v_mfma_f32_16x16x32_f16 v[48:51], v[122:125], v[110:113], v[48:51]
	ds_read_b128 v[110:113], v23 offset:18432
	s_waitcnt lgkmcnt(1)
	v_mfma_f32_16x16x32_f16 v[36:39], v[62:65], v[90:93], v[36:39]
	ds_read_b128 v[122:125], v22 offset:55296
	s_waitcnt lgkmcnt(1)
	v_mfma_f32_16x16x32_f16 v[66:69], v[62:65], v[110:113], v[66:69]
	s_waitcnt vmcnt(4)
	ds_write_b128 v18, v[158:161]
	v_mfma_f32_16x16x32_f16 v[44:47], v[74:77], v[90:93], v[44:47]
	s_waitcnt vmcnt(3)
	ds_write_b128 v19, v[94:97] offset:32768
	v_mfma_f32_16x16x32_f16 v[78:81], v[74:77], v[110:113], v[78:81]
	s_waitcnt vmcnt(2)
	ds_write_b128 v20, v[162:165] offset:32768
	v_mfma_f32_16x16x32_f16 v[82:85], v[118:121], v[90:93], v[82:85]
	s_waitcnt vmcnt(1)
	ds_write_b128 v17, v[166:169] offset:32768
	v_mfma_f32_16x16x32_f16 v[86:89], v[118:121], v[110:113], v[86:89]
	s_waitcnt vmcnt(0)
	ds_write_b128 v18, v[190:193] offset:32768
	s_waitcnt lgkmcnt(5)
	v_mfma_f32_16x16x32_f16 v[28:31], v[122:125], v[90:93], v[28:31]
	ds_read_b128 v[90:93], v23 offset:20480
	v_mfma_f32_16x16x32_f16 v[32:35], v[122:125], v[110:113], v[32:35]
	ds_read_b128 v[110:113], v23 offset:22528
	s_waitcnt lgkmcnt(1)
	v_mfma_f32_16x16x32_f16 v[98:101], v[62:65], v[90:93], v[98:101]
	s_waitcnt lgkmcnt(0)
	v_mfma_f32_16x16x32_f16 v[52:55], v[62:65], v[110:113], v[52:55]
	global_load_dwordx4 v[62:65], v[0:1], off offset:1920
	global_load_dwordx4 v[0:3], v[2:3], off offset:1920
	v_mfma_f32_16x16x32_f16 v[102:105], v[74:77], v[90:93], v[102:105]
	v_mfma_f32_16x16x32_f16 v[24:27], v[74:77], v[110:113], v[24:27]
	v_mfma_f32_16x16x32_f16 v[114:117], v[118:121], v[90:93], v[114:117]
	v_mfma_f32_16x16x32_f16 v[40:43], v[118:121], v[110:113], v[40:43]
	v_mfma_f32_16x16x32_f16 v[70:73], v[122:125], v[90:93], v[70:73]
	global_load_dwordx4 v[90:93], v[4:5], off offset:1920
	global_load_dwordx4 v[4:7], v[6:7], off offset:1920
	global_load_dwordx4 v[74:77], v[8:9], off offset:1920
	global_load_dwordx4 v[8:11], v[10:11], off offset:1920
	global_load_dwordx4 v[126:129], v[12:13], off offset:1920
	global_load_dwordx4 v[12:15], v[14:15], off offset:1920
	s_waitcnt lgkmcnt(0)
	s_barrier
; #define GL_LOAD(s_, kt_) if (VAR != 1) { a##s_##0 = GL_A(0, kt_); a##s_##1 = GL_A(1, kt_); a##s_##2 = GL_A(2, kt_); a##s_##3 = GL_A(3, kt_); b##s_##0 = GL_B(0, kt_); b##s_##1 = GL_B(1, kt_); b##s_##2 = GL_B(2, kt_); b##s_##3 = GL_B(3, kt_); }
; #define LDS_STORE(s_, buf_) if (VAR != 2) { LDS_ST1(sA, 0, buf_, a##s_##0) LDS_ST1(sA, 1, buf_, a##s_##1) LDS_ST1(sA, 2, buf_, a##s_##2) LDS_ST1(sA, 3, buf_, a##s_##3) LDS_ST1(sB, 0, buf_, b##s_##0) LDS_ST1(sB, 1, buf_, b##s_##1) LDS_ST1(sB, 2, buf_, b##s_##2) LDS_ST1(sB, 3, buf_, b##s_##3) }
;     ...
;   for (int kt = 0; kt < nk; kt += 2) {
;     if (kt + 2 < nk) { GL_LOAD(0, kt + 2) }
;     MMA_TILE(0)
;     LDS_STORE(1, 1)
;     if (VAR != 4) __syncthreads();
;     if (kt + 3 < nk) { GL_LOAD(1, kt + 3) }
;     MMA_TILE(1)
;     if (kt + 2 < nk) { LDS_STORE(0, 0) }
;     if (VAR != 4) __syncthreads();
	ds_read_b128 v[58:61], v16 offset:32768
	v_mfma_f32_16x16x32_f16 v[48:51], v[122:125], v[110:113], v[48:51]
	ds_read_b128 v[94:97], v16 offset:34816
	ds_read_b128 v[106:109], v21
	ds_read_b128 v[110:113], v21 offset:2048
	ds_read_b128 v[118:121], v16 offset:36864
	ds_read_b128 v[122:125], v16 offset:38912
	s_waitcnt lgkmcnt(3)
	v_mfma_f32_16x16x32_f16 v[36:39], v[58:61], v[106:109], v[36:39]
	v_mfma_f32_16x16x32_f16 v[44:47], v[94:97], v[106:109], v[44:47]
	s_waitcnt lgkmcnt(1)
	v_mfma_f32_16x16x32_f16 v[82:85], v[118:121], v[106:109], v[82:85]
	s_waitcnt lgkmcnt(0)
	v_mfma_f32_16x16x32_f16 v[28:31], v[122:125], v[106:109], v[28:31]
	v_mfma_f32_16x16x32_f16 v[66:69], v[58:61], v[110:113], v[66:69]
	v_mfma_f32_16x16x32_f16 v[78:81], v[94:97], v[110:113], v[78:81]
	v_mfma_f32_16x16x32_f16 v[86:89], v[118:121], v[110:113], v[86:89]
	v_mfma_f32_16x16x32_f16 v[32:35], v[122:125], v[110:113], v[32:35]
	ds_read_b128 v[106:109], v21 offset:4096
	ds_read_b128 v[110:113], v21 offset:6144
	s_waitcnt lgkmcnt(1)
	v_mfma_f32_16x16x32_f16 v[98:101], v[58:61], v[106:109], v[98:101]
	v_mfma_f32_16x16x32_f16 v[102:105], v[94:97], v[106:109], v[102:105]
	v_mfma_f32_16x16x32_f16 v[114:117], v[118:121], v[106:109], v[114:117]
	v_mfma_f32_16x16x32_f16 v[70:73], v[122:125], v[106:109], v[70:73]
	s_waitcnt lgkmcnt(0)
	v_mfma_f32_16x16x32_f16 v[52:55], v[58:61], v[110:113], v[52:55]
	ds_read_b128 v[58:61], v22 offset:32768
	v_mfma_f32_16x16x32_f16 v[24:27], v[94:97], v[110:113], v[24:27]
	v_mfma_f32_16x16x32_f16 v[40:43], v[118:121], v[110:113], v[40:43]
	v_mfma_f32_16x16x32_f16 v[48:51], v[122:125], v[110:113], v[48:51]
	ds_read_b128 v[94:97], v22 offset:34816
	ds_read_b128 v[106:109], v23
	ds_read_b128 v[110:113], v23 offset:2048
	ds_read_b128 v[118:121], v22 offset:36864
	ds_read_b128 v[122:125], v22 offset:38912
	s_waitcnt lgkmcnt(3)
	v_mfma_f32_16x16x32_f16 v[36:39], v[58:61], v[106:109], v[36:39]
	v_mfma_f32_16x16x32_f16 v[44:47], v[94:97], v[106:109], v[44:47]
	s_waitcnt lgkmcnt(1)
	v_mfma_f32_16x16x32_f16 v[82:85], v[118:121], v[106:109], v[82:85]
	s_waitcnt lgkmcnt(0)
	v_mfma_f32_16x16x32_f16 v[28:31], v[122:125], v[106:109], v[28:31]
	v_mfma_f32_16x16x32_f16 v[66:69], v[58:61], v[110:113], v[66:69]
	v_mfma_f32_16x16x32_f16 v[78:81], v[94:97], v[110:113], v[78:81]
	v_mfma_f32_16x16x32_f16 v[86:89], v[118:121], v[110:113], v[86:89]
	v_mfma_f32_16x16x32_f16 v[32:35], v[122:125], v[110:113], v[32:35]
	ds_read_b128 v[106:109], v23 offset:4096
	ds_read_b128 v[110:113], v23 offset:6144
	s_waitcnt vmcnt(7)
	ds_write_b128 v19, v[62:65] offset:16384
	s_waitcnt vmcnt(6)
	ds_write_b128 v20, v[0:3] offset:16384
	s_waitcnt vmcnt(5)
	ds_write_b128 v17, v[90:93] offset:16384
	s_waitcnt vmcnt(4)
	ds_write_b128 v18, v[4:7] offset:16384
	s_waitcnt vmcnt(3)
	ds_write_b128 v19, v[74:77] offset:49152
	s_waitcnt vmcnt(2)
	ds_write_b128 v20, v[8:11] offset:49152
	s_waitcnt lgkmcnt(7)
	v_mfma_f32_16x16x32_f16 v[98:101], v[58:61], v[106:109], v[98:101]
	s_waitcnt vmcnt(1)
	ds_write_b128 v17, v[126:129] offset:49152
	s_waitcnt vmcnt(0)
	ds_write_b128 v18, v[12:15] offset:49152
	s_waitcnt lgkmcnt(0)
	s_barrier
	v_mfma_f32_16x16x32_f16 v[52:55], v[58:61], v[110:113], v[52:55]
	ds_read_b128 v[8:11], v16 offset:49152
	v_mfma_f32_16x16x32_f16 v[0:3], v[94:97], v[110:113], v[24:27]
	v_mfma_f32_16x16x32_f16 v[4:7], v[118:121], v[110:113], v[40:43]
	v_mfma_f32_16x16x32_f16 v[12:15], v[122:125], v[110:113], v[48:51]
	s_nop 0
	ds_read_b128 v[24:27], v16 offset:51200
	ds_read_b128 v[40:43], v21 offset:16384
	ds_read_b128 v[48:51], v21 offset:18432
	ds_read_b128 v[58:61], v16 offset:53248
	ds_read_b128 v[16:19], v16 offset:55296
	v_mfma_f32_16x16x32_f16 v[102:105], v[94:97], v[106:109], v[102:105]
	v_mfma_f32_16x16x32_f16 v[114:117], v[118:121], v[106:109], v[114:117]
	v_mfma_f32_16x16x32_f16 v[70:73], v[122:125], v[106:109], v[70:73]
	s_waitcnt lgkmcnt(3)
	v_mfma_f32_16x16x32_f16 v[36:39], v[8:11], v[40:43], v[36:39]
	v_mfma_f32_16x16x32_f16 v[44:47], v[24:27], v[40:43], v[44:47]
	s_waitcnt lgkmcnt(1)
	v_mfma_f32_16x16x32_f16 v[62:65], v[58:61], v[40:43], v[82:85]
	ds_read_b128 v[74:77], v21 offset:20480
	s_nop 1
	ds_read_b128 v[82:85], v21 offset:22528
	s_waitcnt lgkmcnt(2)
	v_mfma_f32_16x16x32_f16 v[28:31], v[16:19], v[40:43], v[28:31]
	ds_read_b128 v[40:43], v23 offset:16384
	ds_read_b128 v[90:93], v23 offset:18432
	ds_read_b128 v[94:97], v22 offset:49152
	ds_read_b128 v[106:109], v22 offset:51200
	ds_read_b128 v[110:113], v23 offset:20480
	ds_read_b128 v[118:121], v23 offset:22528
	ds_read_b128 v[122:125], v22 offset:53248
	ds_read_b128 v[126:129], v22 offset:55296
	s_waitcnt lgkmcnt(0)
	v_mfma_f32_16x16x32_f16 v[20:23], v[24:27], v[48:51], v[78:81]
	s_barrier
; DI int TIDX() { int t = threadIdx.x; asm volatile("" : "+v"(t)); return t; }
; DI unsigned pack2(float lo, float hi) { f2_t v = {lo, hi}; h2_t b = __builtin_convertvector(v, h2_t); return __builtin_bit_cast(unsigned, b); }
; DI void epi_residual(const f32x4 (&v)[4][4], int row0, int col0, const float* xsrc, float* x, bf16_t* xb, float* ssq_out, bool write_xb, bool write_ssq) {
;   const int lane = TIDX() & 63, lr = lane & 15, g = lane >> 4;
; #pragma unroll
;   for (int mt = 0; mt < 4; ++mt) {
;     const int row = row0 + mt * 16 + lr;
;     float ss = 0.f;
; #pragma unroll
;     for (int nt = 0; nt < 4; ++nt) {
;       const int col = col0 + nt * 16 + 4 * g;
;       float4* px = (float4*)(x + (size_t)row * DM + col);
;       float4 o = *(const float4*)(xsrc + (size_t)row * DM + col);
;       o.x += v[mt][nt][0]; o.y += v[mt][nt][1]; o.z += v[mt][nt][2]; o.w += v[mt][nt][3];
;       *px = o;
;       ss += (o.x * o.x + o.y * o.y) + (o.z * o.z + o.w * o.w);
;       if (write_xb) *(uint2*)(xb + (size_t)row * DM + col) = make_uint2(pack2(o.x, o.y), pack2(o.z, o.w));
;     }
;     if (write_ssq) {
;       ss += __shfl_xor(ss, 16); ss += __shfl_xor(ss, 32);
;       if (g == 0) ssq_out[(size_t)row * 16 + (col0 >> 6)] = ss;
;     }
;   }
; }
	v_mfma_f32_16x16x32_f16 v[78:81], v[58:61], v[48:51], v[86:89]
	s_nop 2
	v_add_u32_e32 v86, s6, v57
	v_mov_b32_e32 v87, v148
	v_mfma_f32_16x16x32_f16 v[66:69], v[8:11], v[48:51], v[66:69]
	v_readlane_b32 s6, v254, 41
	v_bfe_u32 v134, v87, 4, 2
	v_mfma_f32_16x16x32_f16 v[32:35], v[16:19], v[48:51], v[32:35]
	v_and_or_b32 v50, v87, 15, v86
	v_ashrrev_i32_e32 v51, 31, v50
	v_lshl_or_b32 v135, v134, 2, v130
	v_readlane_b32 s7, v254, 42
	v_lshlrev_b64 v[130:131], 12, v[50:51]
	v_lshl_add_u64 v[132:133], s[4:5], 0, v[130:131]
	v_lshl_add_u64 v[48:49], s[6:7], 0, v[150:151]
	v_lshlrev_b32_e32 v150, 2, v135
	v_lshl_add_u64 v[132:133], v[132:133], 0, v[150:151]
	v_mfma_f32_16x16x32_f16 v[86:89], v[8:11], v[74:77], v[98:101]
	v_readlane_b32 s6, v254, 43
	v_readlane_b32 s7, v254, 44
	v_cmp_eq_u32_e32 vcc, 0, v134
	v_mfma_f32_16x16x32_f16 v[98:101], v[24:27], v[74:77], v[102:105]
	v_mfma_f32_16x16x32_f16 v[102:105], v[58:61], v[74:77], v[114:117]
	s_nop 2
	global_load_dwordx4 v[114:117], v[132:133], off
	v_mfma_f32_16x16x32_f16 v[36:39], v[94:97], v[40:43], v[36:39]
	v_mfma_f32_16x16x32_f16 v[70:73], v[16:19], v[74:77], v[70:73]
	v_lshlrev_b64 v[76:77], 11, v[50:51]
	v_lshl_add_u64 v[74:75], s[12:13], 0, v[130:131]
	v_lshl_add_u64 v[76:77], s[6:7], 0, v[76:77]
	v_mfma_f32_16x16x32_f16 v[8:11], v[8:11], v[82:85], v[52:55]
	v_lshl_add_u64 v[74:75], v[74:75], 0, v[150:151]
	s_waitcnt vmcnt(0)
	s_nop 0
	v_pk_add_f32 v[36:37], v[36:37], v[114:115]
	v_pk_add_f32 v[38:39], v[38:39], v[116:117]
	v_lshlrev_b32_e32 v52, 1, v135
	v_mov_b32_e32 v53, v151
	v_cvt_pk_f16_f32 v54, v36, v37
	v_cvt_pk_f16_f32 v55, v38, v39
	v_lshl_add_u64 v[76:77], v[76:77], 0, v[52:53]
	global_store_dwordx4 v[74:75], v[36:39], off
	global_store_dwordx2 v[76:77], v[54:55], off
	v_mfma_f32_16x16x32_f16 v[0:3], v[24:27], v[82:85], v[0:3]
	v_mul_f32_e64 v54, v36, v36
	v_mul_f32_e64 v55, v37, v37
	v_mfma_f32_16x16x32_f16 v[24:27], v[106:109], v[40:43], v[44:47]
	s_nop 2
	global_load_dwordx4 v[44:47], v[132:133], off offset:64
	v_mfma_f32_16x16x32_f16 v[4:7], v[58:61], v[82:85], v[4:7]
	s_waitcnt vmcnt(0)
	s_nop 1
	v_pk_add_f32 v[24:25], v[24:25], v[44:45]
	v_pk_add_f32 v[26:27], v[26:27], v[46:47]
	v_cvt_pk_f16_f32 v44, v24, v25
	v_cvt_pk_f16_f32 v45, v26, v27
	global_store_dwordx4 v[74:75], v[24:27], off offset:64
	global_store_dwordx2 v[76:77], v[44:45], off offset:32
	v_mfma_f32_16x16x32_f16 v[58:61], v[16:19], v[82:85], v[12:15]
	s_nop 2
	global_load_dwordx4 v[12:15], v[132:133], off offset:128
	v_mfma_f32_16x16x32_f16 v[16:19], v[122:125], v[40:43], v[62:65]
	v_mfma_f32_16x16x32_f16 v[44:47], v[94:97], v[90:93], v[66:69]
	s_nop 2
	v_mul_f32_e64 v66, v26, v26
	v_mul_f32_e64 v67, v27, v27
	v_mfma_f32_16x16x32_f16 v[32:35], v[126:129], v[90:93], v[32:35]
	s_waitcnt vmcnt(0)
	v_pk_add_f32 v[12:13], v[16:17], v[12:13]
	v_pk_add_f32 v[14:15], v[18:19], v[14:15]
	v_mfma_f32_16x16x32_f16 v[16:19], v[126:129], v[40:43], v[28:31]
	global_store_dwordx4 v[74:75], v[12:15], off offset:128
	s_nop 1
	v_cvt_pk_f16_f32 v28, v12, v13
	v_cvt_pk_f16_f32 v29, v14, v15
	global_store_dwordx2 v[76:77], v[28:29], off offset:64
	global_load_dwordx4 v[28:31], v[132:133], off offset:192
	v_mfma_f32_16x16x32_f16 v[40:43], v[106:109], v[90:93], v[20:23]
	v_mul_f32_e64 v12, v12, v12
	v_mul_f32_e64 v13, v13, v13
	v_pk_mul_f32 v[14:15], v[14:15], v[14:15]
	v_add_f32_e32 v12, v12, v13
	v_pk_mul_f32 v[20:21], v[38:39], v[38:39]
	v_pk_mul_f32 v[22:23], v[24:25], v[24:25]
	v_add_f32_e32 v14, v14, v15
	v_add_f32_e32 v12, v12, v14
	v_mfma_f32_16x16x32_f16 v[36:39], v[122:125], v[90:93], v[78:81]
	s_waitcnt vmcnt(0)
	v_pk_add_f32 v[62:63], v[16:17], v[28:29]
	v_add_f32_e32 v16, v20, v21
	v_add_f32_e32 v17, v54, v55
	v_pk_add_f32 v[64:65], v[18:19], v[30:31]
	v_add_f32_e32 v16, v17, v16
	v_add_f32_e32 v17, v66, v67
	v_add_f32_e32 v18, v22, v23
	v_add_f32_e32 v17, v18, v17
	global_store_dwordx4 v[74:75], v[62:65], off offset:192
	v_pk_mul_f32 v[68:69], v[62:63], v[62:63]
	v_pk_mul_f32 v[74:75], v[64:65], v[64:65]
	v_add_f32_e32 v54, v16, v17
	v_add_f32_e32 v54, v54, v12
	v_mfma_f32_16x16x32_f16 v[12:15], v[94:97], v[118:121], v[8:11]
	s_nop 2
	v_add_f32_e32 v8, v74, v75
	v_add_f32_e32 v9, v68, v69
	v_add_f32_e32 v55, v9, v8
	v_mfma_f32_16x16x32_f16 v[8:11], v[106:109], v[118:121], v[0:3]
	s_nop 2
	v_add_f32_e32 v2, v54, v55
	ds_bpermute_b32 v3, v189, v2
	v_cvt_pk_f16_f32 v0, v62, v63
	v_cvt_pk_f16_f32 v1, v64, v65
	v_mfma_f32_16x16x32_f16 v[28:31], v[94:97], v[110:113], v[86:89]
	global_store_dwordx2 v[76:77], v[0:1], off offset:96
	s_waitcnt lgkmcnt(0)
	v_add_f32_e32 v54, v2, v3
	ds_bpermute_b32 v55, v188, v54
	v_mfma_f32_16x16x32_f16 v[24:27], v[106:109], v[110:113], v[98:101]
	v_mfma_f32_16x16x32_f16 v[20:23], v[122:125], v[110:113], v[102:105]
	v_mfma_f32_16x16x32_f16 v[16:19], v[126:129], v[110:113], v[70:73]
	v_mfma_f32_16x16x32_f16 v[4:7], v[122:125], v[118:121], v[4:7]
	v_mfma_f32_16x16x32_f16 v[0:3], v[126:129], v[118:121], v[58:61]
	s_and_saveexec_b64 s[6:7], vcc
	s_cbranch_execz .LBB0_1252
	s_waitcnt lgkmcnt(0)
	v_add_f32_e32 v58, v54, v55
	v_lshlrev_b64 v[54:55], 6, v[50:51]
	v_lshl_add_u64 v[54:55], v[48:49], 0, v[54:55]
	global_store_dword v[54:55], v58, off

; DI int BIDX() { int b = blockIdx.x; asm volatile("" : "+s"(b)); return b; }
; DI int tile_groups(int MT, int NT) { return (MT >> 6) * ((NT + 7) >> 3) * 512; }
; DI void load_rstd(float (&rs)[4], const float* ssq, int row0, int lr) {
; #pragma unroll
;   for (int mt = 0; mt < 4; ++mt) {
;     const float4* q = (const float4*)(ssq + (size_t)(row0 + mt * 16 + lr) * 16);
;     const float4 a = q[0], b = q[1], c = q[2], d = q[3];
;     const float s = ((a.x + a.y) + (a.z + a.w)) + ((b.x + b.y) + (b.z + b.w)) + ((c.x + c.y) + (c.z + c.w)) + ((d.x + d.y) + (d.z + d.w));
;     rs[mt] = rsqrtf(s * (1.0f / 1024.0f) + EPS);
;   }
; }
; template <int VAR> DI void phase_up(const Params& P, int l, char* smem) {
;     ...
;   for (int vb = BIDX(); vb < tile_groups(128, 32); vb += gridDim.x) {
;     int tm, tn; if (!tile_of(vb, 128, 32, tm, tn)) continue;
;     const int m0 = tm * 128, n0 = tn * 128;
;     const int row0 = m0 + wm * 64, col0 = n0 + wn * 64;
;     f32x4 acc[4][4]; zero_acc(acc);
;     float rs[4]; load_rstd(rs, ssq, row0, lr);
.LBB0_1313:
	s_ashr_i32 s4, s2, 9
	s_lshr_b32 s1, s4, 30
	s_add_i32 s1, s4, s1
	s_ashr_i32 s5, s1, 2
	s_lshl_b32 s1, s5, 6
	s_and_b32 s6, s12, 56
	s_lshl_b32 s5, s5, 5
	s_lshl_b32 s4, s4, 3
	s_or_b32 s1, s1, s6
	s_bfe_u32 s6, s2, 0x30003
	s_sub_i32 s4, s4, s5
	s_bfe_u32 s5, s2, 0x30006
	s_or_b32 s1, s1, s6
	s_or_b32 s4, s4, s5
	s_cmpk_lt_i32 s1, 0x80
	s_cselect_b64 s[6:7], -1, 0
	s_cmp_lt_i32 s4, 32
	s_cselect_b64 s[8:9], -1, 0
	s_and_b64 s[6:7], s[6:7], s[8:9]
	s_andn2_b64 vcc, exec, s[6:7]
	s_cbranch_vccnz .LBB0_1312
	s_lshl_b32 s8, s1, 7
	v_add_u32_e32 v102, s8, v125
	v_ashrrev_i32_e32 v103, 31, v102
	v_readlane_b32 s14, v254, 41
	v_lshlrev_b64 v[0:1], 6, v[102:103]
	v_readlane_b32 s15, v254, 42
	v_or_b32_e32 v98, 16, v102
	v_ashrrev_i32_e32 v99, 31, v98
	v_lshl_add_u64 v[12:13], s[14:15], 0, v[0:1]
	global_load_dwordx4 v[0:3], v[12:13], off offset:32
	global_load_dwordx4 v[4:7], v[12:13], off offset:16
	global_load_dwordx4 v[8:11], v[12:13], off
	s_nop 0
	global_load_dwordx4 v[12:15], v[12:13], off offset:48
	s_lshl_b32 s6, s4, 7
	s_mov_b32 s4, 0x358637bd
	s_mov_b32 s16, 0x3a800000
	s_mov_b32 s1, 0x800000
	v_or_b32_e32 v106, 32, v102
	v_ashrrev_i32_e32 v107, 31, v106
	v_or_b32_e32 v104, 48, v102
	v_ashrrev_i32_e32 v105, 31, v104
	s_ashr_i32 s9, s8, 31
	s_waitcnt vmcnt(7)
	v_mov_b32_e32 v72, v148
	v_or_b32_e32 v100, s6, v124
	s_waitcnt vmcnt(2)
	v_mov_b32_e32 v18, v5
	s_waitcnt vmcnt(1)
	v_mov_b32_e32 v16, v9
	v_mov_b32_e32 v17, v10
	v_mov_b32_e32 v19, v6
	v_mov_b32_e32 v9, v11
	v_mov_b32_e32 v5, v7
	v_mov_b32_e32 v6, v1
	v_pk_add_f32 v[8:9], v[16:17], v[8:9]
	v_pk_add_f32 v[4:5], v[18:19], v[4:5]
	v_pk_add_f32 v[0:1], v[0:1], v[6:7]
	v_mov_b32_e32 v6, v3
	v_pk_add_f32 v[8:9], v[8:9], v[8:9] op_sel:[0,1] op_sel_hi:[1,0]
	v_pk_add_f32 v[4:5], v[4:5], v[4:5] op_sel:[0,1] op_sel_hi:[1,0]
	v_pk_add_f32 v[2:3], v[2:3], v[6:7]
	s_waitcnt vmcnt(0)
	v_mov_b32_e32 v9, v12
	v_mov_b32_e32 v5, v13
	v_mov_b32_e32 v1, v14
	v_mov_b32_e32 v3, v15
	v_pk_add_f32 v[4:5], v[8:9], v[4:5]
	v_pk_add_f32 v[0:1], v[0:1], v[2:3]
	s_nop 0
	v_pk_add_f32 v[16:17], v[4:5], v[0:1]
	v_lshlrev_b64 v[0:1], 6, v[98:99]
	v_lshl_add_u64 v[12:13], s[14:15], 0, v[0:1]
	global_load_dwordx4 v[0:3], v[12:13], off offset:32
	global_load_dwordx4 v[4:7], v[12:13], off offset:16
	global_load_dwordx4 v[8:11], v[12:13], off
	s_nop 0
	global_load_dwordx4 v[12:15], v[12:13], off offset:48
	s_waitcnt vmcnt(2)
	v_mov_b32_e32 v20, v5
	s_waitcnt vmcnt(1)
	v_mov_b32_e32 v18, v9
	v_mov_b32_e32 v19, v10
	v_mov_b32_e32 v21, v6
	v_mov_b32_e32 v9, v11
	v_mov_b32_e32 v5, v7
	v_mov_b32_e32 v6, v1
	v_pk_add_f32 v[8:9], v[18:19], v[8:9]
	v_pk_add_f32 v[4:5], v[20:21], v[4:5]
	v_pk_add_f32 v[0:1], v[0:1], v[6:7]
	v_mov_b32_e32 v6, v3
	v_pk_add_f32 v[8:9], v[8:9], v[8:9] op_sel:[0,1] op_sel_hi:[1,0]
	v_pk_add_f32 v[4:5], v[4:5], v[4:5] op_sel:[0,1] op_sel_hi:[1,0]
	v_pk_add_f32 v[2:3], v[2:3], v[6:7]
	s_waitcnt vmcnt(0)
	v_mov_b32_e32 v9, v12
	v_mov_b32_e32 v5, v13
	v_mov_b32_e32 v1, v14
	v_mov_b32_e32 v3, v15
	v_pk_add_f32 v[4:5], v[8:9], v[4:5]
	v_pk_add_f32 v[0:1], v[0:1], v[2:3]
	v_mov_b32_e32 v3, v16
	v_pk_add_f32 v[0:1], v[4:5], v[0:1]
	s_nop 0
	v_mov_b32_e32 v2, v0
	v_mov_b32_e32 v16, v1
	v_pk_add_f32 v[2:3], v[2:3], v[16:17]
	v_mov_b64_e32 v[0:1], s[4:5]
	v_pk_fma_f32 v[2:3], v[2:3], s[16:17], v[0:1] op_sel_hi:[1,0,0]
	s_nop 0
	v_mul_f32_e32 v4, 0x4b800000, v3
	v_cmp_gt_f32_e64 s[4:5], s1, v3
	v_cmp_gt_f32_e32 vcc, s1, v2
	s_nop 0
	v_cndmask_b32_e64 v3, v3, v4, s[4:5]
	v_rsq_f32_e32 v3, v3
	s_nop 0
	v_mul_f32_e32 v4, 0x45800000, v3
	v_cndmask_b32_e64 v128, v3, v4, s[4:5]
	v_mul_f32_e32 v3, 0x4b800000, v2
	v_cndmask_b32_e32 v2, v2, v3, vcc
	v_rsq_f32_e32 v2, v2
	s_nop 0
	v_mul_f32_e32 v3, 0x45800000, v2
	v_cndmask_b32_e32 v126, v2, v3, vcc
	v_lshlrev_b64 v[2:3], 6, v[106:107]
	v_lshl_add_u64 v[14:15], s[14:15], 0, v[2:3]
	global_load_dwordx4 v[2:5], v[14:15], off offset:32
	global_load_dwordx4 v[6:9], v[14:15], off offset:16
	global_load_dwordx4 v[10:13], v[14:15], off
	s_nop 0
	global_load_dwordx4 v[14:17], v[14:15], off offset:48
	s_waitcnt vmcnt(2)
	v_mov_b32_e32 v20, v7
	s_waitcnt vmcnt(1)
	v_mov_b32_e32 v18, v11
	v_mov_b32_e32 v19, v12
	v_mov_b32_e32 v21, v8
	v_mov_b32_e32 v11, v13
	v_mov_b32_e32 v7, v9
	v_mov_b32_e32 v8, v3
	v_pk_add_f32 v[10:11], v[18:19], v[10:11]
	v_pk_add_f32 v[6:7], v[20:21], v[6:7]
	v_pk_add_f32 v[2:3], v[2:3], v[8:9]
	v_mov_b32_e32 v8, v5
	v_pk_add_f32 v[10:11], v[10:11], v[10:11] op_sel:[0,1] op_sel_hi:[1,0]
	v_pk_add_f32 v[6:7], v[6:7], v[6:7] op_sel:[0,1] op_sel_hi:[1,0]
	v_pk_add_f32 v[4:5], v[4:5], v[8:9]
	s_waitcnt vmcnt(0)
	v_mov_b32_e32 v11, v14
	v_mov_b32_e32 v7, v15
	v_mov_b32_e32 v3, v16
	v_mov_b32_e32 v5, v17
	v_pk_add_f32 v[6:7], v[10:11], v[6:7]
	v_pk_add_f32 v[2:3], v[2:3], v[4:5]
	s_nop 0
	v_pk_add_f32 v[18:19], v[6:7], v[2:3]
	v_lshlrev_b64 v[2:3], 6, v[104:105]
	v_lshl_add_u64 v[14:15], s[14:15], 0, v[2:3]
	global_load_dwordx4 v[2:5], v[14:15], off offset:32
	global_load_dwordx4 v[6:9], v[14:15], off offset:16
	global_load_dwordx4 v[10:13], v[14:15], off
	s_nop 0
	global_load_dwordx4 v[14:17], v[14:15], off offset:48
	s_waitcnt vmcnt(2)
	v_mov_b32_e32 v22, v7
	s_waitcnt vmcnt(1)
	v_mov_b32_e32 v20, v11
	v_mov_b32_e32 v21, v12
	v_mov_b32_e32 v23, v8
	v_mov_b32_e32 v11, v13
	v_mov_b32_e32 v7, v9
	v_mov_b32_e32 v8, v3
	v_pk_add_f32 v[10:11], v[20:21], v[10:11]
	v_pk_add_f32 v[6:7], v[22:23], v[6:7]
	v_pk_add_f32 v[2:3], v[2:3], v[8:9]
	v_mov_b32_e32 v8, v5
	v_pk_add_f32 v[10:11], v[10:11], v[10:11] op_sel:[0,1] op_sel_hi:[1,0]
	v_pk_add_f32 v[6:7], v[6:7], v[6:7] op_sel:[0,1] op_sel_hi:[1,0]
	v_pk_add_f32 v[4:5], v[4:5], v[8:9]
	s_waitcnt vmcnt(0)
; #define GL_LOAD(s_, kt_) if (VAR != 1) { a##s_##0 = GL_A(0, kt_); a##s_##1 = GL_A(1, kt_); a##s_##2 = GL_A(2, kt_); a##s_##3 = GL_A(3, kt_); b##s_##0 = GL_B(0, kt_); b##s_##1 = GL_B(1, kt_); b##s_##2 = GL_B(2, kt_); b##s_##3 = GL_B(3, kt_); }
; #define LDS_STORE(s_, buf_) if (VAR != 2) { LDS_ST1(sA, 0, buf_, a##s_##0) LDS_ST1(sA, 1, buf_, a##s_##1) LDS_ST1(sA, 2, buf_, a##s_##2) LDS_ST1(sA, 3, buf_, a##s_##3) LDS_ST1(sB, 0, buf_, b##s_##0) LDS_ST1(sB, 1, buf_, b##s_##1) LDS_ST1(sB, 2, buf_, b##s_##2) LDS_ST1(sB, 3, buf_, b##s_##3) }
;     ...
;   GL_LOAD(0, 0)
;   GL_LOAD(1, 1)
;   LDS_STORE(0, 0)
;   if (VAR != 4) __syncthreads();
; #pragma unroll
;   for (int kt = 0; kt < nk; kt += 2) {
;     if (kt + 2 < nk) { GL_LOAD(0, kt + 2) }
;     MMA_TILE(0)
;     LDS_STORE(1, 1)
;     if (VAR != 4) __syncthreads();
;     if (kt + 3 < nk) { GL_LOAD(1, kt + 3) }
;     MMA_TILE(1)
; DI void load_rstd(float (&rs)[4], const float* ssq, int row0, int lr) {
; #pragma unroll
;   for (int mt = 0; mt < 4; ++mt) {
;     const float4* q = (const float4*)(ssq + (size_t)(row0 + mt * 16 + lr) * 16);
;     const float4 a = q[0], b = q[1], c = q[2], d = q[3];
;     const float s = ((a.x + a.y) + (a.z + a.w)) + ((b.x + b.y) + (b.z + b.w)) + ((c.x + c.y) + (c.z + c.w)) + ((d.x + d.y) + (d.z + d.w));
;     rs[mt] = rsqrtf(s * (1.0f / 1024.0f) + EPS);
;   }
; }
	v_mov_b32_e32 v11, v14
	v_mov_b32_e32 v7, v15
	v_mov_b32_e32 v3, v16
	v_mov_b32_e32 v5, v17
	v_pk_add_f32 v[6:7], v[10:11], v[6:7]
	v_pk_add_f32 v[2:3], v[2:3], v[4:5]
	v_mov_b32_e32 v5, v18
	v_pk_add_f32 v[2:3], v[6:7], v[2:3]
	v_ashrrev_i32_e32 v64, 3, v72
	v_mov_b32_e32 v4, v2
	v_mov_b32_e32 v18, v3
	v_pk_add_f32 v[2:3], v[4:5], v[18:19]
	v_ashrrev_i32_e32 v65, 31, v64
	v_pk_fma_f32 v[0:1], v[2:3], s[16:17], v[0:1] op_sel_hi:[1,0,0]
	v_and_b32_e32 v75, 48, v72
	v_mul_f32_e32 v2, 0x4b800000, v1
	v_cmp_gt_f32_e64 s[4:5], s1, v1
	v_cmp_gt_f32_e32 vcc, s1, v0
	v_lshlrev_b64 v[16:17], 11, v[64:65]
	v_cndmask_b32_e64 v1, v1, v2, s[4:5]
	v_rsq_f32_e32 v1, v1
	v_lshlrev_b32_e32 v65, 4, v72
	v_and_b32_e32 v150, 0x70, v65
	v_add_u32_e32 v66, 32, v64
	v_mul_f32_e32 v2, 0x45800000, v1
	v_cndmask_b32_e64 v129, v1, v2, s[4:5]
	v_mul_f32_e32 v1, 0x4b800000, v0
	v_cndmask_b32_e32 v0, v0, v1, vcc
	v_rsq_f32_e32 v0, v0
	s_lshl_b64 s[4:5], s[8:9], 11
	v_readlane_b32 s8, v254, 43
	v_readlane_b32 s9, v254, 44
	v_mul_f32_e32 v1, 0x45800000, v0
	s_add_u32 s4, s8, s4
	v_cndmask_b32_e32 v127, v0, v1, vcc
	s_addc_u32 s5, s9, s5
	v_lshlrev_b32_e32 v0, 3, v72
	s_ashr_i32 s7, s6, 31
	v_and_b32_e32 v74, 0x70, v0
	v_bitop3_b32 v134, v0, v75, s23 bitop3:0x6c
	v_lshl_add_u64 v[0:1], s[4:5], 0, v[16:17]
	v_add_u32_e32 v68, 64, v64
	v_add_u32_e32 v70, 0x60, v64
	s_lshl_b64 s[6:7], s[6:7], 11
	v_lshl_add_u64 v[108:109], v[0:1], 0, v[150:151]
	v_ashrrev_i32_e32 v67, 31, v66
	v_ashrrev_i32_e32 v69, 31, v68
	v_ashrrev_i32_e32 v71, 31, v70
	s_add_u32 s6, s10, s6
	global_load_dwordx4 v[0:3], v[108:109], off
	v_lshlrev_b64 v[20:21], 11, v[66:67]
	v_lshlrev_b64 v[24:25], 11, v[68:69]
	v_lshlrev_b64 v[28:29], 11, v[70:71]
	s_addc_u32 s7, s11, s7
	v_lshl_add_u64 v[4:5], s[4:5], 0, v[20:21]
	v_lshl_add_u64 v[8:9], s[4:5], 0, v[24:25]
	v_lshl_add_u64 v[12:13], s[4:5], 0, v[28:29]
	v_lshl_add_u64 v[110:111], v[4:5], 0, v[150:151]
	v_lshl_add_u64 v[112:113], v[8:9], 0, v[150:151]
	v_lshl_add_u64 v[114:115], v[12:13], 0, v[150:151]
	v_lshl_add_u64 v[16:17], s[6:7], 0, v[16:17]
	global_load_dwordx4 v[4:7], v[110:111], off
	global_load_dwordx4 v[8:11], v[112:113], off
	global_load_dwordx4 v[12:15], v[114:115], off
	v_lshl_add_u64 v[116:117], v[16:17], 0, v[150:151]
	v_lshl_add_u64 v[20:21], s[6:7], 0, v[20:21]
	global_load_dwordx4 v[16:19], v[116:117], off
	v_lshl_add_u64 v[118:119], v[20:21], 0, v[150:151]
	v_lshl_add_u64 v[24:25], s[6:7], 0, v[24:25]
	global_load_dwordx4 v[20:23], v[118:119], off
	v_lshl_add_u64 v[120:121], v[24:25], 0, v[150:151]
	global_load_dwordx4 v[24:27], v[120:121], off
	v_lshl_add_u64 v[28:29], s[6:7], 0, v[28:29]
	v_lshl_add_u64 v[122:123], v[28:29], 0, v[150:151]
	global_load_dwordx4 v[28:31], v[122:123], off
	global_load_dwordx4 v[32:35], v[108:109], off offset:128
	global_load_dwordx4 v[36:39], v[110:111], off offset:128
	global_load_dwordx4 v[40:43], v[112:113], off offset:128
	global_load_dwordx4 v[44:47], v[114:115], off offset:128
	global_load_dwordx4 v[48:51], v[116:117], off offset:128
	global_load_dwordx4 v[52:55], v[118:119], off offset:128
	global_load_dwordx4 v[56:59], v[120:121], off offset:128
	global_load_dwordx4 v[60:63], v[122:123], off offset:128
	v_bitop3_b32 v65, v65, s23, v72 bitop3:0x48
	v_lshl_or_b32 v101, v64, 7, v65
	v_and_b32_e32 v73, 15, v72
	v_lshl_or_b32 v131, v66, 7, v65
	v_lshl_or_b32 v132, v68, 7, v65
	v_lshl_or_b32 v130, v70, 7, v65
	v_xor_b32_e32 v135, 64, v134
	s_waitcnt vmcnt(15)
	ds_write_b128 v101, v[0:3]
	v_lshrrev_b32_e32 v0, 1, v72
	v_and_or_b32 v0, v0, s24, v73
	v_lshlrev_b32_e32 v137, 7, v0
	v_lshlrev_b32_e32 v0, 7, v72
	v_and_b32_e32 v146, 0x2780, v0
	v_bitop3_b32 v133, v137, v74, v75 bitop3:0xf6
	v_or_b32_e32 v136, v146, v134
	v_bitop3_b32 v134, v137, v134, 64 bitop3:0xf6
	v_or_b32_e32 v135, v146, v135
	s_waitcnt vmcnt(14)
	ds_write_b128 v131, v[4:7]
	s_waitcnt vmcnt(13)
	ds_write_b128 v132, v[8:11]
	s_waitcnt vmcnt(12)
	ds_write_b128 v130, v[12:15]
	s_waitcnt vmcnt(11)
	ds_write_b128 v101, v[16:19] offset:32768
	s_waitcnt vmcnt(10)
	ds_write_b128 v131, v[20:23] offset:32768
	s_waitcnt vmcnt(9)
	ds_write_b128 v132, v[24:27] offset:32768
	s_waitcnt vmcnt(8)
	ds_write_b128 v130, v[28:31] offset:32768
	s_waitcnt lgkmcnt(0)
	s_barrier
	global_load_dwordx4 v[0:3], v[108:109], off offset:256
	global_load_dwordx4 v[4:7], v[110:111], off offset:256
	global_load_dwordx4 v[8:11], v[112:113], off offset:256
	global_load_dwordx4 v[12:15], v[114:115], off offset:256
	global_load_dwordx4 v[16:19], v[116:117], off offset:256
	global_load_dwordx4 v[20:23], v[118:119], off offset:256
	global_load_dwordx4 v[24:27], v[120:121], off offset:256
	global_load_dwordx4 v[28:31], v[122:123], off offset:256
	ds_read_b128 v[64:67], v133
	ds_read_b128 v[68:71], v136 offset:32768
	ds_read_b128 v[72:75], v133 offset:2048
	ds_read_b128 v[76:79], v136 offset:34816
	ds_read_b128 v[80:83], v133 offset:4096
	ds_read_b128 v[84:87], v136 offset:36864
	ds_read_b128 v[88:91], v133 offset:6144
	ds_read_b128 v[92:95], v136 offset:38912
	s_waitcnt lgkmcnt(6)
	v_mfma_f32_16x16x32_f16 v[138:141], v[68:71], v[64:67], 0
	s_waitcnt lgkmcnt(4)
	v_mfma_f32_16x16x32_f16 v[142:145], v[76:79], v[64:67], 0
	s_waitcnt lgkmcnt(2)
	v_mfma_f32_16x16x32_f16 v[154:157], v[84:87], v[64:67], 0
	s_waitcnt lgkmcnt(0)
	v_mfma_f32_16x16x32_f16 v[64:67], v[92:95], v[64:67], 0
	v_mfma_f32_16x16x32_f16 v[158:161], v[68:71], v[72:75], 0
	v_mfma_f32_16x16x32_f16 v[162:165], v[76:79], v[72:75], 0
	v_mfma_f32_16x16x32_f16 v[166:169], v[84:87], v[72:75], 0
	v_mfma_f32_16x16x32_f16 v[72:75], v[92:95], v[72:75], 0
	v_mfma_f32_16x16x32_f16 v[190:193], v[68:71], v[80:83], 0
	v_mfma_f32_16x16x32_f16 v[194:197], v[76:79], v[80:83], 0
	v_mfma_f32_16x16x32_f16 v[198:201], v[84:87], v[80:83], 0
	v_mfma_f32_16x16x32_f16 v[80:83], v[92:95], v[80:83], 0
	v_mfma_f32_16x16x32_f16 v[68:71], v[68:71], v[88:91], 0
	v_mfma_f32_16x16x32_f16 v[76:79], v[76:79], v[88:91], 0
	v_mfma_f32_16x16x32_f16 v[84:87], v[84:87], v[88:91], 0
	v_mfma_f32_16x16x32_f16 v[88:91], v[92:95], v[88:91], 0
	ds_read_b128 v[92:95], v134
	ds_read_b128 v[202:205], v135 offset:32768
	ds_read_b128 v[206:209], v134 offset:2048
	ds_read_b128 v[210:213], v135 offset:34816
	ds_read_b128 v[220:223], v134 offset:4096
	ds_read_b128 v[224:227], v135 offset:36864
	ds_read_b128 v[228:231], v134 offset:6144
	ds_read_b128 v[232:235], v135 offset:38912
	s_waitcnt vmcnt(15)
	ds_write_b128 v101, v[32:35] offset:16384
	s_waitcnt vmcnt(14)
	ds_write_b128 v131, v[36:39] offset:16384
	s_waitcnt vmcnt(13)
	ds_write_b128 v132, v[40:43] offset:16384
	s_waitcnt vmcnt(12)
	ds_write_b128 v130, v[44:47] offset:16384
	s_waitcnt vmcnt(11)
	ds_write_b128 v101, v[48:51] offset:49152
	s_waitcnt vmcnt(10)
	ds_write_b128 v131, v[52:55] offset:49152
	s_waitcnt vmcnt(9)
	ds_write_b128 v132, v[56:59] offset:49152
	s_waitcnt vmcnt(8)
	ds_write_b128 v130, v[60:63] offset:49152
	s_waitcnt lgkmcnt(0)
	s_barrier
; #define GL_LOAD(s_, kt_) if (VAR != 1) { a##s_##0 = GL_A(0, kt_); a##s_##1 = GL_A(1, kt_); a##s_##2 = GL_A(2, kt_); a##s_##3 = GL_A(3, kt_); b##s_##0 = GL_B(0, kt_); b##s_##1 = GL_B(1, kt_); b##s_##2 = GL_B(2, kt_); b##s_##3 = GL_B(3, kt_); }
; #define LDS_STORE(s_, buf_) if (VAR != 2) { LDS_ST1(sA, 0, buf_, a##s_##0) LDS_ST1(sA, 1, buf_, a##s_##1) LDS_ST1(sA, 2, buf_, a##s_##2) LDS_ST1(sA, 3, buf_, a##s_##3) LDS_ST1(sB, 0, buf_, b##s_##0) LDS_ST1(sB, 1, buf_, b##s_##1) LDS_ST1(sB, 2, buf_, b##s_##2) LDS_ST1(sB, 3, buf_, b##s_##3) }
;     ...
;   for (int kt = 0; kt < nk; kt += 2) {
;     if (kt + 2 < nk) { GL_LOAD(0, kt + 2) }
;     MMA_TILE(0)
;     LDS_STORE(1, 1)
;     if (VAR != 4) __syncthreads();
;     if (kt + 3 < nk) { GL_LOAD(1, kt + 3) }
;     MMA_TILE(1)
;     if (kt + 2 < nk) { LDS_STORE(0, 0) }
;     if (VAR != 4) __syncthreads();
	v_mfma_f32_16x16x32_f16 v[138:141], v[202:205], v[92:95], v[138:141]
	global_load_dwordx4 v[32:35], v[108:109], off offset:384
	v_mfma_f32_16x16x32_f16 v[142:145], v[210:213], v[92:95], v[142:145]
	v_mfma_f32_16x16x32_f16 v[154:157], v[224:227], v[92:95], v[154:157]
	v_mfma_f32_16x16x32_f16 v[64:67], v[232:235], v[92:95], v[64:67]
	v_mfma_f32_16x16x32_f16 v[92:95], v[202:205], v[206:209], v[158:161]
	global_load_dwordx4 v[36:39], v[110:111], off offset:384
	global_load_dwordx4 v[40:43], v[112:113], off offset:384
	global_load_dwordx4 v[44:47], v[114:115], off offset:384
	v_mfma_f32_16x16x32_f16 v[158:161], v[210:213], v[206:209], v[162:165]
	global_load_dwordx4 v[48:51], v[116:117], off offset:384
	v_mfma_f32_16x16x32_f16 v[162:165], v[224:227], v[206:209], v[166:169]
	v_mfma_f32_16x16x32_f16 v[166:169], v[202:205], v[220:223], v[190:193]
	global_load_dwordx4 v[52:55], v[118:119], off offset:384
	global_load_dwordx4 v[56:59], v[120:121], off offset:384
	v_mfma_f32_16x16x32_f16 v[68:71], v[202:205], v[228:231], v[68:71]
	ds_read_b128 v[202:205], v136 offset:49152
	v_mfma_f32_16x16x32_f16 v[190:193], v[210:213], v[220:223], v[194:197]
	global_load_dwordx4 v[60:63], v[122:123], off offset:384
	v_mfma_f32_16x16x32_f16 v[76:79], v[210:213], v[228:231], v[76:79]
	ds_read_b128 v[210:213], v136 offset:51200
	v_mfma_f32_16x16x32_f16 v[72:75], v[232:235], v[206:209], v[72:75]
	ds_read_b128 v[206:209], v133 offset:18432
	v_mfma_f32_16x16x32_f16 v[194:197], v[224:227], v[220:223], v[198:201]
	s_nop 2
	ds_read_b128 v[198:201], v133 offset:16384
	v_mfma_f32_16x16x32_f16 v[84:87], v[224:227], v[228:231], v[84:87]
	ds_read_b128 v[224:227], v136 offset:53248
	v_mfma_f32_16x16x32_f16 v[80:83], v[232:235], v[220:223], v[80:83]
	ds_read_b128 v[220:223], v133 offset:20480
	v_mfma_f32_16x16x32_f16 v[88:91], v[232:235], v[228:231], v[88:91]
	ds_read_b128 v[228:231], v133 offset:22528
	s_waitcnt lgkmcnt(3)
	v_mfma_f32_16x16x32_f16 v[138:141], v[202:205], v[198:201], v[138:141]
	ds_read_b128 v[232:235], v136 offset:55296
	v_mfma_f32_16x16x32_f16 v[92:95], v[202:205], v[206:209], v[92:95]
	s_waitcnt vmcnt(15)
	ds_write_b128 v101, v[0:3]
	v_mfma_f32_16x16x32_f16 v[142:145], v[210:213], v[198:201], v[142:145]
	s_waitcnt vmcnt(14)
	ds_write_b128 v131, v[4:7]
	v_mfma_f32_16x16x32_f16 v[158:161], v[210:213], v[206:209], v[158:161]
	s_waitcnt vmcnt(13)
	ds_write_b128 v132, v[8:11]
	s_waitcnt lgkmcnt(5)
	v_mfma_f32_16x16x32_f16 v[166:169], v[202:205], v[220:223], v[166:169]
	s_waitcnt vmcnt(12)
	ds_write_b128 v130, v[12:15]
	s_waitcnt lgkmcnt(5)
	v_mfma_f32_16x16x32_f16 v[68:71], v[202:205], v[228:231], v[68:71]
	ds_read_b128 v[202:205], v135 offset:49152
	v_mfma_f32_16x16x32_f16 v[190:193], v[210:213], v[220:223], v[190:193]
	s_waitcnt vmcnt(11)
	ds_write_b128 v101, v[16:19] offset:32768
	v_mfma_f32_16x16x32_f16 v[76:79], v[210:213], v[228:231], v[76:79]
	ds_read_b128 v[210:213], v135 offset:51200
	v_mfma_f32_16x16x32_f16 v[154:157], v[224:227], v[198:201], v[154:157]
	s_waitcnt vmcnt(10)
	ds_write_b128 v131, v[20:23] offset:32768
	v_mfma_f32_16x16x32_f16 v[162:165], v[224:227], v[206:209], v[162:165]
	s_waitcnt vmcnt(9)
	ds_write_b128 v132, v[24:27] offset:32768
	s_waitcnt lgkmcnt(9)
	v_mfma_f32_16x16x32_f16 v[64:67], v[232:235], v[198:201], v[64:67]
	ds_read_b128 v[198:201], v134 offset:16384
	v_mfma_f32_16x16x32_f16 v[72:75], v[232:235], v[206:209], v[72:75]
	ds_read_b128 v[206:209], v134 offset:18432
	v_mfma_f32_16x16x32_f16 v[194:197], v[224:227], v[220:223], v[194:197]
	s_waitcnt vmcnt(8)
	ds_write_b128 v130, v[28:31] offset:32768
	v_mfma_f32_16x16x32_f16 v[84:87], v[224:227], v[228:231], v[84:87]
	ds_read_b128 v[224:227], v135 offset:53248
	v_mfma_f32_16x16x32_f16 v[80:83], v[232:235], v[220:223], v[80:83]
	ds_read_b128 v[220:223], v134 offset:20480
	v_mfma_f32_16x16x32_f16 v[88:91], v[232:235], v[228:231], v[88:91]
	ds_read_b128 v[228:231], v134 offset:22528
	ds_read_b128 v[232:235], v135 offset:55296
	s_waitcnt lgkmcnt(0)
	s_barrier
	v_mfma_f32_16x16x32_f16 v[138:141], v[202:205], v[198:201], v[138:141]
	global_load_dwordx4 v[0:3], v[108:109], off offset:512
	v_mfma_f32_16x16x32_f16 v[92:95], v[202:205], v[206:209], v[92:95]
	global_load_dwordx4 v[4:7], v[110:111], off offset:512
	v_mfma_f32_16x16x32_f16 v[142:145], v[210:213], v[198:201], v[142:145]
	global_load_dwordx4 v[8:11], v[112:113], off offset:512
	v_mfma_f32_16x16x32_f16 v[158:161], v[210:213], v[206:209], v[158:161]
	global_load_dwordx4 v[12:15], v[114:115], off offset:512
	v_mfma_f32_16x16x32_f16 v[166:169], v[202:205], v[220:223], v[166:169]
	global_load_dwordx4 v[16:19], v[116:117], off offset:512
	v_mfma_f32_16x16x32_f16 v[68:71], v[202:205], v[228:231], v[68:71]
	ds_read_b128 v[202:205], v136 offset:32768
	v_mfma_f32_16x16x32_f16 v[190:193], v[210:213], v[220:223], v[190:193]
	global_load_dwordx4 v[20:23], v[118:119], off offset:512
	v_mfma_f32_16x16x32_f16 v[76:79], v[210:213], v[228:231], v[76:79]
	ds_read_b128 v[210:213], v136 offset:34816
	v_mfma_f32_16x16x32_f16 v[154:157], v[224:227], v[198:201], v[154:157]
	global_load_dwordx4 v[24:27], v[120:121], off offset:512
	v_mfma_f32_16x16x32_f16 v[162:165], v[224:227], v[206:209], v[162:165]
	global_load_dwordx4 v[28:31], v[122:123], off offset:512
	v_mfma_f32_16x16x32_f16 v[64:67], v[232:235], v[198:201], v[64:67]
	ds_read_b128 v[198:201], v133
	v_mfma_f32_16x16x32_f16 v[72:75], v[232:235], v[206:209], v[72:75]
	ds_read_b128 v[206:209], v133 offset:2048
	v_mfma_f32_16x16x32_f16 v[194:197], v[224:227], v[220:223], v[194:197]
	v_mfma_f32_16x16x32_f16 v[84:87], v[224:227], v[228:231], v[84:87]
	ds_read_b128 v[224:227], v136 offset:36864
	v_mfma_f32_16x16x32_f16 v[80:83], v[232:235], v[220:223], v[80:83]
	ds_read_b128 v[220:223], v133 offset:4096
	v_mfma_f32_16x16x32_f16 v[88:91], v[232:235], v[228:231], v[88:91]
	ds_read_b128 v[228:231], v133 offset:6144
	s_waitcnt lgkmcnt(4)
; #define GL_LOAD(s_, kt_) if (VAR != 1) { a##s_##0 = GL_A(0, kt_); a##s_##1 = GL_A(1, kt_); a##s_##2 = GL_A(2, kt_); a##s_##3 = GL_A(3, kt_); b##s_##0 = GL_B(0, kt_); b##s_##1 = GL_B(1, kt_); b##s_##2 = GL_B(2, kt_); b##s_##3 = GL_B(3, kt_); }
; #define LDS_STORE(s_, buf_) if (VAR != 2) { LDS_ST1(sA, 0, buf_, a##s_##0) LDS_ST1(sA, 1, buf_, a##s_##1) LDS_ST1(sA, 2, buf_, a##s_##2) LDS_ST1(sA, 3, buf_, a##s_##3) LDS_ST1(sB, 0, buf_, b##s_##0) LDS_ST1(sB, 1, buf_, b##s_##1) LDS_ST1(sB, 2, buf_, b##s_##2) LDS_ST1(sB, 3, buf_, b##s_##3) }
;     ...
;   GL_LOAD(0, 0)
;   GL_LOAD(1, 1)
;   LDS_STORE(0, 0)
;   if (VAR != 4) __syncthreads();
; #pragma unroll
;   for (int kt = 0; kt < nk; kt += 2) {
;     if (kt + 2 < nk) { GL_LOAD(0, kt + 2) }
;     MMA_TILE(0)
;     LDS_STORE(1, 1)
;     if (VAR != 4) __syncthreads();
;     if (kt + 3 < nk) { GL_LOAD(1, kt + 3) }
;     MMA_TILE(1)
;     if (kt + 2 < nk) { LDS_STORE(0, 0) }
;     if (VAR != 4) __syncthreads();
	v_mfma_f32_16x16x32_f16 v[138:141], v[202:205], v[198:201], v[138:141]
	ds_read_b128 v[232:235], v136 offset:38912
	s_waitcnt lgkmcnt(4)
	v_mfma_f32_16x16x32_f16 v[92:95], v[202:205], v[206:209], v[92:95]
	s_waitcnt vmcnt(15)
	ds_write_b128 v101, v[32:35] offset:16384
	v_mfma_f32_16x16x32_f16 v[142:145], v[210:213], v[198:201], v[142:145]
	s_waitcnt vmcnt(14)
	ds_write_b128 v131, v[36:39] offset:16384
	v_mfma_f32_16x16x32_f16 v[158:161], v[210:213], v[206:209], v[158:161]
	s_waitcnt vmcnt(13)
	ds_write_b128 v132, v[40:43] offset:16384
	s_waitcnt lgkmcnt(5)
	v_mfma_f32_16x16x32_f16 v[166:169], v[202:205], v[220:223], v[166:169]
	s_waitcnt vmcnt(12)
	ds_write_b128 v130, v[44:47] offset:16384
	s_waitcnt lgkmcnt(5)
	v_mfma_f32_16x16x32_f16 v[68:71], v[202:205], v[228:231], v[68:71]
	ds_read_b128 v[202:205], v135 offset:32768
	v_mfma_f32_16x16x32_f16 v[190:193], v[210:213], v[220:223], v[190:193]
	s_waitcnt vmcnt(11)
	ds_write_b128 v101, v[48:51] offset:49152
	v_mfma_f32_16x16x32_f16 v[76:79], v[210:213], v[228:231], v[76:79]
	ds_read_b128 v[210:213], v135 offset:34816
	v_mfma_f32_16x16x32_f16 v[154:157], v[224:227], v[198:201], v[154:157]
	s_waitcnt vmcnt(10)
	ds_write_b128 v131, v[52:55] offset:49152
	v_mfma_f32_16x16x32_f16 v[162:165], v[224:227], v[206:209], v[162:165]
	s_waitcnt vmcnt(9)
	ds_write_b128 v132, v[56:59] offset:49152
	s_waitcnt lgkmcnt(9)
	v_mfma_f32_16x16x32_f16 v[64:67], v[232:235], v[198:201], v[64:67]
	ds_read_b128 v[198:201], v134
	v_mfma_f32_16x16x32_f16 v[72:75], v[232:235], v[206:209], v[72:75]
	ds_read_b128 v[206:209], v134 offset:2048
	v_mfma_f32_16x16x32_f16 v[194:197], v[224:227], v[220:223], v[194:197]
	s_waitcnt vmcnt(8)
	ds_write_b128 v130, v[60:63] offset:49152
	v_mfma_f32_16x16x32_f16 v[84:87], v[224:227], v[228:231], v[84:87]
	ds_read_b128 v[224:227], v135 offset:36864
	v_mfma_f32_16x16x32_f16 v[80:83], v[232:235], v[220:223], v[80:83]
	ds_read_b128 v[220:223], v134 offset:4096
	v_mfma_f32_16x16x32_f16 v[88:91], v[232:235], v[228:231], v[88:91]
	ds_read_b128 v[228:231], v134 offset:6144
	ds_read_b128 v[232:235], v135 offset:38912
	s_waitcnt lgkmcnt(0)
	s_barrier
	v_mfma_f32_16x16x32_f16 v[138:141], v[202:205], v[198:201], v[138:141]
	global_load_dwordx4 v[32:35], v[108:109], off offset:640
	v_mfma_f32_16x16x32_f16 v[92:95], v[202:205], v[206:209], v[92:95]
	global_load_dwordx4 v[36:39], v[110:111], off offset:640
	v_mfma_f32_16x16x32_f16 v[142:145], v[210:213], v[198:201], v[142:145]
	global_load_dwordx4 v[40:43], v[112:113], off offset:640
	v_mfma_f32_16x16x32_f16 v[158:161], v[210:213], v[206:209], v[158:161]
	global_load_dwordx4 v[44:47], v[114:115], off offset:640
	v_mfma_f32_16x16x32_f16 v[166:169], v[202:205], v[220:223], v[166:169]
	global_load_dwordx4 v[48:51], v[116:117], off offset:640
	v_mfma_f32_16x16x32_f16 v[68:71], v[202:205], v[228:231], v[68:71]
	ds_read_b128 v[202:205], v136 offset:49152
	v_mfma_f32_16x16x32_f16 v[190:193], v[210:213], v[220:223], v[190:193]
	global_load_dwordx4 v[52:55], v[118:119], off offset:640
	v_mfma_f32_16x16x32_f16 v[76:79], v[210:213], v[228:231], v[76:79]
	ds_read_b128 v[210:213], v136 offset:51200
	v_mfma_f32_16x16x32_f16 v[154:157], v[224:227], v[198:201], v[154:157]
	global_load_dwordx4 v[56:59], v[120:121], off offset:640
	v_mfma_f32_16x16x32_f16 v[162:165], v[224:227], v[206:209], v[162:165]
	global_load_dwordx4 v[60:63], v[122:123], off offset:640
	v_mfma_f32_16x16x32_f16 v[64:67], v[232:235], v[198:201], v[64:67]
	ds_read_b128 v[198:201], v133 offset:16384
	v_mfma_f32_16x16x32_f16 v[72:75], v[232:235], v[206:209], v[72:75]
	ds_read_b128 v[206:209], v133 offset:18432
	v_mfma_f32_16x16x32_f16 v[194:197], v[224:227], v[220:223], v[194:197]
	v_mfma_f32_16x16x32_f16 v[84:87], v[224:227], v[228:231], v[84:87]
	ds_read_b128 v[224:227], v136 offset:53248
	v_mfma_f32_16x16x32_f16 v[80:83], v[232:235], v[220:223], v[80:83]
	ds_read_b128 v[220:223], v133 offset:20480
	v_mfma_f32_16x16x32_f16 v[88:91], v[232:235], v[228:231], v[88:91]
	ds_read_b128 v[228:231], v133 offset:22528
	s_waitcnt lgkmcnt(4)
	v_mfma_f32_16x16x32_f16 v[138:141], v[202:205], v[198:201], v[138:141]
	ds_read_b128 v[232:235], v136 offset:55296
	s_waitcnt lgkmcnt(4)
	v_mfma_f32_16x16x32_f16 v[92:95], v[202:205], v[206:209], v[92:95]
	s_waitcnt vmcnt(15)
	ds_write_b128 v101, v[0:3]
	v_mfma_f32_16x16x32_f16 v[142:145], v[210:213], v[198:201], v[142:145]
	s_waitcnt vmcnt(14)
	ds_write_b128 v131, v[4:7]
	v_mfma_f32_16x16x32_f16 v[158:161], v[210:213], v[206:209], v[158:161]
	s_waitcnt vmcnt(13)
	ds_write_b128 v132, v[8:11]
	s_waitcnt lgkmcnt(5)
	v_mfma_f32_16x16x32_f16 v[166:169], v[202:205], v[220:223], v[166:169]
	s_waitcnt vmcnt(12)
	ds_write_b128 v130, v[12:15]
	s_waitcnt lgkmcnt(5)
	v_mfma_f32_16x16x32_f16 v[68:71], v[202:205], v[228:231], v[68:71]
	ds_read_b128 v[202:205], v135 offset:49152
	v_mfma_f32_16x16x32_f16 v[190:193], v[210:213], v[220:223], v[190:193]
	s_waitcnt vmcnt(11)
	ds_write_b128 v101, v[16:19] offset:32768
	v_mfma_f32_16x16x32_f16 v[76:79], v[210:213], v[228:231], v[76:79]
	ds_read_b128 v[210:213], v135 offset:51200
	v_mfma_f32_16x16x32_f16 v[154:157], v[224:227], v[198:201], v[154:157]
	s_waitcnt vmcnt(10)
	ds_write_b128 v131, v[20:23] offset:32768
	v_mfma_f32_16x16x32_f16 v[162:165], v[224:227], v[206:209], v[162:165]
	s_waitcnt vmcnt(9)
	ds_write_b128 v132, v[24:27] offset:32768
	s_waitcnt lgkmcnt(9)
	v_mfma_f32_16x16x32_f16 v[64:67], v[232:235], v[198:201], v[64:67]
	ds_read_b128 v[198:201], v134 offset:16384
	v_mfma_f32_16x16x32_f16 v[72:75], v[232:235], v[206:209], v[72:75]
	ds_read_b128 v[206:209], v134 offset:18432
	v_mfma_f32_16x16x32_f16 v[194:197], v[224:227], v[220:223], v[194:197]
	s_waitcnt vmcnt(8)
	ds_write_b128 v130, v[28:31] offset:32768
	v_mfma_f32_16x16x32_f16 v[84:87], v[224:227], v[228:231], v[84:87]
	ds_read_b128 v[224:227], v135 offset:53248
	v_mfma_f32_16x16x32_f16 v[80:83], v[232:235], v[220:223], v[80:83]
	ds_read_b128 v[220:223], v134 offset:20480
	v_mfma_f32_16x16x32_f16 v[88:91], v[232:235], v[228:231], v[88:91]
	ds_read_b128 v[228:231], v134 offset:22528
	ds_read_b128 v[232:235], v135 offset:55296
	s_waitcnt lgkmcnt(0)
	s_barrier
; #define GL_LOAD(s_, kt_) if (VAR != 1) { a##s_##0 = GL_A(0, kt_); a##s_##1 = GL_A(1, kt_); a##s_##2 = GL_A(2, kt_); a##s_##3 = GL_A(3, kt_); b##s_##0 = GL_B(0, kt_); b##s_##1 = GL_B(1, kt_); b##s_##2 = GL_B(2, kt_); b##s_##3 = GL_B(3, kt_); }
; #define LDS_STORE(s_, buf_) if (VAR != 2) { LDS_ST1(sA, 0, buf_, a##s_##0) LDS_ST1(sA, 1, buf_, a##s_##1) LDS_ST1(sA, 2, buf_, a##s_##2) LDS_ST1(sA, 3, buf_, a##s_##3) LDS_ST1(sB, 0, buf_, b##s_##0) LDS_ST1(sB, 1, buf_, b##s_##1) LDS_ST1(sB, 2, buf_, b##s_##2) LDS_ST1(sB, 3, buf_, b##s_##3) }
;     ...
;   GL_LOAD(0, 0)
;   GL_LOAD(1, 1)
;   LDS_STORE(0, 0)
;   if (VAR != 4) __syncthreads();
; #pragma unroll
;   for (int kt = 0; kt < nk; kt += 2) {
;     if (kt + 2 < nk) { GL_LOAD(0, kt + 2) }
;     MMA_TILE(0)
;     LDS_STORE(1, 1)
;     if (VAR != 4) __syncthreads();
;     if (kt + 3 < nk) { GL_LOAD(1, kt + 3) }
;     MMA_TILE(1)
;     if (kt + 2 < nk) { LDS_STORE(0, 0) }
;     if (VAR != 4) __syncthreads();
	v_mfma_f32_16x16x32_f16 v[138:141], v[202:205], v[198:201], v[138:141]
	global_load_dwordx4 v[0:3], v[108:109], off offset:768
	v_mfma_f32_16x16x32_f16 v[92:95], v[202:205], v[206:209], v[92:95]
	global_load_dwordx4 v[4:7], v[110:111], off offset:768
	v_mfma_f32_16x16x32_f16 v[142:145], v[210:213], v[198:201], v[142:145]
	global_load_dwordx4 v[8:11], v[112:113], off offset:768
	v_mfma_f32_16x16x32_f16 v[158:161], v[210:213], v[206:209], v[158:161]
	global_load_dwordx4 v[12:15], v[114:115], off offset:768
	v_mfma_f32_16x16x32_f16 v[166:169], v[202:205], v[220:223], v[166:169]
	global_load_dwordx4 v[16:19], v[116:117], off offset:768
	v_mfma_f32_16x16x32_f16 v[68:71], v[202:205], v[228:231], v[68:71]
	ds_read_b128 v[202:205], v136 offset:32768
	v_mfma_f32_16x16x32_f16 v[190:193], v[210:213], v[220:223], v[190:193]
	global_load_dwordx4 v[20:23], v[118:119], off offset:768
	v_mfma_f32_16x16x32_f16 v[76:79], v[210:213], v[228:231], v[76:79]
	ds_read_b128 v[210:213], v136 offset:34816
	v_mfma_f32_16x16x32_f16 v[154:157], v[224:227], v[198:201], v[154:157]
	global_load_dwordx4 v[24:27], v[120:121], off offset:768
	v_mfma_f32_16x16x32_f16 v[162:165], v[224:227], v[206:209], v[162:165]
	global_load_dwordx4 v[28:31], v[122:123], off offset:768
	v_mfma_f32_16x16x32_f16 v[64:67], v[232:235], v[198:201], v[64:67]
	ds_read_b128 v[198:201], v133
	v_mfma_f32_16x16x32_f16 v[72:75], v[232:235], v[206:209], v[72:75]
	ds_read_b128 v[206:209], v133 offset:2048
	v_mfma_f32_16x16x32_f16 v[194:197], v[224:227], v[220:223], v[194:197]
	v_mfma_f32_16x16x32_f16 v[84:87], v[224:227], v[228:231], v[84:87]
	ds_read_b128 v[224:227], v136 offset:36864
	v_mfma_f32_16x16x32_f16 v[80:83], v[232:235], v[220:223], v[80:83]
	ds_read_b128 v[220:223], v133 offset:4096
	v_mfma_f32_16x16x32_f16 v[88:91], v[232:235], v[228:231], v[88:91]
	ds_read_b128 v[228:231], v133 offset:6144
	s_waitcnt lgkmcnt(4)
	v_mfma_f32_16x16x32_f16 v[138:141], v[202:205], v[198:201], v[138:141]
	ds_read_b128 v[232:235], v136 offset:38912
	s_waitcnt lgkmcnt(4)
	v_mfma_f32_16x16x32_f16 v[92:95], v[202:205], v[206:209], v[92:95]
	s_waitcnt vmcnt(15)
	ds_write_b128 v101, v[32:35] offset:16384
	v_mfma_f32_16x16x32_f16 v[142:145], v[210:213], v[198:201], v[142:145]
	s_waitcnt vmcnt(14)
	ds_write_b128 v131, v[36:39] offset:16384
	v_mfma_f32_16x16x32_f16 v[158:161], v[210:213], v[206:209], v[158:161]
	s_waitcnt vmcnt(13)
	ds_write_b128 v132, v[40:43] offset:16384
	s_waitcnt lgkmcnt(5)
	v_mfma_f32_16x16x32_f16 v[166:169], v[202:205], v[220:223], v[166:169]
	s_waitcnt vmcnt(12)
	ds_write_b128 v130, v[44:47] offset:16384
	s_waitcnt lgkmcnt(5)
	v_mfma_f32_16x16x32_f16 v[68:71], v[202:205], v[228:231], v[68:71]
	ds_read_b128 v[202:205], v135 offset:32768
	v_mfma_f32_16x16x32_f16 v[190:193], v[210:213], v[220:223], v[190:193]
	s_waitcnt vmcnt(11)
	ds_write_b128 v101, v[48:51] offset:49152
	v_mfma_f32_16x16x32_f16 v[76:79], v[210:213], v[228:231], v[76:79]
	ds_read_b128 v[210:213], v135 offset:34816
	v_mfma_f32_16x16x32_f16 v[154:157], v[224:227], v[198:201], v[154:157]
	s_waitcnt vmcnt(10)
	ds_write_b128 v131, v[52:55] offset:49152
	v_mfma_f32_16x16x32_f16 v[162:165], v[224:227], v[206:209], v[162:165]
	s_waitcnt vmcnt(9)
	ds_write_b128 v132, v[56:59] offset:49152
	s_waitcnt lgkmcnt(9)
	v_mfma_f32_16x16x32_f16 v[64:67], v[232:235], v[198:201], v[64:67]
	ds_read_b128 v[198:201], v134
	v_mfma_f32_16x16x32_f16 v[72:75], v[232:235], v[206:209], v[72:75]
	ds_read_b128 v[206:209], v134 offset:2048
	v_mfma_f32_16x16x32_f16 v[194:197], v[224:227], v[220:223], v[194:197]
	s_waitcnt vmcnt(8)
	ds_write_b128 v130, v[60:63] offset:49152
	v_mfma_f32_16x16x32_f16 v[84:87], v[224:227], v[228:231], v[84:87]
	ds_read_b128 v[224:227], v135 offset:36864
	v_mfma_f32_16x16x32_f16 v[80:83], v[232:235], v[220:223], v[80:83]
	ds_read_b128 v[220:223], v134 offset:4096
	v_mfma_f32_16x16x32_f16 v[88:91], v[232:235], v[228:231], v[88:91]
	ds_read_b128 v[228:231], v134 offset:6144
	ds_read_b128 v[232:235], v135 offset:38912
	s_waitcnt lgkmcnt(0)
	s_barrier
	v_mfma_f32_16x16x32_f16 v[138:141], v[202:205], v[198:201], v[138:141]
	global_load_dwordx4 v[32:35], v[108:109], off offset:896
	v_mfma_f32_16x16x32_f16 v[92:95], v[202:205], v[206:209], v[92:95]
	global_load_dwordx4 v[36:39], v[110:111], off offset:896
	v_mfma_f32_16x16x32_f16 v[142:145], v[210:213], v[198:201], v[142:145]
	global_load_dwordx4 v[40:43], v[112:113], off offset:896
	v_mfma_f32_16x16x32_f16 v[158:161], v[210:213], v[206:209], v[158:161]
	global_load_dwordx4 v[44:47], v[114:115], off offset:896
	v_mfma_f32_16x16x32_f16 v[166:169], v[202:205], v[220:223], v[166:169]
	global_load_dwordx4 v[48:51], v[116:117], off offset:896
	v_mfma_f32_16x16x32_f16 v[68:71], v[202:205], v[228:231], v[68:71]
	ds_read_b128 v[202:205], v136 offset:49152
	v_mfma_f32_16x16x32_f16 v[190:193], v[210:213], v[220:223], v[190:193]
	global_load_dwordx4 v[52:55], v[118:119], off offset:896
	v_mfma_f32_16x16x32_f16 v[76:79], v[210:213], v[228:231], v[76:79]
	ds_read_b128 v[210:213], v136 offset:51200
	v_mfma_f32_16x16x32_f16 v[154:157], v[224:227], v[198:201], v[154:157]
	global_load_dwordx4 v[56:59], v[120:121], off offset:896
	v_mfma_f32_16x16x32_f16 v[162:165], v[224:227], v[206:209], v[162:165]
	global_load_dwordx4 v[60:63], v[122:123], off offset:896
	v_mfma_f32_16x16x32_f16 v[64:67], v[232:235], v[198:201], v[64:67]
	ds_read_b128 v[198:201], v133 offset:16384
	v_mfma_f32_16x16x32_f16 v[72:75], v[232:235], v[206:209], v[72:75]
	ds_read_b128 v[206:209], v133 offset:18432
	v_mfma_f32_16x16x32_f16 v[194:197], v[224:227], v[220:223], v[194:197]
	v_mfma_f32_16x16x32_f16 v[84:87], v[224:227], v[228:231], v[84:87]
	ds_read_b128 v[224:227], v136 offset:53248
	v_mfma_f32_16x16x32_f16 v[80:83], v[232:235], v[220:223], v[80:83]
	ds_read_b128 v[220:223], v133 offset:20480
	v_mfma_f32_16x16x32_f16 v[88:91], v[232:235], v[228:231], v[88:91]
	ds_read_b128 v[228:231], v133 offset:22528
	s_waitcnt lgkmcnt(4)
; #define GL_LOAD(s_, kt_) if (VAR != 1) { a##s_##0 = GL_A(0, kt_); a##s_##1 = GL_A(1, kt_); a##s_##2 = GL_A(2, kt_); a##s_##3 = GL_A(3, kt_); b##s_##0 = GL_B(0, kt_); b##s_##1 = GL_B(1, kt_); b##s_##2 = GL_B(2, kt_); b##s_##3 = GL_B(3, kt_); }
; #define LDS_STORE(s_, buf_) if (VAR != 2) { LDS_ST1(sA, 0, buf_, a##s_##0) LDS_ST1(sA, 1, buf_, a##s_##1) LDS_ST1(sA, 2, buf_, a##s_##2) LDS_ST1(sA, 3, buf_, a##s_##3) LDS_ST1(sB, 0, buf_, b##s_##0) LDS_ST1(sB, 1, buf_, b##s_##1) LDS_ST1(sB, 2, buf_, b##s_##2) LDS_ST1(sB, 3, buf_, b##s_##3) }
;     ...
;   GL_LOAD(0, 0)
;   GL_LOAD(1, 1)
;   LDS_STORE(0, 0)
;   if (VAR != 4) __syncthreads();
; #pragma unroll
;   for (int kt = 0; kt < nk; kt += 2) {
;     if (kt + 2 < nk) { GL_LOAD(0, kt + 2) }
;     MMA_TILE(0)
;     LDS_STORE(1, 1)
;     if (VAR != 4) __syncthreads();
;     if (kt + 3 < nk) { GL_LOAD(1, kt + 3) }
;     MMA_TILE(1)
;     if (kt + 2 < nk) { LDS_STORE(0, 0) }
;     if (VAR != 4) __syncthreads();
	v_mfma_f32_16x16x32_f16 v[138:141], v[202:205], v[198:201], v[138:141]
	ds_read_b128 v[232:235], v136 offset:55296
	s_waitcnt lgkmcnt(4)
	v_mfma_f32_16x16x32_f16 v[92:95], v[202:205], v[206:209], v[92:95]
	s_waitcnt vmcnt(15)
	ds_write_b128 v101, v[0:3]
	v_mfma_f32_16x16x32_f16 v[142:145], v[210:213], v[198:201], v[142:145]
	s_waitcnt vmcnt(14)
	ds_write_b128 v131, v[4:7]
	v_mfma_f32_16x16x32_f16 v[158:161], v[210:213], v[206:209], v[158:161]
	s_waitcnt vmcnt(13)
	ds_write_b128 v132, v[8:11]
	s_waitcnt lgkmcnt(5)
	v_mfma_f32_16x16x32_f16 v[166:169], v[202:205], v[220:223], v[166:169]
	s_waitcnt vmcnt(12)
	ds_write_b128 v130, v[12:15]
	s_waitcnt lgkmcnt(5)
	v_mfma_f32_16x16x32_f16 v[68:71], v[202:205], v[228:231], v[68:71]
	ds_read_b128 v[202:205], v135 offset:49152
	v_mfma_f32_16x16x32_f16 v[190:193], v[210:213], v[220:223], v[190:193]
	s_waitcnt vmcnt(11)
	ds_write_b128 v101, v[16:19] offset:32768
	v_mfma_f32_16x16x32_f16 v[76:79], v[210:213], v[228:231], v[76:79]
	ds_read_b128 v[210:213], v135 offset:51200
	v_mfma_f32_16x16x32_f16 v[154:157], v[224:227], v[198:201], v[154:157]
	s_waitcnt vmcnt(10)
	ds_write_b128 v131, v[20:23] offset:32768
	v_mfma_f32_16x16x32_f16 v[162:165], v[224:227], v[206:209], v[162:165]
	s_waitcnt vmcnt(9)
	ds_write_b128 v132, v[24:27] offset:32768
	s_waitcnt lgkmcnt(9)
	v_mfma_f32_16x16x32_f16 v[64:67], v[232:235], v[198:201], v[64:67]
	ds_read_b128 v[198:201], v134 offset:16384
	v_mfma_f32_16x16x32_f16 v[72:75], v[232:235], v[206:209], v[72:75]
	ds_read_b128 v[206:209], v134 offset:18432
	v_mfma_f32_16x16x32_f16 v[194:197], v[224:227], v[220:223], v[194:197]
	s_waitcnt vmcnt(8)
	ds_write_b128 v130, v[28:31] offset:32768
	v_mfma_f32_16x16x32_f16 v[84:87], v[224:227], v[228:231], v[84:87]
	ds_read_b128 v[224:227], v135 offset:53248
	v_mfma_f32_16x16x32_f16 v[80:83], v[232:235], v[220:223], v[80:83]
	ds_read_b128 v[220:223], v134 offset:20480
	v_mfma_f32_16x16x32_f16 v[88:91], v[232:235], v[228:231], v[88:91]
	ds_read_b128 v[228:231], v134 offset:22528
	ds_read_b128 v[232:235], v135 offset:55296
	s_waitcnt lgkmcnt(0)
	s_barrier
	v_mfma_f32_16x16x32_f16 v[138:141], v[202:205], v[198:201], v[138:141]
	global_load_dwordx4 v[0:3], v[108:109], off offset:1024
	v_mfma_f32_16x16x32_f16 v[92:95], v[202:205], v[206:209], v[92:95]
	global_load_dwordx4 v[4:7], v[110:111], off offset:1024
	v_mfma_f32_16x16x32_f16 v[142:145], v[210:213], v[198:201], v[142:145]
	global_load_dwordx4 v[8:11], v[112:113], off offset:1024
	v_mfma_f32_16x16x32_f16 v[158:161], v[210:213], v[206:209], v[158:161]
	global_load_dwordx4 v[12:15], v[114:115], off offset:1024
	v_mfma_f32_16x16x32_f16 v[166:169], v[202:205], v[220:223], v[166:169]
	global_load_dwordx4 v[16:19], v[116:117], off offset:1024
	v_mfma_f32_16x16x32_f16 v[68:71], v[202:205], v[228:231], v[68:71]
	ds_read_b128 v[202:205], v136 offset:32768
	v_mfma_f32_16x16x32_f16 v[190:193], v[210:213], v[220:223], v[190:193]
	global_load_dwordx4 v[20:23], v[118:119], off offset:1024
	v_mfma_f32_16x16x32_f16 v[76:79], v[210:213], v[228:231], v[76:79]
	ds_read_b128 v[210:213], v136 offset:34816
	v_mfma_f32_16x16x32_f16 v[154:157], v[224:227], v[198:201], v[154:157]
	global_load_dwordx4 v[24:27], v[120:121], off offset:1024
	v_mfma_f32_16x16x32_f16 v[162:165], v[224:227], v[206:209], v[162:165]
	global_load_dwordx4 v[28:31], v[122:123], off offset:1024
	v_mfma_f32_16x16x32_f16 v[64:67], v[232:235], v[198:201], v[64:67]
	ds_read_b128 v[198:201], v133
	v_mfma_f32_16x16x32_f16 v[72:75], v[232:235], v[206:209], v[72:75]
	ds_read_b128 v[206:209], v133 offset:2048
	v_mfma_f32_16x16x32_f16 v[194:197], v[224:227], v[220:223], v[194:197]
	v_mfma_f32_16x16x32_f16 v[84:87], v[224:227], v[228:231], v[84:87]
	ds_read_b128 v[224:227], v136 offset:36864
	v_mfma_f32_16x16x32_f16 v[80:83], v[232:235], v[220:223], v[80:83]
	ds_read_b128 v[220:223], v133 offset:4096
	v_mfma_f32_16x16x32_f16 v[88:91], v[232:235], v[228:231], v[88:91]
	ds_read_b128 v[228:231], v133 offset:6144
	s_waitcnt lgkmcnt(4)
	v_mfma_f32_16x16x32_f16 v[138:141], v[202:205], v[198:201], v[138:141]
	ds_read_b128 v[232:235], v136 offset:38912
	s_waitcnt lgkmcnt(4)
	v_mfma_f32_16x16x32_f16 v[92:95], v[202:205], v[206:209], v[92:95]
	s_waitcnt vmcnt(15)
	ds_write_b128 v101, v[32:35] offset:16384
	v_mfma_f32_16x16x32_f16 v[142:145], v[210:213], v[198:201], v[142:145]
	s_waitcnt vmcnt(14)
	ds_write_b128 v131, v[36:39] offset:16384
	v_mfma_f32_16x16x32_f16 v[158:161], v[210:213], v[206:209], v[158:161]
	s_waitcnt vmcnt(13)
	ds_write_b128 v132, v[40:43] offset:16384
	s_waitcnt lgkmcnt(5)
	v_mfma_f32_16x16x32_f16 v[166:169], v[202:205], v[220:223], v[166:169]
	s_waitcnt vmcnt(12)
	ds_write_b128 v130, v[44:47] offset:16384
	s_waitcnt lgkmcnt(5)
	v_mfma_f32_16x16x32_f16 v[68:71], v[202:205], v[228:231], v[68:71]
	ds_read_b128 v[202:205], v135 offset:32768
	v_mfma_f32_16x16x32_f16 v[190:193], v[210:213], v[220:223], v[190:193]
	s_waitcnt vmcnt(11)
	ds_write_b128 v101, v[48:51] offset:49152
	v_mfma_f32_16x16x32_f16 v[76:79], v[210:213], v[228:231], v[76:79]
	ds_read_b128 v[210:213], v135 offset:34816
	v_mfma_f32_16x16x32_f16 v[154:157], v[224:227], v[198:201], v[154:157]
	s_waitcnt vmcnt(10)
	ds_write_b128 v131, v[52:55] offset:49152
	v_mfma_f32_16x16x32_f16 v[162:165], v[224:227], v[206:209], v[162:165]
	s_waitcnt vmcnt(9)
	ds_write_b128 v132, v[56:59] offset:49152
	s_waitcnt lgkmcnt(9)
	v_mfma_f32_16x16x32_f16 v[64:67], v[232:235], v[198:201], v[64:67]
	ds_read_b128 v[198:201], v134
	v_mfma_f32_16x16x32_f16 v[72:75], v[232:235], v[206:209], v[72:75]
	ds_read_b128 v[206:209], v134 offset:2048
	v_mfma_f32_16x16x32_f16 v[194:197], v[224:227], v[220:223], v[194:197]
	s_waitcnt vmcnt(8)
	ds_write_b128 v130, v[60:63] offset:49152
	v_mfma_f32_16x16x32_f16 v[84:87], v[224:227], v[228:231], v[84:87]
	ds_read_b128 v[224:227], v135 offset:36864
	v_mfma_f32_16x16x32_f16 v[80:83], v[232:235], v[220:223], v[80:83]
	ds_read_b128 v[220:223], v134 offset:4096
	v_mfma_f32_16x16x32_f16 v[88:91], v[232:235], v[228:231], v[88:91]
	ds_read_b128 v[228:231], v134 offset:6144
	ds_read_b128 v[232:235], v135 offset:38912
	s_waitcnt lgkmcnt(0)
	s_barrier
; #define GL_LOAD(s_, kt_) if (VAR != 1) { a##s_##0 = GL_A(0, kt_); a##s_##1 = GL_A(1, kt_); a##s_##2 = GL_A(2, kt_); a##s_##3 = GL_A(3, kt_); b##s_##0 = GL_B(0, kt_); b##s_##1 = GL_B(1, kt_); b##s_##2 = GL_B(2, kt_); b##s_##3 = GL_B(3, kt_); }
; #define LDS_STORE(s_, buf_) if (VAR != 2) { LDS_ST1(sA, 0, buf_, a##s_##0) LDS_ST1(sA, 1, buf_, a##s_##1) LDS_ST1(sA, 2, buf_, a##s_##2) LDS_ST1(sA, 3, buf_, a##s_##3) LDS_ST1(sB, 0, buf_, b##s_##0) LDS_ST1(sB, 1, buf_, b##s_##1) LDS_ST1(sB, 2, buf_, b##s_##2) LDS_ST1(sB, 3, buf_, b##s_##3) }
;     ...
;   GL_LOAD(0, 0)
;   GL_LOAD(1, 1)
;   LDS_STORE(0, 0)
;   if (VAR != 4) __syncthreads();
; #pragma unroll
;   for (int kt = 0; kt < nk; kt += 2) {
;     if (kt + 2 < nk) { GL_LOAD(0, kt + 2) }
;     MMA_TILE(0)
;     LDS_STORE(1, 1)
;     if (VAR != 4) __syncthreads();
;     if (kt + 3 < nk) { GL_LOAD(1, kt + 3) }
;     MMA_TILE(1)
;     if (kt + 2 < nk) { LDS_STORE(0, 0) }
;     if (VAR != 4) __syncthreads();
	v_mfma_f32_16x16x32_f16 v[138:141], v[202:205], v[198:201], v[138:141]
	global_load_dwordx4 v[32:35], v[108:109], off offset:1152
	v_mfma_f32_16x16x32_f16 v[92:95], v[202:205], v[206:209], v[92:95]
	global_load_dwordx4 v[36:39], v[110:111], off offset:1152
	v_mfma_f32_16x16x32_f16 v[142:145], v[210:213], v[198:201], v[142:145]
	global_load_dwordx4 v[40:43], v[112:113], off offset:1152
	v_mfma_f32_16x16x32_f16 v[158:161], v[210:213], v[206:209], v[158:161]
	global_load_dwordx4 v[44:47], v[114:115], off offset:1152
	v_mfma_f32_16x16x32_f16 v[166:169], v[202:205], v[220:223], v[166:169]
	global_load_dwordx4 v[48:51], v[116:117], off offset:1152
	v_mfma_f32_16x16x32_f16 v[68:71], v[202:205], v[228:231], v[68:71]
	ds_read_b128 v[202:205], v136 offset:49152
	v_mfma_f32_16x16x32_f16 v[190:193], v[210:213], v[220:223], v[190:193]
	global_load_dwordx4 v[52:55], v[118:119], off offset:1152
	v_mfma_f32_16x16x32_f16 v[76:79], v[210:213], v[228:231], v[76:79]
	ds_read_b128 v[210:213], v136 offset:51200
	v_mfma_f32_16x16x32_f16 v[154:157], v[224:227], v[198:201], v[154:157]
	global_load_dwordx4 v[56:59], v[120:121], off offset:1152
	v_mfma_f32_16x16x32_f16 v[162:165], v[224:227], v[206:209], v[162:165]
	global_load_dwordx4 v[60:63], v[122:123], off offset:1152
	v_mfma_f32_16x16x32_f16 v[64:67], v[232:235], v[198:201], v[64:67]
	ds_read_b128 v[198:201], v133 offset:16384
	v_mfma_f32_16x16x32_f16 v[72:75], v[232:235], v[206:209], v[72:75]
	ds_read_b128 v[206:209], v133 offset:18432
	v_mfma_f32_16x16x32_f16 v[194:197], v[224:227], v[220:223], v[194:197]
	v_mfma_f32_16x16x32_f16 v[84:87], v[224:227], v[228:231], v[84:87]
	ds_read_b128 v[224:227], v136 offset:53248
	v_mfma_f32_16x16x32_f16 v[80:83], v[232:235], v[220:223], v[80:83]
	ds_read_b128 v[220:223], v133 offset:20480
	v_mfma_f32_16x16x32_f16 v[88:91], v[232:235], v[228:231], v[88:91]
	ds_read_b128 v[228:231], v133 offset:22528
	s_waitcnt lgkmcnt(4)
	v_mfma_f32_16x16x32_f16 v[138:141], v[202:205], v[198:201], v[138:141]
	ds_read_b128 v[232:235], v136 offset:55296
	s_waitcnt lgkmcnt(4)
	v_mfma_f32_16x16x32_f16 v[92:95], v[202:205], v[206:209], v[92:95]
	s_waitcnt vmcnt(15)
	ds_write_b128 v101, v[0:3]
	v_mfma_f32_16x16x32_f16 v[142:145], v[210:213], v[198:201], v[142:145]
	s_waitcnt vmcnt(14)
	ds_write_b128 v131, v[4:7]
	v_mfma_f32_16x16x32_f16 v[158:161], v[210:213], v[206:209], v[158:161]
	s_waitcnt vmcnt(13)
	ds_write_b128 v132, v[8:11]
	s_waitcnt lgkmcnt(5)
	v_mfma_f32_16x16x32_f16 v[166:169], v[202:205], v[220:223], v[166:169]
	s_waitcnt vmcnt(12)
	ds_write_b128 v130, v[12:15]
	s_waitcnt lgkmcnt(5)
	v_mfma_f32_16x16x32_f16 v[68:71], v[202:205], v[228:231], v[68:71]
	ds_read_b128 v[202:205], v135 offset:49152
	v_mfma_f32_16x16x32_f16 v[190:193], v[210:213], v[220:223], v[190:193]
	s_waitcnt vmcnt(11)
	ds_write_b128 v101, v[16:19] offset:32768
	v_mfma_f32_16x16x32_f16 v[76:79], v[210:213], v[228:231], v[76:79]
	ds_read_b128 v[210:213], v135 offset:51200
	v_mfma_f32_16x16x32_f16 v[154:157], v[224:227], v[198:201], v[154:157]
	s_waitcnt vmcnt(10)
	ds_write_b128 v131, v[20:23] offset:32768
	v_mfma_f32_16x16x32_f16 v[162:165], v[224:227], v[206:209], v[162:165]
	s_waitcnt vmcnt(9)
	ds_write_b128 v132, v[24:27] offset:32768
	s_waitcnt lgkmcnt(9)
	v_mfma_f32_16x16x32_f16 v[64:67], v[232:235], v[198:201], v[64:67]
	ds_read_b128 v[198:201], v134 offset:16384
	v_mfma_f32_16x16x32_f16 v[72:75], v[232:235], v[206:209], v[72:75]
	ds_read_b128 v[206:209], v134 offset:18432
	v_mfma_f32_16x16x32_f16 v[194:197], v[224:227], v[220:223], v[194:197]
	s_waitcnt vmcnt(8)
	ds_write_b128 v130, v[28:31] offset:32768
	v_mfma_f32_16x16x32_f16 v[84:87], v[224:227], v[228:231], v[84:87]
	ds_read_b128 v[224:227], v135 offset:53248
	v_mfma_f32_16x16x32_f16 v[80:83], v[232:235], v[220:223], v[80:83]
	ds_read_b128 v[220:223], v134 offset:20480
	v_mfma_f32_16x16x32_f16 v[88:91], v[232:235], v[228:231], v[88:91]
	ds_read_b128 v[228:231], v134 offset:22528
	s_waitcnt lgkmcnt(5)
	v_mfma_f32_16x16x32_f16 v[138:141], v[202:205], v[198:201], v[138:141]
	ds_read_b128 v[232:235], v135 offset:55296
	s_waitcnt lgkmcnt(0)
	s_barrier
	v_mfma_f32_16x16x32_f16 v[142:145], v[210:213], v[198:201], v[142:145]
	ds_read_b128 v[0:3], v133
	v_mfma_f32_16x16x32_f16 v[158:161], v[210:213], v[206:209], v[158:161]
	ds_read_b128 v[4:7], v136 offset:32768
	v_mfma_f32_16x16x32_f16 v[154:157], v[224:227], v[198:201], v[154:157]
	ds_read_b128 v[8:11], v133 offset:2048
	v_mfma_f32_16x16x32_f16 v[162:165], v[224:227], v[206:209], v[162:165]
	ds_read_b128 v[12:15], v136 offset:34816
	v_mfma_f32_16x16x32_f16 v[190:193], v[210:213], v[220:223], v[190:193]
	ds_read_b128 v[16:19], v133 offset:4096
	v_mfma_f32_16x16x32_f16 v[210:213], v[210:213], v[228:231], v[76:79]
	ds_read_b128 v[20:23], v136 offset:36864
	v_mfma_f32_16x16x32_f16 v[194:197], v[224:227], v[220:223], v[194:197]
	ds_read_b128 v[24:27], v133 offset:6144
	v_mfma_f32_16x16x32_f16 v[224:227], v[224:227], v[228:231], v[84:87]
	ds_read_b128 v[28:31], v136 offset:38912
	v_mfma_f32_16x16x32_f16 v[198:201], v[232:235], v[198:201], v[64:67]
	s_nop 2
	global_load_dwordx4 v[64:67], v[108:109], off offset:1280
	v_mfma_f32_16x16x32_f16 v[236:239], v[202:205], v[206:209], v[92:95]
	v_mfma_f32_16x16x32_f16 v[206:209], v[232:235], v[206:209], v[72:75]
	v_mfma_f32_16x16x32_f16 v[166:169], v[202:205], v[220:223], v[166:169]
	v_mfma_f32_16x16x32_f16 v[220:223], v[232:235], v[220:223], v[80:83]
	v_mfma_f32_16x16x32_f16 v[202:205], v[202:205], v[228:231], v[68:71]
	v_mfma_f32_16x16x32_f16 v[228:231], v[232:235], v[228:231], v[88:91]
	ds_read_b128 v[232:235], v135 offset:38912
	s_nop 0
	global_load_dwordx4 v[68:71], v[110:111], off offset:1280
	global_load_dwordx4 v[72:75], v[112:113], off offset:1280
	global_load_dwordx4 v[76:79], v[114:115], off offset:1280
	global_load_dwordx4 v[80:83], v[116:117], off offset:1280
	s_waitcnt lgkmcnt(7)
; #define GL_LOAD(s_, kt_) if (VAR != 1) { a##s_##0 = GL_A(0, kt_); a##s_##1 = GL_A(1, kt_); a##s_##2 = GL_A(2, kt_); a##s_##3 = GL_A(3, kt_); b##s_##0 = GL_B(0, kt_); b##s_##1 = GL_B(1, kt_); b##s_##2 = GL_B(2, kt_); b##s_##3 = GL_B(3, kt_); }
; #define LDS_STORE(s_, buf_) if (VAR != 2) { LDS_ST1(sA, 0, buf_, a##s_##0) LDS_ST1(sA, 1, buf_, a##s_##1) LDS_ST1(sA, 2, buf_, a##s_##2) LDS_ST1(sA, 3, buf_, a##s_##3) LDS_ST1(sB, 0, buf_, b##s_##0) LDS_ST1(sB, 1, buf_, b##s_##1) LDS_ST1(sB, 2, buf_, b##s_##2) LDS_ST1(sB, 3, buf_, b##s_##3) }
;     ...
;   GL_LOAD(0, 0)
;   GL_LOAD(1, 1)
;   LDS_STORE(0, 0)
;   if (VAR != 4) __syncthreads();
; #pragma unroll
;   for (int kt = 0; kt < nk; kt += 2) {
;     if (kt + 2 < nk) { GL_LOAD(0, kt + 2) }
;     MMA_TILE(0)
;     LDS_STORE(1, 1)
;     if (VAR != 4) __syncthreads();
;     if (kt + 3 < nk) { GL_LOAD(1, kt + 3) }
;     MMA_TILE(1)
;     if (kt + 2 < nk) { LDS_STORE(0, 0) }
;     if (VAR != 4) __syncthreads();
	v_mfma_f32_16x16x32_f16 v[138:141], v[4:7], v[0:3], v[138:141]
	global_load_dwordx4 v[84:87], v[118:119], off offset:1280
	s_waitcnt lgkmcnt(5)
	v_mfma_f32_16x16x32_f16 v[142:145], v[12:15], v[0:3], v[142:145]
	s_waitcnt lgkmcnt(3)
	v_mfma_f32_16x16x32_f16 v[154:157], v[20:23], v[0:3], v[154:157]
	s_waitcnt lgkmcnt(1)
	v_mfma_f32_16x16x32_f16 v[0:3], v[28:31], v[0:3], v[198:201]
	v_mfma_f32_16x16x32_f16 v[198:201], v[4:7], v[8:11], v[236:239]
	global_load_dwordx4 v[88:91], v[120:121], off offset:1280
	global_load_dwordx4 v[92:95], v[122:123], off offset:1280
	s_waitcnt vmcnt(15)
	ds_write_b128 v101, v[32:35] offset:16384
	s_waitcnt vmcnt(14)
	ds_write_b128 v131, v[36:39] offset:16384
	v_mfma_f32_16x16x32_f16 v[158:161], v[12:15], v[8:11], v[158:161]
	s_waitcnt vmcnt(13)
	ds_write_b128 v132, v[40:43] offset:16384
	v_mfma_f32_16x16x32_f16 v[166:169], v[4:7], v[16:19], v[166:169]
	s_waitcnt vmcnt(12)
	ds_write_b128 v130, v[44:47] offset:16384
	v_mfma_f32_16x16x32_f16 v[4:7], v[4:7], v[24:27], v[202:205]
	s_nop 2
	ds_read_b128 v[202:205], v135 offset:32768
	v_mfma_f32_16x16x32_f16 v[190:193], v[12:15], v[16:19], v[190:193]
	s_waitcnt vmcnt(11)
	ds_write_b128 v101, v[48:51] offset:49152
	v_mfma_f32_16x16x32_f16 v[12:15], v[12:15], v[24:27], v[210:213]
	s_nop 2
	ds_read_b128 v[210:213], v135 offset:34816
	s_waitcnt vmcnt(10)
	ds_write_b128 v131, v[52:55] offset:49152
	v_mfma_f32_16x16x32_f16 v[162:165], v[20:23], v[8:11], v[162:165]
	s_waitcnt vmcnt(9)
	ds_write_b128 v132, v[56:59] offset:49152
	s_waitcnt vmcnt(8)
	ds_write_b128 v130, v[60:63] offset:49152
	v_mfma_f32_16x16x32_f16 v[8:11], v[28:31], v[8:11], v[206:209]
	s_nop 2
	ds_read_b128 v[206:209], v134 offset:2048
	v_mfma_f32_16x16x32_f16 v[194:197], v[20:23], v[16:19], v[194:197]
	v_mfma_f32_16x16x32_f16 v[20:23], v[20:23], v[24:27], v[224:227]
	s_nop 2
	ds_read_b128 v[224:227], v135 offset:36864
	v_mfma_f32_16x16x32_f16 v[16:19], v[28:31], v[16:19], v[220:223]
	s_nop 2
	ds_read_b128 v[220:223], v134 offset:4096
	v_mfma_f32_16x16x32_f16 v[24:27], v[28:31], v[24:27], v[228:231]
	ds_read_b128 v[28:31], v134
	s_waitcnt lgkmcnt(0)
	v_mfma_f32_16x16x32_f16 v[138:141], v[202:205], v[28:31], v[138:141]
	ds_read_b128 v[228:231], v134 offset:6144
	s_waitcnt lgkmcnt(0)
	s_barrier
	v_mfma_f32_16x16x32_f16 v[142:145], v[210:213], v[28:31], v[142:145]
	ds_read_b128 v[32:35], v133 offset:16384
	v_mfma_f32_16x16x32_f16 v[158:161], v[210:213], v[206:209], v[158:161]
	ds_read_b128 v[36:39], v136 offset:49152
	v_mfma_f32_16x16x32_f16 v[154:157], v[224:227], v[28:31], v[154:157]
	ds_read_b128 v[40:43], v133 offset:18432
	v_mfma_f32_16x16x32_f16 v[162:165], v[224:227], v[206:209], v[162:165]
	ds_read_b128 v[44:47], v136 offset:51200
	v_mfma_f32_16x16x32_f16 v[190:193], v[210:213], v[220:223], v[190:193]
	ds_read_b128 v[48:51], v133 offset:20480
	v_mfma_f32_16x16x32_f16 v[210:213], v[210:213], v[228:231], v[12:15]
	ds_read_b128 v[52:55], v136 offset:53248
	v_mfma_f32_16x16x32_f16 v[194:197], v[224:227], v[220:223], v[194:197]
	ds_read_b128 v[56:59], v133 offset:22528
	v_mfma_f32_16x16x32_f16 v[224:227], v[224:227], v[228:231], v[20:23]
	ds_read_b128 v[60:63], v136 offset:55296
	v_mfma_f32_16x16x32_f16 v[236:239], v[232:235], v[28:31], v[0:3]
	global_load_dwordx4 v[28:31], v[108:109], off offset:1408
	v_mfma_f32_16x16x32_f16 v[198:201], v[202:205], v[206:209], v[198:201]
	v_mfma_f32_16x16x32_f16 v[206:209], v[232:235], v[206:209], v[8:11]
	v_mfma_f32_16x16x32_f16 v[166:169], v[202:205], v[220:223], v[166:169]
	v_mfma_f32_16x16x32_f16 v[220:223], v[232:235], v[220:223], v[16:19]
	v_mfma_f32_16x16x32_f16 v[202:205], v[202:205], v[228:231], v[4:7]
	v_mfma_f32_16x16x32_f16 v[228:231], v[232:235], v[228:231], v[24:27]
	ds_read_b128 v[232:235], v135 offset:55296
	s_nop 1
	global_load_dwordx4 v[24:27], v[110:111], off offset:1408
	global_load_dwordx4 v[12:15], v[112:113], off offset:1408
	global_load_dwordx4 v[16:19], v[114:115], off offset:1408
	global_load_dwordx4 v[20:23], v[116:117], off offset:1408
	s_waitcnt lgkmcnt(7)
	v_mfma_f32_16x16x32_f16 v[138:141], v[36:39], v[32:35], v[138:141]
	global_load_dwordx4 v[0:3], v[118:119], off offset:1408
	s_waitcnt lgkmcnt(6)
	v_mfma_f32_16x16x32_f16 v[198:201], v[36:39], v[40:43], v[198:201]
	global_load_dwordx4 v[4:7], v[120:121], off offset:1408
	s_waitcnt lgkmcnt(5)
	v_mfma_f32_16x16x32_f16 v[142:145], v[44:47], v[32:35], v[142:145]
	global_load_dwordx4 v[8:11], v[122:123], off offset:1408
	v_mfma_f32_16x16x32_f16 v[158:161], v[44:47], v[40:43], v[158:161]
	s_waitcnt vmcnt(15)
	ds_write_b128 v101, v[64:67]
	s_waitcnt lgkmcnt(5)
	v_mfma_f32_16x16x32_f16 v[166:169], v[36:39], v[48:51], v[166:169]
	s_waitcnt vmcnt(14)
	ds_write_b128 v131, v[68:71]
	s_waitcnt lgkmcnt(4)
	v_mfma_f32_16x16x32_f16 v[36:39], v[36:39], v[56:59], v[202:205]
	s_nop 2
	ds_read_b128 v[202:205], v135 offset:49152
	v_mfma_f32_16x16x32_f16 v[190:193], v[44:47], v[48:51], v[190:193]
	s_waitcnt vmcnt(13)
	ds_write_b128 v132, v[72:75]
	v_mfma_f32_16x16x32_f16 v[44:47], v[44:47], v[56:59], v[210:213]
	s_nop 2
	ds_read_b128 v[210:213], v135 offset:51200
	v_mfma_f32_16x16x32_f16 v[154:157], v[52:55], v[32:35], v[154:157]
	s_waitcnt vmcnt(12)
	ds_write_b128 v130, v[76:79]
	v_mfma_f32_16x16x32_f16 v[162:165], v[52:55], v[40:43], v[162:165]
	s_waitcnt vmcnt(11)
	ds_write_b128 v101, v[80:83] offset:32768
	s_waitcnt lgkmcnt(8)
	v_mfma_f32_16x16x32_f16 v[32:35], v[60:63], v[32:35], v[236:239]
	s_waitcnt vmcnt(10)
	ds_write_b128 v131, v[84:87] offset:32768
	v_mfma_f32_16x16x32_f16 v[40:43], v[60:63], v[40:43], v[206:209]
	s_nop 2
	ds_read_b128 v[206:209], v134 offset:18432
	v_mfma_f32_16x16x32_f16 v[194:197], v[52:55], v[48:51], v[194:197]
	s_waitcnt vmcnt(9)
	ds_write_b128 v132, v[88:91] offset:32768
	v_mfma_f32_16x16x32_f16 v[52:55], v[52:55], v[56:59], v[224:227]
	s_nop 2
	ds_read_b128 v[224:227], v135 offset:53248
	v_mfma_f32_16x16x32_f16 v[48:51], v[60:63], v[48:51], v[220:223]
	s_nop 2
	ds_read_b128 v[220:223], v134 offset:20480
	v_mfma_f32_16x16x32_f16 v[56:59], v[60:63], v[56:59], v[228:231]
	ds_read_b128 v[60:63], v134 offset:16384
	s_waitcnt lgkmcnt(0)
	v_mfma_f32_16x16x32_f16 v[138:141], v[202:205], v[60:63], v[138:141]
	ds_read_b128 v[228:231], v134 offset:22528
	s_waitcnt vmcnt(8)
	ds_write_b128 v130, v[92:95] offset:32768
	s_waitcnt lgkmcnt(0)
	s_barrier
; #define GL_LOAD(s_, kt_) if (VAR != 1) { a##s_##0 = GL_A(0, kt_); a##s_##1 = GL_A(1, kt_); a##s_##2 = GL_A(2, kt_); a##s_##3 = GL_A(3, kt_); b##s_##0 = GL_B(0, kt_); b##s_##1 = GL_B(1, kt_); b##s_##2 = GL_B(2, kt_); b##s_##3 = GL_B(3, kt_); }
; #define LDS_STORE(s_, buf_) if (VAR != 2) { LDS_ST1(sA, 0, buf_, a##s_##0) LDS_ST1(sA, 1, buf_, a##s_##1) LDS_ST1(sA, 2, buf_, a##s_##2) LDS_ST1(sA, 3, buf_, a##s_##3) LDS_ST1(sB, 0, buf_, b##s_##0) LDS_ST1(sB, 1, buf_, b##s_##1) LDS_ST1(sB, 2, buf_, b##s_##2) LDS_ST1(sB, 3, buf_, b##s_##3) }
;     ...
;   GL_LOAD(0, 0)
;   GL_LOAD(1, 1)
;   LDS_STORE(0, 0)
;   if (VAR != 4) __syncthreads();
; #pragma unroll
;   for (int kt = 0; kt < nk; kt += 2) {
;     if (kt + 2 < nk) { GL_LOAD(0, kt + 2) }
;     MMA_TILE(0)
;     LDS_STORE(1, 1)
;     if (VAR != 4) __syncthreads();
;     if (kt + 3 < nk) { GL_LOAD(1, kt + 3) }
;     MMA_TILE(1)
;     if (kt + 2 < nk) { LDS_STORE(0, 0) }
;     if (VAR != 4) __syncthreads();
	v_mfma_f32_16x16x32_f16 v[142:145], v[210:213], v[60:63], v[142:145]
	ds_read_b128 v[64:67], v133
	v_mfma_f32_16x16x32_f16 v[158:161], v[210:213], v[206:209], v[158:161]
	ds_read_b128 v[68:71], v136 offset:32768
	v_mfma_f32_16x16x32_f16 v[154:157], v[224:227], v[60:63], v[154:157]
	ds_read_b128 v[72:75], v133 offset:2048
	v_mfma_f32_16x16x32_f16 v[162:165], v[224:227], v[206:209], v[162:165]
	ds_read_b128 v[76:79], v136 offset:34816
	v_mfma_f32_16x16x32_f16 v[190:193], v[210:213], v[220:223], v[190:193]
	ds_read_b128 v[80:83], v133 offset:4096
	v_mfma_f32_16x16x32_f16 v[210:213], v[210:213], v[228:231], v[44:47]
	ds_read_b128 v[84:87], v136 offset:36864
	v_mfma_f32_16x16x32_f16 v[194:197], v[224:227], v[220:223], v[194:197]
	ds_read_b128 v[88:91], v133 offset:6144
	v_mfma_f32_16x16x32_f16 v[224:227], v[224:227], v[228:231], v[52:55]
	ds_read_b128 v[92:95], v136 offset:38912
	v_mfma_f32_16x16x32_f16 v[236:239], v[232:235], v[60:63], v[32:35]
	s_nop 0
	global_load_dwordx4 v[52:55], v[108:109], off offset:1536
	v_mfma_f32_16x16x32_f16 v[198:201], v[202:205], v[206:209], v[198:201]
	v_mfma_f32_16x16x32_f16 v[206:209], v[232:235], v[206:209], v[40:43]
	v_mfma_f32_16x16x32_f16 v[166:169], v[202:205], v[220:223], v[166:169]
	v_mfma_f32_16x16x32_f16 v[220:223], v[232:235], v[220:223], v[48:51]
	s_waitcnt vmcnt(8)
	ds_write_b128 v101, v[28:31] offset:16384
	s_waitcnt vmcnt(7)
	ds_write_b128 v131, v[24:27] offset:16384
	v_mfma_f32_16x16x32_f16 v[202:205], v[202:205], v[228:231], v[36:39]
	v_mfma_f32_16x16x32_f16 v[228:231], v[232:235], v[228:231], v[56:59]
	ds_read_b128 v[232:235], v135 offset:38912
	s_nop 1
	global_load_dwordx4 v[56:59], v[110:111], off offset:1536
	global_load_dwordx4 v[60:63], v[112:113], off offset:1536
	global_load_dwordx4 v[40:43], v[114:115], off offset:1536
	global_load_dwordx4 v[44:47], v[116:117], off offset:1536
	s_waitcnt lgkmcnt(9)
	v_mfma_f32_16x16x32_f16 v[138:141], v[68:71], v[64:67], v[138:141]
	global_load_dwordx4 v[48:51], v[118:119], off offset:1536
	s_waitcnt lgkmcnt(8)
	v_mfma_f32_16x16x32_f16 v[198:201], v[68:71], v[72:75], v[198:201]
	global_load_dwordx4 v[32:35], v[120:121], off offset:1536
	s_waitcnt lgkmcnt(7)
	v_mfma_f32_16x16x32_f16 v[142:145], v[76:79], v[64:67], v[142:145]
	global_load_dwordx4 v[36:39], v[122:123], off offset:1536
	v_mfma_f32_16x16x32_f16 v[158:161], v[76:79], v[72:75], v[158:161]
	s_waitcnt vmcnt(13)
	ds_write_b128 v132, v[12:15] offset:16384
	s_waitcnt lgkmcnt(7)
	v_mfma_f32_16x16x32_f16 v[166:169], v[68:71], v[80:83], v[166:169]
	s_waitcnt vmcnt(12)
	ds_write_b128 v130, v[16:19] offset:16384
	s_waitcnt lgkmcnt(6)
	v_mfma_f32_16x16x32_f16 v[68:71], v[68:71], v[88:91], v[202:205]
	s_nop 2
	ds_read_b128 v[202:205], v135 offset:32768
	v_mfma_f32_16x16x32_f16 v[190:193], v[76:79], v[80:83], v[190:193]
	s_waitcnt vmcnt(11)
	ds_write_b128 v101, v[20:23] offset:49152
	v_mfma_f32_16x16x32_f16 v[76:79], v[76:79], v[88:91], v[210:213]
	s_nop 2
	ds_read_b128 v[210:213], v135 offset:34816
	v_mfma_f32_16x16x32_f16 v[154:157], v[84:87], v[64:67], v[154:157]
	s_waitcnt vmcnt(10)
	ds_write_b128 v131, v[0:3] offset:49152
	v_mfma_f32_16x16x32_f16 v[162:165], v[84:87], v[72:75], v[162:165]
	s_waitcnt vmcnt(9)
	ds_write_b128 v132, v[4:7] offset:49152
	s_waitcnt lgkmcnt(10)
	v_mfma_f32_16x16x32_f16 v[64:67], v[92:95], v[64:67], v[236:239]
	s_waitcnt vmcnt(8)
	ds_write_b128 v130, v[8:11] offset:49152
	v_mfma_f32_16x16x32_f16 v[72:75], v[92:95], v[72:75], v[206:209]
	s_nop 2
	ds_read_b128 v[206:209], v134 offset:2048
	v_mfma_f32_16x16x32_f16 v[194:197], v[84:87], v[80:83], v[194:197]
	v_mfma_f32_16x16x32_f16 v[84:87], v[84:87], v[88:91], v[224:227]
	s_nop 2
	ds_read_b128 v[224:227], v135 offset:36864
	v_mfma_f32_16x16x32_f16 v[80:83], v[92:95], v[80:83], v[220:223]
	s_nop 2
	ds_read_b128 v[220:223], v134 offset:4096
	v_mfma_f32_16x16x32_f16 v[88:91], v[92:95], v[88:91], v[228:231]
	ds_read_b128 v[92:95], v134
	s_nop 1
	ds_read_b128 v[228:231], v134 offset:6144
	s_waitcnt lgkmcnt(0)
	s_barrier
	v_mfma_f32_16x16x32_f16 v[138:141], v[202:205], v[92:95], v[138:141]
	global_load_dwordx4 v[20:23], v[108:109], off offset:1664
	v_mfma_f32_16x16x32_f16 v[142:145], v[210:213], v[92:95], v[142:145]
	v_mfma_f32_16x16x32_f16 v[154:157], v[224:227], v[92:95], v[154:157]
	v_mfma_f32_16x16x32_f16 v[64:67], v[232:235], v[92:95], v[64:67]
	v_mfma_f32_16x16x32_f16 v[92:95], v[202:205], v[206:209], v[198:201]
	s_nop 2
	ds_read_b128 v[198:201], v133 offset:16384
	global_load_dwordx4 v[24:27], v[110:111], off offset:1664
	global_load_dwordx4 v[28:31], v[112:113], off offset:1664
	v_mfma_f32_16x16x32_f16 v[158:161], v[210:213], v[206:209], v[158:161]
	global_load_dwordx4 v[8:11], v[114:115], off offset:1664
	v_mfma_f32_16x16x32_f16 v[166:169], v[202:205], v[220:223], v[166:169]
	global_load_dwordx4 v[12:15], v[116:117], off offset:1664
	v_mfma_f32_16x16x32_f16 v[68:71], v[202:205], v[228:231], v[68:71]
	ds_read_b128 v[202:205], v136 offset:49152
	v_mfma_f32_16x16x32_f16 v[190:193], v[210:213], v[220:223], v[190:193]
	global_load_dwordx4 v[16:19], v[118:119], off offset:1664
	v_mfma_f32_16x16x32_f16 v[76:79], v[210:213], v[228:231], v[76:79]
	ds_read_b128 v[210:213], v136 offset:51200
	global_load_dwordx4 v[0:3], v[120:121], off offset:1664
	v_mfma_f32_16x16x32_f16 v[162:165], v[224:227], v[206:209], v[162:165]
	global_load_dwordx4 v[4:7], v[122:123], off offset:1664
	v_mfma_f32_16x16x32_f16 v[72:75], v[232:235], v[206:209], v[72:75]
	ds_read_b128 v[206:209], v133 offset:18432
	v_mfma_f32_16x16x32_f16 v[194:197], v[224:227], v[220:223], v[194:197]
	v_mfma_f32_16x16x32_f16 v[84:87], v[224:227], v[228:231], v[84:87]
	ds_read_b128 v[224:227], v136 offset:53248
	v_mfma_f32_16x16x32_f16 v[80:83], v[232:235], v[220:223], v[80:83]
	ds_read_b128 v[220:223], v133 offset:20480
	v_mfma_f32_16x16x32_f16 v[88:91], v[232:235], v[228:231], v[88:91]
	ds_read_b128 v[228:231], v133 offset:22528
	s_waitcnt lgkmcnt(5)
; #define GL_LOAD(s_, kt_) if (VAR != 1) { a##s_##0 = GL_A(0, kt_); a##s_##1 = GL_A(1, kt_); a##s_##2 = GL_A(2, kt_); a##s_##3 = GL_A(3, kt_); b##s_##0 = GL_B(0, kt_); b##s_##1 = GL_B(1, kt_); b##s_##2 = GL_B(2, kt_); b##s_##3 = GL_B(3, kt_); }
; #define LDS_STORE(s_, buf_) if (VAR != 2) { LDS_ST1(sA, 0, buf_, a##s_##0) LDS_ST1(sA, 1, buf_, a##s_##1) LDS_ST1(sA, 2, buf_, a##s_##2) LDS_ST1(sA, 3, buf_, a##s_##3) LDS_ST1(sB, 0, buf_, b##s_##0) LDS_ST1(sB, 1, buf_, b##s_##1) LDS_ST1(sB, 2, buf_, b##s_##2) LDS_ST1(sB, 3, buf_, b##s_##3) }
;     ...
;   GL_LOAD(0, 0)
;   GL_LOAD(1, 1)
;   LDS_STORE(0, 0)
;   if (VAR != 4) __syncthreads();
; #pragma unroll
;   for (int kt = 0; kt < nk; kt += 2) {
;     if (kt + 2 < nk) { GL_LOAD(0, kt + 2) }
;     MMA_TILE(0)
;     LDS_STORE(1, 1)
;     if (VAR != 4) __syncthreads();
;     if (kt + 3 < nk) { GL_LOAD(1, kt + 3) }
;     MMA_TILE(1)
;     if (kt + 2 < nk) { LDS_STORE(0, 0) }
;     if (VAR != 4) __syncthreads();
	v_mfma_f32_16x16x32_f16 v[138:141], v[202:205], v[198:201], v[138:141]
	ds_read_b128 v[232:235], v136 offset:55296
	s_waitcnt lgkmcnt(4)
	v_mfma_f32_16x16x32_f16 v[92:95], v[202:205], v[206:209], v[92:95]
	s_waitcnt vmcnt(15)
	ds_write_b128 v101, v[52:55]
	v_mfma_f32_16x16x32_f16 v[142:145], v[210:213], v[198:201], v[142:145]
	s_waitcnt vmcnt(14)
	ds_write_b128 v131, v[56:59]
	v_mfma_f32_16x16x32_f16 v[158:161], v[210:213], v[206:209], v[158:161]
	s_waitcnt vmcnt(13)
	ds_write_b128 v132, v[60:63]
	s_waitcnt lgkmcnt(5)
	v_mfma_f32_16x16x32_f16 v[166:169], v[202:205], v[220:223], v[166:169]
	s_waitcnt vmcnt(12)
	ds_write_b128 v130, v[40:43]
	s_waitcnt lgkmcnt(5)
	v_mfma_f32_16x16x32_f16 v[68:71], v[202:205], v[228:231], v[68:71]
	ds_read_b128 v[202:205], v135 offset:49152
	v_mfma_f32_16x16x32_f16 v[190:193], v[210:213], v[220:223], v[190:193]
	s_waitcnt vmcnt(11)
	ds_write_b128 v101, v[44:47] offset:32768
	v_mfma_f32_16x16x32_f16 v[76:79], v[210:213], v[228:231], v[76:79]
	ds_read_b128 v[210:213], v135 offset:51200
	v_mfma_f32_16x16x32_f16 v[154:157], v[224:227], v[198:201], v[154:157]
	s_waitcnt vmcnt(10)
	ds_write_b128 v131, v[48:51] offset:32768
	v_mfma_f32_16x16x32_f16 v[162:165], v[224:227], v[206:209], v[162:165]
	s_waitcnt vmcnt(9)
	ds_write_b128 v132, v[32:35] offset:32768
	s_waitcnt lgkmcnt(9)
	v_mfma_f32_16x16x32_f16 v[64:67], v[232:235], v[198:201], v[64:67]
	ds_read_b128 v[198:201], v134 offset:16384
	v_mfma_f32_16x16x32_f16 v[72:75], v[232:235], v[206:209], v[72:75]
	ds_read_b128 v[206:209], v134 offset:18432
	v_mfma_f32_16x16x32_f16 v[194:197], v[224:227], v[220:223], v[194:197]
	s_waitcnt vmcnt(8)
	ds_write_b128 v130, v[36:39] offset:32768
	v_mfma_f32_16x16x32_f16 v[84:87], v[224:227], v[228:231], v[84:87]
	ds_read_b128 v[224:227], v135 offset:53248
	v_mfma_f32_16x16x32_f16 v[80:83], v[232:235], v[220:223], v[80:83]
	ds_read_b128 v[220:223], v134 offset:20480
	v_mfma_f32_16x16x32_f16 v[88:91], v[232:235], v[228:231], v[88:91]
	ds_read_b128 v[228:231], v134 offset:22528
	ds_read_b128 v[232:235], v135 offset:55296
	s_waitcnt lgkmcnt(0)
	s_barrier
	v_mfma_f32_16x16x32_f16 v[138:141], v[202:205], v[198:201], v[138:141]
	global_load_dwordx4 v[60:63], v[108:109], off offset:1792
	v_mfma_f32_16x16x32_f16 v[92:95], v[202:205], v[206:209], v[92:95]
	global_load_dwordx4 v[48:51], v[110:111], off offset:1792
	v_mfma_f32_16x16x32_f16 v[142:145], v[210:213], v[198:201], v[142:145]
	global_load_dwordx4 v[52:55], v[112:113], off offset:1792
	v_mfma_f32_16x16x32_f16 v[158:161], v[210:213], v[206:209], v[158:161]
	global_load_dwordx4 v[56:59], v[114:115], off offset:1792
	v_mfma_f32_16x16x32_f16 v[166:169], v[202:205], v[220:223], v[166:169]
	global_load_dwordx4 v[36:39], v[116:117], off offset:1792
	v_mfma_f32_16x16x32_f16 v[68:71], v[202:205], v[228:231], v[68:71]
	ds_read_b128 v[202:205], v136 offset:32768
	v_mfma_f32_16x16x32_f16 v[190:193], v[210:213], v[220:223], v[190:193]
	global_load_dwordx4 v[40:43], v[118:119], off offset:1792
	v_mfma_f32_16x16x32_f16 v[76:79], v[210:213], v[228:231], v[76:79]
	ds_read_b128 v[210:213], v136 offset:34816
	v_mfma_f32_16x16x32_f16 v[154:157], v[224:227], v[198:201], v[154:157]
	global_load_dwordx4 v[44:47], v[120:121], off offset:1792
	v_mfma_f32_16x16x32_f16 v[162:165], v[224:227], v[206:209], v[162:165]
	global_load_dwordx4 v[32:35], v[122:123], off offset:1792
	v_mfma_f32_16x16x32_f16 v[64:67], v[232:235], v[198:201], v[64:67]
	ds_read_b128 v[198:201], v133
	v_mfma_f32_16x16x32_f16 v[72:75], v[232:235], v[206:209], v[72:75]
	ds_read_b128 v[206:209], v133 offset:2048
	v_mfma_f32_16x16x32_f16 v[194:197], v[224:227], v[220:223], v[194:197]
	v_mfma_f32_16x16x32_f16 v[84:87], v[224:227], v[228:231], v[84:87]
	ds_read_b128 v[224:227], v136 offset:36864
	v_mfma_f32_16x16x32_f16 v[80:83], v[232:235], v[220:223], v[80:83]
	ds_read_b128 v[220:223], v133 offset:4096
	v_mfma_f32_16x16x32_f16 v[88:91], v[232:235], v[228:231], v[88:91]
	ds_read_b128 v[228:231], v133 offset:6144
	s_waitcnt lgkmcnt(4)
	v_mfma_f32_16x16x32_f16 v[138:141], v[202:205], v[198:201], v[138:141]
	ds_read_b128 v[232:235], v136 offset:38912
	s_waitcnt lgkmcnt(4)
	v_mfma_f32_16x16x32_f16 v[92:95], v[202:205], v[206:209], v[92:95]
	s_waitcnt vmcnt(15)
	ds_write_b128 v101, v[20:23] offset:16384
	v_mfma_f32_16x16x32_f16 v[142:145], v[210:213], v[198:201], v[142:145]
	s_waitcnt vmcnt(14)
	ds_write_b128 v131, v[24:27] offset:16384
	v_mfma_f32_16x16x32_f16 v[158:161], v[210:213], v[206:209], v[158:161]
	s_waitcnt vmcnt(13)
	ds_write_b128 v132, v[28:31] offset:16384
	s_waitcnt lgkmcnt(5)
	v_mfma_f32_16x16x32_f16 v[166:169], v[202:205], v[220:223], v[166:169]
	s_waitcnt vmcnt(12)
	ds_write_b128 v130, v[8:11] offset:16384
	s_waitcnt lgkmcnt(5)
	v_mfma_f32_16x16x32_f16 v[68:71], v[202:205], v[228:231], v[68:71]
	ds_read_b128 v[202:205], v135 offset:32768
	v_mfma_f32_16x16x32_f16 v[190:193], v[210:213], v[220:223], v[190:193]
	s_waitcnt vmcnt(11)
	ds_write_b128 v101, v[12:15] offset:49152
	v_mfma_f32_16x16x32_f16 v[76:79], v[210:213], v[228:231], v[76:79]
	ds_read_b128 v[210:213], v135 offset:34816
	v_mfma_f32_16x16x32_f16 v[154:157], v[224:227], v[198:201], v[154:157]
	s_waitcnt vmcnt(10)
	ds_write_b128 v131, v[16:19] offset:49152
	v_mfma_f32_16x16x32_f16 v[162:165], v[224:227], v[206:209], v[162:165]
	s_waitcnt vmcnt(9)
	ds_write_b128 v132, v[0:3] offset:49152
	s_waitcnt lgkmcnt(9)
	v_mfma_f32_16x16x32_f16 v[64:67], v[232:235], v[198:201], v[64:67]
	ds_read_b128 v[198:201], v134
	v_mfma_f32_16x16x32_f16 v[72:75], v[232:235], v[206:209], v[72:75]
	ds_read_b128 v[206:209], v134 offset:2048
	v_mfma_f32_16x16x32_f16 v[194:197], v[224:227], v[220:223], v[194:197]
	s_waitcnt vmcnt(8)
	ds_write_b128 v130, v[4:7] offset:49152
	v_mfma_f32_16x16x32_f16 v[84:87], v[224:227], v[228:231], v[84:87]
	ds_read_b128 v[224:227], v135 offset:36864
	v_mfma_f32_16x16x32_f16 v[80:83], v[232:235], v[220:223], v[80:83]
	ds_read_b128 v[220:223], v134 offset:4096
	v_mfma_f32_16x16x32_f16 v[88:91], v[232:235], v[228:231], v[88:91]
	ds_read_b128 v[228:231], v134 offset:6144
	ds_read_b128 v[232:235], v135 offset:38912
	s_waitcnt lgkmcnt(0)
	s_barrier
; #define GL_LOAD(s_, kt_) if (VAR != 1) { a##s_##0 = GL_A(0, kt_); a##s_##1 = GL_A(1, kt_); a##s_##2 = GL_A(2, kt_); a##s_##3 = GL_A(3, kt_); b##s_##0 = GL_B(0, kt_); b##s_##1 = GL_B(1, kt_); b##s_##2 = GL_B(2, kt_); b##s_##3 = GL_B(3, kt_); }
; #define LDS_STORE(s_, buf_) if (VAR != 2) { LDS_ST1(sA, 0, buf_, a##s_##0) LDS_ST1(sA, 1, buf_, a##s_##1) LDS_ST1(sA, 2, buf_, a##s_##2) LDS_ST1(sA, 3, buf_, a##s_##3) LDS_ST1(sB, 0, buf_, b##s_##0) LDS_ST1(sB, 1, buf_, b##s_##1) LDS_ST1(sB, 2, buf_, b##s_##2) LDS_ST1(sB, 3, buf_, b##s_##3) }
;     ...
;   GL_LOAD(0, 0)
;   GL_LOAD(1, 1)
;   LDS_STORE(0, 0)
;   if (VAR != 4) __syncthreads();
; #pragma unroll
;   for (int kt = 0; kt < nk; kt += 2) {
;     if (kt + 2 < nk) { GL_LOAD(0, kt + 2) }
;     MMA_TILE(0)
;     LDS_STORE(1, 1)
;     if (VAR != 4) __syncthreads();
;     if (kt + 3 < nk) { GL_LOAD(1, kt + 3) }
;     MMA_TILE(1)
;     if (kt + 2 < nk) { LDS_STORE(0, 0) }
;     if (VAR != 4) __syncthreads();
	v_mfma_f32_16x16x32_f16 v[138:141], v[202:205], v[198:201], v[138:141]
	global_load_dwordx4 v[28:31], v[108:109], off offset:1920
	v_mfma_f32_16x16x32_f16 v[92:95], v[202:205], v[206:209], v[92:95]
	global_load_dwordx4 v[16:19], v[110:111], off offset:1920
	v_mfma_f32_16x16x32_f16 v[142:145], v[210:213], v[198:201], v[142:145]
	ds_read_b128 v[108:111], v133 offset:16384
	v_mfma_f32_16x16x32_f16 v[158:161], v[210:213], v[206:209], v[158:161]
	global_load_dwordx4 v[20:23], v[112:113], off offset:1920
	v_mfma_f32_16x16x32_f16 v[166:169], v[202:205], v[220:223], v[166:169]
	global_load_dwordx4 v[24:27], v[114:115], off offset:1920
	v_mfma_f32_16x16x32_f16 v[68:71], v[202:205], v[228:231], v[68:71]
	ds_read_b128 v[112:115], v136 offset:49152
	v_mfma_f32_16x16x32_f16 v[190:193], v[210:213], v[220:223], v[190:193]
	ds_read_b128 v[202:205], v136 offset:53248
	v_mfma_f32_16x16x32_f16 v[76:79], v[210:213], v[228:231], v[76:79]
	ds_read_b128 v[210:213], v136 offset:55296
	v_mfma_f32_16x16x32_f16 v[154:157], v[224:227], v[198:201], v[154:157]
	global_load_dwordx4 v[4:7], v[116:117], off offset:1920
	v_mfma_f32_16x16x32_f16 v[162:165], v[224:227], v[206:209], v[162:165]
	global_load_dwordx4 v[8:11], v[118:119], off offset:1920
	v_mfma_f32_16x16x32_f16 v[64:67], v[232:235], v[198:201], v[64:67]
	ds_read_b128 v[116:119], v133 offset:18432
	v_mfma_f32_16x16x32_f16 v[72:75], v[232:235], v[206:209], v[72:75]
	ds_read_b128 v[198:201], v133 offset:20480
	v_mfma_f32_16x16x32_f16 v[194:197], v[224:227], v[220:223], v[194:197]
	ds_read_b128 v[206:209], v133 offset:22528
	v_mfma_f32_16x16x32_f16 v[84:87], v[224:227], v[228:231], v[84:87]
	global_load_dwordx4 v[12:15], v[120:121], off offset:1920
	v_mfma_f32_16x16x32_f16 v[80:83], v[232:235], v[220:223], v[80:83]
	global_load_dwordx4 v[0:3], v[122:123], off offset:1920
	v_mfma_f32_16x16x32_f16 v[88:91], v[232:235], v[228:231], v[88:91]
	ds_read_b128 v[120:123], v136 offset:51200
	s_waitcnt lgkmcnt(6)
	v_mfma_f32_16x16x32_f16 v[138:141], v[112:115], v[108:111], v[138:141]
	s_waitcnt vmcnt(15)
	ds_write_b128 v101, v[60:63]
	s_waitcnt lgkmcnt(4)
	v_mfma_f32_16x16x32_f16 v[92:95], v[112:115], v[116:119], v[92:95]
	s_waitcnt vmcnt(14)
	ds_write_b128 v131, v[48:51]
	s_waitcnt lgkmcnt(2)
	v_mfma_f32_16x16x32_f16 v[142:145], v[120:123], v[108:111], v[142:145]
	s_waitcnt vmcnt(13)
	ds_write_b128 v132, v[52:55]
	v_mfma_f32_16x16x32_f16 v[154:157], v[202:205], v[108:111], v[154:157]
	v_mfma_f32_16x16x32_f16 v[64:67], v[210:213], v[108:111], v[64:67]
	v_mfma_f32_16x16x32_f16 v[108:111], v[120:123], v[116:119], v[158:161]
	s_waitcnt vmcnt(12)
	ds_write_b128 v130, v[56:59]
	v_mfma_f32_16x16x32_f16 v[158:161], v[202:205], v[116:119], v[162:165]
	v_mfma_f32_16x16x32_f16 v[72:75], v[210:213], v[116:119], v[72:75]
	v_mfma_f32_16x16x32_f16 v[116:119], v[112:115], v[198:201], v[166:169]
	s_waitcnt vmcnt(11)
	ds_write_b128 v101, v[36:39] offset:32768
	s_waitcnt vmcnt(10)
	ds_write_b128 v131, v[40:43] offset:32768
	v_mfma_f32_16x16x32_f16 v[68:71], v[112:115], v[206:209], v[68:71]
	ds_read_b128 v[112:115], v134 offset:16384
	s_waitcnt vmcnt(9)
	ds_write_b128 v132, v[44:47] offset:32768
	v_mfma_f32_16x16x32_f16 v[162:165], v[120:123], v[198:201], v[190:193]
	s_nop 2
	ds_read_b128 v[190:193], v134 offset:18432
	v_mfma_f32_16x16x32_f16 v[76:79], v[120:123], v[206:209], v[76:79]
	ds_read_b128 v[120:123], v135 offset:49152
	s_waitcnt vmcnt(8)
	ds_write_b128 v130, v[32:35] offset:32768
	v_mfma_f32_16x16x32_f16 v[166:169], v[202:205], v[198:201], v[194:197]
	s_nop 2
	ds_read_b128 v[194:197], v135 offset:51200
	v_mfma_f32_16x16x32_f16 v[84:87], v[202:205], v[206:209], v[84:87]
	ds_read_b128 v[202:205], v135 offset:53248
	v_mfma_f32_16x16x32_f16 v[80:83], v[210:213], v[198:201], v[80:83]
	ds_read_b128 v[198:201], v134 offset:20480
	v_mfma_f32_16x16x32_f16 v[88:91], v[210:213], v[206:209], v[88:91]
	ds_read_b128 v[206:209], v134 offset:22528
	s_waitcnt lgkmcnt(5)
	v_mfma_f32_16x16x32_f16 v[138:141], v[120:123], v[112:115], v[138:141]
	ds_read_b128 v[210:213], v135 offset:55296
	s_waitcnt lgkmcnt(0)
	s_barrier
	ds_read_b128 v[32:35], v133
	ds_read_b128 v[36:39], v136 offset:32768
	ds_read_b128 v[40:43], v133 offset:2048
	ds_read_b128 v[44:47], v136 offset:34816
	ds_read_b128 v[48:51], v133 offset:4096
	ds_read_b128 v[52:55], v136 offset:36864
	ds_read_b128 v[56:59], v133 offset:6144
	ds_read_b128 v[60:63], v136 offset:38912
	v_mfma_f32_16x16x32_f16 v[142:145], v[194:197], v[112:115], v[142:145]
	v_mfma_f32_16x16x32_f16 v[154:157], v[202:205], v[112:115], v[154:157]
	v_mfma_f32_16x16x32_f16 v[64:67], v[210:213], v[112:115], v[64:67]
	v_mfma_f32_16x16x32_f16 v[92:95], v[120:123], v[190:193], v[92:95]
	v_mfma_f32_16x16x32_f16 v[108:111], v[194:197], v[190:193], v[108:111]
	v_mfma_f32_16x16x32_f16 v[112:115], v[202:205], v[190:193], v[158:161]
	v_mfma_f32_16x16x32_f16 v[72:75], v[210:213], v[190:193], v[72:75]
	v_mfma_f32_16x16x32_f16 v[116:119], v[120:123], v[198:201], v[116:119]
	v_mfma_f32_16x16x32_f16 v[158:161], v[194:197], v[198:201], v[162:165]
	v_mfma_f32_16x16x32_f16 v[162:165], v[202:205], v[198:201], v[166:169]
	v_mfma_f32_16x16x32_f16 v[80:83], v[210:213], v[198:201], v[80:83]
	v_mfma_f32_16x16x32_f16 v[68:71], v[120:123], v[206:209], v[68:71]
	v_mfma_f32_16x16x32_f16 v[76:79], v[194:197], v[206:209], v[76:79]
	v_mfma_f32_16x16x32_f16 v[84:87], v[202:205], v[206:209], v[84:87]
	v_mfma_f32_16x16x32_f16 v[88:91], v[210:213], v[206:209], v[88:91]
	s_waitcnt lgkmcnt(6)
	v_mfma_f32_16x16x32_f16 v[120:123], v[36:39], v[32:35], v[138:141]
	s_waitcnt lgkmcnt(4)
	v_mfma_f32_16x16x32_f16 v[138:141], v[44:47], v[32:35], v[142:145]
	s_waitcnt lgkmcnt(2)
; #define GL_LOAD(s_, kt_) if (VAR != 1) { a##s_##0 = GL_A(0, kt_); a##s_##1 = GL_A(1, kt_); a##s_##2 = GL_A(2, kt_); a##s_##3 = GL_A(3, kt_); b##s_##0 = GL_B(0, kt_); b##s_##1 = GL_B(1, kt_); b##s_##2 = GL_B(2, kt_); b##s_##3 = GL_B(3, kt_); }
; #define LDS_STORE(s_, buf_) if (VAR != 2) { LDS_ST1(sA, 0, buf_, a##s_##0) LDS_ST1(sA, 1, buf_, a##s_##1) LDS_ST1(sA, 2, buf_, a##s_##2) LDS_ST1(sA, 3, buf_, a##s_##3) LDS_ST1(sB, 0, buf_, b##s_##0) LDS_ST1(sB, 1, buf_, b##s_##1) LDS_ST1(sB, 2, buf_, b##s_##2) LDS_ST1(sB, 3, buf_, b##s_##3) }
;     ...
;   for (int kt = 0; kt < nk; kt += 2) {
;     if (kt + 2 < nk) { GL_LOAD(0, kt + 2) }
;     MMA_TILE(0)
;     LDS_STORE(1, 1)
;     if (VAR != 4) __syncthreads();
;     if (kt + 3 < nk) { GL_LOAD(1, kt + 3) }
;     MMA_TILE(1)
;     if (kt + 2 < nk) { LDS_STORE(0, 0) }
;     if (VAR != 4) __syncthreads();
	v_mfma_f32_16x16x32_f16 v[142:145], v[52:55], v[32:35], v[154:157]
	s_waitcnt lgkmcnt(0)
	v_mfma_f32_16x16x32_f16 v[32:35], v[60:63], v[32:35], v[64:67]
	v_mfma_f32_16x16x32_f16 v[64:67], v[36:39], v[40:43], v[92:95]
	v_mfma_f32_16x16x32_f16 v[92:95], v[44:47], v[40:43], v[108:111]
	v_mfma_f32_16x16x32_f16 v[108:111], v[52:55], v[40:43], v[112:115]
	v_mfma_f32_16x16x32_f16 v[40:43], v[60:63], v[40:43], v[72:75]
	v_mfma_f32_16x16x32_f16 v[72:75], v[36:39], v[48:51], v[116:119]
	v_mfma_f32_16x16x32_f16 v[112:115], v[44:47], v[48:51], v[158:161]
	v_mfma_f32_16x16x32_f16 v[116:119], v[52:55], v[48:51], v[162:165]
	v_mfma_f32_16x16x32_f16 v[48:51], v[60:63], v[48:51], v[80:83]
	v_mfma_f32_16x16x32_f16 v[36:39], v[36:39], v[56:59], v[68:71]
	v_mfma_f32_16x16x32_f16 v[44:47], v[44:47], v[56:59], v[76:79]
	v_mfma_f32_16x16x32_f16 v[52:55], v[52:55], v[56:59], v[84:87]
	v_mfma_f32_16x16x32_f16 v[56:59], v[60:63], v[56:59], v[88:91]
	ds_read_b128 v[60:63], v134
	ds_read_b128 v[68:71], v135 offset:32768
	ds_read_b128 v[76:79], v134 offset:2048
	ds_read_b128 v[80:83], v135 offset:34816
	ds_read_b128 v[84:87], v134 offset:4096
	ds_read_b128 v[88:91], v135 offset:36864
	ds_read_b128 v[154:157], v134 offset:6144
	ds_read_b128 v[158:161], v135 offset:38912
	s_waitcnt vmcnt(7)
	ds_write_b128 v101, v[28:31] offset:16384
	s_waitcnt vmcnt(6)
	ds_write_b128 v131, v[16:19] offset:16384
	s_waitcnt vmcnt(5)
	ds_write_b128 v132, v[20:23] offset:16384
	s_waitcnt vmcnt(4)
	ds_write_b128 v130, v[24:27] offset:16384
	s_waitcnt vmcnt(3)
	ds_write_b128 v101, v[4:7] offset:49152
	s_waitcnt vmcnt(2)
	ds_write_b128 v131, v[8:11] offset:49152
	s_waitcnt vmcnt(1)
	ds_write_b128 v132, v[12:15] offset:49152
	s_waitcnt vmcnt(0)
	ds_write_b128 v130, v[0:3] offset:49152
	s_waitcnt lgkmcnt(0)
	v_mfma_f32_16x16x32_f16 v[120:123], v[68:71], v[60:63], v[120:123]
	s_barrier
	ds_read_b128 v[0:3], v133 offset:16384
	ds_read_b128 v[4:7], v136 offset:49152
	ds_read_b128 v[8:11], v133 offset:18432
	ds_read_b128 v[12:15], v136 offset:51200
	ds_read_b128 v[16:19], v133 offset:20480
	ds_read_b128 v[20:23], v136 offset:53248
	ds_read_b128 v[24:27], v133 offset:22528
	ds_read_b128 v[28:31], v136 offset:55296
	v_mfma_f32_16x16x32_f16 v[138:141], v[80:83], v[60:63], v[138:141]
	v_ashrrev_i32_e32 v101, 31, v100
	v_mfma_f32_16x16x32_f16 v[142:145], v[88:91], v[60:63], v[142:145]
	v_mfma_f32_16x16x32_f16 v[32:35], v[158:161], v[60:63], v[32:35]
	v_mfma_f32_16x16x32_f16 v[60:63], v[68:71], v[76:79], v[64:67]
	v_mfma_f32_16x16x32_f16 v[64:67], v[80:83], v[76:79], v[92:95]
	v_mfma_f32_16x16x32_f16 v[92:95], v[88:91], v[76:79], v[108:111]
	v_mfma_f32_16x16x32_f16 v[40:43], v[158:161], v[76:79], v[40:43]
	v_mfma_f32_16x16x32_f16 v[72:75], v[68:71], v[84:87], v[72:75]
	v_mfma_f32_16x16x32_f16 v[76:79], v[80:83], v[84:87], v[112:115]
	v_mfma_f32_16x16x32_f16 v[108:111], v[88:91], v[84:87], v[116:119]
	v_mfma_f32_16x16x32_f16 v[48:51], v[158:161], v[84:87], v[48:51]
	v_mfma_f32_16x16x32_f16 v[44:47], v[80:83], v[154:157], v[44:47]
	v_mfma_f32_16x16x32_f16 v[52:55], v[88:91], v[154:157], v[52:55]
	v_mfma_f32_16x16x32_f16 v[56:59], v[158:161], v[154:157], v[56:59]
	v_mfma_f32_16x16x32_f16 v[36:39], v[68:71], v[154:157], v[36:39]
	s_waitcnt lgkmcnt(6)
	v_mfma_f32_16x16x32_f16 v[68:71], v[4:7], v[0:3], v[120:123]
	s_waitcnt lgkmcnt(4)
	v_mfma_f32_16x16x32_f16 v[80:83], v[12:15], v[0:3], v[138:141]
	s_waitcnt lgkmcnt(2)
	v_mfma_f32_16x16x32_f16 v[84:87], v[20:23], v[0:3], v[142:145]
	s_waitcnt lgkmcnt(0)
	v_mfma_f32_16x16x32_f16 v[0:3], v[28:31], v[0:3], v[32:35]
	v_mfma_f32_16x16x32_f16 v[32:35], v[4:7], v[8:11], v[60:63]
	v_mfma_f32_16x16x32_f16 v[60:63], v[12:15], v[8:11], v[64:67]
	v_mfma_f32_16x16x32_f16 v[64:67], v[20:23], v[8:11], v[92:95]
	v_mfma_f32_16x16x32_f16 v[72:75], v[4:7], v[16:19], v[72:75]
	v_mfma_f32_16x16x32_f16 v[76:79], v[12:15], v[16:19], v[76:79]
	v_mfma_f32_16x16x32_f16 v[88:91], v[20:23], v[16:19], v[108:111]
	v_mfma_f32_16x16x32_f16 v[16:19], v[28:31], v[16:19], v[48:51]
	v_mfma_f32_16x16x32_f16 v[44:47], v[12:15], v[24:27], v[44:47]
	v_mfma_f32_16x16x32_f16 v[48:51], v[20:23], v[24:27], v[52:55]
	v_mfma_f32_16x16x32_f16 v[52:55], v[28:31], v[24:27], v[56:59]
	ds_read_b128 v[12:15], v134 offset:16384
	s_nop 1
	ds_read_b128 v[56:59], v135 offset:49152
	ds_read_b128 v[20:23], v134 offset:18432
	ds_read_b128 v[92:95], v135 offset:51200
	ds_read_b128 v[108:111], v134 offset:20480
	ds_read_b128 v[112:115], v135 offset:53248
	ds_read_b128 v[116:119], v134 offset:22528
	ds_read_b128 v[120:123], v135 offset:55296
	s_waitcnt lgkmcnt(0)
	s_barrier
; DI unsigned pack2(float lo, float hi) { f2_t v = {lo, hi}; h2_t b = __builtin_convertvector(v, h2_t); return __builtin_bit_cast(unsigned, b); }
; #define GL_LOAD(s_, kt_) if (VAR != 1) { a##s_##0 = GL_A(0, kt_); a##s_##1 = GL_A(1, kt_); a##s_##2 = GL_A(2, kt_); a##s_##3 = GL_A(3, kt_); b##s_##0 = GL_B(0, kt_); b##s_##1 = GL_B(1, kt_); b##s_##2 = GL_B(2, kt_); b##s_##3 = GL_B(3, kt_); }
; #define LDS_STORE(s_, buf_) if (VAR != 2) { LDS_ST1(sA, 0, buf_, a##s_##0) LDS_ST1(sA, 1, buf_, a##s_##1) LDS_ST1(sA, 2, buf_, a##s_##2) LDS_ST1(sA, 3, buf_, a##s_##3) LDS_ST1(sB, 0, buf_, b##s_##0) LDS_ST1(sB, 1, buf_, b##s_##1) LDS_ST1(sB, 2, buf_, b##s_##2) LDS_ST1(sB, 3, buf_, b##s_##3) }
;     ...
;     MMA_TILE(0)
;     LDS_STORE(1, 1)
;     if (VAR != 4) __syncthreads();
;     if (kt + 3 < nk) { GL_LOAD(1, kt + 3) }
;     MMA_TILE(1)
; template <int VAR> DI void phase_up(const Params& P, int l, char* smem) {
;     ...
; #pragma unroll
;     for (int mt = 0; mt < 4; ++mt) {
;       const int row = row0 + mt * 16 + lr;
; #pragma unroll
;       for (int nt = 0; nt < 4; ++nt) {
;         float v[4];
; #pragma unroll
;         for (int j = 0; j < 4; ++j) { const float a = fmaxf(acc[mt][nt][j] * rs[mt], 0.f); v[j] = a * a; }
;         *(uint2*)(U + (size_t)row * DFF + col0 + nt * 16 + 4 * g) = make_uint2(pack2(v[0], v[1]), pack2(v[2], v[3]));
;       }
	v_mfma_f32_16x16x32_f16 v[4:7], v[4:7], v[24:27], v[36:39]
	v_mfma_f32_16x16x32_f16 v[68:71], v[56:59], v[12:15], v[68:71]
	v_mfma_f32_16x16x32_f16 v[8:11], v[28:31], v[8:11], v[40:43]
	v_mfma_f32_16x16x32_f16 v[80:83], v[92:95], v[12:15], v[80:83]
	v_mfma_f32_16x16x32_f16 v[84:87], v[112:115], v[12:15], v[84:87]
	v_mfma_f32_16x16x32_f16 v[130:133], v[120:123], v[12:15], v[0:3]
	v_mfma_f32_16x16x32_f16 v[12:15], v[56:59], v[116:119], v[4:7]
	v_mfma_f32_16x16x32_f16 v[4:7], v[112:115], v[116:119], v[48:51]
	s_nop 2
	v_mul_f32_e32 v48, v128, v68
	v_mul_f32_e32 v49, v128, v69
	v_mul_f32_e32 v50, v128, v70
	v_mul_f32_e32 v51, v128, v71
	v_max_f32_e32 v48, 0, v48
	v_max_f32_e32 v49, 0, v49
	v_max_f32_e32 v50, 0, v50
	v_max_f32_e32 v51, 0, v51
	v_mfma_f32_16x16x32_f16 v[134:137], v[56:59], v[20:23], v[32:35]
	v_mul_f32_e64 v48, v48, v48
	v_mul_f32_e64 v49, v49, v49
	v_pk_mul_f32 v[50:51], v[50:51], v[50:51]
	v_cvt_pk_f16_f32 v48, v48, v49
	v_mfma_f32_16x16x32_f16 v[32:35], v[120:123], v[20:23], v[8:11]
	v_cvt_pk_f16_f32 v49, v50, v51
	v_mul_f32_e32 v50, v128, v82
	v_mul_f32_e32 v51, v128, v83
	v_mfma_f32_16x16x32_f16 v[8:11], v[92:95], v[116:119], v[44:47]
	v_max_f32_e32 v50, 0, v50
	v_max_f32_e32 v51, 0, v51
	v_pk_mul_f32 v[50:51], v[50:51], v[50:51]
	v_lshl_add_u64 v[44:45], v[100:101], 1, v[96:97]
	v_lshlrev_b64 v[46:47], 13, v[102:103]
	v_lshl_add_u64 v[46:47], v[44:45], 0, v[46:47]
	global_store_dwordx2 v[46:47], v[48:49], off
	v_mul_f32_e32 v48, v128, v80
	v_mul_f32_e32 v49, v128, v81
	v_max_f32_e32 v48, 0, v48
	v_max_f32_e32 v49, 0, v49
	v_pk_mul_f32 v[48:49], v[48:49], v[48:49]
	v_mfma_f32_16x16x32_f16 v[16:19], v[120:123], v[108:111], v[16:19]
	v_cvt_pk_f16_f32 v48, v48, v49
	v_cvt_pk_f16_f32 v49, v50, v51
	global_store_dwordx2 v[46:47], v[48:49], off offset:32
	v_mul_f32_e32 v48, v128, v84
	v_mul_f32_e32 v49, v128, v85
	v_mul_f32_e32 v50, v128, v86
	v_mul_f32_e32 v51, v128, v87
	v_max_f32_e32 v48, 0, v48
	v_max_f32_e32 v49, 0, v49
	v_max_f32_e32 v50, 0, v50
	v_max_f32_e32 v51, 0, v51
	v_pk_mul_f32 v[48:49], v[48:49], v[48:49]
	v_pk_mul_f32 v[50:51], v[50:51], v[50:51]
	v_cvt_pk_f16_f32 v48, v48, v49
	v_cvt_pk_f16_f32 v49, v50, v51
	global_store_dwordx2 v[46:47], v[48:49], off offset:64
	v_mul_f32_e32 v48, v128, v130
	v_mul_f32_e32 v49, v128, v131
	v_mul_f32_e32 v50, v128, v132
	v_mul_f32_e32 v51, v128, v133
	v_max_f32_e32 v48, 0, v48
	v_max_f32_e32 v49, 0, v49
	v_max_f32_e32 v50, 0, v50
	v_max_f32_e32 v51, 0, v51
	v_mfma_f32_16x16x32_f16 v[40:43], v[92:95], v[20:23], v[60:63]
	v_mul_f32_e64 v48, v48, v48
	v_mul_f32_e64 v49, v49, v49
	v_pk_mul_f32 v[50:51], v[50:51], v[50:51]
	v_mul_f32_e32 v32, v126, v32
	v_mfma_f32_16x16x32_f16 v[36:39], v[112:115], v[20:23], v[64:67]
	v_mul_f32_e32 v33, v126, v33
	v_mul_f32_e32 v34, v126, v34
	v_mul_f32_e32 v35, v126, v35
	v_mfma_f32_16x16x32_f16 v[28:31], v[56:59], v[108:111], v[72:75]
	v_cvt_pk_f16_f32 v48, v48, v49
	v_cvt_pk_f16_f32 v49, v50, v51
	v_max_f32_e32 v32, 0, v32
	v_mfma_f32_16x16x32_f16 v[24:27], v[92:95], v[108:111], v[76:79]
	v_max_f32_e32 v33, 0, v33
	v_max_f32_e32 v34, 0, v34
	v_max_f32_e32 v35, 0, v35
	v_mfma_f32_16x16x32_f16 v[20:23], v[112:115], v[108:111], v[88:91]
	global_store_dwordx2 v[46:47], v[48:49], off offset:96
	v_lshlrev_b64 v[46:47], 13, v[98:99]
	v_pk_mul_f32 v[32:33], v[32:33], v[32:33]
	v_mfma_f32_16x16x32_f16 v[0:3], v[120:123], v[116:119], v[52:55]
	v_mul_f32_e64 v34, v34, v34
	v_mul_f32_e64 v35, v35, v35
	v_mul_f32_e32 v16, v129, v16
	v_mul_f32_e32 v17, v129, v17
	v_mul_f32_e32 v18, v129, v18
	v_mul_f32_e32 v19, v129, v19
	v_lshl_add_u64 v[46:47], v[44:45], 0, v[46:47]
	v_cvt_pk_f16_f32 v32, v32, v33
	v_cvt_pk_f16_f32 v33, v34, v35
	v_max_f32_e32 v16, 0, v16
	v_max_f32_e32 v17, 0, v17
	v_max_f32_e32 v18, 0, v18
	v_max_f32_e32 v19, 0, v19
	v_mul_f32_e32 v48, v126, v134
	v_mul_f32_e32 v49, v126, v135
	v_mul_f32_e32 v50, v126, v136
	v_mul_f32_e32 v51, v126, v137
	v_mul_f32_e32 v40, v126, v40
	v_mul_f32_e32 v41, v126, v41
	v_mul_f32_e32 v42, v126, v42
	v_mul_f32_e32 v43, v126, v43
	v_mul_f32_e32 v36, v126, v36
	v_mul_f32_e32 v37, v126, v37
	v_mul_f32_e32 v38, v126, v38
	v_mul_f32_e32 v39, v126, v39
	global_store_dwordx2 v[46:47], v[32:33], off offset:96
	v_lshlrev_b64 v[32:33], 13, v[106:107]
; DI unsigned pack2(float lo, float hi) { f2_t v = {lo, hi}; h2_t b = __builtin_convertvector(v, h2_t); return __builtin_bit_cast(unsigned, b); }
; template <int VAR> DI void phase_up(const Params& P, int l, char* smem) {
;     ...
; #pragma unroll
;     for (int mt = 0; mt < 4; ++mt) {
;       const int row = row0 + mt * 16 + lr;
; #pragma unroll
;       for (int nt = 0; nt < 4; ++nt) {
;         float v[4];
; #pragma unroll
;         for (int j = 0; j < 4; ++j) { const float a = fmaxf(acc[mt][nt][j] * rs[mt], 0.f); v[j] = a * a; }
;         *(uint2*)(U + (size_t)row * DFF + col0 + nt * 16 + 4 * g) = make_uint2(pack2(v[0], v[1]), pack2(v[2], v[3]));
;       }
	v_mul_f32_e32 v28, v129, v28
	v_mul_f32_e32 v29, v129, v29
	v_mul_f32_e32 v30, v129, v30
	v_mul_f32_e32 v31, v129, v31
	v_mul_f32_e32 v24, v129, v24
	v_mul_f32_e32 v25, v129, v25
	v_mul_f32_e32 v26, v129, v26
	v_mul_f32_e32 v27, v129, v27
	v_mul_f32_e32 v20, v129, v20
	v_mul_f32_e32 v21, v129, v21
	v_mul_f32_e32 v22, v129, v22
	v_mul_f32_e32 v23, v129, v23
	v_pk_mul_f32 v[16:17], v[16:17], v[16:17]
	v_pk_mul_f32 v[18:19], v[18:19], v[18:19]
	v_mul_f32_e32 v12, v127, v12
	v_mul_f32_e32 v13, v127, v13
	v_mul_f32_e32 v14, v127, v14
	v_mul_f32_e32 v15, v127, v15
	v_mul_f32_e32 v8, v127, v8
	v_mul_f32_e32 v9, v127, v9
	v_mul_f32_e32 v10, v127, v10
	v_mul_f32_e32 v11, v127, v11
	v_mul_f32_e32 v4, v127, v4
	v_mul_f32_e32 v5, v127, v5
	v_mul_f32_e32 v6, v127, v6
	v_mul_f32_e32 v7, v127, v7
	v_mul_f32_e32 v0, v127, v0
	v_mul_f32_e32 v1, v127, v1
	v_mul_f32_e32 v2, v127, v2
	v_mul_f32_e32 v3, v127, v3
	v_max_f32_e32 v48, 0, v48
	v_max_f32_e32 v49, 0, v49
	v_max_f32_e32 v50, 0, v50
	v_max_f32_e32 v51, 0, v51
	v_max_f32_e32 v40, 0, v40
	v_max_f32_e32 v41, 0, v41
	v_max_f32_e32 v42, 0, v42
	v_max_f32_e32 v43, 0, v43
	v_max_f32_e32 v36, 0, v36
	v_max_f32_e32 v37, 0, v37
	v_max_f32_e32 v38, 0, v38
	v_max_f32_e32 v39, 0, v39
	v_lshl_add_u64 v[32:33], v[44:45], 0, v[32:33]
	v_max_f32_e32 v28, 0, v28
	v_max_f32_e32 v29, 0, v29
	v_max_f32_e32 v30, 0, v30
	v_max_f32_e32 v31, 0, v31
	v_max_f32_e32 v24, 0, v24
	v_max_f32_e32 v25, 0, v25
	v_max_f32_e32 v26, 0, v26
	v_max_f32_e32 v27, 0, v27
	v_max_f32_e32 v20, 0, v20
	v_max_f32_e32 v21, 0, v21
	v_max_f32_e32 v22, 0, v22
	v_max_f32_e32 v23, 0, v23
	v_cvt_pk_f16_f32 v16, v16, v17
	v_cvt_pk_f16_f32 v17, v18, v19
	v_max_f32_e32 v12, 0, v12
	v_max_f32_e32 v13, 0, v13
	v_max_f32_e32 v14, 0, v14
	v_max_f32_e32 v15, 0, v15
	v_max_f32_e32 v8, 0, v8
	v_max_f32_e32 v9, 0, v9
	v_max_f32_e32 v10, 0, v10
	v_max_f32_e32 v11, 0, v11
	v_max_f32_e32 v4, 0, v4
	v_max_f32_e32 v5, 0, v5
	v_max_f32_e32 v6, 0, v6
	v_max_f32_e32 v7, 0, v7
	v_max_f32_e32 v0, 0, v0
	v_max_f32_e32 v1, 0, v1
	v_max_f32_e32 v2, 0, v2
	v_max_f32_e32 v3, 0, v3
	v_pk_mul_f32 v[48:49], v[48:49], v[48:49]
	v_pk_mul_f32 v[50:51], v[50:51], v[50:51]
	v_pk_mul_f32 v[40:41], v[40:41], v[40:41]
	v_pk_mul_f32 v[42:43], v[42:43], v[42:43]
	v_pk_mul_f32 v[36:37], v[36:37], v[36:37]
	v_pk_mul_f32 v[38:39], v[38:39], v[38:39]
	v_pk_mul_f32 v[28:29], v[28:29], v[28:29]
	v_pk_mul_f32 v[30:31], v[30:31], v[30:31]
	v_pk_mul_f32 v[24:25], v[24:25], v[24:25]
	v_pk_mul_f32 v[26:27], v[26:27], v[26:27]
	v_pk_mul_f32 v[20:21], v[20:21], v[20:21]
	v_pk_mul_f32 v[22:23], v[22:23], v[22:23]
	global_store_dwordx2 v[32:33], v[16:17], off offset:96
	v_lshlrev_b64 v[16:17], 13, v[104:105]
	v_pk_mul_f32 v[12:13], v[12:13], v[12:13]
	v_pk_mul_f32 v[14:15], v[14:15], v[14:15]
	v_pk_mul_f32 v[8:9], v[8:9], v[8:9]
	v_pk_mul_f32 v[10:11], v[10:11], v[10:11]
	v_pk_mul_f32 v[4:5], v[4:5], v[4:5]
	v_pk_mul_f32 v[6:7], v[6:7], v[6:7]
	v_pk_mul_f32 v[0:1], v[0:1], v[0:1]
	v_pk_mul_f32 v[2:3], v[2:3], v[2:3]
	v_cvt_pk_f16_f32 v48, v48, v49
	v_cvt_pk_f16_f32 v49, v50, v51
	v_cvt_pk_f16_f32 v40, v40, v41
	v_cvt_pk_f16_f32 v41, v42, v43
	v_cvt_pk_f16_f32 v36, v36, v37
	v_cvt_pk_f16_f32 v37, v38, v39
	v_cvt_pk_f16_f32 v28, v28, v29
	v_cvt_pk_f16_f32 v29, v30, v31
	v_cvt_pk_f16_f32 v24, v24, v25
	v_cvt_pk_f16_f32 v25, v26, v27
	v_cvt_pk_f16_f32 v20, v20, v21
	v_cvt_pk_f16_f32 v21, v22, v23
	v_lshl_add_u64 v[16:17], v[44:45], 0, v[16:17]
	v_cvt_pk_f16_f32 v12, v12, v13
	v_cvt_pk_f16_f32 v13, v14, v15
	v_cvt_pk_f16_f32 v8, v8, v9
	v_cvt_pk_f16_f32 v9, v10, v11
	v_cvt_pk_f16_f32 v4, v4, v5
	v_cvt_pk_f16_f32 v5, v6, v7
	v_cvt_pk_f16_f32 v0, v0, v1
	v_cvt_pk_f16_f32 v1, v2, v3
	global_store_dwordx2 v[46:47], v[48:49], off
	global_store_dwordx2 v[46:47], v[40:41], off offset:32
	global_store_dwordx2 v[46:47], v[36:37], off offset:64
	global_store_dwordx2 v[32:33], v[28:29], off
	global_store_dwordx2 v[32:33], v[24:25], off offset:32
	global_store_dwordx2 v[32:33], v[20:21], off offset:64
	global_store_dwordx2 v[16:17], v[12:13], off
	global_store_dwordx2 v[16:17], v[8:9], off offset:32
	global_store_dwordx2 v[16:17], v[4:5], off offset:64
	global_store_dwordx2 v[16:17], v[0:1], off offset:96
	s_branch .LBB0_1312

; #define GL_LOAD(s_, kt_) if (VAR != 1) { a##s_##0 = GL_A(0, kt_); a##s_##1 = GL_A(1, kt_); a##s_##2 = GL_A(2, kt_); a##s_##3 = GL_A(3, kt_); b##s_##0 = GL_B(0, kt_); b##s_##1 = GL_B(1, kt_); b##s_##2 = GL_B(2, kt_); b##s_##3 = GL_B(3, kt_); }
; #define LDS_STORE(s_, buf_) if (VAR != 2) { LDS_ST1(sA, 0, buf_, a##s_##0) LDS_ST1(sA, 1, buf_, a##s_##1) LDS_ST1(sA, 2, buf_, a##s_##2) LDS_ST1(sA, 3, buf_, a##s_##3) LDS_ST1(sB, 0, buf_, b##s_##0) LDS_ST1(sB, 1, buf_, b##s_##1) LDS_ST1(sB, 2, buf_, b##s_##2) LDS_ST1(sB, 3, buf_, b##s_##3) }
;     ...
;   GL_LOAD(0, 0)
;   GL_LOAD(1, 1)
;   LDS_STORE(0, 0)
;   if (VAR != 4) __syncthreads();
; #pragma unroll
;   for (int kt = 0; kt < nk; kt += 2) {
;     if (kt + 2 < nk) { GL_LOAD(0, kt + 2) }
;     MMA_TILE(0)
;     LDS_STORE(1, 1)
;     if (VAR != 4) __syncthreads();
;     if (kt + 3 < nk) { GL_LOAD(1, kt + 3) }
;     MMA_TILE(1)
;     if (kt + 2 < nk) { LDS_STORE(0, 0) }
;     if (VAR != 4) __syncthreads();
.LBB0_1371:
	s_ashr_i32 s1, s2, 3
	s_andn2_b32 s1, s1, 63
	s_and_b32 s4, s9, 56
	s_or_b32 s1, s1, s4
	s_bfe_u32 s4, s2, 0x30003
	s_or_b32 s1, s1, s4
	s_cmpk_gt_i32 s1, 0x7f
	s_cbranch_scc1 .LBB0_1370
	s_lshl_b32 s4, s1, 7
	s_ashr_i32 s5, s4, 31
	v_mov_b32_e32 v58, v148
	s_and_b32 s10, s8, 0x380
	s_lshl_b64 s[12:13], s[4:5], 13
	s_add_u32 s12, s34, s12
	v_ashrrev_i32_e32 v16, 3, v58
	v_ashrrev_i32_e32 v17, 31, v16
	v_add_u32_e32 v18, 32, v16
	s_addc_u32 s13, s35, s13
	v_lshlrev_b64 v[6:7], 13, v[16:17]
	v_lshlrev_b32_e32 v17, 4, v58
	v_ashrrev_i32_e32 v19, 31, v18
	v_add_u32_e32 v20, 64, v16
	s_waitcnt lgkmcnt(0)
	v_lshl_add_u64 v[0:1], s[12:13], 0, v[6:7]
	v_and_b32_e32 v150, 0x70, v17
	v_lshlrev_b64 v[8:9], 13, v[18:19]
	v_ashrrev_i32_e32 v21, 31, v20
	v_add_u32_e32 v54, 0x60, v16
	s_lshl_b32 s1, s10, 13
	v_lshl_add_u64 v[0:1], v[0:1], 0, v[150:151]
	v_lshl_add_u64 v[2:3], s[12:13], 0, v[8:9]
	v_lshlrev_b64 v[46:47], 13, v[20:21]
	v_ashrrev_i32_e32 v55, 31, v54
	s_add_u32 s14, s6, s1
	global_load_dwordx4 v[22:25], v[0:1], off
	v_lshl_add_u64 v[2:3], v[2:3], 0, v[150:151]
	v_lshl_add_u64 v[4:5], s[12:13], 0, v[46:47]
	v_lshlrev_b64 v[50:51], 13, v[54:55]
	s_addc_u32 s15, s7, 0
	global_load_dwordx4 v[26:29], v[2:3], off
	v_lshl_add_u64 v[4:5], v[4:5], 0, v[150:151]
	v_lshl_add_u64 v[10:11], s[12:13], 0, v[50:51]
	global_load_dwordx4 v[30:33], v[4:5], off
	v_lshl_add_u64 v[14:15], v[10:11], 0, v[150:151]
	v_lshl_add_u64 v[6:7], s[14:15], 0, v[6:7]
	global_load_dwordx4 v[34:37], v[14:15], off
	v_lshl_add_u64 v[10:11], v[6:7], 0, v[150:151]
	v_lshl_add_u64 v[6:7], s[14:15], 0, v[8:9]
	global_load_dwordx4 v[38:41], v[10:11], off
	v_lshl_add_u64 v[12:13], v[6:7], 0, v[150:151]
	v_lshl_add_u64 v[6:7], s[14:15], 0, v[46:47]
	global_load_dwordx4 v[42:45], v[12:13], off
	v_lshl_add_u64 v[8:9], v[6:7], 0, v[150:151]
	v_lshl_add_u64 v[6:7], s[14:15], 0, v[50:51]
	global_load_dwordx4 v[46:49], v[8:9], off
	v_lshl_add_u64 v[6:7], v[6:7], 0, v[150:151]
	global_load_dwordx4 v[50:53], v[6:7], off
	v_and_b32_e32 v19, 15, v58
	v_lshlrev_b32_e32 v21, 3, v58
	v_and_b32_e32 v55, 48, v58
	v_lshrrev_b32_e32 v59, 1, v58
	s_waitcnt vmcnt(10)
	v_lshlrev_b32_e32 v60, 7, v58
	v_and_b32_e32 v90, 0x70, v21
	v_bitop3_b32 v134, v21, v55, s23 bitop3:0x6c
	v_bitop3_b32 v21, v17, s23, v58 bitop3:0x48
	v_and_or_b32 v91, v59, s24, v19
	v_and_b32_e32 v130, 0x2780, v60
	global_load_dwordx4 v[58:61], v[0:1], off offset:128
	global_load_dwordx4 v[62:65], v[2:3], off offset:128
	global_load_dwordx4 v[66:69], v[4:5], off offset:128
	global_load_dwordx4 v[70:73], v[14:15], off offset:128
	global_load_dwordx4 v[74:77], v[10:11], off offset:128
	global_load_dwordx4 v[78:81], v[12:13], off offset:128
	global_load_dwordx4 v[82:85], v[8:9], off offset:128
	global_load_dwordx4 v[86:89], v[6:7], off offset:128
	v_lshl_or_b32 v17, v16, 7, v21
	v_or_b32_e32 v16, v130, v134
	v_lshl_or_b32 v18, v18, 7, v21
	v_lshl_or_b32 v19, v20, 7, v21
	v_lshl_or_b32 v20, v54, 7, v21
	v_lshlrev_b32_e32 v54, 7, v91
	v_bitop3_b32 v21, v54, v90, v55 bitop3:0xf6
	s_movk_i32 s1, 0x1000
	v_readlane_b32 s12, v254, 55
	v_readlane_b32 s13, v254, 56
	v_readlane_b32 s14, v254, 57
	v_readlane_b32 s15, v254, 58
	s_waitcnt vmcnt(15)
	ds_write_b128 v17, v[22:25]
	s_waitcnt vmcnt(14)
	ds_write_b128 v18, v[26:29]
	s_waitcnt vmcnt(13)
	ds_write_b128 v19, v[30:33]
	s_waitcnt vmcnt(12)
	ds_write_b128 v20, v[34:37]
	s_waitcnt vmcnt(11)
	ds_write_b128 v17, v[38:41] offset:32768
	s_waitcnt vmcnt(10)
	ds_write_b128 v18, v[42:45] offset:32768
	s_waitcnt vmcnt(9)
	ds_write_b128 v19, v[46:49] offset:32768
	s_waitcnt vmcnt(8)
	ds_write_b128 v20, v[50:53] offset:32768
	s_waitcnt lgkmcnt(0)
	s_barrier
	ds_read_b128 v[22:25], v16 offset:32768
	ds_read_b128 v[30:33], v21
	s_waitcnt lgkmcnt(0)
	v_mfma_f32_16x16x32_f16 v[38:41], v[22:25], v[30:33], 0
	ds_read_b128 v[26:29], v16 offset:34816
	ds_read_b128 v[34:37], v21 offset:2048
	s_waitcnt lgkmcnt(0)
	v_mfma_f32_16x16x32_f16 v[94:97], v[22:25], v[34:37], 0
	ds_read_b128 v[42:45], v16 offset:36864
	ds_read_b128 v[106:109], v21 offset:4096
	s_waitcnt lgkmcnt(0)
	v_mfma_f32_16x16x32_f16 v[114:117], v[22:25], v[106:109], 0
	ds_read_b128 v[50:53], v16 offset:38912
	ds_read_b128 v[110:113], v21 offset:6144
	s_waitcnt lgkmcnt(0)
	v_mfma_f32_16x16x32_f16 v[126:129], v[22:25], v[110:113], 0
	v_xor_b32_e32 v22, 64, v134
	v_mfma_f32_16x16x32_f16 v[46:49], v[26:29], v[30:33], 0
	v_or_b32_e32 v22, v130, v22
	v_mfma_f32_16x16x32_f16 v[90:93], v[42:45], v[30:33], 0
	ds_read_b128 v[130:133], v22 offset:32768
	v_mfma_f32_16x16x32_f16 v[30:33], v[50:53], v[30:33], 0
	ds_read_b128 v[142:145], v22 offset:36864
	v_mfma_f32_16x16x32_f16 v[98:101], v[26:29], v[34:37], 0
	ds_read_b128 v[154:157], v22 offset:38912
	v_mfma_f32_16x16x32_f16 v[102:105], v[42:45], v[34:37], 0
	v_bitop3_b32 v23, v54, v134, 64 bitop3:0xf6
	v_mfma_f32_16x16x32_f16 v[34:37], v[50:53], v[34:37], 0
	ds_read_b128 v[134:137], v23
	v_mfma_f32_16x16x32_f16 v[118:121], v[26:29], v[106:109], 0
	ds_read_b128 v[138:141], v23 offset:2048
	v_mfma_f32_16x16x32_f16 v[122:125], v[42:45], v[106:109], 0
	v_mfma_f32_16x16x32_f16 v[106:109], v[50:53], v[106:109], 0
	s_waitcnt vmcnt(7)
	ds_write_b128 v17, v[58:61] offset:16384
	v_mfma_f32_16x16x32_f16 v[24:27], v[26:29], v[110:113], 0
	s_waitcnt vmcnt(6)
	ds_write_b128 v18, v[62:65] offset:16384
	v_mfma_f32_16x16x32_f16 v[42:45], v[42:45], v[110:113], 0
	s_waitcnt vmcnt(5)
	ds_write_b128 v19, v[66:69] offset:16384
	v_mfma_f32_16x16x32_f16 v[50:53], v[50:53], v[110:113], 0
	ds_read_b128 v[110:113], v22 offset:34816
	s_waitcnt lgkmcnt(5)
	v_mfma_f32_16x16x32_f16 v[38:41], v[130:133], v[134:137], v[38:41]
	s_waitcnt vmcnt(4)
; #define GL_LOAD(s_, kt_) if (VAR != 1) { a##s_##0 = GL_A(0, kt_); a##s_##1 = GL_A(1, kt_); a##s_##2 = GL_A(2, kt_); a##s_##3 = GL_A(3, kt_); b##s_##0 = GL_B(0, kt_); b##s_##1 = GL_B(1, kt_); b##s_##2 = GL_B(2, kt_); b##s_##3 = GL_B(3, kt_); }
; #define LDS_STORE(s_, buf_) if (VAR != 2) { LDS_ST1(sA, 0, buf_, a##s_##0) LDS_ST1(sA, 1, buf_, a##s_##1) LDS_ST1(sA, 2, buf_, a##s_##2) LDS_ST1(sA, 3, buf_, a##s_##3) LDS_ST1(sB, 0, buf_, b##s_##0) LDS_ST1(sB, 1, buf_, b##s_##1) LDS_ST1(sB, 2, buf_, b##s_##2) LDS_ST1(sB, 3, buf_, b##s_##3) }
;     ...
;   GL_LOAD(0, 0)
;   GL_LOAD(1, 1)
;   LDS_STORE(0, 0)
;   if (VAR != 4) __syncthreads();
; #pragma unroll
;   for (int kt = 0; kt < nk; kt += 2) {
;     if (kt + 2 < nk) { GL_LOAD(0, kt + 2) }
;     MMA_TILE(0)
;     LDS_STORE(1, 1)
;     if (VAR != 4) __syncthreads();
;     if (kt + 3 < nk) { GL_LOAD(1, kt + 3) }
;     MMA_TILE(1)
;     if (kt + 2 < nk) { LDS_STORE(0, 0) }
;     if (VAR != 4) __syncthreads();
	ds_write_b128 v20, v[70:73] offset:16384
	v_mfma_f32_16x16x32_f16 v[90:93], v[142:145], v[134:137], v[90:93]
	s_waitcnt vmcnt(3)
	ds_write_b128 v17, v[74:77] offset:49152
	v_mfma_f32_16x16x32_f16 v[28:31], v[154:157], v[134:137], v[30:33]
	s_waitcnt vmcnt(2)
	ds_write_b128 v18, v[78:81] offset:49152
	s_waitcnt lgkmcnt(7)
	v_mfma_f32_16x16x32_f16 v[94:97], v[130:133], v[138:141], v[94:97]
	s_waitcnt vmcnt(1)
	ds_write_b128 v19, v[82:85] offset:49152
	v_mfma_f32_16x16x32_f16 v[102:105], v[142:145], v[138:141], v[102:105]
	s_waitcnt vmcnt(0)
	ds_write_b128 v20, v[86:89] offset:49152
	v_mfma_f32_16x16x32_f16 v[32:35], v[154:157], v[138:141], v[34:37]
	s_waitcnt lgkmcnt(5)
	v_mfma_f32_16x16x32_f16 v[46:49], v[110:113], v[134:137], v[46:49]
	ds_read_b128 v[134:137], v23 offset:4096
	v_mfma_f32_16x16x32_f16 v[98:101], v[110:113], v[138:141], v[98:101]
	ds_read_b128 v[138:141], v23 offset:6144
	s_waitcnt lgkmcnt(1)
	v_mfma_f32_16x16x32_f16 v[114:117], v[130:133], v[134:137], v[114:117]
	s_waitcnt lgkmcnt(0)
	v_mfma_f32_16x16x32_f16 v[126:129], v[130:133], v[138:141], v[126:129]
	global_load_dwordx4 v[130:133], v[0:1], off offset:256
	v_mfma_f32_16x16x32_f16 v[118:121], v[110:113], v[134:137], v[118:121]
	v_mfma_f32_16x16x32_f16 v[24:27], v[110:113], v[138:141], v[24:27]
	v_mfma_f32_16x16x32_f16 v[122:125], v[142:145], v[134:137], v[122:125]
	v_mfma_f32_16x16x32_f16 v[106:109], v[154:157], v[134:137], v[106:109]
	global_load_dwordx4 v[134:137], v[2:3], off offset:256
	global_load_dwordx4 v[158:161], v[4:5], off offset:256
	global_load_dwordx4 v[162:165], v[14:15], off offset:256
	global_load_dwordx4 v[110:113], v[10:11], off offset:256
	global_load_dwordx4 v[166:169], v[12:13], off offset:256
	global_load_dwordx4 v[190:193], v[8:9], off offset:256
	global_load_dwordx4 v[194:197], v[6:7], off offset:256
	s_waitcnt lgkmcnt(0)
	s_barrier
	v_mfma_f32_16x16x32_f16 v[42:45], v[142:145], v[138:141], v[42:45]
	ds_read_b128 v[58:61], v16 offset:49152
	v_mfma_f32_16x16x32_f16 v[50:53], v[154:157], v[138:141], v[50:53]
	ds_read_b128 v[62:65], v16 offset:51200
	ds_read_b128 v[66:69], v21 offset:16384
	s_waitcnt lgkmcnt(0)
	v_mfma_f32_16x16x32_f16 v[36:39], v[58:61], v[66:69], v[38:41]
	ds_read_b128 v[70:73], v21 offset:18432
	v_mfma_f32_16x16x32_f16 v[46:49], v[62:65], v[66:69], v[46:49]
	ds_read_b128 v[74:77], v16 offset:53248
	s_waitcnt lgkmcnt(0)
	v_mfma_f32_16x16x32_f16 v[82:85], v[74:77], v[66:69], v[90:93]
	ds_read_b128 v[78:81], v16 offset:55296
	s_waitcnt lgkmcnt(0)
	v_mfma_f32_16x16x32_f16 v[28:31], v[78:81], v[66:69], v[28:31]
	v_mfma_f32_16x16x32_f16 v[66:69], v[58:61], v[70:73], v[94:97]
	s_nop 2
	ds_read_b128 v[94:97], v21 offset:22528
	v_mfma_f32_16x16x32_f16 v[86:89], v[62:65], v[70:73], v[98:101]
	v_mfma_f32_16x16x32_f16 v[90:93], v[74:77], v[70:73], v[102:105]
	v_mfma_f32_16x16x32_f16 v[32:35], v[78:81], v[70:73], v[32:35]
	ds_read_b128 v[70:73], v21 offset:20480
	s_waitcnt lgkmcnt(0)
	v_mfma_f32_16x16x32_f16 v[98:101], v[58:61], v[70:73], v[114:117]
	v_mfma_f32_16x16x32_f16 v[58:61], v[58:61], v[94:97], v[126:129]
	v_mfma_f32_16x16x32_f16 v[102:105], v[62:65], v[70:73], v[118:121]
	s_nop 2
	ds_read_b128 v[118:121], v22 offset:55296
	v_mfma_f32_16x16x32_f16 v[24:27], v[62:65], v[94:97], v[24:27]
	ds_read_b128 v[62:65], v22 offset:49152
	s_waitcnt vmcnt(7)
	ds_write_b128 v17, v[130:133]
	v_mfma_f32_16x16x32_f16 v[114:117], v[74:77], v[70:73], v[122:125]
	s_waitcnt vmcnt(6)
	ds_write_b128 v18, v[134:137]
	s_waitcnt vmcnt(5)
	ds_write_b128 v19, v[158:161]
	v_mfma_f32_16x16x32_f16 v[40:43], v[74:77], v[94:97], v[42:45]
	ds_read_b128 v[74:77], v22 offset:51200
	v_mfma_f32_16x16x32_f16 v[70:73], v[78:81], v[70:73], v[106:109]
	s_nop 2
	ds_read_b128 v[106:109], v22 offset:53248
	v_mfma_f32_16x16x32_f16 v[50:53], v[78:81], v[94:97], v[50:53]
	ds_read_b128 v[78:81], v23 offset:16384
	s_waitcnt lgkmcnt(0)
	v_mfma_f32_16x16x32_f16 v[36:39], v[62:65], v[78:81], v[36:39]
	ds_read_b128 v[94:97], v23 offset:18432
	s_waitcnt lgkmcnt(0)
	v_mfma_f32_16x16x32_f16 v[66:69], v[62:65], v[94:97], v[66:69]
	s_waitcnt vmcnt(4)
	ds_write_b128 v20, v[162:165]
	v_mfma_f32_16x16x32_f16 v[44:47], v[74:77], v[78:81], v[46:49]
	s_waitcnt vmcnt(3)
	ds_write_b128 v17, v[110:113] offset:32768
	v_mfma_f32_16x16x32_f16 v[82:85], v[106:109], v[78:81], v[82:85]
	v_mfma_f32_16x16x32_f16 v[28:31], v[118:121], v[78:81], v[28:31]
	v_mfma_f32_16x16x32_f16 v[78:81], v[74:77], v[94:97], v[86:89]
	s_waitcnt vmcnt(2)
	ds_write_b128 v18, v[166:169] offset:32768
	s_waitcnt vmcnt(1)
	ds_write_b128 v19, v[190:193] offset:32768
	s_waitcnt vmcnt(0)
	ds_write_b128 v20, v[194:197] offset:32768
	v_mfma_f32_16x16x32_f16 v[86:89], v[106:109], v[94:97], v[90:93]
	s_nop 2
	ds_read_b128 v[90:93], v23 offset:20480
	v_mfma_f32_16x16x32_f16 v[32:35], v[118:121], v[94:97], v[32:35]
	ds_read_b128 v[94:97], v23 offset:22528
	s_waitcnt lgkmcnt(1)
	v_mfma_f32_16x16x32_f16 v[98:101], v[62:65], v[90:93], v[98:101]
	s_waitcnt lgkmcnt(0)
	v_mfma_f32_16x16x32_f16 v[58:61], v[62:65], v[94:97], v[58:61]
	global_load_dwordx4 v[62:65], v[0:1], off offset:384
	v_mfma_f32_16x16x32_f16 v[102:105], v[74:77], v[90:93], v[102:105]
	v_mfma_f32_16x16x32_f16 v[24:27], v[74:77], v[94:97], v[24:27]
	v_mfma_f32_16x16x32_f16 v[114:117], v[106:109], v[90:93], v[114:117]
	v_mfma_f32_16x16x32_f16 v[40:43], v[106:109], v[94:97], v[40:43]
	v_mfma_f32_16x16x32_f16 v[70:73], v[118:121], v[90:93], v[70:73]
	global_load_dwordx4 v[90:93], v[2:3], off offset:384
	global_load_dwordx4 v[122:125], v[4:5], off offset:384
	global_load_dwordx4 v[126:129], v[14:15], off offset:384
	global_load_dwordx4 v[74:77], v[10:11], off offset:384
	global_load_dwordx4 v[138:141], v[12:13], off offset:384
	global_load_dwordx4 v[142:145], v[8:9], off offset:384
	global_load_dwordx4 v[154:157], v[6:7], off offset:384
	s_waitcnt lgkmcnt(0)
	s_barrier
; #define GL_LOAD(s_, kt_) if (VAR != 1) { a##s_##0 = GL_A(0, kt_); a##s_##1 = GL_A(1, kt_); a##s_##2 = GL_A(2, kt_); a##s_##3 = GL_A(3, kt_); b##s_##0 = GL_B(0, kt_); b##s_##1 = GL_B(1, kt_); b##s_##2 = GL_B(2, kt_); b##s_##3 = GL_B(3, kt_); }
; #define LDS_STORE(s_, buf_) if (VAR != 2) { LDS_ST1(sA, 0, buf_, a##s_##0) LDS_ST1(sA, 1, buf_, a##s_##1) LDS_ST1(sA, 2, buf_, a##s_##2) LDS_ST1(sA, 3, buf_, a##s_##3) LDS_ST1(sB, 0, buf_, b##s_##0) LDS_ST1(sB, 1, buf_, b##s_##1) LDS_ST1(sB, 2, buf_, b##s_##2) LDS_ST1(sB, 3, buf_, b##s_##3) }
;     ...
;   GL_LOAD(0, 0)
;   GL_LOAD(1, 1)
;   LDS_STORE(0, 0)
;   if (VAR != 4) __syncthreads();
; #pragma unroll
;   for (int kt = 0; kt < nk; kt += 2) {
;     if (kt + 2 < nk) { GL_LOAD(0, kt + 2) }
;     MMA_TILE(0)
;     LDS_STORE(1, 1)
;     if (VAR != 4) __syncthreads();
;     if (kt + 3 < nk) { GL_LOAD(1, kt + 3) }
;     MMA_TILE(1)
;     if (kt + 2 < nk) { LDS_STORE(0, 0) }
;     if (VAR != 4) __syncthreads();
	v_mfma_f32_16x16x32_f16 v[48:51], v[118:121], v[94:97], v[50:53]
	ds_read_b128 v[106:109], v16 offset:32768
	ds_read_b128 v[94:97], v21
	s_waitcnt lgkmcnt(0)
	v_mfma_f32_16x16x32_f16 v[36:39], v[106:109], v[94:97], v[36:39]
	ds_read_b128 v[52:55], v16 offset:34816
	ds_read_b128 v[110:113], v21 offset:2048
	s_waitcnt lgkmcnt(0)
	v_mfma_f32_16x16x32_f16 v[66:69], v[106:109], v[110:113], v[66:69]
	ds_read_b128 v[118:121], v16 offset:36864
	v_mfma_f32_16x16x32_f16 v[44:47], v[52:55], v[94:97], v[44:47]
	ds_read_b128 v[130:133], v16 offset:38912
	v_mfma_f32_16x16x32_f16 v[78:81], v[52:55], v[110:113], v[78:81]
	s_waitcnt lgkmcnt(1)
	v_mfma_f32_16x16x32_f16 v[82:85], v[118:121], v[94:97], v[82:85]
	v_mfma_f32_16x16x32_f16 v[86:89], v[118:121], v[110:113], v[86:89]
	s_waitcnt lgkmcnt(0)
	v_mfma_f32_16x16x32_f16 v[28:31], v[130:133], v[94:97], v[28:31]
	ds_read_b128 v[94:97], v21 offset:4096
	v_mfma_f32_16x16x32_f16 v[32:35], v[130:133], v[110:113], v[32:35]
	ds_read_b128 v[110:113], v21 offset:6144
	s_waitcnt lgkmcnt(1)
	v_mfma_f32_16x16x32_f16 v[98:101], v[106:109], v[94:97], v[98:101]
	s_waitcnt lgkmcnt(0)
	v_mfma_f32_16x16x32_f16 v[58:61], v[106:109], v[110:113], v[58:61]
	ds_read_b128 v[106:109], v23
	v_mfma_f32_16x16x32_f16 v[102:105], v[52:55], v[94:97], v[102:105]
	v_mfma_f32_16x16x32_f16 v[24:27], v[52:55], v[110:113], v[24:27]
	ds_read_b128 v[52:55], v22 offset:32768
	v_mfma_f32_16x16x32_f16 v[114:117], v[118:121], v[94:97], v[114:117]
	s_waitcnt vmcnt(7)
	ds_write_b128 v17, v[62:65] offset:16384
	s_waitcnt vmcnt(6)
	ds_write_b128 v18, v[90:93] offset:16384
	v_mfma_f32_16x16x32_f16 v[40:43], v[118:121], v[110:113], v[40:43]
	ds_read_b128 v[118:121], v22 offset:36864
	s_waitcnt vmcnt(5)
	ds_write_b128 v19, v[122:125] offset:16384
	v_mfma_f32_16x16x32_f16 v[70:73], v[130:133], v[94:97], v[70:73]
	ds_read_b128 v[94:97], v22 offset:34816
	v_mfma_f32_16x16x32_f16 v[48:51], v[130:133], v[110:113], v[48:51]
	ds_read_b128 v[110:113], v23 offset:2048
	s_waitcnt lgkmcnt(6)
	v_mfma_f32_16x16x32_f16 v[36:39], v[52:55], v[106:109], v[36:39]
	ds_read_b128 v[130:133], v22 offset:38912
	s_waitcnt lgkmcnt(1)
	v_mfma_f32_16x16x32_f16 v[66:69], v[52:55], v[110:113], v[66:69]
	s_waitcnt vmcnt(4)
	ds_write_b128 v20, v[126:129] offset:16384
	v_mfma_f32_16x16x32_f16 v[44:47], v[94:97], v[106:109], v[44:47]
	s_waitcnt vmcnt(3)
	ds_write_b128 v17, v[74:77] offset:49152
	v_mfma_f32_16x16x32_f16 v[78:81], v[94:97], v[110:113], v[78:81]
	s_waitcnt vmcnt(2)
	ds_write_b128 v18, v[138:141] offset:49152
	v_mfma_f32_16x16x32_f16 v[82:85], v[118:121], v[106:109], v[82:85]
	s_waitcnt vmcnt(1)
	ds_write_b128 v19, v[142:145] offset:49152
	v_mfma_f32_16x16x32_f16 v[86:89], v[118:121], v[110:113], v[86:89]
	s_waitcnt vmcnt(0)
	ds_write_b128 v20, v[154:157] offset:49152
	s_waitcnt lgkmcnt(5)
	v_mfma_f32_16x16x32_f16 v[28:31], v[130:133], v[106:109], v[28:31]
	ds_read_b128 v[106:109], v23 offset:4096
	v_mfma_f32_16x16x32_f16 v[32:35], v[130:133], v[110:113], v[32:35]
	ds_read_b128 v[110:113], v23 offset:6144
	s_waitcnt lgkmcnt(1)
	v_mfma_f32_16x16x32_f16 v[98:101], v[52:55], v[106:109], v[98:101]
	s_waitcnt lgkmcnt(0)
	v_mfma_f32_16x16x32_f16 v[52:55], v[52:55], v[110:113], v[58:61]
	s_nop 2
	global_load_dwordx4 v[58:61], v[0:1], off offset:512
	v_mfma_f32_16x16x32_f16 v[102:105], v[94:97], v[106:109], v[102:105]
	v_mfma_f32_16x16x32_f16 v[24:27], v[94:97], v[110:113], v[24:27]
	v_mfma_f32_16x16x32_f16 v[114:117], v[118:121], v[106:109], v[114:117]
	v_mfma_f32_16x16x32_f16 v[40:43], v[118:121], v[110:113], v[40:43]
	v_mfma_f32_16x16x32_f16 v[70:73], v[130:133], v[106:109], v[70:73]
	global_load_dwordx4 v[106:109], v[2:3], off offset:512
	global_load_dwordx4 v[134:137], v[4:5], off offset:512
	global_load_dwordx4 v[158:161], v[14:15], off offset:512
	global_load_dwordx4 v[94:97], v[10:11], off offset:512
	global_load_dwordx4 v[162:165], v[12:13], off offset:512
	global_load_dwordx4 v[166:169], v[8:9], off offset:512
	global_load_dwordx4 v[190:193], v[6:7], off offset:512
	s_waitcnt lgkmcnt(0)
	s_barrier
	v_mfma_f32_16x16x32_f16 v[48:51], v[130:133], v[110:113], v[48:51]
	ds_read_b128 v[62:65], v16 offset:49152
	ds_read_b128 v[90:93], v21 offset:16384
	s_waitcnt lgkmcnt(0)
	v_mfma_f32_16x16x32_f16 v[36:39], v[62:65], v[90:93], v[36:39]
	ds_read_b128 v[74:77], v16 offset:51200
	ds_read_b128 v[110:113], v21 offset:18432
	s_waitcnt lgkmcnt(0)
	v_mfma_f32_16x16x32_f16 v[66:69], v[62:65], v[110:113], v[66:69]
	ds_read_b128 v[118:121], v16 offset:53248
	v_mfma_f32_16x16x32_f16 v[44:47], v[74:77], v[90:93], v[44:47]
	ds_read_b128 v[122:125], v16 offset:55296
	v_mfma_f32_16x16x32_f16 v[78:81], v[74:77], v[110:113], v[78:81]
	s_waitcnt lgkmcnt(1)
	v_mfma_f32_16x16x32_f16 v[82:85], v[118:121], v[90:93], v[82:85]
	v_mfma_f32_16x16x32_f16 v[86:89], v[118:121], v[110:113], v[86:89]
	s_waitcnt lgkmcnt(0)
	v_mfma_f32_16x16x32_f16 v[28:31], v[122:125], v[90:93], v[28:31]
	ds_read_b128 v[90:93], v21 offset:20480
	v_mfma_f32_16x16x32_f16 v[32:35], v[122:125], v[110:113], v[32:35]
	ds_read_b128 v[110:113], v21 offset:22528
	s_waitcnt lgkmcnt(1)
	v_mfma_f32_16x16x32_f16 v[98:101], v[62:65], v[90:93], v[98:101]
	s_waitcnt lgkmcnt(0)
	v_mfma_f32_16x16x32_f16 v[52:55], v[62:65], v[110:113], v[52:55]
	ds_read_b128 v[62:65], v22 offset:49152
	v_mfma_f32_16x16x32_f16 v[102:105], v[74:77], v[90:93], v[102:105]
	v_mfma_f32_16x16x32_f16 v[24:27], v[74:77], v[110:113], v[24:27]
	ds_read_b128 v[74:77], v22 offset:51200
	v_mfma_f32_16x16x32_f16 v[114:117], v[118:121], v[90:93], v[114:117]
	s_waitcnt vmcnt(7)
	ds_write_b128 v17, v[58:61]
	s_waitcnt vmcnt(6)
; #define GL_LOAD(s_, kt_) if (VAR != 1) { a##s_##0 = GL_A(0, kt_); a##s_##1 = GL_A(1, kt_); a##s_##2 = GL_A(2, kt_); a##s_##3 = GL_A(3, kt_); b##s_##0 = GL_B(0, kt_); b##s_##1 = GL_B(1, kt_); b##s_##2 = GL_B(2, kt_); b##s_##3 = GL_B(3, kt_); }
; #define LDS_STORE(s_, buf_) if (VAR != 2) { LDS_ST1(sA, 0, buf_, a##s_##0) LDS_ST1(sA, 1, buf_, a##s_##1) LDS_ST1(sA, 2, buf_, a##s_##2) LDS_ST1(sA, 3, buf_, a##s_##3) LDS_ST1(sB, 0, buf_, b##s_##0) LDS_ST1(sB, 1, buf_, b##s_##1) LDS_ST1(sB, 2, buf_, b##s_##2) LDS_ST1(sB, 3, buf_, b##s_##3) }
;     ...
;   GL_LOAD(0, 0)
;   GL_LOAD(1, 1)
;   LDS_STORE(0, 0)
;   if (VAR != 4) __syncthreads();
; #pragma unroll
;   for (int kt = 0; kt < nk; kt += 2) {
;     if (kt + 2 < nk) { GL_LOAD(0, kt + 2) }
;     MMA_TILE(0)
;     LDS_STORE(1, 1)
;     if (VAR != 4) __syncthreads();
;     if (kt + 3 < nk) { GL_LOAD(1, kt + 3) }
;     MMA_TILE(1)
;     if (kt + 2 < nk) { LDS_STORE(0, 0) }
;     if (VAR != 4) __syncthreads();
	ds_write_b128 v18, v[106:109]
	v_mfma_f32_16x16x32_f16 v[40:43], v[118:121], v[110:113], v[40:43]
	ds_read_b128 v[118:121], v22 offset:53248
	s_waitcnt vmcnt(5)
	ds_write_b128 v19, v[134:137]
	v_mfma_f32_16x16x32_f16 v[70:73], v[122:125], v[90:93], v[70:73]
	ds_read_b128 v[90:93], v23 offset:16384
	v_mfma_f32_16x16x32_f16 v[48:51], v[122:125], v[110:113], v[48:51]
	ds_read_b128 v[110:113], v23 offset:18432
	s_waitcnt lgkmcnt(1)
	v_mfma_f32_16x16x32_f16 v[36:39], v[62:65], v[90:93], v[36:39]
	ds_read_b128 v[122:125], v22 offset:55296
	s_waitcnt lgkmcnt(1)
	v_mfma_f32_16x16x32_f16 v[66:69], v[62:65], v[110:113], v[66:69]
	s_waitcnt vmcnt(4)
	ds_write_b128 v20, v[158:161]
	v_mfma_f32_16x16x32_f16 v[44:47], v[74:77], v[90:93], v[44:47]
	s_waitcnt vmcnt(3)
	ds_write_b128 v17, v[94:97] offset:32768
	v_mfma_f32_16x16x32_f16 v[78:81], v[74:77], v[110:113], v[78:81]
	s_waitcnt vmcnt(2)
	ds_write_b128 v18, v[162:165] offset:32768
	v_mfma_f32_16x16x32_f16 v[82:85], v[118:121], v[90:93], v[82:85]
	s_waitcnt vmcnt(1)
	ds_write_b128 v19, v[166:169] offset:32768
	v_mfma_f32_16x16x32_f16 v[86:89], v[118:121], v[110:113], v[86:89]
	s_waitcnt vmcnt(0)
	ds_write_b128 v20, v[190:193] offset:32768
	s_waitcnt lgkmcnt(5)
	v_mfma_f32_16x16x32_f16 v[28:31], v[122:125], v[90:93], v[28:31]
	ds_read_b128 v[90:93], v23 offset:20480
	v_mfma_f32_16x16x32_f16 v[32:35], v[122:125], v[110:113], v[32:35]
	ds_read_b128 v[110:113], v23 offset:22528
	s_waitcnt lgkmcnt(1)
	v_mfma_f32_16x16x32_f16 v[98:101], v[62:65], v[90:93], v[98:101]
	s_waitcnt lgkmcnt(0)
	v_mfma_f32_16x16x32_f16 v[52:55], v[62:65], v[110:113], v[52:55]
	global_load_dwordx4 v[62:65], v[0:1], off offset:640
	v_mfma_f32_16x16x32_f16 v[102:105], v[74:77], v[90:93], v[102:105]
	v_mfma_f32_16x16x32_f16 v[24:27], v[74:77], v[110:113], v[24:27]
	v_mfma_f32_16x16x32_f16 v[114:117], v[118:121], v[90:93], v[114:117]
	v_mfma_f32_16x16x32_f16 v[40:43], v[118:121], v[110:113], v[40:43]
	v_mfma_f32_16x16x32_f16 v[70:73], v[122:125], v[90:93], v[70:73]
	global_load_dwordx4 v[90:93], v[2:3], off offset:640
	global_load_dwordx4 v[126:129], v[4:5], off offset:640
	global_load_dwordx4 v[130:133], v[14:15], off offset:640
	global_load_dwordx4 v[74:77], v[10:11], off offset:640
	global_load_dwordx4 v[138:141], v[12:13], off offset:640
	global_load_dwordx4 v[142:145], v[8:9], off offset:640
	global_load_dwordx4 v[154:157], v[6:7], off offset:640
	s_waitcnt lgkmcnt(0)
	s_barrier
	v_mfma_f32_16x16x32_f16 v[48:51], v[122:125], v[110:113], v[48:51]
	ds_read_b128 v[58:61], v16 offset:32768
	ds_read_b128 v[106:109], v21
	s_waitcnt lgkmcnt(0)
	v_mfma_f32_16x16x32_f16 v[36:39], v[58:61], v[106:109], v[36:39]
	ds_read_b128 v[94:97], v16 offset:34816
	ds_read_b128 v[110:113], v21 offset:2048
	s_waitcnt lgkmcnt(0)
	v_mfma_f32_16x16x32_f16 v[66:69], v[58:61], v[110:113], v[66:69]
	ds_read_b128 v[118:121], v16 offset:36864
	v_mfma_f32_16x16x32_f16 v[44:47], v[94:97], v[106:109], v[44:47]
	ds_read_b128 v[122:125], v16 offset:38912
	v_mfma_f32_16x16x32_f16 v[78:81], v[94:97], v[110:113], v[78:81]
	s_waitcnt lgkmcnt(1)
	v_mfma_f32_16x16x32_f16 v[82:85], v[118:121], v[106:109], v[82:85]
	v_mfma_f32_16x16x32_f16 v[86:89], v[118:121], v[110:113], v[86:89]
	s_waitcnt lgkmcnt(0)
	v_mfma_f32_16x16x32_f16 v[28:31], v[122:125], v[106:109], v[28:31]
	ds_read_b128 v[106:109], v21 offset:4096
	v_mfma_f32_16x16x32_f16 v[32:35], v[122:125], v[110:113], v[32:35]
	ds_read_b128 v[110:113], v21 offset:6144
	s_waitcnt lgkmcnt(1)
	v_mfma_f32_16x16x32_f16 v[98:101], v[58:61], v[106:109], v[98:101]
	s_waitcnt lgkmcnt(0)
	v_mfma_f32_16x16x32_f16 v[52:55], v[58:61], v[110:113], v[52:55]
	ds_read_b128 v[58:61], v22 offset:32768
	v_mfma_f32_16x16x32_f16 v[102:105], v[94:97], v[106:109], v[102:105]
	v_mfma_f32_16x16x32_f16 v[24:27], v[94:97], v[110:113], v[24:27]
	ds_read_b128 v[94:97], v22 offset:34816
	v_mfma_f32_16x16x32_f16 v[114:117], v[118:121], v[106:109], v[114:117]
	s_waitcnt vmcnt(7)
	ds_write_b128 v17, v[62:65] offset:16384
	s_waitcnt vmcnt(6)
	ds_write_b128 v18, v[90:93] offset:16384
	v_mfma_f32_16x16x32_f16 v[40:43], v[118:121], v[110:113], v[40:43]
	ds_read_b128 v[118:121], v22 offset:36864
	s_waitcnt vmcnt(5)
	ds_write_b128 v19, v[126:129] offset:16384
	v_mfma_f32_16x16x32_f16 v[70:73], v[122:125], v[106:109], v[70:73]
	ds_read_b128 v[106:109], v23
	v_mfma_f32_16x16x32_f16 v[48:51], v[122:125], v[110:113], v[48:51]
	ds_read_b128 v[110:113], v23 offset:2048
	s_waitcnt lgkmcnt(1)
	v_mfma_f32_16x16x32_f16 v[36:39], v[58:61], v[106:109], v[36:39]
	ds_read_b128 v[122:125], v22 offset:38912
	s_waitcnt lgkmcnt(1)
	v_mfma_f32_16x16x32_f16 v[66:69], v[58:61], v[110:113], v[66:69]
	s_waitcnt vmcnt(4)
	ds_write_b128 v20, v[130:133] offset:16384
	v_mfma_f32_16x16x32_f16 v[44:47], v[94:97], v[106:109], v[44:47]
	s_waitcnt vmcnt(3)
	ds_write_b128 v17, v[74:77] offset:49152
	v_mfma_f32_16x16x32_f16 v[78:81], v[94:97], v[110:113], v[78:81]
	s_waitcnt vmcnt(2)
	ds_write_b128 v18, v[138:141] offset:49152
	v_mfma_f32_16x16x32_f16 v[82:85], v[118:121], v[106:109], v[82:85]
	s_waitcnt vmcnt(1)
	ds_write_b128 v19, v[142:145] offset:49152
	v_mfma_f32_16x16x32_f16 v[86:89], v[118:121], v[110:113], v[86:89]
	s_waitcnt vmcnt(0)
	ds_write_b128 v20, v[154:157] offset:49152
	s_waitcnt lgkmcnt(5)
	v_mfma_f32_16x16x32_f16 v[28:31], v[122:125], v[106:109], v[28:31]
	ds_read_b128 v[106:109], v23 offset:4096
	v_mfma_f32_16x16x32_f16 v[32:35], v[122:125], v[110:113], v[32:35]
	ds_read_b128 v[110:113], v23 offset:6144
	s_waitcnt lgkmcnt(1)
	v_mfma_f32_16x16x32_f16 v[98:101], v[58:61], v[106:109], v[98:101]
	s_waitcnt lgkmcnt(0)
	v_mfma_f32_16x16x32_f16 v[52:55], v[58:61], v[110:113], v[52:55]
	global_load_dwordx4 v[58:61], v[0:1], off offset:768
	v_mfma_f32_16x16x32_f16 v[102:105], v[94:97], v[106:109], v[102:105]
	v_mfma_f32_16x16x32_f16 v[24:27], v[94:97], v[110:113], v[24:27]
	v_mfma_f32_16x16x32_f16 v[114:117], v[118:121], v[106:109], v[114:117]
	v_mfma_f32_16x16x32_f16 v[40:43], v[118:121], v[110:113], v[40:43]
	v_mfma_f32_16x16x32_f16 v[70:73], v[122:125], v[106:109], v[70:73]
	global_load_dwordx4 v[106:109], v[2:3], off offset:768
	global_load_dwordx4 v[134:137], v[4:5], off offset:768
	global_load_dwordx4 v[158:161], v[14:15], off offset:768
	global_load_dwordx4 v[94:97], v[10:11], off offset:768
	global_load_dwordx4 v[162:165], v[12:13], off offset:768
	global_load_dwordx4 v[166:169], v[8:9], off offset:768
	global_load_dwordx4 v[190:193], v[6:7], off offset:768
	s_waitcnt lgkmcnt(0)
	s_barrier
; #define GL_LOAD(s_, kt_) if (VAR != 1) { a##s_##0 = GL_A(0, kt_); a##s_##1 = GL_A(1, kt_); a##s_##2 = GL_A(2, kt_); a##s_##3 = GL_A(3, kt_); b##s_##0 = GL_B(0, kt_); b##s_##1 = GL_B(1, kt_); b##s_##2 = GL_B(2, kt_); b##s_##3 = GL_B(3, kt_); }
; #define LDS_STORE(s_, buf_) if (VAR != 2) { LDS_ST1(sA, 0, buf_, a##s_##0) LDS_ST1(sA, 1, buf_, a##s_##1) LDS_ST1(sA, 2, buf_, a##s_##2) LDS_ST1(sA, 3, buf_, a##s_##3) LDS_ST1(sB, 0, buf_, b##s_##0) LDS_ST1(sB, 1, buf_, b##s_##1) LDS_ST1(sB, 2, buf_, b##s_##2) LDS_ST1(sB, 3, buf_, b##s_##3) }
;     ...
;   GL_LOAD(0, 0)
;   GL_LOAD(1, 1)
;   LDS_STORE(0, 0)
;   if (VAR != 4) __syncthreads();
; #pragma unroll
;   for (int kt = 0; kt < nk; kt += 2) {
;     if (kt + 2 < nk) { GL_LOAD(0, kt + 2) }
;     MMA_TILE(0)
;     LDS_STORE(1, 1)
;     if (VAR != 4) __syncthreads();
;     if (kt + 3 < nk) { GL_LOAD(1, kt + 3) }
;     MMA_TILE(1)
;     if (kt + 2 < nk) { LDS_STORE(0, 0) }
;     if (VAR != 4) __syncthreads();
	v_mfma_f32_16x16x32_f16 v[48:51], v[122:125], v[110:113], v[48:51]
	ds_read_b128 v[62:65], v16 offset:49152
	ds_read_b128 v[90:93], v21 offset:16384
	s_waitcnt lgkmcnt(0)
	v_mfma_f32_16x16x32_f16 v[36:39], v[62:65], v[90:93], v[36:39]
	ds_read_b128 v[74:77], v16 offset:51200
	ds_read_b128 v[110:113], v21 offset:18432
	s_waitcnt lgkmcnt(0)
	v_mfma_f32_16x16x32_f16 v[66:69], v[62:65], v[110:113], v[66:69]
	ds_read_b128 v[118:121], v16 offset:53248
	v_mfma_f32_16x16x32_f16 v[44:47], v[74:77], v[90:93], v[44:47]
	ds_read_b128 v[122:125], v16 offset:55296
	v_mfma_f32_16x16x32_f16 v[78:81], v[74:77], v[110:113], v[78:81]
	s_waitcnt lgkmcnt(1)
	v_mfma_f32_16x16x32_f16 v[82:85], v[118:121], v[90:93], v[82:85]
	v_mfma_f32_16x16x32_f16 v[86:89], v[118:121], v[110:113], v[86:89]
	s_waitcnt lgkmcnt(0)
	v_mfma_f32_16x16x32_f16 v[28:31], v[122:125], v[90:93], v[28:31]
	ds_read_b128 v[90:93], v21 offset:20480
	v_mfma_f32_16x16x32_f16 v[32:35], v[122:125], v[110:113], v[32:35]
	ds_read_b128 v[110:113], v21 offset:22528
	s_waitcnt lgkmcnt(1)
	v_mfma_f32_16x16x32_f16 v[98:101], v[62:65], v[90:93], v[98:101]
	s_waitcnt lgkmcnt(0)
	v_mfma_f32_16x16x32_f16 v[52:55], v[62:65], v[110:113], v[52:55]
	ds_read_b128 v[62:65], v22 offset:49152
	v_mfma_f32_16x16x32_f16 v[102:105], v[74:77], v[90:93], v[102:105]
	v_mfma_f32_16x16x32_f16 v[24:27], v[74:77], v[110:113], v[24:27]
	ds_read_b128 v[74:77], v22 offset:51200
	v_mfma_f32_16x16x32_f16 v[114:117], v[118:121], v[90:93], v[114:117]
	s_waitcnt vmcnt(7)
	ds_write_b128 v17, v[58:61]
	s_waitcnt vmcnt(6)
	ds_write_b128 v18, v[106:109]
	v_mfma_f32_16x16x32_f16 v[40:43], v[118:121], v[110:113], v[40:43]
	ds_read_b128 v[118:121], v22 offset:53248
	s_waitcnt vmcnt(5)
	ds_write_b128 v19, v[134:137]
	v_mfma_f32_16x16x32_f16 v[70:73], v[122:125], v[90:93], v[70:73]
	ds_read_b128 v[90:93], v23 offset:16384
	v_mfma_f32_16x16x32_f16 v[48:51], v[122:125], v[110:113], v[48:51]
	ds_read_b128 v[110:113], v23 offset:18432
	s_waitcnt lgkmcnt(1)
	v_mfma_f32_16x16x32_f16 v[36:39], v[62:65], v[90:93], v[36:39]
	ds_read_b128 v[122:125], v22 offset:55296
	s_waitcnt lgkmcnt(1)
	v_mfma_f32_16x16x32_f16 v[66:69], v[62:65], v[110:113], v[66:69]
	s_waitcnt vmcnt(4)
	ds_write_b128 v20, v[158:161]
	v_mfma_f32_16x16x32_f16 v[44:47], v[74:77], v[90:93], v[44:47]
	s_waitcnt vmcnt(3)
	ds_write_b128 v17, v[94:97] offset:32768
	v_mfma_f32_16x16x32_f16 v[78:81], v[74:77], v[110:113], v[78:81]
	s_waitcnt vmcnt(2)
	ds_write_b128 v18, v[162:165] offset:32768
	v_mfma_f32_16x16x32_f16 v[82:85], v[118:121], v[90:93], v[82:85]
	s_waitcnt vmcnt(1)
	ds_write_b128 v19, v[166:169] offset:32768
	v_mfma_f32_16x16x32_f16 v[86:89], v[118:121], v[110:113], v[86:89]
	s_waitcnt vmcnt(0)
	ds_write_b128 v20, v[190:193] offset:32768
	s_waitcnt lgkmcnt(5)
	v_mfma_f32_16x16x32_f16 v[28:31], v[122:125], v[90:93], v[28:31]
	ds_read_b128 v[90:93], v23 offset:20480
	v_mfma_f32_16x16x32_f16 v[32:35], v[122:125], v[110:113], v[32:35]
	ds_read_b128 v[110:113], v23 offset:22528
	s_waitcnt lgkmcnt(1)
	v_mfma_f32_16x16x32_f16 v[98:101], v[62:65], v[90:93], v[98:101]
	s_waitcnt lgkmcnt(0)
	v_mfma_f32_16x16x32_f16 v[52:55], v[62:65], v[110:113], v[52:55]
	global_load_dwordx4 v[62:65], v[0:1], off offset:896
	v_mfma_f32_16x16x32_f16 v[102:105], v[74:77], v[90:93], v[102:105]
	v_mfma_f32_16x16x32_f16 v[24:27], v[74:77], v[110:113], v[24:27]
	v_mfma_f32_16x16x32_f16 v[114:117], v[118:121], v[90:93], v[114:117]
	v_mfma_f32_16x16x32_f16 v[40:43], v[118:121], v[110:113], v[40:43]
	v_mfma_f32_16x16x32_f16 v[70:73], v[122:125], v[90:93], v[70:73]
	global_load_dwordx4 v[90:93], v[2:3], off offset:896
	global_load_dwordx4 v[126:129], v[4:5], off offset:896
	global_load_dwordx4 v[130:133], v[14:15], off offset:896
	global_load_dwordx4 v[74:77], v[10:11], off offset:896
	global_load_dwordx4 v[138:141], v[12:13], off offset:896
	global_load_dwordx4 v[142:145], v[8:9], off offset:896
	global_load_dwordx4 v[154:157], v[6:7], off offset:896
	s_waitcnt lgkmcnt(0)
	s_barrier
	v_mfma_f32_16x16x32_f16 v[48:51], v[122:125], v[110:113], v[48:51]
	ds_read_b128 v[58:61], v16 offset:32768
	ds_read_b128 v[106:109], v21
	s_waitcnt lgkmcnt(0)
	v_mfma_f32_16x16x32_f16 v[36:39], v[58:61], v[106:109], v[36:39]
	ds_read_b128 v[94:97], v16 offset:34816
	ds_read_b128 v[110:113], v21 offset:2048
	s_waitcnt lgkmcnt(0)
	v_mfma_f32_16x16x32_f16 v[66:69], v[58:61], v[110:113], v[66:69]
	ds_read_b128 v[118:121], v16 offset:36864
	v_mfma_f32_16x16x32_f16 v[44:47], v[94:97], v[106:109], v[44:47]
	ds_read_b128 v[122:125], v16 offset:38912
	v_mfma_f32_16x16x32_f16 v[78:81], v[94:97], v[110:113], v[78:81]
	s_waitcnt lgkmcnt(1)
	v_mfma_f32_16x16x32_f16 v[82:85], v[118:121], v[106:109], v[82:85]
	v_mfma_f32_16x16x32_f16 v[86:89], v[118:121], v[110:113], v[86:89]
	s_waitcnt lgkmcnt(0)
	v_mfma_f32_16x16x32_f16 v[28:31], v[122:125], v[106:109], v[28:31]
	ds_read_b128 v[106:109], v21 offset:4096
	v_mfma_f32_16x16x32_f16 v[32:35], v[122:125], v[110:113], v[32:35]
	ds_read_b128 v[110:113], v21 offset:6144
	s_waitcnt lgkmcnt(1)
	v_mfma_f32_16x16x32_f16 v[98:101], v[58:61], v[106:109], v[98:101]
	s_waitcnt lgkmcnt(0)
	v_mfma_f32_16x16x32_f16 v[52:55], v[58:61], v[110:113], v[52:55]
	ds_read_b128 v[58:61], v22 offset:32768
	v_mfma_f32_16x16x32_f16 v[102:105], v[94:97], v[106:109], v[102:105]
	v_mfma_f32_16x16x32_f16 v[24:27], v[94:97], v[110:113], v[24:27]
	ds_read_b128 v[94:97], v22 offset:34816
	v_mfma_f32_16x16x32_f16 v[114:117], v[118:121], v[106:109], v[114:117]
	s_waitcnt vmcnt(7)
	ds_write_b128 v17, v[62:65] offset:16384
	s_waitcnt vmcnt(6)
	ds_write_b128 v18, v[90:93] offset:16384
	v_mfma_f32_16x16x32_f16 v[40:43], v[118:121], v[110:113], v[40:43]
	ds_read_b128 v[118:121], v22 offset:36864
	s_waitcnt vmcnt(5)
; #define GL_LOAD(s_, kt_) if (VAR != 1) { a##s_##0 = GL_A(0, kt_); a##s_##1 = GL_A(1, kt_); a##s_##2 = GL_A(2, kt_); a##s_##3 = GL_A(3, kt_); b##s_##0 = GL_B(0, kt_); b##s_##1 = GL_B(1, kt_); b##s_##2 = GL_B(2, kt_); b##s_##3 = GL_B(3, kt_); }
; #define LDS_STORE(s_, buf_) if (VAR != 2) { LDS_ST1(sA, 0, buf_, a##s_##0) LDS_ST1(sA, 1, buf_, a##s_##1) LDS_ST1(sA, 2, buf_, a##s_##2) LDS_ST1(sA, 3, buf_, a##s_##3) LDS_ST1(sB, 0, buf_, b##s_##0) LDS_ST1(sB, 1, buf_, b##s_##1) LDS_ST1(sB, 2, buf_, b##s_##2) LDS_ST1(sB, 3, buf_, b##s_##3) }
;     ...
;   GL_LOAD(0, 0)
;   GL_LOAD(1, 1)
;   LDS_STORE(0, 0)
;   if (VAR != 4) __syncthreads();
; #pragma unroll
;   for (int kt = 0; kt < nk; kt += 2) {
;     if (kt + 2 < nk) { GL_LOAD(0, kt + 2) }
;     MMA_TILE(0)
;     LDS_STORE(1, 1)
;     if (VAR != 4) __syncthreads();
;     if (kt + 3 < nk) { GL_LOAD(1, kt + 3) }
;     MMA_TILE(1)
;     if (kt + 2 < nk) { LDS_STORE(0, 0) }
;     if (VAR != 4) __syncthreads();
	ds_write_b128 v19, v[126:129] offset:16384
	v_mfma_f32_16x16x32_f16 v[70:73], v[122:125], v[106:109], v[70:73]
	ds_read_b128 v[106:109], v23
	v_mfma_f32_16x16x32_f16 v[48:51], v[122:125], v[110:113], v[48:51]
	ds_read_b128 v[110:113], v23 offset:2048
	s_waitcnt lgkmcnt(1)
	v_mfma_f32_16x16x32_f16 v[36:39], v[58:61], v[106:109], v[36:39]
	ds_read_b128 v[122:125], v22 offset:38912
	s_waitcnt lgkmcnt(1)
	v_mfma_f32_16x16x32_f16 v[66:69], v[58:61], v[110:113], v[66:69]
	s_waitcnt vmcnt(4)
	ds_write_b128 v20, v[130:133] offset:16384
	v_mfma_f32_16x16x32_f16 v[44:47], v[94:97], v[106:109], v[44:47]
	s_waitcnt vmcnt(3)
	ds_write_b128 v17, v[74:77] offset:49152
	v_mfma_f32_16x16x32_f16 v[78:81], v[94:97], v[110:113], v[78:81]
	s_waitcnt vmcnt(2)
	ds_write_b128 v18, v[138:141] offset:49152
	v_mfma_f32_16x16x32_f16 v[82:85], v[118:121], v[106:109], v[82:85]
	s_waitcnt vmcnt(1)
	ds_write_b128 v19, v[142:145] offset:49152
	v_mfma_f32_16x16x32_f16 v[86:89], v[118:121], v[110:113], v[86:89]
	s_waitcnt vmcnt(0)
	ds_write_b128 v20, v[154:157] offset:49152
	s_waitcnt lgkmcnt(5)
	v_mfma_f32_16x16x32_f16 v[28:31], v[122:125], v[106:109], v[28:31]
	ds_read_b128 v[106:109], v23 offset:4096
	v_mfma_f32_16x16x32_f16 v[32:35], v[122:125], v[110:113], v[32:35]
	ds_read_b128 v[110:113], v23 offset:6144
	s_waitcnt lgkmcnt(1)
	v_mfma_f32_16x16x32_f16 v[98:101], v[58:61], v[106:109], v[98:101]
	s_waitcnt lgkmcnt(0)
	v_mfma_f32_16x16x32_f16 v[52:55], v[58:61], v[110:113], v[52:55]
	global_load_dwordx4 v[58:61], v[0:1], off offset:1024
	v_mfma_f32_16x16x32_f16 v[102:105], v[94:97], v[106:109], v[102:105]
	v_mfma_f32_16x16x32_f16 v[24:27], v[94:97], v[110:113], v[24:27]
	v_mfma_f32_16x16x32_f16 v[114:117], v[118:121], v[106:109], v[114:117]
	v_mfma_f32_16x16x32_f16 v[40:43], v[118:121], v[110:113], v[40:43]
	v_mfma_f32_16x16x32_f16 v[70:73], v[122:125], v[106:109], v[70:73]
	global_load_dwordx4 v[106:109], v[2:3], off offset:1024
	global_load_dwordx4 v[134:137], v[4:5], off offset:1024
	global_load_dwordx4 v[158:161], v[14:15], off offset:1024
	global_load_dwordx4 v[94:97], v[10:11], off offset:1024
	global_load_dwordx4 v[162:165], v[12:13], off offset:1024
	global_load_dwordx4 v[166:169], v[8:9], off offset:1024
	global_load_dwordx4 v[190:193], v[6:7], off offset:1024
	s_waitcnt lgkmcnt(0)
	s_barrier
	v_mfma_f32_16x16x32_f16 v[48:51], v[122:125], v[110:113], v[48:51]
	ds_read_b128 v[62:65], v16 offset:49152
	ds_read_b128 v[90:93], v21 offset:16384
	s_waitcnt lgkmcnt(0)
	v_mfma_f32_16x16x32_f16 v[36:39], v[62:65], v[90:93], v[36:39]
	ds_read_b128 v[74:77], v16 offset:51200
	ds_read_b128 v[110:113], v21 offset:18432
	s_waitcnt lgkmcnt(0)
	v_mfma_f32_16x16x32_f16 v[66:69], v[62:65], v[110:113], v[66:69]
	ds_read_b128 v[118:121], v16 offset:53248
	v_mfma_f32_16x16x32_f16 v[44:47], v[74:77], v[90:93], v[44:47]
	ds_read_b128 v[122:125], v16 offset:55296
	v_mfma_f32_16x16x32_f16 v[78:81], v[74:77], v[110:113], v[78:81]
	s_waitcnt lgkmcnt(1)
	v_mfma_f32_16x16x32_f16 v[82:85], v[118:121], v[90:93], v[82:85]
	v_mfma_f32_16x16x32_f16 v[86:89], v[118:121], v[110:113], v[86:89]
	s_waitcnt lgkmcnt(0)
	v_mfma_f32_16x16x32_f16 v[28:31], v[122:125], v[90:93], v[28:31]
	ds_read_b128 v[90:93], v21 offset:20480
	v_mfma_f32_16x16x32_f16 v[32:35], v[122:125], v[110:113], v[32:35]
	ds_read_b128 v[110:113], v21 offset:22528
	s_waitcnt lgkmcnt(1)
	v_mfma_f32_16x16x32_f16 v[98:101], v[62:65], v[90:93], v[98:101]
	s_waitcnt lgkmcnt(0)
	v_mfma_f32_16x16x32_f16 v[52:55], v[62:65], v[110:113], v[52:55]
	ds_read_b128 v[62:65], v22 offset:49152
	v_mfma_f32_16x16x32_f16 v[102:105], v[74:77], v[90:93], v[102:105]
	v_mfma_f32_16x16x32_f16 v[24:27], v[74:77], v[110:113], v[24:27]
	ds_read_b128 v[74:77], v22 offset:51200
	v_mfma_f32_16x16x32_f16 v[114:117], v[118:121], v[90:93], v[114:117]
	s_waitcnt vmcnt(7)
	ds_write_b128 v17, v[58:61]
	s_waitcnt vmcnt(6)
	ds_write_b128 v18, v[106:109]
	v_mfma_f32_16x16x32_f16 v[40:43], v[118:121], v[110:113], v[40:43]
	ds_read_b128 v[118:121], v22 offset:53248
	s_waitcnt vmcnt(5)
	ds_write_b128 v19, v[134:137]
	v_mfma_f32_16x16x32_f16 v[70:73], v[122:125], v[90:93], v[70:73]
	ds_read_b128 v[90:93], v23 offset:16384
	v_mfma_f32_16x16x32_f16 v[48:51], v[122:125], v[110:113], v[48:51]
	ds_read_b128 v[110:113], v23 offset:18432
	s_waitcnt lgkmcnt(1)
	v_mfma_f32_16x16x32_f16 v[36:39], v[62:65], v[90:93], v[36:39]
	ds_read_b128 v[122:125], v22 offset:55296
	s_waitcnt lgkmcnt(1)
	v_mfma_f32_16x16x32_f16 v[66:69], v[62:65], v[110:113], v[66:69]
	s_waitcnt vmcnt(4)
	ds_write_b128 v20, v[158:161]
	v_mfma_f32_16x16x32_f16 v[44:47], v[74:77], v[90:93], v[44:47]
	s_waitcnt vmcnt(3)
	ds_write_b128 v17, v[94:97] offset:32768
	v_mfma_f32_16x16x32_f16 v[78:81], v[74:77], v[110:113], v[78:81]
	s_waitcnt vmcnt(2)
	ds_write_b128 v18, v[162:165] offset:32768
	v_mfma_f32_16x16x32_f16 v[82:85], v[118:121], v[90:93], v[82:85]
	s_waitcnt vmcnt(1)
	ds_write_b128 v19, v[166:169] offset:32768
	v_mfma_f32_16x16x32_f16 v[86:89], v[118:121], v[110:113], v[86:89]
	s_waitcnt vmcnt(0)
	ds_write_b128 v20, v[190:193] offset:32768
	s_waitcnt lgkmcnt(5)
	v_mfma_f32_16x16x32_f16 v[28:31], v[122:125], v[90:93], v[28:31]
	ds_read_b128 v[90:93], v23 offset:20480
	v_mfma_f32_16x16x32_f16 v[32:35], v[122:125], v[110:113], v[32:35]
	ds_read_b128 v[110:113], v23 offset:22528
	s_waitcnt lgkmcnt(1)
	v_mfma_f32_16x16x32_f16 v[98:101], v[62:65], v[90:93], v[98:101]
	s_waitcnt lgkmcnt(0)
	v_mfma_f32_16x16x32_f16 v[52:55], v[62:65], v[110:113], v[52:55]
	global_load_dwordx4 v[62:65], v[0:1], off offset:1152
	v_mfma_f32_16x16x32_f16 v[102:105], v[74:77], v[90:93], v[102:105]
	v_mfma_f32_16x16x32_f16 v[24:27], v[74:77], v[110:113], v[24:27]
	v_mfma_f32_16x16x32_f16 v[114:117], v[118:121], v[90:93], v[114:117]
	v_mfma_f32_16x16x32_f16 v[40:43], v[118:121], v[110:113], v[40:43]
	v_mfma_f32_16x16x32_f16 v[70:73], v[122:125], v[90:93], v[70:73]
	global_load_dwordx4 v[90:93], v[2:3], off offset:1152
	global_load_dwordx4 v[126:129], v[4:5], off offset:1152
	global_load_dwordx4 v[130:133], v[14:15], off offset:1152
	global_load_dwordx4 v[74:77], v[10:11], off offset:1152
	global_load_dwordx4 v[138:141], v[12:13], off offset:1152
	global_load_dwordx4 v[142:145], v[8:9], off offset:1152
	global_load_dwordx4 v[154:157], v[6:7], off offset:1152
	s_waitcnt lgkmcnt(0)
	s_barrier
; #define GL_LOAD(s_, kt_) if (VAR != 1) { a##s_##0 = GL_A(0, kt_); a##s_##1 = GL_A(1, kt_); a##s_##2 = GL_A(2, kt_); a##s_##3 = GL_A(3, kt_); b##s_##0 = GL_B(0, kt_); b##s_##1 = GL_B(1, kt_); b##s_##2 = GL_B(2, kt_); b##s_##3 = GL_B(3, kt_); }
; #define LDS_STORE(s_, buf_) if (VAR != 2) { LDS_ST1(sA, 0, buf_, a##s_##0) LDS_ST1(sA, 1, buf_, a##s_##1) LDS_ST1(sA, 2, buf_, a##s_##2) LDS_ST1(sA, 3, buf_, a##s_##3) LDS_ST1(sB, 0, buf_, b##s_##0) LDS_ST1(sB, 1, buf_, b##s_##1) LDS_ST1(sB, 2, buf_, b##s_##2) LDS_ST1(sB, 3, buf_, b##s_##3) }
;     ...
;   GL_LOAD(0, 0)
;   GL_LOAD(1, 1)
;   LDS_STORE(0, 0)
;   if (VAR != 4) __syncthreads();
; #pragma unroll
;   for (int kt = 0; kt < nk; kt += 2) {
;     if (kt + 2 < nk) { GL_LOAD(0, kt + 2) }
;     MMA_TILE(0)
;     LDS_STORE(1, 1)
;     if (VAR != 4) __syncthreads();
;     if (kt + 3 < nk) { GL_LOAD(1, kt + 3) }
;     MMA_TILE(1)
;     if (kt + 2 < nk) { LDS_STORE(0, 0) }
;     if (VAR != 4) __syncthreads();
	v_mfma_f32_16x16x32_f16 v[48:51], v[122:125], v[110:113], v[48:51]
	ds_read_b128 v[58:61], v16 offset:32768
	ds_read_b128 v[106:109], v21
	s_waitcnt lgkmcnt(0)
	v_mfma_f32_16x16x32_f16 v[36:39], v[58:61], v[106:109], v[36:39]
	ds_read_b128 v[94:97], v16 offset:34816
	ds_read_b128 v[110:113], v21 offset:2048
	s_waitcnt lgkmcnt(0)
	v_mfma_f32_16x16x32_f16 v[66:69], v[58:61], v[110:113], v[66:69]
	ds_read_b128 v[118:121], v16 offset:36864
	v_mfma_f32_16x16x32_f16 v[44:47], v[94:97], v[106:109], v[44:47]
	ds_read_b128 v[122:125], v16 offset:38912
	v_mfma_f32_16x16x32_f16 v[78:81], v[94:97], v[110:113], v[78:81]
	s_waitcnt lgkmcnt(1)
	v_mfma_f32_16x16x32_f16 v[82:85], v[118:121], v[106:109], v[82:85]
	v_mfma_f32_16x16x32_f16 v[86:89], v[118:121], v[110:113], v[86:89]
	s_waitcnt lgkmcnt(0)
	v_mfma_f32_16x16x32_f16 v[28:31], v[122:125], v[106:109], v[28:31]
	ds_read_b128 v[106:109], v21 offset:4096
	v_mfma_f32_16x16x32_f16 v[32:35], v[122:125], v[110:113], v[32:35]
	ds_read_b128 v[110:113], v21 offset:6144
	s_waitcnt lgkmcnt(1)
	v_mfma_f32_16x16x32_f16 v[98:101], v[58:61], v[106:109], v[98:101]
	s_waitcnt lgkmcnt(0)
	v_mfma_f32_16x16x32_f16 v[52:55], v[58:61], v[110:113], v[52:55]
	ds_read_b128 v[58:61], v22 offset:32768
	v_mfma_f32_16x16x32_f16 v[102:105], v[94:97], v[106:109], v[102:105]
	v_mfma_f32_16x16x32_f16 v[24:27], v[94:97], v[110:113], v[24:27]
	ds_read_b128 v[94:97], v22 offset:34816
	v_mfma_f32_16x16x32_f16 v[114:117], v[118:121], v[106:109], v[114:117]
	s_waitcnt vmcnt(7)
	ds_write_b128 v17, v[62:65] offset:16384
	s_waitcnt vmcnt(6)
	ds_write_b128 v18, v[90:93] offset:16384
	v_mfma_f32_16x16x32_f16 v[40:43], v[118:121], v[110:113], v[40:43]
	ds_read_b128 v[118:121], v22 offset:36864
	s_waitcnt vmcnt(5)
	ds_write_b128 v19, v[126:129] offset:16384
	v_mfma_f32_16x16x32_f16 v[70:73], v[122:125], v[106:109], v[70:73]
	ds_read_b128 v[106:109], v23
	v_mfma_f32_16x16x32_f16 v[48:51], v[122:125], v[110:113], v[48:51]
	ds_read_b128 v[110:113], v23 offset:2048
	s_waitcnt lgkmcnt(1)
	v_mfma_f32_16x16x32_f16 v[36:39], v[58:61], v[106:109], v[36:39]
	ds_read_b128 v[122:125], v22 offset:38912
	s_waitcnt lgkmcnt(1)
	v_mfma_f32_16x16x32_f16 v[66:69], v[58:61], v[110:113], v[66:69]
	s_waitcnt vmcnt(4)
	ds_write_b128 v20, v[130:133] offset:16384
	v_mfma_f32_16x16x32_f16 v[44:47], v[94:97], v[106:109], v[44:47]
	s_waitcnt vmcnt(3)
	ds_write_b128 v17, v[74:77] offset:49152
	v_mfma_f32_16x16x32_f16 v[78:81], v[94:97], v[110:113], v[78:81]
	s_waitcnt vmcnt(2)
	ds_write_b128 v18, v[138:141] offset:49152
	v_mfma_f32_16x16x32_f16 v[82:85], v[118:121], v[106:109], v[82:85]
	s_waitcnt vmcnt(1)
	ds_write_b128 v19, v[142:145] offset:49152
	v_mfma_f32_16x16x32_f16 v[86:89], v[118:121], v[110:113], v[86:89]
	s_waitcnt vmcnt(0)
	ds_write_b128 v20, v[154:157] offset:49152
	s_waitcnt lgkmcnt(5)
	v_mfma_f32_16x16x32_f16 v[28:31], v[122:125], v[106:109], v[28:31]
	ds_read_b128 v[106:109], v23 offset:4096
	v_mfma_f32_16x16x32_f16 v[32:35], v[122:125], v[110:113], v[32:35]
	ds_read_b128 v[110:113], v23 offset:6144
	s_waitcnt lgkmcnt(1)
	v_mfma_f32_16x16x32_f16 v[98:101], v[58:61], v[106:109], v[98:101]
	s_waitcnt lgkmcnt(0)
	v_mfma_f32_16x16x32_f16 v[52:55], v[58:61], v[110:113], v[52:55]
	global_load_dwordx4 v[58:61], v[0:1], off offset:1280
	v_mfma_f32_16x16x32_f16 v[102:105], v[94:97], v[106:109], v[102:105]
	v_mfma_f32_16x16x32_f16 v[24:27], v[94:97], v[110:113], v[24:27]
	v_mfma_f32_16x16x32_f16 v[114:117], v[118:121], v[106:109], v[114:117]
	v_mfma_f32_16x16x32_f16 v[40:43], v[118:121], v[110:113], v[40:43]
	v_mfma_f32_16x16x32_f16 v[70:73], v[122:125], v[106:109], v[70:73]
	global_load_dwordx4 v[106:109], v[2:3], off offset:1280
	global_load_dwordx4 v[134:137], v[4:5], off offset:1280
	global_load_dwordx4 v[158:161], v[14:15], off offset:1280
	global_load_dwordx4 v[94:97], v[10:11], off offset:1280
	global_load_dwordx4 v[162:165], v[12:13], off offset:1280
	global_load_dwordx4 v[166:169], v[8:9], off offset:1280
	global_load_dwordx4 v[190:193], v[6:7], off offset:1280
	s_waitcnt lgkmcnt(0)
	s_barrier
	v_mfma_f32_16x16x32_f16 v[48:51], v[122:125], v[110:113], v[48:51]
	ds_read_b128 v[62:65], v16 offset:49152
	ds_read_b128 v[90:93], v21 offset:16384
	s_waitcnt lgkmcnt(0)
	v_mfma_f32_16x16x32_f16 v[36:39], v[62:65], v[90:93], v[36:39]
	ds_read_b128 v[74:77], v16 offset:51200
	ds_read_b128 v[110:113], v21 offset:18432
	s_waitcnt lgkmcnt(0)
	v_mfma_f32_16x16x32_f16 v[66:69], v[62:65], v[110:113], v[66:69]
	ds_read_b128 v[118:121], v16 offset:53248
	v_mfma_f32_16x16x32_f16 v[44:47], v[74:77], v[90:93], v[44:47]
	ds_read_b128 v[122:125], v16 offset:55296
	v_mfma_f32_16x16x32_f16 v[78:81], v[74:77], v[110:113], v[78:81]
	s_waitcnt lgkmcnt(1)
	v_mfma_f32_16x16x32_f16 v[82:85], v[118:121], v[90:93], v[82:85]
	v_mfma_f32_16x16x32_f16 v[86:89], v[118:121], v[110:113], v[86:89]
	s_waitcnt lgkmcnt(0)
	v_mfma_f32_16x16x32_f16 v[28:31], v[122:125], v[90:93], v[28:31]
	ds_read_b128 v[90:93], v21 offset:20480
	v_mfma_f32_16x16x32_f16 v[32:35], v[122:125], v[110:113], v[32:35]
	ds_read_b128 v[110:113], v21 offset:22528
	s_waitcnt lgkmcnt(1)
	v_mfma_f32_16x16x32_f16 v[98:101], v[62:65], v[90:93], v[98:101]
	s_waitcnt lgkmcnt(0)
	v_mfma_f32_16x16x32_f16 v[52:55], v[62:65], v[110:113], v[52:55]
	ds_read_b128 v[62:65], v22 offset:49152
	v_mfma_f32_16x16x32_f16 v[102:105], v[74:77], v[90:93], v[102:105]
	v_mfma_f32_16x16x32_f16 v[24:27], v[74:77], v[110:113], v[24:27]
	ds_read_b128 v[74:77], v22 offset:51200
	v_mfma_f32_16x16x32_f16 v[114:117], v[118:121], v[90:93], v[114:117]
	s_waitcnt vmcnt(7)
	ds_write_b128 v17, v[58:61]
	s_waitcnt vmcnt(6)
; #define GL_LOAD(s_, kt_) if (VAR != 1) { a##s_##0 = GL_A(0, kt_); a##s_##1 = GL_A(1, kt_); a##s_##2 = GL_A(2, kt_); a##s_##3 = GL_A(3, kt_); b##s_##0 = GL_B(0, kt_); b##s_##1 = GL_B(1, kt_); b##s_##2 = GL_B(2, kt_); b##s_##3 = GL_B(3, kt_); }
; #define LDS_STORE(s_, buf_) if (VAR != 2) { LDS_ST1(sA, 0, buf_, a##s_##0) LDS_ST1(sA, 1, buf_, a##s_##1) LDS_ST1(sA, 2, buf_, a##s_##2) LDS_ST1(sA, 3, buf_, a##s_##3) LDS_ST1(sB, 0, buf_, b##s_##0) LDS_ST1(sB, 1, buf_, b##s_##1) LDS_ST1(sB, 2, buf_, b##s_##2) LDS_ST1(sB, 3, buf_, b##s_##3) }
;     ...
;   GL_LOAD(0, 0)
;   GL_LOAD(1, 1)
;   LDS_STORE(0, 0)
;   if (VAR != 4) __syncthreads();
; #pragma unroll
;   for (int kt = 0; kt < nk; kt += 2) {
;     if (kt + 2 < nk) { GL_LOAD(0, kt + 2) }
;     MMA_TILE(0)
;     LDS_STORE(1, 1)
;     if (VAR != 4) __syncthreads();
;     if (kt + 3 < nk) { GL_LOAD(1, kt + 3) }
;     MMA_TILE(1)
;     if (kt + 2 < nk) { LDS_STORE(0, 0) }
;     if (VAR != 4) __syncthreads();
	ds_write_b128 v18, v[106:109]
	v_mfma_f32_16x16x32_f16 v[40:43], v[118:121], v[110:113], v[40:43]
	ds_read_b128 v[118:121], v22 offset:53248
	s_waitcnt vmcnt(5)
	ds_write_b128 v19, v[134:137]
	v_mfma_f32_16x16x32_f16 v[70:73], v[122:125], v[90:93], v[70:73]
	ds_read_b128 v[90:93], v23 offset:16384
	v_mfma_f32_16x16x32_f16 v[48:51], v[122:125], v[110:113], v[48:51]
	ds_read_b128 v[110:113], v23 offset:18432
	s_waitcnt lgkmcnt(1)
	v_mfma_f32_16x16x32_f16 v[36:39], v[62:65], v[90:93], v[36:39]
	ds_read_b128 v[122:125], v22 offset:55296
	s_waitcnt lgkmcnt(1)
	v_mfma_f32_16x16x32_f16 v[66:69], v[62:65], v[110:113], v[66:69]
	s_waitcnt vmcnt(4)
	ds_write_b128 v20, v[158:161]
	v_mfma_f32_16x16x32_f16 v[44:47], v[74:77], v[90:93], v[44:47]
	s_waitcnt vmcnt(3)
	ds_write_b128 v17, v[94:97] offset:32768
	v_mfma_f32_16x16x32_f16 v[78:81], v[74:77], v[110:113], v[78:81]
	s_waitcnt vmcnt(2)
	ds_write_b128 v18, v[162:165] offset:32768
	v_mfma_f32_16x16x32_f16 v[82:85], v[118:121], v[90:93], v[82:85]
	s_waitcnt vmcnt(1)
	ds_write_b128 v19, v[166:169] offset:32768
	v_mfma_f32_16x16x32_f16 v[86:89], v[118:121], v[110:113], v[86:89]
	s_waitcnt vmcnt(0)
	ds_write_b128 v20, v[190:193] offset:32768
	s_waitcnt lgkmcnt(5)
	v_mfma_f32_16x16x32_f16 v[28:31], v[122:125], v[90:93], v[28:31]
	ds_read_b128 v[90:93], v23 offset:20480
	v_mfma_f32_16x16x32_f16 v[32:35], v[122:125], v[110:113], v[32:35]
	ds_read_b128 v[110:113], v23 offset:22528
	s_waitcnt lgkmcnt(1)
	v_mfma_f32_16x16x32_f16 v[98:101], v[62:65], v[90:93], v[98:101]
	s_waitcnt lgkmcnt(0)
	v_mfma_f32_16x16x32_f16 v[52:55], v[62:65], v[110:113], v[52:55]
	global_load_dwordx4 v[62:65], v[0:1], off offset:1408
	v_mfma_f32_16x16x32_f16 v[102:105], v[74:77], v[90:93], v[102:105]
	v_mfma_f32_16x16x32_f16 v[24:27], v[74:77], v[110:113], v[24:27]
	v_mfma_f32_16x16x32_f16 v[114:117], v[118:121], v[90:93], v[114:117]
	v_mfma_f32_16x16x32_f16 v[40:43], v[118:121], v[110:113], v[40:43]
	v_mfma_f32_16x16x32_f16 v[70:73], v[122:125], v[90:93], v[70:73]
	global_load_dwordx4 v[90:93], v[2:3], off offset:1408
	global_load_dwordx4 v[126:129], v[4:5], off offset:1408
	global_load_dwordx4 v[130:133], v[14:15], off offset:1408
	global_load_dwordx4 v[74:77], v[10:11], off offset:1408
	global_load_dwordx4 v[138:141], v[12:13], off offset:1408
	global_load_dwordx4 v[142:145], v[8:9], off offset:1408
	global_load_dwordx4 v[154:157], v[6:7], off offset:1408
	s_waitcnt lgkmcnt(0)
	s_barrier
	v_mfma_f32_16x16x32_f16 v[48:51], v[122:125], v[110:113], v[48:51]
	ds_read_b128 v[58:61], v16 offset:32768
	ds_read_b128 v[106:109], v21
	s_waitcnt lgkmcnt(0)
	v_mfma_f32_16x16x32_f16 v[36:39], v[58:61], v[106:109], v[36:39]
	ds_read_b128 v[94:97], v16 offset:34816
	ds_read_b128 v[110:113], v21 offset:2048
	s_waitcnt lgkmcnt(0)
	v_mfma_f32_16x16x32_f16 v[66:69], v[58:61], v[110:113], v[66:69]
	ds_read_b128 v[118:121], v16 offset:36864
	v_mfma_f32_16x16x32_f16 v[44:47], v[94:97], v[106:109], v[44:47]
	ds_read_b128 v[122:125], v16 offset:38912
	v_mfma_f32_16x16x32_f16 v[78:81], v[94:97], v[110:113], v[78:81]
	s_waitcnt lgkmcnt(1)
	v_mfma_f32_16x16x32_f16 v[82:85], v[118:121], v[106:109], v[82:85]
	v_mfma_f32_16x16x32_f16 v[86:89], v[118:121], v[110:113], v[86:89]
	s_waitcnt lgkmcnt(0)
	v_mfma_f32_16x16x32_f16 v[28:31], v[122:125], v[106:109], v[28:31]
	ds_read_b128 v[106:109], v21 offset:4096
	v_mfma_f32_16x16x32_f16 v[32:35], v[122:125], v[110:113], v[32:35]
	ds_read_b128 v[110:113], v21 offset:6144
	s_waitcnt lgkmcnt(1)
	v_mfma_f32_16x16x32_f16 v[98:101], v[58:61], v[106:109], v[98:101]
	s_waitcnt lgkmcnt(0)
	v_mfma_f32_16x16x32_f16 v[52:55], v[58:61], v[110:113], v[52:55]
	ds_read_b128 v[58:61], v22 offset:32768
	v_mfma_f32_16x16x32_f16 v[102:105], v[94:97], v[106:109], v[102:105]
	v_mfma_f32_16x16x32_f16 v[24:27], v[94:97], v[110:113], v[24:27]
	ds_read_b128 v[94:97], v22 offset:34816
	v_mfma_f32_16x16x32_f16 v[114:117], v[118:121], v[106:109], v[114:117]
	s_waitcnt vmcnt(7)
	ds_write_b128 v17, v[62:65] offset:16384
	s_waitcnt vmcnt(6)
	ds_write_b128 v18, v[90:93] offset:16384
	v_mfma_f32_16x16x32_f16 v[40:43], v[118:121], v[110:113], v[40:43]
	ds_read_b128 v[118:121], v22 offset:36864
	s_waitcnt vmcnt(5)
	ds_write_b128 v19, v[126:129] offset:16384
	v_mfma_f32_16x16x32_f16 v[70:73], v[122:125], v[106:109], v[70:73]
	ds_read_b128 v[106:109], v23
	v_mfma_f32_16x16x32_f16 v[48:51], v[122:125], v[110:113], v[48:51]
	ds_read_b128 v[110:113], v23 offset:2048
	s_waitcnt lgkmcnt(1)
	v_mfma_f32_16x16x32_f16 v[36:39], v[58:61], v[106:109], v[36:39]
	ds_read_b128 v[122:125], v22 offset:38912
	s_waitcnt lgkmcnt(1)
	v_mfma_f32_16x16x32_f16 v[66:69], v[58:61], v[110:113], v[66:69]
	s_waitcnt vmcnt(4)
	ds_write_b128 v20, v[130:133] offset:16384
	v_mfma_f32_16x16x32_f16 v[44:47], v[94:97], v[106:109], v[44:47]
	s_waitcnt vmcnt(3)
	ds_write_b128 v17, v[74:77] offset:49152
	v_mfma_f32_16x16x32_f16 v[78:81], v[94:97], v[110:113], v[78:81]
	s_waitcnt vmcnt(2)
	ds_write_b128 v18, v[138:141] offset:49152
	v_mfma_f32_16x16x32_f16 v[82:85], v[118:121], v[106:109], v[82:85]
	s_waitcnt vmcnt(1)
	ds_write_b128 v19, v[142:145] offset:49152
	v_mfma_f32_16x16x32_f16 v[86:89], v[118:121], v[110:113], v[86:89]
	s_waitcnt vmcnt(0)
	ds_write_b128 v20, v[154:157] offset:49152
	s_waitcnt lgkmcnt(5)
	v_mfma_f32_16x16x32_f16 v[28:31], v[122:125], v[106:109], v[28:31]
	ds_read_b128 v[106:109], v23 offset:4096
	v_mfma_f32_16x16x32_f16 v[32:35], v[122:125], v[110:113], v[32:35]
	ds_read_b128 v[110:113], v23 offset:6144
	s_waitcnt lgkmcnt(1)
	v_mfma_f32_16x16x32_f16 v[98:101], v[58:61], v[106:109], v[98:101]
	s_waitcnt lgkmcnt(0)
	v_mfma_f32_16x16x32_f16 v[52:55], v[58:61], v[110:113], v[52:55]
	global_load_dwordx4 v[58:61], v[0:1], off offset:1536
	v_mfma_f32_16x16x32_f16 v[102:105], v[94:97], v[106:109], v[102:105]
	v_mfma_f32_16x16x32_f16 v[24:27], v[94:97], v[110:113], v[24:27]
	v_mfma_f32_16x16x32_f16 v[114:117], v[118:121], v[106:109], v[114:117]
	v_mfma_f32_16x16x32_f16 v[40:43], v[118:121], v[110:113], v[40:43]
	v_mfma_f32_16x16x32_f16 v[70:73], v[122:125], v[106:109], v[70:73]
	global_load_dwordx4 v[106:109], v[2:3], off offset:1536
	global_load_dwordx4 v[134:137], v[4:5], off offset:1536
	global_load_dwordx4 v[158:161], v[14:15], off offset:1536
	global_load_dwordx4 v[94:97], v[10:11], off offset:1536
	global_load_dwordx4 v[162:165], v[12:13], off offset:1536
	global_load_dwordx4 v[166:169], v[8:9], off offset:1536
	global_load_dwordx4 v[190:193], v[6:7], off offset:1536
	s_waitcnt lgkmcnt(0)
	s_barrier
; #define GL_LOAD(s_, kt_) if (VAR != 1) { a##s_##0 = GL_A(0, kt_); a##s_##1 = GL_A(1, kt_); a##s_##2 = GL_A(2, kt_); a##s_##3 = GL_A(3, kt_); b##s_##0 = GL_B(0, kt_); b##s_##1 = GL_B(1, kt_); b##s_##2 = GL_B(2, kt_); b##s_##3 = GL_B(3, kt_); }
; #define LDS_STORE(s_, buf_) if (VAR != 2) { LDS_ST1(sA, 0, buf_, a##s_##0) LDS_ST1(sA, 1, buf_, a##s_##1) LDS_ST1(sA, 2, buf_, a##s_##2) LDS_ST1(sA, 3, buf_, a##s_##3) LDS_ST1(sB, 0, buf_, b##s_##0) LDS_ST1(sB, 1, buf_, b##s_##1) LDS_ST1(sB, 2, buf_, b##s_##2) LDS_ST1(sB, 3, buf_, b##s_##3) }
;     ...
;   GL_LOAD(0, 0)
;   GL_LOAD(1, 1)
;   LDS_STORE(0, 0)
;   if (VAR != 4) __syncthreads();
; #pragma unroll
;   for (int kt = 0; kt < nk; kt += 2) {
;     if (kt + 2 < nk) { GL_LOAD(0, kt + 2) }
;     MMA_TILE(0)
;     LDS_STORE(1, 1)
;     if (VAR != 4) __syncthreads();
;     if (kt + 3 < nk) { GL_LOAD(1, kt + 3) }
;     MMA_TILE(1)
;     if (kt + 2 < nk) { LDS_STORE(0, 0) }
;     if (VAR != 4) __syncthreads();
	v_mfma_f32_16x16x32_f16 v[48:51], v[122:125], v[110:113], v[48:51]
	ds_read_b128 v[62:65], v16 offset:49152
	ds_read_b128 v[90:93], v21 offset:16384
	s_waitcnt lgkmcnt(0)
	v_mfma_f32_16x16x32_f16 v[36:39], v[62:65], v[90:93], v[36:39]
	ds_read_b128 v[74:77], v16 offset:51200
	ds_read_b128 v[110:113], v21 offset:18432
	s_waitcnt lgkmcnt(0)
	v_mfma_f32_16x16x32_f16 v[66:69], v[62:65], v[110:113], v[66:69]
	ds_read_b128 v[118:121], v16 offset:53248
	v_mfma_f32_16x16x32_f16 v[44:47], v[74:77], v[90:93], v[44:47]
	ds_read_b128 v[122:125], v16 offset:55296
	v_mfma_f32_16x16x32_f16 v[78:81], v[74:77], v[110:113], v[78:81]
	s_waitcnt lgkmcnt(1)
	v_mfma_f32_16x16x32_f16 v[82:85], v[118:121], v[90:93], v[82:85]
	v_mfma_f32_16x16x32_f16 v[86:89], v[118:121], v[110:113], v[86:89]
	s_waitcnt lgkmcnt(0)
	v_mfma_f32_16x16x32_f16 v[28:31], v[122:125], v[90:93], v[28:31]
	ds_read_b128 v[90:93], v21 offset:20480
	v_mfma_f32_16x16x32_f16 v[32:35], v[122:125], v[110:113], v[32:35]
	ds_read_b128 v[110:113], v21 offset:22528
	s_waitcnt lgkmcnt(1)
	v_mfma_f32_16x16x32_f16 v[98:101], v[62:65], v[90:93], v[98:101]
	s_waitcnt lgkmcnt(0)
	v_mfma_f32_16x16x32_f16 v[52:55], v[62:65], v[110:113], v[52:55]
	ds_read_b128 v[62:65], v22 offset:49152
	v_mfma_f32_16x16x32_f16 v[102:105], v[74:77], v[90:93], v[102:105]
	v_mfma_f32_16x16x32_f16 v[24:27], v[74:77], v[110:113], v[24:27]
	ds_read_b128 v[74:77], v22 offset:51200
	v_mfma_f32_16x16x32_f16 v[114:117], v[118:121], v[90:93], v[114:117]
	s_waitcnt vmcnt(7)
	ds_write_b128 v17, v[58:61]
	s_waitcnt vmcnt(6)
	ds_write_b128 v18, v[106:109]
	v_mfma_f32_16x16x32_f16 v[40:43], v[118:121], v[110:113], v[40:43]
	ds_read_b128 v[118:121], v22 offset:53248
	s_waitcnt vmcnt(5)
	ds_write_b128 v19, v[134:137]
	v_mfma_f32_16x16x32_f16 v[70:73], v[122:125], v[90:93], v[70:73]
	ds_read_b128 v[90:93], v23 offset:16384
	v_mfma_f32_16x16x32_f16 v[48:51], v[122:125], v[110:113], v[48:51]
	ds_read_b128 v[110:113], v23 offset:18432
	s_waitcnt lgkmcnt(1)
	v_mfma_f32_16x16x32_f16 v[36:39], v[62:65], v[90:93], v[36:39]
	ds_read_b128 v[122:125], v22 offset:55296
	s_waitcnt lgkmcnt(1)
	v_mfma_f32_16x16x32_f16 v[66:69], v[62:65], v[110:113], v[66:69]
	s_waitcnt vmcnt(4)
	ds_write_b128 v20, v[158:161]
	v_mfma_f32_16x16x32_f16 v[44:47], v[74:77], v[90:93], v[44:47]
	s_waitcnt vmcnt(3)
	ds_write_b128 v17, v[94:97] offset:32768
	v_mfma_f32_16x16x32_f16 v[78:81], v[74:77], v[110:113], v[78:81]
	s_waitcnt vmcnt(2)
	ds_write_b128 v18, v[162:165] offset:32768
	v_mfma_f32_16x16x32_f16 v[82:85], v[118:121], v[90:93], v[82:85]
	s_waitcnt vmcnt(1)
	ds_write_b128 v19, v[166:169] offset:32768
	v_mfma_f32_16x16x32_f16 v[86:89], v[118:121], v[110:113], v[86:89]
	s_waitcnt vmcnt(0)
	ds_write_b128 v20, v[190:193] offset:32768
	s_waitcnt lgkmcnt(5)
	v_mfma_f32_16x16x32_f16 v[28:31], v[122:125], v[90:93], v[28:31]
	ds_read_b128 v[90:93], v23 offset:20480
	v_mfma_f32_16x16x32_f16 v[32:35], v[122:125], v[110:113], v[32:35]
	ds_read_b128 v[110:113], v23 offset:22528
	s_waitcnt lgkmcnt(1)
	v_mfma_f32_16x16x32_f16 v[98:101], v[62:65], v[90:93], v[98:101]
	s_waitcnt lgkmcnt(0)
	v_mfma_f32_16x16x32_f16 v[52:55], v[62:65], v[110:113], v[52:55]
	global_load_dwordx4 v[62:65], v[0:1], off offset:1664
	v_mfma_f32_16x16x32_f16 v[102:105], v[74:77], v[90:93], v[102:105]
	v_mfma_f32_16x16x32_f16 v[24:27], v[74:77], v[110:113], v[24:27]
	v_mfma_f32_16x16x32_f16 v[114:117], v[118:121], v[90:93], v[114:117]
	v_mfma_f32_16x16x32_f16 v[40:43], v[118:121], v[110:113], v[40:43]
	v_mfma_f32_16x16x32_f16 v[70:73], v[122:125], v[90:93], v[70:73]
	global_load_dwordx4 v[90:93], v[2:3], off offset:1664
	global_load_dwordx4 v[126:129], v[4:5], off offset:1664
	global_load_dwordx4 v[130:133], v[14:15], off offset:1664
	global_load_dwordx4 v[74:77], v[10:11], off offset:1664
	global_load_dwordx4 v[138:141], v[12:13], off offset:1664
	global_load_dwordx4 v[142:145], v[8:9], off offset:1664
	global_load_dwordx4 v[154:157], v[6:7], off offset:1664
	s_waitcnt lgkmcnt(0)
	s_barrier
	v_mfma_f32_16x16x32_f16 v[48:51], v[122:125], v[110:113], v[48:51]
	ds_read_b128 v[58:61], v16 offset:32768
	ds_read_b128 v[106:109], v21
	s_waitcnt lgkmcnt(0)
	v_mfma_f32_16x16x32_f16 v[36:39], v[58:61], v[106:109], v[36:39]
	ds_read_b128 v[94:97], v16 offset:34816
	ds_read_b128 v[110:113], v21 offset:2048
	s_waitcnt lgkmcnt(0)
	v_mfma_f32_16x16x32_f16 v[66:69], v[58:61], v[110:113], v[66:69]
	ds_read_b128 v[118:121], v16 offset:36864
	v_mfma_f32_16x16x32_f16 v[44:47], v[94:97], v[106:109], v[44:47]
	ds_read_b128 v[122:125], v16 offset:38912
	v_mfma_f32_16x16x32_f16 v[78:81], v[94:97], v[110:113], v[78:81]
	s_waitcnt lgkmcnt(1)
	v_mfma_f32_16x16x32_f16 v[82:85], v[118:121], v[106:109], v[82:85]
	v_mfma_f32_16x16x32_f16 v[86:89], v[118:121], v[110:113], v[86:89]
	s_waitcnt lgkmcnt(0)
	v_mfma_f32_16x16x32_f16 v[28:31], v[122:125], v[106:109], v[28:31]
	ds_read_b128 v[106:109], v21 offset:4096
	v_mfma_f32_16x16x32_f16 v[32:35], v[122:125], v[110:113], v[32:35]
	ds_read_b128 v[110:113], v21 offset:6144
	s_waitcnt lgkmcnt(1)
	v_mfma_f32_16x16x32_f16 v[98:101], v[58:61], v[106:109], v[98:101]
	s_waitcnt lgkmcnt(0)
	v_mfma_f32_16x16x32_f16 v[52:55], v[58:61], v[110:113], v[52:55]
	ds_read_b128 v[58:61], v22 offset:32768
	v_mfma_f32_16x16x32_f16 v[102:105], v[94:97], v[106:109], v[102:105]
	v_mfma_f32_16x16x32_f16 v[24:27], v[94:97], v[110:113], v[24:27]
	ds_read_b128 v[94:97], v22 offset:34816
	v_mfma_f32_16x16x32_f16 v[114:117], v[118:121], v[106:109], v[114:117]
	s_waitcnt vmcnt(7)
	ds_write_b128 v17, v[62:65] offset:16384
	s_waitcnt vmcnt(6)
; #define GL_LOAD(s_, kt_) if (VAR != 1) { a##s_##0 = GL_A(0, kt_); a##s_##1 = GL_A(1, kt_); a##s_##2 = GL_A(2, kt_); a##s_##3 = GL_A(3, kt_); b##s_##0 = GL_B(0, kt_); b##s_##1 = GL_B(1, kt_); b##s_##2 = GL_B(2, kt_); b##s_##3 = GL_B(3, kt_); }
; #define LDS_STORE(s_, buf_) if (VAR != 2) { LDS_ST1(sA, 0, buf_, a##s_##0) LDS_ST1(sA, 1, buf_, a##s_##1) LDS_ST1(sA, 2, buf_, a##s_##2) LDS_ST1(sA, 3, buf_, a##s_##3) LDS_ST1(sB, 0, buf_, b##s_##0) LDS_ST1(sB, 1, buf_, b##s_##1) LDS_ST1(sB, 2, buf_, b##s_##2) LDS_ST1(sB, 3, buf_, b##s_##3) }
;     ...
;   GL_LOAD(0, 0)
;   GL_LOAD(1, 1)
;   LDS_STORE(0, 0)
;   if (VAR != 4) __syncthreads();
; #pragma unroll
;   for (int kt = 0; kt < nk; kt += 2) {
;     if (kt + 2 < nk) { GL_LOAD(0, kt + 2) }
;     MMA_TILE(0)
;     LDS_STORE(1, 1)
;     if (VAR != 4) __syncthreads();
;     if (kt + 3 < nk) { GL_LOAD(1, kt + 3) }
;     MMA_TILE(1)
;     if (kt + 2 < nk) { LDS_STORE(0, 0) }
;     if (VAR != 4) __syncthreads();
	ds_write_b128 v18, v[90:93] offset:16384
	v_mfma_f32_16x16x32_f16 v[40:43], v[118:121], v[110:113], v[40:43]
	ds_read_b128 v[118:121], v22 offset:36864
	s_waitcnt vmcnt(5)
	ds_write_b128 v19, v[126:129] offset:16384
	v_mfma_f32_16x16x32_f16 v[70:73], v[122:125], v[106:109], v[70:73]
	ds_read_b128 v[106:109], v23
	v_mfma_f32_16x16x32_f16 v[48:51], v[122:125], v[110:113], v[48:51]
	ds_read_b128 v[110:113], v23 offset:2048
	s_waitcnt lgkmcnt(1)
	v_mfma_f32_16x16x32_f16 v[36:39], v[58:61], v[106:109], v[36:39]
	ds_read_b128 v[122:125], v22 offset:38912
	s_waitcnt lgkmcnt(1)
	v_mfma_f32_16x16x32_f16 v[66:69], v[58:61], v[110:113], v[66:69]
	s_waitcnt vmcnt(4)
	ds_write_b128 v20, v[130:133] offset:16384
	v_mfma_f32_16x16x32_f16 v[44:47], v[94:97], v[106:109], v[44:47]
	s_waitcnt vmcnt(3)
	ds_write_b128 v17, v[74:77] offset:49152
	v_mfma_f32_16x16x32_f16 v[78:81], v[94:97], v[110:113], v[78:81]
	s_waitcnt vmcnt(2)
	ds_write_b128 v18, v[138:141] offset:49152
	v_mfma_f32_16x16x32_f16 v[82:85], v[118:121], v[106:109], v[82:85]
	s_waitcnt vmcnt(1)
	ds_write_b128 v19, v[142:145] offset:49152
	v_mfma_f32_16x16x32_f16 v[86:89], v[118:121], v[110:113], v[86:89]
	s_waitcnt vmcnt(0)
	ds_write_b128 v20, v[154:157] offset:49152
	s_waitcnt lgkmcnt(5)
	v_mfma_f32_16x16x32_f16 v[28:31], v[122:125], v[106:109], v[28:31]
	ds_read_b128 v[106:109], v23 offset:4096
	v_mfma_f32_16x16x32_f16 v[32:35], v[122:125], v[110:113], v[32:35]
	ds_read_b128 v[110:113], v23 offset:6144
	s_waitcnt lgkmcnt(1)
	v_mfma_f32_16x16x32_f16 v[98:101], v[58:61], v[106:109], v[98:101]
	s_waitcnt lgkmcnt(0)
	v_mfma_f32_16x16x32_f16 v[52:55], v[58:61], v[110:113], v[52:55]
	global_load_dwordx4 v[58:61], v[0:1], off offset:1792
	v_mfma_f32_16x16x32_f16 v[102:105], v[94:97], v[106:109], v[102:105]
	v_mfma_f32_16x16x32_f16 v[24:27], v[94:97], v[110:113], v[24:27]
	v_mfma_f32_16x16x32_f16 v[114:117], v[118:121], v[106:109], v[114:117]
	v_mfma_f32_16x16x32_f16 v[40:43], v[118:121], v[110:113], v[40:43]
	v_mfma_f32_16x16x32_f16 v[70:73], v[122:125], v[106:109], v[70:73]
	global_load_dwordx4 v[106:109], v[2:3], off offset:1792
	global_load_dwordx4 v[134:137], v[4:5], off offset:1792
	global_load_dwordx4 v[158:161], v[14:15], off offset:1792
	global_load_dwordx4 v[94:97], v[10:11], off offset:1792
	global_load_dwordx4 v[162:165], v[12:13], off offset:1792
	global_load_dwordx4 v[166:169], v[8:9], off offset:1792
	global_load_dwordx4 v[190:193], v[6:7], off offset:1792
	s_waitcnt lgkmcnt(0)
	s_barrier
	v_mfma_f32_16x16x32_f16 v[48:51], v[122:125], v[110:113], v[48:51]
	ds_read_b128 v[62:65], v16 offset:49152
	ds_read_b128 v[90:93], v21 offset:16384
	s_waitcnt lgkmcnt(0)
	v_mfma_f32_16x16x32_f16 v[36:39], v[62:65], v[90:93], v[36:39]
	ds_read_b128 v[74:77], v16 offset:51200
	ds_read_b128 v[110:113], v21 offset:18432
	s_waitcnt lgkmcnt(0)
	v_mfma_f32_16x16x32_f16 v[66:69], v[62:65], v[110:113], v[66:69]
	ds_read_b128 v[118:121], v16 offset:53248
	v_mfma_f32_16x16x32_f16 v[44:47], v[74:77], v[90:93], v[44:47]
	ds_read_b128 v[122:125], v16 offset:55296
	v_mfma_f32_16x16x32_f16 v[78:81], v[74:77], v[110:113], v[78:81]
	s_waitcnt lgkmcnt(1)
	v_mfma_f32_16x16x32_f16 v[82:85], v[118:121], v[90:93], v[82:85]
	v_mfma_f32_16x16x32_f16 v[86:89], v[118:121], v[110:113], v[86:89]
	s_waitcnt lgkmcnt(0)
	v_mfma_f32_16x16x32_f16 v[28:31], v[122:125], v[90:93], v[28:31]
	ds_read_b128 v[90:93], v21 offset:20480
	v_mfma_f32_16x16x32_f16 v[32:35], v[122:125], v[110:113], v[32:35]
	ds_read_b128 v[110:113], v21 offset:22528
	s_waitcnt lgkmcnt(1)
	v_mfma_f32_16x16x32_f16 v[98:101], v[62:65], v[90:93], v[98:101]
	s_waitcnt lgkmcnt(0)
	v_mfma_f32_16x16x32_f16 v[52:55], v[62:65], v[110:113], v[52:55]
	ds_read_b128 v[62:65], v22 offset:49152
	v_mfma_f32_16x16x32_f16 v[102:105], v[74:77], v[90:93], v[102:105]
	v_mfma_f32_16x16x32_f16 v[24:27], v[74:77], v[110:113], v[24:27]
	ds_read_b128 v[74:77], v22 offset:51200
	v_mfma_f32_16x16x32_f16 v[114:117], v[118:121], v[90:93], v[114:117]
	s_waitcnt vmcnt(7)
	ds_write_b128 v17, v[58:61]
	s_waitcnt vmcnt(6)
	ds_write_b128 v18, v[106:109]
	v_mfma_f32_16x16x32_f16 v[40:43], v[118:121], v[110:113], v[40:43]
	ds_read_b128 v[118:121], v22 offset:53248
	s_waitcnt vmcnt(5)
	ds_write_b128 v19, v[134:137]
	v_mfma_f32_16x16x32_f16 v[70:73], v[122:125], v[90:93], v[70:73]
	ds_read_b128 v[90:93], v23 offset:16384
	v_mfma_f32_16x16x32_f16 v[48:51], v[122:125], v[110:113], v[48:51]
	ds_read_b128 v[110:113], v23 offset:18432
	s_waitcnt lgkmcnt(1)
	v_mfma_f32_16x16x32_f16 v[36:39], v[62:65], v[90:93], v[36:39]
	ds_read_b128 v[122:125], v22 offset:55296
	s_waitcnt lgkmcnt(1)
	v_mfma_f32_16x16x32_f16 v[66:69], v[62:65], v[110:113], v[66:69]
	s_waitcnt vmcnt(4)
	ds_write_b128 v20, v[158:161]
	v_mfma_f32_16x16x32_f16 v[44:47], v[74:77], v[90:93], v[44:47]
	s_waitcnt vmcnt(3)
	ds_write_b128 v17, v[94:97] offset:32768
	v_mfma_f32_16x16x32_f16 v[78:81], v[74:77], v[110:113], v[78:81]
	s_waitcnt vmcnt(2)
	ds_write_b128 v18, v[162:165] offset:32768
	v_mfma_f32_16x16x32_f16 v[82:85], v[118:121], v[90:93], v[82:85]
	s_waitcnt vmcnt(1)
	ds_write_b128 v19, v[166:169] offset:32768
	v_mfma_f32_16x16x32_f16 v[86:89], v[118:121], v[110:113], v[86:89]
	s_waitcnt vmcnt(0)
	ds_write_b128 v20, v[190:193] offset:32768
	s_waitcnt lgkmcnt(5)
	v_mfma_f32_16x16x32_f16 v[28:31], v[122:125], v[90:93], v[28:31]
	ds_read_b128 v[90:93], v23 offset:20480
	v_mfma_f32_16x16x32_f16 v[32:35], v[122:125], v[110:113], v[32:35]
	ds_read_b128 v[110:113], v23 offset:22528
	s_waitcnt lgkmcnt(1)
	v_mfma_f32_16x16x32_f16 v[98:101], v[62:65], v[90:93], v[98:101]
	s_waitcnt lgkmcnt(0)
	v_mfma_f32_16x16x32_f16 v[52:55], v[62:65], v[110:113], v[52:55]
	global_load_dwordx4 v[62:65], v[0:1], off offset:1920
	v_mfma_f32_16x16x32_f16 v[102:105], v[74:77], v[90:93], v[102:105]
	v_mfma_f32_16x16x32_f16 v[24:27], v[74:77], v[110:113], v[24:27]
	v_mfma_f32_16x16x32_f16 v[114:117], v[118:121], v[90:93], v[114:117]
	v_mfma_f32_16x16x32_f16 v[40:43], v[118:121], v[110:113], v[40:43]
	v_mfma_f32_16x16x32_f16 v[70:73], v[122:125], v[90:93], v[70:73]
	global_load_dwordx4 v[90:93], v[2:3], off offset:1920
	global_load_dwordx4 v[126:129], v[4:5], off offset:1920
	global_load_dwordx4 v[130:133], v[14:15], off offset:1920
	global_load_dwordx4 v[74:77], v[10:11], off offset:1920
	global_load_dwordx4 v[138:141], v[12:13], off offset:1920
	global_load_dwordx4 v[142:145], v[8:9], off offset:1920
	global_load_dwordx4 v[154:157], v[6:7], off offset:1920
	s_waitcnt lgkmcnt(0)
	s_barrier
; #define GL_LOAD(s_, kt_) if (VAR != 1) { a##s_##0 = GL_A(0, kt_); a##s_##1 = GL_A(1, kt_); a##s_##2 = GL_A(2, kt_); a##s_##3 = GL_A(3, kt_); b##s_##0 = GL_B(0, kt_); b##s_##1 = GL_B(1, kt_); b##s_##2 = GL_B(2, kt_); b##s_##3 = GL_B(3, kt_); }
; #define LDS_STORE(s_, buf_) if (VAR != 2) { LDS_ST1(sA, 0, buf_, a##s_##0) LDS_ST1(sA, 1, buf_, a##s_##1) LDS_ST1(sA, 2, buf_, a##s_##2) LDS_ST1(sA, 3, buf_, a##s_##3) LDS_ST1(sB, 0, buf_, b##s_##0) LDS_ST1(sB, 1, buf_, b##s_##1) LDS_ST1(sB, 2, buf_, b##s_##2) LDS_ST1(sB, 3, buf_, b##s_##3) }
;     ...
;   GL_LOAD(0, 0)
;   GL_LOAD(1, 1)
;   LDS_STORE(0, 0)
;   if (VAR != 4) __syncthreads();
; #pragma unroll
;   for (int kt = 0; kt < nk; kt += 2) {
;     if (kt + 2 < nk) { GL_LOAD(0, kt + 2) }
;     MMA_TILE(0)
;     LDS_STORE(1, 1)
;     if (VAR != 4) __syncthreads();
;     if (kt + 3 < nk) { GL_LOAD(1, kt + 3) }
;     MMA_TILE(1)
;     if (kt + 2 < nk) { LDS_STORE(0, 0) }
;     if (VAR != 4) __syncthreads();
	v_mfma_f32_16x16x32_f16 v[48:51], v[122:125], v[110:113], v[48:51]
	ds_read_b128 v[58:61], v16 offset:32768
	ds_read_b128 v[106:109], v21
	s_waitcnt lgkmcnt(0)
	v_mfma_f32_16x16x32_f16 v[36:39], v[58:61], v[106:109], v[36:39]
	ds_read_b128 v[94:97], v16 offset:34816
	ds_read_b128 v[110:113], v21 offset:2048
	s_waitcnt lgkmcnt(0)
	v_mfma_f32_16x16x32_f16 v[66:69], v[58:61], v[110:113], v[66:69]
	ds_read_b128 v[118:121], v16 offset:36864
	v_mfma_f32_16x16x32_f16 v[44:47], v[94:97], v[106:109], v[44:47]
	ds_read_b128 v[122:125], v16 offset:38912
	v_mfma_f32_16x16x32_f16 v[78:81], v[94:97], v[110:113], v[78:81]
	s_waitcnt lgkmcnt(1)
	v_mfma_f32_16x16x32_f16 v[82:85], v[118:121], v[106:109], v[82:85]
	v_mfma_f32_16x16x32_f16 v[86:89], v[118:121], v[110:113], v[86:89]
	s_waitcnt lgkmcnt(0)
	v_mfma_f32_16x16x32_f16 v[28:31], v[122:125], v[106:109], v[28:31]
	ds_read_b128 v[106:109], v21 offset:4096
	v_mfma_f32_16x16x32_f16 v[32:35], v[122:125], v[110:113], v[32:35]
	ds_read_b128 v[110:113], v21 offset:6144
	s_waitcnt lgkmcnt(1)
	v_mfma_f32_16x16x32_f16 v[98:101], v[58:61], v[106:109], v[98:101]
	s_waitcnt lgkmcnt(0)
	v_mfma_f32_16x16x32_f16 v[52:55], v[58:61], v[110:113], v[52:55]
	ds_read_b128 v[58:61], v22 offset:32768
	v_mfma_f32_16x16x32_f16 v[102:105], v[94:97], v[106:109], v[102:105]
	v_mfma_f32_16x16x32_f16 v[24:27], v[94:97], v[110:113], v[24:27]
	ds_read_b128 v[94:97], v22 offset:34816
	v_mfma_f32_16x16x32_f16 v[114:117], v[118:121], v[106:109], v[114:117]
	s_waitcnt vmcnt(7)
	ds_write_b128 v17, v[62:65] offset:16384
	s_waitcnt vmcnt(6)
	ds_write_b128 v18, v[90:93] offset:16384
	v_mfma_f32_16x16x32_f16 v[40:43], v[118:121], v[110:113], v[40:43]
	ds_read_b128 v[118:121], v22 offset:36864
	s_waitcnt vmcnt(5)
	ds_write_b128 v19, v[126:129] offset:16384
	v_mfma_f32_16x16x32_f16 v[70:73], v[122:125], v[106:109], v[70:73]
	ds_read_b128 v[106:109], v23
	v_mfma_f32_16x16x32_f16 v[48:51], v[122:125], v[110:113], v[48:51]
	ds_read_b128 v[110:113], v23 offset:2048
	s_waitcnt lgkmcnt(1)
	v_mfma_f32_16x16x32_f16 v[36:39], v[58:61], v[106:109], v[36:39]
	ds_read_b128 v[122:125], v22 offset:38912
	s_waitcnt lgkmcnt(1)
	v_mfma_f32_16x16x32_f16 v[66:69], v[58:61], v[110:113], v[66:69]
	s_waitcnt vmcnt(4)
	ds_write_b128 v20, v[130:133] offset:16384
	v_mfma_f32_16x16x32_f16 v[44:47], v[94:97], v[106:109], v[44:47]
	s_waitcnt vmcnt(3)
	ds_write_b128 v17, v[74:77] offset:49152
	v_mfma_f32_16x16x32_f16 v[78:81], v[94:97], v[110:113], v[78:81]
	s_waitcnt vmcnt(2)
	ds_write_b128 v18, v[138:141] offset:49152
	v_mfma_f32_16x16x32_f16 v[82:85], v[118:121], v[106:109], v[82:85]
	s_waitcnt vmcnt(1)
	ds_write_b128 v19, v[142:145] offset:49152
	v_mfma_f32_16x16x32_f16 v[86:89], v[118:121], v[110:113], v[86:89]
	s_waitcnt vmcnt(0)
	ds_write_b128 v20, v[154:157] offset:49152
	s_waitcnt lgkmcnt(5)
	v_mfma_f32_16x16x32_f16 v[28:31], v[122:125], v[106:109], v[28:31]
	ds_read_b128 v[106:109], v23 offset:4096
	v_mfma_f32_16x16x32_f16 v[32:35], v[122:125], v[110:113], v[32:35]
	ds_read_b128 v[110:113], v23 offset:6144
	s_waitcnt lgkmcnt(1)
	v_mfma_f32_16x16x32_f16 v[98:101], v[58:61], v[106:109], v[98:101]
	s_waitcnt lgkmcnt(0)
	v_mfma_f32_16x16x32_f16 v[52:55], v[58:61], v[110:113], v[52:55]
	global_load_dwordx4 v[58:61], v[0:1], off offset:2048
	v_mfma_f32_16x16x32_f16 v[102:105], v[94:97], v[106:109], v[102:105]
	v_mfma_f32_16x16x32_f16 v[24:27], v[94:97], v[110:113], v[24:27]
	v_mfma_f32_16x16x32_f16 v[114:117], v[118:121], v[106:109], v[114:117]
	v_mfma_f32_16x16x32_f16 v[40:43], v[118:121], v[110:113], v[40:43]
	v_mfma_f32_16x16x32_f16 v[70:73], v[122:125], v[106:109], v[70:73]
	global_load_dwordx4 v[106:109], v[2:3], off offset:2048
	global_load_dwordx4 v[134:137], v[4:5], off offset:2048
	global_load_dwordx4 v[158:161], v[14:15], off offset:2048
	global_load_dwordx4 v[94:97], v[10:11], off offset:2048
	global_load_dwordx4 v[162:165], v[12:13], off offset:2048
	global_load_dwordx4 v[166:169], v[8:9], off offset:2048
	global_load_dwordx4 v[190:193], v[6:7], off offset:2048
	s_waitcnt lgkmcnt(0)
	s_barrier
	v_mfma_f32_16x16x32_f16 v[48:51], v[122:125], v[110:113], v[48:51]
	ds_read_b128 v[62:65], v16 offset:49152
	ds_read_b128 v[90:93], v21 offset:16384
	s_waitcnt lgkmcnt(0)
	v_mfma_f32_16x16x32_f16 v[36:39], v[62:65], v[90:93], v[36:39]
	ds_read_b128 v[74:77], v16 offset:51200
	ds_read_b128 v[110:113], v21 offset:18432
	s_waitcnt lgkmcnt(0)
	v_mfma_f32_16x16x32_f16 v[66:69], v[62:65], v[110:113], v[66:69]
	ds_read_b128 v[118:121], v16 offset:53248
	v_mfma_f32_16x16x32_f16 v[44:47], v[74:77], v[90:93], v[44:47]
	ds_read_b128 v[122:125], v16 offset:55296
	v_mfma_f32_16x16x32_f16 v[78:81], v[74:77], v[110:113], v[78:81]
	s_waitcnt lgkmcnt(1)
	v_mfma_f32_16x16x32_f16 v[82:85], v[118:121], v[90:93], v[82:85]
	v_mfma_f32_16x16x32_f16 v[86:89], v[118:121], v[110:113], v[86:89]
	s_waitcnt lgkmcnt(0)
	v_mfma_f32_16x16x32_f16 v[28:31], v[122:125], v[90:93], v[28:31]
	ds_read_b128 v[90:93], v21 offset:20480
	v_mfma_f32_16x16x32_f16 v[32:35], v[122:125], v[110:113], v[32:35]
	ds_read_b128 v[110:113], v21 offset:22528
	s_waitcnt lgkmcnt(1)
	v_mfma_f32_16x16x32_f16 v[98:101], v[62:65], v[90:93], v[98:101]
	s_waitcnt lgkmcnt(0)
	v_mfma_f32_16x16x32_f16 v[52:55], v[62:65], v[110:113], v[52:55]
	ds_read_b128 v[62:65], v22 offset:49152
	v_mfma_f32_16x16x32_f16 v[102:105], v[74:77], v[90:93], v[102:105]
	v_mfma_f32_16x16x32_f16 v[24:27], v[74:77], v[110:113], v[24:27]
	ds_read_b128 v[74:77], v22 offset:51200
	v_mfma_f32_16x16x32_f16 v[114:117], v[118:121], v[90:93], v[114:117]
	s_waitcnt vmcnt(7)
	ds_write_b128 v17, v[58:61]
	s_waitcnt vmcnt(6)
; #define GL_LOAD(s_, kt_) if (VAR != 1) { a##s_##0 = GL_A(0, kt_); a##s_##1 = GL_A(1, kt_); a##s_##2 = GL_A(2, kt_); a##s_##3 = GL_A(3, kt_); b##s_##0 = GL_B(0, kt_); b##s_##1 = GL_B(1, kt_); b##s_##2 = GL_B(2, kt_); b##s_##3 = GL_B(3, kt_); }
; #define LDS_STORE(s_, buf_) if (VAR != 2) { LDS_ST1(sA, 0, buf_, a##s_##0) LDS_ST1(sA, 1, buf_, a##s_##1) LDS_ST1(sA, 2, buf_, a##s_##2) LDS_ST1(sA, 3, buf_, a##s_##3) LDS_ST1(sB, 0, buf_, b##s_##0) LDS_ST1(sB, 1, buf_, b##s_##1) LDS_ST1(sB, 2, buf_, b##s_##2) LDS_ST1(sB, 3, buf_, b##s_##3) }
;     ...
;   GL_LOAD(0, 0)
;   GL_LOAD(1, 1)
;   LDS_STORE(0, 0)
;   if (VAR != 4) __syncthreads();
; #pragma unroll
;   for (int kt = 0; kt < nk; kt += 2) {
;     if (kt + 2 < nk) { GL_LOAD(0, kt + 2) }
;     MMA_TILE(0)
;     LDS_STORE(1, 1)
;     if (VAR != 4) __syncthreads();
;     if (kt + 3 < nk) { GL_LOAD(1, kt + 3) }
;     MMA_TILE(1)
;     if (kt + 2 < nk) { LDS_STORE(0, 0) }
;     if (VAR != 4) __syncthreads();
	ds_write_b128 v18, v[106:109]
	v_mfma_f32_16x16x32_f16 v[40:43], v[118:121], v[110:113], v[40:43]
	ds_read_b128 v[118:121], v22 offset:53248
	s_waitcnt vmcnt(5)
	ds_write_b128 v19, v[134:137]
	v_mfma_f32_16x16x32_f16 v[70:73], v[122:125], v[90:93], v[70:73]
	ds_read_b128 v[90:93], v23 offset:16384
	v_mfma_f32_16x16x32_f16 v[48:51], v[122:125], v[110:113], v[48:51]
	ds_read_b128 v[110:113], v23 offset:18432
	s_waitcnt lgkmcnt(1)
	v_mfma_f32_16x16x32_f16 v[36:39], v[62:65], v[90:93], v[36:39]
	ds_read_b128 v[122:125], v22 offset:55296
	s_waitcnt lgkmcnt(1)
	v_mfma_f32_16x16x32_f16 v[66:69], v[62:65], v[110:113], v[66:69]
	s_waitcnt vmcnt(4)
	ds_write_b128 v20, v[158:161]
	v_mfma_f32_16x16x32_f16 v[44:47], v[74:77], v[90:93], v[44:47]
	s_waitcnt vmcnt(3)
	ds_write_b128 v17, v[94:97] offset:32768
	v_mfma_f32_16x16x32_f16 v[78:81], v[74:77], v[110:113], v[78:81]
	s_waitcnt vmcnt(2)
	ds_write_b128 v18, v[162:165] offset:32768
	v_mfma_f32_16x16x32_f16 v[82:85], v[118:121], v[90:93], v[82:85]
	s_waitcnt vmcnt(1)
	ds_write_b128 v19, v[166:169] offset:32768
	v_mfma_f32_16x16x32_f16 v[86:89], v[118:121], v[110:113], v[86:89]
	s_waitcnt vmcnt(0)
	ds_write_b128 v20, v[190:193] offset:32768
	s_waitcnt lgkmcnt(5)
	v_mfma_f32_16x16x32_f16 v[28:31], v[122:125], v[90:93], v[28:31]
	ds_read_b128 v[90:93], v23 offset:20480
	v_mfma_f32_16x16x32_f16 v[32:35], v[122:125], v[110:113], v[32:35]
	ds_read_b128 v[110:113], v23 offset:22528
	s_waitcnt lgkmcnt(1)
	v_mfma_f32_16x16x32_f16 v[98:101], v[62:65], v[90:93], v[98:101]
	s_waitcnt lgkmcnt(0)
	v_mfma_f32_16x16x32_f16 v[52:55], v[62:65], v[110:113], v[52:55]
	global_load_dwordx4 v[62:65], v[0:1], off offset:2176
	v_mfma_f32_16x16x32_f16 v[102:105], v[74:77], v[90:93], v[102:105]
	v_mfma_f32_16x16x32_f16 v[24:27], v[74:77], v[110:113], v[24:27]
	v_mfma_f32_16x16x32_f16 v[114:117], v[118:121], v[90:93], v[114:117]
	v_mfma_f32_16x16x32_f16 v[40:43], v[118:121], v[110:113], v[40:43]
	v_mfma_f32_16x16x32_f16 v[70:73], v[122:125], v[90:93], v[70:73]
	global_load_dwordx4 v[90:93], v[2:3], off offset:2176
	global_load_dwordx4 v[126:129], v[4:5], off offset:2176
	global_load_dwordx4 v[130:133], v[14:15], off offset:2176
	global_load_dwordx4 v[74:77], v[10:11], off offset:2176
	global_load_dwordx4 v[138:141], v[12:13], off offset:2176
	global_load_dwordx4 v[142:145], v[8:9], off offset:2176
	global_load_dwordx4 v[154:157], v[6:7], off offset:2176
	s_waitcnt lgkmcnt(0)
	s_barrier
	v_mfma_f32_16x16x32_f16 v[48:51], v[122:125], v[110:113], v[48:51]
	ds_read_b128 v[58:61], v16 offset:32768
	ds_read_b128 v[106:109], v21
	s_waitcnt lgkmcnt(0)
	v_mfma_f32_16x16x32_f16 v[36:39], v[58:61], v[106:109], v[36:39]
	ds_read_b128 v[94:97], v16 offset:34816
	ds_read_b128 v[110:113], v21 offset:2048
	s_waitcnt lgkmcnt(0)
	v_mfma_f32_16x16x32_f16 v[66:69], v[58:61], v[110:113], v[66:69]
	ds_read_b128 v[118:121], v16 offset:36864
	v_mfma_f32_16x16x32_f16 v[44:47], v[94:97], v[106:109], v[44:47]
	ds_read_b128 v[122:125], v16 offset:38912
	v_mfma_f32_16x16x32_f16 v[78:81], v[94:97], v[110:113], v[78:81]
	s_waitcnt lgkmcnt(1)
	v_mfma_f32_16x16x32_f16 v[82:85], v[118:121], v[106:109], v[82:85]
	v_mfma_f32_16x16x32_f16 v[86:89], v[118:121], v[110:113], v[86:89]
	s_waitcnt lgkmcnt(0)
	v_mfma_f32_16x16x32_f16 v[28:31], v[122:125], v[106:109], v[28:31]
	ds_read_b128 v[106:109], v21 offset:4096
	v_mfma_f32_16x16x32_f16 v[32:35], v[122:125], v[110:113], v[32:35]
	ds_read_b128 v[110:113], v21 offset:6144
	s_waitcnt lgkmcnt(1)
	v_mfma_f32_16x16x32_f16 v[98:101], v[58:61], v[106:109], v[98:101]
	s_waitcnt lgkmcnt(0)
	v_mfma_f32_16x16x32_f16 v[52:55], v[58:61], v[110:113], v[52:55]
	ds_read_b128 v[58:61], v22 offset:32768
	v_mfma_f32_16x16x32_f16 v[102:105], v[94:97], v[106:109], v[102:105]
	v_mfma_f32_16x16x32_f16 v[24:27], v[94:97], v[110:113], v[24:27]
	ds_read_b128 v[94:97], v22 offset:34816
	v_mfma_f32_16x16x32_f16 v[114:117], v[118:121], v[106:109], v[114:117]
	s_waitcnt vmcnt(7)
	ds_write_b128 v17, v[62:65] offset:16384
	s_waitcnt vmcnt(6)
	ds_write_b128 v18, v[90:93] offset:16384
	v_mfma_f32_16x16x32_f16 v[40:43], v[118:121], v[110:113], v[40:43]
	ds_read_b128 v[118:121], v22 offset:36864
	s_waitcnt vmcnt(5)
	ds_write_b128 v19, v[126:129] offset:16384
	v_mfma_f32_16x16x32_f16 v[70:73], v[122:125], v[106:109], v[70:73]
	ds_read_b128 v[106:109], v23
	v_mfma_f32_16x16x32_f16 v[48:51], v[122:125], v[110:113], v[48:51]
	ds_read_b128 v[110:113], v23 offset:2048
	s_waitcnt lgkmcnt(1)
	v_mfma_f32_16x16x32_f16 v[36:39], v[58:61], v[106:109], v[36:39]
	ds_read_b128 v[122:125], v22 offset:38912
	s_waitcnt lgkmcnt(1)
	v_mfma_f32_16x16x32_f16 v[66:69], v[58:61], v[110:113], v[66:69]
	s_waitcnt vmcnt(4)
	ds_write_b128 v20, v[130:133] offset:16384
	v_mfma_f32_16x16x32_f16 v[44:47], v[94:97], v[106:109], v[44:47]
	s_waitcnt vmcnt(3)
	ds_write_b128 v17, v[74:77] offset:49152
	v_mfma_f32_16x16x32_f16 v[78:81], v[94:97], v[110:113], v[78:81]
	s_waitcnt vmcnt(2)
	ds_write_b128 v18, v[138:141] offset:49152
	v_mfma_f32_16x16x32_f16 v[82:85], v[118:121], v[106:109], v[82:85]
	s_waitcnt vmcnt(1)
	ds_write_b128 v19, v[142:145] offset:49152
	v_mfma_f32_16x16x32_f16 v[86:89], v[118:121], v[110:113], v[86:89]
	s_waitcnt vmcnt(0)
	ds_write_b128 v20, v[154:157] offset:49152
	s_waitcnt lgkmcnt(5)
	v_mfma_f32_16x16x32_f16 v[28:31], v[122:125], v[106:109], v[28:31]
	ds_read_b128 v[106:109], v23 offset:4096
	v_mfma_f32_16x16x32_f16 v[32:35], v[122:125], v[110:113], v[32:35]
	ds_read_b128 v[110:113], v23 offset:6144
	s_waitcnt lgkmcnt(1)
	v_mfma_f32_16x16x32_f16 v[98:101], v[58:61], v[106:109], v[98:101]
	s_waitcnt lgkmcnt(0)
	v_mfma_f32_16x16x32_f16 v[52:55], v[58:61], v[110:113], v[52:55]
	global_load_dwordx4 v[58:61], v[0:1], off offset:2304
	v_mfma_f32_16x16x32_f16 v[102:105], v[94:97], v[106:109], v[102:105]
	v_mfma_f32_16x16x32_f16 v[24:27], v[94:97], v[110:113], v[24:27]
	v_mfma_f32_16x16x32_f16 v[114:117], v[118:121], v[106:109], v[114:117]
	v_mfma_f32_16x16x32_f16 v[40:43], v[118:121], v[110:113], v[40:43]
	v_mfma_f32_16x16x32_f16 v[70:73], v[122:125], v[106:109], v[70:73]
	global_load_dwordx4 v[106:109], v[2:3], off offset:2304
	global_load_dwordx4 v[134:137], v[4:5], off offset:2304
	global_load_dwordx4 v[158:161], v[14:15], off offset:2304
	global_load_dwordx4 v[94:97], v[10:11], off offset:2304
	global_load_dwordx4 v[162:165], v[12:13], off offset:2304
	global_load_dwordx4 v[166:169], v[8:9], off offset:2304
	global_load_dwordx4 v[190:193], v[6:7], off offset:2304
	s_waitcnt lgkmcnt(0)
	s_barrier
; #define GL_LOAD(s_, kt_) if (VAR != 1) { a##s_##0 = GL_A(0, kt_); a##s_##1 = GL_A(1, kt_); a##s_##2 = GL_A(2, kt_); a##s_##3 = GL_A(3, kt_); b##s_##0 = GL_B(0, kt_); b##s_##1 = GL_B(1, kt_); b##s_##2 = GL_B(2, kt_); b##s_##3 = GL_B(3, kt_); }
; #define LDS_STORE(s_, buf_) if (VAR != 2) { LDS_ST1(sA, 0, buf_, a##s_##0) LDS_ST1(sA, 1, buf_, a##s_##1) LDS_ST1(sA, 2, buf_, a##s_##2) LDS_ST1(sA, 3, buf_, a##s_##3) LDS_ST1(sB, 0, buf_, b##s_##0) LDS_ST1(sB, 1, buf_, b##s_##1) LDS_ST1(sB, 2, buf_, b##s_##2) LDS_ST1(sB, 3, buf_, b##s_##3) }
;     ...
;   GL_LOAD(0, 0)
;   GL_LOAD(1, 1)
;   LDS_STORE(0, 0)
;   if (VAR != 4) __syncthreads();
; #pragma unroll
;   for (int kt = 0; kt < nk; kt += 2) {
;     if (kt + 2 < nk) { GL_LOAD(0, kt + 2) }
;     MMA_TILE(0)
;     LDS_STORE(1, 1)
;     if (VAR != 4) __syncthreads();
;     if (kt + 3 < nk) { GL_LOAD(1, kt + 3) }
;     MMA_TILE(1)
;     if (kt + 2 < nk) { LDS_STORE(0, 0) }
;     if (VAR != 4) __syncthreads();
	v_mfma_f32_16x16x32_f16 v[48:51], v[122:125], v[110:113], v[48:51]
	ds_read_b128 v[62:65], v16 offset:49152
	ds_read_b128 v[90:93], v21 offset:16384
	s_waitcnt lgkmcnt(0)
	v_mfma_f32_16x16x32_f16 v[36:39], v[62:65], v[90:93], v[36:39]
	ds_read_b128 v[74:77], v16 offset:51200
	ds_read_b128 v[110:113], v21 offset:18432
	s_waitcnt lgkmcnt(0)
	v_mfma_f32_16x16x32_f16 v[66:69], v[62:65], v[110:113], v[66:69]
	ds_read_b128 v[118:121], v16 offset:53248
	v_mfma_f32_16x16x32_f16 v[44:47], v[74:77], v[90:93], v[44:47]
	ds_read_b128 v[122:125], v16 offset:55296
	v_mfma_f32_16x16x32_f16 v[78:81], v[74:77], v[110:113], v[78:81]
	s_waitcnt lgkmcnt(1)
	v_mfma_f32_16x16x32_f16 v[82:85], v[118:121], v[90:93], v[82:85]
	v_mfma_f32_16x16x32_f16 v[86:89], v[118:121], v[110:113], v[86:89]
	s_waitcnt lgkmcnt(0)
	v_mfma_f32_16x16x32_f16 v[28:31], v[122:125], v[90:93], v[28:31]
	ds_read_b128 v[90:93], v21 offset:20480
	v_mfma_f32_16x16x32_f16 v[32:35], v[122:125], v[110:113], v[32:35]
	ds_read_b128 v[110:113], v21 offset:22528
	s_waitcnt lgkmcnt(1)
	v_mfma_f32_16x16x32_f16 v[98:101], v[62:65], v[90:93], v[98:101]
	s_waitcnt lgkmcnt(0)
	v_mfma_f32_16x16x32_f16 v[52:55], v[62:65], v[110:113], v[52:55]
	ds_read_b128 v[62:65], v22 offset:49152
	v_mfma_f32_16x16x32_f16 v[102:105], v[74:77], v[90:93], v[102:105]
	v_mfma_f32_16x16x32_f16 v[24:27], v[74:77], v[110:113], v[24:27]
	ds_read_b128 v[74:77], v22 offset:51200
	v_mfma_f32_16x16x32_f16 v[114:117], v[118:121], v[90:93], v[114:117]
	s_waitcnt vmcnt(7)
	ds_write_b128 v17, v[58:61]
	s_waitcnt vmcnt(6)
	ds_write_b128 v18, v[106:109]
	v_mfma_f32_16x16x32_f16 v[40:43], v[118:121], v[110:113], v[40:43]
	ds_read_b128 v[118:121], v22 offset:53248
	s_waitcnt vmcnt(5)
	ds_write_b128 v19, v[134:137]
	v_mfma_f32_16x16x32_f16 v[70:73], v[122:125], v[90:93], v[70:73]
	ds_read_b128 v[90:93], v23 offset:16384
	v_mfma_f32_16x16x32_f16 v[48:51], v[122:125], v[110:113], v[48:51]
	ds_read_b128 v[110:113], v23 offset:18432
	s_waitcnt lgkmcnt(1)
	v_mfma_f32_16x16x32_f16 v[36:39], v[62:65], v[90:93], v[36:39]
	ds_read_b128 v[122:125], v22 offset:55296
	s_waitcnt lgkmcnt(1)
	v_mfma_f32_16x16x32_f16 v[66:69], v[62:65], v[110:113], v[66:69]
	s_waitcnt vmcnt(4)
	ds_write_b128 v20, v[158:161]
	v_mfma_f32_16x16x32_f16 v[44:47], v[74:77], v[90:93], v[44:47]
	s_waitcnt vmcnt(3)
	ds_write_b128 v17, v[94:97] offset:32768
	v_mfma_f32_16x16x32_f16 v[78:81], v[74:77], v[110:113], v[78:81]
	s_waitcnt vmcnt(2)
	ds_write_b128 v18, v[162:165] offset:32768
	v_mfma_f32_16x16x32_f16 v[82:85], v[118:121], v[90:93], v[82:85]
	s_waitcnt vmcnt(1)
	ds_write_b128 v19, v[166:169] offset:32768
	v_mfma_f32_16x16x32_f16 v[86:89], v[118:121], v[110:113], v[86:89]
	s_waitcnt vmcnt(0)
	ds_write_b128 v20, v[190:193] offset:32768
	s_waitcnt lgkmcnt(5)
	v_mfma_f32_16x16x32_f16 v[28:31], v[122:125], v[90:93], v[28:31]
	ds_read_b128 v[90:93], v23 offset:20480
	v_mfma_f32_16x16x32_f16 v[32:35], v[122:125], v[110:113], v[32:35]
	ds_read_b128 v[110:113], v23 offset:22528
	s_waitcnt lgkmcnt(1)
	v_mfma_f32_16x16x32_f16 v[98:101], v[62:65], v[90:93], v[98:101]
	s_waitcnt lgkmcnt(0)
	v_mfma_f32_16x16x32_f16 v[52:55], v[62:65], v[110:113], v[52:55]
	global_load_dwordx4 v[62:65], v[0:1], off offset:2432
	v_mfma_f32_16x16x32_f16 v[102:105], v[74:77], v[90:93], v[102:105]
	v_mfma_f32_16x16x32_f16 v[24:27], v[74:77], v[110:113], v[24:27]
	v_mfma_f32_16x16x32_f16 v[114:117], v[118:121], v[90:93], v[114:117]
	v_mfma_f32_16x16x32_f16 v[40:43], v[118:121], v[110:113], v[40:43]
	v_mfma_f32_16x16x32_f16 v[70:73], v[122:125], v[90:93], v[70:73]
	global_load_dwordx4 v[90:93], v[2:3], off offset:2432
	global_load_dwordx4 v[126:129], v[4:5], off offset:2432
	global_load_dwordx4 v[130:133], v[14:15], off offset:2432
	global_load_dwordx4 v[74:77], v[10:11], off offset:2432
	global_load_dwordx4 v[138:141], v[12:13], off offset:2432
	global_load_dwordx4 v[142:145], v[8:9], off offset:2432
	global_load_dwordx4 v[154:157], v[6:7], off offset:2432
	s_waitcnt lgkmcnt(0)
	s_barrier
	v_mfma_f32_16x16x32_f16 v[48:51], v[122:125], v[110:113], v[48:51]
	ds_read_b128 v[58:61], v16 offset:32768
	ds_read_b128 v[106:109], v21
	s_waitcnt lgkmcnt(0)
	v_mfma_f32_16x16x32_f16 v[36:39], v[58:61], v[106:109], v[36:39]
	ds_read_b128 v[94:97], v16 offset:34816
	ds_read_b128 v[110:113], v21 offset:2048
	s_waitcnt lgkmcnt(0)
	v_mfma_f32_16x16x32_f16 v[66:69], v[58:61], v[110:113], v[66:69]
	ds_read_b128 v[118:121], v16 offset:36864
	v_mfma_f32_16x16x32_f16 v[44:47], v[94:97], v[106:109], v[44:47]
	ds_read_b128 v[122:125], v16 offset:38912
	v_mfma_f32_16x16x32_f16 v[78:81], v[94:97], v[110:113], v[78:81]
	s_waitcnt lgkmcnt(1)
	v_mfma_f32_16x16x32_f16 v[82:85], v[118:121], v[106:109], v[82:85]
	v_mfma_f32_16x16x32_f16 v[86:89], v[118:121], v[110:113], v[86:89]
	s_waitcnt lgkmcnt(0)
	v_mfma_f32_16x16x32_f16 v[28:31], v[122:125], v[106:109], v[28:31]
	ds_read_b128 v[106:109], v21 offset:4096
	v_mfma_f32_16x16x32_f16 v[32:35], v[122:125], v[110:113], v[32:35]
	ds_read_b128 v[110:113], v21 offset:6144
	s_waitcnt lgkmcnt(1)
	v_mfma_f32_16x16x32_f16 v[98:101], v[58:61], v[106:109], v[98:101]
	s_waitcnt lgkmcnt(0)
	v_mfma_f32_16x16x32_f16 v[52:55], v[58:61], v[110:113], v[52:55]
	ds_read_b128 v[58:61], v22 offset:32768
	v_mfma_f32_16x16x32_f16 v[102:105], v[94:97], v[106:109], v[102:105]
	v_mfma_f32_16x16x32_f16 v[24:27], v[94:97], v[110:113], v[24:27]
	ds_read_b128 v[94:97], v22 offset:34816
	v_mfma_f32_16x16x32_f16 v[114:117], v[118:121], v[106:109], v[114:117]
	s_waitcnt vmcnt(7)
	ds_write_b128 v17, v[62:65] offset:16384
	s_waitcnt vmcnt(6)
; #define GL_LOAD(s_, kt_) if (VAR != 1) { a##s_##0 = GL_A(0, kt_); a##s_##1 = GL_A(1, kt_); a##s_##2 = GL_A(2, kt_); a##s_##3 = GL_A(3, kt_); b##s_##0 = GL_B(0, kt_); b##s_##1 = GL_B(1, kt_); b##s_##2 = GL_B(2, kt_); b##s_##3 = GL_B(3, kt_); }
; #define LDS_STORE(s_, buf_) if (VAR != 2) { LDS_ST1(sA, 0, buf_, a##s_##0) LDS_ST1(sA, 1, buf_, a##s_##1) LDS_ST1(sA, 2, buf_, a##s_##2) LDS_ST1(sA, 3, buf_, a##s_##3) LDS_ST1(sB, 0, buf_, b##s_##0) LDS_ST1(sB, 1, buf_, b##s_##1) LDS_ST1(sB, 2, buf_, b##s_##2) LDS_ST1(sB, 3, buf_, b##s_##3) }
;     ...
;   GL_LOAD(0, 0)
;   GL_LOAD(1, 1)
;   LDS_STORE(0, 0)
;   if (VAR != 4) __syncthreads();
; #pragma unroll
;   for (int kt = 0; kt < nk; kt += 2) {
;     if (kt + 2 < nk) { GL_LOAD(0, kt + 2) }
;     MMA_TILE(0)
;     LDS_STORE(1, 1)
;     if (VAR != 4) __syncthreads();
;     if (kt + 3 < nk) { GL_LOAD(1, kt + 3) }
;     MMA_TILE(1)
;     if (kt + 2 < nk) { LDS_STORE(0, 0) }
;     if (VAR != 4) __syncthreads();
	ds_write_b128 v18, v[90:93] offset:16384
	v_mfma_f32_16x16x32_f16 v[40:43], v[118:121], v[110:113], v[40:43]
	ds_read_b128 v[118:121], v22 offset:36864
	s_waitcnt vmcnt(5)
	ds_write_b128 v19, v[126:129] offset:16384
	v_mfma_f32_16x16x32_f16 v[70:73], v[122:125], v[106:109], v[70:73]
	ds_read_b128 v[106:109], v23
	v_mfma_f32_16x16x32_f16 v[48:51], v[122:125], v[110:113], v[48:51]
	ds_read_b128 v[110:113], v23 offset:2048
	s_waitcnt lgkmcnt(1)
	v_mfma_f32_16x16x32_f16 v[36:39], v[58:61], v[106:109], v[36:39]
	ds_read_b128 v[122:125], v22 offset:38912
	s_waitcnt lgkmcnt(1)
	v_mfma_f32_16x16x32_f16 v[66:69], v[58:61], v[110:113], v[66:69]
	s_waitcnt vmcnt(4)
	ds_write_b128 v20, v[130:133] offset:16384
	v_mfma_f32_16x16x32_f16 v[44:47], v[94:97], v[106:109], v[44:47]
	s_waitcnt vmcnt(3)
	ds_write_b128 v17, v[74:77] offset:49152
	v_mfma_f32_16x16x32_f16 v[78:81], v[94:97], v[110:113], v[78:81]
	s_waitcnt vmcnt(2)
	ds_write_b128 v18, v[138:141] offset:49152
	v_mfma_f32_16x16x32_f16 v[82:85], v[118:121], v[106:109], v[82:85]
	s_waitcnt vmcnt(1)
	ds_write_b128 v19, v[142:145] offset:49152
	v_mfma_f32_16x16x32_f16 v[86:89], v[118:121], v[110:113], v[86:89]
	s_waitcnt vmcnt(0)
	ds_write_b128 v20, v[154:157] offset:49152
	s_waitcnt lgkmcnt(5)
	v_mfma_f32_16x16x32_f16 v[28:31], v[122:125], v[106:109], v[28:31]
	ds_read_b128 v[106:109], v23 offset:4096
	v_mfma_f32_16x16x32_f16 v[32:35], v[122:125], v[110:113], v[32:35]
	ds_read_b128 v[110:113], v23 offset:6144
	s_waitcnt lgkmcnt(1)
	v_mfma_f32_16x16x32_f16 v[98:101], v[58:61], v[106:109], v[98:101]
	s_waitcnt lgkmcnt(0)
	v_mfma_f32_16x16x32_f16 v[52:55], v[58:61], v[110:113], v[52:55]
	global_load_dwordx4 v[58:61], v[0:1], off offset:2560
	v_mfma_f32_16x16x32_f16 v[102:105], v[94:97], v[106:109], v[102:105]
	v_mfma_f32_16x16x32_f16 v[24:27], v[94:97], v[110:113], v[24:27]
	v_mfma_f32_16x16x32_f16 v[114:117], v[118:121], v[106:109], v[114:117]
	v_mfma_f32_16x16x32_f16 v[40:43], v[118:121], v[110:113], v[40:43]
	v_mfma_f32_16x16x32_f16 v[70:73], v[122:125], v[106:109], v[70:73]
	global_load_dwordx4 v[106:109], v[2:3], off offset:2560
	global_load_dwordx4 v[134:137], v[4:5], off offset:2560
	global_load_dwordx4 v[158:161], v[14:15], off offset:2560
	global_load_dwordx4 v[94:97], v[10:11], off offset:2560
	global_load_dwordx4 v[162:165], v[12:13], off offset:2560
	global_load_dwordx4 v[166:169], v[8:9], off offset:2560
	global_load_dwordx4 v[190:193], v[6:7], off offset:2560
	s_waitcnt lgkmcnt(0)
	s_barrier
	v_mfma_f32_16x16x32_f16 v[48:51], v[122:125], v[110:113], v[48:51]
	ds_read_b128 v[62:65], v16 offset:49152
	ds_read_b128 v[90:93], v21 offset:16384
	s_waitcnt lgkmcnt(0)
	v_mfma_f32_16x16x32_f16 v[36:39], v[62:65], v[90:93], v[36:39]
	ds_read_b128 v[74:77], v16 offset:51200
	ds_read_b128 v[110:113], v21 offset:18432
	s_waitcnt lgkmcnt(0)
	v_mfma_f32_16x16x32_f16 v[66:69], v[62:65], v[110:113], v[66:69]
	ds_read_b128 v[118:121], v16 offset:53248
	v_mfma_f32_16x16x32_f16 v[44:47], v[74:77], v[90:93], v[44:47]
	ds_read_b128 v[122:125], v16 offset:55296
	v_mfma_f32_16x16x32_f16 v[78:81], v[74:77], v[110:113], v[78:81]
	s_waitcnt lgkmcnt(1)
	v_mfma_f32_16x16x32_f16 v[82:85], v[118:121], v[90:93], v[82:85]
	v_mfma_f32_16x16x32_f16 v[86:89], v[118:121], v[110:113], v[86:89]
	s_waitcnt lgkmcnt(0)
	v_mfma_f32_16x16x32_f16 v[28:31], v[122:125], v[90:93], v[28:31]
	ds_read_b128 v[90:93], v21 offset:20480
	v_mfma_f32_16x16x32_f16 v[32:35], v[122:125], v[110:113], v[32:35]
	ds_read_b128 v[110:113], v21 offset:22528
	s_waitcnt lgkmcnt(1)
	v_mfma_f32_16x16x32_f16 v[98:101], v[62:65], v[90:93], v[98:101]
	s_waitcnt lgkmcnt(0)
	v_mfma_f32_16x16x32_f16 v[52:55], v[62:65], v[110:113], v[52:55]
	ds_read_b128 v[62:65], v22 offset:49152
	v_mfma_f32_16x16x32_f16 v[102:105], v[74:77], v[90:93], v[102:105]
	v_mfma_f32_16x16x32_f16 v[24:27], v[74:77], v[110:113], v[24:27]
	ds_read_b128 v[74:77], v22 offset:51200
	v_mfma_f32_16x16x32_f16 v[114:117], v[118:121], v[90:93], v[114:117]
	s_waitcnt vmcnt(7)
	ds_write_b128 v17, v[58:61]
	s_waitcnt vmcnt(6)
	ds_write_b128 v18, v[106:109]
	v_mfma_f32_16x16x32_f16 v[40:43], v[118:121], v[110:113], v[40:43]
	ds_read_b128 v[118:121], v22 offset:53248
	s_waitcnt vmcnt(5)
	ds_write_b128 v19, v[134:137]
	v_mfma_f32_16x16x32_f16 v[70:73], v[122:125], v[90:93], v[70:73]
	ds_read_b128 v[90:93], v23 offset:16384
	v_mfma_f32_16x16x32_f16 v[48:51], v[122:125], v[110:113], v[48:51]
	ds_read_b128 v[110:113], v23 offset:18432
	s_waitcnt lgkmcnt(1)
	v_mfma_f32_16x16x32_f16 v[36:39], v[62:65], v[90:93], v[36:39]
	ds_read_b128 v[122:125], v22 offset:55296
	s_waitcnt lgkmcnt(1)
	v_mfma_f32_16x16x32_f16 v[66:69], v[62:65], v[110:113], v[66:69]
	s_waitcnt vmcnt(4)
	ds_write_b128 v20, v[158:161]
	v_mfma_f32_16x16x32_f16 v[44:47], v[74:77], v[90:93], v[44:47]
	s_waitcnt vmcnt(3)
	ds_write_b128 v17, v[94:97] offset:32768
	v_mfma_f32_16x16x32_f16 v[78:81], v[74:77], v[110:113], v[78:81]
	s_waitcnt vmcnt(2)
	ds_write_b128 v18, v[162:165] offset:32768
	v_mfma_f32_16x16x32_f16 v[82:85], v[118:121], v[90:93], v[82:85]
	s_waitcnt vmcnt(1)
	ds_write_b128 v19, v[166:169] offset:32768
	v_mfma_f32_16x16x32_f16 v[86:89], v[118:121], v[110:113], v[86:89]
	s_waitcnt vmcnt(0)
	ds_write_b128 v20, v[190:193] offset:32768
	s_waitcnt lgkmcnt(5)
	v_mfma_f32_16x16x32_f16 v[28:31], v[122:125], v[90:93], v[28:31]
	ds_read_b128 v[90:93], v23 offset:20480
	v_mfma_f32_16x16x32_f16 v[32:35], v[122:125], v[110:113], v[32:35]
	ds_read_b128 v[110:113], v23 offset:22528
	s_waitcnt lgkmcnt(1)
	v_mfma_f32_16x16x32_f16 v[98:101], v[62:65], v[90:93], v[98:101]
	s_waitcnt lgkmcnt(0)
	v_mfma_f32_16x16x32_f16 v[52:55], v[62:65], v[110:113], v[52:55]
	global_load_dwordx4 v[62:65], v[0:1], off offset:2688
	v_mfma_f32_16x16x32_f16 v[102:105], v[74:77], v[90:93], v[102:105]
	v_mfma_f32_16x16x32_f16 v[24:27], v[74:77], v[110:113], v[24:27]
	v_mfma_f32_16x16x32_f16 v[114:117], v[118:121], v[90:93], v[114:117]
	v_mfma_f32_16x16x32_f16 v[40:43], v[118:121], v[110:113], v[40:43]
	v_mfma_f32_16x16x32_f16 v[70:73], v[122:125], v[90:93], v[70:73]
	global_load_dwordx4 v[90:93], v[2:3], off offset:2688
	global_load_dwordx4 v[126:129], v[4:5], off offset:2688
	global_load_dwordx4 v[130:133], v[14:15], off offset:2688
	global_load_dwordx4 v[74:77], v[10:11], off offset:2688
	global_load_dwordx4 v[138:141], v[12:13], off offset:2688
	global_load_dwordx4 v[142:145], v[8:9], off offset:2688
	global_load_dwordx4 v[154:157], v[6:7], off offset:2688
	s_waitcnt lgkmcnt(0)
	s_barrier
; #define GL_LOAD(s_, kt_) if (VAR != 1) { a##s_##0 = GL_A(0, kt_); a##s_##1 = GL_A(1, kt_); a##s_##2 = GL_A(2, kt_); a##s_##3 = GL_A(3, kt_); b##s_##0 = GL_B(0, kt_); b##s_##1 = GL_B(1, kt_); b##s_##2 = GL_B(2, kt_); b##s_##3 = GL_B(3, kt_); }
; #define LDS_STORE(s_, buf_) if (VAR != 2) { LDS_ST1(sA, 0, buf_, a##s_##0) LDS_ST1(sA, 1, buf_, a##s_##1) LDS_ST1(sA, 2, buf_, a##s_##2) LDS_ST1(sA, 3, buf_, a##s_##3) LDS_ST1(sB, 0, buf_, b##s_##0) LDS_ST1(sB, 1, buf_, b##s_##1) LDS_ST1(sB, 2, buf_, b##s_##2) LDS_ST1(sB, 3, buf_, b##s_##3) }
;     ...
;   GL_LOAD(0, 0)
;   GL_LOAD(1, 1)
;   LDS_STORE(0, 0)
;   if (VAR != 4) __syncthreads();
; #pragma unroll
;   for (int kt = 0; kt < nk; kt += 2) {
;     if (kt + 2 < nk) { GL_LOAD(0, kt + 2) }
;     MMA_TILE(0)
;     LDS_STORE(1, 1)
;     if (VAR != 4) __syncthreads();
;     if (kt + 3 < nk) { GL_LOAD(1, kt + 3) }
;     MMA_TILE(1)
;     if (kt + 2 < nk) { LDS_STORE(0, 0) }
;     if (VAR != 4) __syncthreads();
	v_mfma_f32_16x16x32_f16 v[48:51], v[122:125], v[110:113], v[48:51]
	ds_read_b128 v[58:61], v16 offset:32768
	ds_read_b128 v[106:109], v21
	s_waitcnt lgkmcnt(0)
	v_mfma_f32_16x16x32_f16 v[36:39], v[58:61], v[106:109], v[36:39]
	ds_read_b128 v[94:97], v16 offset:34816
	ds_read_b128 v[110:113], v21 offset:2048
	s_waitcnt lgkmcnt(0)
	v_mfma_f32_16x16x32_f16 v[66:69], v[58:61], v[110:113], v[66:69]
	ds_read_b128 v[118:121], v16 offset:36864
	v_mfma_f32_16x16x32_f16 v[44:47], v[94:97], v[106:109], v[44:47]
	ds_read_b128 v[122:125], v16 offset:38912
	v_mfma_f32_16x16x32_f16 v[78:81], v[94:97], v[110:113], v[78:81]
	s_waitcnt lgkmcnt(1)
	v_mfma_f32_16x16x32_f16 v[82:85], v[118:121], v[106:109], v[82:85]
	v_mfma_f32_16x16x32_f16 v[86:89], v[118:121], v[110:113], v[86:89]
	s_waitcnt lgkmcnt(0)
	v_mfma_f32_16x16x32_f16 v[28:31], v[122:125], v[106:109], v[28:31]
	ds_read_b128 v[106:109], v21 offset:4096
	v_mfma_f32_16x16x32_f16 v[32:35], v[122:125], v[110:113], v[32:35]
	ds_read_b128 v[110:113], v21 offset:6144
	s_waitcnt lgkmcnt(1)
	v_mfma_f32_16x16x32_f16 v[98:101], v[58:61], v[106:109], v[98:101]
	s_waitcnt lgkmcnt(0)
	v_mfma_f32_16x16x32_f16 v[52:55], v[58:61], v[110:113], v[52:55]
	ds_read_b128 v[58:61], v22 offset:32768
	v_mfma_f32_16x16x32_f16 v[102:105], v[94:97], v[106:109], v[102:105]
	v_mfma_f32_16x16x32_f16 v[24:27], v[94:97], v[110:113], v[24:27]
	ds_read_b128 v[94:97], v22 offset:34816
	v_mfma_f32_16x16x32_f16 v[114:117], v[118:121], v[106:109], v[114:117]
	s_waitcnt vmcnt(7)
	ds_write_b128 v17, v[62:65] offset:16384
	s_waitcnt vmcnt(6)
	ds_write_b128 v18, v[90:93] offset:16384
	v_mfma_f32_16x16x32_f16 v[40:43], v[118:121], v[110:113], v[40:43]
	ds_read_b128 v[118:121], v22 offset:36864
	s_waitcnt vmcnt(5)
	ds_write_b128 v19, v[126:129] offset:16384
	v_mfma_f32_16x16x32_f16 v[70:73], v[122:125], v[106:109], v[70:73]
	ds_read_b128 v[106:109], v23
	v_mfma_f32_16x16x32_f16 v[48:51], v[122:125], v[110:113], v[48:51]
	ds_read_b128 v[110:113], v23 offset:2048
	s_waitcnt lgkmcnt(1)
	v_mfma_f32_16x16x32_f16 v[36:39], v[58:61], v[106:109], v[36:39]
	ds_read_b128 v[122:125], v22 offset:38912
	s_waitcnt lgkmcnt(1)
	v_mfma_f32_16x16x32_f16 v[66:69], v[58:61], v[110:113], v[66:69]
	s_waitcnt vmcnt(4)
	ds_write_b128 v20, v[130:133] offset:16384
	v_mfma_f32_16x16x32_f16 v[44:47], v[94:97], v[106:109], v[44:47]
	s_waitcnt vmcnt(3)
	ds_write_b128 v17, v[74:77] offset:49152
	v_mfma_f32_16x16x32_f16 v[78:81], v[94:97], v[110:113], v[78:81]
	s_waitcnt vmcnt(2)
	ds_write_b128 v18, v[138:141] offset:49152
	v_mfma_f32_16x16x32_f16 v[82:85], v[118:121], v[106:109], v[82:85]
	s_waitcnt vmcnt(1)
	ds_write_b128 v19, v[142:145] offset:49152
	v_mfma_f32_16x16x32_f16 v[86:89], v[118:121], v[110:113], v[86:89]
	s_waitcnt vmcnt(0)
	ds_write_b128 v20, v[154:157] offset:49152
	s_waitcnt lgkmcnt(5)
	v_mfma_f32_16x16x32_f16 v[28:31], v[122:125], v[106:109], v[28:31]
	ds_read_b128 v[106:109], v23 offset:4096
	v_mfma_f32_16x16x32_f16 v[32:35], v[122:125], v[110:113], v[32:35]
	ds_read_b128 v[110:113], v23 offset:6144
	s_waitcnt lgkmcnt(1)
	v_mfma_f32_16x16x32_f16 v[98:101], v[58:61], v[106:109], v[98:101]
	s_waitcnt lgkmcnt(0)
	v_mfma_f32_16x16x32_f16 v[52:55], v[58:61], v[110:113], v[52:55]
	global_load_dwordx4 v[58:61], v[0:1], off offset:2816
	v_mfma_f32_16x16x32_f16 v[102:105], v[94:97], v[106:109], v[102:105]
	v_mfma_f32_16x16x32_f16 v[24:27], v[94:97], v[110:113], v[24:27]
	v_mfma_f32_16x16x32_f16 v[114:117], v[118:121], v[106:109], v[114:117]
	v_mfma_f32_16x16x32_f16 v[40:43], v[118:121], v[110:113], v[40:43]
	v_mfma_f32_16x16x32_f16 v[70:73], v[122:125], v[106:109], v[70:73]
	global_load_dwordx4 v[106:109], v[2:3], off offset:2816
	global_load_dwordx4 v[134:137], v[4:5], off offset:2816
	global_load_dwordx4 v[158:161], v[14:15], off offset:2816
	global_load_dwordx4 v[94:97], v[10:11], off offset:2816
	global_load_dwordx4 v[162:165], v[12:13], off offset:2816
	global_load_dwordx4 v[166:169], v[8:9], off offset:2816
	global_load_dwordx4 v[190:193], v[6:7], off offset:2816
	s_waitcnt lgkmcnt(0)
	s_barrier
	v_mfma_f32_16x16x32_f16 v[48:51], v[122:125], v[110:113], v[48:51]
	ds_read_b128 v[62:65], v16 offset:49152
	ds_read_b128 v[90:93], v21 offset:16384
	s_waitcnt lgkmcnt(0)
	v_mfma_f32_16x16x32_f16 v[36:39], v[62:65], v[90:93], v[36:39]
	ds_read_b128 v[74:77], v16 offset:51200
	ds_read_b128 v[110:113], v21 offset:18432
	s_waitcnt lgkmcnt(0)
	v_mfma_f32_16x16x32_f16 v[66:69], v[62:65], v[110:113], v[66:69]
	ds_read_b128 v[118:121], v16 offset:53248
	v_mfma_f32_16x16x32_f16 v[44:47], v[74:77], v[90:93], v[44:47]
	ds_read_b128 v[122:125], v16 offset:55296
	v_mfma_f32_16x16x32_f16 v[78:81], v[74:77], v[110:113], v[78:81]
	s_waitcnt lgkmcnt(1)
	v_mfma_f32_16x16x32_f16 v[82:85], v[118:121], v[90:93], v[82:85]
	v_mfma_f32_16x16x32_f16 v[86:89], v[118:121], v[110:113], v[86:89]
	s_waitcnt lgkmcnt(0)
	v_mfma_f32_16x16x32_f16 v[28:31], v[122:125], v[90:93], v[28:31]
	ds_read_b128 v[90:93], v21 offset:20480
	v_mfma_f32_16x16x32_f16 v[32:35], v[122:125], v[110:113], v[32:35]
	ds_read_b128 v[110:113], v21 offset:22528
	s_waitcnt lgkmcnt(1)
	v_mfma_f32_16x16x32_f16 v[98:101], v[62:65], v[90:93], v[98:101]
	s_waitcnt lgkmcnt(0)
	v_mfma_f32_16x16x32_f16 v[52:55], v[62:65], v[110:113], v[52:55]
	ds_read_b128 v[62:65], v22 offset:49152
	v_mfma_f32_16x16x32_f16 v[102:105], v[74:77], v[90:93], v[102:105]
	v_mfma_f32_16x16x32_f16 v[24:27], v[74:77], v[110:113], v[24:27]
	ds_read_b128 v[74:77], v22 offset:51200
	v_mfma_f32_16x16x32_f16 v[114:117], v[118:121], v[90:93], v[114:117]
	s_waitcnt vmcnt(7)
	ds_write_b128 v17, v[58:61]
	s_waitcnt vmcnt(6)
; #define GL_LOAD(s_, kt_) if (VAR != 1) { a##s_##0 = GL_A(0, kt_); a##s_##1 = GL_A(1, kt_); a##s_##2 = GL_A(2, kt_); a##s_##3 = GL_A(3, kt_); b##s_##0 = GL_B(0, kt_); b##s_##1 = GL_B(1, kt_); b##s_##2 = GL_B(2, kt_); b##s_##3 = GL_B(3, kt_); }
; #define LDS_STORE(s_, buf_) if (VAR != 2) { LDS_ST1(sA, 0, buf_, a##s_##0) LDS_ST1(sA, 1, buf_, a##s_##1) LDS_ST1(sA, 2, buf_, a##s_##2) LDS_ST1(sA, 3, buf_, a##s_##3) LDS_ST1(sB, 0, buf_, b##s_##0) LDS_ST1(sB, 1, buf_, b##s_##1) LDS_ST1(sB, 2, buf_, b##s_##2) LDS_ST1(sB, 3, buf_, b##s_##3) }
;     ...
;   GL_LOAD(0, 0)
;   GL_LOAD(1, 1)
;   LDS_STORE(0, 0)
;   if (VAR != 4) __syncthreads();
; #pragma unroll
;   for (int kt = 0; kt < nk; kt += 2) {
;     if (kt + 2 < nk) { GL_LOAD(0, kt + 2) }
;     MMA_TILE(0)
;     LDS_STORE(1, 1)
;     if (VAR != 4) __syncthreads();
;     if (kt + 3 < nk) { GL_LOAD(1, kt + 3) }
;     MMA_TILE(1)
;     if (kt + 2 < nk) { LDS_STORE(0, 0) }
;     if (VAR != 4) __syncthreads();
	ds_write_b128 v18, v[106:109]
	v_mfma_f32_16x16x32_f16 v[40:43], v[118:121], v[110:113], v[40:43]
	ds_read_b128 v[118:121], v22 offset:53248
	s_waitcnt vmcnt(5)
	ds_write_b128 v19, v[134:137]
	v_mfma_f32_16x16x32_f16 v[70:73], v[122:125], v[90:93], v[70:73]
	ds_read_b128 v[90:93], v23 offset:16384
	v_mfma_f32_16x16x32_f16 v[48:51], v[122:125], v[110:113], v[48:51]
	ds_read_b128 v[110:113], v23 offset:18432
	s_waitcnt lgkmcnt(1)
	v_mfma_f32_16x16x32_f16 v[36:39], v[62:65], v[90:93], v[36:39]
	ds_read_b128 v[122:125], v22 offset:55296
	s_waitcnt lgkmcnt(1)
	v_mfma_f32_16x16x32_f16 v[66:69], v[62:65], v[110:113], v[66:69]
	s_waitcnt vmcnt(4)
	ds_write_b128 v20, v[158:161]
	v_mfma_f32_16x16x32_f16 v[44:47], v[74:77], v[90:93], v[44:47]
	s_waitcnt vmcnt(3)
	ds_write_b128 v17, v[94:97] offset:32768
	v_mfma_f32_16x16x32_f16 v[78:81], v[74:77], v[110:113], v[78:81]
	s_waitcnt vmcnt(2)
	ds_write_b128 v18, v[162:165] offset:32768
	v_mfma_f32_16x16x32_f16 v[82:85], v[118:121], v[90:93], v[82:85]
	s_waitcnt vmcnt(1)
	ds_write_b128 v19, v[166:169] offset:32768
	v_mfma_f32_16x16x32_f16 v[86:89], v[118:121], v[110:113], v[86:89]
	s_waitcnt vmcnt(0)
	ds_write_b128 v20, v[190:193] offset:32768
	s_waitcnt lgkmcnt(5)
	v_mfma_f32_16x16x32_f16 v[28:31], v[122:125], v[90:93], v[28:31]
	ds_read_b128 v[90:93], v23 offset:20480
	v_mfma_f32_16x16x32_f16 v[32:35], v[122:125], v[110:113], v[32:35]
	ds_read_b128 v[110:113], v23 offset:22528
	s_waitcnt lgkmcnt(1)
	v_mfma_f32_16x16x32_f16 v[98:101], v[62:65], v[90:93], v[98:101]
	s_waitcnt lgkmcnt(0)
	v_mfma_f32_16x16x32_f16 v[52:55], v[62:65], v[110:113], v[52:55]
	global_load_dwordx4 v[62:65], v[0:1], off offset:2944
	v_mfma_f32_16x16x32_f16 v[102:105], v[74:77], v[90:93], v[102:105]
	v_mfma_f32_16x16x32_f16 v[24:27], v[74:77], v[110:113], v[24:27]
	v_mfma_f32_16x16x32_f16 v[114:117], v[118:121], v[90:93], v[114:117]
	v_mfma_f32_16x16x32_f16 v[40:43], v[118:121], v[110:113], v[40:43]
	v_mfma_f32_16x16x32_f16 v[70:73], v[122:125], v[90:93], v[70:73]
	global_load_dwordx4 v[90:93], v[2:3], off offset:2944
	global_load_dwordx4 v[126:129], v[4:5], off offset:2944
	global_load_dwordx4 v[130:133], v[14:15], off offset:2944
	global_load_dwordx4 v[74:77], v[10:11], off offset:2944
	global_load_dwordx4 v[138:141], v[12:13], off offset:2944
	global_load_dwordx4 v[142:145], v[8:9], off offset:2944
	global_load_dwordx4 v[154:157], v[6:7], off offset:2944
	s_waitcnt lgkmcnt(0)
	s_barrier
	v_mfma_f32_16x16x32_f16 v[48:51], v[122:125], v[110:113], v[48:51]
	ds_read_b128 v[58:61], v16 offset:32768
	ds_read_b128 v[106:109], v21
	s_waitcnt lgkmcnt(0)
	v_mfma_f32_16x16x32_f16 v[36:39], v[58:61], v[106:109], v[36:39]
	ds_read_b128 v[94:97], v16 offset:34816
	ds_read_b128 v[110:113], v21 offset:2048
	s_waitcnt lgkmcnt(0)
	v_mfma_f32_16x16x32_f16 v[66:69], v[58:61], v[110:113], v[66:69]
	ds_read_b128 v[118:121], v16 offset:36864
	v_mfma_f32_16x16x32_f16 v[44:47], v[94:97], v[106:109], v[44:47]
	ds_read_b128 v[122:125], v16 offset:38912
	v_mfma_f32_16x16x32_f16 v[78:81], v[94:97], v[110:113], v[78:81]
	s_waitcnt lgkmcnt(1)
	v_mfma_f32_16x16x32_f16 v[82:85], v[118:121], v[106:109], v[82:85]
	v_mfma_f32_16x16x32_f16 v[86:89], v[118:121], v[110:113], v[86:89]
	s_waitcnt lgkmcnt(0)
	v_mfma_f32_16x16x32_f16 v[28:31], v[122:125], v[106:109], v[28:31]
	ds_read_b128 v[106:109], v21 offset:4096
	v_mfma_f32_16x16x32_f16 v[32:35], v[122:125], v[110:113], v[32:35]
	ds_read_b128 v[110:113], v21 offset:6144
	s_waitcnt lgkmcnt(1)
	v_mfma_f32_16x16x32_f16 v[98:101], v[58:61], v[106:109], v[98:101]
	s_waitcnt lgkmcnt(0)
	v_mfma_f32_16x16x32_f16 v[52:55], v[58:61], v[110:113], v[52:55]
	ds_read_b128 v[58:61], v22 offset:32768
	v_mfma_f32_16x16x32_f16 v[102:105], v[94:97], v[106:109], v[102:105]
	v_mfma_f32_16x16x32_f16 v[24:27], v[94:97], v[110:113], v[24:27]
	ds_read_b128 v[94:97], v22 offset:34816
	v_mfma_f32_16x16x32_f16 v[114:117], v[118:121], v[106:109], v[114:117]
	s_waitcnt vmcnt(7)
	ds_write_b128 v17, v[62:65] offset:16384
	s_waitcnt vmcnt(6)
	ds_write_b128 v18, v[90:93] offset:16384
	v_mfma_f32_16x16x32_f16 v[40:43], v[118:121], v[110:113], v[40:43]
	ds_read_b128 v[118:121], v22 offset:36864
	s_waitcnt vmcnt(5)
	ds_write_b128 v19, v[126:129] offset:16384
	v_mfma_f32_16x16x32_f16 v[70:73], v[122:125], v[106:109], v[70:73]
	ds_read_b128 v[106:109], v23
	v_mfma_f32_16x16x32_f16 v[48:51], v[122:125], v[110:113], v[48:51]
	ds_read_b128 v[110:113], v23 offset:2048
	s_waitcnt lgkmcnt(1)
	v_mfma_f32_16x16x32_f16 v[36:39], v[58:61], v[106:109], v[36:39]
	ds_read_b128 v[122:125], v22 offset:38912
	s_waitcnt lgkmcnt(1)
	v_mfma_f32_16x16x32_f16 v[66:69], v[58:61], v[110:113], v[66:69]
	s_waitcnt vmcnt(4)
	ds_write_b128 v20, v[130:133] offset:16384
	v_mfma_f32_16x16x32_f16 v[44:47], v[94:97], v[106:109], v[44:47]
	s_waitcnt vmcnt(3)
	ds_write_b128 v17, v[74:77] offset:49152
	v_mfma_f32_16x16x32_f16 v[78:81], v[94:97], v[110:113], v[78:81]
	s_waitcnt vmcnt(2)
	ds_write_b128 v18, v[138:141] offset:49152
	v_mfma_f32_16x16x32_f16 v[82:85], v[118:121], v[106:109], v[82:85]
	s_waitcnt vmcnt(1)
	ds_write_b128 v19, v[142:145] offset:49152
	v_mfma_f32_16x16x32_f16 v[86:89], v[118:121], v[110:113], v[86:89]
	s_waitcnt vmcnt(0)
	ds_write_b128 v20, v[154:157] offset:49152
	s_waitcnt lgkmcnt(5)
	v_mfma_f32_16x16x32_f16 v[28:31], v[122:125], v[106:109], v[28:31]
	ds_read_b128 v[106:109], v23 offset:4096
	v_mfma_f32_16x16x32_f16 v[32:35], v[122:125], v[110:113], v[32:35]
	ds_read_b128 v[110:113], v23 offset:6144
	s_waitcnt lgkmcnt(1)
	v_mfma_f32_16x16x32_f16 v[98:101], v[58:61], v[106:109], v[98:101]
	s_waitcnt lgkmcnt(0)
	v_mfma_f32_16x16x32_f16 v[52:55], v[58:61], v[110:113], v[52:55]
	global_load_dwordx4 v[58:61], v[0:1], off offset:3072
	v_mfma_f32_16x16x32_f16 v[102:105], v[94:97], v[106:109], v[102:105]
	v_mfma_f32_16x16x32_f16 v[24:27], v[94:97], v[110:113], v[24:27]
	v_mfma_f32_16x16x32_f16 v[114:117], v[118:121], v[106:109], v[114:117]
	v_mfma_f32_16x16x32_f16 v[40:43], v[118:121], v[110:113], v[40:43]
	v_mfma_f32_16x16x32_f16 v[70:73], v[122:125], v[106:109], v[70:73]
	global_load_dwordx4 v[106:109], v[2:3], off offset:3072
	global_load_dwordx4 v[134:137], v[4:5], off offset:3072
	global_load_dwordx4 v[158:161], v[14:15], off offset:3072
	global_load_dwordx4 v[94:97], v[10:11], off offset:3072
	global_load_dwordx4 v[162:165], v[12:13], off offset:3072
	global_load_dwordx4 v[166:169], v[8:9], off offset:3072
	global_load_dwordx4 v[190:193], v[6:7], off offset:3072
	s_waitcnt lgkmcnt(0)
	s_barrier
; #define GL_LOAD(s_, kt_) if (VAR != 1) { a##s_##0 = GL_A(0, kt_); a##s_##1 = GL_A(1, kt_); a##s_##2 = GL_A(2, kt_); a##s_##3 = GL_A(3, kt_); b##s_##0 = GL_B(0, kt_); b##s_##1 = GL_B(1, kt_); b##s_##2 = GL_B(2, kt_); b##s_##3 = GL_B(3, kt_); }
; #define LDS_STORE(s_, buf_) if (VAR != 2) { LDS_ST1(sA, 0, buf_, a##s_##0) LDS_ST1(sA, 1, buf_, a##s_##1) LDS_ST1(sA, 2, buf_, a##s_##2) LDS_ST1(sA, 3, buf_, a##s_##3) LDS_ST1(sB, 0, buf_, b##s_##0) LDS_ST1(sB, 1, buf_, b##s_##1) LDS_ST1(sB, 2, buf_, b##s_##2) LDS_ST1(sB, 3, buf_, b##s_##3) }
;     ...
;   GL_LOAD(0, 0)
;   GL_LOAD(1, 1)
;   LDS_STORE(0, 0)
;   if (VAR != 4) __syncthreads();
; #pragma unroll
;   for (int kt = 0; kt < nk; kt += 2) {
;     if (kt + 2 < nk) { GL_LOAD(0, kt + 2) }
;     MMA_TILE(0)
;     LDS_STORE(1, 1)
;     if (VAR != 4) __syncthreads();
;     if (kt + 3 < nk) { GL_LOAD(1, kt + 3) }
;     MMA_TILE(1)
;     if (kt + 2 < nk) { LDS_STORE(0, 0) }
;     if (VAR != 4) __syncthreads();
	v_mfma_f32_16x16x32_f16 v[48:51], v[122:125], v[110:113], v[48:51]
	ds_read_b128 v[62:65], v16 offset:49152
	ds_read_b128 v[90:93], v21 offset:16384
	s_waitcnt lgkmcnt(0)
	v_mfma_f32_16x16x32_f16 v[36:39], v[62:65], v[90:93], v[36:39]
	ds_read_b128 v[74:77], v16 offset:51200
	ds_read_b128 v[110:113], v21 offset:18432
	s_waitcnt lgkmcnt(0)
	v_mfma_f32_16x16x32_f16 v[66:69], v[62:65], v[110:113], v[66:69]
	ds_read_b128 v[118:121], v16 offset:53248
	v_mfma_f32_16x16x32_f16 v[44:47], v[74:77], v[90:93], v[44:47]
	ds_read_b128 v[122:125], v16 offset:55296
	v_mfma_f32_16x16x32_f16 v[78:81], v[74:77], v[110:113], v[78:81]
	s_waitcnt lgkmcnt(1)
	v_mfma_f32_16x16x32_f16 v[82:85], v[118:121], v[90:93], v[82:85]
	v_mfma_f32_16x16x32_f16 v[86:89], v[118:121], v[110:113], v[86:89]
	s_waitcnt lgkmcnt(0)
	v_mfma_f32_16x16x32_f16 v[28:31], v[122:125], v[90:93], v[28:31]
	ds_read_b128 v[90:93], v21 offset:20480
	v_mfma_f32_16x16x32_f16 v[32:35], v[122:125], v[110:113], v[32:35]
	ds_read_b128 v[110:113], v21 offset:22528
	s_waitcnt lgkmcnt(1)
	v_mfma_f32_16x16x32_f16 v[98:101], v[62:65], v[90:93], v[98:101]
	s_waitcnt lgkmcnt(0)
	v_mfma_f32_16x16x32_f16 v[52:55], v[62:65], v[110:113], v[52:55]
	ds_read_b128 v[62:65], v22 offset:49152
	v_mfma_f32_16x16x32_f16 v[102:105], v[74:77], v[90:93], v[102:105]
	v_mfma_f32_16x16x32_f16 v[24:27], v[74:77], v[110:113], v[24:27]
	ds_read_b128 v[74:77], v22 offset:51200
	v_mfma_f32_16x16x32_f16 v[114:117], v[118:121], v[90:93], v[114:117]
	s_waitcnt vmcnt(7)
	ds_write_b128 v17, v[58:61]
	s_waitcnt vmcnt(6)
	ds_write_b128 v18, v[106:109]
	v_mfma_f32_16x16x32_f16 v[40:43], v[118:121], v[110:113], v[40:43]
	ds_read_b128 v[118:121], v22 offset:53248
	s_waitcnt vmcnt(5)
	ds_write_b128 v19, v[134:137]
	v_mfma_f32_16x16x32_f16 v[70:73], v[122:125], v[90:93], v[70:73]
	ds_read_b128 v[90:93], v23 offset:16384
	v_mfma_f32_16x16x32_f16 v[48:51], v[122:125], v[110:113], v[48:51]
	ds_read_b128 v[110:113], v23 offset:18432
	s_waitcnt lgkmcnt(1)
	v_mfma_f32_16x16x32_f16 v[36:39], v[62:65], v[90:93], v[36:39]
	ds_read_b128 v[122:125], v22 offset:55296
	s_waitcnt lgkmcnt(1)
	v_mfma_f32_16x16x32_f16 v[66:69], v[62:65], v[110:113], v[66:69]
	s_waitcnt vmcnt(4)
	ds_write_b128 v20, v[158:161]
	v_mfma_f32_16x16x32_f16 v[44:47], v[74:77], v[90:93], v[44:47]
	s_waitcnt vmcnt(3)
	ds_write_b128 v17, v[94:97] offset:32768
	v_mfma_f32_16x16x32_f16 v[78:81], v[74:77], v[110:113], v[78:81]
	s_waitcnt vmcnt(2)
	ds_write_b128 v18, v[162:165] offset:32768
	v_mfma_f32_16x16x32_f16 v[82:85], v[118:121], v[90:93], v[82:85]
	s_waitcnt vmcnt(1)
	ds_write_b128 v19, v[166:169] offset:32768
	v_mfma_f32_16x16x32_f16 v[86:89], v[118:121], v[110:113], v[86:89]
	s_waitcnt vmcnt(0)
	ds_write_b128 v20, v[190:193] offset:32768
	s_waitcnt lgkmcnt(5)
	v_mfma_f32_16x16x32_f16 v[28:31], v[122:125], v[90:93], v[28:31]
	ds_read_b128 v[90:93], v23 offset:20480
	v_mfma_f32_16x16x32_f16 v[32:35], v[122:125], v[110:113], v[32:35]
	ds_read_b128 v[110:113], v23 offset:22528
	s_waitcnt lgkmcnt(1)
	v_mfma_f32_16x16x32_f16 v[98:101], v[62:65], v[90:93], v[98:101]
	s_waitcnt lgkmcnt(0)
	v_mfma_f32_16x16x32_f16 v[52:55], v[62:65], v[110:113], v[52:55]
	global_load_dwordx4 v[62:65], v[0:1], off offset:3200
	v_mfma_f32_16x16x32_f16 v[102:105], v[74:77], v[90:93], v[102:105]
	v_mfma_f32_16x16x32_f16 v[24:27], v[74:77], v[110:113], v[24:27]
	v_mfma_f32_16x16x32_f16 v[114:117], v[118:121], v[90:93], v[114:117]
	v_mfma_f32_16x16x32_f16 v[40:43], v[118:121], v[110:113], v[40:43]
	v_mfma_f32_16x16x32_f16 v[70:73], v[122:125], v[90:93], v[70:73]
	global_load_dwordx4 v[90:93], v[2:3], off offset:3200
	global_load_dwordx4 v[126:129], v[4:5], off offset:3200
	global_load_dwordx4 v[130:133], v[14:15], off offset:3200
	global_load_dwordx4 v[74:77], v[10:11], off offset:3200
	global_load_dwordx4 v[138:141], v[12:13], off offset:3200
	global_load_dwordx4 v[142:145], v[8:9], off offset:3200
	global_load_dwordx4 v[154:157], v[6:7], off offset:3200
	s_waitcnt lgkmcnt(0)
	s_barrier
	v_mfma_f32_16x16x32_f16 v[48:51], v[122:125], v[110:113], v[48:51]
	ds_read_b128 v[58:61], v16 offset:32768
	ds_read_b128 v[106:109], v21
	s_waitcnt lgkmcnt(0)
	v_mfma_f32_16x16x32_f16 v[36:39], v[58:61], v[106:109], v[36:39]
	ds_read_b128 v[94:97], v16 offset:34816
	ds_read_b128 v[110:113], v21 offset:2048
	s_waitcnt lgkmcnt(0)
	v_mfma_f32_16x16x32_f16 v[66:69], v[58:61], v[110:113], v[66:69]
	ds_read_b128 v[118:121], v16 offset:36864
	v_mfma_f32_16x16x32_f16 v[44:47], v[94:97], v[106:109], v[44:47]
	ds_read_b128 v[122:125], v16 offset:38912
	v_mfma_f32_16x16x32_f16 v[78:81], v[94:97], v[110:113], v[78:81]
	s_waitcnt lgkmcnt(1)
	v_mfma_f32_16x16x32_f16 v[82:85], v[118:121], v[106:109], v[82:85]
	v_mfma_f32_16x16x32_f16 v[86:89], v[118:121], v[110:113], v[86:89]
	s_waitcnt lgkmcnt(0)
	v_mfma_f32_16x16x32_f16 v[28:31], v[122:125], v[106:109], v[28:31]
	ds_read_b128 v[106:109], v21 offset:4096
	v_mfma_f32_16x16x32_f16 v[32:35], v[122:125], v[110:113], v[32:35]
	ds_read_b128 v[110:113], v21 offset:6144
	s_waitcnt lgkmcnt(1)
	v_mfma_f32_16x16x32_f16 v[98:101], v[58:61], v[106:109], v[98:101]
	s_waitcnt lgkmcnt(0)
	v_mfma_f32_16x16x32_f16 v[52:55], v[58:61], v[110:113], v[52:55]
	ds_read_b128 v[58:61], v22 offset:32768
	v_mfma_f32_16x16x32_f16 v[102:105], v[94:97], v[106:109], v[102:105]
	v_mfma_f32_16x16x32_f16 v[24:27], v[94:97], v[110:113], v[24:27]
	ds_read_b128 v[94:97], v22 offset:34816
	v_mfma_f32_16x16x32_f16 v[114:117], v[118:121], v[106:109], v[114:117]
	s_waitcnt vmcnt(7)
	ds_write_b128 v17, v[62:65] offset:16384
	s_waitcnt vmcnt(6)
; #define GL_LOAD(s_, kt_) if (VAR != 1) { a##s_##0 = GL_A(0, kt_); a##s_##1 = GL_A(1, kt_); a##s_##2 = GL_A(2, kt_); a##s_##3 = GL_A(3, kt_); b##s_##0 = GL_B(0, kt_); b##s_##1 = GL_B(1, kt_); b##s_##2 = GL_B(2, kt_); b##s_##3 = GL_B(3, kt_); }
; #define LDS_STORE(s_, buf_) if (VAR != 2) { LDS_ST1(sA, 0, buf_, a##s_##0) LDS_ST1(sA, 1, buf_, a##s_##1) LDS_ST1(sA, 2, buf_, a##s_##2) LDS_ST1(sA, 3, buf_, a##s_##3) LDS_ST1(sB, 0, buf_, b##s_##0) LDS_ST1(sB, 1, buf_, b##s_##1) LDS_ST1(sB, 2, buf_, b##s_##2) LDS_ST1(sB, 3, buf_, b##s_##3) }
;     ...
;   GL_LOAD(0, 0)
;   GL_LOAD(1, 1)
;   LDS_STORE(0, 0)
;   if (VAR != 4) __syncthreads();
; #pragma unroll
;   for (int kt = 0; kt < nk; kt += 2) {
;     if (kt + 2 < nk) { GL_LOAD(0, kt + 2) }
;     MMA_TILE(0)
;     LDS_STORE(1, 1)
;     if (VAR != 4) __syncthreads();
;     if (kt + 3 < nk) { GL_LOAD(1, kt + 3) }
;     MMA_TILE(1)
;     if (kt + 2 < nk) { LDS_STORE(0, 0) }
;     if (VAR != 4) __syncthreads();
	ds_write_b128 v18, v[90:93] offset:16384
	v_mfma_f32_16x16x32_f16 v[40:43], v[118:121], v[110:113], v[40:43]
	ds_read_b128 v[118:121], v22 offset:36864
	s_waitcnt vmcnt(5)
	ds_write_b128 v19, v[126:129] offset:16384
	v_mfma_f32_16x16x32_f16 v[70:73], v[122:125], v[106:109], v[70:73]
	ds_read_b128 v[106:109], v23
	v_mfma_f32_16x16x32_f16 v[48:51], v[122:125], v[110:113], v[48:51]
	ds_read_b128 v[110:113], v23 offset:2048
	s_waitcnt lgkmcnt(1)
	v_mfma_f32_16x16x32_f16 v[36:39], v[58:61], v[106:109], v[36:39]
	ds_read_b128 v[122:125], v22 offset:38912
	s_waitcnt lgkmcnt(1)
	v_mfma_f32_16x16x32_f16 v[66:69], v[58:61], v[110:113], v[66:69]
	s_waitcnt vmcnt(4)
	ds_write_b128 v20, v[130:133] offset:16384
	v_mfma_f32_16x16x32_f16 v[44:47], v[94:97], v[106:109], v[44:47]
	s_waitcnt vmcnt(3)
	ds_write_b128 v17, v[74:77] offset:49152
	v_mfma_f32_16x16x32_f16 v[78:81], v[94:97], v[110:113], v[78:81]
	s_waitcnt vmcnt(2)
	ds_write_b128 v18, v[138:141] offset:49152
	v_mfma_f32_16x16x32_f16 v[82:85], v[118:121], v[106:109], v[82:85]
	s_waitcnt vmcnt(1)
	ds_write_b128 v19, v[142:145] offset:49152
	v_mfma_f32_16x16x32_f16 v[86:89], v[118:121], v[110:113], v[86:89]
	s_waitcnt vmcnt(0)
	ds_write_b128 v20, v[154:157] offset:49152
	s_waitcnt lgkmcnt(5)
	v_mfma_f32_16x16x32_f16 v[28:31], v[122:125], v[106:109], v[28:31]
	ds_read_b128 v[106:109], v23 offset:4096
	v_mfma_f32_16x16x32_f16 v[32:35], v[122:125], v[110:113], v[32:35]
	ds_read_b128 v[110:113], v23 offset:6144
	s_waitcnt lgkmcnt(1)
	v_mfma_f32_16x16x32_f16 v[98:101], v[58:61], v[106:109], v[98:101]
	s_waitcnt lgkmcnt(0)
	v_mfma_f32_16x16x32_f16 v[52:55], v[58:61], v[110:113], v[52:55]
	global_load_dwordx4 v[58:61], v[0:1], off offset:3328
	v_mfma_f32_16x16x32_f16 v[102:105], v[94:97], v[106:109], v[102:105]
	v_mfma_f32_16x16x32_f16 v[24:27], v[94:97], v[110:113], v[24:27]
	v_mfma_f32_16x16x32_f16 v[114:117], v[118:121], v[106:109], v[114:117]
	v_mfma_f32_16x16x32_f16 v[40:43], v[118:121], v[110:113], v[40:43]
	v_mfma_f32_16x16x32_f16 v[70:73], v[122:125], v[106:109], v[70:73]
	global_load_dwordx4 v[106:109], v[2:3], off offset:3328
	global_load_dwordx4 v[134:137], v[4:5], off offset:3328
	global_load_dwordx4 v[158:161], v[14:15], off offset:3328
	global_load_dwordx4 v[94:97], v[10:11], off offset:3328
	global_load_dwordx4 v[162:165], v[12:13], off offset:3328
	global_load_dwordx4 v[166:169], v[8:9], off offset:3328
	global_load_dwordx4 v[190:193], v[6:7], off offset:3328
	s_waitcnt lgkmcnt(0)
	s_barrier
	v_mfma_f32_16x16x32_f16 v[48:51], v[122:125], v[110:113], v[48:51]
	ds_read_b128 v[62:65], v16 offset:49152
	ds_read_b128 v[90:93], v21 offset:16384
	s_waitcnt lgkmcnt(0)
	v_mfma_f32_16x16x32_f16 v[36:39], v[62:65], v[90:93], v[36:39]
	ds_read_b128 v[74:77], v16 offset:51200
	ds_read_b128 v[110:113], v21 offset:18432
	s_waitcnt lgkmcnt(0)
	v_mfma_f32_16x16x32_f16 v[66:69], v[62:65], v[110:113], v[66:69]
	ds_read_b128 v[118:121], v16 offset:53248
	v_mfma_f32_16x16x32_f16 v[44:47], v[74:77], v[90:93], v[44:47]
	ds_read_b128 v[122:125], v16 offset:55296
	v_mfma_f32_16x16x32_f16 v[78:81], v[74:77], v[110:113], v[78:81]
	s_waitcnt lgkmcnt(1)
	v_mfma_f32_16x16x32_f16 v[82:85], v[118:121], v[90:93], v[82:85]
	v_mfma_f32_16x16x32_f16 v[86:89], v[118:121], v[110:113], v[86:89]
	s_waitcnt lgkmcnt(0)
	v_mfma_f32_16x16x32_f16 v[28:31], v[122:125], v[90:93], v[28:31]
	ds_read_b128 v[90:93], v21 offset:20480
	v_mfma_f32_16x16x32_f16 v[32:35], v[122:125], v[110:113], v[32:35]
	ds_read_b128 v[110:113], v21 offset:22528
	s_waitcnt lgkmcnt(1)
	v_mfma_f32_16x16x32_f16 v[98:101], v[62:65], v[90:93], v[98:101]
	s_waitcnt lgkmcnt(0)
	v_mfma_f32_16x16x32_f16 v[52:55], v[62:65], v[110:113], v[52:55]
	ds_read_b128 v[62:65], v22 offset:49152
	v_mfma_f32_16x16x32_f16 v[102:105], v[74:77], v[90:93], v[102:105]
	v_mfma_f32_16x16x32_f16 v[24:27], v[74:77], v[110:113], v[24:27]
	ds_read_b128 v[74:77], v22 offset:51200
	v_mfma_f32_16x16x32_f16 v[114:117], v[118:121], v[90:93], v[114:117]
	s_waitcnt vmcnt(7)
	ds_write_b128 v17, v[58:61]
	s_waitcnt vmcnt(6)
	ds_write_b128 v18, v[106:109]
	v_mfma_f32_16x16x32_f16 v[40:43], v[118:121], v[110:113], v[40:43]
	ds_read_b128 v[118:121], v22 offset:53248
	s_waitcnt vmcnt(5)
	ds_write_b128 v19, v[134:137]
	v_mfma_f32_16x16x32_f16 v[70:73], v[122:125], v[90:93], v[70:73]
	ds_read_b128 v[90:93], v23 offset:16384
	v_mfma_f32_16x16x32_f16 v[48:51], v[122:125], v[110:113], v[48:51]
	ds_read_b128 v[110:113], v23 offset:18432
	s_waitcnt lgkmcnt(1)
	v_mfma_f32_16x16x32_f16 v[36:39], v[62:65], v[90:93], v[36:39]
	ds_read_b128 v[122:125], v22 offset:55296
	s_waitcnt lgkmcnt(1)
	v_mfma_f32_16x16x32_f16 v[66:69], v[62:65], v[110:113], v[66:69]
	s_waitcnt vmcnt(4)
	ds_write_b128 v20, v[158:161]
	v_mfma_f32_16x16x32_f16 v[44:47], v[74:77], v[90:93], v[44:47]
	s_waitcnt vmcnt(3)
	ds_write_b128 v17, v[94:97] offset:32768
	v_mfma_f32_16x16x32_f16 v[78:81], v[74:77], v[110:113], v[78:81]
	s_waitcnt vmcnt(2)
	ds_write_b128 v18, v[162:165] offset:32768
	v_mfma_f32_16x16x32_f16 v[82:85], v[118:121], v[90:93], v[82:85]
	s_waitcnt vmcnt(1)
	ds_write_b128 v19, v[166:169] offset:32768
	v_mfma_f32_16x16x32_f16 v[86:89], v[118:121], v[110:113], v[86:89]
	s_waitcnt vmcnt(0)
	ds_write_b128 v20, v[190:193] offset:32768
	s_waitcnt lgkmcnt(5)
	v_mfma_f32_16x16x32_f16 v[28:31], v[122:125], v[90:93], v[28:31]
	ds_read_b128 v[90:93], v23 offset:20480
	v_mfma_f32_16x16x32_f16 v[32:35], v[122:125], v[110:113], v[32:35]
	ds_read_b128 v[110:113], v23 offset:22528
	s_waitcnt lgkmcnt(1)
	v_mfma_f32_16x16x32_f16 v[98:101], v[62:65], v[90:93], v[98:101]
	s_waitcnt lgkmcnt(0)
	v_mfma_f32_16x16x32_f16 v[52:55], v[62:65], v[110:113], v[52:55]
	global_load_dwordx4 v[62:65], v[0:1], off offset:3456
	v_mfma_f32_16x16x32_f16 v[102:105], v[74:77], v[90:93], v[102:105]
	v_mfma_f32_16x16x32_f16 v[24:27], v[74:77], v[110:113], v[24:27]
	v_mfma_f32_16x16x32_f16 v[114:117], v[118:121], v[90:93], v[114:117]
	v_mfma_f32_16x16x32_f16 v[40:43], v[118:121], v[110:113], v[40:43]
	v_mfma_f32_16x16x32_f16 v[70:73], v[122:125], v[90:93], v[70:73]
	global_load_dwordx4 v[90:93], v[2:3], off offset:3456
	global_load_dwordx4 v[126:129], v[4:5], off offset:3456
	global_load_dwordx4 v[130:133], v[14:15], off offset:3456
	global_load_dwordx4 v[74:77], v[10:11], off offset:3456
	global_load_dwordx4 v[138:141], v[12:13], off offset:3456
	global_load_dwordx4 v[142:145], v[8:9], off offset:3456
	global_load_dwordx4 v[154:157], v[6:7], off offset:3456
	s_waitcnt lgkmcnt(0)
	s_barrier
; #define GL_LOAD(s_, kt_) if (VAR != 1) { a##s_##0 = GL_A(0, kt_); a##s_##1 = GL_A(1, kt_); a##s_##2 = GL_A(2, kt_); a##s_##3 = GL_A(3, kt_); b##s_##0 = GL_B(0, kt_); b##s_##1 = GL_B(1, kt_); b##s_##2 = GL_B(2, kt_); b##s_##3 = GL_B(3, kt_); }
; #define LDS_STORE(s_, buf_) if (VAR != 2) { LDS_ST1(sA, 0, buf_, a##s_##0) LDS_ST1(sA, 1, buf_, a##s_##1) LDS_ST1(sA, 2, buf_, a##s_##2) LDS_ST1(sA, 3, buf_, a##s_##3) LDS_ST1(sB, 0, buf_, b##s_##0) LDS_ST1(sB, 1, buf_, b##s_##1) LDS_ST1(sB, 2, buf_, b##s_##2) LDS_ST1(sB, 3, buf_, b##s_##3) }
;     ...
;   GL_LOAD(0, 0)
;   GL_LOAD(1, 1)
;   LDS_STORE(0, 0)
;   if (VAR != 4) __syncthreads();
; #pragma unroll
;   for (int kt = 0; kt < nk; kt += 2) {
;     if (kt + 2 < nk) { GL_LOAD(0, kt + 2) }
;     MMA_TILE(0)
;     LDS_STORE(1, 1)
;     if (VAR != 4) __syncthreads();
;     if (kt + 3 < nk) { GL_LOAD(1, kt + 3) }
;     MMA_TILE(1)
;     if (kt + 2 < nk) { LDS_STORE(0, 0) }
;     if (VAR != 4) __syncthreads();
;   }
	v_mfma_f32_16x16x32_f16 v[48:51], v[122:125], v[110:113], v[48:51]
	ds_read_b128 v[58:61], v16 offset:32768
	ds_read_b128 v[106:109], v21
	s_waitcnt lgkmcnt(0)
	v_mfma_f32_16x16x32_f16 v[36:39], v[58:61], v[106:109], v[36:39]
	ds_read_b128 v[94:97], v16 offset:34816
	ds_read_b128 v[110:113], v21 offset:2048
	s_waitcnt lgkmcnt(0)
	v_mfma_f32_16x16x32_f16 v[66:69], v[58:61], v[110:113], v[66:69]
	ds_read_b128 v[118:121], v16 offset:36864
	v_mfma_f32_16x16x32_f16 v[44:47], v[94:97], v[106:109], v[44:47]
	ds_read_b128 v[122:125], v16 offset:38912
	v_mfma_f32_16x16x32_f16 v[78:81], v[94:97], v[110:113], v[78:81]
	s_waitcnt lgkmcnt(1)
	v_mfma_f32_16x16x32_f16 v[82:85], v[118:121], v[106:109], v[82:85]
	v_mfma_f32_16x16x32_f16 v[86:89], v[118:121], v[110:113], v[86:89]
	s_waitcnt lgkmcnt(0)
	v_mfma_f32_16x16x32_f16 v[28:31], v[122:125], v[106:109], v[28:31]
	ds_read_b128 v[106:109], v21 offset:4096
	v_mfma_f32_16x16x32_f16 v[32:35], v[122:125], v[110:113], v[32:35]
	ds_read_b128 v[110:113], v21 offset:6144
	s_waitcnt lgkmcnt(1)
	v_mfma_f32_16x16x32_f16 v[98:101], v[58:61], v[106:109], v[98:101]
	s_waitcnt lgkmcnt(0)
	v_mfma_f32_16x16x32_f16 v[52:55], v[58:61], v[110:113], v[52:55]
	ds_read_b128 v[58:61], v22 offset:32768
	v_mfma_f32_16x16x32_f16 v[102:105], v[94:97], v[106:109], v[102:105]
	v_mfma_f32_16x16x32_f16 v[24:27], v[94:97], v[110:113], v[24:27]
	ds_read_b128 v[94:97], v22 offset:34816
	v_mfma_f32_16x16x32_f16 v[114:117], v[118:121], v[106:109], v[114:117]
	s_waitcnt vmcnt(7)
	ds_write_b128 v17, v[62:65] offset:16384
	s_waitcnt vmcnt(6)
	ds_write_b128 v18, v[90:93] offset:16384
	v_mfma_f32_16x16x32_f16 v[40:43], v[118:121], v[110:113], v[40:43]
	ds_read_b128 v[118:121], v22 offset:36864
	s_waitcnt vmcnt(5)
	ds_write_b128 v19, v[126:129] offset:16384
	v_mfma_f32_16x16x32_f16 v[70:73], v[122:125], v[106:109], v[70:73]
	ds_read_b128 v[106:109], v23
	v_mfma_f32_16x16x32_f16 v[48:51], v[122:125], v[110:113], v[48:51]
	ds_read_b128 v[110:113], v23 offset:2048
	s_waitcnt lgkmcnt(1)
	v_mfma_f32_16x16x32_f16 v[36:39], v[58:61], v[106:109], v[36:39]
	ds_read_b128 v[122:125], v22 offset:38912
	s_waitcnt lgkmcnt(1)
	v_mfma_f32_16x16x32_f16 v[66:69], v[58:61], v[110:113], v[66:69]
	s_waitcnt vmcnt(4)
	ds_write_b128 v20, v[130:133] offset:16384
	v_mfma_f32_16x16x32_f16 v[44:47], v[94:97], v[106:109], v[44:47]
	s_waitcnt vmcnt(3)
	ds_write_b128 v17, v[74:77] offset:49152
	v_mfma_f32_16x16x32_f16 v[78:81], v[94:97], v[110:113], v[78:81]
	s_waitcnt vmcnt(2)
	ds_write_b128 v18, v[138:141] offset:49152
	v_mfma_f32_16x16x32_f16 v[82:85], v[118:121], v[106:109], v[82:85]
	s_waitcnt vmcnt(1)
	ds_write_b128 v19, v[142:145] offset:49152
	v_mfma_f32_16x16x32_f16 v[86:89], v[118:121], v[110:113], v[86:89]
	s_waitcnt vmcnt(0)
	ds_write_b128 v20, v[154:157] offset:49152
	s_waitcnt lgkmcnt(5)
	v_mfma_f32_16x16x32_f16 v[28:31], v[122:125], v[106:109], v[28:31]
	ds_read_b128 v[106:109], v23 offset:4096
	v_mfma_f32_16x16x32_f16 v[32:35], v[122:125], v[110:113], v[32:35]
	ds_read_b128 v[110:113], v23 offset:6144
	s_waitcnt lgkmcnt(1)
	v_mfma_f32_16x16x32_f16 v[98:101], v[58:61], v[106:109], v[98:101]
	s_waitcnt lgkmcnt(0)
	v_mfma_f32_16x16x32_f16 v[52:55], v[58:61], v[110:113], v[52:55]
	global_load_dwordx4 v[58:61], v[0:1], off offset:3584
	v_mfma_f32_16x16x32_f16 v[102:105], v[94:97], v[106:109], v[102:105]
	v_mfma_f32_16x16x32_f16 v[24:27], v[94:97], v[110:113], v[24:27]
	v_mfma_f32_16x16x32_f16 v[114:117], v[118:121], v[106:109], v[114:117]
	v_mfma_f32_16x16x32_f16 v[40:43], v[118:121], v[110:113], v[40:43]
	v_mfma_f32_16x16x32_f16 v[70:73], v[122:125], v[106:109], v[70:73]
	global_load_dwordx4 v[106:109], v[2:3], off offset:3584
	global_load_dwordx4 v[134:137], v[4:5], off offset:3584
	global_load_dwordx4 v[158:161], v[14:15], off offset:3584
	global_load_dwordx4 v[94:97], v[10:11], off offset:3584
	global_load_dwordx4 v[162:165], v[12:13], off offset:3584
	global_load_dwordx4 v[166:169], v[8:9], off offset:3584
	global_load_dwordx4 v[190:193], v[6:7], off offset:3584
	s_waitcnt lgkmcnt(0)
	s_barrier
	v_mfma_f32_16x16x32_f16 v[48:51], v[122:125], v[110:113], v[48:51]
	ds_read_b128 v[62:65], v16 offset:49152
	ds_read_b128 v[90:93], v21 offset:16384
	s_waitcnt lgkmcnt(0)
	v_mfma_f32_16x16x32_f16 v[36:39], v[62:65], v[90:93], v[36:39]
	ds_read_b128 v[74:77], v16 offset:51200
	ds_read_b128 v[110:113], v21 offset:18432
	s_waitcnt lgkmcnt(0)
	v_mfma_f32_16x16x32_f16 v[66:69], v[62:65], v[110:113], v[66:69]
	ds_read_b128 v[118:121], v16 offset:53248
	v_mfma_f32_16x16x32_f16 v[44:47], v[74:77], v[90:93], v[44:47]
	ds_read_b128 v[122:125], v16 offset:55296
	v_mfma_f32_16x16x32_f16 v[78:81], v[74:77], v[110:113], v[78:81]
	s_waitcnt lgkmcnt(1)
	v_mfma_f32_16x16x32_f16 v[82:85], v[118:121], v[90:93], v[82:85]
	v_mfma_f32_16x16x32_f16 v[86:89], v[118:121], v[110:113], v[86:89]
	s_waitcnt lgkmcnt(0)
	v_mfma_f32_16x16x32_f16 v[28:31], v[122:125], v[90:93], v[28:31]
	ds_read_b128 v[90:93], v21 offset:20480
	v_mfma_f32_16x16x32_f16 v[32:35], v[122:125], v[110:113], v[32:35]
	ds_read_b128 v[110:113], v21 offset:22528
	s_waitcnt lgkmcnt(1)
	v_mfma_f32_16x16x32_f16 v[98:101], v[62:65], v[90:93], v[98:101]
	s_waitcnt lgkmcnt(0)
	v_mfma_f32_16x16x32_f16 v[52:55], v[62:65], v[110:113], v[52:55]
	ds_read_b128 v[62:65], v22 offset:49152
	v_mfma_f32_16x16x32_f16 v[102:105], v[74:77], v[90:93], v[102:105]
	v_mfma_f32_16x16x32_f16 v[24:27], v[74:77], v[110:113], v[24:27]
	ds_read_b128 v[74:77], v22 offset:51200
	v_mfma_f32_16x16x32_f16 v[114:117], v[118:121], v[90:93], v[114:117]
	s_waitcnt vmcnt(7)
	ds_write_b128 v17, v[58:61]
	s_waitcnt vmcnt(6)
; #define GL_LOAD(s_, kt_) if (VAR != 1) { a##s_##0 = GL_A(0, kt_); a##s_##1 = GL_A(1, kt_); a##s_##2 = GL_A(2, kt_); a##s_##3 = GL_A(3, kt_); b##s_##0 = GL_B(0, kt_); b##s_##1 = GL_B(1, kt_); b##s_##2 = GL_B(2, kt_); b##s_##3 = GL_B(3, kt_); }
; #define LDS_STORE(s_, buf_) if (VAR != 2) { LDS_ST1(sA, 0, buf_, a##s_##0) LDS_ST1(sA, 1, buf_, a##s_##1) LDS_ST1(sA, 2, buf_, a##s_##2) LDS_ST1(sA, 3, buf_, a##s_##3) LDS_ST1(sB, 0, buf_, b##s_##0) LDS_ST1(sB, 1, buf_, b##s_##1) LDS_ST1(sB, 2, buf_, b##s_##2) LDS_ST1(sB, 3, buf_, b##s_##3) }
;     ...
;   GL_LOAD(0, 0)
;   GL_LOAD(1, 1)
;   LDS_STORE(0, 0)
;   if (VAR != 4) __syncthreads();
; #pragma unroll
;   for (int kt = 0; kt < nk; kt += 2) {
;     if (kt + 2 < nk) { GL_LOAD(0, kt + 2) }
;     MMA_TILE(0)
;     LDS_STORE(1, 1)
;     if (VAR != 4) __syncthreads();
;     if (kt + 3 < nk) { GL_LOAD(1, kt + 3) }
;     MMA_TILE(1)
;     if (kt + 2 < nk) { LDS_STORE(0, 0) }
;     if (VAR != 4) __syncthreads();
;   }
	ds_write_b128 v18, v[106:109]
	v_mfma_f32_16x16x32_f16 v[40:43], v[118:121], v[110:113], v[40:43]
	ds_read_b128 v[118:121], v22 offset:53248
	s_waitcnt vmcnt(5)
	ds_write_b128 v19, v[134:137]
	v_mfma_f32_16x16x32_f16 v[70:73], v[122:125], v[90:93], v[70:73]
	ds_read_b128 v[90:93], v23 offset:16384
	v_mfma_f32_16x16x32_f16 v[48:51], v[122:125], v[110:113], v[48:51]
	ds_read_b128 v[110:113], v23 offset:18432
	s_waitcnt lgkmcnt(1)
	v_mfma_f32_16x16x32_f16 v[36:39], v[62:65], v[90:93], v[36:39]
	ds_read_b128 v[122:125], v22 offset:55296
	s_waitcnt lgkmcnt(1)
	v_mfma_f32_16x16x32_f16 v[66:69], v[62:65], v[110:113], v[66:69]
	s_waitcnt vmcnt(4)
	ds_write_b128 v20, v[158:161]
	v_mfma_f32_16x16x32_f16 v[44:47], v[74:77], v[90:93], v[44:47]
	s_waitcnt vmcnt(3)
	ds_write_b128 v17, v[94:97] offset:32768
	v_mfma_f32_16x16x32_f16 v[78:81], v[74:77], v[110:113], v[78:81]
	s_waitcnt vmcnt(2)
	ds_write_b128 v18, v[162:165] offset:32768
	v_mfma_f32_16x16x32_f16 v[82:85], v[118:121], v[90:93], v[82:85]
	s_waitcnt vmcnt(1)
	ds_write_b128 v19, v[166:169] offset:32768
	v_mfma_f32_16x16x32_f16 v[86:89], v[118:121], v[110:113], v[86:89]
	s_waitcnt vmcnt(0)
	ds_write_b128 v20, v[190:193] offset:32768
	s_waitcnt lgkmcnt(5)
	v_mfma_f32_16x16x32_f16 v[28:31], v[122:125], v[90:93], v[28:31]
	ds_read_b128 v[90:93], v23 offset:20480
	v_mfma_f32_16x16x32_f16 v[32:35], v[122:125], v[110:113], v[32:35]
	ds_read_b128 v[110:113], v23 offset:22528
	s_waitcnt lgkmcnt(1)
	v_mfma_f32_16x16x32_f16 v[98:101], v[62:65], v[90:93], v[98:101]
	s_waitcnt lgkmcnt(0)
	v_mfma_f32_16x16x32_f16 v[52:55], v[62:65], v[110:113], v[52:55]
	global_load_dwordx4 v[62:65], v[0:1], off offset:3712
	v_mfma_f32_16x16x32_f16 v[102:105], v[74:77], v[90:93], v[102:105]
	v_mfma_f32_16x16x32_f16 v[24:27], v[74:77], v[110:113], v[24:27]
	v_mfma_f32_16x16x32_f16 v[114:117], v[118:121], v[90:93], v[114:117]
	v_mfma_f32_16x16x32_f16 v[40:43], v[118:121], v[110:113], v[40:43]
	v_mfma_f32_16x16x32_f16 v[70:73], v[122:125], v[90:93], v[70:73]
	global_load_dwordx4 v[90:93], v[2:3], off offset:3712
	global_load_dwordx4 v[126:129], v[4:5], off offset:3712
	global_load_dwordx4 v[130:133], v[14:15], off offset:3712
	global_load_dwordx4 v[74:77], v[10:11], off offset:3712
	global_load_dwordx4 v[138:141], v[12:13], off offset:3712
	global_load_dwordx4 v[142:145], v[8:9], off offset:3712
	global_load_dwordx4 v[154:157], v[6:7], off offset:3712
	s_waitcnt lgkmcnt(0)
	s_barrier
	v_mfma_f32_16x16x32_f16 v[48:51], v[122:125], v[110:113], v[48:51]
	ds_read_b128 v[58:61], v16 offset:32768
	ds_read_b128 v[106:109], v21
	s_waitcnt lgkmcnt(0)
	v_mfma_f32_16x16x32_f16 v[36:39], v[58:61], v[106:109], v[36:39]
	ds_read_b128 v[94:97], v16 offset:34816
	ds_read_b128 v[110:113], v21 offset:2048
	s_waitcnt lgkmcnt(0)
	v_mfma_f32_16x16x32_f16 v[66:69], v[58:61], v[110:113], v[66:69]
	ds_read_b128 v[118:121], v16 offset:36864
	v_mfma_f32_16x16x32_f16 v[44:47], v[94:97], v[106:109], v[44:47]
	ds_read_b128 v[122:125], v16 offset:38912
	v_mfma_f32_16x16x32_f16 v[78:81], v[94:97], v[110:113], v[78:81]
	s_waitcnt lgkmcnt(1)
	v_mfma_f32_16x16x32_f16 v[82:85], v[118:121], v[106:109], v[82:85]
	v_mfma_f32_16x16x32_f16 v[86:89], v[118:121], v[110:113], v[86:89]
	s_waitcnt lgkmcnt(0)
	v_mfma_f32_16x16x32_f16 v[28:31], v[122:125], v[106:109], v[28:31]
	ds_read_b128 v[106:109], v21 offset:4096
	v_mfma_f32_16x16x32_f16 v[32:35], v[122:125], v[110:113], v[32:35]
	ds_read_b128 v[110:113], v21 offset:6144
	s_waitcnt lgkmcnt(1)
	v_mfma_f32_16x16x32_f16 v[98:101], v[58:61], v[106:109], v[98:101]
	s_waitcnt lgkmcnt(0)
	v_mfma_f32_16x16x32_f16 v[52:55], v[58:61], v[110:113], v[52:55]
	ds_read_b128 v[58:61], v22 offset:32768
	v_mfma_f32_16x16x32_f16 v[102:105], v[94:97], v[106:109], v[102:105]
	v_mfma_f32_16x16x32_f16 v[24:27], v[94:97], v[110:113], v[24:27]
	ds_read_b128 v[94:97], v22 offset:34816
	v_mfma_f32_16x16x32_f16 v[114:117], v[118:121], v[106:109], v[114:117]
	s_waitcnt vmcnt(7)
	ds_write_b128 v17, v[62:65] offset:16384
	s_waitcnt vmcnt(6)
	ds_write_b128 v18, v[90:93] offset:16384
	v_mfma_f32_16x16x32_f16 v[40:43], v[118:121], v[110:113], v[40:43]
	ds_read_b128 v[118:121], v22 offset:36864
	s_waitcnt vmcnt(5)
	ds_write_b128 v19, v[126:129] offset:16384
	v_mfma_f32_16x16x32_f16 v[70:73], v[122:125], v[106:109], v[70:73]
	ds_read_b128 v[106:109], v23
	v_mfma_f32_16x16x32_f16 v[48:51], v[122:125], v[110:113], v[48:51]
	ds_read_b128 v[110:113], v23 offset:2048
	s_waitcnt lgkmcnt(1)
	v_mfma_f32_16x16x32_f16 v[36:39], v[58:61], v[106:109], v[36:39]
	ds_read_b128 v[122:125], v22 offset:38912
	s_waitcnt lgkmcnt(1)
	v_mfma_f32_16x16x32_f16 v[66:69], v[58:61], v[110:113], v[66:69]
	s_waitcnt vmcnt(4)
	ds_write_b128 v20, v[130:133] offset:16384
	v_mfma_f32_16x16x32_f16 v[44:47], v[94:97], v[106:109], v[44:47]
	s_waitcnt vmcnt(3)
	ds_write_b128 v17, v[74:77] offset:49152
	v_mfma_f32_16x16x32_f16 v[78:81], v[94:97], v[110:113], v[78:81]
	s_waitcnt vmcnt(2)
	ds_write_b128 v18, v[138:141] offset:49152
	v_mfma_f32_16x16x32_f16 v[82:85], v[118:121], v[106:109], v[82:85]
	s_waitcnt vmcnt(1)
	ds_write_b128 v19, v[142:145] offset:49152
	v_mfma_f32_16x16x32_f16 v[86:89], v[118:121], v[110:113], v[86:89]
	s_waitcnt vmcnt(0)
	ds_write_b128 v20, v[154:157] offset:49152
	s_waitcnt lgkmcnt(5)
	v_mfma_f32_16x16x32_f16 v[28:31], v[122:125], v[106:109], v[28:31]
	ds_read_b128 v[106:109], v23 offset:4096
	v_mfma_f32_16x16x32_f16 v[32:35], v[122:125], v[110:113], v[32:35]
	ds_read_b128 v[110:113], v23 offset:6144
	s_waitcnt lgkmcnt(1)
	v_mfma_f32_16x16x32_f16 v[98:101], v[58:61], v[106:109], v[98:101]
	s_waitcnt lgkmcnt(0)
	v_mfma_f32_16x16x32_f16 v[52:55], v[58:61], v[110:113], v[52:55]
	global_load_dwordx4 v[58:61], v[0:1], off offset:3840
	v_mfma_f32_16x16x32_f16 v[102:105], v[94:97], v[106:109], v[102:105]
	v_mfma_f32_16x16x32_f16 v[24:27], v[94:97], v[110:113], v[24:27]
	v_mfma_f32_16x16x32_f16 v[114:117], v[118:121], v[106:109], v[114:117]
	v_mfma_f32_16x16x32_f16 v[40:43], v[118:121], v[110:113], v[40:43]
	v_mfma_f32_16x16x32_f16 v[70:73], v[122:125], v[106:109], v[70:73]
	global_load_dwordx4 v[106:109], v[2:3], off offset:3840
	global_load_dwordx4 v[134:137], v[4:5], off offset:3840
	global_load_dwordx4 v[158:161], v[14:15], off offset:3840
	global_load_dwordx4 v[94:97], v[10:11], off offset:3840
	global_load_dwordx4 v[162:165], v[12:13], off offset:3840
	global_load_dwordx4 v[166:169], v[8:9], off offset:3840
	global_load_dwordx4 v[190:193], v[6:7], off offset:3840
	s_waitcnt lgkmcnt(0)
	s_barrier
; #define GL_LOAD(s_, kt_) if (VAR != 1) { a##s_##0 = GL_A(0, kt_); a##s_##1 = GL_A(1, kt_); a##s_##2 = GL_A(2, kt_); a##s_##3 = GL_A(3, kt_); b##s_##0 = GL_B(0, kt_); b##s_##1 = GL_B(1, kt_); b##s_##2 = GL_B(2, kt_); b##s_##3 = GL_B(3, kt_); }
; #define LDS_STORE(s_, buf_) if (VAR != 2) { LDS_ST1(sA, 0, buf_, a##s_##0) LDS_ST1(sA, 1, buf_, a##s_##1) LDS_ST1(sA, 2, buf_, a##s_##2) LDS_ST1(sA, 3, buf_, a##s_##3) LDS_ST1(sB, 0, buf_, b##s_##0) LDS_ST1(sB, 1, buf_, b##s_##1) LDS_ST1(sB, 2, buf_, b##s_##2) LDS_ST1(sB, 3, buf_, b##s_##3) }
;     ...
;   GL_LOAD(0, 0)
;   GL_LOAD(1, 1)
;   LDS_STORE(0, 0)
;   if (VAR != 4) __syncthreads();
; #pragma unroll
;   for (int kt = 0; kt < nk; kt += 2) {
;     if (kt + 2 < nk) { GL_LOAD(0, kt + 2) }
;     MMA_TILE(0)
;     LDS_STORE(1, 1)
;     if (VAR != 4) __syncthreads();
;     if (kt + 3 < nk) { GL_LOAD(1, kt + 3) }
;     MMA_TILE(1)
;     if (kt + 2 < nk) { LDS_STORE(0, 0) }
;     if (VAR != 4) __syncthreads();
;   }
	v_mfma_f32_16x16x32_f16 v[48:51], v[122:125], v[110:113], v[48:51]
	ds_read_b128 v[62:65], v16 offset:49152
	ds_read_b128 v[90:93], v21 offset:16384
	s_waitcnt lgkmcnt(0)
	v_mfma_f32_16x16x32_f16 v[36:39], v[62:65], v[90:93], v[36:39]
	ds_read_b128 v[74:77], v16 offset:51200
	ds_read_b128 v[110:113], v21 offset:18432
	s_waitcnt lgkmcnt(0)
	v_mfma_f32_16x16x32_f16 v[66:69], v[62:65], v[110:113], v[66:69]
	ds_read_b128 v[118:121], v16 offset:53248
	v_mfma_f32_16x16x32_f16 v[44:47], v[74:77], v[90:93], v[44:47]
	ds_read_b128 v[122:125], v16 offset:55296
	v_mfma_f32_16x16x32_f16 v[78:81], v[74:77], v[110:113], v[78:81]
	s_waitcnt lgkmcnt(1)
	v_mfma_f32_16x16x32_f16 v[82:85], v[118:121], v[90:93], v[82:85]
	v_mfma_f32_16x16x32_f16 v[86:89], v[118:121], v[110:113], v[86:89]
	s_waitcnt lgkmcnt(0)
	v_mfma_f32_16x16x32_f16 v[28:31], v[122:125], v[90:93], v[28:31]
	ds_read_b128 v[90:93], v21 offset:20480
	v_mfma_f32_16x16x32_f16 v[32:35], v[122:125], v[110:113], v[32:35]
	ds_read_b128 v[110:113], v21 offset:22528
	s_waitcnt lgkmcnt(1)
	v_mfma_f32_16x16x32_f16 v[98:101], v[62:65], v[90:93], v[98:101]
	s_waitcnt lgkmcnt(0)
	v_mfma_f32_16x16x32_f16 v[52:55], v[62:65], v[110:113], v[52:55]
	ds_read_b128 v[62:65], v22 offset:49152
	v_mfma_f32_16x16x32_f16 v[102:105], v[74:77], v[90:93], v[102:105]
	v_mfma_f32_16x16x32_f16 v[24:27], v[74:77], v[110:113], v[24:27]
	ds_read_b128 v[74:77], v22 offset:51200
	v_mfma_f32_16x16x32_f16 v[114:117], v[118:121], v[90:93], v[114:117]
	s_waitcnt vmcnt(7)
	ds_write_b128 v17, v[58:61]
	s_waitcnt vmcnt(6)
	ds_write_b128 v18, v[106:109]
	v_mfma_f32_16x16x32_f16 v[40:43], v[118:121], v[110:113], v[40:43]
	ds_read_b128 v[118:121], v22 offset:53248
	s_waitcnt vmcnt(5)
	ds_write_b128 v19, v[134:137]
	v_mfma_f32_16x16x32_f16 v[70:73], v[122:125], v[90:93], v[70:73]
	ds_read_b128 v[90:93], v23 offset:16384
	v_mfma_f32_16x16x32_f16 v[48:51], v[122:125], v[110:113], v[48:51]
	ds_read_b128 v[110:113], v23 offset:18432
	s_waitcnt lgkmcnt(1)
	v_mfma_f32_16x16x32_f16 v[36:39], v[62:65], v[90:93], v[36:39]
	ds_read_b128 v[122:125], v22 offset:55296
	s_waitcnt lgkmcnt(1)
	v_mfma_f32_16x16x32_f16 v[66:69], v[62:65], v[110:113], v[66:69]
	s_waitcnt vmcnt(4)
	ds_write_b128 v20, v[158:161]
	v_mfma_f32_16x16x32_f16 v[44:47], v[74:77], v[90:93], v[44:47]
	s_waitcnt vmcnt(3)
	ds_write_b128 v17, v[94:97] offset:32768
	v_mfma_f32_16x16x32_f16 v[78:81], v[74:77], v[110:113], v[78:81]
	s_waitcnt vmcnt(2)
	ds_write_b128 v18, v[162:165] offset:32768
	v_mfma_f32_16x16x32_f16 v[82:85], v[118:121], v[90:93], v[82:85]
	s_waitcnt vmcnt(1)
	ds_write_b128 v19, v[166:169] offset:32768
	v_mfma_f32_16x16x32_f16 v[86:89], v[118:121], v[110:113], v[86:89]
	s_waitcnt vmcnt(0)
	ds_write_b128 v20, v[190:193] offset:32768
	s_waitcnt lgkmcnt(5)
	v_mfma_f32_16x16x32_f16 v[28:31], v[122:125], v[90:93], v[28:31]
	ds_read_b128 v[90:93], v23 offset:20480
	v_mfma_f32_16x16x32_f16 v[32:35], v[122:125], v[110:113], v[32:35]
	ds_read_b128 v[110:113], v23 offset:22528
	s_waitcnt lgkmcnt(1)
	v_mfma_f32_16x16x32_f16 v[98:101], v[62:65], v[90:93], v[98:101]
	s_waitcnt lgkmcnt(0)
	v_mfma_f32_16x16x32_f16 v[52:55], v[62:65], v[110:113], v[52:55]
	global_load_dwordx4 v[62:65], v[0:1], off offset:3968
	v_add_co_u32_e32 v0, vcc, s1, v0
	v_mfma_f32_16x16x32_f16 v[102:105], v[74:77], v[90:93], v[102:105]
	v_mfma_f32_16x16x32_f16 v[24:27], v[74:77], v[110:113], v[24:27]
	v_mfma_f32_16x16x32_f16 v[114:117], v[118:121], v[90:93], v[114:117]
	v_mfma_f32_16x16x32_f16 v[40:43], v[118:121], v[110:113], v[40:43]
	v_mfma_f32_16x16x32_f16 v[70:73], v[122:125], v[90:93], v[70:73]
	global_load_dwordx4 v[90:93], v[2:3], off offset:3968
	global_load_dwordx4 v[126:129], v[4:5], off offset:3968
	global_load_dwordx4 v[130:133], v[14:15], off offset:3968
	global_load_dwordx4 v[74:77], v[10:11], off offset:3968
	global_load_dwordx4 v[138:141], v[12:13], off offset:3968
	global_load_dwordx4 v[142:145], v[8:9], off offset:3968
	global_load_dwordx4 v[154:157], v[6:7], off offset:3968
	s_waitcnt lgkmcnt(0)
	s_barrier
	v_mfma_f32_16x16x32_f16 v[48:51], v[122:125], v[110:113], v[48:51]
	ds_read_b128 v[58:61], v16 offset:32768
	ds_read_b128 v[106:109], v21
	s_waitcnt lgkmcnt(0)
	v_mfma_f32_16x16x32_f16 v[36:39], v[58:61], v[106:109], v[36:39]
	ds_read_b128 v[94:97], v16 offset:34816
	ds_read_b128 v[110:113], v21 offset:2048
	s_waitcnt lgkmcnt(0)
	v_mfma_f32_16x16x32_f16 v[66:69], v[58:61], v[110:113], v[66:69]
	ds_read_b128 v[118:121], v16 offset:36864
	v_mfma_f32_16x16x32_f16 v[44:47], v[94:97], v[106:109], v[44:47]
	ds_read_b128 v[122:125], v16 offset:38912
	v_mfma_f32_16x16x32_f16 v[78:81], v[94:97], v[110:113], v[78:81]
	ds_read_b128 v[158:161], v23 offset:6144
	s_waitcnt lgkmcnt(2)
	v_mfma_f32_16x16x32_f16 v[82:85], v[118:121], v[106:109], v[82:85]
	v_addc_co_u32_e32 v1, vcc, 0, v1, vcc
	v_mfma_f32_16x16x32_f16 v[86:89], v[118:121], v[110:113], v[86:89]
	v_add_co_u32_e32 v2, vcc, s1, v2
	s_waitcnt lgkmcnt(1)
	v_mfma_f32_16x16x32_f16 v[28:31], v[122:125], v[106:109], v[28:31]
	ds_read_b128 v[106:109], v21 offset:4096
	v_mfma_f32_16x16x32_f16 v[32:35], v[122:125], v[110:113], v[32:35]
	ds_read_b128 v[110:113], v21 offset:6144
	s_waitcnt lgkmcnt(1)
	v_mfma_f32_16x16x32_f16 v[98:101], v[58:61], v[106:109], v[98:101]
	v_addc_co_u32_e32 v3, vcc, 0, v3, vcc
	s_waitcnt lgkmcnt(0)
; #define GL_LOAD(s_, kt_) if (VAR != 1) { a##s_##0 = GL_A(0, kt_); a##s_##1 = GL_A(1, kt_); a##s_##2 = GL_A(2, kt_); a##s_##3 = GL_A(3, kt_); b##s_##0 = GL_B(0, kt_); b##s_##1 = GL_B(1, kt_); b##s_##2 = GL_B(2, kt_); b##s_##3 = GL_B(3, kt_); }
; #define LDS_STORE(s_, buf_) if (VAR != 2) { LDS_ST1(sA, 0, buf_, a##s_##0) LDS_ST1(sA, 1, buf_, a##s_##1) LDS_ST1(sA, 2, buf_, a##s_##2) LDS_ST1(sA, 3, buf_, a##s_##3) LDS_ST1(sB, 0, buf_, b##s_##0) LDS_ST1(sB, 1, buf_, b##s_##1) LDS_ST1(sB, 2, buf_, b##s_##2) LDS_ST1(sB, 3, buf_, b##s_##3) }
;     ...
;   GL_LOAD(0, 0)
;   GL_LOAD(1, 1)
;   LDS_STORE(0, 0)
;   if (VAR != 4) __syncthreads();
; #pragma unroll
;   for (int kt = 0; kt < nk; kt += 2) {
;     if (kt + 2 < nk) { GL_LOAD(0, kt + 2) }
;     MMA_TILE(0)
;     LDS_STORE(1, 1)
;     if (VAR != 4) __syncthreads();
;     if (kt + 3 < nk) { GL_LOAD(1, kt + 3) }
;     MMA_TILE(1)
;     if (kt + 2 < nk) { LDS_STORE(0, 0) }
;     if (VAR != 4) __syncthreads();
;   }
	v_mfma_f32_16x16x32_f16 v[52:55], v[58:61], v[110:113], v[52:55]
	ds_read_b128 v[58:61], v22 offset:32768
	v_mfma_f32_16x16x32_f16 v[102:105], v[94:97], v[106:109], v[102:105]
	v_add_co_u32_e32 v4, vcc, s1, v4
	v_mfma_f32_16x16x32_f16 v[24:27], v[94:97], v[110:113], v[24:27]
	ds_read_b128 v[94:97], v22 offset:34816
	v_addc_co_u32_e32 v5, vcc, 0, v5, vcc
	v_mfma_f32_16x16x32_f16 v[114:117], v[118:121], v[106:109], v[114:117]
	v_add_co_u32_e32 v14, vcc, s1, v14
	v_addc_co_u32_e32 v15, vcc, 0, v15, vcc
	v_mfma_f32_16x16x32_f16 v[40:43], v[118:121], v[110:113], v[40:43]
	ds_read_b128 v[118:121], v22 offset:36864
	v_add_co_u32_e32 v10, vcc, s1, v10
	v_mfma_f32_16x16x32_f16 v[70:73], v[122:125], v[106:109], v[70:73]
	ds_read_b128 v[106:109], v23
	v_addc_co_u32_e32 v11, vcc, 0, v11, vcc
	v_mfma_f32_16x16x32_f16 v[48:51], v[122:125], v[110:113], v[48:51]
	ds_read_b128 v[110:113], v23 offset:2048
	ds_read_b128 v[122:125], v22 offset:38912
	s_waitcnt lgkmcnt(2)
	v_mfma_f32_16x16x32_f16 v[36:39], v[58:61], v[106:109], v[36:39]
	v_add_co_u32_e32 v12, vcc, s1, v12
	v_addc_co_u32_e32 v13, vcc, 0, v13, vcc
	s_waitcnt lgkmcnt(1)
	v_mfma_f32_16x16x32_f16 v[66:69], v[58:61], v[110:113], v[66:69]
	v_add_co_u32_e32 v8, vcc, s1, v8
	v_addc_co_u32_e32 v9, vcc, 0, v9, vcc
	v_mfma_f32_16x16x32_f16 v[44:47], v[94:97], v[106:109], v[44:47]
	v_add_co_u32_e32 v6, vcc, s1, v6
	v_addc_co_u32_e32 v7, vcc, 0, v7, vcc
	v_mfma_f32_16x16x32_f16 v[78:81], v[94:97], v[110:113], v[78:81]
	s_waitcnt vmcnt(7)
	ds_write_b128 v17, v[62:65] offset:16384
	s_waitcnt vmcnt(6)
	ds_write_b128 v18, v[90:93] offset:16384
	v_mfma_f32_16x16x32_f16 v[52:55], v[58:61], v[158:161], v[52:55]
	s_waitcnt vmcnt(5)
	ds_write_b128 v19, v[126:129] offset:16384
	s_waitcnt vmcnt(4)
	ds_write_b128 v20, v[130:133] offset:16384
	v_mfma_f32_16x16x32_f16 v[24:27], v[94:97], v[158:161], v[24:27]
	s_waitcnt vmcnt(3)
	ds_write_b128 v17, v[74:77] offset:49152
	s_waitcnt vmcnt(2)
	ds_write_b128 v18, v[138:141] offset:49152
	v_mfma_f32_16x16x32_f16 v[82:85], v[118:121], v[106:109], v[82:85]
	s_waitcnt vmcnt(1)
	ds_write_b128 v19, v[142:145] offset:49152
	s_waitcnt vmcnt(0)
	ds_write_b128 v20, v[154:157] offset:49152
	v_mfma_f32_16x16x32_f16 v[86:89], v[118:121], v[110:113], v[86:89]
	s_waitcnt lgkmcnt(8)
	v_mfma_f32_16x16x32_f16 v[28:31], v[122:125], v[106:109], v[28:31]
	ds_read_b128 v[106:109], v23 offset:4096
	v_mfma_f32_16x16x32_f16 v[32:35], v[122:125], v[110:113], v[32:35]
	global_load_dwordx4 v[110:113], v[0:1], off
	global_load_dwordx4 v[134:137], v[2:3], off
	v_mfma_f32_16x16x32_f16 v[40:43], v[118:121], v[158:161], v[40:43]
	global_load_dwordx4 v[162:165], v[4:5], off
	s_waitcnt lgkmcnt(0)
	v_mfma_f32_16x16x32_f16 v[98:101], v[58:61], v[106:109], v[98:101]
	global_load_dwordx4 v[166:169], v[14:15], off
	v_mfma_f32_16x16x32_f16 v[102:105], v[94:97], v[106:109], v[102:105]
	v_mfma_f32_16x16x32_f16 v[114:117], v[118:121], v[106:109], v[114:117]
	v_mfma_f32_16x16x32_f16 v[70:73], v[122:125], v[106:109], v[70:73]
	global_load_dwordx4 v[106:109], v[10:11], off
	global_load_dwordx4 v[190:193], v[12:13], off
	global_load_dwordx4 v[58:61], v[8:9], off
	global_load_dwordx4 v[94:97], v[6:7], off
	s_waitcnt lgkmcnt(0)
	s_barrier
	v_mfma_f32_16x16x32_f16 v[48:51], v[122:125], v[158:161], v[48:51]
	ds_read_b128 v[62:65], v16 offset:49152
	ds_read_b128 v[90:93], v21 offset:16384
	s_waitcnt lgkmcnt(0)
	v_mfma_f32_16x16x32_f16 v[36:39], v[62:65], v[90:93], v[36:39]
	ds_read_b128 v[74:77], v16 offset:51200
	ds_read_b128 v[118:121], v21 offset:18432
	s_waitcnt lgkmcnt(0)
	v_mfma_f32_16x16x32_f16 v[66:69], v[62:65], v[118:121], v[66:69]
	ds_read_b128 v[122:125], v16 offset:53248
	v_mfma_f32_16x16x32_f16 v[44:47], v[74:77], v[90:93], v[44:47]
	ds_read_b128 v[126:129], v16 offset:55296
	v_mfma_f32_16x16x32_f16 v[78:81], v[74:77], v[118:121], v[78:81]
	s_waitcnt lgkmcnt(1)
	v_mfma_f32_16x16x32_f16 v[82:85], v[122:125], v[90:93], v[82:85]
	v_mfma_f32_16x16x32_f16 v[86:89], v[122:125], v[118:121], v[86:89]
	s_waitcnt lgkmcnt(0)
	v_mfma_f32_16x16x32_f16 v[28:31], v[126:129], v[90:93], v[28:31]
	ds_read_b128 v[90:93], v21 offset:20480
	v_mfma_f32_16x16x32_f16 v[32:35], v[126:129], v[118:121], v[32:35]
	ds_read_b128 v[118:121], v21 offset:22528
	s_waitcnt lgkmcnt(1)
	v_mfma_f32_16x16x32_f16 v[98:101], v[62:65], v[90:93], v[98:101]
	s_waitcnt lgkmcnt(0)
	v_mfma_f32_16x16x32_f16 v[52:55], v[62:65], v[118:121], v[52:55]
	ds_read_b128 v[62:65], v22 offset:49152
	v_mfma_f32_16x16x32_f16 v[102:105], v[74:77], v[90:93], v[102:105]
	v_mfma_f32_16x16x32_f16 v[24:27], v[74:77], v[118:121], v[24:27]
	ds_read_b128 v[74:77], v22 offset:51200
	v_mfma_f32_16x16x32_f16 v[114:117], v[122:125], v[90:93], v[114:117]
	s_waitcnt vmcnt(7)
	ds_write_b128 v17, v[110:113]
	s_waitcnt vmcnt(6)
	ds_write_b128 v18, v[134:137]
	v_mfma_f32_16x16x32_f16 v[40:43], v[122:125], v[118:121], v[40:43]
	ds_read_b128 v[122:125], v22 offset:53248
	s_waitcnt vmcnt(5)
	ds_write_b128 v19, v[162:165]
	v_mfma_f32_16x16x32_f16 v[70:73], v[126:129], v[90:93], v[70:73]
	ds_read_b128 v[90:93], v23 offset:16384
	v_mfma_f32_16x16x32_f16 v[48:51], v[126:129], v[118:121], v[48:51]
	ds_read_b128 v[118:121], v23 offset:18432
	s_waitcnt lgkmcnt(1)
	v_mfma_f32_16x16x32_f16 v[36:39], v[62:65], v[90:93], v[36:39]
	ds_read_b128 v[126:129], v22 offset:55296
	s_waitcnt lgkmcnt(1)
	v_mfma_f32_16x16x32_f16 v[66:69], v[62:65], v[118:121], v[66:69]
	s_waitcnt vmcnt(4)
	ds_write_b128 v20, v[166:169]
	v_mfma_f32_16x16x32_f16 v[44:47], v[74:77], v[90:93], v[44:47]
	s_waitcnt vmcnt(3)
	ds_write_b128 v17, v[106:109] offset:32768
	v_mfma_f32_16x16x32_f16 v[78:81], v[74:77], v[118:121], v[78:81]
	s_waitcnt vmcnt(2)
; #define GL_LOAD(s_, kt_) if (VAR != 1) { a##s_##0 = GL_A(0, kt_); a##s_##1 = GL_A(1, kt_); a##s_##2 = GL_A(2, kt_); a##s_##3 = GL_A(3, kt_); b##s_##0 = GL_B(0, kt_); b##s_##1 = GL_B(1, kt_); b##s_##2 = GL_B(2, kt_); b##s_##3 = GL_B(3, kt_); }
; #define LDS_STORE(s_, buf_) if (VAR != 2) { LDS_ST1(sA, 0, buf_, a##s_##0) LDS_ST1(sA, 1, buf_, a##s_##1) LDS_ST1(sA, 2, buf_, a##s_##2) LDS_ST1(sA, 3, buf_, a##s_##3) LDS_ST1(sB, 0, buf_, b##s_##0) LDS_ST1(sB, 1, buf_, b##s_##1) LDS_ST1(sB, 2, buf_, b##s_##2) LDS_ST1(sB, 3, buf_, b##s_##3) }
;     ...
;   GL_LOAD(0, 0)
;   GL_LOAD(1, 1)
;   LDS_STORE(0, 0)
;   if (VAR != 4) __syncthreads();
; #pragma unroll
;   for (int kt = 0; kt < nk; kt += 2) {
;     if (kt + 2 < nk) { GL_LOAD(0, kt + 2) }
;     MMA_TILE(0)
;     LDS_STORE(1, 1)
;     if (VAR != 4) __syncthreads();
;     if (kt + 3 < nk) { GL_LOAD(1, kt + 3) }
;     MMA_TILE(1)
;     if (kt + 2 < nk) { LDS_STORE(0, 0) }
;     if (VAR != 4) __syncthreads();
;   }
	ds_write_b128 v18, v[190:193] offset:32768
	v_mfma_f32_16x16x32_f16 v[82:85], v[122:125], v[90:93], v[82:85]
	s_waitcnt vmcnt(1)
	ds_write_b128 v19, v[58:61] offset:32768
	v_mfma_f32_16x16x32_f16 v[86:89], v[122:125], v[118:121], v[86:89]
	s_waitcnt vmcnt(0)
	ds_write_b128 v20, v[94:97] offset:32768
	s_waitcnt lgkmcnt(5)
	v_mfma_f32_16x16x32_f16 v[28:31], v[126:129], v[90:93], v[28:31]
	ds_read_b128 v[90:93], v23 offset:20480
	v_mfma_f32_16x16x32_f16 v[32:35], v[126:129], v[118:121], v[32:35]
	ds_read_b128 v[118:121], v23 offset:22528
	s_waitcnt lgkmcnt(1)
	v_mfma_f32_16x16x32_f16 v[98:101], v[62:65], v[90:93], v[98:101]
	s_waitcnt lgkmcnt(0)
	v_mfma_f32_16x16x32_f16 v[52:55], v[62:65], v[118:121], v[52:55]
	global_load_dwordx4 v[62:65], v[0:1], off offset:128
	v_mfma_f32_16x16x32_f16 v[102:105], v[74:77], v[90:93], v[102:105]
	v_mfma_f32_16x16x32_f16 v[24:27], v[74:77], v[118:121], v[24:27]
	v_mfma_f32_16x16x32_f16 v[114:117], v[122:125], v[90:93], v[114:117]
	v_mfma_f32_16x16x32_f16 v[40:43], v[122:125], v[118:121], v[40:43]
	v_mfma_f32_16x16x32_f16 v[70:73], v[126:129], v[90:93], v[70:73]
	global_load_dwordx4 v[90:93], v[2:3], off offset:128
	global_load_dwordx4 v[130:133], v[4:5], off offset:128
	global_load_dwordx4 v[138:141], v[14:15], off offset:128
	global_load_dwordx4 v[74:77], v[10:11], off offset:128
	global_load_dwordx4 v[142:145], v[12:13], off offset:128
	global_load_dwordx4 v[154:157], v[8:9], off offset:128
	global_load_dwordx4 v[158:161], v[6:7], off offset:128
	s_waitcnt lgkmcnt(0)
	s_barrier
	v_mfma_f32_16x16x32_f16 v[48:51], v[126:129], v[118:121], v[48:51]
	ds_read_b128 v[58:61], v16 offset:32768
	ds_read_b128 v[106:109], v21
	s_waitcnt lgkmcnt(0)
	v_mfma_f32_16x16x32_f16 v[36:39], v[58:61], v[106:109], v[36:39]
	ds_read_b128 v[94:97], v16 offset:34816
	ds_read_b128 v[110:113], v21 offset:2048
	s_waitcnt lgkmcnt(0)
	v_mfma_f32_16x16x32_f16 v[66:69], v[58:61], v[110:113], v[66:69]
	ds_read_b128 v[118:121], v16 offset:36864
	v_mfma_f32_16x16x32_f16 v[44:47], v[94:97], v[106:109], v[44:47]
	ds_read_b128 v[122:125], v16 offset:38912
	v_mfma_f32_16x16x32_f16 v[78:81], v[94:97], v[110:113], v[78:81]
	s_waitcnt lgkmcnt(1)
	v_mfma_f32_16x16x32_f16 v[82:85], v[118:121], v[106:109], v[82:85]
	v_mfma_f32_16x16x32_f16 v[86:89], v[118:121], v[110:113], v[86:89]
	s_waitcnt lgkmcnt(0)
	v_mfma_f32_16x16x32_f16 v[28:31], v[122:125], v[106:109], v[28:31]
	ds_read_b128 v[106:109], v21 offset:4096
	v_mfma_f32_16x16x32_f16 v[32:35], v[122:125], v[110:113], v[32:35]
	ds_read_b128 v[110:113], v21 offset:6144
	s_waitcnt lgkmcnt(1)
	v_mfma_f32_16x16x32_f16 v[98:101], v[58:61], v[106:109], v[98:101]
	s_waitcnt lgkmcnt(0)
	v_mfma_f32_16x16x32_f16 v[52:55], v[58:61], v[110:113], v[52:55]
	ds_read_b128 v[58:61], v22 offset:32768
	v_mfma_f32_16x16x32_f16 v[102:105], v[94:97], v[106:109], v[102:105]
	v_mfma_f32_16x16x32_f16 v[24:27], v[94:97], v[110:113], v[24:27]
	ds_read_b128 v[94:97], v22 offset:34816
	v_mfma_f32_16x16x32_f16 v[114:117], v[118:121], v[106:109], v[114:117]
	s_waitcnt vmcnt(7)
	ds_write_b128 v17, v[62:65] offset:16384
	s_waitcnt vmcnt(6)
	ds_write_b128 v18, v[90:93] offset:16384
	v_mfma_f32_16x16x32_f16 v[40:43], v[118:121], v[110:113], v[40:43]
	ds_read_b128 v[118:121], v22 offset:36864
	s_waitcnt vmcnt(5)
	ds_write_b128 v19, v[130:133] offset:16384
	v_mfma_f32_16x16x32_f16 v[70:73], v[122:125], v[106:109], v[70:73]
	ds_read_b128 v[106:109], v23
	v_mfma_f32_16x16x32_f16 v[48:51], v[122:125], v[110:113], v[48:51]
	ds_read_b128 v[110:113], v23 offset:2048
	s_waitcnt lgkmcnt(1)
	v_mfma_f32_16x16x32_f16 v[36:39], v[58:61], v[106:109], v[36:39]
	ds_read_b128 v[122:125], v22 offset:38912
	s_waitcnt lgkmcnt(1)
	v_mfma_f32_16x16x32_f16 v[66:69], v[58:61], v[110:113], v[66:69]
	s_waitcnt vmcnt(4)
	ds_write_b128 v20, v[138:141] offset:16384
	v_mfma_f32_16x16x32_f16 v[44:47], v[94:97], v[106:109], v[44:47]
	s_waitcnt vmcnt(3)
	ds_write_b128 v17, v[74:77] offset:49152
	v_mfma_f32_16x16x32_f16 v[78:81], v[94:97], v[110:113], v[78:81]
	s_waitcnt vmcnt(2)
	ds_write_b128 v18, v[142:145] offset:49152
	v_mfma_f32_16x16x32_f16 v[82:85], v[118:121], v[106:109], v[82:85]
	s_waitcnt vmcnt(1)
	ds_write_b128 v19, v[154:157] offset:49152
	v_mfma_f32_16x16x32_f16 v[86:89], v[118:121], v[110:113], v[86:89]
	s_waitcnt vmcnt(0)
	ds_write_b128 v20, v[158:161] offset:49152
	s_waitcnt lgkmcnt(5)
	v_mfma_f32_16x16x32_f16 v[28:31], v[122:125], v[106:109], v[28:31]
	ds_read_b128 v[106:109], v23 offset:4096
	v_mfma_f32_16x16x32_f16 v[32:35], v[122:125], v[110:113], v[32:35]
	ds_read_b128 v[110:113], v23 offset:6144
	s_waitcnt lgkmcnt(1)
	v_mfma_f32_16x16x32_f16 v[98:101], v[58:61], v[106:109], v[98:101]
	s_waitcnt lgkmcnt(0)
	v_mfma_f32_16x16x32_f16 v[52:55], v[58:61], v[110:113], v[52:55]
	global_load_dwordx4 v[58:61], v[0:1], off offset:256
	v_mfma_f32_16x16x32_f16 v[102:105], v[94:97], v[106:109], v[102:105]
	v_mfma_f32_16x16x32_f16 v[24:27], v[94:97], v[110:113], v[24:27]
	v_mfma_f32_16x16x32_f16 v[114:117], v[118:121], v[106:109], v[114:117]
	v_mfma_f32_16x16x32_f16 v[40:43], v[118:121], v[110:113], v[40:43]
	v_mfma_f32_16x16x32_f16 v[70:73], v[122:125], v[106:109], v[70:73]
	global_load_dwordx4 v[106:109], v[2:3], off offset:256
	global_load_dwordx4 v[126:129], v[4:5], off offset:256
	global_load_dwordx4 v[134:137], v[14:15], off offset:256
	global_load_dwordx4 v[94:97], v[10:11], off offset:256
	global_load_dwordx4 v[162:165], v[12:13], off offset:256
	global_load_dwordx4 v[166:169], v[8:9], off offset:256
	global_load_dwordx4 v[190:193], v[6:7], off offset:256
	s_waitcnt lgkmcnt(0)
	s_barrier
; #define GL_LOAD(s_, kt_) if (VAR != 1) { a##s_##0 = GL_A(0, kt_); a##s_##1 = GL_A(1, kt_); a##s_##2 = GL_A(2, kt_); a##s_##3 = GL_A(3, kt_); b##s_##0 = GL_B(0, kt_); b##s_##1 = GL_B(1, kt_); b##s_##2 = GL_B(2, kt_); b##s_##3 = GL_B(3, kt_); }
; #define LDS_STORE(s_, buf_) if (VAR != 2) { LDS_ST1(sA, 0, buf_, a##s_##0) LDS_ST1(sA, 1, buf_, a##s_##1) LDS_ST1(sA, 2, buf_, a##s_##2) LDS_ST1(sA, 3, buf_, a##s_##3) LDS_ST1(sB, 0, buf_, b##s_##0) LDS_ST1(sB, 1, buf_, b##s_##1) LDS_ST1(sB, 2, buf_, b##s_##2) LDS_ST1(sB, 3, buf_, b##s_##3) }
;     ...
;   GL_LOAD(0, 0)
;   GL_LOAD(1, 1)
;   LDS_STORE(0, 0)
;   if (VAR != 4) __syncthreads();
; #pragma unroll
;   for (int kt = 0; kt < nk; kt += 2) {
;     if (kt + 2 < nk) { GL_LOAD(0, kt + 2) }
;     MMA_TILE(0)
;     LDS_STORE(1, 1)
;     if (VAR != 4) __syncthreads();
;     if (kt + 3 < nk) { GL_LOAD(1, kt + 3) }
;     MMA_TILE(1)
;     if (kt + 2 < nk) { LDS_STORE(0, 0) }
;     if (VAR != 4) __syncthreads();
;   }
	v_mfma_f32_16x16x32_f16 v[48:51], v[122:125], v[110:113], v[48:51]
	ds_read_b128 v[62:65], v16 offset:49152
	ds_read_b128 v[90:93], v21 offset:16384
	s_waitcnt lgkmcnt(0)
	v_mfma_f32_16x16x32_f16 v[36:39], v[62:65], v[90:93], v[36:39]
	ds_read_b128 v[74:77], v16 offset:51200
	ds_read_b128 v[110:113], v21 offset:18432
	s_waitcnt lgkmcnt(0)
	v_mfma_f32_16x16x32_f16 v[66:69], v[62:65], v[110:113], v[66:69]
	ds_read_b128 v[118:121], v16 offset:53248
	v_mfma_f32_16x16x32_f16 v[44:47], v[74:77], v[90:93], v[44:47]
	ds_read_b128 v[122:125], v16 offset:55296
	v_mfma_f32_16x16x32_f16 v[78:81], v[74:77], v[110:113], v[78:81]
	s_waitcnt lgkmcnt(1)
	v_mfma_f32_16x16x32_f16 v[82:85], v[118:121], v[90:93], v[82:85]
	v_mfma_f32_16x16x32_f16 v[86:89], v[118:121], v[110:113], v[86:89]
	s_waitcnt lgkmcnt(0)
	v_mfma_f32_16x16x32_f16 v[28:31], v[122:125], v[90:93], v[28:31]
	ds_read_b128 v[90:93], v21 offset:20480
	v_mfma_f32_16x16x32_f16 v[32:35], v[122:125], v[110:113], v[32:35]
	ds_read_b128 v[110:113], v21 offset:22528
	s_waitcnt lgkmcnt(1)
	v_mfma_f32_16x16x32_f16 v[98:101], v[62:65], v[90:93], v[98:101]
	s_waitcnt lgkmcnt(0)
	v_mfma_f32_16x16x32_f16 v[52:55], v[62:65], v[110:113], v[52:55]
	ds_read_b128 v[62:65], v22 offset:49152
	v_mfma_f32_16x16x32_f16 v[102:105], v[74:77], v[90:93], v[102:105]
	v_mfma_f32_16x16x32_f16 v[24:27], v[74:77], v[110:113], v[24:27]
	ds_read_b128 v[74:77], v22 offset:51200
	v_mfma_f32_16x16x32_f16 v[114:117], v[118:121], v[90:93], v[114:117]
	s_waitcnt vmcnt(7)
	ds_write_b128 v17, v[58:61]
	s_waitcnt vmcnt(6)
	ds_write_b128 v18, v[106:109]
	v_mfma_f32_16x16x32_f16 v[40:43], v[118:121], v[110:113], v[40:43]
	ds_read_b128 v[118:121], v22 offset:53248
	s_waitcnt vmcnt(5)
	ds_write_b128 v19, v[126:129]
	v_mfma_f32_16x16x32_f16 v[70:73], v[122:125], v[90:93], v[70:73]
	ds_read_b128 v[90:93], v23 offset:16384
	v_mfma_f32_16x16x32_f16 v[48:51], v[122:125], v[110:113], v[48:51]
	ds_read_b128 v[110:113], v23 offset:18432
	s_waitcnt lgkmcnt(1)
	v_mfma_f32_16x16x32_f16 v[36:39], v[62:65], v[90:93], v[36:39]
	ds_read_b128 v[122:125], v22 offset:55296
	s_waitcnt lgkmcnt(1)
	v_mfma_f32_16x16x32_f16 v[66:69], v[62:65], v[110:113], v[66:69]
	s_waitcnt vmcnt(4)
	ds_write_b128 v20, v[134:137]
	v_mfma_f32_16x16x32_f16 v[44:47], v[74:77], v[90:93], v[44:47]
	s_waitcnt vmcnt(3)
	ds_write_b128 v17, v[94:97] offset:32768
	v_mfma_f32_16x16x32_f16 v[78:81], v[74:77], v[110:113], v[78:81]
	s_waitcnt vmcnt(2)
	ds_write_b128 v18, v[162:165] offset:32768
	v_mfma_f32_16x16x32_f16 v[82:85], v[118:121], v[90:93], v[82:85]
	s_waitcnt vmcnt(1)
	ds_write_b128 v19, v[166:169] offset:32768
	v_mfma_f32_16x16x32_f16 v[86:89], v[118:121], v[110:113], v[86:89]
	s_waitcnt vmcnt(0)
	ds_write_b128 v20, v[190:193] offset:32768
	s_waitcnt lgkmcnt(5)
	v_mfma_f32_16x16x32_f16 v[28:31], v[122:125], v[90:93], v[28:31]
	ds_read_b128 v[90:93], v23 offset:20480
	v_mfma_f32_16x16x32_f16 v[32:35], v[122:125], v[110:113], v[32:35]
	ds_read_b128 v[110:113], v23 offset:22528
	s_waitcnt lgkmcnt(1)
	v_mfma_f32_16x16x32_f16 v[98:101], v[62:65], v[90:93], v[98:101]
	s_waitcnt lgkmcnt(0)
	v_mfma_f32_16x16x32_f16 v[52:55], v[62:65], v[110:113], v[52:55]
	global_load_dwordx4 v[62:65], v[0:1], off offset:384
	v_mfma_f32_16x16x32_f16 v[102:105], v[74:77], v[90:93], v[102:105]
	v_mfma_f32_16x16x32_f16 v[24:27], v[74:77], v[110:113], v[24:27]
	v_mfma_f32_16x16x32_f16 v[114:117], v[118:121], v[90:93], v[114:117]
	v_mfma_f32_16x16x32_f16 v[40:43], v[118:121], v[110:113], v[40:43]
	v_mfma_f32_16x16x32_f16 v[70:73], v[122:125], v[90:93], v[70:73]
	global_load_dwordx4 v[90:93], v[2:3], off offset:384
	global_load_dwordx4 v[130:133], v[4:5], off offset:384
	global_load_dwordx4 v[138:141], v[14:15], off offset:384
	global_load_dwordx4 v[74:77], v[10:11], off offset:384
	global_load_dwordx4 v[142:145], v[12:13], off offset:384
	global_load_dwordx4 v[154:157], v[8:9], off offset:384
	global_load_dwordx4 v[158:161], v[6:7], off offset:384
	s_waitcnt lgkmcnt(0)
	s_barrier
	v_mfma_f32_16x16x32_f16 v[48:51], v[122:125], v[110:113], v[48:51]
	ds_read_b128 v[58:61], v16 offset:32768
	ds_read_b128 v[106:109], v21
	s_waitcnt lgkmcnt(0)
	v_mfma_f32_16x16x32_f16 v[36:39], v[58:61], v[106:109], v[36:39]
	ds_read_b128 v[94:97], v16 offset:34816
	ds_read_b128 v[110:113], v21 offset:2048
	s_waitcnt lgkmcnt(0)
	v_mfma_f32_16x16x32_f16 v[66:69], v[58:61], v[110:113], v[66:69]
	ds_read_b128 v[118:121], v16 offset:36864
	v_mfma_f32_16x16x32_f16 v[44:47], v[94:97], v[106:109], v[44:47]
	ds_read_b128 v[122:125], v16 offset:38912
	v_mfma_f32_16x16x32_f16 v[78:81], v[94:97], v[110:113], v[78:81]
	s_waitcnt lgkmcnt(1)
	v_mfma_f32_16x16x32_f16 v[82:85], v[118:121], v[106:109], v[82:85]
	v_mfma_f32_16x16x32_f16 v[86:89], v[118:121], v[110:113], v[86:89]
	s_waitcnt lgkmcnt(0)
	v_mfma_f32_16x16x32_f16 v[28:31], v[122:125], v[106:109], v[28:31]
	ds_read_b128 v[106:109], v21 offset:4096
	v_mfma_f32_16x16x32_f16 v[32:35], v[122:125], v[110:113], v[32:35]
	ds_read_b128 v[110:113], v21 offset:6144
	s_waitcnt lgkmcnt(1)
	v_mfma_f32_16x16x32_f16 v[98:101], v[58:61], v[106:109], v[98:101]
	s_waitcnt lgkmcnt(0)
	v_mfma_f32_16x16x32_f16 v[52:55], v[58:61], v[110:113], v[52:55]
	ds_read_b128 v[58:61], v22 offset:32768
	v_mfma_f32_16x16x32_f16 v[102:105], v[94:97], v[106:109], v[102:105]
	v_mfma_f32_16x16x32_f16 v[24:27], v[94:97], v[110:113], v[24:27]
	ds_read_b128 v[94:97], v22 offset:34816
	v_mfma_f32_16x16x32_f16 v[114:117], v[118:121], v[106:109], v[114:117]
	s_waitcnt vmcnt(7)
	ds_write_b128 v17, v[62:65] offset:16384
	s_waitcnt vmcnt(6)
	ds_write_b128 v18, v[90:93] offset:16384
	v_mfma_f32_16x16x32_f16 v[40:43], v[118:121], v[110:113], v[40:43]
	ds_read_b128 v[118:121], v22 offset:36864
	s_waitcnt vmcnt(5)
; #define GL_LOAD(s_, kt_) if (VAR != 1) { a##s_##0 = GL_A(0, kt_); a##s_##1 = GL_A(1, kt_); a##s_##2 = GL_A(2, kt_); a##s_##3 = GL_A(3, kt_); b##s_##0 = GL_B(0, kt_); b##s_##1 = GL_B(1, kt_); b##s_##2 = GL_B(2, kt_); b##s_##3 = GL_B(3, kt_); }
; #define LDS_STORE(s_, buf_) if (VAR != 2) { LDS_ST1(sA, 0, buf_, a##s_##0) LDS_ST1(sA, 1, buf_, a##s_##1) LDS_ST1(sA, 2, buf_, a##s_##2) LDS_ST1(sA, 3, buf_, a##s_##3) LDS_ST1(sB, 0, buf_, b##s_##0) LDS_ST1(sB, 1, buf_, b##s_##1) LDS_ST1(sB, 2, buf_, b##s_##2) LDS_ST1(sB, 3, buf_, b##s_##3) }
;     ...
;   GL_LOAD(0, 0)
;   GL_LOAD(1, 1)
;   LDS_STORE(0, 0)
;   if (VAR != 4) __syncthreads();
; #pragma unroll
;   for (int kt = 0; kt < nk; kt += 2) {
;     if (kt + 2 < nk) { GL_LOAD(0, kt + 2) }
;     MMA_TILE(0)
;     LDS_STORE(1, 1)
;     if (VAR != 4) __syncthreads();
;     if (kt + 3 < nk) { GL_LOAD(1, kt + 3) }
;     MMA_TILE(1)
;     if (kt + 2 < nk) { LDS_STORE(0, 0) }
;     if (VAR != 4) __syncthreads();
;   }
	ds_write_b128 v19, v[130:133] offset:16384
	v_mfma_f32_16x16x32_f16 v[70:73], v[122:125], v[106:109], v[70:73]
	ds_read_b128 v[106:109], v23
	v_mfma_f32_16x16x32_f16 v[48:51], v[122:125], v[110:113], v[48:51]
	ds_read_b128 v[110:113], v23 offset:2048
	s_waitcnt lgkmcnt(1)
	v_mfma_f32_16x16x32_f16 v[36:39], v[58:61], v[106:109], v[36:39]
	ds_read_b128 v[122:125], v22 offset:38912
	s_waitcnt lgkmcnt(1)
	v_mfma_f32_16x16x32_f16 v[66:69], v[58:61], v[110:113], v[66:69]
	s_waitcnt vmcnt(4)
	ds_write_b128 v20, v[138:141] offset:16384
	v_mfma_f32_16x16x32_f16 v[44:47], v[94:97], v[106:109], v[44:47]
	s_waitcnt vmcnt(3)
	ds_write_b128 v17, v[74:77] offset:49152
	v_mfma_f32_16x16x32_f16 v[78:81], v[94:97], v[110:113], v[78:81]
	s_waitcnt vmcnt(2)
	ds_write_b128 v18, v[142:145] offset:49152
	v_mfma_f32_16x16x32_f16 v[82:85], v[118:121], v[106:109], v[82:85]
	s_waitcnt vmcnt(1)
	ds_write_b128 v19, v[154:157] offset:49152
	v_mfma_f32_16x16x32_f16 v[86:89], v[118:121], v[110:113], v[86:89]
	s_waitcnt vmcnt(0)
	ds_write_b128 v20, v[158:161] offset:49152
	s_waitcnt lgkmcnt(5)
	v_mfma_f32_16x16x32_f16 v[28:31], v[122:125], v[106:109], v[28:31]
	ds_read_b128 v[106:109], v23 offset:4096
	v_mfma_f32_16x16x32_f16 v[32:35], v[122:125], v[110:113], v[32:35]
	ds_read_b128 v[110:113], v23 offset:6144
	s_waitcnt lgkmcnt(1)
	v_mfma_f32_16x16x32_f16 v[98:101], v[58:61], v[106:109], v[98:101]
	s_waitcnt lgkmcnt(0)
	v_mfma_f32_16x16x32_f16 v[52:55], v[58:61], v[110:113], v[52:55]
	global_load_dwordx4 v[58:61], v[0:1], off offset:512
	v_mfma_f32_16x16x32_f16 v[102:105], v[94:97], v[106:109], v[102:105]
	v_mfma_f32_16x16x32_f16 v[24:27], v[94:97], v[110:113], v[24:27]
	v_mfma_f32_16x16x32_f16 v[114:117], v[118:121], v[106:109], v[114:117]
	v_mfma_f32_16x16x32_f16 v[40:43], v[118:121], v[110:113], v[40:43]
	v_mfma_f32_16x16x32_f16 v[70:73], v[122:125], v[106:109], v[70:73]
	global_load_dwordx4 v[106:109], v[2:3], off offset:512
	global_load_dwordx4 v[126:129], v[4:5], off offset:512
	global_load_dwordx4 v[134:137], v[14:15], off offset:512
	global_load_dwordx4 v[94:97], v[10:11], off offset:512
	global_load_dwordx4 v[162:165], v[12:13], off offset:512
	global_load_dwordx4 v[166:169], v[8:9], off offset:512
	global_load_dwordx4 v[190:193], v[6:7], off offset:512
	s_waitcnt lgkmcnt(0)
	s_barrier
	v_mfma_f32_16x16x32_f16 v[48:51], v[122:125], v[110:113], v[48:51]
	ds_read_b128 v[62:65], v16 offset:49152
	ds_read_b128 v[90:93], v21 offset:16384
	s_waitcnt lgkmcnt(0)
	v_mfma_f32_16x16x32_f16 v[36:39], v[62:65], v[90:93], v[36:39]
	ds_read_b128 v[74:77], v16 offset:51200
	ds_read_b128 v[110:113], v21 offset:18432
	s_waitcnt lgkmcnt(0)
	v_mfma_f32_16x16x32_f16 v[66:69], v[62:65], v[110:113], v[66:69]
	ds_read_b128 v[118:121], v16 offset:53248
	v_mfma_f32_16x16x32_f16 v[44:47], v[74:77], v[90:93], v[44:47]
	ds_read_b128 v[122:125], v16 offset:55296
	v_mfma_f32_16x16x32_f16 v[78:81], v[74:77], v[110:113], v[78:81]
	s_waitcnt lgkmcnt(1)
	v_mfma_f32_16x16x32_f16 v[82:85], v[118:121], v[90:93], v[82:85]
	v_mfma_f32_16x16x32_f16 v[86:89], v[118:121], v[110:113], v[86:89]
	s_waitcnt lgkmcnt(0)
	v_mfma_f32_16x16x32_f16 v[28:31], v[122:125], v[90:93], v[28:31]
	ds_read_b128 v[90:93], v21 offset:20480
	v_mfma_f32_16x16x32_f16 v[32:35], v[122:125], v[110:113], v[32:35]
	ds_read_b128 v[110:113], v21 offset:22528
	s_waitcnt lgkmcnt(1)
	v_mfma_f32_16x16x32_f16 v[98:101], v[62:65], v[90:93], v[98:101]
	s_waitcnt lgkmcnt(0)
	v_mfma_f32_16x16x32_f16 v[52:55], v[62:65], v[110:113], v[52:55]
	ds_read_b128 v[62:65], v22 offset:49152
	v_mfma_f32_16x16x32_f16 v[102:105], v[74:77], v[90:93], v[102:105]
	v_mfma_f32_16x16x32_f16 v[24:27], v[74:77], v[110:113], v[24:27]
	ds_read_b128 v[74:77], v22 offset:51200
	v_mfma_f32_16x16x32_f16 v[114:117], v[118:121], v[90:93], v[114:117]
	s_waitcnt vmcnt(7)
	ds_write_b128 v17, v[58:61]
	s_waitcnt vmcnt(6)
	ds_write_b128 v18, v[106:109]
	v_mfma_f32_16x16x32_f16 v[40:43], v[118:121], v[110:113], v[40:43]
	ds_read_b128 v[118:121], v22 offset:53248
	s_waitcnt vmcnt(5)
	ds_write_b128 v19, v[126:129]
	v_mfma_f32_16x16x32_f16 v[70:73], v[122:125], v[90:93], v[70:73]
	ds_read_b128 v[90:93], v23 offset:16384
	v_mfma_f32_16x16x32_f16 v[48:51], v[122:125], v[110:113], v[48:51]
	ds_read_b128 v[110:113], v23 offset:18432
	s_waitcnt lgkmcnt(1)
	v_mfma_f32_16x16x32_f16 v[36:39], v[62:65], v[90:93], v[36:39]
	ds_read_b128 v[122:125], v22 offset:55296
	s_waitcnt lgkmcnt(1)
	v_mfma_f32_16x16x32_f16 v[66:69], v[62:65], v[110:113], v[66:69]
	s_waitcnt vmcnt(4)
	ds_write_b128 v20, v[134:137]
	v_mfma_f32_16x16x32_f16 v[44:47], v[74:77], v[90:93], v[44:47]
	s_waitcnt vmcnt(3)
	ds_write_b128 v17, v[94:97] offset:32768
	v_mfma_f32_16x16x32_f16 v[78:81], v[74:77], v[110:113], v[78:81]
	s_waitcnt vmcnt(2)
	ds_write_b128 v18, v[162:165] offset:32768
	v_mfma_f32_16x16x32_f16 v[82:85], v[118:121], v[90:93], v[82:85]
	s_waitcnt vmcnt(1)
	ds_write_b128 v19, v[166:169] offset:32768
	v_mfma_f32_16x16x32_f16 v[86:89], v[118:121], v[110:113], v[86:89]
	s_waitcnt vmcnt(0)
	ds_write_b128 v20, v[190:193] offset:32768
	s_waitcnt lgkmcnt(5)
	v_mfma_f32_16x16x32_f16 v[28:31], v[122:125], v[90:93], v[28:31]
	ds_read_b128 v[90:93], v23 offset:20480
	v_mfma_f32_16x16x32_f16 v[32:35], v[122:125], v[110:113], v[32:35]
	ds_read_b128 v[110:113], v23 offset:22528
	s_waitcnt lgkmcnt(1)
	v_mfma_f32_16x16x32_f16 v[98:101], v[62:65], v[90:93], v[98:101]
	s_waitcnt lgkmcnt(0)
	v_mfma_f32_16x16x32_f16 v[52:55], v[62:65], v[110:113], v[52:55]
	global_load_dwordx4 v[62:65], v[0:1], off offset:640
	v_mfma_f32_16x16x32_f16 v[102:105], v[74:77], v[90:93], v[102:105]
	v_mfma_f32_16x16x32_f16 v[24:27], v[74:77], v[110:113], v[24:27]
	v_mfma_f32_16x16x32_f16 v[114:117], v[118:121], v[90:93], v[114:117]
	v_mfma_f32_16x16x32_f16 v[40:43], v[118:121], v[110:113], v[40:43]
	v_mfma_f32_16x16x32_f16 v[70:73], v[122:125], v[90:93], v[70:73]
	global_load_dwordx4 v[90:93], v[2:3], off offset:640
	global_load_dwordx4 v[130:133], v[4:5], off offset:640
	global_load_dwordx4 v[138:141], v[14:15], off offset:640
	global_load_dwordx4 v[74:77], v[10:11], off offset:640
	global_load_dwordx4 v[142:145], v[12:13], off offset:640
	global_load_dwordx4 v[154:157], v[8:9], off offset:640
	global_load_dwordx4 v[158:161], v[6:7], off offset:640
	s_waitcnt lgkmcnt(0)
	s_barrier
; #define GL_LOAD(s_, kt_) if (VAR != 1) { a##s_##0 = GL_A(0, kt_); a##s_##1 = GL_A(1, kt_); a##s_##2 = GL_A(2, kt_); a##s_##3 = GL_A(3, kt_); b##s_##0 = GL_B(0, kt_); b##s_##1 = GL_B(1, kt_); b##s_##2 = GL_B(2, kt_); b##s_##3 = GL_B(3, kt_); }
; #define LDS_STORE(s_, buf_) if (VAR != 2) { LDS_ST1(sA, 0, buf_, a##s_##0) LDS_ST1(sA, 1, buf_, a##s_##1) LDS_ST1(sA, 2, buf_, a##s_##2) LDS_ST1(sA, 3, buf_, a##s_##3) LDS_ST1(sB, 0, buf_, b##s_##0) LDS_ST1(sB, 1, buf_, b##s_##1) LDS_ST1(sB, 2, buf_, b##s_##2) LDS_ST1(sB, 3, buf_, b##s_##3) }
;     ...
;   GL_LOAD(0, 0)
;   GL_LOAD(1, 1)
;   LDS_STORE(0, 0)
;   if (VAR != 4) __syncthreads();
; #pragma unroll
;   for (int kt = 0; kt < nk; kt += 2) {
;     if (kt + 2 < nk) { GL_LOAD(0, kt + 2) }
;     MMA_TILE(0)
;     LDS_STORE(1, 1)
;     if (VAR != 4) __syncthreads();
;     if (kt + 3 < nk) { GL_LOAD(1, kt + 3) }
;     MMA_TILE(1)
;     if (kt + 2 < nk) { LDS_STORE(0, 0) }
;     if (VAR != 4) __syncthreads();
;   }
	v_mfma_f32_16x16x32_f16 v[48:51], v[122:125], v[110:113], v[48:51]
	ds_read_b128 v[58:61], v16 offset:32768
	ds_read_b128 v[106:109], v21
	s_waitcnt lgkmcnt(0)
	v_mfma_f32_16x16x32_f16 v[36:39], v[58:61], v[106:109], v[36:39]
	ds_read_b128 v[94:97], v16 offset:34816
	ds_read_b128 v[110:113], v21 offset:2048
	s_waitcnt lgkmcnt(0)
	v_mfma_f32_16x16x32_f16 v[66:69], v[58:61], v[110:113], v[66:69]
	ds_read_b128 v[118:121], v16 offset:36864
	v_mfma_f32_16x16x32_f16 v[44:47], v[94:97], v[106:109], v[44:47]
	ds_read_b128 v[122:125], v16 offset:38912
	v_mfma_f32_16x16x32_f16 v[78:81], v[94:97], v[110:113], v[78:81]
	s_waitcnt lgkmcnt(1)
	v_mfma_f32_16x16x32_f16 v[82:85], v[118:121], v[106:109], v[82:85]
	v_mfma_f32_16x16x32_f16 v[86:89], v[118:121], v[110:113], v[86:89]
	s_waitcnt lgkmcnt(0)
	v_mfma_f32_16x16x32_f16 v[28:31], v[122:125], v[106:109], v[28:31]
	ds_read_b128 v[106:109], v21 offset:4096
	v_mfma_f32_16x16x32_f16 v[32:35], v[122:125], v[110:113], v[32:35]
	ds_read_b128 v[110:113], v21 offset:6144
	s_waitcnt lgkmcnt(1)
	v_mfma_f32_16x16x32_f16 v[98:101], v[58:61], v[106:109], v[98:101]
	s_waitcnt lgkmcnt(0)
	v_mfma_f32_16x16x32_f16 v[52:55], v[58:61], v[110:113], v[52:55]
	ds_read_b128 v[58:61], v22 offset:32768
	v_mfma_f32_16x16x32_f16 v[102:105], v[94:97], v[106:109], v[102:105]
	v_mfma_f32_16x16x32_f16 v[24:27], v[94:97], v[110:113], v[24:27]
	ds_read_b128 v[94:97], v22 offset:34816
	v_mfma_f32_16x16x32_f16 v[114:117], v[118:121], v[106:109], v[114:117]
	s_waitcnt vmcnt(7)
	ds_write_b128 v17, v[62:65] offset:16384
	s_waitcnt vmcnt(6)
	ds_write_b128 v18, v[90:93] offset:16384
	v_mfma_f32_16x16x32_f16 v[40:43], v[118:121], v[110:113], v[40:43]
	ds_read_b128 v[118:121], v22 offset:36864
	s_waitcnt vmcnt(5)
	ds_write_b128 v19, v[130:133] offset:16384
	v_mfma_f32_16x16x32_f16 v[70:73], v[122:125], v[106:109], v[70:73]
	ds_read_b128 v[106:109], v23
	v_mfma_f32_16x16x32_f16 v[48:51], v[122:125], v[110:113], v[48:51]
	ds_read_b128 v[110:113], v23 offset:2048
	s_waitcnt lgkmcnt(1)
	v_mfma_f32_16x16x32_f16 v[36:39], v[58:61], v[106:109], v[36:39]
	ds_read_b128 v[122:125], v22 offset:38912
	s_waitcnt lgkmcnt(1)
	v_mfma_f32_16x16x32_f16 v[66:69], v[58:61], v[110:113], v[66:69]
	s_waitcnt vmcnt(4)
	ds_write_b128 v20, v[138:141] offset:16384
	v_mfma_f32_16x16x32_f16 v[44:47], v[94:97], v[106:109], v[44:47]
	s_waitcnt vmcnt(3)
	ds_write_b128 v17, v[74:77] offset:49152
	v_mfma_f32_16x16x32_f16 v[78:81], v[94:97], v[110:113], v[78:81]
	s_waitcnt vmcnt(2)
	ds_write_b128 v18, v[142:145] offset:49152
	v_mfma_f32_16x16x32_f16 v[82:85], v[118:121], v[106:109], v[82:85]
	s_waitcnt vmcnt(1)
	ds_write_b128 v19, v[154:157] offset:49152
	v_mfma_f32_16x16x32_f16 v[86:89], v[118:121], v[110:113], v[86:89]
	s_waitcnt vmcnt(0)
	ds_write_b128 v20, v[158:161] offset:49152
	s_waitcnt lgkmcnt(5)
	v_mfma_f32_16x16x32_f16 v[28:31], v[122:125], v[106:109], v[28:31]
	ds_read_b128 v[106:109], v23 offset:4096
	v_mfma_f32_16x16x32_f16 v[32:35], v[122:125], v[110:113], v[32:35]
	ds_read_b128 v[110:113], v23 offset:6144
	s_waitcnt lgkmcnt(1)
	v_mfma_f32_16x16x32_f16 v[98:101], v[58:61], v[106:109], v[98:101]
	s_waitcnt lgkmcnt(0)
	v_mfma_f32_16x16x32_f16 v[52:55], v[58:61], v[110:113], v[52:55]
	global_load_dwordx4 v[58:61], v[0:1], off offset:768
	v_mfma_f32_16x16x32_f16 v[102:105], v[94:97], v[106:109], v[102:105]
	v_mfma_f32_16x16x32_f16 v[24:27], v[94:97], v[110:113], v[24:27]
	v_mfma_f32_16x16x32_f16 v[114:117], v[118:121], v[106:109], v[114:117]
	v_mfma_f32_16x16x32_f16 v[40:43], v[118:121], v[110:113], v[40:43]
	v_mfma_f32_16x16x32_f16 v[70:73], v[122:125], v[106:109], v[70:73]
	global_load_dwordx4 v[106:109], v[2:3], off offset:768
	global_load_dwordx4 v[126:129], v[4:5], off offset:768
	global_load_dwordx4 v[134:137], v[14:15], off offset:768
	global_load_dwordx4 v[94:97], v[10:11], off offset:768
	global_load_dwordx4 v[162:165], v[12:13], off offset:768
	global_load_dwordx4 v[166:169], v[8:9], off offset:768
	global_load_dwordx4 v[190:193], v[6:7], off offset:768
	s_waitcnt lgkmcnt(0)
	s_barrier
	v_mfma_f32_16x16x32_f16 v[48:51], v[122:125], v[110:113], v[48:51]
	ds_read_b128 v[62:65], v16 offset:49152
	ds_read_b128 v[90:93], v21 offset:16384
	s_waitcnt lgkmcnt(0)
	v_mfma_f32_16x16x32_f16 v[36:39], v[62:65], v[90:93], v[36:39]
	ds_read_b128 v[74:77], v16 offset:51200
	ds_read_b128 v[110:113], v21 offset:18432
	s_waitcnt lgkmcnt(0)
	v_mfma_f32_16x16x32_f16 v[66:69], v[62:65], v[110:113], v[66:69]
	ds_read_b128 v[118:121], v16 offset:53248
	v_mfma_f32_16x16x32_f16 v[44:47], v[74:77], v[90:93], v[44:47]
	ds_read_b128 v[122:125], v16 offset:55296
	v_mfma_f32_16x16x32_f16 v[78:81], v[74:77], v[110:113], v[78:81]
	s_waitcnt lgkmcnt(1)
	v_mfma_f32_16x16x32_f16 v[82:85], v[118:121], v[90:93], v[82:85]
	v_mfma_f32_16x16x32_f16 v[86:89], v[118:121], v[110:113], v[86:89]
	s_waitcnt lgkmcnt(0)
	v_mfma_f32_16x16x32_f16 v[28:31], v[122:125], v[90:93], v[28:31]
	ds_read_b128 v[90:93], v21 offset:20480
	v_mfma_f32_16x16x32_f16 v[32:35], v[122:125], v[110:113], v[32:35]
	ds_read_b128 v[110:113], v21 offset:22528
	s_waitcnt lgkmcnt(1)
	v_mfma_f32_16x16x32_f16 v[98:101], v[62:65], v[90:93], v[98:101]
	s_waitcnt lgkmcnt(0)
	v_mfma_f32_16x16x32_f16 v[52:55], v[62:65], v[110:113], v[52:55]
	ds_read_b128 v[62:65], v22 offset:49152
	v_mfma_f32_16x16x32_f16 v[102:105], v[74:77], v[90:93], v[102:105]
	v_mfma_f32_16x16x32_f16 v[24:27], v[74:77], v[110:113], v[24:27]
	ds_read_b128 v[74:77], v22 offset:51200
	v_mfma_f32_16x16x32_f16 v[114:117], v[118:121], v[90:93], v[114:117]
	s_waitcnt vmcnt(7)
	ds_write_b128 v17, v[58:61]
	s_waitcnt vmcnt(6)
; #define GL_LOAD(s_, kt_) if (VAR != 1) { a##s_##0 = GL_A(0, kt_); a##s_##1 = GL_A(1, kt_); a##s_##2 = GL_A(2, kt_); a##s_##3 = GL_A(3, kt_); b##s_##0 = GL_B(0, kt_); b##s_##1 = GL_B(1, kt_); b##s_##2 = GL_B(2, kt_); b##s_##3 = GL_B(3, kt_); }
; #define LDS_STORE(s_, buf_) if (VAR != 2) { LDS_ST1(sA, 0, buf_, a##s_##0) LDS_ST1(sA, 1, buf_, a##s_##1) LDS_ST1(sA, 2, buf_, a##s_##2) LDS_ST1(sA, 3, buf_, a##s_##3) LDS_ST1(sB, 0, buf_, b##s_##0) LDS_ST1(sB, 1, buf_, b##s_##1) LDS_ST1(sB, 2, buf_, b##s_##2) LDS_ST1(sB, 3, buf_, b##s_##3) }
;     ...
;   GL_LOAD(0, 0)
;   GL_LOAD(1, 1)
;   LDS_STORE(0, 0)
;   if (VAR != 4) __syncthreads();
; #pragma unroll
;   for (int kt = 0; kt < nk; kt += 2) {
;     if (kt + 2 < nk) { GL_LOAD(0, kt + 2) }
;     MMA_TILE(0)
;     LDS_STORE(1, 1)
;     if (VAR != 4) __syncthreads();
;     if (kt + 3 < nk) { GL_LOAD(1, kt + 3) }
;     MMA_TILE(1)
;     if (kt + 2 < nk) { LDS_STORE(0, 0) }
;     if (VAR != 4) __syncthreads();
;   }
	ds_write_b128 v18, v[106:109]
	v_mfma_f32_16x16x32_f16 v[40:43], v[118:121], v[110:113], v[40:43]
	ds_read_b128 v[118:121], v22 offset:53248
	s_waitcnt vmcnt(5)
	ds_write_b128 v19, v[126:129]
	v_mfma_f32_16x16x32_f16 v[70:73], v[122:125], v[90:93], v[70:73]
	ds_read_b128 v[90:93], v23 offset:16384
	v_mfma_f32_16x16x32_f16 v[48:51], v[122:125], v[110:113], v[48:51]
	ds_read_b128 v[110:113], v23 offset:18432
	s_waitcnt lgkmcnt(1)
	v_mfma_f32_16x16x32_f16 v[36:39], v[62:65], v[90:93], v[36:39]
	ds_read_b128 v[122:125], v22 offset:55296
	s_waitcnt lgkmcnt(1)
	v_mfma_f32_16x16x32_f16 v[66:69], v[62:65], v[110:113], v[66:69]
	s_waitcnt vmcnt(4)
	ds_write_b128 v20, v[134:137]
	v_mfma_f32_16x16x32_f16 v[44:47], v[74:77], v[90:93], v[44:47]
	s_waitcnt vmcnt(3)
	ds_write_b128 v17, v[94:97] offset:32768
	v_mfma_f32_16x16x32_f16 v[78:81], v[74:77], v[110:113], v[78:81]
	s_waitcnt vmcnt(2)
	ds_write_b128 v18, v[162:165] offset:32768
	v_mfma_f32_16x16x32_f16 v[82:85], v[118:121], v[90:93], v[82:85]
	s_waitcnt vmcnt(1)
	ds_write_b128 v19, v[166:169] offset:32768
	v_mfma_f32_16x16x32_f16 v[86:89], v[118:121], v[110:113], v[86:89]
	s_waitcnt vmcnt(0)
	ds_write_b128 v20, v[190:193] offset:32768
	s_waitcnt lgkmcnt(5)
	v_mfma_f32_16x16x32_f16 v[28:31], v[122:125], v[90:93], v[28:31]
	ds_read_b128 v[90:93], v23 offset:20480
	v_mfma_f32_16x16x32_f16 v[32:35], v[122:125], v[110:113], v[32:35]
	ds_read_b128 v[110:113], v23 offset:22528
	s_waitcnt lgkmcnt(1)
	v_mfma_f32_16x16x32_f16 v[98:101], v[62:65], v[90:93], v[98:101]
	s_waitcnt lgkmcnt(0)
	v_mfma_f32_16x16x32_f16 v[52:55], v[62:65], v[110:113], v[52:55]
	global_load_dwordx4 v[62:65], v[0:1], off offset:896
	v_mfma_f32_16x16x32_f16 v[102:105], v[74:77], v[90:93], v[102:105]
	v_mfma_f32_16x16x32_f16 v[24:27], v[74:77], v[110:113], v[24:27]
	v_mfma_f32_16x16x32_f16 v[114:117], v[118:121], v[90:93], v[114:117]
	v_mfma_f32_16x16x32_f16 v[40:43], v[118:121], v[110:113], v[40:43]
	v_mfma_f32_16x16x32_f16 v[70:73], v[122:125], v[90:93], v[70:73]
	global_load_dwordx4 v[90:93], v[2:3], off offset:896
	global_load_dwordx4 v[130:133], v[4:5], off offset:896
	global_load_dwordx4 v[138:141], v[14:15], off offset:896
	global_load_dwordx4 v[74:77], v[10:11], off offset:896
	global_load_dwordx4 v[142:145], v[12:13], off offset:896
	global_load_dwordx4 v[154:157], v[8:9], off offset:896
	global_load_dwordx4 v[158:161], v[6:7], off offset:896
	s_waitcnt lgkmcnt(0)
	s_barrier
	v_mfma_f32_16x16x32_f16 v[48:51], v[122:125], v[110:113], v[48:51]
	ds_read_b128 v[58:61], v16 offset:32768
	ds_read_b128 v[106:109], v21
	s_waitcnt lgkmcnt(0)
	v_mfma_f32_16x16x32_f16 v[36:39], v[58:61], v[106:109], v[36:39]
	ds_read_b128 v[94:97], v16 offset:34816
	ds_read_b128 v[110:113], v21 offset:2048
	s_waitcnt lgkmcnt(0)
	v_mfma_f32_16x16x32_f16 v[66:69], v[58:61], v[110:113], v[66:69]
	ds_read_b128 v[118:121], v16 offset:36864
	v_mfma_f32_16x16x32_f16 v[44:47], v[94:97], v[106:109], v[44:47]
	ds_read_b128 v[122:125], v16 offset:38912
	v_mfma_f32_16x16x32_f16 v[78:81], v[94:97], v[110:113], v[78:81]
	s_waitcnt lgkmcnt(1)
	v_mfma_f32_16x16x32_f16 v[82:85], v[118:121], v[106:109], v[82:85]
	v_mfma_f32_16x16x32_f16 v[86:89], v[118:121], v[110:113], v[86:89]
	s_waitcnt lgkmcnt(0)
	v_mfma_f32_16x16x32_f16 v[28:31], v[122:125], v[106:109], v[28:31]
	ds_read_b128 v[106:109], v21 offset:4096
	v_mfma_f32_16x16x32_f16 v[32:35], v[122:125], v[110:113], v[32:35]
	ds_read_b128 v[110:113], v21 offset:6144
	s_waitcnt lgkmcnt(1)
	v_mfma_f32_16x16x32_f16 v[98:101], v[58:61], v[106:109], v[98:101]
	s_waitcnt lgkmcnt(0)
	v_mfma_f32_16x16x32_f16 v[52:55], v[58:61], v[110:113], v[52:55]
	ds_read_b128 v[58:61], v22 offset:32768
	v_mfma_f32_16x16x32_f16 v[102:105], v[94:97], v[106:109], v[102:105]
	v_mfma_f32_16x16x32_f16 v[24:27], v[94:97], v[110:113], v[24:27]
	ds_read_b128 v[94:97], v22 offset:34816
	v_mfma_f32_16x16x32_f16 v[114:117], v[118:121], v[106:109], v[114:117]
	s_waitcnt vmcnt(7)
	ds_write_b128 v17, v[62:65] offset:16384
	s_waitcnt vmcnt(6)
	ds_write_b128 v18, v[90:93] offset:16384
	v_mfma_f32_16x16x32_f16 v[40:43], v[118:121], v[110:113], v[40:43]
	ds_read_b128 v[118:121], v22 offset:36864
	s_waitcnt vmcnt(5)
	ds_write_b128 v19, v[130:133] offset:16384
	v_mfma_f32_16x16x32_f16 v[70:73], v[122:125], v[106:109], v[70:73]
	ds_read_b128 v[106:109], v23
	v_mfma_f32_16x16x32_f16 v[48:51], v[122:125], v[110:113], v[48:51]
	ds_read_b128 v[110:113], v23 offset:2048
	s_waitcnt lgkmcnt(1)
	v_mfma_f32_16x16x32_f16 v[36:39], v[58:61], v[106:109], v[36:39]
	ds_read_b128 v[122:125], v22 offset:38912
	s_waitcnt lgkmcnt(1)
	v_mfma_f32_16x16x32_f16 v[66:69], v[58:61], v[110:113], v[66:69]
	s_waitcnt vmcnt(4)
	ds_write_b128 v20, v[138:141] offset:16384
	v_mfma_f32_16x16x32_f16 v[44:47], v[94:97], v[106:109], v[44:47]
	s_waitcnt vmcnt(3)
	ds_write_b128 v17, v[74:77] offset:49152
	v_mfma_f32_16x16x32_f16 v[78:81], v[94:97], v[110:113], v[78:81]
	s_waitcnt vmcnt(2)
	ds_write_b128 v18, v[142:145] offset:49152
	v_mfma_f32_16x16x32_f16 v[82:85], v[118:121], v[106:109], v[82:85]
	s_waitcnt vmcnt(1)
	ds_write_b128 v19, v[154:157] offset:49152
	v_mfma_f32_16x16x32_f16 v[86:89], v[118:121], v[110:113], v[86:89]
	s_waitcnt vmcnt(0)
	ds_write_b128 v20, v[158:161] offset:49152
	s_waitcnt lgkmcnt(5)
	v_mfma_f32_16x16x32_f16 v[28:31], v[122:125], v[106:109], v[28:31]
	ds_read_b128 v[106:109], v23 offset:4096
	v_mfma_f32_16x16x32_f16 v[32:35], v[122:125], v[110:113], v[32:35]
	ds_read_b128 v[110:113], v23 offset:6144
	s_waitcnt lgkmcnt(1)
	v_mfma_f32_16x16x32_f16 v[98:101], v[58:61], v[106:109], v[98:101]
	s_waitcnt lgkmcnt(0)
	v_mfma_f32_16x16x32_f16 v[52:55], v[58:61], v[110:113], v[52:55]
	global_load_dwordx4 v[58:61], v[0:1], off offset:1024
	v_mfma_f32_16x16x32_f16 v[102:105], v[94:97], v[106:109], v[102:105]
	v_mfma_f32_16x16x32_f16 v[24:27], v[94:97], v[110:113], v[24:27]
	v_mfma_f32_16x16x32_f16 v[114:117], v[118:121], v[106:109], v[114:117]
	v_mfma_f32_16x16x32_f16 v[40:43], v[118:121], v[110:113], v[40:43]
	v_mfma_f32_16x16x32_f16 v[70:73], v[122:125], v[106:109], v[70:73]
	global_load_dwordx4 v[106:109], v[2:3], off offset:1024
	global_load_dwordx4 v[126:129], v[4:5], off offset:1024
	global_load_dwordx4 v[134:137], v[14:15], off offset:1024
	global_load_dwordx4 v[94:97], v[10:11], off offset:1024
	global_load_dwordx4 v[162:165], v[12:13], off offset:1024
	global_load_dwordx4 v[166:169], v[8:9], off offset:1024
	global_load_dwordx4 v[190:193], v[6:7], off offset:1024
	s_waitcnt lgkmcnt(0)
	s_barrier
; #define GL_LOAD(s_, kt_) if (VAR != 1) { a##s_##0 = GL_A(0, kt_); a##s_##1 = GL_A(1, kt_); a##s_##2 = GL_A(2, kt_); a##s_##3 = GL_A(3, kt_); b##s_##0 = GL_B(0, kt_); b##s_##1 = GL_B(1, kt_); b##s_##2 = GL_B(2, kt_); b##s_##3 = GL_B(3, kt_); }
; #define LDS_STORE(s_, buf_) if (VAR != 2) { LDS_ST1(sA, 0, buf_, a##s_##0) LDS_ST1(sA, 1, buf_, a##s_##1) LDS_ST1(sA, 2, buf_, a##s_##2) LDS_ST1(sA, 3, buf_, a##s_##3) LDS_ST1(sB, 0, buf_, b##s_##0) LDS_ST1(sB, 1, buf_, b##s_##1) LDS_ST1(sB, 2, buf_, b##s_##2) LDS_ST1(sB, 3, buf_, b##s_##3) }
;     ...
;   GL_LOAD(0, 0)
;   GL_LOAD(1, 1)
;   LDS_STORE(0, 0)
;   if (VAR != 4) __syncthreads();
; #pragma unroll
;   for (int kt = 0; kt < nk; kt += 2) {
;     if (kt + 2 < nk) { GL_LOAD(0, kt + 2) }
;     MMA_TILE(0)
;     LDS_STORE(1, 1)
;     if (VAR != 4) __syncthreads();
;     if (kt + 3 < nk) { GL_LOAD(1, kt + 3) }
;     MMA_TILE(1)
;     if (kt + 2 < nk) { LDS_STORE(0, 0) }
;     if (VAR != 4) __syncthreads();
;   }
	v_mfma_f32_16x16x32_f16 v[48:51], v[122:125], v[110:113], v[48:51]
	ds_read_b128 v[62:65], v16 offset:49152
	ds_read_b128 v[90:93], v21 offset:16384
	s_waitcnt lgkmcnt(0)
	v_mfma_f32_16x16x32_f16 v[36:39], v[62:65], v[90:93], v[36:39]
	ds_read_b128 v[74:77], v16 offset:51200
	ds_read_b128 v[110:113], v21 offset:18432
	s_waitcnt lgkmcnt(0)
	v_mfma_f32_16x16x32_f16 v[66:69], v[62:65], v[110:113], v[66:69]
	ds_read_b128 v[118:121], v16 offset:53248
	v_mfma_f32_16x16x32_f16 v[44:47], v[74:77], v[90:93], v[44:47]
	ds_read_b128 v[122:125], v16 offset:55296
	v_mfma_f32_16x16x32_f16 v[78:81], v[74:77], v[110:113], v[78:81]
	s_waitcnt lgkmcnt(1)
	v_mfma_f32_16x16x32_f16 v[82:85], v[118:121], v[90:93], v[82:85]
	v_mfma_f32_16x16x32_f16 v[86:89], v[118:121], v[110:113], v[86:89]
	s_waitcnt lgkmcnt(0)
	v_mfma_f32_16x16x32_f16 v[28:31], v[122:125], v[90:93], v[28:31]
	ds_read_b128 v[90:93], v21 offset:20480
	v_mfma_f32_16x16x32_f16 v[32:35], v[122:125], v[110:113], v[32:35]
	ds_read_b128 v[110:113], v21 offset:22528
	s_waitcnt lgkmcnt(1)
	v_mfma_f32_16x16x32_f16 v[98:101], v[62:65], v[90:93], v[98:101]
	s_waitcnt lgkmcnt(0)
	v_mfma_f32_16x16x32_f16 v[52:55], v[62:65], v[110:113], v[52:55]
	ds_read_b128 v[62:65], v22 offset:49152
	v_mfma_f32_16x16x32_f16 v[102:105], v[74:77], v[90:93], v[102:105]
	v_mfma_f32_16x16x32_f16 v[24:27], v[74:77], v[110:113], v[24:27]
	ds_read_b128 v[74:77], v22 offset:51200
	v_mfma_f32_16x16x32_f16 v[114:117], v[118:121], v[90:93], v[114:117]
	s_waitcnt vmcnt(7)
	ds_write_b128 v17, v[58:61]
	s_waitcnt vmcnt(6)
	ds_write_b128 v18, v[106:109]
	v_mfma_f32_16x16x32_f16 v[40:43], v[118:121], v[110:113], v[40:43]
	ds_read_b128 v[118:121], v22 offset:53248
	s_waitcnt vmcnt(5)
	ds_write_b128 v19, v[126:129]
	v_mfma_f32_16x16x32_f16 v[70:73], v[122:125], v[90:93], v[70:73]
	ds_read_b128 v[90:93], v23 offset:16384
	v_mfma_f32_16x16x32_f16 v[48:51], v[122:125], v[110:113], v[48:51]
	ds_read_b128 v[110:113], v23 offset:18432
	s_waitcnt lgkmcnt(1)
	v_mfma_f32_16x16x32_f16 v[36:39], v[62:65], v[90:93], v[36:39]
	ds_read_b128 v[122:125], v22 offset:55296
	s_waitcnt lgkmcnt(1)
	v_mfma_f32_16x16x32_f16 v[66:69], v[62:65], v[110:113], v[66:69]
	s_waitcnt vmcnt(4)
	ds_write_b128 v20, v[134:137]
	v_mfma_f32_16x16x32_f16 v[44:47], v[74:77], v[90:93], v[44:47]
	s_waitcnt vmcnt(3)
	ds_write_b128 v17, v[94:97] offset:32768
	v_mfma_f32_16x16x32_f16 v[78:81], v[74:77], v[110:113], v[78:81]
	s_waitcnt vmcnt(2)
	ds_write_b128 v18, v[162:165] offset:32768
	v_mfma_f32_16x16x32_f16 v[82:85], v[118:121], v[90:93], v[82:85]
	s_waitcnt vmcnt(1)
	ds_write_b128 v19, v[166:169] offset:32768
	v_mfma_f32_16x16x32_f16 v[86:89], v[118:121], v[110:113], v[86:89]
	s_waitcnt vmcnt(0)
	ds_write_b128 v20, v[190:193] offset:32768
	s_waitcnt lgkmcnt(5)
	v_mfma_f32_16x16x32_f16 v[28:31], v[122:125], v[90:93], v[28:31]
	ds_read_b128 v[90:93], v23 offset:20480
	v_mfma_f32_16x16x32_f16 v[32:35], v[122:125], v[110:113], v[32:35]
	ds_read_b128 v[110:113], v23 offset:22528
	s_waitcnt lgkmcnt(1)
	v_mfma_f32_16x16x32_f16 v[98:101], v[62:65], v[90:93], v[98:101]
	s_waitcnt lgkmcnt(0)
	v_mfma_f32_16x16x32_f16 v[52:55], v[62:65], v[110:113], v[52:55]
	global_load_dwordx4 v[62:65], v[0:1], off offset:1152
	v_mfma_f32_16x16x32_f16 v[102:105], v[74:77], v[90:93], v[102:105]
	v_mfma_f32_16x16x32_f16 v[24:27], v[74:77], v[110:113], v[24:27]
	v_mfma_f32_16x16x32_f16 v[114:117], v[118:121], v[90:93], v[114:117]
	v_mfma_f32_16x16x32_f16 v[40:43], v[118:121], v[110:113], v[40:43]
	v_mfma_f32_16x16x32_f16 v[70:73], v[122:125], v[90:93], v[70:73]
	global_load_dwordx4 v[90:93], v[2:3], off offset:1152
	global_load_dwordx4 v[130:133], v[4:5], off offset:1152
	global_load_dwordx4 v[138:141], v[14:15], off offset:1152
	global_load_dwordx4 v[74:77], v[10:11], off offset:1152
	global_load_dwordx4 v[142:145], v[12:13], off offset:1152
	global_load_dwordx4 v[154:157], v[8:9], off offset:1152
	global_load_dwordx4 v[158:161], v[6:7], off offset:1152
	s_waitcnt lgkmcnt(0)
	s_barrier
	v_mfma_f32_16x16x32_f16 v[48:51], v[122:125], v[110:113], v[48:51]
	ds_read_b128 v[58:61], v16 offset:32768
	ds_read_b128 v[106:109], v21
	s_waitcnt lgkmcnt(0)
	v_mfma_f32_16x16x32_f16 v[36:39], v[58:61], v[106:109], v[36:39]
	ds_read_b128 v[94:97], v16 offset:34816
	ds_read_b128 v[110:113], v21 offset:2048
	s_waitcnt lgkmcnt(0)
	v_mfma_f32_16x16x32_f16 v[66:69], v[58:61], v[110:113], v[66:69]
	ds_read_b128 v[118:121], v16 offset:36864
	v_mfma_f32_16x16x32_f16 v[44:47], v[94:97], v[106:109], v[44:47]
	ds_read_b128 v[122:125], v16 offset:38912
	v_mfma_f32_16x16x32_f16 v[78:81], v[94:97], v[110:113], v[78:81]
	s_waitcnt lgkmcnt(1)
	v_mfma_f32_16x16x32_f16 v[82:85], v[118:121], v[106:109], v[82:85]
	v_mfma_f32_16x16x32_f16 v[86:89], v[118:121], v[110:113], v[86:89]
	s_waitcnt lgkmcnt(0)
	v_mfma_f32_16x16x32_f16 v[28:31], v[122:125], v[106:109], v[28:31]
	ds_read_b128 v[106:109], v21 offset:4096
	v_mfma_f32_16x16x32_f16 v[32:35], v[122:125], v[110:113], v[32:35]
	ds_read_b128 v[110:113], v21 offset:6144
	s_waitcnt lgkmcnt(1)
	v_mfma_f32_16x16x32_f16 v[98:101], v[58:61], v[106:109], v[98:101]
	s_waitcnt lgkmcnt(0)
	v_mfma_f32_16x16x32_f16 v[52:55], v[58:61], v[110:113], v[52:55]
	ds_read_b128 v[58:61], v22 offset:32768
	v_mfma_f32_16x16x32_f16 v[102:105], v[94:97], v[106:109], v[102:105]
	v_mfma_f32_16x16x32_f16 v[24:27], v[94:97], v[110:113], v[24:27]
	ds_read_b128 v[94:97], v22 offset:34816
	v_mfma_f32_16x16x32_f16 v[114:117], v[118:121], v[106:109], v[114:117]
	s_waitcnt vmcnt(7)
	ds_write_b128 v17, v[62:65] offset:16384
	s_waitcnt vmcnt(6)
; #define GL_LOAD(s_, kt_) if (VAR != 1) { a##s_##0 = GL_A(0, kt_); a##s_##1 = GL_A(1, kt_); a##s_##2 = GL_A(2, kt_); a##s_##3 = GL_A(3, kt_); b##s_##0 = GL_B(0, kt_); b##s_##1 = GL_B(1, kt_); b##s_##2 = GL_B(2, kt_); b##s_##3 = GL_B(3, kt_); }
; #define LDS_STORE(s_, buf_) if (VAR != 2) { LDS_ST1(sA, 0, buf_, a##s_##0) LDS_ST1(sA, 1, buf_, a##s_##1) LDS_ST1(sA, 2, buf_, a##s_##2) LDS_ST1(sA, 3, buf_, a##s_##3) LDS_ST1(sB, 0, buf_, b##s_##0) LDS_ST1(sB, 1, buf_, b##s_##1) LDS_ST1(sB, 2, buf_, b##s_##2) LDS_ST1(sB, 3, buf_, b##s_##3) }
;     ...
;   GL_LOAD(0, 0)
;   GL_LOAD(1, 1)
;   LDS_STORE(0, 0)
;   if (VAR != 4) __syncthreads();
; #pragma unroll
;   for (int kt = 0; kt < nk; kt += 2) {
;     if (kt + 2 < nk) { GL_LOAD(0, kt + 2) }
;     MMA_TILE(0)
;     LDS_STORE(1, 1)
;     if (VAR != 4) __syncthreads();
;     if (kt + 3 < nk) { GL_LOAD(1, kt + 3) }
;     MMA_TILE(1)
;     if (kt + 2 < nk) { LDS_STORE(0, 0) }
;     if (VAR != 4) __syncthreads();
;   }
	ds_write_b128 v18, v[90:93] offset:16384
	v_mfma_f32_16x16x32_f16 v[40:43], v[118:121], v[110:113], v[40:43]
	ds_read_b128 v[118:121], v22 offset:36864
	s_waitcnt vmcnt(5)
	ds_write_b128 v19, v[130:133] offset:16384
	v_mfma_f32_16x16x32_f16 v[70:73], v[122:125], v[106:109], v[70:73]
	ds_read_b128 v[106:109], v23
	v_mfma_f32_16x16x32_f16 v[48:51], v[122:125], v[110:113], v[48:51]
	ds_read_b128 v[110:113], v23 offset:2048
	s_waitcnt lgkmcnt(1)
	v_mfma_f32_16x16x32_f16 v[36:39], v[58:61], v[106:109], v[36:39]
	ds_read_b128 v[122:125], v22 offset:38912
	s_waitcnt lgkmcnt(1)
	v_mfma_f32_16x16x32_f16 v[66:69], v[58:61], v[110:113], v[66:69]
	s_waitcnt vmcnt(4)
	ds_write_b128 v20, v[138:141] offset:16384
	v_mfma_f32_16x16x32_f16 v[44:47], v[94:97], v[106:109], v[44:47]
	s_waitcnt vmcnt(3)
	ds_write_b128 v17, v[74:77] offset:49152
	v_mfma_f32_16x16x32_f16 v[78:81], v[94:97], v[110:113], v[78:81]
	s_waitcnt vmcnt(2)
	ds_write_b128 v18, v[142:145] offset:49152
	v_mfma_f32_16x16x32_f16 v[82:85], v[118:121], v[106:109], v[82:85]
	s_waitcnt vmcnt(1)
	ds_write_b128 v19, v[154:157] offset:49152
	v_mfma_f32_16x16x32_f16 v[86:89], v[118:121], v[110:113], v[86:89]
	s_waitcnt vmcnt(0)
	ds_write_b128 v20, v[158:161] offset:49152
	s_waitcnt lgkmcnt(5)
	v_mfma_f32_16x16x32_f16 v[28:31], v[122:125], v[106:109], v[28:31]
	ds_read_b128 v[106:109], v23 offset:4096
	v_mfma_f32_16x16x32_f16 v[32:35], v[122:125], v[110:113], v[32:35]
	ds_read_b128 v[110:113], v23 offset:6144
	s_waitcnt lgkmcnt(1)
	v_mfma_f32_16x16x32_f16 v[98:101], v[58:61], v[106:109], v[98:101]
	s_waitcnt lgkmcnt(0)
	v_mfma_f32_16x16x32_f16 v[52:55], v[58:61], v[110:113], v[52:55]
	global_load_dwordx4 v[58:61], v[0:1], off offset:1280
	v_mfma_f32_16x16x32_f16 v[102:105], v[94:97], v[106:109], v[102:105]
	v_mfma_f32_16x16x32_f16 v[24:27], v[94:97], v[110:113], v[24:27]
	v_mfma_f32_16x16x32_f16 v[114:117], v[118:121], v[106:109], v[114:117]
	v_mfma_f32_16x16x32_f16 v[40:43], v[118:121], v[110:113], v[40:43]
	v_mfma_f32_16x16x32_f16 v[70:73], v[122:125], v[106:109], v[70:73]
	global_load_dwordx4 v[106:109], v[2:3], off offset:1280
	global_load_dwordx4 v[126:129], v[4:5], off offset:1280
	global_load_dwordx4 v[134:137], v[14:15], off offset:1280
	global_load_dwordx4 v[94:97], v[10:11], off offset:1280
	global_load_dwordx4 v[162:165], v[12:13], off offset:1280
	global_load_dwordx4 v[166:169], v[8:9], off offset:1280
	global_load_dwordx4 v[190:193], v[6:7], off offset:1280
	s_waitcnt lgkmcnt(0)
	s_barrier
	v_mfma_f32_16x16x32_f16 v[48:51], v[122:125], v[110:113], v[48:51]
	ds_read_b128 v[62:65], v16 offset:49152
	ds_read_b128 v[90:93], v21 offset:16384
	s_waitcnt lgkmcnt(0)
	v_mfma_f32_16x16x32_f16 v[36:39], v[62:65], v[90:93], v[36:39]
	ds_read_b128 v[74:77], v16 offset:51200
	ds_read_b128 v[110:113], v21 offset:18432
	s_waitcnt lgkmcnt(0)
	v_mfma_f32_16x16x32_f16 v[66:69], v[62:65], v[110:113], v[66:69]
	ds_read_b128 v[118:121], v16 offset:53248
	v_mfma_f32_16x16x32_f16 v[44:47], v[74:77], v[90:93], v[44:47]
	ds_read_b128 v[122:125], v16 offset:55296
	v_mfma_f32_16x16x32_f16 v[78:81], v[74:77], v[110:113], v[78:81]
	s_waitcnt lgkmcnt(1)
	v_mfma_f32_16x16x32_f16 v[82:85], v[118:121], v[90:93], v[82:85]
	v_mfma_f32_16x16x32_f16 v[86:89], v[118:121], v[110:113], v[86:89]
	s_waitcnt lgkmcnt(0)
	v_mfma_f32_16x16x32_f16 v[28:31], v[122:125], v[90:93], v[28:31]
	ds_read_b128 v[90:93], v21 offset:20480
	v_mfma_f32_16x16x32_f16 v[32:35], v[122:125], v[110:113], v[32:35]
	ds_read_b128 v[110:113], v21 offset:22528
	s_waitcnt lgkmcnt(1)
	v_mfma_f32_16x16x32_f16 v[98:101], v[62:65], v[90:93], v[98:101]
	s_waitcnt lgkmcnt(0)
	v_mfma_f32_16x16x32_f16 v[52:55], v[62:65], v[110:113], v[52:55]
	ds_read_b128 v[62:65], v22 offset:49152
	v_mfma_f32_16x16x32_f16 v[102:105], v[74:77], v[90:93], v[102:105]
	v_mfma_f32_16x16x32_f16 v[24:27], v[74:77], v[110:113], v[24:27]
	ds_read_b128 v[74:77], v22 offset:51200
	v_mfma_f32_16x16x32_f16 v[114:117], v[118:121], v[90:93], v[114:117]
	s_waitcnt vmcnt(7)
	ds_write_b128 v17, v[58:61]
	s_waitcnt vmcnt(6)
	ds_write_b128 v18, v[106:109]
	v_mfma_f32_16x16x32_f16 v[40:43], v[118:121], v[110:113], v[40:43]
	ds_read_b128 v[118:121], v22 offset:53248
	s_waitcnt vmcnt(5)
	ds_write_b128 v19, v[126:129]
	v_mfma_f32_16x16x32_f16 v[70:73], v[122:125], v[90:93], v[70:73]
	ds_read_b128 v[90:93], v23 offset:16384
	v_mfma_f32_16x16x32_f16 v[48:51], v[122:125], v[110:113], v[48:51]
	ds_read_b128 v[110:113], v23 offset:18432
	s_waitcnt lgkmcnt(1)
	v_mfma_f32_16x16x32_f16 v[36:39], v[62:65], v[90:93], v[36:39]
	ds_read_b128 v[122:125], v22 offset:55296
	s_waitcnt lgkmcnt(1)
	v_mfma_f32_16x16x32_f16 v[66:69], v[62:65], v[110:113], v[66:69]
	s_waitcnt vmcnt(4)
	ds_write_b128 v20, v[134:137]
	v_mfma_f32_16x16x32_f16 v[44:47], v[74:77], v[90:93], v[44:47]
	s_waitcnt vmcnt(3)
	ds_write_b128 v17, v[94:97] offset:32768
	v_mfma_f32_16x16x32_f16 v[78:81], v[74:77], v[110:113], v[78:81]
	s_waitcnt vmcnt(2)
	ds_write_b128 v18, v[162:165] offset:32768
	v_mfma_f32_16x16x32_f16 v[82:85], v[118:121], v[90:93], v[82:85]
	s_waitcnt vmcnt(1)
	ds_write_b128 v19, v[166:169] offset:32768
	v_mfma_f32_16x16x32_f16 v[86:89], v[118:121], v[110:113], v[86:89]
	s_waitcnt vmcnt(0)
	ds_write_b128 v20, v[190:193] offset:32768
	s_waitcnt lgkmcnt(5)
	v_mfma_f32_16x16x32_f16 v[28:31], v[122:125], v[90:93], v[28:31]
	ds_read_b128 v[90:93], v23 offset:20480
	v_mfma_f32_16x16x32_f16 v[32:35], v[122:125], v[110:113], v[32:35]
	ds_read_b128 v[110:113], v23 offset:22528
	s_waitcnt lgkmcnt(1)
	v_mfma_f32_16x16x32_f16 v[98:101], v[62:65], v[90:93], v[98:101]
	s_waitcnt lgkmcnt(0)
	v_mfma_f32_16x16x32_f16 v[52:55], v[62:65], v[110:113], v[52:55]
	global_load_dwordx4 v[62:65], v[0:1], off offset:1408
	v_mfma_f32_16x16x32_f16 v[102:105], v[74:77], v[90:93], v[102:105]
	v_mfma_f32_16x16x32_f16 v[24:27], v[74:77], v[110:113], v[24:27]
	v_mfma_f32_16x16x32_f16 v[114:117], v[118:121], v[90:93], v[114:117]
	v_mfma_f32_16x16x32_f16 v[40:43], v[118:121], v[110:113], v[40:43]
	v_mfma_f32_16x16x32_f16 v[70:73], v[122:125], v[90:93], v[70:73]
	global_load_dwordx4 v[90:93], v[2:3], off offset:1408
	global_load_dwordx4 v[130:133], v[4:5], off offset:1408
	global_load_dwordx4 v[138:141], v[14:15], off offset:1408
	global_load_dwordx4 v[74:77], v[10:11], off offset:1408
	global_load_dwordx4 v[142:145], v[12:13], off offset:1408
	global_load_dwordx4 v[154:157], v[8:9], off offset:1408
	global_load_dwordx4 v[158:161], v[6:7], off offset:1408
	s_waitcnt lgkmcnt(0)
	s_barrier
; #define GL_LOAD(s_, kt_) if (VAR != 1) { a##s_##0 = GL_A(0, kt_); a##s_##1 = GL_A(1, kt_); a##s_##2 = GL_A(2, kt_); a##s_##3 = GL_A(3, kt_); b##s_##0 = GL_B(0, kt_); b##s_##1 = GL_B(1, kt_); b##s_##2 = GL_B(2, kt_); b##s_##3 = GL_B(3, kt_); }
; #define LDS_STORE(s_, buf_) if (VAR != 2) { LDS_ST1(sA, 0, buf_, a##s_##0) LDS_ST1(sA, 1, buf_, a##s_##1) LDS_ST1(sA, 2, buf_, a##s_##2) LDS_ST1(sA, 3, buf_, a##s_##3) LDS_ST1(sB, 0, buf_, b##s_##0) LDS_ST1(sB, 1, buf_, b##s_##1) LDS_ST1(sB, 2, buf_, b##s_##2) LDS_ST1(sB, 3, buf_, b##s_##3) }
;     ...
;   GL_LOAD(0, 0)
;   GL_LOAD(1, 1)
;   LDS_STORE(0, 0)
;   if (VAR != 4) __syncthreads();
; #pragma unroll
;   for (int kt = 0; kt < nk; kt += 2) {
;     if (kt + 2 < nk) { GL_LOAD(0, kt + 2) }
;     MMA_TILE(0)
;     LDS_STORE(1, 1)
;     if (VAR != 4) __syncthreads();
;     if (kt + 3 < nk) { GL_LOAD(1, kt + 3) }
;     MMA_TILE(1)
;     if (kt + 2 < nk) { LDS_STORE(0, 0) }
;     if (VAR != 4) __syncthreads();
;   }
	v_mfma_f32_16x16x32_f16 v[48:51], v[122:125], v[110:113], v[48:51]
	ds_read_b128 v[58:61], v16 offset:32768
	ds_read_b128 v[106:109], v21
	s_waitcnt lgkmcnt(0)
	v_mfma_f32_16x16x32_f16 v[36:39], v[58:61], v[106:109], v[36:39]
	ds_read_b128 v[94:97], v16 offset:34816
	ds_read_b128 v[110:113], v21 offset:2048
	s_waitcnt lgkmcnt(0)
	v_mfma_f32_16x16x32_f16 v[66:69], v[58:61], v[110:113], v[66:69]
	ds_read_b128 v[118:121], v16 offset:36864
	v_mfma_f32_16x16x32_f16 v[44:47], v[94:97], v[106:109], v[44:47]
	ds_read_b128 v[122:125], v16 offset:38912
	v_mfma_f32_16x16x32_f16 v[78:81], v[94:97], v[110:113], v[78:81]
	s_waitcnt lgkmcnt(1)
	v_mfma_f32_16x16x32_f16 v[82:85], v[118:121], v[106:109], v[82:85]
	v_mfma_f32_16x16x32_f16 v[86:89], v[118:121], v[110:113], v[86:89]
	s_waitcnt lgkmcnt(0)
	v_mfma_f32_16x16x32_f16 v[28:31], v[122:125], v[106:109], v[28:31]
	ds_read_b128 v[106:109], v21 offset:4096
	v_mfma_f32_16x16x32_f16 v[32:35], v[122:125], v[110:113], v[32:35]
	ds_read_b128 v[110:113], v21 offset:6144
	s_waitcnt lgkmcnt(1)
	v_mfma_f32_16x16x32_f16 v[98:101], v[58:61], v[106:109], v[98:101]
	s_waitcnt lgkmcnt(0)
	v_mfma_f32_16x16x32_f16 v[52:55], v[58:61], v[110:113], v[52:55]
	ds_read_b128 v[58:61], v22 offset:32768
	v_mfma_f32_16x16x32_f16 v[102:105], v[94:97], v[106:109], v[102:105]
	v_mfma_f32_16x16x32_f16 v[24:27], v[94:97], v[110:113], v[24:27]
	ds_read_b128 v[94:97], v22 offset:34816
	v_mfma_f32_16x16x32_f16 v[114:117], v[118:121], v[106:109], v[114:117]
	s_waitcnt vmcnt(7)
	ds_write_b128 v17, v[62:65] offset:16384
	s_waitcnt vmcnt(6)
	ds_write_b128 v18, v[90:93] offset:16384
	v_mfma_f32_16x16x32_f16 v[40:43], v[118:121], v[110:113], v[40:43]
	ds_read_b128 v[118:121], v22 offset:36864
	s_waitcnt vmcnt(5)
	ds_write_b128 v19, v[130:133] offset:16384
	v_mfma_f32_16x16x32_f16 v[70:73], v[122:125], v[106:109], v[70:73]
	ds_read_b128 v[106:109], v23
	v_mfma_f32_16x16x32_f16 v[48:51], v[122:125], v[110:113], v[48:51]
	ds_read_b128 v[110:113], v23 offset:2048
	s_waitcnt lgkmcnt(1)
	v_mfma_f32_16x16x32_f16 v[36:39], v[58:61], v[106:109], v[36:39]
	ds_read_b128 v[122:125], v22 offset:38912
	s_waitcnt lgkmcnt(1)
	v_mfma_f32_16x16x32_f16 v[66:69], v[58:61], v[110:113], v[66:69]
	s_waitcnt vmcnt(4)
	ds_write_b128 v20, v[138:141] offset:16384
	v_mfma_f32_16x16x32_f16 v[44:47], v[94:97], v[106:109], v[44:47]
	s_waitcnt vmcnt(3)
	ds_write_b128 v17, v[74:77] offset:49152
	v_mfma_f32_16x16x32_f16 v[78:81], v[94:97], v[110:113], v[78:81]
	s_waitcnt vmcnt(2)
	ds_write_b128 v18, v[142:145] offset:49152
	v_mfma_f32_16x16x32_f16 v[82:85], v[118:121], v[106:109], v[82:85]
	s_waitcnt vmcnt(1)
	ds_write_b128 v19, v[154:157] offset:49152
	v_mfma_f32_16x16x32_f16 v[86:89], v[118:121], v[110:113], v[86:89]
	s_waitcnt vmcnt(0)
	ds_write_b128 v20, v[158:161] offset:49152
	s_waitcnt lgkmcnt(5)
	v_mfma_f32_16x16x32_f16 v[28:31], v[122:125], v[106:109], v[28:31]
	ds_read_b128 v[106:109], v23 offset:4096
	v_mfma_f32_16x16x32_f16 v[32:35], v[122:125], v[110:113], v[32:35]
	ds_read_b128 v[110:113], v23 offset:6144
	s_waitcnt lgkmcnt(1)
	v_mfma_f32_16x16x32_f16 v[98:101], v[58:61], v[106:109], v[98:101]
	s_waitcnt lgkmcnt(0)
	v_mfma_f32_16x16x32_f16 v[52:55], v[58:61], v[110:113], v[52:55]
	global_load_dwordx4 v[58:61], v[0:1], off offset:1536
	v_mfma_f32_16x16x32_f16 v[102:105], v[94:97], v[106:109], v[102:105]
	v_mfma_f32_16x16x32_f16 v[24:27], v[94:97], v[110:113], v[24:27]
	v_mfma_f32_16x16x32_f16 v[114:117], v[118:121], v[106:109], v[114:117]
	v_mfma_f32_16x16x32_f16 v[40:43], v[118:121], v[110:113], v[40:43]
	v_mfma_f32_16x16x32_f16 v[70:73], v[122:125], v[106:109], v[70:73]
	global_load_dwordx4 v[106:109], v[2:3], off offset:1536
	global_load_dwordx4 v[126:129], v[4:5], off offset:1536
	global_load_dwordx4 v[134:137], v[14:15], off offset:1536
	global_load_dwordx4 v[94:97], v[10:11], off offset:1536
	global_load_dwordx4 v[162:165], v[12:13], off offset:1536
	global_load_dwordx4 v[166:169], v[8:9], off offset:1536
	global_load_dwordx4 v[190:193], v[6:7], off offset:1536
	s_waitcnt lgkmcnt(0)
	s_barrier
	v_mfma_f32_16x16x32_f16 v[48:51], v[122:125], v[110:113], v[48:51]
	ds_read_b128 v[62:65], v16 offset:49152
	ds_read_b128 v[90:93], v21 offset:16384
	s_waitcnt lgkmcnt(0)
	v_mfma_f32_16x16x32_f16 v[36:39], v[62:65], v[90:93], v[36:39]
	ds_read_b128 v[74:77], v16 offset:51200
	ds_read_b128 v[110:113], v21 offset:18432
	s_waitcnt lgkmcnt(0)
	v_mfma_f32_16x16x32_f16 v[66:69], v[62:65], v[110:113], v[66:69]
	ds_read_b128 v[118:121], v16 offset:53248
	v_mfma_f32_16x16x32_f16 v[44:47], v[74:77], v[90:93], v[44:47]
	ds_read_b128 v[122:125], v16 offset:55296
	v_mfma_f32_16x16x32_f16 v[78:81], v[74:77], v[110:113], v[78:81]
	s_waitcnt lgkmcnt(1)
	v_mfma_f32_16x16x32_f16 v[82:85], v[118:121], v[90:93], v[82:85]
	v_mfma_f32_16x16x32_f16 v[86:89], v[118:121], v[110:113], v[86:89]
	s_waitcnt lgkmcnt(0)
	v_mfma_f32_16x16x32_f16 v[28:31], v[122:125], v[90:93], v[28:31]
	ds_read_b128 v[90:93], v21 offset:20480
	v_mfma_f32_16x16x32_f16 v[32:35], v[122:125], v[110:113], v[32:35]
	ds_read_b128 v[110:113], v21 offset:22528
	s_waitcnt lgkmcnt(1)
	v_mfma_f32_16x16x32_f16 v[98:101], v[62:65], v[90:93], v[98:101]
	s_waitcnt lgkmcnt(0)
	v_mfma_f32_16x16x32_f16 v[52:55], v[62:65], v[110:113], v[52:55]
	ds_read_b128 v[62:65], v22 offset:49152
	v_mfma_f32_16x16x32_f16 v[102:105], v[74:77], v[90:93], v[102:105]
	v_mfma_f32_16x16x32_f16 v[24:27], v[74:77], v[110:113], v[24:27]
	ds_read_b128 v[74:77], v22 offset:51200
	v_mfma_f32_16x16x32_f16 v[114:117], v[118:121], v[90:93], v[114:117]
	s_waitcnt vmcnt(7)
	ds_write_b128 v17, v[58:61]
	s_waitcnt vmcnt(6)
; #define GL_LOAD(s_, kt_) if (VAR != 1) { a##s_##0 = GL_A(0, kt_); a##s_##1 = GL_A(1, kt_); a##s_##2 = GL_A(2, kt_); a##s_##3 = GL_A(3, kt_); b##s_##0 = GL_B(0, kt_); b##s_##1 = GL_B(1, kt_); b##s_##2 = GL_B(2, kt_); b##s_##3 = GL_B(3, kt_); }
; #define LDS_STORE(s_, buf_) if (VAR != 2) { LDS_ST1(sA, 0, buf_, a##s_##0) LDS_ST1(sA, 1, buf_, a##s_##1) LDS_ST1(sA, 2, buf_, a##s_##2) LDS_ST1(sA, 3, buf_, a##s_##3) LDS_ST1(sB, 0, buf_, b##s_##0) LDS_ST1(sB, 1, buf_, b##s_##1) LDS_ST1(sB, 2, buf_, b##s_##2) LDS_ST1(sB, 3, buf_, b##s_##3) }
;     ...
;   GL_LOAD(0, 0)
;   GL_LOAD(1, 1)
;   LDS_STORE(0, 0)
;   if (VAR != 4) __syncthreads();
; #pragma unroll
;   for (int kt = 0; kt < nk; kt += 2) {
;     if (kt + 2 < nk) { GL_LOAD(0, kt + 2) }
;     MMA_TILE(0)
;     LDS_STORE(1, 1)
;     if (VAR != 4) __syncthreads();
;     if (kt + 3 < nk) { GL_LOAD(1, kt + 3) }
;     MMA_TILE(1)
;     if (kt + 2 < nk) { LDS_STORE(0, 0) }
;     if (VAR != 4) __syncthreads();
;   }
	ds_write_b128 v18, v[106:109]
	v_mfma_f32_16x16x32_f16 v[40:43], v[118:121], v[110:113], v[40:43]
	ds_read_b128 v[118:121], v22 offset:53248
	s_waitcnt vmcnt(5)
	ds_write_b128 v19, v[126:129]
	v_mfma_f32_16x16x32_f16 v[70:73], v[122:125], v[90:93], v[70:73]
	ds_read_b128 v[90:93], v23 offset:16384
	v_mfma_f32_16x16x32_f16 v[48:51], v[122:125], v[110:113], v[48:51]
	ds_read_b128 v[110:113], v23 offset:18432
	s_waitcnt lgkmcnt(1)
	v_mfma_f32_16x16x32_f16 v[36:39], v[62:65], v[90:93], v[36:39]
	ds_read_b128 v[122:125], v22 offset:55296
	s_waitcnt lgkmcnt(1)
	v_mfma_f32_16x16x32_f16 v[66:69], v[62:65], v[110:113], v[66:69]
	s_waitcnt vmcnt(4)
	ds_write_b128 v20, v[134:137]
	v_mfma_f32_16x16x32_f16 v[44:47], v[74:77], v[90:93], v[44:47]
	s_waitcnt vmcnt(3)
	ds_write_b128 v17, v[94:97] offset:32768
	v_mfma_f32_16x16x32_f16 v[78:81], v[74:77], v[110:113], v[78:81]
	s_waitcnt vmcnt(2)
	ds_write_b128 v18, v[162:165] offset:32768
	v_mfma_f32_16x16x32_f16 v[82:85], v[118:121], v[90:93], v[82:85]
	s_waitcnt vmcnt(1)
	ds_write_b128 v19, v[166:169] offset:32768
	v_mfma_f32_16x16x32_f16 v[86:89], v[118:121], v[110:113], v[86:89]
	s_waitcnt vmcnt(0)
	ds_write_b128 v20, v[190:193] offset:32768
	s_waitcnt lgkmcnt(5)
	v_mfma_f32_16x16x32_f16 v[28:31], v[122:125], v[90:93], v[28:31]
	ds_read_b128 v[90:93], v23 offset:20480
	v_mfma_f32_16x16x32_f16 v[32:35], v[122:125], v[110:113], v[32:35]
	ds_read_b128 v[110:113], v23 offset:22528
	s_waitcnt lgkmcnt(1)
	v_mfma_f32_16x16x32_f16 v[98:101], v[62:65], v[90:93], v[98:101]
	s_waitcnt lgkmcnt(0)
	v_mfma_f32_16x16x32_f16 v[52:55], v[62:65], v[110:113], v[52:55]
	global_load_dwordx4 v[62:65], v[0:1], off offset:1664
	v_mfma_f32_16x16x32_f16 v[102:105], v[74:77], v[90:93], v[102:105]
	v_mfma_f32_16x16x32_f16 v[24:27], v[74:77], v[110:113], v[24:27]
	v_mfma_f32_16x16x32_f16 v[114:117], v[118:121], v[90:93], v[114:117]
	v_mfma_f32_16x16x32_f16 v[40:43], v[118:121], v[110:113], v[40:43]
	v_mfma_f32_16x16x32_f16 v[70:73], v[122:125], v[90:93], v[70:73]
	global_load_dwordx4 v[90:93], v[2:3], off offset:1664
	global_load_dwordx4 v[130:133], v[4:5], off offset:1664
	global_load_dwordx4 v[138:141], v[14:15], off offset:1664
	global_load_dwordx4 v[74:77], v[10:11], off offset:1664
	global_load_dwordx4 v[142:145], v[12:13], off offset:1664
	global_load_dwordx4 v[154:157], v[8:9], off offset:1664
	global_load_dwordx4 v[158:161], v[6:7], off offset:1664
	s_waitcnt lgkmcnt(0)
	s_barrier
	v_mfma_f32_16x16x32_f16 v[48:51], v[122:125], v[110:113], v[48:51]
	ds_read_b128 v[58:61], v16 offset:32768
	ds_read_b128 v[106:109], v21
	s_waitcnt lgkmcnt(0)
	v_mfma_f32_16x16x32_f16 v[36:39], v[58:61], v[106:109], v[36:39]
	ds_read_b128 v[94:97], v16 offset:34816
	ds_read_b128 v[110:113], v21 offset:2048
	s_waitcnt lgkmcnt(0)
	v_mfma_f32_16x16x32_f16 v[66:69], v[58:61], v[110:113], v[66:69]
	ds_read_b128 v[118:121], v16 offset:36864
	v_mfma_f32_16x16x32_f16 v[44:47], v[94:97], v[106:109], v[44:47]
	ds_read_b128 v[122:125], v16 offset:38912
	v_mfma_f32_16x16x32_f16 v[78:81], v[94:97], v[110:113], v[78:81]
	s_waitcnt lgkmcnt(1)
	v_mfma_f32_16x16x32_f16 v[82:85], v[118:121], v[106:109], v[82:85]
	v_mfma_f32_16x16x32_f16 v[86:89], v[118:121], v[110:113], v[86:89]
	s_waitcnt lgkmcnt(0)
	v_mfma_f32_16x16x32_f16 v[28:31], v[122:125], v[106:109], v[28:31]
	ds_read_b128 v[106:109], v21 offset:4096
	v_mfma_f32_16x16x32_f16 v[32:35], v[122:125], v[110:113], v[32:35]
	ds_read_b128 v[110:113], v21 offset:6144
	s_waitcnt lgkmcnt(1)
	v_mfma_f32_16x16x32_f16 v[98:101], v[58:61], v[106:109], v[98:101]
	s_waitcnt lgkmcnt(0)
	v_mfma_f32_16x16x32_f16 v[52:55], v[58:61], v[110:113], v[52:55]
	ds_read_b128 v[58:61], v22 offset:32768
	v_mfma_f32_16x16x32_f16 v[102:105], v[94:97], v[106:109], v[102:105]
	v_mfma_f32_16x16x32_f16 v[24:27], v[94:97], v[110:113], v[24:27]
	ds_read_b128 v[94:97], v22 offset:34816
	v_mfma_f32_16x16x32_f16 v[114:117], v[118:121], v[106:109], v[114:117]
	s_waitcnt vmcnt(7)
	ds_write_b128 v17, v[62:65] offset:16384
	s_waitcnt vmcnt(6)
	ds_write_b128 v18, v[90:93] offset:16384
	v_mfma_f32_16x16x32_f16 v[40:43], v[118:121], v[110:113], v[40:43]
	ds_read_b128 v[118:121], v22 offset:36864
	s_waitcnt vmcnt(5)
	ds_write_b128 v19, v[130:133] offset:16384
	v_mfma_f32_16x16x32_f16 v[70:73], v[122:125], v[106:109], v[70:73]
	ds_read_b128 v[106:109], v23
	v_mfma_f32_16x16x32_f16 v[48:51], v[122:125], v[110:113], v[48:51]
	ds_read_b128 v[110:113], v23 offset:2048
	s_waitcnt lgkmcnt(1)
	v_mfma_f32_16x16x32_f16 v[36:39], v[58:61], v[106:109], v[36:39]
	ds_read_b128 v[122:125], v22 offset:38912
	s_waitcnt lgkmcnt(1)
	v_mfma_f32_16x16x32_f16 v[66:69], v[58:61], v[110:113], v[66:69]
	s_waitcnt vmcnt(4)
	ds_write_b128 v20, v[138:141] offset:16384
	v_mfma_f32_16x16x32_f16 v[44:47], v[94:97], v[106:109], v[44:47]
	s_waitcnt vmcnt(3)
	ds_write_b128 v17, v[74:77] offset:49152
	v_mfma_f32_16x16x32_f16 v[78:81], v[94:97], v[110:113], v[78:81]
	s_waitcnt vmcnt(2)
	ds_write_b128 v18, v[142:145] offset:49152
	v_mfma_f32_16x16x32_f16 v[82:85], v[118:121], v[106:109], v[82:85]
	s_waitcnt vmcnt(1)
	ds_write_b128 v19, v[154:157] offset:49152
	v_mfma_f32_16x16x32_f16 v[86:89], v[118:121], v[110:113], v[86:89]
	s_waitcnt vmcnt(0)
	ds_write_b128 v20, v[158:161] offset:49152
	s_waitcnt lgkmcnt(5)
	v_mfma_f32_16x16x32_f16 v[28:31], v[122:125], v[106:109], v[28:31]
	ds_read_b128 v[106:109], v23 offset:4096
	v_mfma_f32_16x16x32_f16 v[32:35], v[122:125], v[110:113], v[32:35]
	ds_read_b128 v[110:113], v23 offset:6144
	s_waitcnt lgkmcnt(1)
	v_mfma_f32_16x16x32_f16 v[98:101], v[58:61], v[106:109], v[98:101]
	s_waitcnt lgkmcnt(0)
	v_mfma_f32_16x16x32_f16 v[52:55], v[58:61], v[110:113], v[52:55]
	global_load_dwordx4 v[58:61], v[0:1], off offset:1792
	v_mfma_f32_16x16x32_f16 v[102:105], v[94:97], v[106:109], v[102:105]
	v_mfma_f32_16x16x32_f16 v[24:27], v[94:97], v[110:113], v[24:27]
	v_mfma_f32_16x16x32_f16 v[114:117], v[118:121], v[106:109], v[114:117]
	v_mfma_f32_16x16x32_f16 v[40:43], v[118:121], v[110:113], v[40:43]
	v_mfma_f32_16x16x32_f16 v[70:73], v[122:125], v[106:109], v[70:73]
	global_load_dwordx4 v[106:109], v[2:3], off offset:1792
	global_load_dwordx4 v[126:129], v[4:5], off offset:1792
	global_load_dwordx4 v[134:137], v[14:15], off offset:1792
	global_load_dwordx4 v[94:97], v[10:11], off offset:1792
	global_load_dwordx4 v[162:165], v[12:13], off offset:1792
	global_load_dwordx4 v[166:169], v[8:9], off offset:1792
	global_load_dwordx4 v[190:193], v[6:7], off offset:1792
	s_waitcnt lgkmcnt(0)
	s_barrier
; #define GL_LOAD(s_, kt_) if (VAR != 1) { a##s_##0 = GL_A(0, kt_); a##s_##1 = GL_A(1, kt_); a##s_##2 = GL_A(2, kt_); a##s_##3 = GL_A(3, kt_); b##s_##0 = GL_B(0, kt_); b##s_##1 = GL_B(1, kt_); b##s_##2 = GL_B(2, kt_); b##s_##3 = GL_B(3, kt_); }
; #define LDS_STORE(s_, buf_) if (VAR != 2) { LDS_ST1(sA, 0, buf_, a##s_##0) LDS_ST1(sA, 1, buf_, a##s_##1) LDS_ST1(sA, 2, buf_, a##s_##2) LDS_ST1(sA, 3, buf_, a##s_##3) LDS_ST1(sB, 0, buf_, b##s_##0) LDS_ST1(sB, 1, buf_, b##s_##1) LDS_ST1(sB, 2, buf_, b##s_##2) LDS_ST1(sB, 3, buf_, b##s_##3) }
;     ...
;   GL_LOAD(0, 0)
;   GL_LOAD(1, 1)
;   LDS_STORE(0, 0)
;   if (VAR != 4) __syncthreads();
; #pragma unroll
;   for (int kt = 0; kt < nk; kt += 2) {
;     if (kt + 2 < nk) { GL_LOAD(0, kt + 2) }
;     MMA_TILE(0)
;     LDS_STORE(1, 1)
;     if (VAR != 4) __syncthreads();
;     if (kt + 3 < nk) { GL_LOAD(1, kt + 3) }
;     MMA_TILE(1)
;     if (kt + 2 < nk) { LDS_STORE(0, 0) }
;     if (VAR != 4) __syncthreads();
;   }
	v_mfma_f32_16x16x32_f16 v[48:51], v[122:125], v[110:113], v[48:51]
	ds_read_b128 v[62:65], v16 offset:49152
	ds_read_b128 v[90:93], v21 offset:16384
	s_waitcnt lgkmcnt(0)
	v_mfma_f32_16x16x32_f16 v[36:39], v[62:65], v[90:93], v[36:39]
	ds_read_b128 v[74:77], v16 offset:51200
	ds_read_b128 v[110:113], v21 offset:18432
	s_waitcnt lgkmcnt(0)
	v_mfma_f32_16x16x32_f16 v[66:69], v[62:65], v[110:113], v[66:69]
	ds_read_b128 v[118:121], v16 offset:53248
	v_mfma_f32_16x16x32_f16 v[44:47], v[74:77], v[90:93], v[44:47]
	ds_read_b128 v[122:125], v16 offset:55296
	v_mfma_f32_16x16x32_f16 v[78:81], v[74:77], v[110:113], v[78:81]
	s_waitcnt lgkmcnt(1)
	v_mfma_f32_16x16x32_f16 v[82:85], v[118:121], v[90:93], v[82:85]
	v_mfma_f32_16x16x32_f16 v[86:89], v[118:121], v[110:113], v[86:89]
	s_waitcnt lgkmcnt(0)
	v_mfma_f32_16x16x32_f16 v[28:31], v[122:125], v[90:93], v[28:31]
	ds_read_b128 v[90:93], v21 offset:20480
	v_mfma_f32_16x16x32_f16 v[32:35], v[122:125], v[110:113], v[32:35]
	ds_read_b128 v[110:113], v21 offset:22528
	s_waitcnt lgkmcnt(1)
	v_mfma_f32_16x16x32_f16 v[98:101], v[62:65], v[90:93], v[98:101]
	s_waitcnt lgkmcnt(0)
	v_mfma_f32_16x16x32_f16 v[52:55], v[62:65], v[110:113], v[52:55]
	ds_read_b128 v[62:65], v22 offset:49152
	v_mfma_f32_16x16x32_f16 v[102:105], v[74:77], v[90:93], v[102:105]
	v_mfma_f32_16x16x32_f16 v[24:27], v[74:77], v[110:113], v[24:27]
	ds_read_b128 v[74:77], v22 offset:51200
	v_mfma_f32_16x16x32_f16 v[114:117], v[118:121], v[90:93], v[114:117]
	s_waitcnt vmcnt(7)
	ds_write_b128 v17, v[58:61]
	s_waitcnt vmcnt(6)
	ds_write_b128 v18, v[106:109]
	v_mfma_f32_16x16x32_f16 v[40:43], v[118:121], v[110:113], v[40:43]
	ds_read_b128 v[118:121], v22 offset:53248
	s_waitcnt vmcnt(5)
	ds_write_b128 v19, v[126:129]
	v_mfma_f32_16x16x32_f16 v[70:73], v[122:125], v[90:93], v[70:73]
	ds_read_b128 v[90:93], v23 offset:16384
	v_mfma_f32_16x16x32_f16 v[48:51], v[122:125], v[110:113], v[48:51]
	ds_read_b128 v[110:113], v23 offset:18432
	s_waitcnt lgkmcnt(1)
	v_mfma_f32_16x16x32_f16 v[36:39], v[62:65], v[90:93], v[36:39]
	ds_read_b128 v[122:125], v22 offset:55296
	s_waitcnt lgkmcnt(1)
	v_mfma_f32_16x16x32_f16 v[66:69], v[62:65], v[110:113], v[66:69]
	s_waitcnt vmcnt(4)
	ds_write_b128 v20, v[134:137]
	v_mfma_f32_16x16x32_f16 v[44:47], v[74:77], v[90:93], v[44:47]
	s_waitcnt vmcnt(3)
	ds_write_b128 v17, v[94:97] offset:32768
	v_mfma_f32_16x16x32_f16 v[78:81], v[74:77], v[110:113], v[78:81]
	s_waitcnt vmcnt(2)
	ds_write_b128 v18, v[162:165] offset:32768
	v_mfma_f32_16x16x32_f16 v[82:85], v[118:121], v[90:93], v[82:85]
	s_waitcnt vmcnt(1)
	ds_write_b128 v19, v[166:169] offset:32768
	v_mfma_f32_16x16x32_f16 v[86:89], v[118:121], v[110:113], v[86:89]
	s_waitcnt vmcnt(0)
	ds_write_b128 v20, v[190:193] offset:32768
	s_waitcnt lgkmcnt(5)
	v_mfma_f32_16x16x32_f16 v[28:31], v[122:125], v[90:93], v[28:31]
	ds_read_b128 v[90:93], v23 offset:20480
	v_mfma_f32_16x16x32_f16 v[32:35], v[122:125], v[110:113], v[32:35]
	ds_read_b128 v[110:113], v23 offset:22528
	s_waitcnt lgkmcnt(1)
	v_mfma_f32_16x16x32_f16 v[98:101], v[62:65], v[90:93], v[98:101]
	s_waitcnt lgkmcnt(0)
	v_mfma_f32_16x16x32_f16 v[52:55], v[62:65], v[110:113], v[52:55]
	global_load_dwordx4 v[62:65], v[0:1], off offset:1920
	v_mfma_f32_16x16x32_f16 v[102:105], v[74:77], v[90:93], v[102:105]
	v_mfma_f32_16x16x32_f16 v[24:27], v[74:77], v[110:113], v[24:27]
	v_mfma_f32_16x16x32_f16 v[114:117], v[118:121], v[90:93], v[114:117]
	v_mfma_f32_16x16x32_f16 v[40:43], v[118:121], v[110:113], v[40:43]
	v_mfma_f32_16x16x32_f16 v[70:73], v[122:125], v[90:93], v[70:73]
	global_load_dwordx4 v[90:93], v[2:3], off offset:1920
	global_load_dwordx4 v[130:133], v[4:5], off offset:1920
	global_load_dwordx4 v[138:141], v[14:15], off offset:1920
	global_load_dwordx4 v[74:77], v[10:11], off offset:1920
	global_load_dwordx4 v[142:145], v[12:13], off offset:1920
	global_load_dwordx4 v[154:157], v[8:9], off offset:1920
	global_load_dwordx4 v[158:161], v[6:7], off offset:1920
	s_waitcnt lgkmcnt(0)
	s_barrier
	v_mfma_f32_16x16x32_f16 v[48:51], v[122:125], v[110:113], v[48:51]
	ds_read_b128 v[58:61], v16 offset:32768
	ds_read_b128 v[106:109], v21
	s_waitcnt lgkmcnt(0)
	v_mfma_f32_16x16x32_f16 v[36:39], v[58:61], v[106:109], v[36:39]
	ds_read_b128 v[94:97], v16 offset:34816
	ds_read_b128 v[110:113], v21 offset:2048
	s_waitcnt lgkmcnt(0)
	v_mfma_f32_16x16x32_f16 v[66:69], v[58:61], v[110:113], v[66:69]
	ds_read_b128 v[118:121], v16 offset:36864
	v_mfma_f32_16x16x32_f16 v[44:47], v[94:97], v[106:109], v[44:47]
	ds_read_b128 v[122:125], v16 offset:38912
	v_mfma_f32_16x16x32_f16 v[78:81], v[94:97], v[110:113], v[78:81]
	s_waitcnt lgkmcnt(1)
	v_mfma_f32_16x16x32_f16 v[82:85], v[118:121], v[106:109], v[82:85]
	v_mfma_f32_16x16x32_f16 v[86:89], v[118:121], v[110:113], v[86:89]
	s_waitcnt lgkmcnt(0)
	v_mfma_f32_16x16x32_f16 v[28:31], v[122:125], v[106:109], v[28:31]
	ds_read_b128 v[106:109], v21 offset:4096
	v_mfma_f32_16x16x32_f16 v[32:35], v[122:125], v[110:113], v[32:35]
	ds_read_b128 v[110:113], v21 offset:6144
	s_waitcnt lgkmcnt(1)
	v_mfma_f32_16x16x32_f16 v[98:101], v[58:61], v[106:109], v[98:101]
	s_waitcnt lgkmcnt(0)
	v_mfma_f32_16x16x32_f16 v[52:55], v[58:61], v[110:113], v[52:55]
	ds_read_b128 v[58:61], v22 offset:32768
	v_mfma_f32_16x16x32_f16 v[102:105], v[94:97], v[106:109], v[102:105]
	v_mfma_f32_16x16x32_f16 v[24:27], v[94:97], v[110:113], v[24:27]
	ds_read_b128 v[94:97], v22 offset:34816
	v_mfma_f32_16x16x32_f16 v[114:117], v[118:121], v[106:109], v[114:117]
	s_waitcnt vmcnt(7)
	ds_write_b128 v17, v[62:65] offset:16384
	s_waitcnt vmcnt(6)
; #define GL_LOAD(s_, kt_) if (VAR != 1) { a##s_##0 = GL_A(0, kt_); a##s_##1 = GL_A(1, kt_); a##s_##2 = GL_A(2, kt_); a##s_##3 = GL_A(3, kt_); b##s_##0 = GL_B(0, kt_); b##s_##1 = GL_B(1, kt_); b##s_##2 = GL_B(2, kt_); b##s_##3 = GL_B(3, kt_); }
; #define LDS_STORE(s_, buf_) if (VAR != 2) { LDS_ST1(sA, 0, buf_, a##s_##0) LDS_ST1(sA, 1, buf_, a##s_##1) LDS_ST1(sA, 2, buf_, a##s_##2) LDS_ST1(sA, 3, buf_, a##s_##3) LDS_ST1(sB, 0, buf_, b##s_##0) LDS_ST1(sB, 1, buf_, b##s_##1) LDS_ST1(sB, 2, buf_, b##s_##2) LDS_ST1(sB, 3, buf_, b##s_##3) }
;     ...
;   for (int kt = 0; kt < nk; kt += 2) {
;     if (kt + 2 < nk) { GL_LOAD(0, kt + 2) }
;     MMA_TILE(0)
;     LDS_STORE(1, 1)
;     if (VAR != 4) __syncthreads();
;     if (kt + 3 < nk) { GL_LOAD(1, kt + 3) }
;     MMA_TILE(1)
;     if (kt + 2 < nk) { LDS_STORE(0, 0) }
;     if (VAR != 4) __syncthreads();
	ds_write_b128 v18, v[90:93] offset:16384
	v_mfma_f32_16x16x32_f16 v[40:43], v[118:121], v[110:113], v[40:43]
	ds_read_b128 v[118:121], v22 offset:36864
	s_waitcnt vmcnt(5)
	ds_write_b128 v19, v[130:133] offset:16384
	v_mfma_f32_16x16x32_f16 v[70:73], v[122:125], v[106:109], v[70:73]
	ds_read_b128 v[106:109], v23
	v_mfma_f32_16x16x32_f16 v[48:51], v[122:125], v[110:113], v[48:51]
	ds_read_b128 v[110:113], v23 offset:2048
	s_waitcnt lgkmcnt(1)
	v_mfma_f32_16x16x32_f16 v[36:39], v[58:61], v[106:109], v[36:39]
	ds_read_b128 v[122:125], v22 offset:38912
	s_waitcnt lgkmcnt(1)
	v_mfma_f32_16x16x32_f16 v[66:69], v[58:61], v[110:113], v[66:69]
	s_waitcnt vmcnt(4)
	ds_write_b128 v20, v[138:141] offset:16384
	v_mfma_f32_16x16x32_f16 v[44:47], v[94:97], v[106:109], v[44:47]
	s_waitcnt vmcnt(3)
	ds_write_b128 v17, v[74:77] offset:49152
	v_mfma_f32_16x16x32_f16 v[78:81], v[94:97], v[110:113], v[78:81]
	s_waitcnt vmcnt(2)
	ds_write_b128 v18, v[142:145] offset:49152
	v_mfma_f32_16x16x32_f16 v[82:85], v[118:121], v[106:109], v[82:85]
	s_waitcnt vmcnt(1)
	ds_write_b128 v19, v[154:157] offset:49152
	v_mfma_f32_16x16x32_f16 v[86:89], v[118:121], v[110:113], v[86:89]
	s_waitcnt vmcnt(0)
	ds_write_b128 v20, v[158:161] offset:49152
	s_waitcnt lgkmcnt(5)
	v_mfma_f32_16x16x32_f16 v[28:31], v[122:125], v[106:109], v[28:31]
	ds_read_b128 v[106:109], v23 offset:4096
	v_mfma_f32_16x16x32_f16 v[32:35], v[122:125], v[110:113], v[32:35]
	ds_read_b128 v[110:113], v23 offset:6144
	s_waitcnt lgkmcnt(1)
	v_mfma_f32_16x16x32_f16 v[98:101], v[58:61], v[106:109], v[98:101]
	s_waitcnt lgkmcnt(0)
	v_mfma_f32_16x16x32_f16 v[52:55], v[58:61], v[110:113], v[52:55]
	global_load_dwordx4 v[58:61], v[0:1], off offset:2048
	v_mfma_f32_16x16x32_f16 v[102:105], v[94:97], v[106:109], v[102:105]
	v_mfma_f32_16x16x32_f16 v[24:27], v[94:97], v[110:113], v[24:27]
	v_mfma_f32_16x16x32_f16 v[114:117], v[118:121], v[106:109], v[114:117]
	v_mfma_f32_16x16x32_f16 v[40:43], v[118:121], v[110:113], v[40:43]
	v_mfma_f32_16x16x32_f16 v[70:73], v[122:125], v[106:109], v[70:73]
	global_load_dwordx4 v[106:109], v[2:3], off offset:2048
	global_load_dwordx4 v[126:129], v[4:5], off offset:2048
	global_load_dwordx4 v[134:137], v[14:15], off offset:2048
	global_load_dwordx4 v[94:97], v[10:11], off offset:2048
	global_load_dwordx4 v[162:165], v[12:13], off offset:2048
	global_load_dwordx4 v[166:169], v[8:9], off offset:2048
	global_load_dwordx4 v[190:193], v[6:7], off offset:2048
	s_waitcnt lgkmcnt(0)
	s_barrier
	v_mfma_f32_16x16x32_f16 v[48:51], v[122:125], v[110:113], v[48:51]
	ds_read_b128 v[62:65], v16 offset:49152
	ds_read_b128 v[90:93], v21 offset:16384
	s_waitcnt lgkmcnt(0)
	v_mfma_f32_16x16x32_f16 v[36:39], v[62:65], v[90:93], v[36:39]
	ds_read_b128 v[74:77], v16 offset:51200
	ds_read_b128 v[110:113], v21 offset:18432
	s_waitcnt lgkmcnt(0)
	v_mfma_f32_16x16x32_f16 v[66:69], v[62:65], v[110:113], v[66:69]
	ds_read_b128 v[118:121], v16 offset:53248
	v_mfma_f32_16x16x32_f16 v[44:47], v[74:77], v[90:93], v[44:47]
	ds_read_b128 v[122:125], v16 offset:55296
	v_mfma_f32_16x16x32_f16 v[78:81], v[74:77], v[110:113], v[78:81]
	s_waitcnt lgkmcnt(1)
	v_mfma_f32_16x16x32_f16 v[82:85], v[118:121], v[90:93], v[82:85]
	v_mfma_f32_16x16x32_f16 v[86:89], v[118:121], v[110:113], v[86:89]
	s_waitcnt lgkmcnt(0)
	v_mfma_f32_16x16x32_f16 v[28:31], v[122:125], v[90:93], v[28:31]
	ds_read_b128 v[90:93], v21 offset:20480
	v_mfma_f32_16x16x32_f16 v[32:35], v[122:125], v[110:113], v[32:35]
	ds_read_b128 v[110:113], v21 offset:22528
	s_waitcnt lgkmcnt(1)
	v_mfma_f32_16x16x32_f16 v[98:101], v[62:65], v[90:93], v[98:101]
	s_waitcnt lgkmcnt(0)
	v_mfma_f32_16x16x32_f16 v[52:55], v[62:65], v[110:113], v[52:55]
	ds_read_b128 v[62:65], v22 offset:49152
	v_mfma_f32_16x16x32_f16 v[102:105], v[74:77], v[90:93], v[102:105]
	v_mfma_f32_16x16x32_f16 v[24:27], v[74:77], v[110:113], v[24:27]
	ds_read_b128 v[74:77], v22 offset:51200
	v_mfma_f32_16x16x32_f16 v[114:117], v[118:121], v[90:93], v[114:117]
	s_waitcnt vmcnt(7)
	ds_write_b128 v17, v[58:61]
	s_waitcnt vmcnt(6)
	ds_write_b128 v18, v[106:109]
	v_mfma_f32_16x16x32_f16 v[40:43], v[118:121], v[110:113], v[40:43]
	ds_read_b128 v[118:121], v22 offset:53248
	s_waitcnt vmcnt(5)
	ds_write_b128 v19, v[126:129]
	v_mfma_f32_16x16x32_f16 v[70:73], v[122:125], v[90:93], v[70:73]
	ds_read_b128 v[90:93], v23 offset:16384
	v_mfma_f32_16x16x32_f16 v[48:51], v[122:125], v[110:113], v[48:51]
	ds_read_b128 v[110:113], v23 offset:18432
	s_waitcnt lgkmcnt(1)
	v_mfma_f32_16x16x32_f16 v[36:39], v[62:65], v[90:93], v[36:39]
	ds_read_b128 v[122:125], v22 offset:55296
	s_waitcnt lgkmcnt(1)
	v_mfma_f32_16x16x32_f16 v[66:69], v[62:65], v[110:113], v[66:69]
	s_waitcnt vmcnt(4)
	ds_write_b128 v20, v[134:137]
	v_mfma_f32_16x16x32_f16 v[44:47], v[74:77], v[90:93], v[44:47]
	s_waitcnt vmcnt(3)
	ds_write_b128 v17, v[94:97] offset:32768
	v_mfma_f32_16x16x32_f16 v[78:81], v[74:77], v[110:113], v[78:81]
	s_waitcnt vmcnt(2)
	ds_write_b128 v18, v[162:165] offset:32768
	v_mfma_f32_16x16x32_f16 v[82:85], v[118:121], v[90:93], v[82:85]
	s_waitcnt vmcnt(1)
	ds_write_b128 v19, v[166:169] offset:32768
	v_mfma_f32_16x16x32_f16 v[86:89], v[118:121], v[110:113], v[86:89]
	s_waitcnt vmcnt(0)
	ds_write_b128 v20, v[190:193] offset:32768
	s_waitcnt lgkmcnt(5)
	v_mfma_f32_16x16x32_f16 v[28:31], v[122:125], v[90:93], v[28:31]
	ds_read_b128 v[90:93], v23 offset:20480
	v_mfma_f32_16x16x32_f16 v[32:35], v[122:125], v[110:113], v[32:35]
	ds_read_b128 v[110:113], v23 offset:22528
	s_waitcnt lgkmcnt(1)
	v_mfma_f32_16x16x32_f16 v[98:101], v[62:65], v[90:93], v[98:101]
	s_waitcnt lgkmcnt(0)
	v_mfma_f32_16x16x32_f16 v[52:55], v[62:65], v[110:113], v[52:55]
	global_load_dwordx4 v[62:65], v[0:1], off offset:2176
	v_mfma_f32_16x16x32_f16 v[102:105], v[74:77], v[90:93], v[102:105]
	v_mfma_f32_16x16x32_f16 v[24:27], v[74:77], v[110:113], v[24:27]
	v_mfma_f32_16x16x32_f16 v[114:117], v[118:121], v[90:93], v[114:117]
	v_mfma_f32_16x16x32_f16 v[40:43], v[118:121], v[110:113], v[40:43]
	v_mfma_f32_16x16x32_f16 v[70:73], v[122:125], v[90:93], v[70:73]
	global_load_dwordx4 v[90:93], v[2:3], off offset:2176
	global_load_dwordx4 v[130:133], v[4:5], off offset:2176
	global_load_dwordx4 v[138:141], v[14:15], off offset:2176
	global_load_dwordx4 v[74:77], v[10:11], off offset:2176
	global_load_dwordx4 v[142:145], v[12:13], off offset:2176
	global_load_dwordx4 v[154:157], v[8:9], off offset:2176
	global_load_dwordx4 v[158:161], v[6:7], off offset:2176
	s_waitcnt lgkmcnt(0)
	s_barrier
; #define GL_LOAD(s_, kt_) if (VAR != 1) { a##s_##0 = GL_A(0, kt_); a##s_##1 = GL_A(1, kt_); a##s_##2 = GL_A(2, kt_); a##s_##3 = GL_A(3, kt_); b##s_##0 = GL_B(0, kt_); b##s_##1 = GL_B(1, kt_); b##s_##2 = GL_B(2, kt_); b##s_##3 = GL_B(3, kt_); }
; #define LDS_STORE(s_, buf_) if (VAR != 2) { LDS_ST1(sA, 0, buf_, a##s_##0) LDS_ST1(sA, 1, buf_, a##s_##1) LDS_ST1(sA, 2, buf_, a##s_##2) LDS_ST1(sA, 3, buf_, a##s_##3) LDS_ST1(sB, 0, buf_, b##s_##0) LDS_ST1(sB, 1, buf_, b##s_##1) LDS_ST1(sB, 2, buf_, b##s_##2) LDS_ST1(sB, 3, buf_, b##s_##3) }
;     ...
;   for (int kt = 0; kt < nk; kt += 2) {
;     if (kt + 2 < nk) { GL_LOAD(0, kt + 2) }
;     MMA_TILE(0)
;     LDS_STORE(1, 1)
;     if (VAR != 4) __syncthreads();
;     if (kt + 3 < nk) { GL_LOAD(1, kt + 3) }
;     MMA_TILE(1)
;     if (kt + 2 < nk) { LDS_STORE(0, 0) }
;     if (VAR != 4) __syncthreads();
	v_mfma_f32_16x16x32_f16 v[48:51], v[122:125], v[110:113], v[48:51]
	ds_read_b128 v[58:61], v16 offset:32768
	ds_read_b128 v[106:109], v21
	s_waitcnt lgkmcnt(0)
	v_mfma_f32_16x16x32_f16 v[36:39], v[58:61], v[106:109], v[36:39]
	ds_read_b128 v[94:97], v16 offset:34816
	ds_read_b128 v[110:113], v21 offset:2048
	s_waitcnt lgkmcnt(0)
	v_mfma_f32_16x16x32_f16 v[66:69], v[58:61], v[110:113], v[66:69]
	ds_read_b128 v[118:121], v16 offset:36864
	v_mfma_f32_16x16x32_f16 v[44:47], v[94:97], v[106:109], v[44:47]
	ds_read_b128 v[122:125], v16 offset:38912
	v_mfma_f32_16x16x32_f16 v[78:81], v[94:97], v[110:113], v[78:81]
	s_waitcnt lgkmcnt(1)
	v_mfma_f32_16x16x32_f16 v[82:85], v[118:121], v[106:109], v[82:85]
	v_mfma_f32_16x16x32_f16 v[86:89], v[118:121], v[110:113], v[86:89]
	s_waitcnt lgkmcnt(0)
	v_mfma_f32_16x16x32_f16 v[28:31], v[122:125], v[106:109], v[28:31]
	ds_read_b128 v[106:109], v21 offset:4096
	v_mfma_f32_16x16x32_f16 v[32:35], v[122:125], v[110:113], v[32:35]
	ds_read_b128 v[110:113], v21 offset:6144
	s_waitcnt lgkmcnt(1)
	v_mfma_f32_16x16x32_f16 v[98:101], v[58:61], v[106:109], v[98:101]
	s_waitcnt lgkmcnt(0)
	v_mfma_f32_16x16x32_f16 v[52:55], v[58:61], v[110:113], v[52:55]
	ds_read_b128 v[58:61], v22 offset:32768
	v_mfma_f32_16x16x32_f16 v[102:105], v[94:97], v[106:109], v[102:105]
	v_mfma_f32_16x16x32_f16 v[24:27], v[94:97], v[110:113], v[24:27]
	ds_read_b128 v[94:97], v22 offset:34816
	v_mfma_f32_16x16x32_f16 v[114:117], v[118:121], v[106:109], v[114:117]
	s_waitcnt vmcnt(7)
	ds_write_b128 v17, v[62:65] offset:16384
	s_waitcnt vmcnt(6)
	ds_write_b128 v18, v[90:93] offset:16384
	v_mfma_f32_16x16x32_f16 v[40:43], v[118:121], v[110:113], v[40:43]
	ds_read_b128 v[118:121], v22 offset:36864
	s_waitcnt vmcnt(5)
	ds_write_b128 v19, v[130:133] offset:16384
	v_mfma_f32_16x16x32_f16 v[70:73], v[122:125], v[106:109], v[70:73]
	ds_read_b128 v[106:109], v23
	v_mfma_f32_16x16x32_f16 v[48:51], v[122:125], v[110:113], v[48:51]
	ds_read_b128 v[110:113], v23 offset:2048
	s_waitcnt lgkmcnt(1)
	v_mfma_f32_16x16x32_f16 v[36:39], v[58:61], v[106:109], v[36:39]
	ds_read_b128 v[122:125], v22 offset:38912
	s_waitcnt lgkmcnt(1)
	v_mfma_f32_16x16x32_f16 v[66:69], v[58:61], v[110:113], v[66:69]
	s_waitcnt vmcnt(4)
	ds_write_b128 v20, v[138:141] offset:16384
	v_mfma_f32_16x16x32_f16 v[44:47], v[94:97], v[106:109], v[44:47]
	s_waitcnt vmcnt(3)
	ds_write_b128 v17, v[74:77] offset:49152
	v_mfma_f32_16x16x32_f16 v[78:81], v[94:97], v[110:113], v[78:81]
	s_waitcnt vmcnt(2)
	ds_write_b128 v18, v[142:145] offset:49152
	v_mfma_f32_16x16x32_f16 v[82:85], v[118:121], v[106:109], v[82:85]
	s_waitcnt vmcnt(1)
	ds_write_b128 v19, v[154:157] offset:49152
	v_mfma_f32_16x16x32_f16 v[86:89], v[118:121], v[110:113], v[86:89]
	s_waitcnt vmcnt(0)
	ds_write_b128 v20, v[158:161] offset:49152
	s_waitcnt lgkmcnt(5)
	v_mfma_f32_16x16x32_f16 v[28:31], v[122:125], v[106:109], v[28:31]
	ds_read_b128 v[106:109], v23 offset:4096
	v_mfma_f32_16x16x32_f16 v[32:35], v[122:125], v[110:113], v[32:35]
	ds_read_b128 v[110:113], v23 offset:6144
	s_waitcnt lgkmcnt(1)
	v_mfma_f32_16x16x32_f16 v[98:101], v[58:61], v[106:109], v[98:101]
	s_waitcnt lgkmcnt(0)
	v_mfma_f32_16x16x32_f16 v[52:55], v[58:61], v[110:113], v[52:55]
	global_load_dwordx4 v[58:61], v[0:1], off offset:2304
	v_mfma_f32_16x16x32_f16 v[102:105], v[94:97], v[106:109], v[102:105]
	v_mfma_f32_16x16x32_f16 v[24:27], v[94:97], v[110:113], v[24:27]
	v_mfma_f32_16x16x32_f16 v[114:117], v[118:121], v[106:109], v[114:117]
	v_mfma_f32_16x16x32_f16 v[40:43], v[118:121], v[110:113], v[40:43]
	v_mfma_f32_16x16x32_f16 v[70:73], v[122:125], v[106:109], v[70:73]
	global_load_dwordx4 v[106:109], v[2:3], off offset:2304
	global_load_dwordx4 v[126:129], v[4:5], off offset:2304
	global_load_dwordx4 v[134:137], v[14:15], off offset:2304
	global_load_dwordx4 v[94:97], v[10:11], off offset:2304
	global_load_dwordx4 v[162:165], v[12:13], off offset:2304
	global_load_dwordx4 v[166:169], v[8:9], off offset:2304
	global_load_dwordx4 v[190:193], v[6:7], off offset:2304
	s_waitcnt lgkmcnt(0)
	s_barrier
	v_mfma_f32_16x16x32_f16 v[48:51], v[122:125], v[110:113], v[48:51]
	ds_read_b128 v[62:65], v16 offset:49152
	ds_read_b128 v[90:93], v21 offset:16384
	s_waitcnt lgkmcnt(0)
	v_mfma_f32_16x16x32_f16 v[36:39], v[62:65], v[90:93], v[36:39]
	ds_read_b128 v[74:77], v16 offset:51200
	ds_read_b128 v[110:113], v21 offset:18432
	s_waitcnt lgkmcnt(0)
	v_mfma_f32_16x16x32_f16 v[66:69], v[62:65], v[110:113], v[66:69]
	ds_read_b128 v[118:121], v16 offset:53248
	v_mfma_f32_16x16x32_f16 v[44:47], v[74:77], v[90:93], v[44:47]
	ds_read_b128 v[122:125], v16 offset:55296
	v_mfma_f32_16x16x32_f16 v[78:81], v[74:77], v[110:113], v[78:81]
	s_waitcnt lgkmcnt(1)
	v_mfma_f32_16x16x32_f16 v[82:85], v[118:121], v[90:93], v[82:85]
	v_mfma_f32_16x16x32_f16 v[86:89], v[118:121], v[110:113], v[86:89]
	s_waitcnt lgkmcnt(0)
	v_mfma_f32_16x16x32_f16 v[28:31], v[122:125], v[90:93], v[28:31]
	ds_read_b128 v[90:93], v21 offset:20480
	v_mfma_f32_16x16x32_f16 v[32:35], v[122:125], v[110:113], v[32:35]
	ds_read_b128 v[110:113], v21 offset:22528
	s_waitcnt lgkmcnt(1)
	v_mfma_f32_16x16x32_f16 v[98:101], v[62:65], v[90:93], v[98:101]
	s_waitcnt lgkmcnt(0)
	v_mfma_f32_16x16x32_f16 v[52:55], v[62:65], v[110:113], v[52:55]
	ds_read_b128 v[62:65], v22 offset:49152
	v_mfma_f32_16x16x32_f16 v[102:105], v[74:77], v[90:93], v[102:105]
	v_mfma_f32_16x16x32_f16 v[24:27], v[74:77], v[110:113], v[24:27]
	ds_read_b128 v[74:77], v22 offset:51200
	v_mfma_f32_16x16x32_f16 v[114:117], v[118:121], v[90:93], v[114:117]
	s_waitcnt vmcnt(7)
	ds_write_b128 v17, v[58:61]
	s_waitcnt vmcnt(6)
; #define GL_LOAD(s_, kt_) if (VAR != 1) { a##s_##0 = GL_A(0, kt_); a##s_##1 = GL_A(1, kt_); a##s_##2 = GL_A(2, kt_); a##s_##3 = GL_A(3, kt_); b##s_##0 = GL_B(0, kt_); b##s_##1 = GL_B(1, kt_); b##s_##2 = GL_B(2, kt_); b##s_##3 = GL_B(3, kt_); }
; #define LDS_STORE(s_, buf_) if (VAR != 2) { LDS_ST1(sA, 0, buf_, a##s_##0) LDS_ST1(sA, 1, buf_, a##s_##1) LDS_ST1(sA, 2, buf_, a##s_##2) LDS_ST1(sA, 3, buf_, a##s_##3) LDS_ST1(sB, 0, buf_, b##s_##0) LDS_ST1(sB, 1, buf_, b##s_##1) LDS_ST1(sB, 2, buf_, b##s_##2) LDS_ST1(sB, 3, buf_, b##s_##3) }
;     ...
;   for (int kt = 0; kt < nk; kt += 2) {
;     if (kt + 2 < nk) { GL_LOAD(0, kt + 2) }
;     MMA_TILE(0)
;     LDS_STORE(1, 1)
;     if (VAR != 4) __syncthreads();
;     if (kt + 3 < nk) { GL_LOAD(1, kt + 3) }
;     MMA_TILE(1)
;     if (kt + 2 < nk) { LDS_STORE(0, 0) }
;     if (VAR != 4) __syncthreads();
	ds_write_b128 v18, v[106:109]
	v_mfma_f32_16x16x32_f16 v[40:43], v[118:121], v[110:113], v[40:43]
	ds_read_b128 v[118:121], v22 offset:53248
	s_waitcnt vmcnt(5)
	ds_write_b128 v19, v[126:129]
	v_mfma_f32_16x16x32_f16 v[70:73], v[122:125], v[90:93], v[70:73]
	ds_read_b128 v[90:93], v23 offset:16384
	v_mfma_f32_16x16x32_f16 v[48:51], v[122:125], v[110:113], v[48:51]
	ds_read_b128 v[110:113], v23 offset:18432
	s_waitcnt lgkmcnt(1)
	v_mfma_f32_16x16x32_f16 v[36:39], v[62:65], v[90:93], v[36:39]
	ds_read_b128 v[122:125], v22 offset:55296
	s_waitcnt lgkmcnt(1)
	v_mfma_f32_16x16x32_f16 v[66:69], v[62:65], v[110:113], v[66:69]
	s_waitcnt vmcnt(4)
	ds_write_b128 v20, v[134:137]
	v_mfma_f32_16x16x32_f16 v[44:47], v[74:77], v[90:93], v[44:47]
	s_waitcnt vmcnt(3)
	ds_write_b128 v17, v[94:97] offset:32768
	v_mfma_f32_16x16x32_f16 v[78:81], v[74:77], v[110:113], v[78:81]
	s_waitcnt vmcnt(2)
	ds_write_b128 v18, v[162:165] offset:32768
	v_mfma_f32_16x16x32_f16 v[82:85], v[118:121], v[90:93], v[82:85]
	s_waitcnt vmcnt(1)
	ds_write_b128 v19, v[166:169] offset:32768
	v_mfma_f32_16x16x32_f16 v[86:89], v[118:121], v[110:113], v[86:89]
	s_waitcnt vmcnt(0)
	ds_write_b128 v20, v[190:193] offset:32768
	s_waitcnt lgkmcnt(5)
	v_mfma_f32_16x16x32_f16 v[28:31], v[122:125], v[90:93], v[28:31]
	ds_read_b128 v[90:93], v23 offset:20480
	v_mfma_f32_16x16x32_f16 v[32:35], v[122:125], v[110:113], v[32:35]
	ds_read_b128 v[110:113], v23 offset:22528
	s_waitcnt lgkmcnt(1)
	v_mfma_f32_16x16x32_f16 v[98:101], v[62:65], v[90:93], v[98:101]
	s_waitcnt lgkmcnt(0)
	v_mfma_f32_16x16x32_f16 v[52:55], v[62:65], v[110:113], v[52:55]
	global_load_dwordx4 v[62:65], v[0:1], off offset:2432
	v_mfma_f32_16x16x32_f16 v[102:105], v[74:77], v[90:93], v[102:105]
	v_mfma_f32_16x16x32_f16 v[24:27], v[74:77], v[110:113], v[24:27]
	v_mfma_f32_16x16x32_f16 v[114:117], v[118:121], v[90:93], v[114:117]
	v_mfma_f32_16x16x32_f16 v[40:43], v[118:121], v[110:113], v[40:43]
	v_mfma_f32_16x16x32_f16 v[70:73], v[122:125], v[90:93], v[70:73]
	global_load_dwordx4 v[90:93], v[2:3], off offset:2432
	global_load_dwordx4 v[130:133], v[4:5], off offset:2432
	global_load_dwordx4 v[138:141], v[14:15], off offset:2432
	global_load_dwordx4 v[74:77], v[10:11], off offset:2432
	global_load_dwordx4 v[142:145], v[12:13], off offset:2432
	global_load_dwordx4 v[154:157], v[8:9], off offset:2432
	global_load_dwordx4 v[158:161], v[6:7], off offset:2432
	s_waitcnt lgkmcnt(0)
	s_barrier
	v_mfma_f32_16x16x32_f16 v[48:51], v[122:125], v[110:113], v[48:51]
	ds_read_b128 v[58:61], v16 offset:32768
	ds_read_b128 v[106:109], v21
	s_waitcnt lgkmcnt(0)
	v_mfma_f32_16x16x32_f16 v[36:39], v[58:61], v[106:109], v[36:39]
	ds_read_b128 v[94:97], v16 offset:34816
	ds_read_b128 v[110:113], v21 offset:2048
	s_waitcnt lgkmcnt(0)
	v_mfma_f32_16x16x32_f16 v[66:69], v[58:61], v[110:113], v[66:69]
	ds_read_b128 v[118:121], v16 offset:36864
	v_mfma_f32_16x16x32_f16 v[44:47], v[94:97], v[106:109], v[44:47]
	ds_read_b128 v[122:125], v16 offset:38912
	v_mfma_f32_16x16x32_f16 v[78:81], v[94:97], v[110:113], v[78:81]
	s_waitcnt lgkmcnt(1)
	v_mfma_f32_16x16x32_f16 v[82:85], v[118:121], v[106:109], v[82:85]
	v_mfma_f32_16x16x32_f16 v[86:89], v[118:121], v[110:113], v[86:89]
	s_waitcnt lgkmcnt(0)
	v_mfma_f32_16x16x32_f16 v[28:31], v[122:125], v[106:109], v[28:31]
	ds_read_b128 v[106:109], v21 offset:4096
	v_mfma_f32_16x16x32_f16 v[32:35], v[122:125], v[110:113], v[32:35]
	ds_read_b128 v[110:113], v21 offset:6144
	s_waitcnt lgkmcnt(1)
	v_mfma_f32_16x16x32_f16 v[98:101], v[58:61], v[106:109], v[98:101]
	s_waitcnt lgkmcnt(0)
	v_mfma_f32_16x16x32_f16 v[52:55], v[58:61], v[110:113], v[52:55]
	ds_read_b128 v[58:61], v22 offset:32768
	v_mfma_f32_16x16x32_f16 v[102:105], v[94:97], v[106:109], v[102:105]
	v_mfma_f32_16x16x32_f16 v[24:27], v[94:97], v[110:113], v[24:27]
	ds_read_b128 v[94:97], v22 offset:34816
	v_mfma_f32_16x16x32_f16 v[114:117], v[118:121], v[106:109], v[114:117]
	s_waitcnt vmcnt(7)
	ds_write_b128 v17, v[62:65] offset:16384
	s_waitcnt vmcnt(6)
	ds_write_b128 v18, v[90:93] offset:16384
	v_mfma_f32_16x16x32_f16 v[40:43], v[118:121], v[110:113], v[40:43]
	ds_read_b128 v[118:121], v22 offset:36864
	s_waitcnt vmcnt(5)
	ds_write_b128 v19, v[130:133] offset:16384
	v_mfma_f32_16x16x32_f16 v[70:73], v[122:125], v[106:109], v[70:73]
	ds_read_b128 v[106:109], v23
	v_mfma_f32_16x16x32_f16 v[48:51], v[122:125], v[110:113], v[48:51]
	ds_read_b128 v[110:113], v23 offset:2048
	s_waitcnt lgkmcnt(1)
	v_mfma_f32_16x16x32_f16 v[36:39], v[58:61], v[106:109], v[36:39]
	ds_read_b128 v[122:125], v22 offset:38912
	s_waitcnt lgkmcnt(1)
	v_mfma_f32_16x16x32_f16 v[66:69], v[58:61], v[110:113], v[66:69]
	s_waitcnt vmcnt(4)
	ds_write_b128 v20, v[138:141] offset:16384
	v_mfma_f32_16x16x32_f16 v[44:47], v[94:97], v[106:109], v[44:47]
	s_waitcnt vmcnt(3)
	ds_write_b128 v17, v[74:77] offset:49152
	v_mfma_f32_16x16x32_f16 v[78:81], v[94:97], v[110:113], v[78:81]
	s_waitcnt vmcnt(2)
	ds_write_b128 v18, v[142:145] offset:49152
	v_mfma_f32_16x16x32_f16 v[82:85], v[118:121], v[106:109], v[82:85]
	s_waitcnt vmcnt(1)
	ds_write_b128 v19, v[154:157] offset:49152
	v_mfma_f32_16x16x32_f16 v[86:89], v[118:121], v[110:113], v[86:89]
	s_waitcnt vmcnt(0)
	ds_write_b128 v20, v[158:161] offset:49152
	s_waitcnt lgkmcnt(5)
	v_mfma_f32_16x16x32_f16 v[28:31], v[122:125], v[106:109], v[28:31]
	ds_read_b128 v[106:109], v23 offset:4096
	v_mfma_f32_16x16x32_f16 v[32:35], v[122:125], v[110:113], v[32:35]
	ds_read_b128 v[110:113], v23 offset:6144
	s_waitcnt lgkmcnt(1)
	v_mfma_f32_16x16x32_f16 v[98:101], v[58:61], v[106:109], v[98:101]
	s_waitcnt lgkmcnt(0)
	v_mfma_f32_16x16x32_f16 v[52:55], v[58:61], v[110:113], v[52:55]
	global_load_dwordx4 v[58:61], v[0:1], off offset:2560
	v_mfma_f32_16x16x32_f16 v[102:105], v[94:97], v[106:109], v[102:105]
	v_mfma_f32_16x16x32_f16 v[24:27], v[94:97], v[110:113], v[24:27]
	v_mfma_f32_16x16x32_f16 v[114:117], v[118:121], v[106:109], v[114:117]
	v_mfma_f32_16x16x32_f16 v[40:43], v[118:121], v[110:113], v[40:43]
	v_mfma_f32_16x16x32_f16 v[70:73], v[122:125], v[106:109], v[70:73]
	global_load_dwordx4 v[106:109], v[2:3], off offset:2560
	global_load_dwordx4 v[126:129], v[4:5], off offset:2560
	global_load_dwordx4 v[134:137], v[14:15], off offset:2560
	global_load_dwordx4 v[94:97], v[10:11], off offset:2560
	global_load_dwordx4 v[162:165], v[12:13], off offset:2560
	global_load_dwordx4 v[166:169], v[8:9], off offset:2560
	global_load_dwordx4 v[190:193], v[6:7], off offset:2560
	s_waitcnt lgkmcnt(0)
	s_barrier
; #define GL_LOAD(s_, kt_) if (VAR != 1) { a##s_##0 = GL_A(0, kt_); a##s_##1 = GL_A(1, kt_); a##s_##2 = GL_A(2, kt_); a##s_##3 = GL_A(3, kt_); b##s_##0 = GL_B(0, kt_); b##s_##1 = GL_B(1, kt_); b##s_##2 = GL_B(2, kt_); b##s_##3 = GL_B(3, kt_); }
; #define LDS_STORE(s_, buf_) if (VAR != 2) { LDS_ST1(sA, 0, buf_, a##s_##0) LDS_ST1(sA, 1, buf_, a##s_##1) LDS_ST1(sA, 2, buf_, a##s_##2) LDS_ST1(sA, 3, buf_, a##s_##3) LDS_ST1(sB, 0, buf_, b##s_##0) LDS_ST1(sB, 1, buf_, b##s_##1) LDS_ST1(sB, 2, buf_, b##s_##2) LDS_ST1(sB, 3, buf_, b##s_##3) }
;     ...
;   for (int kt = 0; kt < nk; kt += 2) {
;     if (kt + 2 < nk) { GL_LOAD(0, kt + 2) }
;     MMA_TILE(0)
;     LDS_STORE(1, 1)
;     if (VAR != 4) __syncthreads();
;     if (kt + 3 < nk) { GL_LOAD(1, kt + 3) }
;     MMA_TILE(1)
;     if (kt + 2 < nk) { LDS_STORE(0, 0) }
;     if (VAR != 4) __syncthreads();
	v_mfma_f32_16x16x32_f16 v[48:51], v[122:125], v[110:113], v[48:51]
	ds_read_b128 v[62:65], v16 offset:49152
	ds_read_b128 v[90:93], v21 offset:16384
	s_waitcnt lgkmcnt(0)
	v_mfma_f32_16x16x32_f16 v[36:39], v[62:65], v[90:93], v[36:39]
	ds_read_b128 v[74:77], v16 offset:51200
	ds_read_b128 v[110:113], v21 offset:18432
	s_waitcnt lgkmcnt(0)
	v_mfma_f32_16x16x32_f16 v[66:69], v[62:65], v[110:113], v[66:69]
	ds_read_b128 v[118:121], v16 offset:53248
	v_mfma_f32_16x16x32_f16 v[44:47], v[74:77], v[90:93], v[44:47]
	ds_read_b128 v[122:125], v16 offset:55296
	v_mfma_f32_16x16x32_f16 v[78:81], v[74:77], v[110:113], v[78:81]
	s_waitcnt lgkmcnt(1)
	v_mfma_f32_16x16x32_f16 v[82:85], v[118:121], v[90:93], v[82:85]
	v_mfma_f32_16x16x32_f16 v[86:89], v[118:121], v[110:113], v[86:89]
	s_waitcnt lgkmcnt(0)
	v_mfma_f32_16x16x32_f16 v[28:31], v[122:125], v[90:93], v[28:31]
	ds_read_b128 v[90:93], v21 offset:20480
	v_mfma_f32_16x16x32_f16 v[32:35], v[122:125], v[110:113], v[32:35]
	ds_read_b128 v[110:113], v21 offset:22528
	s_waitcnt lgkmcnt(1)
	v_mfma_f32_16x16x32_f16 v[98:101], v[62:65], v[90:93], v[98:101]
	s_waitcnt lgkmcnt(0)
	v_mfma_f32_16x16x32_f16 v[52:55], v[62:65], v[110:113], v[52:55]
	ds_read_b128 v[62:65], v22 offset:49152
	v_mfma_f32_16x16x32_f16 v[102:105], v[74:77], v[90:93], v[102:105]
	v_mfma_f32_16x16x32_f16 v[24:27], v[74:77], v[110:113], v[24:27]
	ds_read_b128 v[74:77], v22 offset:51200
	v_mfma_f32_16x16x32_f16 v[114:117], v[118:121], v[90:93], v[114:117]
	s_waitcnt vmcnt(7)
	ds_write_b128 v17, v[58:61]
	s_waitcnt vmcnt(6)
	ds_write_b128 v18, v[106:109]
	v_mfma_f32_16x16x32_f16 v[40:43], v[118:121], v[110:113], v[40:43]
	ds_read_b128 v[118:121], v22 offset:53248
	s_waitcnt vmcnt(5)
	ds_write_b128 v19, v[126:129]
	v_mfma_f32_16x16x32_f16 v[70:73], v[122:125], v[90:93], v[70:73]
	ds_read_b128 v[90:93], v23 offset:16384
	v_mfma_f32_16x16x32_f16 v[48:51], v[122:125], v[110:113], v[48:51]
	ds_read_b128 v[110:113], v23 offset:18432
	s_waitcnt lgkmcnt(1)
	v_mfma_f32_16x16x32_f16 v[36:39], v[62:65], v[90:93], v[36:39]
	ds_read_b128 v[122:125], v22 offset:55296
	s_waitcnt lgkmcnt(1)
	v_mfma_f32_16x16x32_f16 v[66:69], v[62:65], v[110:113], v[66:69]
	s_waitcnt vmcnt(4)
	ds_write_b128 v20, v[134:137]
	v_mfma_f32_16x16x32_f16 v[44:47], v[74:77], v[90:93], v[44:47]
	s_waitcnt vmcnt(3)
	ds_write_b128 v17, v[94:97] offset:32768
	v_mfma_f32_16x16x32_f16 v[78:81], v[74:77], v[110:113], v[78:81]
	s_waitcnt vmcnt(2)
	ds_write_b128 v18, v[162:165] offset:32768
	v_mfma_f32_16x16x32_f16 v[82:85], v[118:121], v[90:93], v[82:85]
	s_waitcnt vmcnt(1)
	ds_write_b128 v19, v[166:169] offset:32768
	v_mfma_f32_16x16x32_f16 v[86:89], v[118:121], v[110:113], v[86:89]
	s_waitcnt vmcnt(0)
	ds_write_b128 v20, v[190:193] offset:32768
	s_waitcnt lgkmcnt(5)
	v_mfma_f32_16x16x32_f16 v[28:31], v[122:125], v[90:93], v[28:31]
	ds_read_b128 v[90:93], v23 offset:20480
	v_mfma_f32_16x16x32_f16 v[32:35], v[122:125], v[110:113], v[32:35]
	ds_read_b128 v[110:113], v23 offset:22528
	s_waitcnt lgkmcnt(1)
	v_mfma_f32_16x16x32_f16 v[98:101], v[62:65], v[90:93], v[98:101]
	s_waitcnt lgkmcnt(0)
	v_mfma_f32_16x16x32_f16 v[52:55], v[62:65], v[110:113], v[52:55]
	global_load_dwordx4 v[62:65], v[0:1], off offset:2688
	v_mfma_f32_16x16x32_f16 v[102:105], v[74:77], v[90:93], v[102:105]
	v_mfma_f32_16x16x32_f16 v[24:27], v[74:77], v[110:113], v[24:27]
	v_mfma_f32_16x16x32_f16 v[114:117], v[118:121], v[90:93], v[114:117]
	v_mfma_f32_16x16x32_f16 v[40:43], v[118:121], v[110:113], v[40:43]
	v_mfma_f32_16x16x32_f16 v[70:73], v[122:125], v[90:93], v[70:73]
	global_load_dwordx4 v[90:93], v[2:3], off offset:2688
	global_load_dwordx4 v[130:133], v[4:5], off offset:2688
	global_load_dwordx4 v[138:141], v[14:15], off offset:2688
	global_load_dwordx4 v[74:77], v[10:11], off offset:2688
	global_load_dwordx4 v[142:145], v[12:13], off offset:2688
	global_load_dwordx4 v[154:157], v[8:9], off offset:2688
	global_load_dwordx4 v[158:161], v[6:7], off offset:2688
	s_waitcnt lgkmcnt(0)
	s_barrier
	v_mfma_f32_16x16x32_f16 v[48:51], v[122:125], v[110:113], v[48:51]
	ds_read_b128 v[58:61], v16 offset:32768
	ds_read_b128 v[106:109], v21
	s_waitcnt lgkmcnt(0)
	v_mfma_f32_16x16x32_f16 v[36:39], v[58:61], v[106:109], v[36:39]
	ds_read_b128 v[94:97], v16 offset:34816
	ds_read_b128 v[110:113], v21 offset:2048
	s_waitcnt lgkmcnt(0)
	v_mfma_f32_16x16x32_f16 v[66:69], v[58:61], v[110:113], v[66:69]
	ds_read_b128 v[118:121], v16 offset:36864
	v_mfma_f32_16x16x32_f16 v[44:47], v[94:97], v[106:109], v[44:47]
	ds_read_b128 v[122:125], v16 offset:38912
	v_mfma_f32_16x16x32_f16 v[78:81], v[94:97], v[110:113], v[78:81]
	s_waitcnt lgkmcnt(1)
	v_mfma_f32_16x16x32_f16 v[82:85], v[118:121], v[106:109], v[82:85]
	v_mfma_f32_16x16x32_f16 v[86:89], v[118:121], v[110:113], v[86:89]
	s_waitcnt lgkmcnt(0)
	v_mfma_f32_16x16x32_f16 v[28:31], v[122:125], v[106:109], v[28:31]
	ds_read_b128 v[106:109], v21 offset:4096
	v_mfma_f32_16x16x32_f16 v[32:35], v[122:125], v[110:113], v[32:35]
	ds_read_b128 v[110:113], v21 offset:6144
	s_waitcnt lgkmcnt(1)
	v_mfma_f32_16x16x32_f16 v[98:101], v[58:61], v[106:109], v[98:101]
	s_waitcnt lgkmcnt(0)
	v_mfma_f32_16x16x32_f16 v[52:55], v[58:61], v[110:113], v[52:55]
	ds_read_b128 v[58:61], v22 offset:32768
	v_mfma_f32_16x16x32_f16 v[102:105], v[94:97], v[106:109], v[102:105]
	v_mfma_f32_16x16x32_f16 v[24:27], v[94:97], v[110:113], v[24:27]
	ds_read_b128 v[94:97], v22 offset:34816
	v_mfma_f32_16x16x32_f16 v[114:117], v[118:121], v[106:109], v[114:117]
	s_waitcnt vmcnt(7)
	ds_write_b128 v17, v[62:65] offset:16384
	s_waitcnt vmcnt(6)
; #define GL_LOAD(s_, kt_) if (VAR != 1) { a##s_##0 = GL_A(0, kt_); a##s_##1 = GL_A(1, kt_); a##s_##2 = GL_A(2, kt_); a##s_##3 = GL_A(3, kt_); b##s_##0 = GL_B(0, kt_); b##s_##1 = GL_B(1, kt_); b##s_##2 = GL_B(2, kt_); b##s_##3 = GL_B(3, kt_); }
; #define LDS_STORE(s_, buf_) if (VAR != 2) { LDS_ST1(sA, 0, buf_, a##s_##0) LDS_ST1(sA, 1, buf_, a##s_##1) LDS_ST1(sA, 2, buf_, a##s_##2) LDS_ST1(sA, 3, buf_, a##s_##3) LDS_ST1(sB, 0, buf_, b##s_##0) LDS_ST1(sB, 1, buf_, b##s_##1) LDS_ST1(sB, 2, buf_, b##s_##2) LDS_ST1(sB, 3, buf_, b##s_##3) }
;     ...
;   for (int kt = 0; kt < nk; kt += 2) {
;     if (kt + 2 < nk) { GL_LOAD(0, kt + 2) }
;     MMA_TILE(0)
;     LDS_STORE(1, 1)
;     if (VAR != 4) __syncthreads();
;     if (kt + 3 < nk) { GL_LOAD(1, kt + 3) }
;     MMA_TILE(1)
;     if (kt + 2 < nk) { LDS_STORE(0, 0) }
;     if (VAR != 4) __syncthreads();
	ds_write_b128 v18, v[90:93] offset:16384
	v_mfma_f32_16x16x32_f16 v[40:43], v[118:121], v[110:113], v[40:43]
	ds_read_b128 v[118:121], v22 offset:36864
	s_waitcnt vmcnt(5)
	ds_write_b128 v19, v[130:133] offset:16384
	v_mfma_f32_16x16x32_f16 v[70:73], v[122:125], v[106:109], v[70:73]
	ds_read_b128 v[106:109], v23
	v_mfma_f32_16x16x32_f16 v[48:51], v[122:125], v[110:113], v[48:51]
	ds_read_b128 v[110:113], v23 offset:2048
	s_waitcnt lgkmcnt(1)
	v_mfma_f32_16x16x32_f16 v[36:39], v[58:61], v[106:109], v[36:39]
	ds_read_b128 v[122:125], v22 offset:38912
	s_waitcnt lgkmcnt(1)
	v_mfma_f32_16x16x32_f16 v[66:69], v[58:61], v[110:113], v[66:69]
	s_waitcnt vmcnt(4)
	ds_write_b128 v20, v[138:141] offset:16384
	v_mfma_f32_16x16x32_f16 v[44:47], v[94:97], v[106:109], v[44:47]
	s_waitcnt vmcnt(3)
	ds_write_b128 v17, v[74:77] offset:49152
	v_mfma_f32_16x16x32_f16 v[78:81], v[94:97], v[110:113], v[78:81]
	s_waitcnt vmcnt(2)
	ds_write_b128 v18, v[142:145] offset:49152
	v_mfma_f32_16x16x32_f16 v[82:85], v[118:121], v[106:109], v[82:85]
	s_waitcnt vmcnt(1)
	ds_write_b128 v19, v[154:157] offset:49152
	v_mfma_f32_16x16x32_f16 v[86:89], v[118:121], v[110:113], v[86:89]
	s_waitcnt vmcnt(0)
	ds_write_b128 v20, v[158:161] offset:49152
	s_waitcnt lgkmcnt(5)
	v_mfma_f32_16x16x32_f16 v[28:31], v[122:125], v[106:109], v[28:31]
	ds_read_b128 v[106:109], v23 offset:4096
	v_mfma_f32_16x16x32_f16 v[32:35], v[122:125], v[110:113], v[32:35]
	ds_read_b128 v[110:113], v23 offset:6144
	s_waitcnt lgkmcnt(1)
	v_mfma_f32_16x16x32_f16 v[98:101], v[58:61], v[106:109], v[98:101]
	s_waitcnt lgkmcnt(0)
	v_mfma_f32_16x16x32_f16 v[52:55], v[58:61], v[110:113], v[52:55]
	global_load_dwordx4 v[58:61], v[0:1], off offset:2816
	v_mfma_f32_16x16x32_f16 v[102:105], v[94:97], v[106:109], v[102:105]
	v_mfma_f32_16x16x32_f16 v[24:27], v[94:97], v[110:113], v[24:27]
	v_mfma_f32_16x16x32_f16 v[114:117], v[118:121], v[106:109], v[114:117]
	v_mfma_f32_16x16x32_f16 v[40:43], v[118:121], v[110:113], v[40:43]
	v_mfma_f32_16x16x32_f16 v[70:73], v[122:125], v[106:109], v[70:73]
	global_load_dwordx4 v[106:109], v[2:3], off offset:2816
	global_load_dwordx4 v[126:129], v[4:5], off offset:2816
	global_load_dwordx4 v[134:137], v[14:15], off offset:2816
	global_load_dwordx4 v[94:97], v[10:11], off offset:2816
	global_load_dwordx4 v[162:165], v[12:13], off offset:2816
	global_load_dwordx4 v[166:169], v[8:9], off offset:2816
	global_load_dwordx4 v[190:193], v[6:7], off offset:2816
	s_waitcnt lgkmcnt(0)
	s_barrier
	v_mfma_f32_16x16x32_f16 v[48:51], v[122:125], v[110:113], v[48:51]
	ds_read_b128 v[62:65], v16 offset:49152
	ds_read_b128 v[90:93], v21 offset:16384
	s_waitcnt lgkmcnt(0)
	v_mfma_f32_16x16x32_f16 v[36:39], v[62:65], v[90:93], v[36:39]
	ds_read_b128 v[74:77], v16 offset:51200
	ds_read_b128 v[110:113], v21 offset:18432
	s_waitcnt lgkmcnt(0)
	v_mfma_f32_16x16x32_f16 v[66:69], v[62:65], v[110:113], v[66:69]
	ds_read_b128 v[118:121], v16 offset:53248
	v_mfma_f32_16x16x32_f16 v[44:47], v[74:77], v[90:93], v[44:47]
	ds_read_b128 v[122:125], v16 offset:55296
	v_mfma_f32_16x16x32_f16 v[78:81], v[74:77], v[110:113], v[78:81]
	s_waitcnt lgkmcnt(1)
	v_mfma_f32_16x16x32_f16 v[82:85], v[118:121], v[90:93], v[82:85]
	v_mfma_f32_16x16x32_f16 v[86:89], v[118:121], v[110:113], v[86:89]
	s_waitcnt lgkmcnt(0)
	v_mfma_f32_16x16x32_f16 v[28:31], v[122:125], v[90:93], v[28:31]
	ds_read_b128 v[90:93], v21 offset:20480
	v_mfma_f32_16x16x32_f16 v[32:35], v[122:125], v[110:113], v[32:35]
	ds_read_b128 v[110:113], v21 offset:22528
	s_waitcnt lgkmcnt(1)
	v_mfma_f32_16x16x32_f16 v[98:101], v[62:65], v[90:93], v[98:101]
	s_waitcnt lgkmcnt(0)
	v_mfma_f32_16x16x32_f16 v[52:55], v[62:65], v[110:113], v[52:55]
	ds_read_b128 v[62:65], v22 offset:49152
	v_mfma_f32_16x16x32_f16 v[102:105], v[74:77], v[90:93], v[102:105]
	v_mfma_f32_16x16x32_f16 v[24:27], v[74:77], v[110:113], v[24:27]
	ds_read_b128 v[74:77], v22 offset:51200
	v_mfma_f32_16x16x32_f16 v[114:117], v[118:121], v[90:93], v[114:117]
	s_waitcnt vmcnt(7)
	ds_write_b128 v17, v[58:61]
	s_waitcnt vmcnt(6)
	ds_write_b128 v18, v[106:109]
	v_mfma_f32_16x16x32_f16 v[40:43], v[118:121], v[110:113], v[40:43]
	ds_read_b128 v[118:121], v22 offset:53248
	s_waitcnt vmcnt(5)
	ds_write_b128 v19, v[126:129]
	v_mfma_f32_16x16x32_f16 v[70:73], v[122:125], v[90:93], v[70:73]
	ds_read_b128 v[90:93], v23 offset:16384
	v_mfma_f32_16x16x32_f16 v[48:51], v[122:125], v[110:113], v[48:51]
	ds_read_b128 v[110:113], v23 offset:18432
	s_waitcnt lgkmcnt(1)
	v_mfma_f32_16x16x32_f16 v[36:39], v[62:65], v[90:93], v[36:39]
	ds_read_b128 v[122:125], v22 offset:55296
	s_waitcnt lgkmcnt(1)
	v_mfma_f32_16x16x32_f16 v[66:69], v[62:65], v[110:113], v[66:69]
	s_waitcnt vmcnt(4)
	ds_write_b128 v20, v[134:137]
	v_mfma_f32_16x16x32_f16 v[44:47], v[74:77], v[90:93], v[44:47]
	s_waitcnt vmcnt(3)
	ds_write_b128 v17, v[94:97] offset:32768
	v_mfma_f32_16x16x32_f16 v[78:81], v[74:77], v[110:113], v[78:81]
	s_waitcnt vmcnt(2)
	ds_write_b128 v18, v[162:165] offset:32768
	v_mfma_f32_16x16x32_f16 v[82:85], v[118:121], v[90:93], v[82:85]
	s_waitcnt vmcnt(1)
	ds_write_b128 v19, v[166:169] offset:32768
	v_mfma_f32_16x16x32_f16 v[86:89], v[118:121], v[110:113], v[86:89]
	s_waitcnt vmcnt(0)
	ds_write_b128 v20, v[190:193] offset:32768
	s_waitcnt lgkmcnt(5)
	v_mfma_f32_16x16x32_f16 v[28:31], v[122:125], v[90:93], v[28:31]
	ds_read_b128 v[90:93], v23 offset:20480
	v_mfma_f32_16x16x32_f16 v[32:35], v[122:125], v[110:113], v[32:35]
	ds_read_b128 v[110:113], v23 offset:22528
	s_waitcnt lgkmcnt(1)
	v_mfma_f32_16x16x32_f16 v[98:101], v[62:65], v[90:93], v[98:101]
	s_waitcnt lgkmcnt(0)
	v_mfma_f32_16x16x32_f16 v[52:55], v[62:65], v[110:113], v[52:55]
	global_load_dwordx4 v[62:65], v[0:1], off offset:2944
	v_mfma_f32_16x16x32_f16 v[102:105], v[74:77], v[90:93], v[102:105]
	v_mfma_f32_16x16x32_f16 v[24:27], v[74:77], v[110:113], v[24:27]
	v_mfma_f32_16x16x32_f16 v[114:117], v[118:121], v[90:93], v[114:117]
	v_mfma_f32_16x16x32_f16 v[40:43], v[118:121], v[110:113], v[40:43]
	v_mfma_f32_16x16x32_f16 v[70:73], v[122:125], v[90:93], v[70:73]
	global_load_dwordx4 v[90:93], v[2:3], off offset:2944
	global_load_dwordx4 v[130:133], v[4:5], off offset:2944
	global_load_dwordx4 v[138:141], v[14:15], off offset:2944
	global_load_dwordx4 v[74:77], v[10:11], off offset:2944
	global_load_dwordx4 v[142:145], v[12:13], off offset:2944
	global_load_dwordx4 v[154:157], v[8:9], off offset:2944
	global_load_dwordx4 v[158:161], v[6:7], off offset:2944
	s_waitcnt lgkmcnt(0)
	s_barrier
; #define GL_LOAD(s_, kt_) if (VAR != 1) { a##s_##0 = GL_A(0, kt_); a##s_##1 = GL_A(1, kt_); a##s_##2 = GL_A(2, kt_); a##s_##3 = GL_A(3, kt_); b##s_##0 = GL_B(0, kt_); b##s_##1 = GL_B(1, kt_); b##s_##2 = GL_B(2, kt_); b##s_##3 = GL_B(3, kt_); }
; #define LDS_STORE(s_, buf_) if (VAR != 2) { LDS_ST1(sA, 0, buf_, a##s_##0) LDS_ST1(sA, 1, buf_, a##s_##1) LDS_ST1(sA, 2, buf_, a##s_##2) LDS_ST1(sA, 3, buf_, a##s_##3) LDS_ST1(sB, 0, buf_, b##s_##0) LDS_ST1(sB, 1, buf_, b##s_##1) LDS_ST1(sB, 2, buf_, b##s_##2) LDS_ST1(sB, 3, buf_, b##s_##3) }
;     ...
;   for (int kt = 0; kt < nk; kt += 2) {
;     if (kt + 2 < nk) { GL_LOAD(0, kt + 2) }
;     MMA_TILE(0)
;     LDS_STORE(1, 1)
;     if (VAR != 4) __syncthreads();
;     if (kt + 3 < nk) { GL_LOAD(1, kt + 3) }
;     MMA_TILE(1)
;     if (kt + 2 < nk) { LDS_STORE(0, 0) }
;     if (VAR != 4) __syncthreads();
	v_mfma_f32_16x16x32_f16 v[48:51], v[122:125], v[110:113], v[48:51]
	ds_read_b128 v[58:61], v16 offset:32768
	ds_read_b128 v[106:109], v21
	s_waitcnt lgkmcnt(0)
	v_mfma_f32_16x16x32_f16 v[36:39], v[58:61], v[106:109], v[36:39]
	ds_read_b128 v[94:97], v16 offset:34816
	ds_read_b128 v[110:113], v21 offset:2048
	s_waitcnt lgkmcnt(0)
	v_mfma_f32_16x16x32_f16 v[66:69], v[58:61], v[110:113], v[66:69]
	ds_read_b128 v[118:121], v16 offset:36864
	v_mfma_f32_16x16x32_f16 v[44:47], v[94:97], v[106:109], v[44:47]
	ds_read_b128 v[122:125], v16 offset:38912
	v_mfma_f32_16x16x32_f16 v[78:81], v[94:97], v[110:113], v[78:81]
	s_waitcnt lgkmcnt(1)
	v_mfma_f32_16x16x32_f16 v[82:85], v[118:121], v[106:109], v[82:85]
	v_mfma_f32_16x16x32_f16 v[86:89], v[118:121], v[110:113], v[86:89]
	s_waitcnt lgkmcnt(0)
	v_mfma_f32_16x16x32_f16 v[28:31], v[122:125], v[106:109], v[28:31]
	ds_read_b128 v[106:109], v21 offset:4096
	v_mfma_f32_16x16x32_f16 v[32:35], v[122:125], v[110:113], v[32:35]
	ds_read_b128 v[110:113], v21 offset:6144
	s_waitcnt lgkmcnt(1)
	v_mfma_f32_16x16x32_f16 v[98:101], v[58:61], v[106:109], v[98:101]
	s_waitcnt lgkmcnt(0)
	v_mfma_f32_16x16x32_f16 v[52:55], v[58:61], v[110:113], v[52:55]
	ds_read_b128 v[58:61], v22 offset:32768
	v_mfma_f32_16x16x32_f16 v[102:105], v[94:97], v[106:109], v[102:105]
	v_mfma_f32_16x16x32_f16 v[24:27], v[94:97], v[110:113], v[24:27]
	ds_read_b128 v[94:97], v22 offset:34816
	v_mfma_f32_16x16x32_f16 v[114:117], v[118:121], v[106:109], v[114:117]
	s_waitcnt vmcnt(7)
	ds_write_b128 v17, v[62:65] offset:16384
	s_waitcnt vmcnt(6)
	ds_write_b128 v18, v[90:93] offset:16384
	v_mfma_f32_16x16x32_f16 v[40:43], v[118:121], v[110:113], v[40:43]
	ds_read_b128 v[118:121], v22 offset:36864
	s_waitcnt vmcnt(5)
	ds_write_b128 v19, v[130:133] offset:16384
	v_mfma_f32_16x16x32_f16 v[70:73], v[122:125], v[106:109], v[70:73]
	ds_read_b128 v[106:109], v23
	v_mfma_f32_16x16x32_f16 v[48:51], v[122:125], v[110:113], v[48:51]
	ds_read_b128 v[110:113], v23 offset:2048
	s_waitcnt lgkmcnt(1)
	v_mfma_f32_16x16x32_f16 v[36:39], v[58:61], v[106:109], v[36:39]
	ds_read_b128 v[122:125], v22 offset:38912
	s_waitcnt lgkmcnt(1)
	v_mfma_f32_16x16x32_f16 v[66:69], v[58:61], v[110:113], v[66:69]
	s_waitcnt vmcnt(4)
	ds_write_b128 v20, v[138:141] offset:16384
	v_mfma_f32_16x16x32_f16 v[44:47], v[94:97], v[106:109], v[44:47]
	s_waitcnt vmcnt(3)
	ds_write_b128 v17, v[74:77] offset:49152
	v_mfma_f32_16x16x32_f16 v[78:81], v[94:97], v[110:113], v[78:81]
	s_waitcnt vmcnt(2)
	ds_write_b128 v18, v[142:145] offset:49152
	v_mfma_f32_16x16x32_f16 v[82:85], v[118:121], v[106:109], v[82:85]
	s_waitcnt vmcnt(1)
	ds_write_b128 v19, v[154:157] offset:49152
	v_mfma_f32_16x16x32_f16 v[86:89], v[118:121], v[110:113], v[86:89]
	s_waitcnt vmcnt(0)
	ds_write_b128 v20, v[158:161] offset:49152
	s_waitcnt lgkmcnt(5)
	v_mfma_f32_16x16x32_f16 v[28:31], v[122:125], v[106:109], v[28:31]
	ds_read_b128 v[106:109], v23 offset:4096
	v_mfma_f32_16x16x32_f16 v[32:35], v[122:125], v[110:113], v[32:35]
	ds_read_b128 v[110:113], v23 offset:6144
	s_waitcnt lgkmcnt(1)
	v_mfma_f32_16x16x32_f16 v[98:101], v[58:61], v[106:109], v[98:101]
	s_waitcnt lgkmcnt(0)
	v_mfma_f32_16x16x32_f16 v[52:55], v[58:61], v[110:113], v[52:55]
	global_load_dwordx4 v[58:61], v[0:1], off offset:3072
	v_mfma_f32_16x16x32_f16 v[102:105], v[94:97], v[106:109], v[102:105]
	v_mfma_f32_16x16x32_f16 v[24:27], v[94:97], v[110:113], v[24:27]
	v_mfma_f32_16x16x32_f16 v[114:117], v[118:121], v[106:109], v[114:117]
	v_mfma_f32_16x16x32_f16 v[40:43], v[118:121], v[110:113], v[40:43]
	v_mfma_f32_16x16x32_f16 v[70:73], v[122:125], v[106:109], v[70:73]
	global_load_dwordx4 v[106:109], v[2:3], off offset:3072
	global_load_dwordx4 v[126:129], v[4:5], off offset:3072
	global_load_dwordx4 v[134:137], v[14:15], off offset:3072
	global_load_dwordx4 v[94:97], v[10:11], off offset:3072
	global_load_dwordx4 v[162:165], v[12:13], off offset:3072
	global_load_dwordx4 v[166:169], v[8:9], off offset:3072
	global_load_dwordx4 v[190:193], v[6:7], off offset:3072
	s_waitcnt lgkmcnt(0)
	s_barrier
	v_mfma_f32_16x16x32_f16 v[48:51], v[122:125], v[110:113], v[48:51]
	ds_read_b128 v[62:65], v16 offset:49152
	ds_read_b128 v[90:93], v21 offset:16384
	s_waitcnt lgkmcnt(0)
	v_mfma_f32_16x16x32_f16 v[36:39], v[62:65], v[90:93], v[36:39]
	ds_read_b128 v[74:77], v16 offset:51200
	ds_read_b128 v[110:113], v21 offset:18432
	s_waitcnt lgkmcnt(0)
	v_mfma_f32_16x16x32_f16 v[66:69], v[62:65], v[110:113], v[66:69]
	ds_read_b128 v[118:121], v16 offset:53248
	v_mfma_f32_16x16x32_f16 v[44:47], v[74:77], v[90:93], v[44:47]
	ds_read_b128 v[122:125], v16 offset:55296
	v_mfma_f32_16x16x32_f16 v[78:81], v[74:77], v[110:113], v[78:81]
	s_waitcnt lgkmcnt(1)
	v_mfma_f32_16x16x32_f16 v[82:85], v[118:121], v[90:93], v[82:85]
	v_mfma_f32_16x16x32_f16 v[86:89], v[118:121], v[110:113], v[86:89]
	s_waitcnt lgkmcnt(0)
	v_mfma_f32_16x16x32_f16 v[28:31], v[122:125], v[90:93], v[28:31]
	ds_read_b128 v[90:93], v21 offset:20480
	v_mfma_f32_16x16x32_f16 v[32:35], v[122:125], v[110:113], v[32:35]
	ds_read_b128 v[110:113], v21 offset:22528
	s_waitcnt lgkmcnt(1)
	v_mfma_f32_16x16x32_f16 v[98:101], v[62:65], v[90:93], v[98:101]
	s_waitcnt lgkmcnt(0)
	v_mfma_f32_16x16x32_f16 v[52:55], v[62:65], v[110:113], v[52:55]
	ds_read_b128 v[62:65], v22 offset:49152
	v_mfma_f32_16x16x32_f16 v[102:105], v[74:77], v[90:93], v[102:105]
	v_mfma_f32_16x16x32_f16 v[24:27], v[74:77], v[110:113], v[24:27]
	ds_read_b128 v[74:77], v22 offset:51200
	v_mfma_f32_16x16x32_f16 v[114:117], v[118:121], v[90:93], v[114:117]
	s_waitcnt vmcnt(7)
	ds_write_b128 v17, v[58:61]
	s_waitcnt vmcnt(6)
; #define GL_LOAD(s_, kt_) if (VAR != 1) { a##s_##0 = GL_A(0, kt_); a##s_##1 = GL_A(1, kt_); a##s_##2 = GL_A(2, kt_); a##s_##3 = GL_A(3, kt_); b##s_##0 = GL_B(0, kt_); b##s_##1 = GL_B(1, kt_); b##s_##2 = GL_B(2, kt_); b##s_##3 = GL_B(3, kt_); }
; #define LDS_STORE(s_, buf_) if (VAR != 2) { LDS_ST1(sA, 0, buf_, a##s_##0) LDS_ST1(sA, 1, buf_, a##s_##1) LDS_ST1(sA, 2, buf_, a##s_##2) LDS_ST1(sA, 3, buf_, a##s_##3) LDS_ST1(sB, 0, buf_, b##s_##0) LDS_ST1(sB, 1, buf_, b##s_##1) LDS_ST1(sB, 2, buf_, b##s_##2) LDS_ST1(sB, 3, buf_, b##s_##3) }
;     ...
;   for (int kt = 0; kt < nk; kt += 2) {
;     if (kt + 2 < nk) { GL_LOAD(0, kt + 2) }
;     MMA_TILE(0)
;     LDS_STORE(1, 1)
;     if (VAR != 4) __syncthreads();
;     if (kt + 3 < nk) { GL_LOAD(1, kt + 3) }
;     MMA_TILE(1)
;     if (kt + 2 < nk) { LDS_STORE(0, 0) }
;     if (VAR != 4) __syncthreads();
	ds_write_b128 v18, v[106:109]
	v_mfma_f32_16x16x32_f16 v[40:43], v[118:121], v[110:113], v[40:43]
	ds_read_b128 v[118:121], v22 offset:53248
	s_waitcnt vmcnt(5)
	ds_write_b128 v19, v[126:129]
	v_mfma_f32_16x16x32_f16 v[70:73], v[122:125], v[90:93], v[70:73]
	ds_read_b128 v[90:93], v23 offset:16384
	v_mfma_f32_16x16x32_f16 v[48:51], v[122:125], v[110:113], v[48:51]
	ds_read_b128 v[110:113], v23 offset:18432
	s_waitcnt lgkmcnt(1)
	v_mfma_f32_16x16x32_f16 v[36:39], v[62:65], v[90:93], v[36:39]
	ds_read_b128 v[122:125], v22 offset:55296
	s_waitcnt lgkmcnt(1)
	v_mfma_f32_16x16x32_f16 v[66:69], v[62:65], v[110:113], v[66:69]
	s_waitcnt vmcnt(4)
	ds_write_b128 v20, v[134:137]
	v_mfma_f32_16x16x32_f16 v[44:47], v[74:77], v[90:93], v[44:47]
	s_waitcnt vmcnt(3)
	ds_write_b128 v17, v[94:97] offset:32768
	v_mfma_f32_16x16x32_f16 v[78:81], v[74:77], v[110:113], v[78:81]
	s_waitcnt vmcnt(2)
	ds_write_b128 v18, v[162:165] offset:32768
	v_mfma_f32_16x16x32_f16 v[82:85], v[118:121], v[90:93], v[82:85]
	s_waitcnt vmcnt(1)
	ds_write_b128 v19, v[166:169] offset:32768
	v_mfma_f32_16x16x32_f16 v[86:89], v[118:121], v[110:113], v[86:89]
	s_waitcnt vmcnt(0)
	ds_write_b128 v20, v[190:193] offset:32768
	s_waitcnt lgkmcnt(5)
	v_mfma_f32_16x16x32_f16 v[28:31], v[122:125], v[90:93], v[28:31]
	ds_read_b128 v[90:93], v23 offset:20480
	v_mfma_f32_16x16x32_f16 v[32:35], v[122:125], v[110:113], v[32:35]
	ds_read_b128 v[110:113], v23 offset:22528
	s_waitcnt lgkmcnt(1)
	v_mfma_f32_16x16x32_f16 v[98:101], v[62:65], v[90:93], v[98:101]
	s_waitcnt lgkmcnt(0)
	v_mfma_f32_16x16x32_f16 v[52:55], v[62:65], v[110:113], v[52:55]
	global_load_dwordx4 v[62:65], v[0:1], off offset:3200
	v_mfma_f32_16x16x32_f16 v[102:105], v[74:77], v[90:93], v[102:105]
	v_mfma_f32_16x16x32_f16 v[24:27], v[74:77], v[110:113], v[24:27]
	v_mfma_f32_16x16x32_f16 v[114:117], v[118:121], v[90:93], v[114:117]
	v_mfma_f32_16x16x32_f16 v[40:43], v[118:121], v[110:113], v[40:43]
	v_mfma_f32_16x16x32_f16 v[70:73], v[122:125], v[90:93], v[70:73]
	global_load_dwordx4 v[90:93], v[2:3], off offset:3200
	global_load_dwordx4 v[130:133], v[4:5], off offset:3200
	global_load_dwordx4 v[138:141], v[14:15], off offset:3200
	global_load_dwordx4 v[74:77], v[10:11], off offset:3200
	global_load_dwordx4 v[142:145], v[12:13], off offset:3200
	global_load_dwordx4 v[154:157], v[8:9], off offset:3200
	global_load_dwordx4 v[158:161], v[6:7], off offset:3200
	s_waitcnt lgkmcnt(0)
	s_barrier
	v_mfma_f32_16x16x32_f16 v[48:51], v[122:125], v[110:113], v[48:51]
	ds_read_b128 v[58:61], v16 offset:32768
	ds_read_b128 v[106:109], v21
	s_waitcnt lgkmcnt(0)
	v_mfma_f32_16x16x32_f16 v[36:39], v[58:61], v[106:109], v[36:39]
	ds_read_b128 v[94:97], v16 offset:34816
	ds_read_b128 v[110:113], v21 offset:2048
	s_waitcnt lgkmcnt(0)
	v_mfma_f32_16x16x32_f16 v[66:69], v[58:61], v[110:113], v[66:69]
	ds_read_b128 v[118:121], v16 offset:36864
	v_mfma_f32_16x16x32_f16 v[44:47], v[94:97], v[106:109], v[44:47]
	ds_read_b128 v[122:125], v16 offset:38912
	v_mfma_f32_16x16x32_f16 v[78:81], v[94:97], v[110:113], v[78:81]
	s_waitcnt lgkmcnt(1)
	v_mfma_f32_16x16x32_f16 v[82:85], v[118:121], v[106:109], v[82:85]
	v_mfma_f32_16x16x32_f16 v[86:89], v[118:121], v[110:113], v[86:89]
	s_waitcnt lgkmcnt(0)
	v_mfma_f32_16x16x32_f16 v[28:31], v[122:125], v[106:109], v[28:31]
	ds_read_b128 v[106:109], v21 offset:4096
	v_mfma_f32_16x16x32_f16 v[32:35], v[122:125], v[110:113], v[32:35]
	ds_read_b128 v[110:113], v21 offset:6144
	s_waitcnt lgkmcnt(1)
	v_mfma_f32_16x16x32_f16 v[98:101], v[58:61], v[106:109], v[98:101]
	s_waitcnt lgkmcnt(0)
	v_mfma_f32_16x16x32_f16 v[52:55], v[58:61], v[110:113], v[52:55]
	ds_read_b128 v[58:61], v22 offset:32768
	v_mfma_f32_16x16x32_f16 v[102:105], v[94:97], v[106:109], v[102:105]
	v_mfma_f32_16x16x32_f16 v[24:27], v[94:97], v[110:113], v[24:27]
	ds_read_b128 v[94:97], v22 offset:34816
	v_mfma_f32_16x16x32_f16 v[114:117], v[118:121], v[106:109], v[114:117]
	s_waitcnt vmcnt(7)
	ds_write_b128 v17, v[62:65] offset:16384
	s_waitcnt vmcnt(6)
	ds_write_b128 v18, v[90:93] offset:16384
	v_mfma_f32_16x16x32_f16 v[40:43], v[118:121], v[110:113], v[40:43]
	ds_read_b128 v[118:121], v22 offset:36864
	s_waitcnt vmcnt(5)
	ds_write_b128 v19, v[130:133] offset:16384
	v_mfma_f32_16x16x32_f16 v[70:73], v[122:125], v[106:109], v[70:73]
	ds_read_b128 v[106:109], v23
	v_mfma_f32_16x16x32_f16 v[48:51], v[122:125], v[110:113], v[48:51]
	ds_read_b128 v[110:113], v23 offset:2048
	s_waitcnt lgkmcnt(1)
	v_mfma_f32_16x16x32_f16 v[36:39], v[58:61], v[106:109], v[36:39]
	ds_read_b128 v[122:125], v22 offset:38912
	s_waitcnt lgkmcnt(1)
	v_mfma_f32_16x16x32_f16 v[66:69], v[58:61], v[110:113], v[66:69]
	s_waitcnt vmcnt(4)
	ds_write_b128 v20, v[138:141] offset:16384
	v_mfma_f32_16x16x32_f16 v[44:47], v[94:97], v[106:109], v[44:47]
	s_waitcnt vmcnt(3)
	ds_write_b128 v17, v[74:77] offset:49152
	v_mfma_f32_16x16x32_f16 v[78:81], v[94:97], v[110:113], v[78:81]
	s_waitcnt vmcnt(2)
	ds_write_b128 v18, v[142:145] offset:49152
	v_mfma_f32_16x16x32_f16 v[82:85], v[118:121], v[106:109], v[82:85]
	s_waitcnt vmcnt(1)
	ds_write_b128 v19, v[154:157] offset:49152
	v_mfma_f32_16x16x32_f16 v[86:89], v[118:121], v[110:113], v[86:89]
	s_waitcnt vmcnt(0)
	ds_write_b128 v20, v[158:161] offset:49152
	s_waitcnt lgkmcnt(5)
	v_mfma_f32_16x16x32_f16 v[28:31], v[122:125], v[106:109], v[28:31]
	ds_read_b128 v[106:109], v23 offset:4096
	v_mfma_f32_16x16x32_f16 v[32:35], v[122:125], v[110:113], v[32:35]
	ds_read_b128 v[110:113], v23 offset:6144
	s_waitcnt lgkmcnt(1)
	v_mfma_f32_16x16x32_f16 v[98:101], v[58:61], v[106:109], v[98:101]
	s_waitcnt lgkmcnt(0)
	v_mfma_f32_16x16x32_f16 v[52:55], v[58:61], v[110:113], v[52:55]
	global_load_dwordx4 v[58:61], v[0:1], off offset:3328
	v_mfma_f32_16x16x32_f16 v[102:105], v[94:97], v[106:109], v[102:105]
	v_mfma_f32_16x16x32_f16 v[24:27], v[94:97], v[110:113], v[24:27]
	v_mfma_f32_16x16x32_f16 v[114:117], v[118:121], v[106:109], v[114:117]
	v_mfma_f32_16x16x32_f16 v[40:43], v[118:121], v[110:113], v[40:43]
	v_mfma_f32_16x16x32_f16 v[70:73], v[122:125], v[106:109], v[70:73]
	global_load_dwordx4 v[106:109], v[2:3], off offset:3328
	global_load_dwordx4 v[126:129], v[4:5], off offset:3328
	global_load_dwordx4 v[134:137], v[14:15], off offset:3328
	global_load_dwordx4 v[94:97], v[10:11], off offset:3328
	global_load_dwordx4 v[162:165], v[12:13], off offset:3328
	global_load_dwordx4 v[166:169], v[8:9], off offset:3328
	global_load_dwordx4 v[190:193], v[6:7], off offset:3328
	s_waitcnt lgkmcnt(0)
	s_barrier
; #define GL_LOAD(s_, kt_) if (VAR != 1) { a##s_##0 = GL_A(0, kt_); a##s_##1 = GL_A(1, kt_); a##s_##2 = GL_A(2, kt_); a##s_##3 = GL_A(3, kt_); b##s_##0 = GL_B(0, kt_); b##s_##1 = GL_B(1, kt_); b##s_##2 = GL_B(2, kt_); b##s_##3 = GL_B(3, kt_); }
; #define LDS_STORE(s_, buf_) if (VAR != 2) { LDS_ST1(sA, 0, buf_, a##s_##0) LDS_ST1(sA, 1, buf_, a##s_##1) LDS_ST1(sA, 2, buf_, a##s_##2) LDS_ST1(sA, 3, buf_, a##s_##3) LDS_ST1(sB, 0, buf_, b##s_##0) LDS_ST1(sB, 1, buf_, b##s_##1) LDS_ST1(sB, 2, buf_, b##s_##2) LDS_ST1(sB, 3, buf_, b##s_##3) }
;     ...
;   for (int kt = 0; kt < nk; kt += 2) {
;     if (kt + 2 < nk) { GL_LOAD(0, kt + 2) }
;     MMA_TILE(0)
;     LDS_STORE(1, 1)
;     if (VAR != 4) __syncthreads();
;     if (kt + 3 < nk) { GL_LOAD(1, kt + 3) }
;     MMA_TILE(1)
;     if (kt + 2 < nk) { LDS_STORE(0, 0) }
;     if (VAR != 4) __syncthreads();
	v_mfma_f32_16x16x32_f16 v[48:51], v[122:125], v[110:113], v[48:51]
	ds_read_b128 v[62:65], v16 offset:49152
	ds_read_b128 v[90:93], v21 offset:16384
	s_waitcnt lgkmcnt(0)
	v_mfma_f32_16x16x32_f16 v[36:39], v[62:65], v[90:93], v[36:39]
	ds_read_b128 v[74:77], v16 offset:51200
	ds_read_b128 v[110:113], v21 offset:18432
	s_waitcnt lgkmcnt(0)
	v_mfma_f32_16x16x32_f16 v[66:69], v[62:65], v[110:113], v[66:69]
	ds_read_b128 v[118:121], v16 offset:53248
	v_mfma_f32_16x16x32_f16 v[44:47], v[74:77], v[90:93], v[44:47]
	ds_read_b128 v[122:125], v16 offset:55296
	v_mfma_f32_16x16x32_f16 v[78:81], v[74:77], v[110:113], v[78:81]
	s_waitcnt lgkmcnt(1)
	v_mfma_f32_16x16x32_f16 v[82:85], v[118:121], v[90:93], v[82:85]
	v_mfma_f32_16x16x32_f16 v[86:89], v[118:121], v[110:113], v[86:89]
	s_waitcnt lgkmcnt(0)
	v_mfma_f32_16x16x32_f16 v[28:31], v[122:125], v[90:93], v[28:31]
	ds_read_b128 v[90:93], v21 offset:20480
	v_mfma_f32_16x16x32_f16 v[32:35], v[122:125], v[110:113], v[32:35]
	ds_read_b128 v[110:113], v21 offset:22528
	s_waitcnt lgkmcnt(1)
	v_mfma_f32_16x16x32_f16 v[98:101], v[62:65], v[90:93], v[98:101]
	s_waitcnt lgkmcnt(0)
	v_mfma_f32_16x16x32_f16 v[52:55], v[62:65], v[110:113], v[52:55]
	ds_read_b128 v[62:65], v22 offset:49152
	v_mfma_f32_16x16x32_f16 v[102:105], v[74:77], v[90:93], v[102:105]
	v_mfma_f32_16x16x32_f16 v[24:27], v[74:77], v[110:113], v[24:27]
	ds_read_b128 v[74:77], v22 offset:51200
	v_mfma_f32_16x16x32_f16 v[114:117], v[118:121], v[90:93], v[114:117]
	s_waitcnt vmcnt(7)
	ds_write_b128 v17, v[58:61]
	s_waitcnt vmcnt(6)
	ds_write_b128 v18, v[106:109]
	v_mfma_f32_16x16x32_f16 v[40:43], v[118:121], v[110:113], v[40:43]
	ds_read_b128 v[118:121], v22 offset:53248
	s_waitcnt vmcnt(5)
	ds_write_b128 v19, v[126:129]
	v_mfma_f32_16x16x32_f16 v[70:73], v[122:125], v[90:93], v[70:73]
	ds_read_b128 v[90:93], v23 offset:16384
	v_mfma_f32_16x16x32_f16 v[48:51], v[122:125], v[110:113], v[48:51]
	ds_read_b128 v[110:113], v23 offset:18432
	s_waitcnt lgkmcnt(1)
	v_mfma_f32_16x16x32_f16 v[36:39], v[62:65], v[90:93], v[36:39]
	ds_read_b128 v[122:125], v22 offset:55296
	s_waitcnt lgkmcnt(1)
	v_mfma_f32_16x16x32_f16 v[66:69], v[62:65], v[110:113], v[66:69]
	s_waitcnt vmcnt(4)
	ds_write_b128 v20, v[134:137]
	v_mfma_f32_16x16x32_f16 v[44:47], v[74:77], v[90:93], v[44:47]
	s_waitcnt vmcnt(3)
	ds_write_b128 v17, v[94:97] offset:32768
	v_mfma_f32_16x16x32_f16 v[78:81], v[74:77], v[110:113], v[78:81]
	s_waitcnt vmcnt(2)
	ds_write_b128 v18, v[162:165] offset:32768
	v_mfma_f32_16x16x32_f16 v[82:85], v[118:121], v[90:93], v[82:85]
	s_waitcnt vmcnt(1)
	ds_write_b128 v19, v[166:169] offset:32768
	v_mfma_f32_16x16x32_f16 v[86:89], v[118:121], v[110:113], v[86:89]
	s_waitcnt vmcnt(0)
	ds_write_b128 v20, v[190:193] offset:32768
	s_waitcnt lgkmcnt(5)
	v_mfma_f32_16x16x32_f16 v[28:31], v[122:125], v[90:93], v[28:31]
	ds_read_b128 v[90:93], v23 offset:20480
	v_mfma_f32_16x16x32_f16 v[32:35], v[122:125], v[110:113], v[32:35]
	ds_read_b128 v[110:113], v23 offset:22528
	s_waitcnt lgkmcnt(1)
	v_mfma_f32_16x16x32_f16 v[98:101], v[62:65], v[90:93], v[98:101]
	s_waitcnt lgkmcnt(0)
	v_mfma_f32_16x16x32_f16 v[52:55], v[62:65], v[110:113], v[52:55]
	global_load_dwordx4 v[62:65], v[0:1], off offset:3456
	v_mfma_f32_16x16x32_f16 v[102:105], v[74:77], v[90:93], v[102:105]
	v_mfma_f32_16x16x32_f16 v[24:27], v[74:77], v[110:113], v[24:27]
	v_mfma_f32_16x16x32_f16 v[114:117], v[118:121], v[90:93], v[114:117]
	v_mfma_f32_16x16x32_f16 v[40:43], v[118:121], v[110:113], v[40:43]
	v_mfma_f32_16x16x32_f16 v[70:73], v[122:125], v[90:93], v[70:73]
	global_load_dwordx4 v[90:93], v[2:3], off offset:3456
	global_load_dwordx4 v[130:133], v[4:5], off offset:3456
	global_load_dwordx4 v[138:141], v[14:15], off offset:3456
	global_load_dwordx4 v[74:77], v[10:11], off offset:3456
	global_load_dwordx4 v[142:145], v[12:13], off offset:3456
	global_load_dwordx4 v[154:157], v[8:9], off offset:3456
	global_load_dwordx4 v[158:161], v[6:7], off offset:3456
	s_waitcnt lgkmcnt(0)
	s_barrier
	v_mfma_f32_16x16x32_f16 v[48:51], v[122:125], v[110:113], v[48:51]
	ds_read_b128 v[58:61], v16 offset:32768
	ds_read_b128 v[106:109], v21
	s_waitcnt lgkmcnt(0)
	v_mfma_f32_16x16x32_f16 v[36:39], v[58:61], v[106:109], v[36:39]
	ds_read_b128 v[94:97], v16 offset:34816
	ds_read_b128 v[110:113], v21 offset:2048
	s_waitcnt lgkmcnt(0)
	v_mfma_f32_16x16x32_f16 v[66:69], v[58:61], v[110:113], v[66:69]
	ds_read_b128 v[118:121], v16 offset:36864
	v_mfma_f32_16x16x32_f16 v[44:47], v[94:97], v[106:109], v[44:47]
	ds_read_b128 v[122:125], v16 offset:38912
	v_mfma_f32_16x16x32_f16 v[78:81], v[94:97], v[110:113], v[78:81]
	s_waitcnt lgkmcnt(1)
	v_mfma_f32_16x16x32_f16 v[82:85], v[118:121], v[106:109], v[82:85]
	v_mfma_f32_16x16x32_f16 v[86:89], v[118:121], v[110:113], v[86:89]
	s_waitcnt lgkmcnt(0)
	v_mfma_f32_16x16x32_f16 v[28:31], v[122:125], v[106:109], v[28:31]
	ds_read_b128 v[106:109], v21 offset:4096
	v_mfma_f32_16x16x32_f16 v[32:35], v[122:125], v[110:113], v[32:35]
	ds_read_b128 v[110:113], v21 offset:6144
	s_waitcnt lgkmcnt(1)
	v_mfma_f32_16x16x32_f16 v[98:101], v[58:61], v[106:109], v[98:101]
	s_waitcnt lgkmcnt(0)
	v_mfma_f32_16x16x32_f16 v[52:55], v[58:61], v[110:113], v[52:55]
	ds_read_b128 v[58:61], v22 offset:32768
	v_mfma_f32_16x16x32_f16 v[102:105], v[94:97], v[106:109], v[102:105]
	v_mfma_f32_16x16x32_f16 v[24:27], v[94:97], v[110:113], v[24:27]
	ds_read_b128 v[94:97], v22 offset:34816
	v_mfma_f32_16x16x32_f16 v[114:117], v[118:121], v[106:109], v[114:117]
	s_waitcnt vmcnt(7)
	ds_write_b128 v17, v[62:65] offset:16384
	s_waitcnt vmcnt(6)
; #define GL_LOAD(s_, kt_) if (VAR != 1) { a##s_##0 = GL_A(0, kt_); a##s_##1 = GL_A(1, kt_); a##s_##2 = GL_A(2, kt_); a##s_##3 = GL_A(3, kt_); b##s_##0 = GL_B(0, kt_); b##s_##1 = GL_B(1, kt_); b##s_##2 = GL_B(2, kt_); b##s_##3 = GL_B(3, kt_); }
; #define LDS_STORE(s_, buf_) if (VAR != 2) { LDS_ST1(sA, 0, buf_, a##s_##0) LDS_ST1(sA, 1, buf_, a##s_##1) LDS_ST1(sA, 2, buf_, a##s_##2) LDS_ST1(sA, 3, buf_, a##s_##3) LDS_ST1(sB, 0, buf_, b##s_##0) LDS_ST1(sB, 1, buf_, b##s_##1) LDS_ST1(sB, 2, buf_, b##s_##2) LDS_ST1(sB, 3, buf_, b##s_##3) }
;     ...
;   for (int kt = 0; kt < nk; kt += 2) {
;     if (kt + 2 < nk) { GL_LOAD(0, kt + 2) }
;     MMA_TILE(0)
;     LDS_STORE(1, 1)
;     if (VAR != 4) __syncthreads();
;     if (kt + 3 < nk) { GL_LOAD(1, kt + 3) }
;     MMA_TILE(1)
;     if (kt + 2 < nk) { LDS_STORE(0, 0) }
;     if (VAR != 4) __syncthreads();
	ds_write_b128 v18, v[90:93] offset:16384
	v_mfma_f32_16x16x32_f16 v[40:43], v[118:121], v[110:113], v[40:43]
	ds_read_b128 v[118:121], v22 offset:36864
	s_waitcnt vmcnt(5)
	ds_write_b128 v19, v[130:133] offset:16384
	v_mfma_f32_16x16x32_f16 v[70:73], v[122:125], v[106:109], v[70:73]
	ds_read_b128 v[106:109], v23
	v_mfma_f32_16x16x32_f16 v[48:51], v[122:125], v[110:113], v[48:51]
	ds_read_b128 v[110:113], v23 offset:2048
	s_waitcnt lgkmcnt(1)
	v_mfma_f32_16x16x32_f16 v[36:39], v[58:61], v[106:109], v[36:39]
	ds_read_b128 v[122:125], v22 offset:38912
	s_waitcnt lgkmcnt(1)
	v_mfma_f32_16x16x32_f16 v[66:69], v[58:61], v[110:113], v[66:69]
	s_waitcnt vmcnt(4)
	ds_write_b128 v20, v[138:141] offset:16384
	v_mfma_f32_16x16x32_f16 v[44:47], v[94:97], v[106:109], v[44:47]
	s_waitcnt vmcnt(3)
	ds_write_b128 v17, v[74:77] offset:49152
	v_mfma_f32_16x16x32_f16 v[78:81], v[94:97], v[110:113], v[78:81]
	s_waitcnt vmcnt(2)
	ds_write_b128 v18, v[142:145] offset:49152
	v_mfma_f32_16x16x32_f16 v[82:85], v[118:121], v[106:109], v[82:85]
	s_waitcnt vmcnt(1)
	ds_write_b128 v19, v[154:157] offset:49152
	v_mfma_f32_16x16x32_f16 v[86:89], v[118:121], v[110:113], v[86:89]
	s_waitcnt vmcnt(0)
	ds_write_b128 v20, v[158:161] offset:49152
	s_waitcnt lgkmcnt(5)
	v_mfma_f32_16x16x32_f16 v[28:31], v[122:125], v[106:109], v[28:31]
	ds_read_b128 v[106:109], v23 offset:4096
	v_mfma_f32_16x16x32_f16 v[32:35], v[122:125], v[110:113], v[32:35]
	ds_read_b128 v[110:113], v23 offset:6144
	s_waitcnt lgkmcnt(1)
	v_mfma_f32_16x16x32_f16 v[98:101], v[58:61], v[106:109], v[98:101]
	s_waitcnt lgkmcnt(0)
	v_mfma_f32_16x16x32_f16 v[52:55], v[58:61], v[110:113], v[52:55]
	global_load_dwordx4 v[58:61], v[0:1], off offset:3584
	v_mfma_f32_16x16x32_f16 v[102:105], v[94:97], v[106:109], v[102:105]
	v_mfma_f32_16x16x32_f16 v[24:27], v[94:97], v[110:113], v[24:27]
	v_mfma_f32_16x16x32_f16 v[114:117], v[118:121], v[106:109], v[114:117]
	v_mfma_f32_16x16x32_f16 v[40:43], v[118:121], v[110:113], v[40:43]
	v_mfma_f32_16x16x32_f16 v[70:73], v[122:125], v[106:109], v[70:73]
	global_load_dwordx4 v[106:109], v[2:3], off offset:3584
	global_load_dwordx4 v[126:129], v[4:5], off offset:3584
	global_load_dwordx4 v[134:137], v[14:15], off offset:3584
	global_load_dwordx4 v[94:97], v[10:11], off offset:3584
	global_load_dwordx4 v[162:165], v[12:13], off offset:3584
	global_load_dwordx4 v[166:169], v[8:9], off offset:3584
	global_load_dwordx4 v[190:193], v[6:7], off offset:3584
	s_waitcnt lgkmcnt(0)
	s_barrier
	v_mfma_f32_16x16x32_f16 v[48:51], v[122:125], v[110:113], v[48:51]
	ds_read_b128 v[62:65], v16 offset:49152
	ds_read_b128 v[90:93], v21 offset:16384
	s_waitcnt lgkmcnt(0)
	v_mfma_f32_16x16x32_f16 v[36:39], v[62:65], v[90:93], v[36:39]
	ds_read_b128 v[74:77], v16 offset:51200
	ds_read_b128 v[110:113], v21 offset:18432
	s_waitcnt lgkmcnt(0)
	v_mfma_f32_16x16x32_f16 v[66:69], v[62:65], v[110:113], v[66:69]
	ds_read_b128 v[118:121], v16 offset:53248
	v_mfma_f32_16x16x32_f16 v[44:47], v[74:77], v[90:93], v[44:47]
	ds_read_b128 v[122:125], v16 offset:55296
	v_mfma_f32_16x16x32_f16 v[78:81], v[74:77], v[110:113], v[78:81]
	s_waitcnt lgkmcnt(1)
	v_mfma_f32_16x16x32_f16 v[82:85], v[118:121], v[90:93], v[82:85]
	v_mfma_f32_16x16x32_f16 v[86:89], v[118:121], v[110:113], v[86:89]
	s_waitcnt lgkmcnt(0)
	v_mfma_f32_16x16x32_f16 v[28:31], v[122:125], v[90:93], v[28:31]
	ds_read_b128 v[90:93], v21 offset:20480
	v_mfma_f32_16x16x32_f16 v[32:35], v[122:125], v[110:113], v[32:35]
	ds_read_b128 v[110:113], v21 offset:22528
	s_waitcnt lgkmcnt(1)
	v_mfma_f32_16x16x32_f16 v[98:101], v[62:65], v[90:93], v[98:101]
	s_waitcnt lgkmcnt(0)
	v_mfma_f32_16x16x32_f16 v[52:55], v[62:65], v[110:113], v[52:55]
	ds_read_b128 v[62:65], v22 offset:49152
	v_mfma_f32_16x16x32_f16 v[102:105], v[74:77], v[90:93], v[102:105]
	v_mfma_f32_16x16x32_f16 v[24:27], v[74:77], v[110:113], v[24:27]
	ds_read_b128 v[74:77], v22 offset:51200
	v_mfma_f32_16x16x32_f16 v[114:117], v[118:121], v[90:93], v[114:117]
	s_waitcnt vmcnt(7)
	ds_write_b128 v17, v[58:61]
	s_waitcnt vmcnt(6)
	ds_write_b128 v18, v[106:109]
	v_mfma_f32_16x16x32_f16 v[40:43], v[118:121], v[110:113], v[40:43]
	ds_read_b128 v[118:121], v22 offset:53248
	s_waitcnt vmcnt(5)
	ds_write_b128 v19, v[126:129]
	v_mfma_f32_16x16x32_f16 v[70:73], v[122:125], v[90:93], v[70:73]
	ds_read_b128 v[90:93], v23 offset:16384
	v_mfma_f32_16x16x32_f16 v[48:51], v[122:125], v[110:113], v[48:51]
	ds_read_b128 v[110:113], v23 offset:18432
	s_waitcnt lgkmcnt(1)
	v_mfma_f32_16x16x32_f16 v[36:39], v[62:65], v[90:93], v[36:39]
	ds_read_b128 v[122:125], v22 offset:55296
	s_waitcnt lgkmcnt(1)
	v_mfma_f32_16x16x32_f16 v[66:69], v[62:65], v[110:113], v[66:69]
	s_waitcnt vmcnt(4)
	ds_write_b128 v20, v[134:137]
	v_mfma_f32_16x16x32_f16 v[44:47], v[74:77], v[90:93], v[44:47]
	s_waitcnt vmcnt(3)
	ds_write_b128 v17, v[94:97] offset:32768
	v_mfma_f32_16x16x32_f16 v[78:81], v[74:77], v[110:113], v[78:81]
	s_waitcnt vmcnt(2)
	ds_write_b128 v18, v[162:165] offset:32768
	v_mfma_f32_16x16x32_f16 v[82:85], v[118:121], v[90:93], v[82:85]
	s_waitcnt vmcnt(1)
	ds_write_b128 v19, v[166:169] offset:32768
	v_mfma_f32_16x16x32_f16 v[86:89], v[118:121], v[110:113], v[86:89]
	s_waitcnt vmcnt(0)
	ds_write_b128 v20, v[190:193] offset:32768
	s_waitcnt lgkmcnt(5)
	v_mfma_f32_16x16x32_f16 v[28:31], v[122:125], v[90:93], v[28:31]
	ds_read_b128 v[90:93], v23 offset:20480
	v_mfma_f32_16x16x32_f16 v[32:35], v[122:125], v[110:113], v[32:35]
	ds_read_b128 v[110:113], v23 offset:22528
	s_waitcnt lgkmcnt(1)
	v_mfma_f32_16x16x32_f16 v[98:101], v[62:65], v[90:93], v[98:101]
	s_waitcnt lgkmcnt(0)
	v_mfma_f32_16x16x32_f16 v[52:55], v[62:65], v[110:113], v[52:55]
	global_load_dwordx4 v[62:65], v[0:1], off offset:3712
	v_mfma_f32_16x16x32_f16 v[102:105], v[74:77], v[90:93], v[102:105]
	v_mfma_f32_16x16x32_f16 v[24:27], v[74:77], v[110:113], v[24:27]
	v_mfma_f32_16x16x32_f16 v[114:117], v[118:121], v[90:93], v[114:117]
	v_mfma_f32_16x16x32_f16 v[40:43], v[118:121], v[110:113], v[40:43]
	v_mfma_f32_16x16x32_f16 v[70:73], v[122:125], v[90:93], v[70:73]
	global_load_dwordx4 v[90:93], v[2:3], off offset:3712
	global_load_dwordx4 v[130:133], v[4:5], off offset:3712
	global_load_dwordx4 v[138:141], v[14:15], off offset:3712
	global_load_dwordx4 v[74:77], v[10:11], off offset:3712
	global_load_dwordx4 v[142:145], v[12:13], off offset:3712
	global_load_dwordx4 v[154:157], v[8:9], off offset:3712
	global_load_dwordx4 v[158:161], v[6:7], off offset:3712
	s_waitcnt lgkmcnt(0)
	s_barrier
; #define GL_LOAD(s_, kt_) if (VAR != 1) { a##s_##0 = GL_A(0, kt_); a##s_##1 = GL_A(1, kt_); a##s_##2 = GL_A(2, kt_); a##s_##3 = GL_A(3, kt_); b##s_##0 = GL_B(0, kt_); b##s_##1 = GL_B(1, kt_); b##s_##2 = GL_B(2, kt_); b##s_##3 = GL_B(3, kt_); }
; #define LDS_STORE(s_, buf_) if (VAR != 2) { LDS_ST1(sA, 0, buf_, a##s_##0) LDS_ST1(sA, 1, buf_, a##s_##1) LDS_ST1(sA, 2, buf_, a##s_##2) LDS_ST1(sA, 3, buf_, a##s_##3) LDS_ST1(sB, 0, buf_, b##s_##0) LDS_ST1(sB, 1, buf_, b##s_##1) LDS_ST1(sB, 2, buf_, b##s_##2) LDS_ST1(sB, 3, buf_, b##s_##3) }
;     ...
;   for (int kt = 0; kt < nk; kt += 2) {
;     if (kt + 2 < nk) { GL_LOAD(0, kt + 2) }
;     MMA_TILE(0)
;     LDS_STORE(1, 1)
;     if (VAR != 4) __syncthreads();
;     if (kt + 3 < nk) { GL_LOAD(1, kt + 3) }
;     MMA_TILE(1)
;     if (kt + 2 < nk) { LDS_STORE(0, 0) }
;     if (VAR != 4) __syncthreads();
	v_mfma_f32_16x16x32_f16 v[48:51], v[122:125], v[110:113], v[48:51]
	ds_read_b128 v[58:61], v16 offset:32768
	ds_read_b128 v[106:109], v21
	s_waitcnt lgkmcnt(0)
	v_mfma_f32_16x16x32_f16 v[36:39], v[58:61], v[106:109], v[36:39]
	ds_read_b128 v[94:97], v16 offset:34816
	ds_read_b128 v[110:113], v21 offset:2048
	s_waitcnt lgkmcnt(0)
	v_mfma_f32_16x16x32_f16 v[66:69], v[58:61], v[110:113], v[66:69]
	ds_read_b128 v[118:121], v16 offset:36864
	v_mfma_f32_16x16x32_f16 v[44:47], v[94:97], v[106:109], v[44:47]
	ds_read_b128 v[122:125], v16 offset:38912
	v_mfma_f32_16x16x32_f16 v[78:81], v[94:97], v[110:113], v[78:81]
	s_waitcnt lgkmcnt(1)
	v_mfma_f32_16x16x32_f16 v[82:85], v[118:121], v[106:109], v[82:85]
	v_mfma_f32_16x16x32_f16 v[86:89], v[118:121], v[110:113], v[86:89]
	s_waitcnt lgkmcnt(0)
	v_mfma_f32_16x16x32_f16 v[28:31], v[122:125], v[106:109], v[28:31]
	ds_read_b128 v[106:109], v21 offset:4096
	v_mfma_f32_16x16x32_f16 v[32:35], v[122:125], v[110:113], v[32:35]
	ds_read_b128 v[110:113], v21 offset:6144
	s_waitcnt lgkmcnt(1)
	v_mfma_f32_16x16x32_f16 v[98:101], v[58:61], v[106:109], v[98:101]
	s_waitcnt lgkmcnt(0)
	v_mfma_f32_16x16x32_f16 v[52:55], v[58:61], v[110:113], v[52:55]
	ds_read_b128 v[58:61], v22 offset:32768
	v_mfma_f32_16x16x32_f16 v[102:105], v[94:97], v[106:109], v[102:105]
	v_mfma_f32_16x16x32_f16 v[24:27], v[94:97], v[110:113], v[24:27]
	ds_read_b128 v[94:97], v22 offset:34816
	v_mfma_f32_16x16x32_f16 v[114:117], v[118:121], v[106:109], v[114:117]
	s_waitcnt vmcnt(7)
	ds_write_b128 v17, v[62:65] offset:16384
	s_waitcnt vmcnt(6)
	ds_write_b128 v18, v[90:93] offset:16384
	v_mfma_f32_16x16x32_f16 v[40:43], v[118:121], v[110:113], v[40:43]
	ds_read_b128 v[118:121], v22 offset:36864
	s_waitcnt vmcnt(5)
	ds_write_b128 v19, v[130:133] offset:16384
	v_mfma_f32_16x16x32_f16 v[70:73], v[122:125], v[106:109], v[70:73]
	ds_read_b128 v[106:109], v23
	v_mfma_f32_16x16x32_f16 v[48:51], v[122:125], v[110:113], v[48:51]
	ds_read_b128 v[110:113], v23 offset:2048
	s_waitcnt lgkmcnt(1)
	v_mfma_f32_16x16x32_f16 v[36:39], v[58:61], v[106:109], v[36:39]
	ds_read_b128 v[122:125], v22 offset:38912
	s_waitcnt lgkmcnt(1)
	v_mfma_f32_16x16x32_f16 v[66:69], v[58:61], v[110:113], v[66:69]
	s_waitcnt vmcnt(4)
	ds_write_b128 v20, v[138:141] offset:16384
	v_mfma_f32_16x16x32_f16 v[44:47], v[94:97], v[106:109], v[44:47]
	s_waitcnt vmcnt(3)
	ds_write_b128 v17, v[74:77] offset:49152
	v_mfma_f32_16x16x32_f16 v[78:81], v[94:97], v[110:113], v[78:81]
	s_waitcnt vmcnt(2)
	ds_write_b128 v18, v[142:145] offset:49152
	v_mfma_f32_16x16x32_f16 v[82:85], v[118:121], v[106:109], v[82:85]
	s_waitcnt vmcnt(1)
	ds_write_b128 v19, v[154:157] offset:49152
	v_mfma_f32_16x16x32_f16 v[86:89], v[118:121], v[110:113], v[86:89]
	s_waitcnt vmcnt(0)
	ds_write_b128 v20, v[158:161] offset:49152
	s_waitcnt lgkmcnt(5)
	v_mfma_f32_16x16x32_f16 v[28:31], v[122:125], v[106:109], v[28:31]
	ds_read_b128 v[106:109], v23 offset:4096
	v_mfma_f32_16x16x32_f16 v[32:35], v[122:125], v[110:113], v[32:35]
	ds_read_b128 v[110:113], v23 offset:6144
	s_waitcnt lgkmcnt(1)
	v_mfma_f32_16x16x32_f16 v[98:101], v[58:61], v[106:109], v[98:101]
	s_waitcnt lgkmcnt(0)
	v_mfma_f32_16x16x32_f16 v[52:55], v[58:61], v[110:113], v[52:55]
	global_load_dwordx4 v[58:61], v[0:1], off offset:3840
	v_mfma_f32_16x16x32_f16 v[102:105], v[94:97], v[106:109], v[102:105]
	v_mfma_f32_16x16x32_f16 v[24:27], v[94:97], v[110:113], v[24:27]
	v_mfma_f32_16x16x32_f16 v[114:117], v[118:121], v[106:109], v[114:117]
	v_mfma_f32_16x16x32_f16 v[40:43], v[118:121], v[110:113], v[40:43]
	v_mfma_f32_16x16x32_f16 v[70:73], v[122:125], v[106:109], v[70:73]
	global_load_dwordx4 v[106:109], v[2:3], off offset:3840
	global_load_dwordx4 v[126:129], v[4:5], off offset:3840
	global_load_dwordx4 v[134:137], v[14:15], off offset:3840
	global_load_dwordx4 v[94:97], v[10:11], off offset:3840
	global_load_dwordx4 v[162:165], v[12:13], off offset:3840
	global_load_dwordx4 v[166:169], v[8:9], off offset:3840
	global_load_dwordx4 v[190:193], v[6:7], off offset:3840
	s_waitcnt lgkmcnt(0)
	s_barrier
	v_mfma_f32_16x16x32_f16 v[48:51], v[122:125], v[110:113], v[48:51]
	ds_read_b128 v[62:65], v16 offset:49152
	ds_read_b128 v[90:93], v21 offset:16384
	s_waitcnt lgkmcnt(0)
	v_mfma_f32_16x16x32_f16 v[36:39], v[62:65], v[90:93], v[36:39]
	ds_read_b128 v[74:77], v16 offset:51200
	ds_read_b128 v[110:113], v21 offset:18432
	s_waitcnt lgkmcnt(0)
	v_mfma_f32_16x16x32_f16 v[66:69], v[62:65], v[110:113], v[66:69]
	ds_read_b128 v[118:121], v16 offset:53248
	v_mfma_f32_16x16x32_f16 v[44:47], v[74:77], v[90:93], v[44:47]
	ds_read_b128 v[122:125], v16 offset:55296
	v_mfma_f32_16x16x32_f16 v[78:81], v[74:77], v[110:113], v[78:81]
	s_waitcnt lgkmcnt(1)
	v_mfma_f32_16x16x32_f16 v[82:85], v[118:121], v[90:93], v[82:85]
	v_mfma_f32_16x16x32_f16 v[86:89], v[118:121], v[110:113], v[86:89]
	s_waitcnt lgkmcnt(0)
	v_mfma_f32_16x16x32_f16 v[28:31], v[122:125], v[90:93], v[28:31]
	ds_read_b128 v[90:93], v21 offset:20480
	v_mfma_f32_16x16x32_f16 v[32:35], v[122:125], v[110:113], v[32:35]
	ds_read_b128 v[110:113], v21 offset:22528
	s_waitcnt lgkmcnt(1)
	v_mfma_f32_16x16x32_f16 v[98:101], v[62:65], v[90:93], v[98:101]
	s_waitcnt lgkmcnt(0)
	v_mfma_f32_16x16x32_f16 v[52:55], v[62:65], v[110:113], v[52:55]
	ds_read_b128 v[62:65], v22 offset:49152
	v_mfma_f32_16x16x32_f16 v[102:105], v[74:77], v[90:93], v[102:105]
	v_mfma_f32_16x16x32_f16 v[24:27], v[74:77], v[110:113], v[24:27]
	ds_read_b128 v[74:77], v22 offset:51200
	v_mfma_f32_16x16x32_f16 v[114:117], v[118:121], v[90:93], v[114:117]
	s_waitcnt vmcnt(7)
	ds_write_b128 v17, v[58:61]
	s_waitcnt vmcnt(6)
; #define GL_LOAD(s_, kt_) if (VAR != 1) { a##s_##0 = GL_A(0, kt_); a##s_##1 = GL_A(1, kt_); a##s_##2 = GL_A(2, kt_); a##s_##3 = GL_A(3, kt_); b##s_##0 = GL_B(0, kt_); b##s_##1 = GL_B(1, kt_); b##s_##2 = GL_B(2, kt_); b##s_##3 = GL_B(3, kt_); }
; #define LDS_STORE(s_, buf_) if (VAR != 2) { LDS_ST1(sA, 0, buf_, a##s_##0) LDS_ST1(sA, 1, buf_, a##s_##1) LDS_ST1(sA, 2, buf_, a##s_##2) LDS_ST1(sA, 3, buf_, a##s_##3) LDS_ST1(sB, 0, buf_, b##s_##0) LDS_ST1(sB, 1, buf_, b##s_##1) LDS_ST1(sB, 2, buf_, b##s_##2) LDS_ST1(sB, 3, buf_, b##s_##3) }
;     ...
;   for (int kt = 0; kt < nk; kt += 2) {
;     if (kt + 2 < nk) { GL_LOAD(0, kt + 2) }
;     MMA_TILE(0)
;     LDS_STORE(1, 1)
;     if (VAR != 4) __syncthreads();
;     if (kt + 3 < nk) { GL_LOAD(1, kt + 3) }
;     MMA_TILE(1)
;     if (kt + 2 < nk) { LDS_STORE(0, 0) }
;     if (VAR != 4) __syncthreads();
	ds_write_b128 v18, v[106:109]
	v_mfma_f32_16x16x32_f16 v[40:43], v[118:121], v[110:113], v[40:43]
	ds_read_b128 v[118:121], v22 offset:53248
	s_waitcnt vmcnt(5)
	ds_write_b128 v19, v[126:129]
	v_mfma_f32_16x16x32_f16 v[70:73], v[122:125], v[90:93], v[70:73]
	ds_read_b128 v[90:93], v23 offset:16384
	v_mfma_f32_16x16x32_f16 v[48:51], v[122:125], v[110:113], v[48:51]
	ds_read_b128 v[110:113], v23 offset:18432
	s_waitcnt lgkmcnt(1)
	v_mfma_f32_16x16x32_f16 v[36:39], v[62:65], v[90:93], v[36:39]
	ds_read_b128 v[122:125], v22 offset:55296
	s_waitcnt lgkmcnt(1)
	v_mfma_f32_16x16x32_f16 v[66:69], v[62:65], v[110:113], v[66:69]
	s_waitcnt vmcnt(4)
	ds_write_b128 v20, v[134:137]
	v_mfma_f32_16x16x32_f16 v[44:47], v[74:77], v[90:93], v[44:47]
	s_waitcnt vmcnt(3)
	ds_write_b128 v17, v[94:97] offset:32768
	v_mfma_f32_16x16x32_f16 v[78:81], v[74:77], v[110:113], v[78:81]
	s_waitcnt vmcnt(2)
	ds_write_b128 v18, v[162:165] offset:32768
	v_mfma_f32_16x16x32_f16 v[82:85], v[118:121], v[90:93], v[82:85]
	s_waitcnt vmcnt(1)
	ds_write_b128 v19, v[166:169] offset:32768
	v_mfma_f32_16x16x32_f16 v[86:89], v[118:121], v[110:113], v[86:89]
	s_waitcnt vmcnt(0)
	ds_write_b128 v20, v[190:193] offset:32768
	s_waitcnt lgkmcnt(5)
	v_mfma_f32_16x16x32_f16 v[28:31], v[122:125], v[90:93], v[28:31]
	ds_read_b128 v[90:93], v23 offset:20480
	v_mfma_f32_16x16x32_f16 v[32:35], v[122:125], v[110:113], v[32:35]
	ds_read_b128 v[110:113], v23 offset:22528
	s_waitcnt lgkmcnt(1)
	v_mfma_f32_16x16x32_f16 v[98:101], v[62:65], v[90:93], v[98:101]
	s_waitcnt lgkmcnt(0)
	v_mfma_f32_16x16x32_f16 v[52:55], v[62:65], v[110:113], v[52:55]
	global_load_dwordx4 v[62:65], v[0:1], off offset:3968
	global_load_dwordx4 v[0:3], v[2:3], off offset:3968
	v_mfma_f32_16x16x32_f16 v[102:105], v[74:77], v[90:93], v[102:105]
	v_mfma_f32_16x16x32_f16 v[24:27], v[74:77], v[110:113], v[24:27]
	v_mfma_f32_16x16x32_f16 v[114:117], v[118:121], v[90:93], v[114:117]
	v_mfma_f32_16x16x32_f16 v[40:43], v[118:121], v[110:113], v[40:43]
	v_mfma_f32_16x16x32_f16 v[70:73], v[122:125], v[90:93], v[70:73]
	global_load_dwordx4 v[90:93], v[4:5], off offset:3968
	global_load_dwordx4 v[130:133], v[14:15], off offset:3968
	global_load_dwordx4 v[74:77], v[10:11], off offset:3968
	global_load_dwordx4 v[10:13], v[12:13], off offset:3968
	global_load_dwordx4 v[138:141], v[8:9], off offset:3968
	global_load_dwordx4 v[4:7], v[6:7], off offset:3968
	s_waitcnt lgkmcnt(0)
	s_barrier
	ds_read_b128 v[58:61], v16 offset:32768
	v_mfma_f32_16x16x32_f16 v[48:51], v[122:125], v[110:113], v[48:51]
	ds_read_b128 v[94:97], v16 offset:34816
	ds_read_b128 v[106:109], v21
	ds_read_b128 v[110:113], v21 offset:2048
	ds_read_b128 v[118:121], v16 offset:36864
	ds_read_b128 v[122:125], v16 offset:38912
	s_waitcnt lgkmcnt(3)
	v_mfma_f32_16x16x32_f16 v[36:39], v[58:61], v[106:109], v[36:39]
	v_mfma_f32_16x16x32_f16 v[44:47], v[94:97], v[106:109], v[44:47]
	s_waitcnt lgkmcnt(1)
	v_mfma_f32_16x16x32_f16 v[82:85], v[118:121], v[106:109], v[82:85]
	s_waitcnt lgkmcnt(0)
	v_mfma_f32_16x16x32_f16 v[28:31], v[122:125], v[106:109], v[28:31]
	v_mfma_f32_16x16x32_f16 v[66:69], v[58:61], v[110:113], v[66:69]
	v_mfma_f32_16x16x32_f16 v[78:81], v[94:97], v[110:113], v[78:81]
	v_mfma_f32_16x16x32_f16 v[86:89], v[118:121], v[110:113], v[86:89]
	v_mfma_f32_16x16x32_f16 v[32:35], v[122:125], v[110:113], v[32:35]
	ds_read_b128 v[106:109], v21 offset:4096
	ds_read_b128 v[110:113], v21 offset:6144
	s_waitcnt lgkmcnt(1)
	v_mfma_f32_16x16x32_f16 v[98:101], v[58:61], v[106:109], v[98:101]
	v_mfma_f32_16x16x32_f16 v[102:105], v[94:97], v[106:109], v[102:105]
	v_mfma_f32_16x16x32_f16 v[114:117], v[118:121], v[106:109], v[114:117]
	v_mfma_f32_16x16x32_f16 v[70:73], v[122:125], v[106:109], v[70:73]
	s_waitcnt lgkmcnt(0)
	v_mfma_f32_16x16x32_f16 v[52:55], v[58:61], v[110:113], v[52:55]
	ds_read_b128 v[58:61], v22 offset:32768
	v_mfma_f32_16x16x32_f16 v[24:27], v[94:97], v[110:113], v[24:27]
	v_mfma_f32_16x16x32_f16 v[40:43], v[118:121], v[110:113], v[40:43]
	v_mfma_f32_16x16x32_f16 v[48:51], v[122:125], v[110:113], v[48:51]
	ds_read_b128 v[94:97], v22 offset:34816
	ds_read_b128 v[106:109], v23
	ds_read_b128 v[110:113], v23 offset:2048
	ds_read_b128 v[118:121], v22 offset:36864
	ds_read_b128 v[122:125], v22 offset:38912
	s_waitcnt lgkmcnt(3)
	v_mfma_f32_16x16x32_f16 v[36:39], v[58:61], v[106:109], v[36:39]
	v_mfma_f32_16x16x32_f16 v[44:47], v[94:97], v[106:109], v[44:47]
	s_waitcnt lgkmcnt(1)
	v_mfma_f32_16x16x32_f16 v[82:85], v[118:121], v[106:109], v[82:85]
	s_waitcnt lgkmcnt(0)
	v_mfma_f32_16x16x32_f16 v[28:31], v[122:125], v[106:109], v[28:31]
	v_mfma_f32_16x16x32_f16 v[66:69], v[58:61], v[110:113], v[66:69]
	v_mfma_f32_16x16x32_f16 v[78:81], v[94:97], v[110:113], v[78:81]
	v_mfma_f32_16x16x32_f16 v[86:89], v[118:121], v[110:113], v[86:89]
	v_mfma_f32_16x16x32_f16 v[32:35], v[122:125], v[110:113], v[32:35]
	ds_read_b128 v[106:109], v23 offset:4096
	ds_read_b128 v[110:113], v23 offset:6144
	s_waitcnt vmcnt(7)
	ds_write_b128 v17, v[62:65] offset:16384
	s_waitcnt vmcnt(6)
	ds_write_b128 v18, v[0:3] offset:16384
	s_waitcnt vmcnt(5)
	ds_write_b128 v19, v[90:93] offset:16384
	s_waitcnt vmcnt(4)
	ds_write_b128 v20, v[130:133] offset:16384
	s_waitcnt lgkmcnt(5)
	v_mfma_f32_16x16x32_f16 v[98:101], v[58:61], v[106:109], v[98:101]
	s_waitcnt vmcnt(3)
	ds_write_b128 v17, v[74:77] offset:49152
	s_waitcnt vmcnt(2)
	ds_write_b128 v18, v[10:13] offset:49152
	s_waitcnt vmcnt(1)
	ds_write_b128 v19, v[138:141] offset:49152
	s_waitcnt vmcnt(0)
	ds_write_b128 v20, v[4:7] offset:49152
	s_waitcnt lgkmcnt(0)
	s_barrier
; DI int TIDX() { int t = threadIdx.x; asm volatile("" : "+v"(t)); return t; }
; DI unsigned pack2(float lo, float hi) { f2_t v = {lo, hi}; h2_t b = __builtin_convertvector(v, h2_t); return __builtin_bit_cast(unsigned, b); }
; #define GL_LOAD(s_, kt_) if (VAR != 1) { a##s_##0 = GL_A(0, kt_); a##s_##1 = GL_A(1, kt_); a##s_##2 = GL_A(2, kt_); a##s_##3 = GL_A(3, kt_); b##s_##0 = GL_B(0, kt_); b##s_##1 = GL_B(1, kt_); b##s_##2 = GL_B(2, kt_); b##s_##3 = GL_B(3, kt_); }
; #define LDS_STORE(s_, buf_) if (VAR != 2) { LDS_ST1(sA, 0, buf_, a##s_##0) LDS_ST1(sA, 1, buf_, a##s_##1) LDS_ST1(sA, 2, buf_, a##s_##2) LDS_ST1(sA, 3, buf_, a##s_##3) LDS_ST1(sB, 0, buf_, b##s_##0) LDS_ST1(sB, 1, buf_, b##s_##1) LDS_ST1(sB, 2, buf_, b##s_##2) LDS_ST1(sB, 3, buf_, b##s_##3) }
;     ...
;   for (int kt = 0; kt < nk; kt += 2) {
;     if (kt + 2 < nk) { GL_LOAD(0, kt + 2) }
;     MMA_TILE(0)
;     LDS_STORE(1, 1)
;     if (VAR != 4) __syncthreads();
;     if (kt + 3 < nk) { GL_LOAD(1, kt + 3) }
;     MMA_TILE(1)
;     if (kt + 2 < nk) { LDS_STORE(0, 0) }
;     if (VAR != 4) __syncthreads();
; DI void epi_residual(const f32x4 (&v)[4][4], int row0, int col0, const float* xsrc, float* x, bf16_t* xb, float* ssq_out, bool write_xb, bool write_ssq) {
;   const int lane = TIDX() & 63, lr = lane & 15, g = lane >> 4;
; #pragma unroll
;   for (int mt = 0; mt < 4; ++mt) {
;     const int row = row0 + mt * 16 + lr;
;     float ss = 0.f;
; #pragma unroll
;     for (int nt = 0; nt < 4; ++nt) {
;       const int col = col0 + nt * 16 + 4 * g;
;       float4* px = (float4*)(x + (size_t)row * DM + col);
;       float4 o = *(const float4*)(xsrc + (size_t)row * DM + col);
;       o.x += v[mt][nt][0]; o.y += v[mt][nt][1]; o.z += v[mt][nt][2]; o.w += v[mt][nt][3];
;       *px = o;
;       ss += (o.x * o.x + o.y * o.y) + (o.z * o.z + o.w * o.w);
;       if (write_xb) *(uint2*)(xb + (size_t)row * DM + col) = make_uint2(pack2(o.x, o.y), pack2(o.z, o.w));
;     }
;     if (write_ssq) {
;       ss += __shfl_xor(ss, 16); ss += __shfl_xor(ss, 32);
;       if (g == 0) ssq_out[(size_t)row * 16 + (col0 >> 6)] = ss;
;     }
;   }
; }
	v_mfma_f32_16x16x32_f16 v[52:55], v[58:61], v[110:113], v[52:55]
	ds_read_b128 v[4:7], v16 offset:49152
	v_add_u32_e32 v130, s4, v57
	v_mfma_f32_16x16x32_f16 v[0:3], v[118:121], v[110:113], v[40:43]
	v_readlane_b32 s4, v254, 45
	v_readlane_b32 s5, v254, 46
	v_mfma_f32_16x16x32_f16 v[8:11], v[122:125], v[110:113], v[48:51]
	ds_read_b128 v[12:15], v16 offset:51200
	ds_read_b128 v[40:43], v21 offset:16384
	s_nop 0
	ds_read_b128 v[48:51], v21 offset:18432
	ds_read_b128 v[58:61], v16 offset:53248
	ds_read_b128 v[16:19], v16 offset:55296
	v_mfma_f32_16x16x32_f16 v[102:105], v[94:97], v[106:109], v[102:105]
	v_mfma_f32_16x16x32_f16 v[114:117], v[118:121], v[106:109], v[114:117]
	v_mfma_f32_16x16x32_f16 v[70:73], v[122:125], v[106:109], v[70:73]
	v_mfma_f32_16x16x32_f16 v[24:27], v[94:97], v[110:113], v[24:27]
	s_waitcnt lgkmcnt(3)
	v_mfma_f32_16x16x32_f16 v[36:39], v[4:7], v[40:43], v[36:39]
	v_mfma_f32_16x16x32_f16 v[44:47], v[12:15], v[40:43], v[44:47]
	s_waitcnt lgkmcnt(1)
	v_mfma_f32_16x16x32_f16 v[62:65], v[58:61], v[40:43], v[82:85]
	s_waitcnt lgkmcnt(0)
	v_mfma_f32_16x16x32_f16 v[28:31], v[16:19], v[40:43], v[28:31]
	ds_read_b128 v[40:43], v21 offset:20480
	ds_read_b128 v[74:77], v21 offset:22528
	ds_read_b128 v[82:85], v23 offset:16384
	ds_read_b128 v[90:93], v23 offset:18432
	ds_read_b128 v[94:97], v22 offset:49152
	ds_read_b128 v[106:109], v22 offset:51200
	ds_read_b128 v[110:113], v23 offset:20480
	ds_read_b128 v[118:121], v23 offset:22528
	ds_read_b128 v[122:125], v22 offset:53248
	ds_read_b128 v[126:129], v22 offset:55296
	v_mfma_f32_16x16x32_f16 v[66:69], v[4:7], v[48:51], v[66:69]
	s_waitcnt lgkmcnt(0)
	s_barrier
	v_mfma_f32_16x16x32_f16 v[78:81], v[12:15], v[48:51], v[78:81]
	v_mfma_f32_16x16x32_f16 v[20:23], v[58:61], v[48:51], v[86:89]
	v_mfma_f32_16x16x32_f16 v[32:35], v[16:19], v[48:51], v[32:35]
	v_mov_b32_e32 v49, v148
	v_or_b32_e32 v48, s10, v56
	v_and_or_b32 v50, v49, 15, v130
	v_bfe_u32 v134, v49, 4, 2
	v_ashrrev_i32_e32 v51, 31, v50
	v_mfma_f32_16x16x32_f16 v[86:89], v[4:7], v[40:43], v[98:101]
	v_lshl_or_b32 v135, v134, 2, v48
	v_lshrrev_b32_e32 v150, 4, v48
	v_lshl_add_u64 v[48:49], s[4:5], 0, v[150:151]
	v_mfma_f32_16x16x32_f16 v[98:101], v[12:15], v[40:43], v[102:105]
	v_lshlrev_b32_e32 v150, 2, v135
	v_readlane_b32 s4, v254, 43
	v_readlane_b32 s5, v254, 44
	v_mfma_f32_16x16x32_f16 v[102:105], v[58:61], v[40:43], v[114:117]
	v_cmp_eq_u32_e32 vcc, 0, v134
	s_nop 1
	v_lshlrev_b64 v[114:115], 12, v[50:51]
	v_lshl_add_u64 v[114:115], s[12:13], 0, v[114:115]
	v_lshl_add_u64 v[130:131], v[114:115], 0, v[150:151]
	v_mfma_f32_16x16x32_f16 v[70:73], v[16:19], v[40:43], v[70:73]
	global_load_dwordx4 v[40:43], v[130:131], off
	v_lshlrev_b64 v[114:115], 11, v[50:51]
	v_lshl_add_u64 v[132:133], s[4:5], 0, v[114:115]
	v_mfma_f32_16x16x32_f16 v[36:39], v[94:97], v[82:85], v[36:39]
	v_mfma_f32_16x16x32_f16 v[4:7], v[4:7], v[74:77], v[52:55]
	s_nop 2
	v_lshlrev_b32_e32 v52, 1, v135
	v_mov_b32_e32 v53, v151
	v_lshl_add_u64 v[54:55], v[132:133], 0, v[52:53]
	v_mfma_f32_16x16x32_f16 v[114:117], v[12:15], v[74:77], v[24:27]
	s_waitcnt vmcnt(0)
	v_pk_add_f32 v[36:37], v[36:37], v[40:41]
	v_pk_add_f32 v[38:39], v[38:39], v[42:43]
	v_cvt_pk_f16_f32 v40, v36, v37
	v_cvt_pk_f16_f32 v41, v38, v39
	global_store_dwordx4 v[130:131], v[36:39], off
	global_store_dwordx2 v[54:55], v[40:41], off
	global_load_dwordx4 v[24:27], v[130:131], off offset:64
	v_mfma_f32_16x16x32_f16 v[12:15], v[106:109], v[82:85], v[44:47]
	v_mfma_f32_16x16x32_f16 v[0:3], v[58:61], v[74:77], v[0:3]
	v_mfma_f32_16x16x32_f16 v[58:61], v[16:19], v[74:77], v[8:11]
	s_waitcnt vmcnt(0)
	s_nop 4
	v_pk_add_f32 v[12:13], v[12:13], v[24:25]
	v_pk_add_f32 v[14:15], v[14:15], v[26:27]
	v_cvt_pk_f16_f32 v24, v12, v13
	v_cvt_pk_f16_f32 v25, v14, v15
	global_store_dwordx4 v[130:131], v[12:15], off offset:64
	global_store_dwordx2 v[54:55], v[24:25], off offset:32
	global_load_dwordx4 v[8:11], v[130:131], off offset:128
	v_mfma_f32_16x16x32_f16 v[16:19], v[122:125], v[82:85], v[62:65]
	v_mul_f32_e64 v12, v12, v12
	v_mul_f32_e64 v13, v13, v13
	v_pk_mul_f32 v[14:15], v[14:15], v[14:15]
	v_add_f32_e32 v12, v12, v13
	v_mfma_f32_16x16x32_f16 v[44:47], v[94:97], v[90:93], v[66:69]
	v_add_f32_e32 v14, v14, v15
	v_add_f32_e32 v12, v12, v14
	s_waitcnt vmcnt(0)
	v_pk_add_f32 v[8:9], v[16:17], v[8:9]
	v_pk_add_f32 v[10:11], v[18:19], v[10:11]
	v_cvt_pk_f16_f32 v24, v8, v9
	v_cvt_pk_f16_f32 v25, v10, v11
	global_store_dwordx4 v[130:131], v[8:11], off offset:128
	global_store_dwordx2 v[54:55], v[24:25], off offset:64
	global_load_dwordx4 v[24:27], v[130:131], off offset:192
	v_mfma_f32_16x16x32_f16 v[16:19], v[126:129], v[82:85], v[28:31]
	v_mul_f32_e64 v66, v36, v36
	v_mul_f32_e64 v67, v37, v37
	v_pk_mul_f32 v[68:69], v[38:39], v[38:39]
	v_pk_mul_f32 v[8:9], v[8:9], v[8:9]
	v_pk_mul_f32 v[10:11], v[10:11], v[10:11]
	v_add_f32_e32 v8, v8, v9
	v_add_f32_e32 v10, v10, v11
	v_add_f32_e32 v8, v8, v10
	v_mfma_f32_16x16x32_f16 v[40:43], v[106:109], v[90:93], v[78:81]
	s_waitcnt vmcnt(0)
	v_pk_add_f32 v[62:63], v[16:17], v[24:25]
	v_add_f32_e32 v16, v68, v69
	v_add_f32_e32 v17, v66, v67
	v_pk_add_f32 v[64:65], v[18:19], v[26:27]
	v_add_f32_e32 v16, v17, v16
	v_pk_mul_f32 v[74:75], v[62:63], v[62:63]
	v_pk_mul_f32 v[76:77], v[64:65], v[64:65]
	v_add_f32_e32 v12, v16, v12
	v_add_f32_e32 v66, v12, v8
	v_mfma_f32_16x16x32_f16 v[12:15], v[94:97], v[118:121], v[4:7]
	global_store_dwordx4 v[130:131], v[62:65], off offset:192
	s_nop 1
	v_add_f32_e32 v4, v76, v77
	v_add_f32_e32 v5, v74, v75
	v_add_f32_e32 v4, v5, v4
	v_add_f32_e32 v66, v66, v4
	ds_bpermute_b32 v67, v189, v66
	v_cvt_pk_f16_f32 v62, v62, v63
	v_cvt_pk_f16_f32 v63, v64, v65
	global_store_dwordx2 v[54:55], v[62:63], off offset:96
	v_mfma_f32_16x16x32_f16 v[36:39], v[122:125], v[90:93], v[20:23]
	s_waitcnt lgkmcnt(0)
	v_add_f32_e32 v54, v66, v67
	ds_bpermute_b32 v55, v188, v54
	v_mfma_f32_16x16x32_f16 v[32:35], v[126:129], v[90:93], v[32:35]
	v_mfma_f32_16x16x32_f16 v[28:31], v[94:97], v[110:113], v[86:89]
	v_mfma_f32_16x16x32_f16 v[24:27], v[106:109], v[110:113], v[98:101]
	v_mfma_f32_16x16x32_f16 v[20:23], v[122:125], v[110:113], v[102:105]
	v_mfma_f32_16x16x32_f16 v[16:19], v[126:129], v[110:113], v[70:73]
	v_mfma_f32_16x16x32_f16 v[8:11], v[106:109], v[118:121], v[114:117]
	v_mfma_f32_16x16x32_f16 v[4:7], v[122:125], v[118:121], v[0:3]
	v_mfma_f32_16x16x32_f16 v[0:3], v[126:129], v[118:121], v[58:61]
	s_and_saveexec_b64 s[4:5], vcc
	s_cbranch_execz .LBB0_1374
	s_waitcnt lgkmcnt(0)
	v_add_f32_e32 v58, v54, v55
	v_lshlrev_b64 v[54:55], 6, v[50:51]
	v_lshl_add_u64 v[54:55], v[48:49], 0, v[54:55]
	global_store_dword v[54:55], v58, off

; DI int BIDX() { int b = blockIdx.x; asm volatile("" : "+s"(b)); return b; }
; #define GL_LOAD(s_, kt_) if (VAR != 1) { a##s_##0 = GL_A(0, kt_); a##s_##1 = GL_A(1, kt_); a##s_##2 = GL_A(2, kt_); a##s_##3 = GL_A(3, kt_); b##s_##0 = GL_B(0, kt_); b##s_##1 = GL_B(1, kt_); b##s_##2 = GL_B(2, kt_); b##s_##3 = GL_B(3, kt_); }
; #define LDS_STORE(s_, buf_) if (VAR != 2) { LDS_ST1(sA, 0, buf_, a##s_##0) LDS_ST1(sA, 1, buf_, a##s_##1) LDS_ST1(sA, 2, buf_, a##s_##2) LDS_ST1(sA, 3, buf_, a##s_##3) LDS_ST1(sB, 0, buf_, b##s_##0) LDS_ST1(sB, 1, buf_, b##s_##1) LDS_ST1(sB, 2, buf_, b##s_##2) LDS_ST1(sB, 3, buf_, b##s_##3) }
; DI int tile_groups(int MT, int NT) { return (MT >> 6) * ((NT + 7) >> 3) * 512; }
;     ...
;   GL_LOAD(0, 0)
;   GL_LOAD(1, 1)
;   LDS_STORE(0, 0)
;   if (VAR != 4) __syncthreads();
; #pragma unroll
;   for (int kt = 0; kt < nk; kt += 2) {
;     if (kt + 2 < nk) { GL_LOAD(0, kt + 2) }
;     MMA_TILE(0)
;     LDS_STORE(1, 1)
;     if (VAR != 4) __syncthreads();
;     if (kt + 3 < nk) { GL_LOAD(1, kt + 3) }
;     MMA_TILE(1)
; DI void phase_ple(const Params& P, int l, char* smem) {
;     ...
;   for (int vb = BIDX(); vb < tile_groups(128, 8); vb += gridDim.x) {
;     int tm, tn; if (!tile_of(vb, 128, 8, tm, tn)) continue;
;     const int m0 = tm * 128, n0 = tn * 128;
;     const int row0 = m0 + wm * 64, col0 = n0 + wn * 64;
;     uint4* park = (uint4*)(ws + OFF_VT) + ((size_t)BIDX() * 256 + tid) * 8;
;     {
;       f32x4 pp[4][4]; zero_acc(pp);
;       gemm_kloop<false, true, 4>(pp, pl + (size_t)m0 * PLE, PLE, W + WO_PP + (size_t)n0 * PLE, PLE, smem);
.LBB0_1435:
	s_ashr_i32 s1, s8, 3
	s_andn2_b32 s1, s1, 63
	s_and_b32 s2, s14, 56
	s_or_b32 s1, s1, s2
	s_bfe_u32 s2, s8, 0x30003
	s_or_b32 s1, s1, s2
	s_cmpk_gt_i32 s1, 0x7f
	s_cbranch_scc1 .LBB0_1434
	s_lshl_b32 s6, s1, 7
	v_readlane_b32 s1, v253, 0
	s_mov_b32 s16, s1
	s_ashr_i32 s17, s16, 31
	s_lshl_b64 s[16:17], s[16:17], 15
	s_ashr_i32 s7, s6, 31
	v_mov_b32_e32 v88, v148
	s_and_b32 s2, s13, 0x380
	v_lshl_add_u64 v[102:103], v[96:97], 0, s[16:17]
	s_lshl_b64 s[16:17], s[6:7], 9
	v_readlane_b32 s18, v254, 39
	v_readlane_b32 s19, v254, 40
	s_waitcnt vmcnt(5)
	v_ashrrev_i32_e32 v80, 3, v88
	s_add_u32 s16, s18, s16
	v_ashrrev_i32_e32 v81, 31, v80
	s_addc_u32 s17, s19, s17
	v_lshlrev_b32_e32 v0, 3, v88
	v_and_b32_e32 v91, 48, v88
	v_lshlrev_b64 v[16:17], 9, v[80:81]
	v_lshlrev_b32_e32 v81, 4, v88
	v_and_b32_e32 v90, 0x70, v0
	v_bitop3_b32 v170, v0, v91, s23 bitop3:0x6c
	s_waitcnt lgkmcnt(0)
	v_lshl_add_u64 v[0:1], s[16:17], 0, v[16:17]
	v_and_b32_e32 v150, 0x70, v81
	v_add_u32_e32 v82, 32, v80
	s_waitcnt vmcnt(4)
	v_add_u32_e32 v84, 64, v80
	v_add_u32_e32 v86, 0x60, v80
	s_lshl_b32 s1, s2, 9
	s_waitcnt vmcnt(1)
	v_lshl_add_u64 v[64:65], v[0:1], 0, v[150:151]
	v_ashrrev_i32_e32 v83, 31, v82
	v_ashrrev_i32_e32 v85, 31, v84
	v_ashrrev_i32_e32 v87, 31, v86
	s_add_u32 s18, s9, s1
	global_load_dwordx4 v[0:3], v[64:65], off
	v_lshlrev_b64 v[20:21], 9, v[82:83]
	v_lshlrev_b64 v[24:25], 9, v[84:85]
	v_lshlrev_b64 v[28:29], 9, v[86:87]
	s_addc_u32 s19, s10, 0
	v_lshl_add_u64 v[4:5], s[16:17], 0, v[20:21]
	v_lshl_add_u64 v[8:9], s[16:17], 0, v[24:25]
	v_lshl_add_u64 v[12:13], s[16:17], 0, v[28:29]
	v_lshl_add_u64 v[66:67], v[4:5], 0, v[150:151]
	s_waitcnt vmcnt(1)
	v_lshl_add_u64 v[68:69], v[8:9], 0, v[150:151]
	v_lshl_add_u64 v[70:71], v[12:13], 0, v[150:151]
	v_lshl_add_u64 v[16:17], s[18:19], 0, v[16:17]
	global_load_dwordx4 v[4:7], v[66:67], off
	global_load_dwordx4 v[8:11], v[68:69], off
	global_load_dwordx4 v[12:15], v[70:71], off
	v_lshl_add_u64 v[72:73], v[16:17], 0, v[150:151]
	v_lshl_add_u64 v[20:21], s[18:19], 0, v[20:21]
	global_load_dwordx4 v[16:19], v[72:73], off
	v_lshl_add_u64 v[74:75], v[20:21], 0, v[150:151]
	v_lshl_add_u64 v[24:25], s[18:19], 0, v[24:25]
	global_load_dwordx4 v[20:23], v[74:75], off
	v_lshl_add_u64 v[76:77], v[24:25], 0, v[150:151]
	global_load_dwordx4 v[24:27], v[76:77], off
	v_lshl_add_u64 v[28:29], s[18:19], 0, v[28:29]
	v_lshl_add_u64 v[78:79], v[28:29], 0, v[150:151]
	global_load_dwordx4 v[28:31], v[78:79], off
	global_load_dwordx4 v[32:35], v[64:65], off offset:128
	global_load_dwordx4 v[36:39], v[66:67], off offset:128
	global_load_dwordx4 v[40:43], v[68:69], off offset:128
	global_load_dwordx4 v[44:47], v[70:71], off offset:128
	global_load_dwordx4 v[48:51], v[72:73], off offset:128
	global_load_dwordx4 v[52:55], v[74:75], off offset:128
	global_load_dwordx4 v[56:59], v[76:77], off offset:128
	global_load_dwordx4 v[60:63], v[78:79], off offset:128
	v_bitop3_b32 v83, v81, s23, v88 bitop3:0x48
	v_lshl_or_b32 v80, v80, 7, v83
	v_and_b32_e32 v89, 15, v88
	v_lshl_or_b32 v81, v82, 7, v83
	v_lshl_or_b32 v82, v84, 7, v83
	v_lshl_or_b32 v83, v86, 7, v83
	v_xor_b32_e32 v171, 64, v170
	v_add_u32_e32 v123, s6, v122
	v_readlane_b32 s16, v254, 45
	v_readlane_b32 s17, v254, 46
	s_mov_b32 s18, 0x358637bd
	s_mov_b32 s1, 0x800000
	s_lshl_b64 s[6:7], s[6:7], 11
	s_waitcnt vmcnt(15)
	ds_write_b128 v80, v[0:3]
	v_lshrrev_b32_e32 v0, 1, v88
	v_and_or_b32 v0, v0, s24, v89
	v_lshlrev_b32_e32 v150, 7, v0
	v_lshlrev_b32_e32 v0, 7, v88
	v_and_b32_e32 v194, 0x2780, v0
	v_bitop3_b32 v84, v150, v90, v91 bitop3:0xf6
	v_or_b32_e32 v85, v194, v170
	s_waitcnt vmcnt(14)
	ds_write_b128 v81, v[4:7]
	s_waitcnt vmcnt(13)
	ds_write_b128 v82, v[8:11]
	s_waitcnt vmcnt(12)
	ds_write_b128 v83, v[12:15]
	s_waitcnt vmcnt(11)
	ds_write_b128 v80, v[16:19] offset:32768
	s_waitcnt vmcnt(10)
	ds_write_b128 v81, v[20:23] offset:32768
	s_waitcnt vmcnt(9)
	ds_write_b128 v82, v[24:27] offset:32768
	s_waitcnt vmcnt(8)
	ds_write_b128 v83, v[28:31] offset:32768
	s_waitcnt lgkmcnt(0)
	s_barrier
	global_load_dwordx4 v[0:3], v[64:65], off offset:256
	global_load_dwordx4 v[4:7], v[66:67], off offset:256
	global_load_dwordx4 v[8:11], v[68:69], off offset:256
	global_load_dwordx4 v[12:15], v[70:71], off offset:256
	global_load_dwordx4 v[16:19], v[72:73], off offset:256
	global_load_dwordx4 v[20:23], v[74:75], off offset:256
	global_load_dwordx4 v[24:27], v[76:77], off offset:256
	global_load_dwordx4 v[28:31], v[78:79], off offset:256
	ds_read_b128 v[86:89], v84
	ds_read_b128 v[90:93], v85 offset:32768
	ds_read_b128 v[98:101], v84 offset:2048
	ds_read_b128 v[104:107], v85 offset:34816
	ds_read_b128 v[108:111], v84 offset:4096
	ds_read_b128 v[112:115], v85 offset:36864
	ds_read_b128 v[116:119], v84 offset:6144
	ds_read_b128 v[124:127], v85 offset:38912
	s_waitcnt lgkmcnt(6)
	v_mfma_f32_16x16x32_f16 v[128:131], v[90:93], v[86:89], 0
	s_waitcnt lgkmcnt(4)
	v_mfma_f32_16x16x32_f16 v[132:135], v[104:107], v[86:89], 0
	s_waitcnt lgkmcnt(2)
	v_mfma_f32_16x16x32_f16 v[136:139], v[112:115], v[86:89], 0
	s_waitcnt lgkmcnt(0)
	v_mfma_f32_16x16x32_f16 v[140:143], v[124:127], v[86:89], 0
	v_bitop3_b32 v86, v150, v170, 64 bitop3:0xf6
	v_or_b32_e32 v87, v194, v171
	v_mfma_f32_16x16x32_f16 v[144:147], v[90:93], v[98:101], 0
	v_mfma_f32_16x16x32_f16 v[154:157], v[104:107], v[98:101], 0
	v_mfma_f32_16x16x32_f16 v[158:161], v[112:115], v[98:101], 0
	v_mfma_f32_16x16x32_f16 v[98:101], v[124:127], v[98:101], 0
	v_mfma_f32_16x16x32_f16 v[162:165], v[90:93], v[108:111], 0
	v_mfma_f32_16x16x32_f16 v[166:169], v[104:107], v[108:111], 0
	v_mfma_f32_16x16x32_f16 v[190:193], v[112:115], v[108:111], 0
	v_mfma_f32_16x16x32_f16 v[108:111], v[124:127], v[108:111], 0
	v_mfma_f32_16x16x32_f16 v[88:91], v[90:93], v[116:119], 0
	v_mfma_f32_16x16x32_f16 v[92:95], v[104:107], v[116:119], 0
	v_mfma_f32_16x16x32_f16 v[104:107], v[112:115], v[116:119], 0
	v_mfma_f32_16x16x32_f16 v[112:115], v[124:127], v[116:119], 0
	ds_read_b128 v[116:119], v86
	ds_read_b128 v[124:127], v87 offset:32768
	ds_read_b128 v[194:197], v86 offset:2048
	ds_read_b128 v[198:201], v87 offset:34816
	ds_read_b128 v[202:205], v86 offset:4096
	ds_read_b128 v[206:209], v87 offset:36864
	ds_read_b128 v[210:213], v86 offset:6144
	ds_read_b128 v[220:223], v87 offset:38912
	s_waitcnt vmcnt(15)
	ds_write_b128 v80, v[32:35] offset:16384
	s_waitcnt vmcnt(14)
	ds_write_b128 v81, v[36:39] offset:16384
	s_waitcnt vmcnt(13)
	ds_write_b128 v82, v[40:43] offset:16384
	s_waitcnt vmcnt(12)
	ds_write_b128 v83, v[44:47] offset:16384
	s_waitcnt vmcnt(11)
	ds_write_b128 v80, v[48:51] offset:49152
	s_waitcnt vmcnt(10)
	ds_write_b128 v81, v[52:55] offset:49152
	s_waitcnt vmcnt(9)
	ds_write_b128 v82, v[56:59] offset:49152
	s_waitcnt vmcnt(8)
	ds_write_b128 v83, v[60:63] offset:49152
	s_waitcnt lgkmcnt(0)
	s_barrier
; #define GL_LOAD(s_, kt_) if (VAR != 1) { a##s_##0 = GL_A(0, kt_); a##s_##1 = GL_A(1, kt_); a##s_##2 = GL_A(2, kt_); a##s_##3 = GL_A(3, kt_); b##s_##0 = GL_B(0, kt_); b##s_##1 = GL_B(1, kt_); b##s_##2 = GL_B(2, kt_); b##s_##3 = GL_B(3, kt_); }
; #define LDS_STORE(s_, buf_) if (VAR != 2) { LDS_ST1(sA, 0, buf_, a##s_##0) LDS_ST1(sA, 1, buf_, a##s_##1) LDS_ST1(sA, 2, buf_, a##s_##2) LDS_ST1(sA, 3, buf_, a##s_##3) LDS_ST1(sB, 0, buf_, b##s_##0) LDS_ST1(sB, 1, buf_, b##s_##1) LDS_ST1(sB, 2, buf_, b##s_##2) LDS_ST1(sB, 3, buf_, b##s_##3) }
;     ...
;   for (int kt = 0; kt < nk; kt += 2) {
;     if (kt + 2 < nk) { GL_LOAD(0, kt + 2) }
;     MMA_TILE(0)
;     LDS_STORE(1, 1)
;     if (VAR != 4) __syncthreads();
;     if (kt + 3 < nk) { GL_LOAD(1, kt + 3) }
;     MMA_TILE(1)
;     if (kt + 2 < nk) { LDS_STORE(0, 0) }
;     if (VAR != 4) __syncthreads();
	v_mfma_f32_16x16x32_f16 v[128:131], v[124:127], v[116:119], v[128:131]
	global_load_dwordx4 v[32:35], v[64:65], off offset:384
	v_mfma_f32_16x16x32_f16 v[132:135], v[198:201], v[116:119], v[132:135]
	v_mfma_f32_16x16x32_f16 v[136:139], v[206:209], v[116:119], v[136:139]
	v_mfma_f32_16x16x32_f16 v[116:119], v[220:223], v[116:119], v[140:143]
	v_mfma_f32_16x16x32_f16 v[140:143], v[124:127], v[194:197], v[144:147]
	global_load_dwordx4 v[36:39], v[66:67], off offset:384
	ds_read_b128 v[64:67], v84 offset:16384
	global_load_dwordx4 v[40:43], v[68:69], off offset:384
	v_mfma_f32_16x16x32_f16 v[144:147], v[198:201], v[194:197], v[154:157]
	global_load_dwordx4 v[44:47], v[70:71], off offset:384
	v_mfma_f32_16x16x32_f16 v[154:157], v[206:209], v[194:197], v[158:161]
	v_mfma_f32_16x16x32_f16 v[158:161], v[124:127], v[202:205], v[162:165]
	ds_read_b128 v[68:71], v85 offset:49152
	global_load_dwordx4 v[48:51], v[72:73], off offset:384
	v_mfma_f32_16x16x32_f16 v[88:91], v[124:127], v[210:213], v[88:91]
	ds_read_b128 v[124:127], v84 offset:20480
	v_mfma_f32_16x16x32_f16 v[162:165], v[198:201], v[202:205], v[166:169]
	global_load_dwordx4 v[52:55], v[74:75], off offset:384
	v_mfma_f32_16x16x32_f16 v[92:95], v[198:201], v[210:213], v[92:95]
	ds_read_b128 v[72:75], v84 offset:18432
	ds_read_b128 v[198:201], v85 offset:55296
	global_load_dwordx4 v[56:59], v[76:77], off offset:384
	global_load_dwordx4 v[60:63], v[78:79], off offset:384
	v_mfma_f32_16x16x32_f16 v[98:101], v[220:223], v[194:197], v[98:101]
	ds_read_b128 v[76:79], v85 offset:51200
	v_mfma_f32_16x16x32_f16 v[166:169], v[206:209], v[202:205], v[190:193]
	s_nop 2
	ds_read_b128 v[190:193], v85 offset:53248
	v_mfma_f32_16x16x32_f16 v[104:107], v[206:209], v[210:213], v[104:107]
	ds_read_b128 v[194:197], v84 offset:22528
	v_mfma_f32_16x16x32_f16 v[108:111], v[220:223], v[202:205], v[108:111]
	s_waitcnt vmcnt(15)
	ds_write_b128 v80, v[0:3]
	v_mfma_f32_16x16x32_f16 v[112:115], v[220:223], v[210:213], v[112:115]
	s_waitcnt vmcnt(14)
	ds_write_b128 v81, v[4:7]
	s_waitcnt lgkmcnt(8)
	v_mfma_f32_16x16x32_f16 v[128:131], v[68:71], v[64:67], v[128:131]
	s_waitcnt vmcnt(13)
	ds_write_b128 v82, v[8:11]
	s_waitcnt lgkmcnt(5)
	v_mfma_f32_16x16x32_f16 v[132:135], v[76:79], v[64:67], v[132:135]
	s_waitcnt lgkmcnt(4)
	v_mfma_f32_16x16x32_f16 v[136:139], v[190:193], v[64:67], v[136:139]
	v_mfma_f32_16x16x32_f16 v[64:67], v[198:201], v[64:67], v[116:119]
	v_mfma_f32_16x16x32_f16 v[116:119], v[68:71], v[72:75], v[140:143]
	s_waitcnt vmcnt(12)
	ds_write_b128 v83, v[12:15]
	s_waitcnt vmcnt(11)
	ds_write_b128 v80, v[16:19] offset:32768
	v_mfma_f32_16x16x32_f16 v[140:143], v[76:79], v[72:75], v[144:147]
	s_waitcnt vmcnt(10)
	ds_write_b128 v81, v[20:23] offset:32768
	v_mfma_f32_16x16x32_f16 v[144:147], v[190:193], v[72:75], v[154:157]
	v_mfma_f32_16x16x32_f16 v[72:75], v[198:201], v[72:75], v[98:101]
	v_mfma_f32_16x16x32_f16 v[98:101], v[68:71], v[124:127], v[158:161]
	s_waitcnt vmcnt(9)
	ds_write_b128 v82, v[24:27] offset:32768
	s_waitcnt vmcnt(8)
	ds_write_b128 v83, v[28:31] offset:32768
	s_waitcnt lgkmcnt(8)
	v_mfma_f32_16x16x32_f16 v[68:71], v[68:71], v[194:197], v[88:91]
	v_mfma_f32_16x16x32_f16 v[154:157], v[76:79], v[124:127], v[162:165]
	s_nop 2
	ds_read_b128 v[162:165], v87 offset:51200
	v_mfma_f32_16x16x32_f16 v[76:79], v[76:79], v[194:197], v[92:95]
	v_mfma_f32_16x16x32_f16 v[158:161], v[190:193], v[124:127], v[166:169]
	s_nop 2
	ds_read_b128 v[166:169], v86 offset:20480
	v_mfma_f32_16x16x32_f16 v[88:91], v[190:193], v[194:197], v[104:107]
	s_nop 2
	ds_read_b128 v[104:107], v86 offset:16384
	ds_read_b128 v[190:193], v87 offset:53248
	v_mfma_f32_16x16x32_f16 v[108:111], v[198:201], v[124:127], v[108:111]
	ds_read_b128 v[124:127], v86 offset:18432
	v_mfma_f32_16x16x32_f16 v[92:95], v[198:201], v[194:197], v[112:115]
	s_nop 2
	ds_read_b128 v[112:115], v87 offset:49152
	ds_read_b128 v[194:197], v86 offset:22528
	ds_read_b128 v[198:201], v87 offset:55296
	s_waitcnt lgkmcnt(0)
	s_barrier
	ds_read_b128 v[0:3], v84
	ds_read_b128 v[4:7], v85 offset:32768
	ds_read_b128 v[8:11], v84 offset:2048
	ds_read_b128 v[12:15], v85 offset:34816
	ds_read_b128 v[16:19], v84 offset:4096
	ds_read_b128 v[20:23], v85 offset:36864
	ds_read_b128 v[24:27], v84 offset:6144
	ds_read_b128 v[28:31], v85 offset:38912
	v_mfma_f32_16x16x32_f16 v[128:131], v[112:115], v[104:107], v[128:131]
	v_mfma_f32_16x16x32_f16 v[132:135], v[162:165], v[104:107], v[132:135]
	v_mfma_f32_16x16x32_f16 v[136:139], v[190:193], v[104:107], v[136:139]
	v_mfma_f32_16x16x32_f16 v[64:67], v[198:201], v[104:107], v[64:67]
	v_mfma_f32_16x16x32_f16 v[104:107], v[112:115], v[124:127], v[116:119]
	v_mfma_f32_16x16x32_f16 v[116:119], v[162:165], v[124:127], v[140:143]
	v_mfma_f32_16x16x32_f16 v[140:143], v[190:193], v[124:127], v[144:147]
	v_mfma_f32_16x16x32_f16 v[72:75], v[198:201], v[124:127], v[72:75]
	v_mfma_f32_16x16x32_f16 v[98:101], v[112:115], v[166:169], v[98:101]
	v_mfma_f32_16x16x32_f16 v[124:127], v[162:165], v[166:169], v[154:157]
	v_mfma_f32_16x16x32_f16 v[144:147], v[190:193], v[166:169], v[158:161]
	v_mfma_f32_16x16x32_f16 v[108:111], v[198:201], v[166:169], v[108:111]
	v_mfma_f32_16x16x32_f16 v[68:71], v[112:115], v[194:197], v[68:71]
	v_mfma_f32_16x16x32_f16 v[76:79], v[162:165], v[194:197], v[76:79]
	v_mfma_f32_16x16x32_f16 v[88:91], v[190:193], v[194:197], v[88:91]
	v_mfma_f32_16x16x32_f16 v[92:95], v[198:201], v[194:197], v[92:95]
	s_waitcnt lgkmcnt(6)
	v_mfma_f32_16x16x32_f16 v[112:115], v[4:7], v[0:3], v[128:131]
	s_waitcnt lgkmcnt(4)
	v_mfma_f32_16x16x32_f16 v[128:131], v[12:15], v[0:3], v[132:135]
	s_waitcnt lgkmcnt(2)
; #define GL_LOAD(s_, kt_) if (VAR != 1) { a##s_##0 = GL_A(0, kt_); a##s_##1 = GL_A(1, kt_); a##s_##2 = GL_A(2, kt_); a##s_##3 = GL_A(3, kt_); b##s_##0 = GL_B(0, kt_); b##s_##1 = GL_B(1, kt_); b##s_##2 = GL_B(2, kt_); b##s_##3 = GL_B(3, kt_); }
; #define LDS_STORE(s_, buf_) if (VAR != 2) { LDS_ST1(sA, 0, buf_, a##s_##0) LDS_ST1(sA, 1, buf_, a##s_##1) LDS_ST1(sA, 2, buf_, a##s_##2) LDS_ST1(sA, 3, buf_, a##s_##3) LDS_ST1(sB, 0, buf_, b##s_##0) LDS_ST1(sB, 1, buf_, b##s_##1) LDS_ST1(sB, 2, buf_, b##s_##2) LDS_ST1(sB, 3, buf_, b##s_##3) }
;     ...
;     MMA_TILE(0)
;     LDS_STORE(1, 1)
;     if (VAR != 4) __syncthreads();
;     if (kt + 3 < nk) { GL_LOAD(1, kt + 3) }
;     MMA_TILE(1)
;     if (kt + 2 < nk) { LDS_STORE(0, 0) }
;     if (VAR != 4) __syncthreads();
	v_mfma_f32_16x16x32_f16 v[132:135], v[20:23], v[0:3], v[136:139]
	s_waitcnt lgkmcnt(0)
	v_mfma_f32_16x16x32_f16 v[0:3], v[28:31], v[0:3], v[64:67]
	v_mfma_f32_16x16x32_f16 v[64:67], v[4:7], v[8:11], v[104:107]
	v_mfma_f32_16x16x32_f16 v[104:107], v[12:15], v[8:11], v[116:119]
	v_mfma_f32_16x16x32_f16 v[116:119], v[20:23], v[8:11], v[140:143]
	v_mfma_f32_16x16x32_f16 v[8:11], v[28:31], v[8:11], v[72:75]
	v_mfma_f32_16x16x32_f16 v[72:75], v[4:7], v[16:19], v[98:101]
	v_mfma_f32_16x16x32_f16 v[98:101], v[12:15], v[16:19], v[124:127]
	v_mfma_f32_16x16x32_f16 v[124:127], v[20:23], v[16:19], v[144:147]
	v_mfma_f32_16x16x32_f16 v[16:19], v[28:31], v[16:19], v[108:111]
	v_mfma_f32_16x16x32_f16 v[4:7], v[4:7], v[24:27], v[68:71]
	v_mfma_f32_16x16x32_f16 v[12:15], v[12:15], v[24:27], v[76:79]
	v_mfma_f32_16x16x32_f16 v[20:23], v[20:23], v[24:27], v[88:91]
	v_mfma_f32_16x16x32_f16 v[24:27], v[28:31], v[24:27], v[92:95]
	ds_read_b128 v[28:31], v86
	ds_read_b128 v[68:71], v87 offset:32768
	ds_read_b128 v[76:79], v86 offset:2048
	ds_read_b128 v[88:91], v87 offset:34816
	ds_read_b128 v[92:95], v86 offset:4096
	ds_read_b128 v[108:111], v87 offset:36864
	ds_read_b128 v[136:139], v86 offset:6144
	ds_read_b128 v[140:143], v87 offset:38912
	s_waitcnt vmcnt(7)
	ds_write_b128 v80, v[32:35] offset:16384
	s_waitcnt vmcnt(6)
	ds_write_b128 v81, v[36:39] offset:16384
	s_waitcnt vmcnt(5)
	ds_write_b128 v82, v[40:43] offset:16384
	s_waitcnt vmcnt(4)
	ds_write_b128 v83, v[44:47] offset:16384
	s_waitcnt vmcnt(3)
	ds_write_b128 v80, v[48:51] offset:49152
	s_waitcnt vmcnt(2)
	ds_write_b128 v81, v[52:55] offset:49152
	s_waitcnt vmcnt(1)
	ds_write_b128 v82, v[56:59] offset:49152
	s_waitcnt vmcnt(0)
	ds_write_b128 v83, v[60:63] offset:49152
	s_waitcnt lgkmcnt(0)
	s_barrier
	ds_read_b128 v[32:35], v84 offset:16384
	ds_read_b128 v[36:39], v85 offset:49152
	ds_read_b128 v[40:43], v84 offset:18432
	ds_read_b128 v[44:47], v85 offset:51200
	ds_read_b128 v[48:51], v84 offset:20480
	ds_read_b128 v[52:55], v85 offset:53248
	ds_read_b128 v[56:59], v84 offset:22528
	ds_read_b128 v[60:63], v85 offset:55296
	v_mfma_f32_16x16x32_f16 v[112:115], v[68:71], v[28:31], v[112:115]
	v_mfma_f32_16x16x32_f16 v[128:131], v[88:91], v[28:31], v[128:131]
	v_mfma_f32_16x16x32_f16 v[132:135], v[108:111], v[28:31], v[132:135]
	v_mfma_f32_16x16x32_f16 v[0:3], v[140:143], v[28:31], v[0:3]
	v_mfma_f32_16x16x32_f16 v[28:31], v[68:71], v[76:79], v[64:67]
	v_mfma_f32_16x16x32_f16 v[64:67], v[88:91], v[76:79], v[104:107]
	v_mfma_f32_16x16x32_f16 v[104:107], v[108:111], v[76:79], v[116:119]
	v_mfma_f32_16x16x32_f16 v[8:11], v[140:143], v[76:79], v[8:11]
	v_mfma_f32_16x16x32_f16 v[72:75], v[68:71], v[92:95], v[72:75]
	v_mfma_f32_16x16x32_f16 v[76:79], v[88:91], v[92:95], v[98:101]
	v_mfma_f32_16x16x32_f16 v[98:101], v[108:111], v[92:95], v[124:127]
	v_mfma_f32_16x16x32_f16 v[16:19], v[140:143], v[92:95], v[16:19]
	v_mfma_f32_16x16x32_f16 v[4:7], v[68:71], v[136:139], v[4:7]
	v_mfma_f32_16x16x32_f16 v[12:15], v[88:91], v[136:139], v[12:15]
	v_mfma_f32_16x16x32_f16 v[20:23], v[108:111], v[136:139], v[20:23]
	v_mfma_f32_16x16x32_f16 v[24:27], v[140:143], v[136:139], v[24:27]
	s_waitcnt lgkmcnt(6)
	v_mfma_f32_16x16x32_f16 v[68:71], v[36:39], v[32:35], v[112:115]
	s_waitcnt lgkmcnt(4)
	v_mfma_f32_16x16x32_f16 v[80:83], v[44:47], v[32:35], v[128:131]
	s_waitcnt lgkmcnt(2)
	v_mfma_f32_16x16x32_f16 v[88:91], v[52:55], v[32:35], v[132:135]
	s_waitcnt lgkmcnt(0)
	v_mfma_f32_16x16x32_f16 v[0:3], v[60:63], v[32:35], v[0:3]
	v_mfma_f32_16x16x32_f16 v[28:31], v[36:39], v[40:43], v[28:31]
	v_mfma_f32_16x16x32_f16 v[32:35], v[44:47], v[40:43], v[64:67]
	v_mfma_f32_16x16x32_f16 v[64:67], v[52:55], v[40:43], v[104:107]
	v_mfma_f32_16x16x32_f16 v[8:11], v[60:63], v[40:43], v[8:11]
	v_mfma_f32_16x16x32_f16 v[40:43], v[36:39], v[48:51], v[72:75]
	v_mfma_f32_16x16x32_f16 v[72:75], v[44:47], v[48:51], v[76:79]
	v_mfma_f32_16x16x32_f16 v[76:79], v[52:55], v[48:51], v[98:101]
	v_mfma_f32_16x16x32_f16 v[16:19], v[60:63], v[48:51], v[16:19]
	v_mfma_f32_16x16x32_f16 v[4:7], v[36:39], v[56:59], v[4:7]
	v_mfma_f32_16x16x32_f16 v[12:15], v[44:47], v[56:59], v[12:15]
	v_mfma_f32_16x16x32_f16 v[20:23], v[52:55], v[56:59], v[20:23]
	v_mfma_f32_16x16x32_f16 v[24:27], v[60:63], v[56:59], v[24:27]
	ds_read_b128 v[36:39], v86 offset:16384
	ds_read_b128 v[44:47], v87 offset:49152
	ds_read_b128 v[48:51], v86 offset:18432
	ds_read_b128 v[52:55], v87 offset:51200
	ds_read_b128 v[56:59], v86 offset:20480
	ds_read_b128 v[60:63], v87 offset:53248
	ds_read_b128 v[92:95], v86 offset:22528
	ds_read_b128 v[84:87], v87 offset:55296
	s_waitcnt lgkmcnt(0)
	s_barrier
; DI unsigned pack2(float lo, float hi) { f2_t v = {lo, hi}; h2_t b = __builtin_convertvector(v, h2_t); return __builtin_bit_cast(unsigned, b); }
; DI void load_rstd(float (&rs)[4], const float* ssq, int row0, int lr) {
; #pragma unroll
;   for (int mt = 0; mt < 4; ++mt) {
;     const float4* q = (const float4*)(ssq + (size_t)(row0 + mt * 16 + lr) * 16);
;     const float4 a = q[0], b = q[1], c = q[2], d = q[3];
;     const float s = ((a.x + a.y) + (a.z + a.w)) + ((b.x + b.y) + (b.z + b.w)) + ((c.x + c.y) + (c.z + c.w)) + ((d.x + d.y) + (d.z + d.w));
;     rs[mt] = rsqrtf(s * (1.0f / 1024.0f) + EPS);
;   }
; }
; DI void phase_ple(const Params& P, int l, char* smem) {
;     ...
;       gemm_kloop<false, true, 4>(pp, pl + (size_t)m0 * PLE, PLE, W + WO_PP + (size_t)n0 * PLE, PLE, smem);
; #pragma unroll
;       for (int mt = 0; mt < 4; ++mt)
; #pragma unroll
;         for (int h = 0; h < 2; ++h)
;           park[mt * 2 + h] = make_uint4(pack2(pp[mt][2 * h][0], pp[mt][2 * h][1]), pack2(pp[mt][2 * h][2], pp[mt][2 * h][3]), pack2(pp[mt][2 * h + 1][0], pp[mt][2 * h + 1][1]), pack2(pp[mt][2 * h + 1][2], pp[mt][2 * h + 1][3]));
;     }
;     f32x4 acc[4][4]; zero_acc(acc);
;     float rs[4]; load_rstd(rs, ssq, row0, lr);
	v_mfma_f32_16x16x32_f16 v[68:71], v[44:47], v[36:39], v[68:71]
	v_mfma_f32_16x16x32_f16 v[80:83], v[52:55], v[36:39], v[80:83]
	v_mfma_f32_16x16x32_f16 v[0:3], v[84:87], v[36:39], v[0:3]
	v_mfma_f32_16x16x32_f16 v[28:31], v[44:47], v[48:51], v[28:31]
	v_mfma_f32_16x16x32_f16 v[32:35], v[52:55], v[48:51], v[32:35]
	v_mfma_f32_16x16x32_f16 v[88:91], v[60:63], v[36:39], v[88:91]
	v_mfma_f32_16x16x32_f16 v[36:39], v[60:63], v[48:51], v[64:67]
	v_mfma_f32_16x16x32_f16 v[8:11], v[84:87], v[48:51], v[8:11]
	v_mfma_f32_16x16x32_f16 v[40:43], v[44:47], v[56:59], v[40:43]
	v_mfma_f32_16x16x32_f16 v[48:51], v[52:55], v[56:59], v[72:75]
	v_mfma_f32_16x16x32_f16 v[64:67], v[60:63], v[56:59], v[76:79]
	s_nop 1
	v_mov_b32_e32 v72, v148
	v_mfma_f32_16x16x32_f16 v[16:19], v[84:87], v[56:59], v[16:19]
	v_mfma_f32_16x16x32_f16 v[4:7], v[44:47], v[92:95], v[4:7]
	v_cvt_pk_f16_f32 v44, v68, v69
	v_cvt_pk_f16_f32 v45, v70, v71
	v_cvt_pk_f16_f32 v46, v80, v81
	v_cvt_pk_f16_f32 v47, v82, v83
	v_mfma_f32_16x16x32_f16 v[12:15], v[52:55], v[92:95], v[12:15]
	global_store_dwordx4 v[102:103], v[44:47], off
	s_nop 1
	v_cvt_pk_f16_f32 v46, v0, v1
	v_cvt_pk_f16_f32 v47, v2, v3
	v_cvt_pk_f16_f32 v0, v28, v29
	v_cvt_pk_f16_f32 v1, v30, v31
	v_cvt_pk_f16_f32 v2, v32, v33
	v_cvt_pk_f16_f32 v3, v34, v35
	v_mfma_f32_16x16x32_f16 v[20:23], v[60:63], v[92:95], v[20:23]
	global_store_dwordx4 v[102:103], v[0:3], off offset:32
	v_cvt_pk_f16_f32 v44, v88, v89
	v_cvt_pk_f16_f32 v45, v90, v91
	v_mfma_f32_16x16x32_f16 v[24:27], v[84:87], v[92:95], v[24:27]
	v_cvt_pk_f16_f32 v0, v36, v37
	v_cvt_pk_f16_f32 v1, v38, v39
	v_cvt_pk_f16_f32 v2, v8, v9
	v_cvt_pk_f16_f32 v3, v10, v11
	global_store_dwordx4 v[102:103], v[0:3], off offset:48
	global_store_dwordx4 v[102:103], v[44:47], off offset:16
	s_nop 0
	v_cvt_pk_f16_f32 v0, v40, v41
	v_cvt_pk_f16_f32 v1, v42, v43
	v_cvt_pk_f16_f32 v2, v48, v49
	v_cvt_pk_f16_f32 v3, v50, v51
	global_store_dwordx4 v[102:103], v[0:3], off offset:64
	s_nop 1
	v_cvt_pk_f16_f32 v0, v64, v65
	v_cvt_pk_f16_f32 v1, v66, v67
	v_cvt_pk_f16_f32 v2, v16, v17
	v_cvt_pk_f16_f32 v3, v18, v19
	global_store_dwordx4 v[102:103], v[0:3], off offset:80
	s_nop 1
	v_cvt_pk_f16_f32 v0, v4, v5
	v_cvt_pk_f16_f32 v1, v6, v7
	v_cvt_pk_f16_f32 v2, v12, v13
	v_cvt_pk_f16_f32 v3, v14, v15
	global_store_dwordx4 v[102:103], v[0:3], off offset:96
	s_nop 1
	v_cvt_pk_f16_f32 v0, v20, v21
	v_cvt_pk_f16_f32 v1, v22, v23
	v_cvt_pk_f16_f32 v2, v24, v25
	v_cvt_pk_f16_f32 v3, v26, v27
	global_store_dwordx4 v[102:103], v[0:3], off offset:112
	s_nop 1
	v_or_b32_e32 v0, v123, v121
	v_ashrrev_i32_e32 v1, 31, v0
	v_lshlrev_b64 v[2:3], 6, v[0:1]
	v_lshl_add_u64 v[14:15], s[16:17], 0, v[2:3]
	global_load_dwordx4 v[2:5], v[14:15], off offset:32
	global_load_dwordx4 v[6:9], v[14:15], off offset:16
	global_load_dwordx4 v[10:13], v[14:15], off
	s_nop 0
	global_load_dwordx4 v[14:17], v[14:15], off offset:48
	s_waitcnt vmcnt(2)
	v_mov_b32_e32 v20, v7
	s_waitcnt vmcnt(1)
	v_mov_b32_e32 v18, v11
	v_mov_b32_e32 v19, v12
	v_mov_b32_e32 v21, v8
	v_mov_b32_e32 v11, v13
	v_mov_b32_e32 v7, v9
	v_mov_b32_e32 v8, v3
	v_pk_add_f32 v[10:11], v[18:19], v[10:11]
	v_pk_add_f32 v[6:7], v[20:21], v[6:7]
	v_pk_add_f32 v[2:3], v[2:3], v[8:9]
	v_mov_b32_e32 v8, v5
	v_pk_add_f32 v[10:11], v[10:11], v[10:11] op_sel:[0,1] op_sel_hi:[1,0]
	v_pk_add_f32 v[6:7], v[6:7], v[6:7] op_sel:[0,1] op_sel_hi:[1,0]
	v_pk_add_f32 v[4:5], v[4:5], v[8:9]
	s_waitcnt vmcnt(0)
	v_mov_b32_e32 v11, v14
	v_mov_b32_e32 v7, v15
	v_mov_b32_e32 v3, v16
	v_mov_b32_e32 v5, v17
	v_pk_add_f32 v[6:7], v[10:11], v[6:7]
	v_pk_add_f32 v[2:3], v[2:3], v[4:5]
	s_nop 0
	v_pk_add_f32 v[18:19], v[6:7], v[2:3]
	v_or_b32_e32 v2, 16, v0
	v_ashrrev_i32_e32 v3, 31, v2
	v_lshlrev_b64 v[2:3], 6, v[2:3]
	v_lshl_add_u64 v[14:15], s[16:17], 0, v[2:3]
	global_load_dwordx4 v[2:5], v[14:15], off offset:32
	global_load_dwordx4 v[6:9], v[14:15], off offset:16
	global_load_dwordx4 v[10:13], v[14:15], off
	s_nop 0
	global_load_dwordx4 v[14:17], v[14:15], off offset:48
	s_waitcnt vmcnt(2)
	v_mov_b32_e32 v22, v7
	s_waitcnt vmcnt(1)
	v_mov_b32_e32 v20, v11
	v_mov_b32_e32 v21, v12
	v_mov_b32_e32 v23, v8
	v_mov_b32_e32 v11, v13
	v_mov_b32_e32 v7, v9
	v_mov_b32_e32 v8, v3
	v_pk_add_f32 v[10:11], v[20:21], v[10:11]
	v_pk_add_f32 v[6:7], v[22:23], v[6:7]
	v_pk_add_f32 v[2:3], v[2:3], v[8:9]
	v_mov_b32_e32 v8, v5
	v_pk_add_f32 v[10:11], v[10:11], v[10:11] op_sel:[0,1] op_sel_hi:[1,0]
	v_pk_add_f32 v[6:7], v[6:7], v[6:7] op_sel:[0,1] op_sel_hi:[1,0]
	v_pk_add_f32 v[4:5], v[4:5], v[8:9]
	s_waitcnt vmcnt(0)
	v_mov_b32_e32 v11, v14
	v_mov_b32_e32 v7, v15
	v_mov_b32_e32 v3, v16
	v_mov_b32_e32 v5, v17
	v_pk_add_f32 v[6:7], v[10:11], v[6:7]
	v_pk_add_f32 v[2:3], v[2:3], v[4:5]
	v_mov_b32_e32 v5, v18
	v_pk_add_f32 v[2:3], v[6:7], v[2:3]
	s_nop 0
	v_mov_b32_e32 v4, v2
	v_mov_b32_e32 v18, v3
	v_pk_add_f32 v[4:5], v[4:5], v[18:19]
	v_mov_b64_e32 v[2:3], s[18:19]
	s_mov_b32 s18, 0x3a800000
	v_pk_fma_f32 v[100:101], v[4:5], s[18:19], v[2:3] op_sel_hi:[1,0,0]
	s_nop 0
	v_mul_f32_e32 v1, 0x4b800000, v101
	v_cmp_gt_f32_e32 vcc, s1, v101
	v_cmp_gt_f32_e64 s[44:45], s1, v100
	s_nop 0
	v_cndmask_b32_e32 v1, v101, v1, vcc
	v_rsq_f32_e32 v1, v1
	s_nop 0
	v_mul_f32_e32 v4, 0x45800000, v1
	v_cndmask_b32_e32 v101, v1, v4, vcc
	v_or_b32_e32 v4, 32, v0
	v_ashrrev_i32_e32 v5, 31, v4
	v_lshlrev_b64 v[4:5], 6, v[4:5]
	v_lshl_add_u64 v[16:17], s[16:17], 0, v[4:5]
	global_load_dwordx4 v[4:7], v[16:17], off offset:32
	global_load_dwordx4 v[8:11], v[16:17], off offset:16
	global_load_dwordx4 v[12:15], v[16:17], off
	s_nop 0
	global_load_dwordx4 v[16:19], v[16:17], off offset:48
	v_or_b32_e32 v0, 48, v0
	v_ashrrev_i32_e32 v1, 31, v0
	v_lshlrev_b64 v[0:1], 6, v[0:1]
	v_lshl_add_u64 v[0:1], s[16:17], 0, v[0:1]
	v_readlane_b32 s16, v254, 43
	v_readlane_b32 s17, v254, 44
	s_add_u32 s6, s16, s6
	s_addc_u32 s7, s17, s7
	s_waitcnt vmcnt(2)
; DI int TIDX() { int t = threadIdx.x; asm volatile("" : "+v"(t)); return t; }
; #define GL_LOAD(s_, kt_) if (VAR != 1) { a##s_##0 = GL_A(0, kt_); a##s_##1 = GL_A(1, kt_); a##s_##2 = GL_A(2, kt_); a##s_##3 = GL_A(3, kt_); b##s_##0 = GL_B(0, kt_); b##s_##1 = GL_B(1, kt_); b##s_##2 = GL_B(2, kt_); b##s_##3 = GL_B(3, kt_); }
; #define LDS_STORE(s_, buf_) if (VAR != 2) { LDS_ST1(sA, 0, buf_, a##s_##0) LDS_ST1(sA, 1, buf_, a##s_##1) LDS_ST1(sA, 2, buf_, a##s_##2) LDS_ST1(sA, 3, buf_, a##s_##3) LDS_ST1(sB, 0, buf_, b##s_##0) LDS_ST1(sB, 1, buf_, b##s_##1) LDS_ST1(sB, 2, buf_, b##s_##2) LDS_ST1(sB, 3, buf_, b##s_##3) }
;   const int tid = TIDX(), lane = tid & 63, wid = tid >> 6, wm = wid >> 1, wn = wid & 1, lr = lane & 15, g = lane >> 4;
;   char* sA = smem; char* sB = smem + 2 * LTILE;
;   uint4 a00 = {}, a01 = {}, a02 = {}, a03 = {}, b00 = {}, b01 = {}, b02 = {}, b03 = {}, a10 = {}, a11 = {}, a12 = {}, a13 = {}, b10 = {}, b11 = {}, b12 = {}, b13 = {};
;   constexpr int nk = NK;
;   const int sw0 = (g ^ ((lr >> 1) & 7)) << 4, sw1 = sw0 ^ 64;
;   const int r0 = tid >> 3, kc = tid & 7, kcs = kc ^ ((r0 >> 1) & 7);
;     ...
;   GL_LOAD(0, 0)
;   GL_LOAD(1, 1)
;   LDS_STORE(0, 0)
;   if (VAR != 4) __syncthreads();
; DI void load_rstd(float (&rs)[4], const float* ssq, int row0, int lr) {
; #pragma unroll
;   for (int mt = 0; mt < 4; ++mt) {
;     const float4* q = (const float4*)(ssq + (size_t)(row0 + mt * 16 + lr) * 16);
;     const float4 a = q[0], b = q[1], c = q[2], d = q[3];
;     const float s = ((a.x + a.y) + (a.z + a.w)) + ((b.x + b.y) + (b.z + b.w)) + ((c.x + c.y) + (c.z + c.w)) + ((d.x + d.y) + (d.z + d.w));
;     rs[mt] = rsqrtf(s * (1.0f / 1024.0f) + EPS);
;   }
; }
	v_mov_b32_e32 v22, v9
	s_waitcnt vmcnt(1)
	v_mov_b32_e32 v20, v13
	v_mov_b32_e32 v21, v14
	v_mov_b32_e32 v23, v10
	v_mov_b32_e32 v13, v15
	v_mov_b32_e32 v9, v11
	v_mov_b32_e32 v10, v5
	v_pk_add_f32 v[12:13], v[20:21], v[12:13]
	v_pk_add_f32 v[8:9], v[22:23], v[8:9]
	v_pk_add_f32 v[4:5], v[4:5], v[10:11]
	v_mov_b32_e32 v10, v7
	v_pk_add_f32 v[12:13], v[12:13], v[12:13] op_sel:[0,1] op_sel_hi:[1,0]
	v_pk_add_f32 v[8:9], v[8:9], v[8:9] op_sel:[0,1] op_sel_hi:[1,0]
	v_pk_add_f32 v[6:7], v[6:7], v[10:11]
	s_waitcnt vmcnt(0)
	v_mov_b32_e32 v13, v16
	v_mov_b32_e32 v9, v17
	v_mov_b32_e32 v5, v18
	v_mov_b32_e32 v7, v19
	v_pk_add_f32 v[8:9], v[12:13], v[8:9]
	v_pk_add_f32 v[4:5], v[4:5], v[6:7]
	s_nop 0
	v_pk_add_f32 v[20:21], v[8:9], v[4:5]
	global_load_dwordx4 v[4:7], v[0:1], off offset:32
	global_load_dwordx4 v[8:11], v[0:1], off offset:16
	global_load_dwordx4 v[12:15], v[0:1], off
	global_load_dwordx4 v[16:19], v[0:1], off offset:48
	s_waitcnt vmcnt(2)
	v_mov_b32_e32 v22, v9
	s_waitcnt vmcnt(1)
	v_mov_b32_e32 v0, v13
	v_mov_b32_e32 v1, v14
	v_mov_b32_e32 v23, v10
	v_mov_b32_e32 v13, v15
	v_mov_b32_e32 v9, v11
	v_mov_b32_e32 v10, v5
	v_pk_add_f32 v[0:1], v[0:1], v[12:13]
	v_pk_add_f32 v[8:9], v[22:23], v[8:9]
	v_pk_add_f32 v[4:5], v[4:5], v[10:11]
	v_mov_b32_e32 v10, v7
	v_pk_add_f32 v[0:1], v[0:1], v[0:1] op_sel:[0,1] op_sel_hi:[1,0]
	v_pk_add_f32 v[8:9], v[8:9], v[8:9] op_sel:[0,1] op_sel_hi:[1,0]
	v_pk_add_f32 v[6:7], v[6:7], v[10:11]
	s_waitcnt vmcnt(0)
	v_mov_b32_e32 v1, v16
	v_mov_b32_e32 v9, v17
	v_mov_b32_e32 v5, v18
	v_mov_b32_e32 v7, v19
	v_pk_add_f32 v[0:1], v[0:1], v[8:9]
	v_pk_add_f32 v[4:5], v[4:5], v[6:7]
	v_ashrrev_i32_e32 v64, 3, v72
	v_pk_add_f32 v[0:1], v[0:1], v[4:5]
	v_mov_b32_e32 v5, v20
	v_mov_b32_e32 v4, v0
	v_mov_b32_e32 v20, v1
	v_pk_add_f32 v[0:1], v[4:5], v[20:21]
	v_ashrrev_i32_e32 v65, 31, v64
	v_pk_fma_f32 v[98:99], v[0:1], s[18:19], v[2:3] op_sel_hi:[1,0,0]
	v_lshlrev_b32_e32 v0, 3, v72
	v_and_b32_e32 v75, 48, v72
	v_lshlrev_b64 v[16:17], 11, v[64:65]
	v_lshlrev_b32_e32 v65, 4, v72
	v_and_b32_e32 v74, 0x70, v0
	v_bitop3_b32 v129, v0, v75, s23 bitop3:0x6c
	v_lshl_add_u64 v[0:1], s[6:7], 0, v[16:17]
	v_and_b32_e32 v150, 0x70, v65
	v_add_u32_e32 v66, 32, v64
	v_add_u32_e32 v68, 64, v64
	v_add_u32_e32 v70, 0x60, v64
	v_cmp_gt_f32_e64 s[38:39], s1, v98
	v_cmp_gt_f32_e64 s[40:41], s1, v99
	s_lshl_b32 s1, s2, 11
	v_lshl_add_u64 v[104:105], v[0:1], 0, v[150:151]
	v_ashrrev_i32_e32 v67, 31, v66
	v_ashrrev_i32_e32 v69, 31, v68
	v_ashrrev_i32_e32 v71, 31, v70
	s_add_u32 s16, s11, s1
	global_load_dwordx4 v[0:3], v[104:105], off
	v_lshlrev_b64 v[20:21], 11, v[66:67]
	v_lshlrev_b64 v[24:25], 11, v[68:69]
	v_lshlrev_b64 v[28:29], 11, v[70:71]
	s_addc_u32 s17, s12, 0
	v_lshl_add_u64 v[4:5], s[6:7], 0, v[20:21]
	v_lshl_add_u64 v[8:9], s[6:7], 0, v[24:25]
	v_lshl_add_u64 v[12:13], s[6:7], 0, v[28:29]
	v_lshl_add_u64 v[106:107], v[4:5], 0, v[150:151]
	v_lshl_add_u64 v[108:109], v[8:9], 0, v[150:151]
	v_lshl_add_u64 v[110:111], v[12:13], 0, v[150:151]
	v_lshl_add_u64 v[16:17], s[16:17], 0, v[16:17]
	global_load_dwordx4 v[4:7], v[106:107], off
	global_load_dwordx4 v[8:11], v[108:109], off
	global_load_dwordx4 v[12:15], v[110:111], off
	v_lshl_add_u64 v[112:113], v[16:17], 0, v[150:151]
	v_lshl_add_u64 v[20:21], s[16:17], 0, v[20:21]
	global_load_dwordx4 v[16:19], v[112:113], off
	v_lshl_add_u64 v[114:115], v[20:21], 0, v[150:151]
	v_lshl_add_u64 v[24:25], s[16:17], 0, v[24:25]
	global_load_dwordx4 v[20:23], v[114:115], off
	v_lshl_add_u64 v[116:117], v[24:25], 0, v[150:151]
	global_load_dwordx4 v[24:27], v[116:117], off
	v_lshl_add_u64 v[28:29], s[16:17], 0, v[28:29]
	v_lshl_add_u64 v[118:119], v[28:29], 0, v[150:151]
	global_load_dwordx4 v[28:31], v[118:119], off
	global_load_dwordx4 v[32:35], v[104:105], off offset:128
	global_load_dwordx4 v[36:39], v[106:107], off offset:128
	global_load_dwordx4 v[40:43], v[108:109], off offset:128
	global_load_dwordx4 v[44:47], v[110:111], off offset:128
	global_load_dwordx4 v[48:51], v[112:113], off offset:128
	global_load_dwordx4 v[52:55], v[114:115], off offset:128
	global_load_dwordx4 v[56:59], v[116:117], off offset:128
	global_load_dwordx4 v[60:63], v[118:119], off offset:128
	v_bitop3_b32 v65, v65, s23, v72 bitop3:0x48
	v_lshl_or_b32 v126, v64, 7, v65
	v_and_b32_e32 v73, 15, v72
	v_lshl_or_b32 v124, v66, 7, v65
	v_lshl_or_b32 v125, v68, 7, v65
	v_lshl_or_b32 v127, v70, 7, v65
	v_xor_b32_e32 v130, 64, v129
	v_readlane_b32 s16, v254, 55
	v_readlane_b32 s6, v253, 11
	v_readlane_b32 s17, v254, 56
	v_readlane_b32 s7, v253, 12
	v_readlane_b32 s18, v254, 57
	v_readlane_b32 s19, v254, 58
	s_waitcnt vmcnt(15)
	ds_write_b128 v126, v[0:3]
	v_lshrrev_b32_e32 v0, 1, v72
	v_and_or_b32 v0, v0, s24, v73
	v_lshlrev_b32_e32 v150, 7, v0
	v_lshlrev_b32_e32 v0, 7, v72
	v_and_b32_e32 v170, 0x2780, v0
	v_bitop3_b32 v128, v150, v74, v75 bitop3:0xf6
	v_or_b32_e32 v131, v170, v129
	v_bitop3_b32 v129, v150, v129, 64 bitop3:0xf6
	v_or_b32_e32 v130, v170, v130
	s_waitcnt vmcnt(14)
	ds_write_b128 v124, v[4:7]
	s_waitcnt vmcnt(13)
	ds_write_b128 v125, v[8:11]
	s_waitcnt vmcnt(12)
	ds_write_b128 v127, v[12:15]
	s_waitcnt vmcnt(11)
	ds_write_b128 v126, v[16:19] offset:32768
	s_waitcnt vmcnt(10)
	ds_write_b128 v124, v[20:23] offset:32768
	s_waitcnt vmcnt(9)
	ds_write_b128 v125, v[24:27] offset:32768
	s_waitcnt vmcnt(8)
	ds_write_b128 v127, v[28:31] offset:32768
	s_waitcnt lgkmcnt(0)
	s_barrier
; #define GL_LOAD(s_, kt_) if (VAR != 1) { a##s_##0 = GL_A(0, kt_); a##s_##1 = GL_A(1, kt_); a##s_##2 = GL_A(2, kt_); a##s_##3 = GL_A(3, kt_); b##s_##0 = GL_B(0, kt_); b##s_##1 = GL_B(1, kt_); b##s_##2 = GL_B(2, kt_); b##s_##3 = GL_B(3, kt_); }
; #define LDS_STORE(s_, buf_) if (VAR != 2) { LDS_ST1(sA, 0, buf_, a##s_##0) LDS_ST1(sA, 1, buf_, a##s_##1) LDS_ST1(sA, 2, buf_, a##s_##2) LDS_ST1(sA, 3, buf_, a##s_##3) LDS_ST1(sB, 0, buf_, b##s_##0) LDS_ST1(sB, 1, buf_, b##s_##1) LDS_ST1(sB, 2, buf_, b##s_##2) LDS_ST1(sB, 3, buf_, b##s_##3) }
;     ...
;   GL_LOAD(0, 0)
;   GL_LOAD(1, 1)
;   LDS_STORE(0, 0)
;   if (VAR != 4) __syncthreads();
; #pragma unroll
;   for (int kt = 0; kt < nk; kt += 2) {
;     if (kt + 2 < nk) { GL_LOAD(0, kt + 2) }
;     MMA_TILE(0)
;     LDS_STORE(1, 1)
;     if (VAR != 4) __syncthreads();
;     if (kt + 3 < nk) { GL_LOAD(1, kt + 3) }
;     MMA_TILE(1)
;     if (kt + 2 < nk) { LDS_STORE(0, 0) }
;     if (VAR != 4) __syncthreads();
	global_load_dwordx4 v[0:3], v[104:105], off offset:256
	global_load_dwordx4 v[4:7], v[106:107], off offset:256
	global_load_dwordx4 v[8:11], v[108:109], off offset:256
	global_load_dwordx4 v[12:15], v[110:111], off offset:256
	global_load_dwordx4 v[16:19], v[112:113], off offset:256
	global_load_dwordx4 v[20:23], v[114:115], off offset:256
	global_load_dwordx4 v[24:27], v[116:117], off offset:256
	global_load_dwordx4 v[28:31], v[118:119], off offset:256
	ds_read_b128 v[64:67], v128
	ds_read_b128 v[68:71], v131 offset:32768
	ds_read_b128 v[72:75], v128 offset:2048
	ds_read_b128 v[76:79], v131 offset:34816
	ds_read_b128 v[80:83], v128 offset:4096
	ds_read_b128 v[84:87], v131 offset:36864
	ds_read_b128 v[88:91], v128 offset:6144
	ds_read_b128 v[92:95], v131 offset:38912
	s_waitcnt lgkmcnt(6)
	v_mfma_f32_16x16x32_f16 v[132:135], v[68:71], v[64:67], 0
	s_waitcnt lgkmcnt(4)
	v_mfma_f32_16x16x32_f16 v[136:139], v[76:79], v[64:67], 0
	s_waitcnt lgkmcnt(2)
	v_mfma_f32_16x16x32_f16 v[140:143], v[84:87], v[64:67], 0
	s_waitcnt lgkmcnt(0)
	v_mfma_f32_16x16x32_f16 v[64:67], v[92:95], v[64:67], 0
	v_mfma_f32_16x16x32_f16 v[144:147], v[68:71], v[72:75], 0
	v_mfma_f32_16x16x32_f16 v[154:157], v[76:79], v[72:75], 0
	v_mfma_f32_16x16x32_f16 v[158:161], v[84:87], v[72:75], 0
	v_mfma_f32_16x16x32_f16 v[72:75], v[92:95], v[72:75], 0
	v_mfma_f32_16x16x32_f16 v[162:165], v[68:71], v[80:83], 0
	v_mfma_f32_16x16x32_f16 v[166:169], v[76:79], v[80:83], 0
	v_mfma_f32_16x16x32_f16 v[190:193], v[84:87], v[80:83], 0
	v_mfma_f32_16x16x32_f16 v[80:83], v[92:95], v[80:83], 0
	v_mfma_f32_16x16x32_f16 v[68:71], v[68:71], v[88:91], 0
	v_mfma_f32_16x16x32_f16 v[76:79], v[76:79], v[88:91], 0
	v_mfma_f32_16x16x32_f16 v[84:87], v[84:87], v[88:91], 0
	v_mfma_f32_16x16x32_f16 v[88:91], v[92:95], v[88:91], 0
	ds_read_b128 v[92:95], v129
	ds_read_b128 v[194:197], v130 offset:32768
	ds_read_b128 v[198:201], v129 offset:2048
	ds_read_b128 v[202:205], v130 offset:34816
	ds_read_b128 v[206:209], v129 offset:4096
	ds_read_b128 v[210:213], v130 offset:36864
	ds_read_b128 v[220:223], v129 offset:6144
	ds_read_b128 v[224:227], v130 offset:38912
	s_waitcnt vmcnt(15)
	ds_write_b128 v126, v[32:35] offset:16384
	s_waitcnt vmcnt(14)
	ds_write_b128 v124, v[36:39] offset:16384
	s_waitcnt vmcnt(13)
	ds_write_b128 v125, v[40:43] offset:16384
	s_waitcnt vmcnt(12)
	ds_write_b128 v127, v[44:47] offset:16384
	s_waitcnt vmcnt(11)
	ds_write_b128 v126, v[48:51] offset:49152
	s_waitcnt vmcnt(10)
	ds_write_b128 v124, v[52:55] offset:49152
	s_waitcnt vmcnt(9)
	ds_write_b128 v125, v[56:59] offset:49152
	s_waitcnt vmcnt(8)
	ds_write_b128 v127, v[60:63] offset:49152
	s_waitcnt lgkmcnt(0)
	s_barrier
	v_mfma_f32_16x16x32_f16 v[132:135], v[194:197], v[92:95], v[132:135]
	global_load_dwordx4 v[32:35], v[104:105], off offset:384
	v_mfma_f32_16x16x32_f16 v[136:139], v[202:205], v[92:95], v[136:139]
	v_mfma_f32_16x16x32_f16 v[140:143], v[210:213], v[92:95], v[140:143]
	v_mfma_f32_16x16x32_f16 v[64:67], v[224:227], v[92:95], v[64:67]
	v_mfma_f32_16x16x32_f16 v[92:95], v[194:197], v[198:201], v[144:147]
	global_load_dwordx4 v[36:39], v[106:107], off offset:384
	global_load_dwordx4 v[40:43], v[108:109], off offset:384
	global_load_dwordx4 v[44:47], v[110:111], off offset:384
	v_mfma_f32_16x16x32_f16 v[144:147], v[202:205], v[198:201], v[154:157]
	global_load_dwordx4 v[48:51], v[112:113], off offset:384
	v_mfma_f32_16x16x32_f16 v[154:157], v[210:213], v[198:201], v[158:161]
	v_mfma_f32_16x16x32_f16 v[158:161], v[194:197], v[206:209], v[162:165]
	global_load_dwordx4 v[52:55], v[114:115], off offset:384
	global_load_dwordx4 v[56:59], v[116:117], off offset:384
	v_mfma_f32_16x16x32_f16 v[68:71], v[194:197], v[220:223], v[68:71]
	ds_read_b128 v[194:197], v131 offset:49152
	v_mfma_f32_16x16x32_f16 v[162:165], v[202:205], v[206:209], v[166:169]
	global_load_dwordx4 v[60:63], v[118:119], off offset:384
	v_mfma_f32_16x16x32_f16 v[76:79], v[202:205], v[220:223], v[76:79]
	ds_read_b128 v[202:205], v131 offset:51200
	v_mfma_f32_16x16x32_f16 v[72:75], v[224:227], v[198:201], v[72:75]
	ds_read_b128 v[198:201], v128 offset:18432
	v_mfma_f32_16x16x32_f16 v[166:169], v[210:213], v[206:209], v[190:193]
	s_nop 2
	ds_read_b128 v[190:193], v128 offset:16384
	v_mfma_f32_16x16x32_f16 v[84:87], v[210:213], v[220:223], v[84:87]
	ds_read_b128 v[210:213], v131 offset:53248
	v_mfma_f32_16x16x32_f16 v[80:83], v[224:227], v[206:209], v[80:83]
	ds_read_b128 v[206:209], v128 offset:20480
	v_mfma_f32_16x16x32_f16 v[88:91], v[224:227], v[220:223], v[88:91]
	ds_read_b128 v[220:223], v128 offset:22528
	s_waitcnt lgkmcnt(3)
	v_mfma_f32_16x16x32_f16 v[132:135], v[194:197], v[190:193], v[132:135]
	ds_read_b128 v[224:227], v131 offset:55296
	v_mfma_f32_16x16x32_f16 v[92:95], v[194:197], v[198:201], v[92:95]
	s_waitcnt vmcnt(15)
	ds_write_b128 v126, v[0:3]
	v_mfma_f32_16x16x32_f16 v[136:139], v[202:205], v[190:193], v[136:139]
	s_waitcnt vmcnt(14)
	ds_write_b128 v124, v[4:7]
	v_mfma_f32_16x16x32_f16 v[144:147], v[202:205], v[198:201], v[144:147]
	s_waitcnt vmcnt(13)
	ds_write_b128 v125, v[8:11]
	s_waitcnt lgkmcnt(5)
	v_mfma_f32_16x16x32_f16 v[158:161], v[194:197], v[206:209], v[158:161]
	s_waitcnt vmcnt(12)
	ds_write_b128 v127, v[12:15]
	s_waitcnt lgkmcnt(5)
	v_mfma_f32_16x16x32_f16 v[68:71], v[194:197], v[220:223], v[68:71]
	ds_read_b128 v[194:197], v130 offset:49152
	v_mfma_f32_16x16x32_f16 v[162:165], v[202:205], v[206:209], v[162:165]
	s_waitcnt vmcnt(11)
	ds_write_b128 v126, v[16:19] offset:32768
	v_mfma_f32_16x16x32_f16 v[76:79], v[202:205], v[220:223], v[76:79]
	ds_read_b128 v[202:205], v130 offset:51200
	v_mfma_f32_16x16x32_f16 v[140:143], v[210:213], v[190:193], v[140:143]
	s_waitcnt vmcnt(10)
	ds_write_b128 v124, v[20:23] offset:32768
	v_mfma_f32_16x16x32_f16 v[154:157], v[210:213], v[198:201], v[154:157]
	s_waitcnt vmcnt(9)
	ds_write_b128 v125, v[24:27] offset:32768
	s_waitcnt lgkmcnt(9)
	v_mfma_f32_16x16x32_f16 v[64:67], v[224:227], v[190:193], v[64:67]
	ds_read_b128 v[190:193], v129 offset:16384
	v_mfma_f32_16x16x32_f16 v[72:75], v[224:227], v[198:201], v[72:75]
	ds_read_b128 v[198:201], v129 offset:18432
	v_mfma_f32_16x16x32_f16 v[166:169], v[210:213], v[206:209], v[166:169]
	s_waitcnt vmcnt(8)
	ds_write_b128 v127, v[28:31] offset:32768
	v_mfma_f32_16x16x32_f16 v[84:87], v[210:213], v[220:223], v[84:87]
	ds_read_b128 v[210:213], v130 offset:53248
	v_mfma_f32_16x16x32_f16 v[80:83], v[224:227], v[206:209], v[80:83]
	ds_read_b128 v[206:209], v129 offset:20480
	v_mfma_f32_16x16x32_f16 v[88:91], v[224:227], v[220:223], v[88:91]
	ds_read_b128 v[220:223], v129 offset:22528
	ds_read_b128 v[224:227], v130 offset:55296
	s_waitcnt lgkmcnt(0)
	s_barrier
; #define GL_LOAD(s_, kt_) if (VAR != 1) { a##s_##0 = GL_A(0, kt_); a##s_##1 = GL_A(1, kt_); a##s_##2 = GL_A(2, kt_); a##s_##3 = GL_A(3, kt_); b##s_##0 = GL_B(0, kt_); b##s_##1 = GL_B(1, kt_); b##s_##2 = GL_B(2, kt_); b##s_##3 = GL_B(3, kt_); }
; #define LDS_STORE(s_, buf_) if (VAR != 2) { LDS_ST1(sA, 0, buf_, a##s_##0) LDS_ST1(sA, 1, buf_, a##s_##1) LDS_ST1(sA, 2, buf_, a##s_##2) LDS_ST1(sA, 3, buf_, a##s_##3) LDS_ST1(sB, 0, buf_, b##s_##0) LDS_ST1(sB, 1, buf_, b##s_##1) LDS_ST1(sB, 2, buf_, b##s_##2) LDS_ST1(sB, 3, buf_, b##s_##3) }
;     ...
;   GL_LOAD(0, 0)
;   GL_LOAD(1, 1)
;   LDS_STORE(0, 0)
;   if (VAR != 4) __syncthreads();
; #pragma unroll
;   for (int kt = 0; kt < nk; kt += 2) {
;     if (kt + 2 < nk) { GL_LOAD(0, kt + 2) }
;     MMA_TILE(0)
;     LDS_STORE(1, 1)
;     if (VAR != 4) __syncthreads();
;     if (kt + 3 < nk) { GL_LOAD(1, kt + 3) }
;     MMA_TILE(1)
;     if (kt + 2 < nk) { LDS_STORE(0, 0) }
;     if (VAR != 4) __syncthreads();
	v_mfma_f32_16x16x32_f16 v[132:135], v[194:197], v[190:193], v[132:135]
	global_load_dwordx4 v[0:3], v[104:105], off offset:512
	v_mfma_f32_16x16x32_f16 v[92:95], v[194:197], v[198:201], v[92:95]
	global_load_dwordx4 v[4:7], v[106:107], off offset:512
	v_mfma_f32_16x16x32_f16 v[136:139], v[202:205], v[190:193], v[136:139]
	global_load_dwordx4 v[8:11], v[108:109], off offset:512
	v_mfma_f32_16x16x32_f16 v[144:147], v[202:205], v[198:201], v[144:147]
	global_load_dwordx4 v[12:15], v[110:111], off offset:512
	v_mfma_f32_16x16x32_f16 v[158:161], v[194:197], v[206:209], v[158:161]
	global_load_dwordx4 v[16:19], v[112:113], off offset:512
	v_mfma_f32_16x16x32_f16 v[68:71], v[194:197], v[220:223], v[68:71]
	ds_read_b128 v[194:197], v131 offset:32768
	v_mfma_f32_16x16x32_f16 v[162:165], v[202:205], v[206:209], v[162:165]
	global_load_dwordx4 v[20:23], v[114:115], off offset:512
	v_mfma_f32_16x16x32_f16 v[76:79], v[202:205], v[220:223], v[76:79]
	ds_read_b128 v[202:205], v131 offset:34816
	v_mfma_f32_16x16x32_f16 v[140:143], v[210:213], v[190:193], v[140:143]
	global_load_dwordx4 v[24:27], v[116:117], off offset:512
	v_mfma_f32_16x16x32_f16 v[154:157], v[210:213], v[198:201], v[154:157]
	global_load_dwordx4 v[28:31], v[118:119], off offset:512
	v_mfma_f32_16x16x32_f16 v[64:67], v[224:227], v[190:193], v[64:67]
	ds_read_b128 v[190:193], v128
	v_mfma_f32_16x16x32_f16 v[72:75], v[224:227], v[198:201], v[72:75]
	ds_read_b128 v[198:201], v128 offset:2048
	v_mfma_f32_16x16x32_f16 v[166:169], v[210:213], v[206:209], v[166:169]
	v_mfma_f32_16x16x32_f16 v[84:87], v[210:213], v[220:223], v[84:87]
	ds_read_b128 v[210:213], v131 offset:36864
	v_mfma_f32_16x16x32_f16 v[80:83], v[224:227], v[206:209], v[80:83]
	ds_read_b128 v[206:209], v128 offset:4096
	v_mfma_f32_16x16x32_f16 v[88:91], v[224:227], v[220:223], v[88:91]
	ds_read_b128 v[220:223], v128 offset:6144
	s_waitcnt lgkmcnt(4)
	v_mfma_f32_16x16x32_f16 v[132:135], v[194:197], v[190:193], v[132:135]
	ds_read_b128 v[224:227], v131 offset:38912
	s_waitcnt lgkmcnt(4)
	v_mfma_f32_16x16x32_f16 v[92:95], v[194:197], v[198:201], v[92:95]
	s_waitcnt vmcnt(15)
	ds_write_b128 v126, v[32:35] offset:16384
	v_mfma_f32_16x16x32_f16 v[136:139], v[202:205], v[190:193], v[136:139]
	s_waitcnt vmcnt(14)
	ds_write_b128 v124, v[36:39] offset:16384
	v_mfma_f32_16x16x32_f16 v[144:147], v[202:205], v[198:201], v[144:147]
	s_waitcnt vmcnt(13)
	ds_write_b128 v125, v[40:43] offset:16384
	s_waitcnt lgkmcnt(5)
	v_mfma_f32_16x16x32_f16 v[158:161], v[194:197], v[206:209], v[158:161]
	s_waitcnt vmcnt(12)
	ds_write_b128 v127, v[44:47] offset:16384
	s_waitcnt lgkmcnt(5)
	v_mfma_f32_16x16x32_f16 v[68:71], v[194:197], v[220:223], v[68:71]
	ds_read_b128 v[194:197], v130 offset:32768
	v_mfma_f32_16x16x32_f16 v[162:165], v[202:205], v[206:209], v[162:165]
	s_waitcnt vmcnt(11)
	ds_write_b128 v126, v[48:51] offset:49152
	v_mfma_f32_16x16x32_f16 v[76:79], v[202:205], v[220:223], v[76:79]
	ds_read_b128 v[202:205], v130 offset:34816
	v_mfma_f32_16x16x32_f16 v[140:143], v[210:213], v[190:193], v[140:143]
	s_waitcnt vmcnt(10)
	ds_write_b128 v124, v[52:55] offset:49152
	v_mfma_f32_16x16x32_f16 v[154:157], v[210:213], v[198:201], v[154:157]
	s_waitcnt vmcnt(9)
	ds_write_b128 v125, v[56:59] offset:49152
	s_waitcnt lgkmcnt(9)
	v_mfma_f32_16x16x32_f16 v[64:67], v[224:227], v[190:193], v[64:67]
	ds_read_b128 v[190:193], v129
	v_mfma_f32_16x16x32_f16 v[72:75], v[224:227], v[198:201], v[72:75]
	ds_read_b128 v[198:201], v129 offset:2048
	v_mfma_f32_16x16x32_f16 v[166:169], v[210:213], v[206:209], v[166:169]
	s_waitcnt vmcnt(8)
	ds_write_b128 v127, v[60:63] offset:49152
	v_mfma_f32_16x16x32_f16 v[84:87], v[210:213], v[220:223], v[84:87]
	ds_read_b128 v[210:213], v130 offset:36864
	v_mfma_f32_16x16x32_f16 v[80:83], v[224:227], v[206:209], v[80:83]
	ds_read_b128 v[206:209], v129 offset:4096
	v_mfma_f32_16x16x32_f16 v[88:91], v[224:227], v[220:223], v[88:91]
	ds_read_b128 v[220:223], v129 offset:6144
	ds_read_b128 v[224:227], v130 offset:38912
	s_waitcnt lgkmcnt(0)
	s_barrier
	v_mfma_f32_16x16x32_f16 v[132:135], v[194:197], v[190:193], v[132:135]
	global_load_dwordx4 v[32:35], v[104:105], off offset:640
	v_mfma_f32_16x16x32_f16 v[92:95], v[194:197], v[198:201], v[92:95]
	global_load_dwordx4 v[36:39], v[106:107], off offset:640
	v_mfma_f32_16x16x32_f16 v[136:139], v[202:205], v[190:193], v[136:139]
	global_load_dwordx4 v[40:43], v[108:109], off offset:640
	v_mfma_f32_16x16x32_f16 v[144:147], v[202:205], v[198:201], v[144:147]
	global_load_dwordx4 v[44:47], v[110:111], off offset:640
	v_mfma_f32_16x16x32_f16 v[158:161], v[194:197], v[206:209], v[158:161]
	global_load_dwordx4 v[48:51], v[112:113], off offset:640
	v_mfma_f32_16x16x32_f16 v[68:71], v[194:197], v[220:223], v[68:71]
	ds_read_b128 v[194:197], v131 offset:49152
	v_mfma_f32_16x16x32_f16 v[162:165], v[202:205], v[206:209], v[162:165]
	global_load_dwordx4 v[52:55], v[114:115], off offset:640
	v_mfma_f32_16x16x32_f16 v[76:79], v[202:205], v[220:223], v[76:79]
	ds_read_b128 v[202:205], v131 offset:51200
	v_mfma_f32_16x16x32_f16 v[140:143], v[210:213], v[190:193], v[140:143]
	global_load_dwordx4 v[56:59], v[116:117], off offset:640
	v_mfma_f32_16x16x32_f16 v[154:157], v[210:213], v[198:201], v[154:157]
	global_load_dwordx4 v[60:63], v[118:119], off offset:640
	v_mfma_f32_16x16x32_f16 v[64:67], v[224:227], v[190:193], v[64:67]
	ds_read_b128 v[190:193], v128 offset:16384
	v_mfma_f32_16x16x32_f16 v[72:75], v[224:227], v[198:201], v[72:75]
	ds_read_b128 v[198:201], v128 offset:18432
	v_mfma_f32_16x16x32_f16 v[166:169], v[210:213], v[206:209], v[166:169]
	v_mfma_f32_16x16x32_f16 v[84:87], v[210:213], v[220:223], v[84:87]
	ds_read_b128 v[210:213], v131 offset:53248
	v_mfma_f32_16x16x32_f16 v[80:83], v[224:227], v[206:209], v[80:83]
	ds_read_b128 v[206:209], v128 offset:20480
	v_mfma_f32_16x16x32_f16 v[88:91], v[224:227], v[220:223], v[88:91]
	ds_read_b128 v[220:223], v128 offset:22528
	s_waitcnt lgkmcnt(4)
; #define GL_LOAD(s_, kt_) if (VAR != 1) { a##s_##0 = GL_A(0, kt_); a##s_##1 = GL_A(1, kt_); a##s_##2 = GL_A(2, kt_); a##s_##3 = GL_A(3, kt_); b##s_##0 = GL_B(0, kt_); b##s_##1 = GL_B(1, kt_); b##s_##2 = GL_B(2, kt_); b##s_##3 = GL_B(3, kt_); }
; #define LDS_STORE(s_, buf_) if (VAR != 2) { LDS_ST1(sA, 0, buf_, a##s_##0) LDS_ST1(sA, 1, buf_, a##s_##1) LDS_ST1(sA, 2, buf_, a##s_##2) LDS_ST1(sA, 3, buf_, a##s_##3) LDS_ST1(sB, 0, buf_, b##s_##0) LDS_ST1(sB, 1, buf_, b##s_##1) LDS_ST1(sB, 2, buf_, b##s_##2) LDS_ST1(sB, 3, buf_, b##s_##3) }
;     ...
;   GL_LOAD(0, 0)
;   GL_LOAD(1, 1)
;   LDS_STORE(0, 0)
;   if (VAR != 4) __syncthreads();
; #pragma unroll
;   for (int kt = 0; kt < nk; kt += 2) {
;     if (kt + 2 < nk) { GL_LOAD(0, kt + 2) }
;     MMA_TILE(0)
;     LDS_STORE(1, 1)
;     if (VAR != 4) __syncthreads();
;     if (kt + 3 < nk) { GL_LOAD(1, kt + 3) }
;     MMA_TILE(1)
;     if (kt + 2 < nk) { LDS_STORE(0, 0) }
;     if (VAR != 4) __syncthreads();
	v_mfma_f32_16x16x32_f16 v[132:135], v[194:197], v[190:193], v[132:135]
	ds_read_b128 v[224:227], v131 offset:55296
	s_waitcnt lgkmcnt(4)
	v_mfma_f32_16x16x32_f16 v[92:95], v[194:197], v[198:201], v[92:95]
	s_waitcnt vmcnt(15)
	ds_write_b128 v126, v[0:3]
	v_mfma_f32_16x16x32_f16 v[136:139], v[202:205], v[190:193], v[136:139]
	s_waitcnt vmcnt(14)
	ds_write_b128 v124, v[4:7]
	v_mfma_f32_16x16x32_f16 v[144:147], v[202:205], v[198:201], v[144:147]
	s_waitcnt vmcnt(13)
	ds_write_b128 v125, v[8:11]
	s_waitcnt lgkmcnt(5)
	v_mfma_f32_16x16x32_f16 v[158:161], v[194:197], v[206:209], v[158:161]
	s_waitcnt vmcnt(12)
	ds_write_b128 v127, v[12:15]
	s_waitcnt lgkmcnt(5)
	v_mfma_f32_16x16x32_f16 v[68:71], v[194:197], v[220:223], v[68:71]
	ds_read_b128 v[194:197], v130 offset:49152
	v_mfma_f32_16x16x32_f16 v[162:165], v[202:205], v[206:209], v[162:165]
	s_waitcnt vmcnt(11)
	ds_write_b128 v126, v[16:19] offset:32768
	v_mfma_f32_16x16x32_f16 v[76:79], v[202:205], v[220:223], v[76:79]
	ds_read_b128 v[202:205], v130 offset:51200
	v_mfma_f32_16x16x32_f16 v[140:143], v[210:213], v[190:193], v[140:143]
	s_waitcnt vmcnt(10)
	ds_write_b128 v124, v[20:23] offset:32768
	v_mfma_f32_16x16x32_f16 v[154:157], v[210:213], v[198:201], v[154:157]
	s_waitcnt vmcnt(9)
	ds_write_b128 v125, v[24:27] offset:32768
	s_waitcnt lgkmcnt(9)
	v_mfma_f32_16x16x32_f16 v[64:67], v[224:227], v[190:193], v[64:67]
	ds_read_b128 v[190:193], v129 offset:16384
	v_mfma_f32_16x16x32_f16 v[72:75], v[224:227], v[198:201], v[72:75]
	ds_read_b128 v[198:201], v129 offset:18432
	v_mfma_f32_16x16x32_f16 v[166:169], v[210:213], v[206:209], v[166:169]
	s_waitcnt vmcnt(8)
	ds_write_b128 v127, v[28:31] offset:32768
	v_mfma_f32_16x16x32_f16 v[84:87], v[210:213], v[220:223], v[84:87]
	ds_read_b128 v[210:213], v130 offset:53248
	v_mfma_f32_16x16x32_f16 v[80:83], v[224:227], v[206:209], v[80:83]
	ds_read_b128 v[206:209], v129 offset:20480
	v_mfma_f32_16x16x32_f16 v[88:91], v[224:227], v[220:223], v[88:91]
	ds_read_b128 v[220:223], v129 offset:22528
	ds_read_b128 v[224:227], v130 offset:55296
	s_waitcnt lgkmcnt(0)
	s_barrier
	v_mfma_f32_16x16x32_f16 v[132:135], v[194:197], v[190:193], v[132:135]
	global_load_dwordx4 v[0:3], v[104:105], off offset:768
	v_mfma_f32_16x16x32_f16 v[92:95], v[194:197], v[198:201], v[92:95]
	global_load_dwordx4 v[4:7], v[106:107], off offset:768
	v_mfma_f32_16x16x32_f16 v[136:139], v[202:205], v[190:193], v[136:139]
	global_load_dwordx4 v[8:11], v[108:109], off offset:768
	v_mfma_f32_16x16x32_f16 v[144:147], v[202:205], v[198:201], v[144:147]
	global_load_dwordx4 v[12:15], v[110:111], off offset:768
	v_mfma_f32_16x16x32_f16 v[158:161], v[194:197], v[206:209], v[158:161]
	global_load_dwordx4 v[16:19], v[112:113], off offset:768
	v_mfma_f32_16x16x32_f16 v[68:71], v[194:197], v[220:223], v[68:71]
	ds_read_b128 v[194:197], v131 offset:32768
	v_mfma_f32_16x16x32_f16 v[162:165], v[202:205], v[206:209], v[162:165]
	global_load_dwordx4 v[20:23], v[114:115], off offset:768
	v_mfma_f32_16x16x32_f16 v[76:79], v[202:205], v[220:223], v[76:79]
	ds_read_b128 v[202:205], v131 offset:34816
	v_mfma_f32_16x16x32_f16 v[140:143], v[210:213], v[190:193], v[140:143]
	global_load_dwordx4 v[24:27], v[116:117], off offset:768
	v_mfma_f32_16x16x32_f16 v[154:157], v[210:213], v[198:201], v[154:157]
	global_load_dwordx4 v[28:31], v[118:119], off offset:768
	v_mfma_f32_16x16x32_f16 v[64:67], v[224:227], v[190:193], v[64:67]
	ds_read_b128 v[190:193], v128
	v_mfma_f32_16x16x32_f16 v[72:75], v[224:227], v[198:201], v[72:75]
	ds_read_b128 v[198:201], v128 offset:2048
	v_mfma_f32_16x16x32_f16 v[166:169], v[210:213], v[206:209], v[166:169]
	v_mfma_f32_16x16x32_f16 v[84:87], v[210:213], v[220:223], v[84:87]
	ds_read_b128 v[210:213], v131 offset:36864
	v_mfma_f32_16x16x32_f16 v[80:83], v[224:227], v[206:209], v[80:83]
	ds_read_b128 v[206:209], v128 offset:4096
	v_mfma_f32_16x16x32_f16 v[88:91], v[224:227], v[220:223], v[88:91]
	ds_read_b128 v[220:223], v128 offset:6144
	s_waitcnt lgkmcnt(4)
	v_mfma_f32_16x16x32_f16 v[132:135], v[194:197], v[190:193], v[132:135]
	ds_read_b128 v[224:227], v131 offset:38912
	s_waitcnt lgkmcnt(4)
	v_mfma_f32_16x16x32_f16 v[92:95], v[194:197], v[198:201], v[92:95]
	s_waitcnt vmcnt(15)
	ds_write_b128 v126, v[32:35] offset:16384
	v_mfma_f32_16x16x32_f16 v[136:139], v[202:205], v[190:193], v[136:139]
	s_waitcnt vmcnt(14)
	ds_write_b128 v124, v[36:39] offset:16384
	v_mfma_f32_16x16x32_f16 v[144:147], v[202:205], v[198:201], v[144:147]
	s_waitcnt vmcnt(13)
	ds_write_b128 v125, v[40:43] offset:16384
	s_waitcnt lgkmcnt(5)
	v_mfma_f32_16x16x32_f16 v[158:161], v[194:197], v[206:209], v[158:161]
	s_waitcnt vmcnt(12)
	ds_write_b128 v127, v[44:47] offset:16384
	s_waitcnt lgkmcnt(5)
	v_mfma_f32_16x16x32_f16 v[68:71], v[194:197], v[220:223], v[68:71]
	ds_read_b128 v[194:197], v130 offset:32768
	v_mfma_f32_16x16x32_f16 v[162:165], v[202:205], v[206:209], v[162:165]
	s_waitcnt vmcnt(11)
	ds_write_b128 v126, v[48:51] offset:49152
	v_mfma_f32_16x16x32_f16 v[76:79], v[202:205], v[220:223], v[76:79]
	ds_read_b128 v[202:205], v130 offset:34816
	v_mfma_f32_16x16x32_f16 v[140:143], v[210:213], v[190:193], v[140:143]
	s_waitcnt vmcnt(10)
	ds_write_b128 v124, v[52:55] offset:49152
	v_mfma_f32_16x16x32_f16 v[154:157], v[210:213], v[198:201], v[154:157]
	s_waitcnt vmcnt(9)
	ds_write_b128 v125, v[56:59] offset:49152
	s_waitcnt lgkmcnt(9)
	v_mfma_f32_16x16x32_f16 v[64:67], v[224:227], v[190:193], v[64:67]
	ds_read_b128 v[190:193], v129
	v_mfma_f32_16x16x32_f16 v[72:75], v[224:227], v[198:201], v[72:75]
	ds_read_b128 v[198:201], v129 offset:2048
	v_mfma_f32_16x16x32_f16 v[166:169], v[210:213], v[206:209], v[166:169]
	s_waitcnt vmcnt(8)
	ds_write_b128 v127, v[60:63] offset:49152
	v_mfma_f32_16x16x32_f16 v[84:87], v[210:213], v[220:223], v[84:87]
	ds_read_b128 v[210:213], v130 offset:36864
	v_mfma_f32_16x16x32_f16 v[80:83], v[224:227], v[206:209], v[80:83]
	ds_read_b128 v[206:209], v129 offset:4096
	v_mfma_f32_16x16x32_f16 v[88:91], v[224:227], v[220:223], v[88:91]
	ds_read_b128 v[220:223], v129 offset:6144
	ds_read_b128 v[224:227], v130 offset:38912
	s_waitcnt lgkmcnt(0)
	s_barrier
; #define GL_LOAD(s_, kt_) if (VAR != 1) { a##s_##0 = GL_A(0, kt_); a##s_##1 = GL_A(1, kt_); a##s_##2 = GL_A(2, kt_); a##s_##3 = GL_A(3, kt_); b##s_##0 = GL_B(0, kt_); b##s_##1 = GL_B(1, kt_); b##s_##2 = GL_B(2, kt_); b##s_##3 = GL_B(3, kt_); }
; #define LDS_STORE(s_, buf_) if (VAR != 2) { LDS_ST1(sA, 0, buf_, a##s_##0) LDS_ST1(sA, 1, buf_, a##s_##1) LDS_ST1(sA, 2, buf_, a##s_##2) LDS_ST1(sA, 3, buf_, a##s_##3) LDS_ST1(sB, 0, buf_, b##s_##0) LDS_ST1(sB, 1, buf_, b##s_##1) LDS_ST1(sB, 2, buf_, b##s_##2) LDS_ST1(sB, 3, buf_, b##s_##3) }
;     ...
;   GL_LOAD(0, 0)
;   GL_LOAD(1, 1)
;   LDS_STORE(0, 0)
;   if (VAR != 4) __syncthreads();
; #pragma unroll
;   for (int kt = 0; kt < nk; kt += 2) {
;     if (kt + 2 < nk) { GL_LOAD(0, kt + 2) }
;     MMA_TILE(0)
;     LDS_STORE(1, 1)
;     if (VAR != 4) __syncthreads();
;     if (kt + 3 < nk) { GL_LOAD(1, kt + 3) }
;     MMA_TILE(1)
;     if (kt + 2 < nk) { LDS_STORE(0, 0) }
;     if (VAR != 4) __syncthreads();
	v_mfma_f32_16x16x32_f16 v[132:135], v[194:197], v[190:193], v[132:135]
	global_load_dwordx4 v[32:35], v[104:105], off offset:896
	v_mfma_f32_16x16x32_f16 v[92:95], v[194:197], v[198:201], v[92:95]
	global_load_dwordx4 v[36:39], v[106:107], off offset:896
	v_mfma_f32_16x16x32_f16 v[136:139], v[202:205], v[190:193], v[136:139]
	global_load_dwordx4 v[40:43], v[108:109], off offset:896
	v_mfma_f32_16x16x32_f16 v[144:147], v[202:205], v[198:201], v[144:147]
	global_load_dwordx4 v[44:47], v[110:111], off offset:896
	v_mfma_f32_16x16x32_f16 v[158:161], v[194:197], v[206:209], v[158:161]
	global_load_dwordx4 v[48:51], v[112:113], off offset:896
	v_mfma_f32_16x16x32_f16 v[68:71], v[194:197], v[220:223], v[68:71]
	ds_read_b128 v[194:197], v131 offset:49152
	v_mfma_f32_16x16x32_f16 v[162:165], v[202:205], v[206:209], v[162:165]
	global_load_dwordx4 v[52:55], v[114:115], off offset:896
	v_mfma_f32_16x16x32_f16 v[76:79], v[202:205], v[220:223], v[76:79]
	ds_read_b128 v[202:205], v131 offset:51200
	v_mfma_f32_16x16x32_f16 v[140:143], v[210:213], v[190:193], v[140:143]
	global_load_dwordx4 v[56:59], v[116:117], off offset:896
	v_mfma_f32_16x16x32_f16 v[154:157], v[210:213], v[198:201], v[154:157]
	global_load_dwordx4 v[60:63], v[118:119], off offset:896
	v_mfma_f32_16x16x32_f16 v[64:67], v[224:227], v[190:193], v[64:67]
	ds_read_b128 v[190:193], v128 offset:16384
	v_mfma_f32_16x16x32_f16 v[72:75], v[224:227], v[198:201], v[72:75]
	ds_read_b128 v[198:201], v128 offset:18432
	v_mfma_f32_16x16x32_f16 v[166:169], v[210:213], v[206:209], v[166:169]
	v_mfma_f32_16x16x32_f16 v[84:87], v[210:213], v[220:223], v[84:87]
	ds_read_b128 v[210:213], v131 offset:53248
	v_mfma_f32_16x16x32_f16 v[80:83], v[224:227], v[206:209], v[80:83]
	ds_read_b128 v[206:209], v128 offset:20480
	v_mfma_f32_16x16x32_f16 v[88:91], v[224:227], v[220:223], v[88:91]
	ds_read_b128 v[220:223], v128 offset:22528
	s_waitcnt lgkmcnt(4)
	v_mfma_f32_16x16x32_f16 v[132:135], v[194:197], v[190:193], v[132:135]
	ds_read_b128 v[224:227], v131 offset:55296
	s_waitcnt lgkmcnt(4)
	v_mfma_f32_16x16x32_f16 v[92:95], v[194:197], v[198:201], v[92:95]
	s_waitcnt vmcnt(15)
	ds_write_b128 v126, v[0:3]
	v_mfma_f32_16x16x32_f16 v[136:139], v[202:205], v[190:193], v[136:139]
	s_waitcnt vmcnt(14)
	ds_write_b128 v124, v[4:7]
	v_mfma_f32_16x16x32_f16 v[144:147], v[202:205], v[198:201], v[144:147]
	s_waitcnt vmcnt(13)
	ds_write_b128 v125, v[8:11]
	s_waitcnt lgkmcnt(5)
	v_mfma_f32_16x16x32_f16 v[158:161], v[194:197], v[206:209], v[158:161]
	s_waitcnt vmcnt(12)
	ds_write_b128 v127, v[12:15]
	s_waitcnt lgkmcnt(5)
	v_mfma_f32_16x16x32_f16 v[68:71], v[194:197], v[220:223], v[68:71]
	ds_read_b128 v[194:197], v130 offset:49152
	v_mfma_f32_16x16x32_f16 v[162:165], v[202:205], v[206:209], v[162:165]
	s_waitcnt vmcnt(11)
	ds_write_b128 v126, v[16:19] offset:32768
	v_mfma_f32_16x16x32_f16 v[76:79], v[202:205], v[220:223], v[76:79]
	ds_read_b128 v[202:205], v130 offset:51200
	v_mfma_f32_16x16x32_f16 v[140:143], v[210:213], v[190:193], v[140:143]
	s_waitcnt vmcnt(10)
	ds_write_b128 v124, v[20:23] offset:32768
	v_mfma_f32_16x16x32_f16 v[154:157], v[210:213], v[198:201], v[154:157]
	s_waitcnt vmcnt(9)
	ds_write_b128 v125, v[24:27] offset:32768
	s_waitcnt lgkmcnt(9)
	v_mfma_f32_16x16x32_f16 v[64:67], v[224:227], v[190:193], v[64:67]
	ds_read_b128 v[190:193], v129 offset:16384
	v_mfma_f32_16x16x32_f16 v[72:75], v[224:227], v[198:201], v[72:75]
	ds_read_b128 v[198:201], v129 offset:18432
	v_mfma_f32_16x16x32_f16 v[166:169], v[210:213], v[206:209], v[166:169]
	s_waitcnt vmcnt(8)
	ds_write_b128 v127, v[28:31] offset:32768
	v_mfma_f32_16x16x32_f16 v[84:87], v[210:213], v[220:223], v[84:87]
	ds_read_b128 v[210:213], v130 offset:53248
	v_mfma_f32_16x16x32_f16 v[80:83], v[224:227], v[206:209], v[80:83]
	ds_read_b128 v[206:209], v129 offset:20480
	v_mfma_f32_16x16x32_f16 v[88:91], v[224:227], v[220:223], v[88:91]
	ds_read_b128 v[220:223], v129 offset:22528
	ds_read_b128 v[224:227], v130 offset:55296
	s_waitcnt lgkmcnt(0)
	s_barrier
	v_mfma_f32_16x16x32_f16 v[132:135], v[194:197], v[190:193], v[132:135]
	global_load_dwordx4 v[0:3], v[104:105], off offset:1024
	v_mfma_f32_16x16x32_f16 v[92:95], v[194:197], v[198:201], v[92:95]
	global_load_dwordx4 v[4:7], v[106:107], off offset:1024
	v_mfma_f32_16x16x32_f16 v[136:139], v[202:205], v[190:193], v[136:139]
	global_load_dwordx4 v[8:11], v[108:109], off offset:1024
	v_mfma_f32_16x16x32_f16 v[144:147], v[202:205], v[198:201], v[144:147]
	global_load_dwordx4 v[12:15], v[110:111], off offset:1024
	v_mfma_f32_16x16x32_f16 v[158:161], v[194:197], v[206:209], v[158:161]
	global_load_dwordx4 v[16:19], v[112:113], off offset:1024
	v_mfma_f32_16x16x32_f16 v[68:71], v[194:197], v[220:223], v[68:71]
	ds_read_b128 v[194:197], v131 offset:32768
	v_mfma_f32_16x16x32_f16 v[162:165], v[202:205], v[206:209], v[162:165]
	global_load_dwordx4 v[20:23], v[114:115], off offset:1024
	v_mfma_f32_16x16x32_f16 v[76:79], v[202:205], v[220:223], v[76:79]
	ds_read_b128 v[202:205], v131 offset:34816
	v_mfma_f32_16x16x32_f16 v[140:143], v[210:213], v[190:193], v[140:143]
	global_load_dwordx4 v[24:27], v[116:117], off offset:1024
	v_mfma_f32_16x16x32_f16 v[154:157], v[210:213], v[198:201], v[154:157]
	global_load_dwordx4 v[28:31], v[118:119], off offset:1024
	v_mfma_f32_16x16x32_f16 v[64:67], v[224:227], v[190:193], v[64:67]
	ds_read_b128 v[190:193], v128
	v_mfma_f32_16x16x32_f16 v[72:75], v[224:227], v[198:201], v[72:75]
	ds_read_b128 v[198:201], v128 offset:2048
	v_mfma_f32_16x16x32_f16 v[166:169], v[210:213], v[206:209], v[166:169]
	v_mfma_f32_16x16x32_f16 v[84:87], v[210:213], v[220:223], v[84:87]
	ds_read_b128 v[210:213], v131 offset:36864
	v_mfma_f32_16x16x32_f16 v[80:83], v[224:227], v[206:209], v[80:83]
	ds_read_b128 v[206:209], v128 offset:4096
	v_mfma_f32_16x16x32_f16 v[88:91], v[224:227], v[220:223], v[88:91]
	ds_read_b128 v[220:223], v128 offset:6144
	s_waitcnt lgkmcnt(4)
; #define GL_LOAD(s_, kt_) if (VAR != 1) { a##s_##0 = GL_A(0, kt_); a##s_##1 = GL_A(1, kt_); a##s_##2 = GL_A(2, kt_); a##s_##3 = GL_A(3, kt_); b##s_##0 = GL_B(0, kt_); b##s_##1 = GL_B(1, kt_); b##s_##2 = GL_B(2, kt_); b##s_##3 = GL_B(3, kt_); }
; #define LDS_STORE(s_, buf_) if (VAR != 2) { LDS_ST1(sA, 0, buf_, a##s_##0) LDS_ST1(sA, 1, buf_, a##s_##1) LDS_ST1(sA, 2, buf_, a##s_##2) LDS_ST1(sA, 3, buf_, a##s_##3) LDS_ST1(sB, 0, buf_, b##s_##0) LDS_ST1(sB, 1, buf_, b##s_##1) LDS_ST1(sB, 2, buf_, b##s_##2) LDS_ST1(sB, 3, buf_, b##s_##3) }
;     ...
;   GL_LOAD(0, 0)
;   GL_LOAD(1, 1)
;   LDS_STORE(0, 0)
;   if (VAR != 4) __syncthreads();
; #pragma unroll
;   for (int kt = 0; kt < nk; kt += 2) {
;     if (kt + 2 < nk) { GL_LOAD(0, kt + 2) }
;     MMA_TILE(0)
;     LDS_STORE(1, 1)
;     if (VAR != 4) __syncthreads();
;     if (kt + 3 < nk) { GL_LOAD(1, kt + 3) }
;     MMA_TILE(1)
;     if (kt + 2 < nk) { LDS_STORE(0, 0) }
;     if (VAR != 4) __syncthreads();
	v_mfma_f32_16x16x32_f16 v[132:135], v[194:197], v[190:193], v[132:135]
	ds_read_b128 v[224:227], v131 offset:38912
	s_waitcnt lgkmcnt(4)
	v_mfma_f32_16x16x32_f16 v[92:95], v[194:197], v[198:201], v[92:95]
	s_waitcnt vmcnt(15)
	ds_write_b128 v126, v[32:35] offset:16384
	v_mfma_f32_16x16x32_f16 v[136:139], v[202:205], v[190:193], v[136:139]
	s_waitcnt vmcnt(14)
	ds_write_b128 v124, v[36:39] offset:16384
	v_mfma_f32_16x16x32_f16 v[144:147], v[202:205], v[198:201], v[144:147]
	s_waitcnt vmcnt(13)
	ds_write_b128 v125, v[40:43] offset:16384
	s_waitcnt lgkmcnt(5)
	v_mfma_f32_16x16x32_f16 v[158:161], v[194:197], v[206:209], v[158:161]
	s_waitcnt vmcnt(12)
	ds_write_b128 v127, v[44:47] offset:16384
	s_waitcnt lgkmcnt(5)
	v_mfma_f32_16x16x32_f16 v[68:71], v[194:197], v[220:223], v[68:71]
	ds_read_b128 v[194:197], v130 offset:32768
	v_mfma_f32_16x16x32_f16 v[162:165], v[202:205], v[206:209], v[162:165]
	s_waitcnt vmcnt(11)
	ds_write_b128 v126, v[48:51] offset:49152
	v_mfma_f32_16x16x32_f16 v[76:79], v[202:205], v[220:223], v[76:79]
	ds_read_b128 v[202:205], v130 offset:34816
	v_mfma_f32_16x16x32_f16 v[140:143], v[210:213], v[190:193], v[140:143]
	s_waitcnt vmcnt(10)
	ds_write_b128 v124, v[52:55] offset:49152
	v_mfma_f32_16x16x32_f16 v[154:157], v[210:213], v[198:201], v[154:157]
	s_waitcnt vmcnt(9)
	ds_write_b128 v125, v[56:59] offset:49152
	s_waitcnt lgkmcnt(9)
	v_mfma_f32_16x16x32_f16 v[64:67], v[224:227], v[190:193], v[64:67]
	ds_read_b128 v[190:193], v129
	v_mfma_f32_16x16x32_f16 v[72:75], v[224:227], v[198:201], v[72:75]
	ds_read_b128 v[198:201], v129 offset:2048
	v_mfma_f32_16x16x32_f16 v[166:169], v[210:213], v[206:209], v[166:169]
	s_waitcnt vmcnt(8)
	ds_write_b128 v127, v[60:63] offset:49152
	v_mfma_f32_16x16x32_f16 v[84:87], v[210:213], v[220:223], v[84:87]
	ds_read_b128 v[210:213], v130 offset:36864
	v_mfma_f32_16x16x32_f16 v[80:83], v[224:227], v[206:209], v[80:83]
	ds_read_b128 v[206:209], v129 offset:4096
	v_mfma_f32_16x16x32_f16 v[88:91], v[224:227], v[220:223], v[88:91]
	ds_read_b128 v[220:223], v129 offset:6144
	ds_read_b128 v[224:227], v130 offset:38912
	s_waitcnt lgkmcnt(0)
	s_barrier
	v_mfma_f32_16x16x32_f16 v[132:135], v[194:197], v[190:193], v[132:135]
	global_load_dwordx4 v[32:35], v[104:105], off offset:1152
	v_mfma_f32_16x16x32_f16 v[92:95], v[194:197], v[198:201], v[92:95]
	global_load_dwordx4 v[36:39], v[106:107], off offset:1152
	v_mfma_f32_16x16x32_f16 v[136:139], v[202:205], v[190:193], v[136:139]
	global_load_dwordx4 v[40:43], v[108:109], off offset:1152
	v_mfma_f32_16x16x32_f16 v[144:147], v[202:205], v[198:201], v[144:147]
	global_load_dwordx4 v[44:47], v[110:111], off offset:1152
	v_mfma_f32_16x16x32_f16 v[158:161], v[194:197], v[206:209], v[158:161]
	global_load_dwordx4 v[48:51], v[112:113], off offset:1152
	v_mfma_f32_16x16x32_f16 v[68:71], v[194:197], v[220:223], v[68:71]
	ds_read_b128 v[194:197], v131 offset:49152
	v_mfma_f32_16x16x32_f16 v[162:165], v[202:205], v[206:209], v[162:165]
	global_load_dwordx4 v[52:55], v[114:115], off offset:1152
	v_mfma_f32_16x16x32_f16 v[76:79], v[202:205], v[220:223], v[76:79]
	ds_read_b128 v[202:205], v131 offset:51200
	v_mfma_f32_16x16x32_f16 v[140:143], v[210:213], v[190:193], v[140:143]
	global_load_dwordx4 v[56:59], v[116:117], off offset:1152
	v_mfma_f32_16x16x32_f16 v[154:157], v[210:213], v[198:201], v[154:157]
	global_load_dwordx4 v[60:63], v[118:119], off offset:1152
	v_mfma_f32_16x16x32_f16 v[64:67], v[224:227], v[190:193], v[64:67]
	ds_read_b128 v[190:193], v128 offset:16384
	v_mfma_f32_16x16x32_f16 v[72:75], v[224:227], v[198:201], v[72:75]
	ds_read_b128 v[198:201], v128 offset:18432
	v_mfma_f32_16x16x32_f16 v[166:169], v[210:213], v[206:209], v[166:169]
	v_mfma_f32_16x16x32_f16 v[84:87], v[210:213], v[220:223], v[84:87]
	ds_read_b128 v[210:213], v131 offset:53248
	v_mfma_f32_16x16x32_f16 v[80:83], v[224:227], v[206:209], v[80:83]
	ds_read_b128 v[206:209], v128 offset:20480
	v_mfma_f32_16x16x32_f16 v[88:91], v[224:227], v[220:223], v[88:91]
	ds_read_b128 v[220:223], v128 offset:22528
	s_waitcnt lgkmcnt(4)
	v_mfma_f32_16x16x32_f16 v[132:135], v[194:197], v[190:193], v[132:135]
	ds_read_b128 v[224:227], v131 offset:55296
	s_waitcnt lgkmcnt(4)
	v_mfma_f32_16x16x32_f16 v[92:95], v[194:197], v[198:201], v[92:95]
	s_waitcnt vmcnt(15)
	ds_write_b128 v126, v[0:3]
	v_mfma_f32_16x16x32_f16 v[136:139], v[202:205], v[190:193], v[136:139]
	s_waitcnt vmcnt(14)
	ds_write_b128 v124, v[4:7]
	v_mfma_f32_16x16x32_f16 v[144:147], v[202:205], v[198:201], v[144:147]
	s_waitcnt vmcnt(13)
	ds_write_b128 v125, v[8:11]
	s_waitcnt lgkmcnt(5)
	v_mfma_f32_16x16x32_f16 v[158:161], v[194:197], v[206:209], v[158:161]
	s_waitcnt vmcnt(12)
	ds_write_b128 v127, v[12:15]
	s_waitcnt lgkmcnt(5)
	v_mfma_f32_16x16x32_f16 v[68:71], v[194:197], v[220:223], v[68:71]
	ds_read_b128 v[194:197], v130 offset:49152
	v_mfma_f32_16x16x32_f16 v[162:165], v[202:205], v[206:209], v[162:165]
	s_waitcnt vmcnt(11)
	ds_write_b128 v126, v[16:19] offset:32768
	v_mfma_f32_16x16x32_f16 v[76:79], v[202:205], v[220:223], v[76:79]
	ds_read_b128 v[202:205], v130 offset:51200
	v_mfma_f32_16x16x32_f16 v[140:143], v[210:213], v[190:193], v[140:143]
	s_waitcnt vmcnt(10)
	ds_write_b128 v124, v[20:23] offset:32768
	v_mfma_f32_16x16x32_f16 v[154:157], v[210:213], v[198:201], v[154:157]
	s_waitcnt vmcnt(9)
	ds_write_b128 v125, v[24:27] offset:32768
	s_waitcnt lgkmcnt(9)
	v_mfma_f32_16x16x32_f16 v[64:67], v[224:227], v[190:193], v[64:67]
	ds_read_b128 v[190:193], v129 offset:16384
	v_mfma_f32_16x16x32_f16 v[72:75], v[224:227], v[198:201], v[72:75]
	ds_read_b128 v[198:201], v129 offset:18432
	v_mfma_f32_16x16x32_f16 v[166:169], v[210:213], v[206:209], v[166:169]
	s_waitcnt vmcnt(8)
	ds_write_b128 v127, v[28:31] offset:32768
	v_mfma_f32_16x16x32_f16 v[84:87], v[210:213], v[220:223], v[84:87]
	ds_read_b128 v[210:213], v130 offset:53248
	v_mfma_f32_16x16x32_f16 v[80:83], v[224:227], v[206:209], v[80:83]
	ds_read_b128 v[206:209], v129 offset:20480
	v_mfma_f32_16x16x32_f16 v[88:91], v[224:227], v[220:223], v[88:91]
	ds_read_b128 v[220:223], v129 offset:22528
	ds_read_b128 v[224:227], v130 offset:55296
	s_waitcnt lgkmcnt(0)
	s_barrier
; #define GL_LOAD(s_, kt_) if (VAR != 1) { a##s_##0 = GL_A(0, kt_); a##s_##1 = GL_A(1, kt_); a##s_##2 = GL_A(2, kt_); a##s_##3 = GL_A(3, kt_); b##s_##0 = GL_B(0, kt_); b##s_##1 = GL_B(1, kt_); b##s_##2 = GL_B(2, kt_); b##s_##3 = GL_B(3, kt_); }
; #define LDS_STORE(s_, buf_) if (VAR != 2) { LDS_ST1(sA, 0, buf_, a##s_##0) LDS_ST1(sA, 1, buf_, a##s_##1) LDS_ST1(sA, 2, buf_, a##s_##2) LDS_ST1(sA, 3, buf_, a##s_##3) LDS_ST1(sB, 0, buf_, b##s_##0) LDS_ST1(sB, 1, buf_, b##s_##1) LDS_ST1(sB, 2, buf_, b##s_##2) LDS_ST1(sB, 3, buf_, b##s_##3) }
;     ...
;   GL_LOAD(0, 0)
;   GL_LOAD(1, 1)
;   LDS_STORE(0, 0)
;   if (VAR != 4) __syncthreads();
; #pragma unroll
;   for (int kt = 0; kt < nk; kt += 2) {
;     if (kt + 2 < nk) { GL_LOAD(0, kt + 2) }
;     MMA_TILE(0)
;     LDS_STORE(1, 1)
;     if (VAR != 4) __syncthreads();
;     if (kt + 3 < nk) { GL_LOAD(1, kt + 3) }
;     MMA_TILE(1)
;     if (kt + 2 < nk) { LDS_STORE(0, 0) }
;     if (VAR != 4) __syncthreads();
	v_mfma_f32_16x16x32_f16 v[132:135], v[194:197], v[190:193], v[132:135]
	global_load_dwordx4 v[0:3], v[104:105], off offset:1280
	v_mfma_f32_16x16x32_f16 v[92:95], v[194:197], v[198:201], v[92:95]
	global_load_dwordx4 v[4:7], v[106:107], off offset:1280
	v_mfma_f32_16x16x32_f16 v[136:139], v[202:205], v[190:193], v[136:139]
	global_load_dwordx4 v[8:11], v[108:109], off offset:1280
	v_mfma_f32_16x16x32_f16 v[144:147], v[202:205], v[198:201], v[144:147]
	global_load_dwordx4 v[12:15], v[110:111], off offset:1280
	v_mfma_f32_16x16x32_f16 v[158:161], v[194:197], v[206:209], v[158:161]
	global_load_dwordx4 v[16:19], v[112:113], off offset:1280
	v_mfma_f32_16x16x32_f16 v[68:71], v[194:197], v[220:223], v[68:71]
	ds_read_b128 v[194:197], v131 offset:32768
	v_mfma_f32_16x16x32_f16 v[162:165], v[202:205], v[206:209], v[162:165]
	global_load_dwordx4 v[20:23], v[114:115], off offset:1280
	v_mfma_f32_16x16x32_f16 v[76:79], v[202:205], v[220:223], v[76:79]
	ds_read_b128 v[202:205], v131 offset:34816
	v_mfma_f32_16x16x32_f16 v[140:143], v[210:213], v[190:193], v[140:143]
	global_load_dwordx4 v[24:27], v[116:117], off offset:1280
	v_mfma_f32_16x16x32_f16 v[154:157], v[210:213], v[198:201], v[154:157]
	global_load_dwordx4 v[28:31], v[118:119], off offset:1280
	v_mfma_f32_16x16x32_f16 v[64:67], v[224:227], v[190:193], v[64:67]
	ds_read_b128 v[190:193], v128
	v_mfma_f32_16x16x32_f16 v[72:75], v[224:227], v[198:201], v[72:75]
	ds_read_b128 v[198:201], v128 offset:2048
	v_mfma_f32_16x16x32_f16 v[166:169], v[210:213], v[206:209], v[166:169]
	v_mfma_f32_16x16x32_f16 v[84:87], v[210:213], v[220:223], v[84:87]
	ds_read_b128 v[210:213], v131 offset:36864
	v_mfma_f32_16x16x32_f16 v[80:83], v[224:227], v[206:209], v[80:83]
	ds_read_b128 v[206:209], v128 offset:4096
	v_mfma_f32_16x16x32_f16 v[88:91], v[224:227], v[220:223], v[88:91]
	ds_read_b128 v[220:223], v128 offset:6144
	s_waitcnt lgkmcnt(4)
	v_mfma_f32_16x16x32_f16 v[132:135], v[194:197], v[190:193], v[132:135]
	ds_read_b128 v[224:227], v131 offset:38912
	s_waitcnt lgkmcnt(4)
	v_mfma_f32_16x16x32_f16 v[92:95], v[194:197], v[198:201], v[92:95]
	s_waitcnt vmcnt(15)
	ds_write_b128 v126, v[32:35] offset:16384
	v_mfma_f32_16x16x32_f16 v[136:139], v[202:205], v[190:193], v[136:139]
	s_waitcnt vmcnt(14)
	ds_write_b128 v124, v[36:39] offset:16384
	v_mfma_f32_16x16x32_f16 v[144:147], v[202:205], v[198:201], v[144:147]
	s_waitcnt vmcnt(13)
	ds_write_b128 v125, v[40:43] offset:16384
	s_waitcnt lgkmcnt(5)
	v_mfma_f32_16x16x32_f16 v[158:161], v[194:197], v[206:209], v[158:161]
	s_waitcnt vmcnt(12)
	ds_write_b128 v127, v[44:47] offset:16384
	s_waitcnt lgkmcnt(5)
	v_mfma_f32_16x16x32_f16 v[68:71], v[194:197], v[220:223], v[68:71]
	ds_read_b128 v[194:197], v130 offset:32768
	v_mfma_f32_16x16x32_f16 v[162:165], v[202:205], v[206:209], v[162:165]
	s_waitcnt vmcnt(11)
	ds_write_b128 v126, v[48:51] offset:49152
	v_mfma_f32_16x16x32_f16 v[76:79], v[202:205], v[220:223], v[76:79]
	ds_read_b128 v[202:205], v130 offset:34816
	v_mfma_f32_16x16x32_f16 v[140:143], v[210:213], v[190:193], v[140:143]
	s_waitcnt vmcnt(10)
	ds_write_b128 v124, v[52:55] offset:49152
	v_mfma_f32_16x16x32_f16 v[154:157], v[210:213], v[198:201], v[154:157]
	s_waitcnt vmcnt(9)
	ds_write_b128 v125, v[56:59] offset:49152
	s_waitcnt lgkmcnt(9)
	v_mfma_f32_16x16x32_f16 v[64:67], v[224:227], v[190:193], v[64:67]
	ds_read_b128 v[190:193], v129
	v_mfma_f32_16x16x32_f16 v[72:75], v[224:227], v[198:201], v[72:75]
	ds_read_b128 v[198:201], v129 offset:2048
	v_mfma_f32_16x16x32_f16 v[166:169], v[210:213], v[206:209], v[166:169]
	s_waitcnt vmcnt(8)
	ds_write_b128 v127, v[60:63] offset:49152
	v_mfma_f32_16x16x32_f16 v[84:87], v[210:213], v[220:223], v[84:87]
	ds_read_b128 v[210:213], v130 offset:36864
	v_mfma_f32_16x16x32_f16 v[80:83], v[224:227], v[206:209], v[80:83]
	ds_read_b128 v[206:209], v129 offset:4096
	v_mfma_f32_16x16x32_f16 v[88:91], v[224:227], v[220:223], v[88:91]
	ds_read_b128 v[220:223], v129 offset:6144
	ds_read_b128 v[224:227], v130 offset:38912
	s_waitcnt lgkmcnt(0)
	s_barrier
	v_mfma_f32_16x16x32_f16 v[132:135], v[194:197], v[190:193], v[132:135]
	global_load_dwordx4 v[32:35], v[104:105], off offset:1408
	v_mfma_f32_16x16x32_f16 v[92:95], v[194:197], v[198:201], v[92:95]
	global_load_dwordx4 v[36:39], v[106:107], off offset:1408
	v_mfma_f32_16x16x32_f16 v[136:139], v[202:205], v[190:193], v[136:139]
	global_load_dwordx4 v[40:43], v[108:109], off offset:1408
	v_mfma_f32_16x16x32_f16 v[144:147], v[202:205], v[198:201], v[144:147]
	global_load_dwordx4 v[44:47], v[110:111], off offset:1408
	v_mfma_f32_16x16x32_f16 v[158:161], v[194:197], v[206:209], v[158:161]
	global_load_dwordx4 v[48:51], v[112:113], off offset:1408
	v_mfma_f32_16x16x32_f16 v[68:71], v[194:197], v[220:223], v[68:71]
	ds_read_b128 v[194:197], v131 offset:49152
	v_mfma_f32_16x16x32_f16 v[162:165], v[202:205], v[206:209], v[162:165]
	global_load_dwordx4 v[52:55], v[114:115], off offset:1408
	v_mfma_f32_16x16x32_f16 v[76:79], v[202:205], v[220:223], v[76:79]
	ds_read_b128 v[202:205], v131 offset:51200
	v_mfma_f32_16x16x32_f16 v[140:143], v[210:213], v[190:193], v[140:143]
	global_load_dwordx4 v[56:59], v[116:117], off offset:1408
	v_mfma_f32_16x16x32_f16 v[154:157], v[210:213], v[198:201], v[154:157]
	global_load_dwordx4 v[60:63], v[118:119], off offset:1408
	v_mfma_f32_16x16x32_f16 v[64:67], v[224:227], v[190:193], v[64:67]
	ds_read_b128 v[190:193], v128 offset:16384
	v_mfma_f32_16x16x32_f16 v[72:75], v[224:227], v[198:201], v[72:75]
	ds_read_b128 v[198:201], v128 offset:18432
	v_mfma_f32_16x16x32_f16 v[166:169], v[210:213], v[206:209], v[166:169]
	v_mfma_f32_16x16x32_f16 v[84:87], v[210:213], v[220:223], v[84:87]
	ds_read_b128 v[210:213], v131 offset:53248
	v_mfma_f32_16x16x32_f16 v[80:83], v[224:227], v[206:209], v[80:83]
	ds_read_b128 v[206:209], v128 offset:20480
	v_mfma_f32_16x16x32_f16 v[88:91], v[224:227], v[220:223], v[88:91]
	ds_read_b128 v[220:223], v128 offset:22528
	s_waitcnt lgkmcnt(4)
; #define GL_LOAD(s_, kt_) if (VAR != 1) { a##s_##0 = GL_A(0, kt_); a##s_##1 = GL_A(1, kt_); a##s_##2 = GL_A(2, kt_); a##s_##3 = GL_A(3, kt_); b##s_##0 = GL_B(0, kt_); b##s_##1 = GL_B(1, kt_); b##s_##2 = GL_B(2, kt_); b##s_##3 = GL_B(3, kt_); }
; #define LDS_STORE(s_, buf_) if (VAR != 2) { LDS_ST1(sA, 0, buf_, a##s_##0) LDS_ST1(sA, 1, buf_, a##s_##1) LDS_ST1(sA, 2, buf_, a##s_##2) LDS_ST1(sA, 3, buf_, a##s_##3) LDS_ST1(sB, 0, buf_, b##s_##0) LDS_ST1(sB, 1, buf_, b##s_##1) LDS_ST1(sB, 2, buf_, b##s_##2) LDS_ST1(sB, 3, buf_, b##s_##3) }
;     ...
;   GL_LOAD(0, 0)
;   GL_LOAD(1, 1)
;   LDS_STORE(0, 0)
;   if (VAR != 4) __syncthreads();
; #pragma unroll
;   for (int kt = 0; kt < nk; kt += 2) {
;     if (kt + 2 < nk) { GL_LOAD(0, kt + 2) }
;     MMA_TILE(0)
;     LDS_STORE(1, 1)
;     if (VAR != 4) __syncthreads();
;     if (kt + 3 < nk) { GL_LOAD(1, kt + 3) }
;     MMA_TILE(1)
;     if (kt + 2 < nk) { LDS_STORE(0, 0) }
;     if (VAR != 4) __syncthreads();
	v_mfma_f32_16x16x32_f16 v[132:135], v[194:197], v[190:193], v[132:135]
	ds_read_b128 v[224:227], v131 offset:55296
	s_waitcnt lgkmcnt(4)
	v_mfma_f32_16x16x32_f16 v[92:95], v[194:197], v[198:201], v[92:95]
	s_waitcnt vmcnt(15)
	ds_write_b128 v126, v[0:3]
	v_mfma_f32_16x16x32_f16 v[136:139], v[202:205], v[190:193], v[136:139]
	s_waitcnt vmcnt(14)
	ds_write_b128 v124, v[4:7]
	v_mfma_f32_16x16x32_f16 v[144:147], v[202:205], v[198:201], v[144:147]
	s_waitcnt vmcnt(13)
	ds_write_b128 v125, v[8:11]
	s_waitcnt lgkmcnt(5)
	v_mfma_f32_16x16x32_f16 v[158:161], v[194:197], v[206:209], v[158:161]
	s_waitcnt vmcnt(12)
	ds_write_b128 v127, v[12:15]
	s_waitcnt lgkmcnt(5)
	v_mfma_f32_16x16x32_f16 v[68:71], v[194:197], v[220:223], v[68:71]
	ds_read_b128 v[194:197], v130 offset:49152
	v_mfma_f32_16x16x32_f16 v[162:165], v[202:205], v[206:209], v[162:165]
	s_waitcnt vmcnt(11)
	ds_write_b128 v126, v[16:19] offset:32768
	v_mfma_f32_16x16x32_f16 v[76:79], v[202:205], v[220:223], v[76:79]
	ds_read_b128 v[202:205], v130 offset:51200
	v_mfma_f32_16x16x32_f16 v[140:143], v[210:213], v[190:193], v[140:143]
	s_waitcnt vmcnt(10)
	ds_write_b128 v124, v[20:23] offset:32768
	v_mfma_f32_16x16x32_f16 v[154:157], v[210:213], v[198:201], v[154:157]
	s_waitcnt vmcnt(9)
	ds_write_b128 v125, v[24:27] offset:32768
	s_waitcnt lgkmcnt(9)
	v_mfma_f32_16x16x32_f16 v[64:67], v[224:227], v[190:193], v[64:67]
	ds_read_b128 v[190:193], v129 offset:16384
	v_mfma_f32_16x16x32_f16 v[72:75], v[224:227], v[198:201], v[72:75]
	ds_read_b128 v[198:201], v129 offset:18432
	v_mfma_f32_16x16x32_f16 v[166:169], v[210:213], v[206:209], v[166:169]
	s_waitcnt vmcnt(8)
	ds_write_b128 v127, v[28:31] offset:32768
	v_mfma_f32_16x16x32_f16 v[84:87], v[210:213], v[220:223], v[84:87]
	ds_read_b128 v[210:213], v130 offset:53248
	v_mfma_f32_16x16x32_f16 v[80:83], v[224:227], v[206:209], v[80:83]
	ds_read_b128 v[206:209], v129 offset:20480
	v_mfma_f32_16x16x32_f16 v[88:91], v[224:227], v[220:223], v[88:91]
	ds_read_b128 v[220:223], v129 offset:22528
	s_waitcnt lgkmcnt(5)
	v_mfma_f32_16x16x32_f16 v[132:135], v[194:197], v[190:193], v[132:135]
	ds_read_b128 v[224:227], v130 offset:55296
	s_waitcnt lgkmcnt(0)
	s_barrier
	v_mfma_f32_16x16x32_f16 v[136:139], v[202:205], v[190:193], v[136:139]
	ds_read_b128 v[0:3], v128
	v_mfma_f32_16x16x32_f16 v[144:147], v[202:205], v[198:201], v[144:147]
	ds_read_b128 v[4:7], v131 offset:32768
	v_mfma_f32_16x16x32_f16 v[140:143], v[210:213], v[190:193], v[140:143]
	ds_read_b128 v[8:11], v128 offset:2048
	v_mfma_f32_16x16x32_f16 v[154:157], v[210:213], v[198:201], v[154:157]
	ds_read_b128 v[12:15], v131 offset:34816
	v_mfma_f32_16x16x32_f16 v[162:165], v[202:205], v[206:209], v[162:165]
	ds_read_b128 v[16:19], v128 offset:4096
	v_mfma_f32_16x16x32_f16 v[202:205], v[202:205], v[220:223], v[76:79]
	ds_read_b128 v[20:23], v131 offset:36864
	v_mfma_f32_16x16x32_f16 v[166:169], v[210:213], v[206:209], v[166:169]
	ds_read_b128 v[24:27], v128 offset:6144
	v_mfma_f32_16x16x32_f16 v[210:213], v[210:213], v[220:223], v[84:87]
	ds_read_b128 v[28:31], v131 offset:38912
	v_mfma_f32_16x16x32_f16 v[190:193], v[224:227], v[190:193], v[64:67]
	s_nop 2
	global_load_dwordx4 v[64:67], v[104:105], off offset:1536
	v_mfma_f32_16x16x32_f16 v[228:231], v[194:197], v[198:201], v[92:95]
	v_mfma_f32_16x16x32_f16 v[198:201], v[224:227], v[198:201], v[72:75]
	v_mfma_f32_16x16x32_f16 v[158:161], v[194:197], v[206:209], v[158:161]
	v_mfma_f32_16x16x32_f16 v[206:209], v[224:227], v[206:209], v[80:83]
	v_mfma_f32_16x16x32_f16 v[194:197], v[194:197], v[220:223], v[68:71]
	v_mfma_f32_16x16x32_f16 v[220:223], v[224:227], v[220:223], v[88:91]
	ds_read_b128 v[224:227], v130 offset:38912
	s_nop 0
	global_load_dwordx4 v[68:71], v[106:107], off offset:1536
	global_load_dwordx4 v[72:75], v[108:109], off offset:1536
	global_load_dwordx4 v[76:79], v[110:111], off offset:1536
	global_load_dwordx4 v[80:83], v[112:113], off offset:1536
	s_waitcnt lgkmcnt(7)
	v_mfma_f32_16x16x32_f16 v[132:135], v[4:7], v[0:3], v[132:135]
	global_load_dwordx4 v[84:87], v[114:115], off offset:1536
	s_waitcnt lgkmcnt(5)
	v_mfma_f32_16x16x32_f16 v[136:139], v[12:15], v[0:3], v[136:139]
	s_waitcnt lgkmcnt(3)
	v_mfma_f32_16x16x32_f16 v[140:143], v[20:23], v[0:3], v[140:143]
	s_waitcnt lgkmcnt(1)
	v_mfma_f32_16x16x32_f16 v[0:3], v[28:31], v[0:3], v[190:193]
	v_mfma_f32_16x16x32_f16 v[190:193], v[4:7], v[8:11], v[228:231]
	global_load_dwordx4 v[88:91], v[116:117], off offset:1536
	global_load_dwordx4 v[92:95], v[118:119], off offset:1536
	s_waitcnt vmcnt(15)
	ds_write_b128 v126, v[32:35] offset:16384
	s_waitcnt vmcnt(14)
	ds_write_b128 v124, v[36:39] offset:16384
	v_mfma_f32_16x16x32_f16 v[144:147], v[12:15], v[8:11], v[144:147]
	s_waitcnt vmcnt(13)
	ds_write_b128 v125, v[40:43] offset:16384
	v_mfma_f32_16x16x32_f16 v[158:161], v[4:7], v[16:19], v[158:161]
	s_waitcnt vmcnt(12)
	ds_write_b128 v127, v[44:47] offset:16384
	v_mfma_f32_16x16x32_f16 v[4:7], v[4:7], v[24:27], v[194:197]
	s_nop 2
	ds_read_b128 v[194:197], v130 offset:32768
	v_mfma_f32_16x16x32_f16 v[162:165], v[12:15], v[16:19], v[162:165]
	s_waitcnt vmcnt(11)
	ds_write_b128 v126, v[48:51] offset:49152
	v_mfma_f32_16x16x32_f16 v[12:15], v[12:15], v[24:27], v[202:205]
	s_nop 2
	ds_read_b128 v[202:205], v130 offset:34816
	s_waitcnt vmcnt(10)
	ds_write_b128 v124, v[52:55] offset:49152
	v_mfma_f32_16x16x32_f16 v[154:157], v[20:23], v[8:11], v[154:157]
	s_waitcnt vmcnt(9)
	ds_write_b128 v125, v[56:59] offset:49152
	s_waitcnt vmcnt(8)
	ds_write_b128 v127, v[60:63] offset:49152
	v_mfma_f32_16x16x32_f16 v[8:11], v[28:31], v[8:11], v[198:201]
	s_nop 2
	ds_read_b128 v[198:201], v129 offset:2048
	v_mfma_f32_16x16x32_f16 v[166:169], v[20:23], v[16:19], v[166:169]
	v_mfma_f32_16x16x32_f16 v[20:23], v[20:23], v[24:27], v[210:213]
	s_nop 2
	ds_read_b128 v[210:213], v130 offset:36864
	v_mfma_f32_16x16x32_f16 v[16:19], v[28:31], v[16:19], v[206:209]
	s_nop 2
	ds_read_b128 v[206:209], v129 offset:4096
	v_mfma_f32_16x16x32_f16 v[24:27], v[28:31], v[24:27], v[220:223]
	ds_read_b128 v[28:31], v129
	s_waitcnt lgkmcnt(0)
	v_mfma_f32_16x16x32_f16 v[132:135], v[194:197], v[28:31], v[132:135]
	ds_read_b128 v[220:223], v129 offset:6144
	s_waitcnt lgkmcnt(0)
	s_barrier
; #define GL_LOAD(s_, kt_) if (VAR != 1) { a##s_##0 = GL_A(0, kt_); a##s_##1 = GL_A(1, kt_); a##s_##2 = GL_A(2, kt_); a##s_##3 = GL_A(3, kt_); b##s_##0 = GL_B(0, kt_); b##s_##1 = GL_B(1, kt_); b##s_##2 = GL_B(2, kt_); b##s_##3 = GL_B(3, kt_); }
; #define LDS_STORE(s_, buf_) if (VAR != 2) { LDS_ST1(sA, 0, buf_, a##s_##0) LDS_ST1(sA, 1, buf_, a##s_##1) LDS_ST1(sA, 2, buf_, a##s_##2) LDS_ST1(sA, 3, buf_, a##s_##3) LDS_ST1(sB, 0, buf_, b##s_##0) LDS_ST1(sB, 1, buf_, b##s_##1) LDS_ST1(sB, 2, buf_, b##s_##2) LDS_ST1(sB, 3, buf_, b##s_##3) }
;     ...
;   GL_LOAD(0, 0)
;   GL_LOAD(1, 1)
;   LDS_STORE(0, 0)
;   if (VAR != 4) __syncthreads();
; #pragma unroll
;   for (int kt = 0; kt < nk; kt += 2) {
;     if (kt + 2 < nk) { GL_LOAD(0, kt + 2) }
;     MMA_TILE(0)
;     LDS_STORE(1, 1)
;     if (VAR != 4) __syncthreads();
;     if (kt + 3 < nk) { GL_LOAD(1, kt + 3) }
;     MMA_TILE(1)
;     if (kt + 2 < nk) { LDS_STORE(0, 0) }
;     if (VAR != 4) __syncthreads();
	v_mfma_f32_16x16x32_f16 v[136:139], v[202:205], v[28:31], v[136:139]
	ds_read_b128 v[32:35], v128 offset:16384
	v_mfma_f32_16x16x32_f16 v[144:147], v[202:205], v[198:201], v[144:147]
	ds_read_b128 v[36:39], v131 offset:49152
	v_mfma_f32_16x16x32_f16 v[140:143], v[210:213], v[28:31], v[140:143]
	ds_read_b128 v[40:43], v128 offset:18432
	v_mfma_f32_16x16x32_f16 v[154:157], v[210:213], v[198:201], v[154:157]
	ds_read_b128 v[44:47], v131 offset:51200
	v_mfma_f32_16x16x32_f16 v[162:165], v[202:205], v[206:209], v[162:165]
	ds_read_b128 v[48:51], v128 offset:20480
	v_mfma_f32_16x16x32_f16 v[202:205], v[202:205], v[220:223], v[12:15]
	ds_read_b128 v[52:55], v131 offset:53248
	v_mfma_f32_16x16x32_f16 v[166:169], v[210:213], v[206:209], v[166:169]
	ds_read_b128 v[56:59], v128 offset:22528
	v_mfma_f32_16x16x32_f16 v[210:213], v[210:213], v[220:223], v[20:23]
	ds_read_b128 v[60:63], v131 offset:55296
	v_mfma_f32_16x16x32_f16 v[228:231], v[224:227], v[28:31], v[0:3]
	global_load_dwordx4 v[28:31], v[104:105], off offset:1664
	v_mfma_f32_16x16x32_f16 v[190:193], v[194:197], v[198:201], v[190:193]
	v_mfma_f32_16x16x32_f16 v[198:201], v[224:227], v[198:201], v[8:11]
	v_mfma_f32_16x16x32_f16 v[158:161], v[194:197], v[206:209], v[158:161]
	v_mfma_f32_16x16x32_f16 v[206:209], v[224:227], v[206:209], v[16:19]
	v_mfma_f32_16x16x32_f16 v[194:197], v[194:197], v[220:223], v[4:7]
	v_mfma_f32_16x16x32_f16 v[220:223], v[224:227], v[220:223], v[24:27]
	ds_read_b128 v[224:227], v130 offset:55296
	s_nop 1
	global_load_dwordx4 v[24:27], v[106:107], off offset:1664
	global_load_dwordx4 v[12:15], v[108:109], off offset:1664
	global_load_dwordx4 v[16:19], v[110:111], off offset:1664
	global_load_dwordx4 v[20:23], v[112:113], off offset:1664
	s_waitcnt lgkmcnt(7)
	v_mfma_f32_16x16x32_f16 v[132:135], v[36:39], v[32:35], v[132:135]
	global_load_dwordx4 v[0:3], v[114:115], off offset:1664
	s_waitcnt lgkmcnt(6)
	v_mfma_f32_16x16x32_f16 v[190:193], v[36:39], v[40:43], v[190:193]
	global_load_dwordx4 v[4:7], v[116:117], off offset:1664
	s_waitcnt lgkmcnt(5)
	v_mfma_f32_16x16x32_f16 v[136:139], v[44:47], v[32:35], v[136:139]
	global_load_dwordx4 v[8:11], v[118:119], off offset:1664
	v_mfma_f32_16x16x32_f16 v[144:147], v[44:47], v[40:43], v[144:147]
	s_waitcnt vmcnt(15)
	ds_write_b128 v126, v[64:67]
	s_waitcnt lgkmcnt(5)
	v_mfma_f32_16x16x32_f16 v[158:161], v[36:39], v[48:51], v[158:161]
	s_waitcnt vmcnt(14)
	ds_write_b128 v124, v[68:71]
	s_waitcnt lgkmcnt(4)
	v_mfma_f32_16x16x32_f16 v[36:39], v[36:39], v[56:59], v[194:197]
	s_nop 2
	ds_read_b128 v[194:197], v130 offset:49152
	v_mfma_f32_16x16x32_f16 v[162:165], v[44:47], v[48:51], v[162:165]
	s_waitcnt vmcnt(13)
	ds_write_b128 v125, v[72:75]
	v_mfma_f32_16x16x32_f16 v[44:47], v[44:47], v[56:59], v[202:205]
	s_nop 2
	ds_read_b128 v[202:205], v130 offset:51200
	v_mfma_f32_16x16x32_f16 v[140:143], v[52:55], v[32:35], v[140:143]
	s_waitcnt vmcnt(12)
	ds_write_b128 v127, v[76:79]
	v_mfma_f32_16x16x32_f16 v[154:157], v[52:55], v[40:43], v[154:157]
	s_waitcnt vmcnt(11)
	ds_write_b128 v126, v[80:83] offset:32768
	s_waitcnt lgkmcnt(8)
	v_mfma_f32_16x16x32_f16 v[32:35], v[60:63], v[32:35], v[228:231]
	s_waitcnt vmcnt(10)
	ds_write_b128 v124, v[84:87] offset:32768
	v_mfma_f32_16x16x32_f16 v[40:43], v[60:63], v[40:43], v[198:201]
	s_nop 2
	ds_read_b128 v[198:201], v129 offset:18432
	v_mfma_f32_16x16x32_f16 v[166:169], v[52:55], v[48:51], v[166:169]
	s_waitcnt vmcnt(9)
	ds_write_b128 v125, v[88:91] offset:32768
	v_mfma_f32_16x16x32_f16 v[52:55], v[52:55], v[56:59], v[210:213]
	s_nop 2
	ds_read_b128 v[210:213], v130 offset:53248
	v_mfma_f32_16x16x32_f16 v[48:51], v[60:63], v[48:51], v[206:209]
	s_nop 2
	ds_read_b128 v[206:209], v129 offset:20480
	v_mfma_f32_16x16x32_f16 v[56:59], v[60:63], v[56:59], v[220:223]
	ds_read_b128 v[60:63], v129 offset:16384
	s_waitcnt lgkmcnt(0)
	v_mfma_f32_16x16x32_f16 v[132:135], v[194:197], v[60:63], v[132:135]
	ds_read_b128 v[220:223], v129 offset:22528
	s_waitcnt vmcnt(8)
	ds_write_b128 v127, v[92:95] offset:32768
	s_waitcnt lgkmcnt(0)
	s_barrier
	v_mfma_f32_16x16x32_f16 v[136:139], v[202:205], v[60:63], v[136:139]
	ds_read_b128 v[64:67], v128
	v_mfma_f32_16x16x32_f16 v[144:147], v[202:205], v[198:201], v[144:147]
	ds_read_b128 v[68:71], v131 offset:32768
	v_mfma_f32_16x16x32_f16 v[140:143], v[210:213], v[60:63], v[140:143]
	ds_read_b128 v[72:75], v128 offset:2048
	v_mfma_f32_16x16x32_f16 v[154:157], v[210:213], v[198:201], v[154:157]
	ds_read_b128 v[76:79], v131 offset:34816
	v_mfma_f32_16x16x32_f16 v[162:165], v[202:205], v[206:209], v[162:165]
	ds_read_b128 v[80:83], v128 offset:4096
	v_mfma_f32_16x16x32_f16 v[202:205], v[202:205], v[220:223], v[44:47]
	ds_read_b128 v[84:87], v131 offset:36864
	v_mfma_f32_16x16x32_f16 v[166:169], v[210:213], v[206:209], v[166:169]
	ds_read_b128 v[88:91], v128 offset:6144
	v_mfma_f32_16x16x32_f16 v[210:213], v[210:213], v[220:223], v[52:55]
	ds_read_b128 v[92:95], v131 offset:38912
	v_mfma_f32_16x16x32_f16 v[228:231], v[224:227], v[60:63], v[32:35]
	s_nop 0
	global_load_dwordx4 v[52:55], v[104:105], off offset:1792
	v_mfma_f32_16x16x32_f16 v[190:193], v[194:197], v[198:201], v[190:193]
	v_mfma_f32_16x16x32_f16 v[198:201], v[224:227], v[198:201], v[40:43]
	v_mfma_f32_16x16x32_f16 v[158:161], v[194:197], v[206:209], v[158:161]
	v_mfma_f32_16x16x32_f16 v[206:209], v[224:227], v[206:209], v[48:51]
	s_waitcnt vmcnt(8)
	ds_write_b128 v126, v[28:31] offset:16384
	s_waitcnt vmcnt(7)
; #define GL_LOAD(s_, kt_) if (VAR != 1) { a##s_##0 = GL_A(0, kt_); a##s_##1 = GL_A(1, kt_); a##s_##2 = GL_A(2, kt_); a##s_##3 = GL_A(3, kt_); b##s_##0 = GL_B(0, kt_); b##s_##1 = GL_B(1, kt_); b##s_##2 = GL_B(2, kt_); b##s_##3 = GL_B(3, kt_); }
; #define LDS_STORE(s_, buf_) if (VAR != 2) { LDS_ST1(sA, 0, buf_, a##s_##0) LDS_ST1(sA, 1, buf_, a##s_##1) LDS_ST1(sA, 2, buf_, a##s_##2) LDS_ST1(sA, 3, buf_, a##s_##3) LDS_ST1(sB, 0, buf_, b##s_##0) LDS_ST1(sB, 1, buf_, b##s_##1) LDS_ST1(sB, 2, buf_, b##s_##2) LDS_ST1(sB, 3, buf_, b##s_##3) }
;     ...
;   GL_LOAD(0, 0)
;   GL_LOAD(1, 1)
;   LDS_STORE(0, 0)
;   if (VAR != 4) __syncthreads();
; #pragma unroll
;   for (int kt = 0; kt < nk; kt += 2) {
;     if (kt + 2 < nk) { GL_LOAD(0, kt + 2) }
;     MMA_TILE(0)
;     LDS_STORE(1, 1)
;     if (VAR != 4) __syncthreads();
;     if (kt + 3 < nk) { GL_LOAD(1, kt + 3) }
;     MMA_TILE(1)
;     if (kt + 2 < nk) { LDS_STORE(0, 0) }
;     if (VAR != 4) __syncthreads();
	ds_write_b128 v124, v[24:27] offset:16384
	v_mfma_f32_16x16x32_f16 v[194:197], v[194:197], v[220:223], v[36:39]
	v_mfma_f32_16x16x32_f16 v[220:223], v[224:227], v[220:223], v[56:59]
	ds_read_b128 v[224:227], v130 offset:38912
	s_nop 1
	global_load_dwordx4 v[56:59], v[106:107], off offset:1792
	global_load_dwordx4 v[60:63], v[108:109], off offset:1792
	global_load_dwordx4 v[40:43], v[110:111], off offset:1792
	global_load_dwordx4 v[44:47], v[112:113], off offset:1792
	s_waitcnt lgkmcnt(9)
	v_mfma_f32_16x16x32_f16 v[132:135], v[68:71], v[64:67], v[132:135]
	global_load_dwordx4 v[48:51], v[114:115], off offset:1792
	s_waitcnt lgkmcnt(8)
	v_mfma_f32_16x16x32_f16 v[190:193], v[68:71], v[72:75], v[190:193]
	global_load_dwordx4 v[32:35], v[116:117], off offset:1792
	s_waitcnt lgkmcnt(7)
	v_mfma_f32_16x16x32_f16 v[136:139], v[76:79], v[64:67], v[136:139]
	global_load_dwordx4 v[36:39], v[118:119], off offset:1792
	v_mfma_f32_16x16x32_f16 v[144:147], v[76:79], v[72:75], v[144:147]
	s_waitcnt vmcnt(13)
	ds_write_b128 v125, v[12:15] offset:16384
	s_waitcnt lgkmcnt(7)
	v_mfma_f32_16x16x32_f16 v[158:161], v[68:71], v[80:83], v[158:161]
	s_waitcnt vmcnt(12)
	ds_write_b128 v127, v[16:19] offset:16384
	s_waitcnt lgkmcnt(6)
	v_mfma_f32_16x16x32_f16 v[68:71], v[68:71], v[88:91], v[194:197]
	s_nop 2
	ds_read_b128 v[194:197], v130 offset:32768
	v_mfma_f32_16x16x32_f16 v[162:165], v[76:79], v[80:83], v[162:165]
	s_waitcnt vmcnt(11)
	ds_write_b128 v126, v[20:23] offset:49152
	v_mfma_f32_16x16x32_f16 v[76:79], v[76:79], v[88:91], v[202:205]
	s_nop 2
	ds_read_b128 v[202:205], v130 offset:34816
	v_mfma_f32_16x16x32_f16 v[140:143], v[84:87], v[64:67], v[140:143]
	s_waitcnt vmcnt(10)
	ds_write_b128 v124, v[0:3] offset:49152
	v_mfma_f32_16x16x32_f16 v[154:157], v[84:87], v[72:75], v[154:157]
	s_waitcnt vmcnt(9)
	ds_write_b128 v125, v[4:7] offset:49152
	s_waitcnt lgkmcnt(10)
	v_mfma_f32_16x16x32_f16 v[64:67], v[92:95], v[64:67], v[228:231]
	s_waitcnt vmcnt(8)
	ds_write_b128 v127, v[8:11] offset:49152
	v_mfma_f32_16x16x32_f16 v[72:75], v[92:95], v[72:75], v[198:201]
	s_nop 2
	ds_read_b128 v[198:201], v129 offset:2048
	v_mfma_f32_16x16x32_f16 v[166:169], v[84:87], v[80:83], v[166:169]
	v_mfma_f32_16x16x32_f16 v[84:87], v[84:87], v[88:91], v[210:213]
	s_nop 2
	ds_read_b128 v[210:213], v130 offset:36864
	v_mfma_f32_16x16x32_f16 v[80:83], v[92:95], v[80:83], v[206:209]
	s_nop 2
	ds_read_b128 v[206:209], v129 offset:4096
	v_mfma_f32_16x16x32_f16 v[88:91], v[92:95], v[88:91], v[220:223]
	ds_read_b128 v[92:95], v129
	s_nop 1
	ds_read_b128 v[220:223], v129 offset:6144
	s_waitcnt lgkmcnt(0)
	s_barrier
	v_mfma_f32_16x16x32_f16 v[132:135], v[194:197], v[92:95], v[132:135]
	global_load_dwordx4 v[24:27], v[104:105], off offset:1920
	v_mfma_f32_16x16x32_f16 v[136:139], v[202:205], v[92:95], v[136:139]
	v_mfma_f32_16x16x32_f16 v[140:143], v[210:213], v[92:95], v[140:143]
	v_mfma_f32_16x16x32_f16 v[64:67], v[224:227], v[92:95], v[64:67]
	v_mfma_f32_16x16x32_f16 v[92:95], v[194:197], v[198:201], v[190:193]
	s_nop 2
	ds_read_b128 v[190:193], v128 offset:20480
	global_load_dwordx4 v[28:31], v[106:107], off offset:1920
	ds_read_b128 v[104:107], v128 offset:16384
	v_mfma_f32_16x16x32_f16 v[144:147], v[202:205], v[198:201], v[144:147]
	global_load_dwordx4 v[12:15], v[108:109], off offset:1920
	v_mfma_f32_16x16x32_f16 v[158:161], v[194:197], v[206:209], v[158:161]
	global_load_dwordx4 v[16:19], v[110:111], off offset:1920
	v_mfma_f32_16x16x32_f16 v[68:71], v[194:197], v[220:223], v[68:71]
	ds_read_b128 v[108:111], v131 offset:49152
	v_mfma_f32_16x16x32_f16 v[162:165], v[202:205], v[206:209], v[162:165]
	ds_read_b128 v[194:197], v131 offset:53248
	v_mfma_f32_16x16x32_f16 v[76:79], v[202:205], v[220:223], v[76:79]
	ds_read_b128 v[202:205], v131 offset:55296
	global_load_dwordx4 v[20:23], v[112:113], off offset:1920
	v_mfma_f32_16x16x32_f16 v[154:157], v[210:213], v[198:201], v[154:157]
	global_load_dwordx4 v[0:3], v[114:115], off offset:1920
	ds_read_b128 v[112:115], v128 offset:18432
	v_mfma_f32_16x16x32_f16 v[72:75], v[224:227], v[198:201], v[72:75]
	ds_read_b128 v[198:201], v128 offset:22528
	v_mfma_f32_16x16x32_f16 v[166:169], v[210:213], v[206:209], v[166:169]
	global_load_dwordx4 v[4:7], v[116:117], off offset:1920
	v_mfma_f32_16x16x32_f16 v[84:87], v[210:213], v[220:223], v[84:87]
	global_load_dwordx4 v[8:11], v[118:119], off offset:1920
	v_mfma_f32_16x16x32_f16 v[80:83], v[224:227], v[206:209], v[80:83]
	ds_read_b128 v[116:119], v131 offset:51200
	v_mfma_f32_16x16x32_f16 v[88:91], v[224:227], v[220:223], v[88:91]
	s_waitcnt vmcnt(15)
	ds_write_b128 v126, v[52:55]
	s_waitcnt lgkmcnt(6)
	v_mfma_f32_16x16x32_f16 v[132:135], v[108:111], v[104:107], v[132:135]
	s_waitcnt vmcnt(14)
	ds_write_b128 v124, v[56:59]
	s_waitcnt lgkmcnt(4)
	v_mfma_f32_16x16x32_f16 v[92:95], v[108:111], v[112:115], v[92:95]
	s_waitcnt vmcnt(13)
	ds_write_b128 v125, v[60:63]
	s_waitcnt lgkmcnt(3)
	v_mfma_f32_16x16x32_f16 v[136:139], v[116:119], v[104:107], v[136:139]
	s_waitcnt vmcnt(12)
	ds_write_b128 v127, v[40:43]
	v_mfma_f32_16x16x32_f16 v[140:143], v[194:197], v[104:107], v[140:143]
	v_mfma_f32_16x16x32_f16 v[64:67], v[202:205], v[104:107], v[64:67]
	v_mfma_f32_16x16x32_f16 v[104:107], v[116:119], v[112:115], v[144:147]
	s_waitcnt vmcnt(11)
	ds_write_b128 v126, v[44:47] offset:32768
	v_mfma_f32_16x16x32_f16 v[144:147], v[194:197], v[112:115], v[154:157]
	v_mfma_f32_16x16x32_f16 v[72:75], v[202:205], v[112:115], v[72:75]
	v_mfma_f32_16x16x32_f16 v[112:115], v[108:111], v[190:193], v[158:161]
	s_waitcnt vmcnt(10)
	ds_write_b128 v124, v[48:51] offset:32768
	s_waitcnt vmcnt(9)
	ds_write_b128 v125, v[32:35] offset:32768
	v_mfma_f32_16x16x32_f16 v[68:71], v[108:111], v[198:201], v[68:71]
	ds_read_b128 v[108:111], v129 offset:16384
	v_mfma_f32_16x16x32_f16 v[154:157], v[116:119], v[190:193], v[162:165]
	s_nop 2
	ds_read_b128 v[162:165], v129 offset:18432
	v_mfma_f32_16x16x32_f16 v[76:79], v[116:119], v[198:201], v[76:79]
	ds_read_b128 v[116:119], v130 offset:49152
	s_waitcnt vmcnt(8)
	ds_write_b128 v127, v[36:39] offset:32768
	v_mfma_f32_16x16x32_f16 v[158:161], v[194:197], v[190:193], v[166:169]
	s_nop 2
	ds_read_b128 v[166:169], v130 offset:51200
	v_mfma_f32_16x16x32_f16 v[84:87], v[194:197], v[198:201], v[84:87]
	ds_read_b128 v[194:197], v130 offset:53248
	v_mfma_f32_16x16x32_f16 v[80:83], v[202:205], v[190:193], v[80:83]
	ds_read_b128 v[190:193], v129 offset:20480
	v_mfma_f32_16x16x32_f16 v[88:91], v[202:205], v[198:201], v[88:91]
	ds_read_b128 v[198:201], v129 offset:22528
	s_waitcnt lgkmcnt(5)
	v_mfma_f32_16x16x32_f16 v[132:135], v[116:119], v[108:111], v[132:135]
	ds_read_b128 v[202:205], v130 offset:55296
	s_waitcnt lgkmcnt(0)
	s_barrier
; #define GL_LOAD(s_, kt_) if (VAR != 1) { a##s_##0 = GL_A(0, kt_); a##s_##1 = GL_A(1, kt_); a##s_##2 = GL_A(2, kt_); a##s_##3 = GL_A(3, kt_); b##s_##0 = GL_B(0, kt_); b##s_##1 = GL_B(1, kt_); b##s_##2 = GL_B(2, kt_); b##s_##3 = GL_B(3, kt_); }
; #define LDS_STORE(s_, buf_) if (VAR != 2) { LDS_ST1(sA, 0, buf_, a##s_##0) LDS_ST1(sA, 1, buf_, a##s_##1) LDS_ST1(sA, 2, buf_, a##s_##2) LDS_ST1(sA, 3, buf_, a##s_##3) LDS_ST1(sB, 0, buf_, b##s_##0) LDS_ST1(sB, 1, buf_, b##s_##1) LDS_ST1(sB, 2, buf_, b##s_##2) LDS_ST1(sB, 3, buf_, b##s_##3) }
;     ...
;   GL_LOAD(0, 0)
;   GL_LOAD(1, 1)
;   LDS_STORE(0, 0)
;   if (VAR != 4) __syncthreads();
; #pragma unroll
;   for (int kt = 0; kt < nk; kt += 2) {
;     if (kt + 2 < nk) { GL_LOAD(0, kt + 2) }
;     MMA_TILE(0)
;     LDS_STORE(1, 1)
;     if (VAR != 4) __syncthreads();
;     if (kt + 3 < nk) { GL_LOAD(1, kt + 3) }
;     MMA_TILE(1)
;     if (kt + 2 < nk) { LDS_STORE(0, 0) }
;     if (VAR != 4) __syncthreads();
	ds_read_b128 v[32:35], v128
	ds_read_b128 v[36:39], v131 offset:32768
	ds_read_b128 v[40:43], v128 offset:2048
	ds_read_b128 v[44:47], v131 offset:34816
	ds_read_b128 v[48:51], v128 offset:4096
	ds_read_b128 v[52:55], v131 offset:36864
	ds_read_b128 v[56:59], v128 offset:6144
	ds_read_b128 v[60:63], v131 offset:38912
	v_mfma_f32_16x16x32_f16 v[136:139], v[166:169], v[108:111], v[136:139]
	v_mfma_f32_16x16x32_f16 v[140:143], v[194:197], v[108:111], v[140:143]
	v_mfma_f32_16x16x32_f16 v[64:67], v[202:205], v[108:111], v[64:67]
	v_mfma_f32_16x16x32_f16 v[92:95], v[116:119], v[162:165], v[92:95]
	v_mfma_f32_16x16x32_f16 v[104:107], v[166:169], v[162:165], v[104:107]
	v_mfma_f32_16x16x32_f16 v[108:111], v[194:197], v[162:165], v[144:147]
	v_mfma_f32_16x16x32_f16 v[72:75], v[202:205], v[162:165], v[72:75]
	v_mfma_f32_16x16x32_f16 v[112:115], v[116:119], v[190:193], v[112:115]
	v_mfma_f32_16x16x32_f16 v[144:147], v[166:169], v[190:193], v[154:157]
	v_mfma_f32_16x16x32_f16 v[154:157], v[194:197], v[190:193], v[158:161]
	v_mfma_f32_16x16x32_f16 v[80:83], v[202:205], v[190:193], v[80:83]
	v_mfma_f32_16x16x32_f16 v[68:71], v[116:119], v[198:201], v[68:71]
	v_mfma_f32_16x16x32_f16 v[76:79], v[166:169], v[198:201], v[76:79]
	v_mfma_f32_16x16x32_f16 v[84:87], v[194:197], v[198:201], v[84:87]
	v_mfma_f32_16x16x32_f16 v[88:91], v[202:205], v[198:201], v[88:91]
	s_waitcnt lgkmcnt(6)
	v_mfma_f32_16x16x32_f16 v[116:119], v[36:39], v[32:35], v[132:135]
	s_waitcnt lgkmcnt(4)
	v_mfma_f32_16x16x32_f16 v[132:135], v[44:47], v[32:35], v[136:139]
	s_waitcnt lgkmcnt(2)
	v_mfma_f32_16x16x32_f16 v[136:139], v[52:55], v[32:35], v[140:143]
	s_waitcnt lgkmcnt(0)
	v_mfma_f32_16x16x32_f16 v[32:35], v[60:63], v[32:35], v[64:67]
	v_mfma_f32_16x16x32_f16 v[64:67], v[36:39], v[40:43], v[92:95]
	v_mfma_f32_16x16x32_f16 v[92:95], v[44:47], v[40:43], v[104:107]
	v_mfma_f32_16x16x32_f16 v[104:107], v[52:55], v[40:43], v[108:111]
	v_mfma_f32_16x16x32_f16 v[40:43], v[60:63], v[40:43], v[72:75]
	v_mfma_f32_16x16x32_f16 v[72:75], v[36:39], v[48:51], v[112:115]
	v_mfma_f32_16x16x32_f16 v[108:111], v[44:47], v[48:51], v[144:147]
	v_mfma_f32_16x16x32_f16 v[112:115], v[52:55], v[48:51], v[154:157]
	v_mfma_f32_16x16x32_f16 v[48:51], v[60:63], v[48:51], v[80:83]
	v_mfma_f32_16x16x32_f16 v[36:39], v[36:39], v[56:59], v[68:71]
	v_mfma_f32_16x16x32_f16 v[44:47], v[44:47], v[56:59], v[76:79]
	v_mfma_f32_16x16x32_f16 v[52:55], v[52:55], v[56:59], v[84:87]
	v_mfma_f32_16x16x32_f16 v[56:59], v[60:63], v[56:59], v[88:91]
	ds_read_b128 v[60:63], v129
	ds_read_b128 v[68:71], v130 offset:32768
	ds_read_b128 v[76:79], v129 offset:2048
	ds_read_b128 v[80:83], v130 offset:34816
	ds_read_b128 v[84:87], v129 offset:4096
	ds_read_b128 v[88:91], v130 offset:36864
	ds_read_b128 v[140:143], v129 offset:6144
	ds_read_b128 v[144:147], v130 offset:38912
	s_waitcnt vmcnt(7)
	ds_write_b128 v126, v[24:27] offset:16384
	s_waitcnt vmcnt(6)
	ds_write_b128 v124, v[28:31] offset:16384
	s_waitcnt vmcnt(5)
	ds_write_b128 v125, v[12:15] offset:16384
	s_waitcnt vmcnt(4)
	ds_write_b128 v127, v[16:19] offset:16384
	s_waitcnt vmcnt(3)
	ds_write_b128 v126, v[20:23] offset:49152
	s_waitcnt vmcnt(2)
	ds_write_b128 v124, v[0:3] offset:49152
	s_waitcnt vmcnt(1)
	ds_write_b128 v125, v[4:7] offset:49152
	s_waitcnt vmcnt(0)
	ds_write_b128 v127, v[8:11] offset:49152
	s_waitcnt lgkmcnt(0)
	v_mfma_f32_16x16x32_f16 v[116:119], v[68:71], v[60:63], v[116:119]
	s_barrier
	ds_read_b128 v[0:3], v128 offset:16384
	ds_read_b128 v[4:7], v131 offset:49152
	ds_read_b128 v[8:11], v128 offset:18432
	ds_read_b128 v[12:15], v131 offset:51200
	ds_read_b128 v[16:19], v128 offset:20480
	ds_read_b128 v[20:23], v131 offset:53248
	ds_read_b128 v[24:27], v128 offset:22528
	ds_read_b128 v[28:31], v131 offset:55296
	v_mfma_f32_16x16x32_f16 v[132:135], v[80:83], v[60:63], v[132:135]
	v_mfma_f32_16x16x32_f16 v[136:139], v[88:91], v[60:63], v[136:139]
	v_mfma_f32_16x16x32_f16 v[32:35], v[144:147], v[60:63], v[32:35]
	v_mfma_f32_16x16x32_f16 v[60:63], v[68:71], v[76:79], v[64:67]
	v_mfma_f32_16x16x32_f16 v[64:67], v[80:83], v[76:79], v[92:95]
	v_mfma_f32_16x16x32_f16 v[92:95], v[88:91], v[76:79], v[104:107]
	v_mfma_f32_16x16x32_f16 v[40:43], v[144:147], v[76:79], v[40:43]
	v_mfma_f32_16x16x32_f16 v[72:75], v[68:71], v[84:87], v[72:75]
	v_mfma_f32_16x16x32_f16 v[76:79], v[80:83], v[84:87], v[108:111]
	v_mfma_f32_16x16x32_f16 v[104:107], v[88:91], v[84:87], v[112:115]
	v_mfma_f32_16x16x32_f16 v[48:51], v[144:147], v[84:87], v[48:51]
	v_mfma_f32_16x16x32_f16 v[36:39], v[68:71], v[140:143], v[36:39]
	v_mfma_f32_16x16x32_f16 v[44:47], v[80:83], v[140:143], v[44:47]
	v_mfma_f32_16x16x32_f16 v[52:55], v[88:91], v[140:143], v[52:55]
	v_mfma_f32_16x16x32_f16 v[56:59], v[144:147], v[140:143], v[56:59]
	s_waitcnt lgkmcnt(6)
	v_mfma_f32_16x16x32_f16 v[68:71], v[4:7], v[0:3], v[116:119]
	s_waitcnt lgkmcnt(4)
	v_mfma_f32_16x16x32_f16 v[80:83], v[12:15], v[0:3], v[132:135]
	s_waitcnt lgkmcnt(2)
	v_mfma_f32_16x16x32_f16 v[84:87], v[20:23], v[0:3], v[136:139]
	s_waitcnt lgkmcnt(0)
	v_mfma_f32_16x16x32_f16 v[0:3], v[28:31], v[0:3], v[32:35]
	v_mfma_f32_16x16x32_f16 v[32:35], v[4:7], v[8:11], v[60:63]
	v_mfma_f32_16x16x32_f16 v[60:63], v[12:15], v[8:11], v[64:67]
	v_mfma_f32_16x16x32_f16 v[64:67], v[20:23], v[8:11], v[92:95]
	v_mfma_f32_16x16x32_f16 v[8:11], v[28:31], v[8:11], v[40:43]
	v_mfma_f32_16x16x32_f16 v[40:43], v[4:7], v[16:19], v[72:75]
	v_mfma_f32_16x16x32_f16 v[72:75], v[12:15], v[16:19], v[76:79]
	v_mfma_f32_16x16x32_f16 v[92:95], v[20:23], v[16:19], v[104:107]
	v_mfma_f32_16x16x32_f16 v[16:19], v[28:31], v[16:19], v[48:51]
	v_mfma_f32_16x16x32_f16 v[4:7], v[4:7], v[24:27], v[36:39]
	v_mfma_f32_16x16x32_f16 v[12:15], v[12:15], v[24:27], v[44:47]
	v_mfma_f32_16x16x32_f16 v[52:55], v[20:23], v[24:27], v[52:55]
	v_mfma_f32_16x16x32_f16 v[28:31], v[28:31], v[24:27], v[56:59]
	ds_read_b128 v[20:23], v129 offset:16384
	ds_read_b128 v[104:107], v130 offset:49152
	ds_read_b128 v[24:27], v129 offset:18432
	ds_read_b128 v[108:111], v130 offset:51200
	ds_read_b128 v[112:115], v129 offset:20480
	ds_read_b128 v[116:119], v130 offset:53248
	ds_read_b128 v[124:127], v129 offset:22528
	ds_read_b128 v[128:131], v130 offset:55296
	s_waitcnt lgkmcnt(0)
	s_barrier
; DI int TIDX() { int t = threadIdx.x; asm volatile("" : "+v"(t)); return t; }
; DI unsigned pack2(float lo, float hi) { f2_t v = {lo, hi}; h2_t b = __builtin_convertvector(v, h2_t); return __builtin_bit_cast(unsigned, b); }
; DI float lo_f(unsigned u) { return (float)(__builtin_bit_cast(h2_t, u)[0]); }
; DI float hi_f(unsigned u) { return (float)(__builtin_bit_cast(h2_t, u)[1]); }
; DI float sigmoidf_(float x) { return 1.0f / (1.0f + __expf(-x)); }
; DI void epi_residual(const f32x4 (&v)[4][4], int row0, int col0, const float* xsrc, float* x, bf16_t* xb, float* ssq_out, bool write_xb, bool write_ssq) {
;   const int lane = TIDX() & 63, lr = lane & 15, g = lane >> 4;
; #pragma unroll
;   for (int mt = 0; mt < 4; ++mt) {
;     const int row = row0 + mt * 16 + lr;
;     float ss = 0.f;
; #pragma unroll
;     for (int nt = 0; nt < 4; ++nt) {
;       const int col = col0 + nt * 16 + 4 * g;
;       float4* px = (float4*)(x + (size_t)row * DM + col);
;       float4 o = *(const float4*)(xsrc + (size_t)row * DM + col);
;       o.x += v[mt][nt][0]; o.y += v[mt][nt][1]; o.z += v[mt][nt][2]; o.w += v[mt][nt][3];
;       *px = o;
;       ss += (o.x * o.x + o.y * o.y) + (o.z * o.z + o.w * o.w);
;       if (write_xb) *(uint2*)(xb + (size_t)row * DM + col) = make_uint2(pack2(o.x, o.y), pack2(o.z, o.w));
;     }
; DI void phase_ple(const Params& P, int l, char* smem) {
;     ...
; #pragma unroll
;     for (int mt = 0; mt < 4; ++mt)
; #pragma unroll
;       for (int h = 0; h < 2; ++h) {
;         const uint4 q = park[mt * 2 + h];
;         acc[mt][2 * h][0] = sigmoidf_(acc[mt][2 * h][0] * rs[mt]) * lo_f(q.x);
;         acc[mt][2 * h][1] = sigmoidf_(acc[mt][2 * h][1] * rs[mt]) * hi_f(q.x);
;         acc[mt][2 * h][2] = sigmoidf_(acc[mt][2 * h][2] * rs[mt]) * lo_f(q.y);
;         acc[mt][2 * h][3] = sigmoidf_(acc[mt][2 * h][3] * rs[mt]) * hi_f(q.y);
;         acc[mt][2 * h + 1][0] = sigmoidf_(acc[mt][2 * h + 1][0] * rs[mt]) * lo_f(q.z);
;         acc[mt][2 * h + 1][1] = sigmoidf_(acc[mt][2 * h + 1][1] * rs[mt]) * hi_f(q.z);
;         acc[mt][2 * h + 1][2] = sigmoidf_(acc[mt][2 * h + 1][2] * rs[mt]) * lo_f(q.w);
;         acc[mt][2 * h + 1][3] = sigmoidf_(acc[mt][2 * h + 1][3] * rs[mt]) * hi_f(q.w);
;       }
;     epi_residual(acc, row0, col0, P.out, P.out, xb2, ssq_out, l + 1 < DEPTH, l + 1 < DEPTH);
	v_mfma_f32_16x16x32_f16 v[132:135], v[104:107], v[20:23], v[68:71]
	v_mfma_f32_16x16x32_f16 v[88:91], v[108:111], v[20:23], v[80:83]
	v_mfma_f32_16x16x32_f16 v[84:87], v[116:119], v[20:23], v[84:87]
	v_mfma_f32_16x16x32_f16 v[76:79], v[128:131], v[20:23], v[0:3]
	v_mfma_f32_16x16x32_f16 v[20:23], v[104:107], v[124:127], v[4:7]
	s_nop 3
	v_mul_f32_e32 v4, v101, v132
	v_mul_f32_e32 v4, 0xbfb8aa3b, v4
	v_mfma_f32_16x16x32_f16 v[36:39], v[108:111], v[112:115], v[72:75]
	s_nop 2
	v_exp_f32_e32 v72, v4
	v_mul_f32_e32 v4, v101, v133
	v_mul_f32_e32 v4, 0xbfb8aa3b, v4
	v_exp_f32_e32 v73, v4
	v_mul_f32_e32 v4, v101, v134
	v_mul_f32_e32 v4, 0xbfb8aa3b, v4
	v_mfma_f32_16x16x32_f16 v[60:63], v[108:111], v[24:27], v[60:63]
	v_mov_b32_e32 v74, v148
	v_pk_add_f32 v[72:73], v[72:73], 1.0 op_sel_hi:[1,0]
	v_mfma_f32_16x16x32_f16 v[12:15], v[108:111], v[124:127], v[12:15]
	v_exp_f32_e32 v110, v4
	v_mul_f32_e32 v4, v101, v135
	v_mul_f32_e32 v4, 0xbfb8aa3b, v4
	v_mfma_f32_16x16x32_f16 v[68:71], v[104:107], v[24:27], v[32:35]
	v_exp_f32_e32 v111, v4
	s_nop 0
	v_pk_add_f32 v[110:111], v[110:111], 1.0 op_sel_hi:[1,0]
	v_mfma_f32_16x16x32_f16 v[56:59], v[116:119], v[24:27], v[64:67]
	v_mfma_f32_16x16x32_f16 v[48:51], v[128:131], v[24:27], v[8:11]
	v_mfma_f32_16x16x32_f16 v[44:47], v[104:107], v[112:115], v[40:43]
	v_mfma_f32_16x16x32_f16 v[32:35], v[116:119], v[112:115], v[92:95]
	v_mfma_f32_16x16x32_f16 v[24:27], v[128:131], v[112:115], v[16:19]
	v_or_b32_e32 v114, s2, v120
	v_mfma_f32_16x16x32_f16 v[8:11], v[116:119], v[124:127], v[52:55]
	s_nop 2
	global_load_dwordx4 v[52:55], v[102:103], off offset:48
	global_load_dwordx4 v[64:67], v[102:103], off offset:32
	global_load_dwordx4 v[80:83], v[102:103], off offset:16
	global_load_dwordx4 v[92:95], v[102:103], off
	s_waitcnt vmcnt(0)
	v_cvt_f32_f16_e32 v116, v92
	v_mfma_f32_16x16x32_f16 v[0:3], v[128:131], v[124:127], v[28:31]
	global_load_dwordx4 v[4:7], v[102:103], off offset:112
	global_load_dwordx4 v[16:19], v[102:103], off offset:96
	s_nop 0
	global_load_dwordx4 v[28:31], v[102:103], off offset:80
	global_load_dwordx4 v[40:43], v[102:103], off offset:64
	v_cvt_f32_f16_sdwa v117, v92 dst_sel:DWORD dst_unused:UNUSED_PAD src0_sel:WORD_1
	v_and_or_b32 v104, v74, 15, v123
	v_bfe_u32 v115, v74, 4, 2
	v_ashrrev_i32_e32 v105, 31, v104
	v_lshl_or_b32 v118, v115, 2, v114
	v_lshlrev_b64 v[74:75], 12, v[104:105]
	v_lshlrev_b64 v[102:103], 11, v[104:105]
	v_lshl_add_u64 v[74:75], s[16:17], 0, v[74:75]
	v_lshl_add_u64 v[106:107], s[6:7], 0, v[102:103]
	v_lshlrev_b32_e32 v102, 2, v118
	v_mov_b32_e32 v103, v151
	v_lshl_add_u64 v[108:109], v[74:75], 0, v[102:103]
	v_div_scale_f32 v74, s[6:7], v73, v73, 1.0
	v_rcp_f32_e32 v75, v74
	v_div_scale_f32 v92, s[6:7], v111, v111, 1.0
	v_fma_f32 v103, -v74, v75, 1.0
	v_fmac_f32_e32 v75, v103, v75
	v_div_scale_f32 v103, vcc, 1.0, v73, 1.0
	v_mul_f32_e32 v112, v103, v75
	v_fma_f32 v113, -v74, v112, v103
	v_fmac_f32_e32 v112, v113, v75
	v_fma_f32 v74, -v74, v112, v103
	v_div_fmas_f32 v74, v74, v75, v112
	v_div_fixup_f32 v113, v74, v73, 1.0
	v_div_scale_f32 v73, s[6:7], v72, v72, 1.0
	v_rcp_f32_e32 v74, v73
	s_nop 0
	v_fma_f32 v75, -v73, v74, 1.0
	v_fmac_f32_e32 v74, v75, v74
	v_div_scale_f32 v75, vcc, 1.0, v72, 1.0
	v_mul_f32_e32 v103, v75, v74
	v_fma_f32 v112, -v73, v103, v75
	v_fmac_f32_e32 v103, v112, v74
	v_fma_f32 v73, -v73, v103, v75
	v_div_fmas_f32 v73, v73, v74, v103
	v_div_fixup_f32 v112, v73, v72, 1.0
	global_load_dwordx4 v[72:75], v[108:109], off
	v_rcp_f32_e32 v103, v92
	s_waitcnt vmcnt(0)
	v_pk_fma_f32 v[72:73], v[112:113], v[116:117], v[72:73]
	v_fma_f32 v112, -v92, v103, 1.0
	v_fmac_f32_e32 v103, v112, v103
	v_div_scale_f32 v112, vcc, 1.0, v111, 1.0
	v_mul_f32_e32 v113, v112, v103
	v_fma_f32 v116, -v92, v113, v112
	v_fmac_f32_e32 v113, v116, v103
	v_fma_f32 v92, -v92, v113, v112
	v_div_fmas_f32 v92, v92, v103, v113
	v_div_fixup_f32 v111, v92, v111, 1.0
	v_div_scale_f32 v92, s[6:7], v110, v110, 1.0
	v_rcp_f32_e32 v103, v92
	s_nop 0
	v_fma_f32 v112, -v92, v103, 1.0
	v_fmac_f32_e32 v103, v112, v103
	v_div_scale_f32 v112, vcc, 1.0, v110, 1.0
	v_mul_f32_e32 v113, v112, v103
	v_fma_f32 v116, -v92, v113, v112
	v_fmac_f32_e32 v113, v116, v103
	v_fma_f32 v92, -v92, v113, v112
	v_div_fmas_f32 v92, v92, v103, v113
	v_div_fixup_f32 v110, v92, v110, 1.0
	v_cvt_f32_f16_e32 v92, v93
	v_cvt_f32_f16_sdwa v93, v93 dst_sel:DWORD dst_unused:UNUSED_PAD src0_sel:WORD_1
	s_andn2_b64 vcc, exec, s[4:5]
	v_pk_fma_f32 v[74:75], v[110:111], v[92:93], v[74:75]
	v_cndmask_b32_e64 v92, 0, 1, s[4:5]
	v_cmp_ne_u32_e64 s[42:43], 1, v92
	v_lshlrev_b32_e32 v92, 1, v118
	global_store_dwordx4 v[108:109], v[72:75], off
	s_cbranch_vccnz .LBB0_1438
	v_mov_b32_e32 v93, v151
	v_cvt_pk_f16_f32 v110, v72, v73
	v_cvt_pk_f16_f32 v111, v74, v75
	v_lshl_add_u64 v[112:113], v[106:107], 0, v[92:93]
	global_store_dwordx2 v[112:113], v[110:111], off
